# provably implied s_waitcnt instructions removed kernel-wide (79 vmcnt, 33 lgkmcnt) on top of the K-loop trims
# baseline (speedup 1.0000x reference)
; #define LAS __attribute__((address_space(3)))
; __device__ __forceinline__ void phase_mod(const Frame& F0) {
;     ...
;         for (int d0 = kg * 256; d0 < kg * 256 + 256; d0 += 32) {
;             float wvv[32];
; #pragma unroll
;             for (int i = 0; i < 32; ++i) wvv[i] = LDG(float, w + (size_t)(d0 + i) * (6 * DM));
; #pragma unroll
;             for (int i = 0; i < 32; ++i) { const int d = d0 + i; const float wv = wvv[i];
;                 const f32x4 s0 = *(const LAS f32x4*)(sl + d * NB), s1 = *(const LAS f32x4*)(sl + d * NB + 4), s2 = *(const LAS f32x4*)(sl + d * NB + 8);
;                 acc[0] += wv * s0[0]; acc[1] += wv * s0[1]; acc[2] += wv * s0[2]; acc[3] += wv * s0[3];
;                 acc[4] += wv * s1[0]; acc[5] += wv * s1[1]; acc[6] += wv * s1[2]; acc[7] += wv * s1[3];
;                 acc[8] += wv * s2[0]; acc[9] += wv * s2[1]; acc[10] += wv * s2[2]; acc[11] += wv * s2[3]; } }
.LBB0_218:
	v_add_co_u32_e64 v32, s[4:5], s23, v136
	ds_read_b128 v[36:39], v167
	ds_read_b128 v[48:51], v167 offset:16
	ds_read_b128 v[52:55], v167 offset:32
	ds_read_b128 v[56:59], v167 offset:48
	ds_read_b128 v[64:67], v167 offset:64
	ds_read_b128 v[68:71], v167 offset:80
	ds_read_b128 v[76:79], v167 offset:96
	ds_read_b128 v[80:83], v167 offset:112
	ds_read_b128 v[84:87], v167 offset:128
	ds_read_b128 v[88:91], v167 offset:144
	ds_read_b128 v[92:95], v167 offset:160
	ds_read_b128 v[100:103], v167 offset:176
	ds_read_b128 v[104:107], v167 offset:192
	ds_read_b128 v[108:111], v167 offset:208
	ds_read_b128 v[120:123], v167 offset:224
	ds_read_b128 v[124:127], v167 offset:240
	ds_read_b128 v[16:19], v167 offset:256
	ds_read_b128 v[4:7], v167 offset:272
	ds_read_b128 v[0:3], v167 offset:288
	ds_read_b128 v[12:15], v167 offset:304
	ds_read_b128 v[8:11], v167 offset:320
	v_addc_co_u32_e64 v33, s[4:5], -1, v137, s[4:5]
	v_add_co_u32_e64 v34, s[4:5], s24, v136
	v_add_u32_e32 v168, 32, v168
	s_nop 0
	v_addc_co_u32_e64 v35, s[4:5], -1, v137, s[4:5]
	v_add_co_u32_e64 v128, s[4:5], s25, v136
	s_nop 1
	v_addc_co_u32_e64 v129, s[4:5], -1, v137, s[4:5]
	v_add_co_u32_e64 v130, s[4:5], s26, v136
	s_nop 1
	v_addc_co_u32_e64 v131, s[4:5], -1, v137, s[4:5]
	v_add_co_u32_e64 v156, s[4:5], s27, v136
	s_nop 1
	v_addc_co_u32_e64 v157, s[4:5], -1, v137, s[4:5]
	v_add_co_u32_e64 v170, s[4:5], s28, v136
	s_nop 1
	v_addc_co_u32_e64 v171, s[4:5], -1, v137, s[4:5]
	v_add_co_u32_e64 v172, s[4:5], s29, v136
	s_nop 1
	v_addc_co_u32_e64 v173, s[4:5], -1, v137, s[4:5]
	v_add_co_u32_e64 v174, s[4:5], s30, v136
	s_nop 1
	v_addc_co_u32_e64 v175, s[4:5], -1, v137, s[4:5]
	global_load_dword v158, v[32:33], off
	global_load_dword v160, v[34:35], off
	global_load_dword v198, v[128:129], off
	global_load_dword v210, v[130:131], off
	s_nop 0
	global_load_dword v156, v[156:157], off
	s_nop 0
	global_load_dword v212, v[170:171], off
	global_load_dword v34, v[172:173], off
	global_load_dword v32, v[174:175], off
	v_add_co_u32_e64 v40, s[4:5], s31, v136
	ds_read_b128 v[128:131], v167 offset:336
	ds_read_b128 v[170:173], v167 offset:352
	v_addc_co_u32_e64 v41, s[4:5], -1, v137, s[4:5]
	v_add_co_u32_e64 v42, s[4:5], s33, v136
	ds_read_b128 v[178:181], v167 offset:400
	s_nop 0
	v_addc_co_u32_e64 v43, s[4:5], -1, v137, s[4:5]
	v_add_co_u32_e64 v44, s[4:5], s34, v136
	ds_read_b128 v[174:177], v167 offset:384
	s_nop 0
	v_addc_co_u32_e64 v45, s[4:5], -1, v137, s[4:5]
	v_add_co_u32_e64 v46, s[4:5], s35, v136
	s_waitcnt vmcnt(0) lgkmcnt(0)
	v_pk_fma_f32 v[28:29], v[158:159], v[36:37], v[28:29] op_sel_hi:[0,1,1]
	v_addc_co_u32_e64 v47, s[4:5], -1, v137, s[4:5]
	v_add_co_u32_e64 v60, s[4:5], s36, v136
	v_pk_fma_f32 v[30:31], v[158:159], v[38:39], v[30:31] op_sel_hi:[0,1,1]
	v_pk_fma_f32 v[24:25], v[158:159], v[48:49], v[24:25] op_sel_hi:[0,1,1]
	v_pk_fma_f32 v[26:27], v[158:159], v[50:51], v[26:27] op_sel_hi:[0,1,1]
	v_pk_fma_f32 v[36:37], v[158:159], v[52:53], v[22:23] op_sel_hi:[0,1,1]
	v_pk_fma_f32 v[38:39], v[158:159], v[54:55], v[20:21] op_sel_hi:[0,1,1]
	v_addc_co_u32_e64 v61, s[4:5], -1, v137, s[4:5]
	v_pk_fma_f32 v[28:29], v[160:161], v[56:57], v[28:29] op_sel_hi:[0,1,1]
	v_pk_fma_f32 v[30:31], v[160:161], v[58:59], v[30:31] op_sel_hi:[0,1,1]
	v_pk_fma_f32 v[24:25], v[160:161], v[64:65], v[24:25] op_sel_hi:[0,1,1]
	v_pk_fma_f32 v[26:27], v[160:161], v[66:67], v[26:27] op_sel_hi:[0,1,1]
	v_pk_fma_f32 v[36:37], v[160:161], v[68:69], v[36:37] op_sel_hi:[0,1,1]
	v_pk_fma_f32 v[38:39], v[160:161], v[70:71], v[38:39] op_sel_hi:[0,1,1]
	v_add_co_u32_e64 v62, s[4:5], s37, v136
	ds_read_b128 v[20:23], v167 offset:368
	v_pk_fma_f32 v[28:29], v[198:199], v[76:77], v[28:29] op_sel_hi:[0,1,1]
	v_pk_fma_f32 v[30:31], v[198:199], v[78:79], v[30:31] op_sel_hi:[0,1,1]
	v_pk_fma_f32 v[24:25], v[198:199], v[80:81], v[24:25] op_sel_hi:[0,1,1]
	v_pk_fma_f32 v[26:27], v[198:199], v[82:83], v[26:27] op_sel_hi:[0,1,1]
	v_pk_fma_f32 v[36:37], v[198:199], v[84:85], v[36:37] op_sel_hi:[0,1,1]
	v_pk_fma_f32 v[38:39], v[198:199], v[86:87], v[38:39] op_sel_hi:[0,1,1]
	v_addc_co_u32_e64 v63, s[4:5], -1, v137, s[4:5]
	v_pk_fma_f32 v[28:29], v[210:211], v[88:89], v[28:29] op_sel_hi:[0,1,1]
	v_pk_fma_f32 v[30:31], v[210:211], v[90:91], v[30:31] op_sel_hi:[0,1,1]
	v_pk_fma_f32 v[24:25], v[210:211], v[92:93], v[24:25] op_sel_hi:[0,1,1]
	v_pk_fma_f32 v[26:27], v[210:211], v[94:95], v[26:27] op_sel_hi:[0,1,1]
	v_pk_fma_f32 v[36:37], v[210:211], v[100:101], v[36:37] op_sel_hi:[0,1,1]
	v_pk_fma_f32 v[38:39], v[210:211], v[102:103], v[38:39] op_sel_hi:[0,1,1]
	v_add_co_u32_e64 v72, s[4:5], s38, v136
	v_pk_fma_f32 v[48:49], v[156:157], v[104:105], v[28:29] op_sel_hi:[0,1,1]
	v_pk_fma_f32 v[50:51], v[156:157], v[106:107], v[30:31] op_sel_hi:[0,1,1]
	v_pk_fma_f32 v[24:25], v[156:157], v[108:109], v[24:25] op_sel_hi:[0,1,1]
	v_pk_fma_f32 v[26:27], v[156:157], v[110:111], v[26:27] op_sel_hi:[0,1,1]
	v_pk_fma_f32 v[80:81], v[156:157], v[120:121], v[36:37] op_sel_hi:[0,1,1]
	v_pk_fma_f32 v[82:83], v[156:157], v[122:123], v[38:39] op_sel_hi:[0,1,1]
	v_addc_co_u32_e64 v73, s[4:5], -1, v137, s[4:5]
	v_pk_fma_f32 v[84:85], v[212:213], v[124:125], v[48:49] op_sel_hi:[0,1,1]
	v_pk_fma_f32 v[86:87], v[212:213], v[126:127], v[50:51] op_sel_hi:[0,1,1]
	v_pk_fma_f32 v[16:17], v[212:213], v[16:17], v[24:25] op_sel_hi:[0,1,1]
	v_pk_fma_f32 v[18:19], v[212:213], v[18:19], v[26:27] op_sel_hi:[0,1,1]
	v_pk_fma_f32 v[80:81], v[212:213], v[4:5], v[80:81] op_sel_hi:[0,1,1]
	v_pk_fma_f32 v[82:83], v[212:213], v[6:7], v[82:83] op_sel_hi:[0,1,1]
	v_add_co_u32_e64 v74, s[4:5], s39, v136
	v_pk_fma_f32 v[84:85], v[34:35], v[0:1], v[84:85] op_sel_hi:[0,1,1]
; #define LAS __attribute__((address_space(3)))
; __device__ __forceinline__ void phase_mod(const Frame& F0) {
;     ...
;         for (int d0 = kg * 256; d0 < kg * 256 + 256; d0 += 32) {
;             float wvv[32];
; #pragma unroll
;             for (int i = 0; i < 32; ++i) wvv[i] = LDG(float, w + (size_t)(d0 + i) * (6 * DM));
; #pragma unroll
;             for (int i = 0; i < 32; ++i) { const int d = d0 + i; const float wv = wvv[i];
;                 const f32x4 s0 = *(const LAS f32x4*)(sl + d * NB), s1 = *(const LAS f32x4*)(sl + d * NB + 4), s2 = *(const LAS f32x4*)(sl + d * NB + 8);
;                 acc[0] += wv * s0[0]; acc[1] += wv * s0[1]; acc[2] += wv * s0[2]; acc[3] += wv * s0[3];
;                 acc[4] += wv * s1[0]; acc[5] += wv * s1[1]; acc[6] += wv * s1[2]; acc[7] += wv * s1[3];
;                 acc[8] += wv * s2[0]; acc[9] += wv * s2[1]; acc[10] += wv * s2[2]; acc[11] += wv * s2[3]; } }
	v_pk_fma_f32 v[86:87], v[34:35], v[2:3], v[86:87] op_sel_hi:[0,1,1]
	v_pk_fma_f32 v[16:17], v[34:35], v[12:13], v[16:17] op_sel_hi:[0,1,1]
	v_pk_fma_f32 v[18:19], v[34:35], v[14:15], v[18:19] op_sel_hi:[0,1,1]
	v_pk_fma_f32 v[80:81], v[34:35], v[8:9], v[80:81] op_sel_hi:[0,1,1]
	v_pk_fma_f32 v[34:35], v[34:35], v[10:11], v[82:83] op_sel_hi:[0,1,1]
	v_addc_co_u32_e64 v75, s[4:5], -1, v137, s[4:5]
	ds_read_b128 v[182:185], v167 offset:416
	ds_read_b128 v[186:189], v167 offset:432
	ds_read_b128 v[190:193], v167 offset:448
	ds_read_b128 v[194:197], v167 offset:464
	ds_read_b128 v[198:201], v167 offset:480
	ds_read_b128 v[202:205], v167 offset:496
	ds_read_b128 v[206:209], v167 offset:512
	ds_read_b128 v[76:79], v167 offset:528
	ds_read_b128 v[68:71], v167 offset:544
	ds_read_b128 v[28:31], v167 offset:560
	ds_read_b128 v[52:55], v167 offset:576
	ds_read_b128 v[64:67], v167 offset:592
	ds_read_b128 v[36:39], v167 offset:608
	ds_read_b128 v[56:59], v167 offset:624
	ds_read_b128 v[48:51], v167 offset:640
	ds_read_b128 v[4:7], v167 offset:656
	ds_read_b128 v[0:3], v167 offset:672
	ds_read_b128 v[24:27], v167 offset:688
	ds_read_b128 v[8:11], v167 offset:704
	ds_read_b128 v[12:15], v167 offset:720
	v_pk_fma_f32 v[82:83], v[32:33], v[128:129], v[84:85] op_sel_hi:[0,1,1]
	v_pk_fma_f32 v[84:85], v[32:33], v[130:131], v[86:87] op_sel_hi:[0,1,1]
	v_pk_fma_f32 v[86:87], v[32:33], v[170:171], v[16:17] op_sel_hi:[0,1,1]
	v_pk_fma_f32 v[88:89], v[32:33], v[172:173], v[18:19] op_sel_hi:[0,1,1]
	ds_read_b128 v[16:19], v167 offset:736
	v_pk_fma_f32 v[80:81], v[32:33], v[20:21], v[80:81] op_sel_hi:[0,1,1]
	v_pk_fma_f32 v[90:91], v[32:33], v[22:23], v[34:35] op_sel_hi:[0,1,1]
	ds_read_b128 v[20:23], v167 offset:752
	ds_read_b128 v[32:35], v167 offset:768
	global_load_dword v92, v[40:41], off
	global_load_dword v94, v[42:43], off
	global_load_dword v104, v[44:45], off
	global_load_dword v124, v[46:47], off
	global_load_dword v170, v[60:61], off
	global_load_dword v160, v[62:63], off
	global_load_dword v158, v[72:73], off
	global_load_dword v156, v[74:75], off
	v_add_co_u32_e64 v96, s[4:5], s40, v136
	ds_read_b128 v[40:43], v167 offset:784
	ds_read_b128 v[44:47], v167 offset:800
	v_addc_co_u32_e64 v97, s[4:5], -1, v137, s[4:5]
	v_add_co_u32_e64 v98, s[4:5], s41, v136
	ds_read_b128 v[60:63], v167 offset:816
	s_nop 0
	v_addc_co_u32_e64 v99, s[4:5], -1, v137, s[4:5]
	v_add_co_u32_e64 v144, s[4:5], s42, v136
	s_waitcnt vmcnt(7)
	v_pk_fma_f32 v[72:73], v[92:93], v[174:175], v[82:83] op_sel_hi:[0,1,1]
	v_addc_co_u32_e64 v145, s[4:5], -1, v137, s[4:5]
	v_add_co_u32_e64 v146, s[4:5], s43, v136
	v_pk_fma_f32 v[74:75], v[92:93], v[176:177], v[84:85] op_sel_hi:[0,1,1]
	s_nop 0
	v_addc_co_u32_e64 v147, s[4:5], -1, v137, s[4:5]
	v_add_co_u32_e64 v148, s[4:5], s44, v136
	v_pk_fma_f32 v[82:83], v[92:93], v[178:179], v[86:87] op_sel_hi:[0,1,1]
	v_pk_fma_f32 v[84:85], v[92:93], v[180:181], v[88:89] op_sel_hi:[0,1,1]
	v_pk_fma_f32 v[86:87], v[92:93], v[182:183], v[80:81] op_sel_hi:[0,1,1]
	v_pk_fma_f32 v[88:89], v[92:93], v[184:185], v[90:91] op_sel_hi:[0,1,1]
	v_addc_co_u32_e64 v149, s[4:5], -1, v137, s[4:5]
	s_waitcnt vmcnt(6)
	v_pk_fma_f32 v[92:93], v[94:95], v[186:187], v[72:73] op_sel_hi:[0,1,1]
	v_pk_fma_f32 v[100:101], v[94:95], v[188:189], v[74:75] op_sel_hi:[0,1,1]
	v_pk_fma_f32 v[102:103], v[94:95], v[190:191], v[82:83] op_sel_hi:[0,1,1]
	v_pk_fma_f32 v[106:107], v[94:95], v[192:193], v[84:85] op_sel_hi:[0,1,1]
	v_pk_fma_f32 v[108:109], v[94:95], v[194:195], v[86:87] op_sel_hi:[0,1,1]
	v_pk_fma_f32 v[110:111], v[94:95], v[196:197], v[88:89] op_sel_hi:[0,1,1]
	v_add_co_u32_e64 v150, s[4:5], s45, v136
	s_waitcnt vmcnt(5)
	v_pk_fma_f32 v[120:121], v[104:105], v[198:199], v[92:93] op_sel_hi:[0,1,1]
	v_pk_fma_f32 v[122:123], v[104:105], v[200:201], v[100:101] op_sel_hi:[0,1,1]
	v_pk_fma_f32 v[126:127], v[104:105], v[202:203], v[102:103] op_sel_hi:[0,1,1]
	v_pk_fma_f32 v[128:129], v[104:105], v[204:205], v[106:107] op_sel_hi:[0,1,1]
	s_waitcnt lgkmcnt(14)
	v_pk_fma_f32 v[130:131], v[104:105], v[206:207], v[108:109] op_sel_hi:[0,1,1]
	v_pk_fma_f32 v[172:173], v[104:105], v[208:209], v[110:111] op_sel_hi:[0,1,1]
	v_addc_co_u32_e64 v151, s[4:5], -1, v137, s[4:5]
	s_waitcnt vmcnt(4)
	v_pk_fma_f32 v[76:77], v[124:125], v[76:77], v[120:121] op_sel_hi:[0,1,1]
	v_pk_fma_f32 v[78:79], v[124:125], v[78:79], v[122:123] op_sel_hi:[0,1,1]
	v_pk_fma_f32 v[68:69], v[124:125], v[68:69], v[126:127] op_sel_hi:[0,1,1]
	v_pk_fma_f32 v[70:71], v[124:125], v[70:71], v[128:129] op_sel_hi:[0,1,1]
	v_pk_fma_f32 v[174:175], v[124:125], v[28:29], v[130:131] op_sel_hi:[0,1,1]
	v_pk_fma_f32 v[172:173], v[124:125], v[30:31], v[172:173] op_sel_hi:[0,1,1]
	v_add_co_u32_e64 v152, s[4:5], s46, v136
	s_waitcnt vmcnt(3)
	v_pk_fma_f32 v[76:77], v[170:171], v[52:53], v[76:77] op_sel_hi:[0,1,1]
	v_pk_fma_f32 v[78:79], v[170:171], v[54:55], v[78:79] op_sel_hi:[0,1,1]
	v_pk_fma_f32 v[64:65], v[170:171], v[64:65], v[68:69] op_sel_hi:[0,1,1]
	v_pk_fma_f32 v[66:67], v[170:171], v[66:67], v[70:71] op_sel_hi:[0,1,1]
	s_waitcnt lgkmcnt(13)
	v_pk_fma_f32 v[174:175], v[170:171], v[36:37], v[174:175] op_sel_hi:[0,1,1]
	v_pk_fma_f32 v[170:171], v[170:171], v[38:39], v[172:173] op_sel_hi:[0,1,1]
	v_addc_co_u32_e64 v153, s[4:5], -1, v137, s[4:5]
	s_waitcnt vmcnt(2) lgkmcnt(12)
	v_pk_fma_f32 v[172:173], v[160:161], v[56:57], v[76:77] op_sel_hi:[0,1,1]
	v_pk_fma_f32 v[176:177], v[160:161], v[58:59], v[78:79] op_sel_hi:[0,1,1]
	s_waitcnt lgkmcnt(11)
	v_pk_fma_f32 v[48:49], v[160:161], v[48:49], v[64:65] op_sel_hi:[0,1,1]
	v_pk_fma_f32 v[50:51], v[160:161], v[50:51], v[66:67] op_sel_hi:[0,1,1]
	s_waitcnt lgkmcnt(10)
; #define LAS __attribute__((address_space(3)))
; __device__ __forceinline__ void phase_mod(const Frame& F0) {
;     ...
;         for (int d0 = kg * 256; d0 < kg * 256 + 256; d0 += 32) {
;             float wvv[32];
; #pragma unroll
;             for (int i = 0; i < 32; ++i) wvv[i] = LDG(float, w + (size_t)(d0 + i) * (6 * DM));
; #pragma unroll
;             for (int i = 0; i < 32; ++i) { const int d = d0 + i; const float wv = wvv[i];
;                 const f32x4 s0 = *(const LAS f32x4*)(sl + d * NB), s1 = *(const LAS f32x4*)(sl + d * NB + 4), s2 = *(const LAS f32x4*)(sl + d * NB + 8);
;                 acc[0] += wv * s0[0]; acc[1] += wv * s0[1]; acc[2] += wv * s0[2]; acc[3] += wv * s0[3];
;                 acc[4] += wv * s1[0]; acc[5] += wv * s1[1]; acc[6] += wv * s1[2]; acc[7] += wv * s1[3];
;                 acc[8] += wv * s2[0]; acc[9] += wv * s2[1]; acc[10] += wv * s2[2]; acc[11] += wv * s2[3]; } }
	v_pk_fma_f32 v[174:175], v[160:161], v[4:5], v[174:175] op_sel_hi:[0,1,1]
	v_pk_fma_f32 v[170:171], v[160:161], v[6:7], v[170:171] op_sel_hi:[0,1,1]
	v_add_co_u32_e64 v154, s[4:5], s47, v136
	s_waitcnt vmcnt(1) lgkmcnt(9)
	v_pk_fma_f32 v[172:173], v[158:159], v[0:1], v[172:173] op_sel_hi:[0,1,1]
	v_pk_fma_f32 v[176:177], v[158:159], v[2:3], v[176:177] op_sel_hi:[0,1,1]
	s_waitcnt lgkmcnt(8)
	v_pk_fma_f32 v[24:25], v[158:159], v[24:25], v[48:49] op_sel_hi:[0,1,1]
	v_pk_fma_f32 v[26:27], v[158:159], v[26:27], v[50:51] op_sel_hi:[0,1,1]
	s_waitcnt lgkmcnt(7)
	v_pk_fma_f32 v[48:49], v[158:159], v[8:9], v[174:175] op_sel_hi:[0,1,1]
	v_pk_fma_f32 v[50:51], v[158:159], v[10:11], v[170:171] op_sel_hi:[0,1,1]
	v_addc_co_u32_e64 v155, s[4:5], -1, v137, s[4:5]
	ds_read_b128 v[72:75], v167 offset:832
	ds_read_b128 v[80:83], v167 offset:848
	ds_read_b128 v[84:87], v167 offset:864
	ds_read_b128 v[88:91], v167 offset:880
	ds_read_b128 v[92:95], v167 offset:896
	ds_read_b128 v[100:103], v167 offset:912
	ds_read_b128 v[104:107], v167 offset:928
	ds_read_b128 v[108:111], v167 offset:944
	ds_read_b128 v[120:123], v167 offset:960
	ds_read_b128 v[124:127], v167 offset:976
	ds_read_b128 v[28:31], v167 offset:992
	ds_read_b128 v[128:131], v167 offset:1008
	ds_read_b128 v[52:55], v167 offset:1024
	ds_read_b128 v[36:39], v167 offset:1040
	ds_read_b128 v[76:79], v167 offset:1056
	ds_read_b128 v[68:71], v167 offset:1072
	ds_read_b128 v[64:67], v167 offset:1088
	ds_read_b128 v[56:59], v167 offset:1104
	ds_read_b128 v[0:3], v167 offset:1120
	ds_read_b128 v[4:7], v167 offset:1136
	ds_read_b128 v[8:11], v167 offset:1152
	s_waitcnt vmcnt(0) lgkmcnt(14)
	v_pk_fma_f32 v[170:171], v[156:157], v[12:13], v[172:173] op_sel_hi:[0,1,1]
	v_pk_fma_f32 v[172:173], v[156:157], v[14:15], v[176:177] op_sel_hi:[0,1,1]
	ds_read_b128 v[12:15], v167 offset:1168
	v_pk_fma_f32 v[174:175], v[156:157], v[16:17], v[24:25] op_sel_hi:[0,1,1]
	v_pk_fma_f32 v[176:177], v[156:157], v[18:19], v[26:27] op_sel_hi:[0,1,1]
	ds_read_b128 v[16:19], v167 offset:1184
	v_pk_fma_f32 v[48:49], v[156:157], v[20:21], v[48:49] op_sel_hi:[0,1,1]
	v_pk_fma_f32 v[50:51], v[156:157], v[22:23], v[50:51] op_sel_hi:[0,1,1]
	ds_read_b128 v[20:23], v167 offset:1200
	ds_read_b128 v[24:27], v167 offset:1216
	global_load_dword v96, v[96:97], off
	s_nop 0
	global_load_dword v98, v[98:99], off
	s_nop 0
	global_load_dword v160, v[144:145], off
	s_nop 0
	global_load_dword v146, v[146:147], off
	s_nop 0
	global_load_dword v156, v[148:149], off
	global_load_dword v158, v[150:151], off
	global_load_dword v144, v[152:153], off
	global_load_dword v145, v[154:155], off
	v_add_co_u32_e64 v112, s[4:5], s48, v136
	s_waitcnt vmcnt(7)
	v_pk_fma_f32 v[148:149], v[96:97], v[32:33], v[170:171] op_sel_hi:[0,1,1]
	v_addc_co_u32_e64 v113, s[4:5], -1, v137, s[4:5]
	v_add_co_u32_e64 v114, s[4:5], s49, v136
	v_pk_fma_f32 v[150:151], v[96:97], v[34:35], v[172:173] op_sel_hi:[0,1,1]
	s_nop 0
	v_addc_co_u32_e64 v115, s[4:5], -1, v137, s[4:5]
	v_add_co_u32_e64 v116, s[4:5], s50, v136
	v_pk_fma_f32 v[152:153], v[96:97], v[40:41], v[174:175] op_sel_hi:[0,1,1]
	s_nop 0
	v_addc_co_u32_e64 v117, s[4:5], -1, v137, s[4:5]
	v_add_co_u32_e64 v118, s[4:5], s51, v136
	v_pk_fma_f32 v[154:155], v[96:97], v[42:43], v[176:177] op_sel_hi:[0,1,1]
	s_nop 0
	v_addc_co_u32_e64 v119, s[4:5], -1, v137, s[4:5]
	v_add_co_u32_e64 v140, s[4:5], s52, v136
	v_pk_fma_f32 v[170:171], v[96:97], v[44:45], v[48:49] op_sel_hi:[0,1,1]
	v_pk_fma_f32 v[96:97], v[96:97], v[46:47], v[50:51] op_sel_hi:[0,1,1]
	v_addc_co_u32_e64 v141, s[4:5], -1, v137, s[4:5]
	s_waitcnt vmcnt(6)
	v_pk_fma_f32 v[148:149], v[98:99], v[60:61], v[148:149] op_sel_hi:[0,1,1]
	v_pk_fma_f32 v[150:151], v[98:99], v[62:63], v[150:151] op_sel_hi:[0,1,1]
	v_pk_fma_f32 v[152:153], v[98:99], v[72:73], v[152:153] op_sel_hi:[0,1,1]
	v_pk_fma_f32 v[154:155], v[98:99], v[74:75], v[154:155] op_sel_hi:[0,1,1]
	v_pk_fma_f32 v[170:171], v[98:99], v[80:81], v[170:171] op_sel_hi:[0,1,1]
	v_pk_fma_f32 v[96:97], v[98:99], v[82:83], v[96:97] op_sel_hi:[0,1,1]
	v_add_co_u32_e64 v142, s[4:5], s53, v136
	s_waitcnt vmcnt(5)
	v_pk_fma_f32 v[148:149], v[160:161], v[84:85], v[148:149] op_sel_hi:[0,1,1]
	v_pk_fma_f32 v[150:151], v[160:161], v[86:87], v[150:151] op_sel_hi:[0,1,1]
	v_pk_fma_f32 v[152:153], v[160:161], v[88:89], v[152:153] op_sel_hi:[0,1,1]
	v_pk_fma_f32 v[154:155], v[160:161], v[90:91], v[154:155] op_sel_hi:[0,1,1]
	v_pk_fma_f32 v[170:171], v[160:161], v[92:93], v[170:171] op_sel_hi:[0,1,1]
	v_pk_fma_f32 v[172:173], v[160:161], v[94:95], v[96:97] op_sel_hi:[0,1,1]
	v_addc_co_u32_e64 v143, s[4:5], -1, v137, s[4:5]
	ds_read_b128 v[32:35], v167 offset:1232
	ds_read_b128 v[40:43], v167 offset:1248
	ds_read_b128 v[44:47], v167 offset:1264
	ds_read_b128 v[48:51], v167 offset:1280
	ds_read_b128 v[60:63], v167 offset:1296
	ds_read_b128 v[72:75], v167 offset:1312
	ds_read_b128 v[80:83], v167 offset:1328
	ds_read_b128 v[84:87], v167 offset:1344
	ds_read_b128 v[88:91], v167 offset:1360
	ds_read_b128 v[92:95], v167 offset:1376
	ds_read_b128 v[96:99], v167 offset:1392
	s_waitcnt vmcnt(4)
	v_pk_fma_f32 v[174:175], v[146:147], v[100:101], v[148:149] op_sel_hi:[0,1,1]
	v_pk_fma_f32 v[176:177], v[146:147], v[102:103], v[150:151] op_sel_hi:[0,1,1]
	ds_read_b128 v[100:103], v167 offset:1408
	v_pk_fma_f32 v[152:153], v[146:147], v[104:105], v[152:153] op_sel_hi:[0,1,1]
	v_pk_fma_f32 v[154:155], v[146:147], v[106:107], v[154:155] op_sel_hi:[0,1,1]
	ds_read_b128 v[104:107], v167 offset:1424
	s_waitcnt lgkmcnt(14)
; #define LAS __attribute__((address_space(3)))
; __device__ __forceinline__ void phase_mod(const Frame& F0) {
;     ...
;         for (int d0 = kg * 256; d0 < kg * 256 + 256; d0 += 32) {
;             float wvv[32];
; #pragma unroll
;             for (int i = 0; i < 32; ++i) wvv[i] = LDG(float, w + (size_t)(d0 + i) * (6 * DM));
; #pragma unroll
;             for (int i = 0; i < 32; ++i) { const int d = d0 + i; const float wv = wvv[i];
;                 const f32x4 s0 = *(const LAS f32x4*)(sl + d * NB), s1 = *(const LAS f32x4*)(sl + d * NB + 4), s2 = *(const LAS f32x4*)(sl + d * NB + 8);
;                 acc[0] += wv * s0[0]; acc[1] += wv * s0[1]; acc[2] += wv * s0[2]; acc[3] += wv * s0[3];
;                 acc[4] += wv * s1[0]; acc[5] += wv * s1[1]; acc[6] += wv * s1[2]; acc[7] += wv * s1[3];
;                 acc[8] += wv * s2[0]; acc[9] += wv * s2[1]; acc[10] += wv * s2[2]; acc[11] += wv * s2[3]; } }
	v_pk_fma_f32 v[170:171], v[146:147], v[108:109], v[170:171] op_sel_hi:[0,1,1]
	v_pk_fma_f32 v[148:149], v[146:147], v[110:111], v[172:173] op_sel_hi:[0,1,1]
	ds_read_b128 v[108:111], v167 offset:1440
	global_load_dword v150, v[112:113], off
	global_load_dword v151, v[114:115], off
	ds_read_b128 v[112:115], v167 offset:1456
	global_load_dword v146, v[116:117], off
	global_load_dword v147, v[118:119], off
	s_nop 0
	global_load_dword v140, v[140:141], off
	s_nop 0
	global_load_dword v141, v[142:143], off
	v_add_co_u32_e64 v138, s[4:5], s54, v136
	s_waitcnt vmcnt(9)
	v_pk_fma_f32 v[152:153], v[156:157], v[124:125], v[152:153] op_sel_hi:[0,1,1]
	v_addc_co_u32_e64 v139, s[4:5], -1, v137, s[4:5]
	global_load_dword v138, v[138:139], off
	s_waitcnt vmcnt(9)
	v_pk_fma_f32 v[52:53], v[158:159], v[52:53], v[152:153] op_sel_hi:[0,1,1]
	global_load_dword v152, v[136:137], off
	v_pk_fma_f32 v[154:155], v[156:157], v[126:127], v[154:155] op_sel_hi:[0,1,1]
	v_pk_fma_f32 v[142:143], v[156:157], v[120:121], v[174:175] op_sel_hi:[0,1,1]
	v_pk_fma_f32 v[172:173], v[156:157], v[122:123], v[176:177] op_sel_hi:[0,1,1]
	v_pk_fma_f32 v[54:55], v[158:159], v[54:55], v[154:155] op_sel_hi:[0,1,1]
	v_mul_f32_e32 v154, v158, v38
	v_mov_b32_e32 v38, v31
	v_pk_fma_f32 v[28:29], v[156:157], v[28:29], v[170:171] op_sel_hi:[0,1,1]
	v_mov_b32_e32 v157, v158
	v_pk_fma_f32 v[142:143], v[158:159], v[128:129], v[142:143] op_sel_hi:[0,1,1]
	v_pk_fma_f32 v[172:173], v[158:159], v[130:131], v[172:173] op_sel_hi:[0,1,1]
	v_pk_fma_f32 v[28:29], v[158:159], v[36:37], v[28:29] op_sel_hi:[0,1,1]
	v_pk_mul_f32 v[38:39], v[156:157], v[38:39]
	v_mul_f32_e32 v30, v156, v30
	s_waitcnt vmcnt(8)
	v_mul_f32_e32 v36, v145, v6
	v_mov_b32_e32 v6, v67
	v_pk_fma_f32 v[76:77], v[144:145], v[76:77], v[142:143] op_sel_hi:[0,1,1]
	v_pk_fma_f32 v[78:79], v[144:145], v[78:79], v[172:173] op_sel_hi:[0,1,1]
	v_pk_fma_f32 v[52:53], v[144:145], v[68:69], v[52:53] op_sel_hi:[0,1,1]
	v_pk_fma_f32 v[54:55], v[144:145], v[70:71], v[54:55] op_sel_hi:[0,1,1]
	v_pk_fma_f32 v[28:29], v[144:145], v[64:65], v[28:29] op_sel_hi:[0,1,1]
	v_mov_b32_e32 v31, v38
	v_pk_mul_f32 v[6:7], v[144:145], v[6:7]
	v_mov_b32_e32 v155, v39
	v_pk_add_f32 v[30:31], v[148:149], v[30:31]
	v_mul_f32_e32 v66, v144, v66
	v_mov_b32_e32 v67, v6
	ds_read_b128 v[116:119], v167 offset:1472
	ds_read_b128 v[120:123], v167 offset:1488
	ds_read_b128 v[124:127], v167 offset:1504
	ds_read_b128 v[128:131], v167 offset:1520
	v_mov_b32_e32 v37, v7
	v_cmp_ge_i32_e64 s[4:5], v168, v162
	v_add_u32_e32 v167, 0x600, v167
	v_lshl_add_u64 v[136:137], v[136:137], 0, s[6:7]
	s_or_b64 s[16:17], s[4:5], s[16:17]
	s_waitcnt vmcnt(7)
	v_mul_f32_e32 v18, v150, v18
	s_waitcnt vmcnt(6) lgkmcnt(14)
	v_mul_f32_e32 v156, v151, v34
	s_waitcnt vmcnt(3) lgkmcnt(9)
	v_mul_f32_e32 v68, v140, v94
	v_mov_b32_e32 v94, v145
	v_pk_fma_f32 v[56:57], v[94:95], v[56:57], v[76:77] op_sel_hi:[0,1,1]
	v_pk_fma_f32 v[58:59], v[94:95], v[58:59], v[78:79] op_sel_hi:[0,1,1]
	v_pk_fma_f32 v[0:1], v[94:95], v[0:1], v[52:53] op_sel_hi:[0,1,1]
	v_pk_fma_f32 v[2:3], v[94:95], v[2:3], v[54:55] op_sel_hi:[0,1,1]
	v_pk_fma_f32 v[4:5], v[94:95], v[4:5], v[28:29] op_sel_hi:[0,1,1]
	v_mov_b32_e32 v34, v19
	v_mov_b32_e32 v76, v151
	v_pk_fma_f32 v[8:9], v[150:151], v[8:9], v[56:57] op_sel_hi:[0,1,1]
	v_pk_fma_f32 v[10:11], v[150:151], v[10:11], v[58:59] op_sel_hi:[0,1,1]
	v_pk_fma_f32 v[0:1], v[150:151], v[12:13], v[0:1] op_sel_hi:[0,1,1]
	v_pk_fma_f32 v[2:3], v[150:151], v[14:15], v[2:3] op_sel_hi:[0,1,1]
	v_pk_fma_f32 v[4:5], v[150:151], v[16:17], v[4:5] op_sel_hi:[0,1,1]
	v_pk_add_f32 v[12:13], v[30:31], v[154:155]
	v_mul_f32_e32 v142, v147, v82
	v_mov_b32_e32 v82, v51
	v_pk_mul_f32 v[6:7], v[150:151], v[34:35]
	v_pk_fma_f32 v[8:9], v[76:77], v[20:21], v[8:9] op_sel_hi:[0,1,1]
	v_pk_fma_f32 v[10:11], v[76:77], v[22:23], v[10:11] op_sel_hi:[0,1,1]
	v_pk_fma_f32 v[0:1], v[76:77], v[24:25], v[0:1] op_sel_hi:[0,1,1]
	v_pk_fma_f32 v[2:3], v[76:77], v[26:27], v[2:3] op_sel_hi:[0,1,1]
	v_pk_fma_f32 v[4:5], v[76:77], v[32:33], v[4:5] op_sel_hi:[0,1,1]
	v_pk_add_f32 v[12:13], v[12:13], v[66:67]
	s_waitcnt vmcnt(2) lgkmcnt(6)
; #define LAS __attribute__((address_space(3)))
; __device__ __forceinline__ void phase_mod(const Frame& F0) {
;     ...
;         for (int d0 = kg * 256; d0 < kg * 256 + 256; d0 += 32) {
;             float wvv[32];
; #pragma unroll
;             for (int i = 0; i < 32; ++i) wvv[i] = LDG(float, w + (size_t)(d0 + i) * (6 * DM));
; #pragma unroll
;             for (int i = 0; i < 32; ++i) { const int d = d0 + i; const float wv = wvv[i];
;                 const f32x4 s0 = *(const LAS f32x4*)(sl + d * NB), s1 = *(const LAS f32x4*)(sl + d * NB + 4), s2 = *(const LAS f32x4*)(sl + d * NB + 8);
;                 acc[0] += wv * s0[0]; acc[1] += wv * s0[1]; acc[2] += wv * s0[2]; acc[3] += wv * s0[3];
;                 acc[4] += wv * s1[0]; acc[5] += wv * s1[1]; acc[6] += wv * s1[2]; acc[7] += wv * s1[3];
;                 acc[8] += wv * s2[0]; acc[9] += wv * s2[1]; acc[10] += wv * s2[2]; acc[11] += wv * s2[3]; } }
; #pragma unroll
;         for (int b = 0; b < NB; ++b) red[(kg * NB + b) * 64 + col] = acc[b];
;         __syncthreads();
;         for (int o = F.tid; o < NB * 64; o += NTHREADS) { const int b = o >> 6, c2 = o & 63; float s = 0.f;
; #pragma unroll
;             for (int k = 0; k < 8; ++k) s += red[(k * NB + b) * 64 + c2];
	v_mul_f32_e32 v70, v141, v106
	v_mov_b32_e32 v106, v95
	v_mov_b32_e32 v78, v147
	v_mov_b32_e32 v19, v6
	v_mov_b32_e32 v157, v7
	v_pk_mul_f32 v[6:7], v[146:147], v[82:83]
	v_pk_fma_f32 v[8:9], v[146:147], v[40:41], v[8:9] op_sel_hi:[0,1,1]
	v_pk_fma_f32 v[10:11], v[146:147], v[42:43], v[10:11] op_sel_hi:[0,1,1]
	v_pk_fma_f32 v[0:1], v[146:147], v[44:45], v[0:1] op_sel_hi:[0,1,1]
	v_pk_fma_f32 v[2:3], v[146:147], v[46:47], v[2:3] op_sel_hi:[0,1,1]
	v_pk_fma_f32 v[4:5], v[146:147], v[48:49], v[4:5] op_sel_hi:[0,1,1]
	v_pk_add_f32 v[12:13], v[12:13], v[36:37]
	v_mov_b32_e32 v51, v6
	v_mov_b32_e32 v143, v7
	v_pk_mul_f32 v[6:7], v[140:141], v[106:107]
	v_pk_fma_f32 v[8:9], v[78:79], v[60:61], v[8:9] op_sel_hi:[0,1,1]
	v_pk_fma_f32 v[10:11], v[78:79], v[62:63], v[10:11] op_sel_hi:[0,1,1]
	v_pk_fma_f32 v[0:1], v[78:79], v[72:73], v[0:1] op_sel_hi:[0,1,1]
	v_pk_fma_f32 v[2:3], v[78:79], v[74:75], v[2:3] op_sel_hi:[0,1,1]
	v_pk_fma_f32 v[4:5], v[78:79], v[80:81], v[4:5] op_sel_hi:[0,1,1]
	v_pk_add_f32 v[12:13], v[12:13], v[18:19]
	v_mul_f32_e32 v50, v146, v50
	v_mov_b32_e32 v69, v6
	v_mov_b32_e32 v6, v141
	v_pk_fma_f32 v[8:9], v[140:141], v[84:85], v[8:9] op_sel_hi:[0,1,1]
	v_pk_fma_f32 v[10:11], v[140:141], v[86:87], v[10:11] op_sel_hi:[0,1,1]
	v_pk_fma_f32 v[0:1], v[140:141], v[88:89], v[0:1] op_sel_hi:[0,1,1]
	v_pk_fma_f32 v[2:3], v[140:141], v[90:91], v[2:3] op_sel_hi:[0,1,1]
	v_pk_fma_f32 v[4:5], v[140:141], v[92:93], v[4:5] op_sel_hi:[0,1,1]
	v_pk_add_f32 v[12:13], v[12:13], v[156:157]
	v_mov_b32_e32 v71, v7
	v_pk_fma_f32 v[8:9], v[6:7], v[96:97], v[8:9] op_sel_hi:[0,1,1]
	v_pk_fma_f32 v[10:11], v[6:7], v[98:99], v[10:11] op_sel_hi:[0,1,1]
	v_pk_fma_f32 v[0:1], v[6:7], v[100:101], v[0:1] op_sel_hi:[0,1,1]
	v_pk_fma_f32 v[2:3], v[6:7], v[102:103], v[2:3] op_sel_hi:[0,1,1]
	v_pk_fma_f32 v[4:5], v[6:7], v[104:105], v[4:5] op_sel_hi:[0,1,1]
	v_pk_add_f32 v[6:7], v[12:13], v[50:51]
	s_waitcnt vmcnt(0) lgkmcnt(0)
	v_mul_f32_e32 v34, v152, v130
	v_mov_b32_e32 v130, v119
	v_pk_fma_f32 v[8:9], v[138:139], v[108:109], v[8:9] op_sel_hi:[0,1,1]
	v_pk_fma_f32 v[10:11], v[138:139], v[110:111], v[10:11] op_sel_hi:[0,1,1]
	v_pk_fma_f32 v[0:1], v[138:139], v[112:113], v[0:1] op_sel_hi:[0,1,1]
	v_pk_fma_f32 v[2:3], v[138:139], v[114:115], v[2:3] op_sel_hi:[0,1,1]
	v_pk_fma_f32 v[4:5], v[138:139], v[116:117], v[4:5] op_sel_hi:[0,1,1]
	v_mov_b32_e32 v139, v152
	v_pk_add_f32 v[6:7], v[6:7], v[142:143]
	v_pk_fma_f32 v[24:25], v[152:153], v[124:125], v[0:1] op_sel_hi:[0,1,1]
	v_pk_fma_f32 v[26:27], v[152:153], v[126:127], v[2:3] op_sel_hi:[0,1,1]
	v_pk_mul_f32 v[0:1], v[138:139], v[130:131]
	v_pk_add_f32 v[2:3], v[6:7], v[68:69]
	v_mul_f32_e32 v64, v138, v118
	v_pk_add_f32 v[2:3], v[2:3], v[70:71]
	v_mov_b32_e32 v65, v0
	v_mov_b32_e32 v35, v1
	v_pk_add_f32 v[0:1], v[2:3], v[64:65]
	v_pk_fma_f32 v[28:29], v[152:153], v[120:121], v[8:9] op_sel_hi:[0,1,1]
	v_pk_fma_f32 v[30:31], v[152:153], v[122:123], v[10:11] op_sel_hi:[0,1,1]
	v_pk_fma_f32 v[22:23], v[152:153], v[128:129], v[4:5] op_sel_hi:[0,1,1]
	v_pk_add_f32 v[20:21], v[0:1], v[34:35]
	s_andn2_b64 exec, exec, s[16:17]
	s_cbranch_execnz .LBB0_218
	s_or_b64 exec, exec, s[16:17]
	ds_write2st64_b32 v165, v28, v29 offset1:1
	ds_write2st64_b32 v165, v30, v31 offset0:2 offset1:3
	ds_write2st64_b32 v165, v24, v25 offset0:4 offset1:5
	ds_write2st64_b32 v165, v26, v27 offset0:6 offset1:7
	ds_write2st64_b32 v165, v22, v23 offset0:8 offset1:9
	ds_write2st64_b32 v165, v20, v21 offset0:10 offset1:11
	s_waitcnt lgkmcnt(0)
	s_barrier
	s_and_saveexec_b64 s[16:17], vcc
	s_cbranch_execz .LBB0_216
	s_mul_hi_i32 s56, s18, 0xc000
	s_mul_i32 s57, s18, 0xc000
	s_mul_hi_i32 s19, s18, 12
	s_mul_i32 s18, s18, 12
	v_lshl_add_u64 v[0:1], s[14:15], 2, v[132:133]
	s_mov_b64 s[14:15], 0
	v_mov_b32_e32 v2, v159

; #define LAS __attribute__((address_space(3)))
; __device__ __forceinline__ unsigned cvt_pk_bf16(float lo, float hi) { unsigned r; asm volatile("v_cvt_pk_bf16_f32 %0, %1, %2" : "=v"(r) : "v"(lo), "v"(hi)); return r; }
; __device__ __forceinline__ bf16_t* wt_ptr(const Frame& F, int layer, size_t off) { return (bf16_t*)(F.ws + WS_WT + (size_t)layer * LWT + off); }
; __device__ __forceinline__ void transpose_item(const float* W, int K, int N, bf16_t* WT, int dest_row0, int k0, int n0, LAS float* scr, int lane) {
;     float wv[32];
; #pragma unroll
;     for (int i = 0; i < 32; ++i) { const int kk = 2 * i + (lane >> 5); wv[i] = LDG(float, W + (size_t)(k0 + kk) * N + n0 + (lane & 31)); }
; #pragma unroll
;     for (int i = 0; i < 32; ++i) { const int kk = 2 * i + (lane >> 5); scr[kk * 33 + (lane & 31)] = wv[i]; }
;     asm volatile("s_waitcnt lgkmcnt(0)" ::: "memory");
;     const int c = lane & 7;
; #pragma unroll
;     for (int j = 0; j < 4; ++j) { const int n = (lane >> 3) + 8 * j; const LAS float* s = scr + (8 * c) * 33 + n;
;         u32x4 o; o.x = cvt_pk_bf16(s[0 * 33], s[1 * 33]); o.y = cvt_pk_bf16(s[2 * 33], s[3 * 33]); o.z = cvt_pk_bf16(s[4 * 33], s[5 * 33]); o.w = cvt_pk_bf16(s[6 * 33], s[7 * 33]);
; __device__ __forceinline__ void phase_weights(const Frame& F0, int lmask, int cu0, int ncu, int pm) {
;     ...
;         for (int it = it_lo + gw_; it < it_hi; it += ngw_) {
;             int r = it;
;             if (r < I_Q) { const int nblk = NQ / 32, kb = r / nblk, nb = r % nblk; transpose_item(wqkv, DM, NQ, wt_ptr(F, layer, WT_QKV), 32 * nb, 64 * kb, 32 * nb, scr, F.lane); continue; } r -= I_Q;
;             if (r < I_O) { const int nblk = DM / 32, kb = r / nblk, nb = r % nblk; transpose_item(wo, DM, DM, wt_ptr(F, layer, WT_WO), 32 * nb, 64 * kb, 32 * nb, scr, F.lane); continue; } r -= I_O;
;             if (r < I_U) { const int nblk = 2 * DFF / 32, kb = r / nblk, nb = r % nblk; const int n0 = 32 * nb; const int half = n0 >= DFF ? 1 : 0, nn = n0 - half * DFF;
;                 const int drow = (nn >> 7) * 256 + half * 128 + (nn & 127);
;                 transpose_item(wup, DM, 2 * DFF, wt_ptr(F, layer, WT_UP), drow, 64 * kb, n0, scr, F.lane); continue; } r -= I_U;
;             { const int nblk = DM / 32, kb = r / nblk, nb = r % nblk; transpose_item(wdn, DFF, DM, wt_ptr(F, layer, WT_DOWN), 32 * nb, 64 * kb, 32 * nb, scr, F.lane); }
.LBB0_233:
	s_add_i32 s21, s68, s69
	s_cmpk_gt_i32 s21, 0x7ff
	s_cbranch_scc0 .LBB0_239
	s_cmpk_gt_u32 s21, 0x32ff
	s_cbranch_scc0 .LBB0_236
	s_and_b32 s4, s21, 0x7fffffc0
	s_add_i32 s18, s4, 0xffffcd00
	s_and_b32 s20, s26, 0x7e0
	v_add_u32_e32 v36, s18, v22
	s_lshl_b32 s4, s20, 2
	v_ashrrev_i32_e32 v37, 31, v36
	v_lshl_add_u64 v[38:39], v[6:7], 0, s[4:5]
	v_lshlrev_b64 v[36:37], 13, v[36:37]
	v_lshl_add_u64 v[36:37], v[38:39], 0, v[36:37]
	v_add_co_u32_e32 v38, vcc, 0x4000, v36
	s_mov_b32 s19, s5
	s_nop 0
	v_addc_co_u32_e32 v39, vcc, 0, v37, vcc
	v_add_co_u32_e32 v40, vcc, 0x8000, v36
	s_nop 1
	v_addc_co_u32_e32 v41, vcc, 0, v37, vcc
	v_add_co_u32_e32 v42, vcc, 0xc000, v36
	s_nop 1
	v_addc_co_u32_e32 v43, vcc, 0, v37, vcc
	v_add_co_u32_e32 v44, vcc, 0x10000, v36
	s_nop 1
	v_addc_co_u32_e32 v45, vcc, 0, v37, vcc
	v_add_co_u32_e32 v46, vcc, 0x14000, v36
	s_nop 1
	v_addc_co_u32_e32 v47, vcc, 0, v37, vcc
	v_add_co_u32_e32 v48, vcc, 0x18000, v36
	s_nop 1
	v_addc_co_u32_e32 v49, vcc, 0, v37, vcc
	v_add_co_u32_e32 v50, vcc, 0x1c000, v36
	s_nop 1
	v_addc_co_u32_e32 v51, vcc, 0, v37, vcc
	global_load_dword v5, v[36:37], off
	global_load_dword v54, v[38:39], off
	global_load_dword v55, v[40:41], off
	global_load_dword v56, v[42:43], off
	global_load_dword v57, v[44:45], off
	global_load_dword v58, v[46:47], off
	global_load_dword v59, v[48:49], off
	global_load_dword v60, v[50:51], off
	v_add_co_u32_e32 v38, vcc, 0x20000, v36
	s_nop 1
	v_addc_co_u32_e32 v39, vcc, 0, v37, vcc
	v_add_co_u32_e32 v40, vcc, 0x24000, v36
	s_nop 1
	v_addc_co_u32_e32 v41, vcc, 0, v37, vcc
	v_add_co_u32_e32 v42, vcc, 0x28000, v36
	s_nop 1
	v_addc_co_u32_e32 v43, vcc, 0, v37, vcc
	v_add_co_u32_e32 v44, vcc, 0x2c000, v36
	s_nop 1
	v_addc_co_u32_e32 v45, vcc, 0, v37, vcc
	v_add_co_u32_e32 v46, vcc, 0x30000, v36
	s_nop 1
	v_addc_co_u32_e32 v47, vcc, 0, v37, vcc
	v_add_co_u32_e32 v48, vcc, 0x34000, v36
	s_nop 1
	v_addc_co_u32_e32 v49, vcc, 0, v37, vcc
	v_add_co_u32_e32 v50, vcc, 0x38000, v36
	s_nop 1
	v_addc_co_u32_e32 v51, vcc, 0, v37, vcc
	v_add_co_u32_e32 v52, vcc, 0x3c000, v36
	s_nop 1
	v_addc_co_u32_e32 v53, vcc, 0, v37, vcc
	global_load_dword v61, v[38:39], off
	global_load_dword v62, v[40:41], off
	global_load_dword v63, v[42:43], off
	global_load_dword v64, v[44:45], off
	global_load_dword v65, v[46:47], off
	global_load_dword v66, v[48:49], off
	global_load_dword v67, v[50:51], off
	global_load_dword v68, v[52:53], off
	v_add_co_u32_e32 v38, vcc, 0x40000, v36
	s_nop 1
	v_addc_co_u32_e32 v39, vcc, 0, v37, vcc
	v_add_co_u32_e32 v40, vcc, 0x44000, v36
	s_nop 1
	v_addc_co_u32_e32 v41, vcc, 0, v37, vcc
	v_add_co_u32_e32 v42, vcc, 0x48000, v36
	s_nop 1
	v_addc_co_u32_e32 v43, vcc, 0, v37, vcc
	v_add_co_u32_e32 v44, vcc, 0x4c000, v36
	s_nop 1
	v_addc_co_u32_e32 v45, vcc, 0, v37, vcc
	v_add_co_u32_e32 v46, vcc, 0x50000, v36
	s_nop 1
	v_addc_co_u32_e32 v47, vcc, 0, v37, vcc
	v_add_co_u32_e32 v48, vcc, 0x54000, v36
	s_nop 1
	v_addc_co_u32_e32 v49, vcc, 0, v37, vcc
	v_add_co_u32_e32 v50, vcc, 0x58000, v36
	s_nop 1
	v_addc_co_u32_e32 v51, vcc, 0, v37, vcc
	v_add_co_u32_e32 v52, vcc, 0x5c000, v36
	s_nop 1
	v_addc_co_u32_e32 v53, vcc, 0, v37, vcc
	global_load_dword v69, v[38:39], off
	global_load_dword v70, v[40:41], off
	global_load_dword v71, v[42:43], off
	global_load_dword v72, v[44:45], off
	global_load_dword v73, v[46:47], off
	global_load_dword v74, v[48:49], off
	global_load_dword v75, v[50:51], off
	s_nop 0
	global_load_dword v52, v[52:53], off
	v_add_co_u32_e32 v38, vcc, 0x60000, v36
	s_nop 1
	v_addc_co_u32_e32 v39, vcc, 0, v37, vcc
	v_add_co_u32_e32 v40, vcc, 0x64000, v36
	s_nop 1
	v_addc_co_u32_e32 v41, vcc, 0, v37, vcc
	v_add_co_u32_e32 v42, vcc, 0x68000, v36
	s_nop 1
	v_addc_co_u32_e32 v43, vcc, 0, v37, vcc
	v_add_co_u32_e32 v44, vcc, 0x6c000, v36
	s_nop 1
	v_addc_co_u32_e32 v45, vcc, 0, v37, vcc
	v_add_co_u32_e32 v46, vcc, 0x70000, v36
	s_nop 1
	v_addc_co_u32_e32 v47, vcc, 0, v37, vcc
	v_add_co_u32_e32 v48, vcc, 0x74000, v36
	s_nop 1
	v_addc_co_u32_e32 v49, vcc, 0, v37, vcc
	v_add_co_u32_e32 v50, vcc, 0x78000, v36
	s_nop 1
	v_addc_co_u32_e32 v51, vcc, 0, v37, vcc
	v_add_co_u32_e32 v36, vcc, 0x7c000, v36
	s_nop 1
	v_addc_co_u32_e32 v37, vcc, 0, v37, vcc
	global_load_dword v38, v[38:39], off
	s_nop 0
	global_load_dword v39, v[40:41], off
	s_nop 0
	global_load_dword v40, v[42:43], off
	global_load_dword v41, v[44:45], off
	s_nop 0
	global_load_dword v42, v[46:47], off
	global_load_dword v43, v[48:49], off
	global_load_dword v44, v[50:51], off
	s_nop 0
	global_load_dword v36, v[36:37], off
	s_waitcnt vmcnt(0)
	ds_write2_b32 v23, v5, v54 offset1:66
	ds_write2_b32 v23, v55, v56 offset0:132 offset1:198
	ds_write2_b32 v29, v57, v58 offset0:8 offset1:74
	ds_write2_b32 v29, v59, v60 offset0:140 offset1:206
	ds_write2_b32 v30, v61, v62 offset0:16 offset1:82
	ds_write2_b32 v30, v63, v64 offset0:148 offset1:214
	ds_write2_b32 v31, v65, v66 offset0:24 offset1:90
	ds_write2_b32 v31, v67, v68 offset0:156 offset1:222
	ds_write2_b32 v32, v69, v70 offset0:32 offset1:98
	ds_write2_b32 v32, v71, v72 offset0:164 offset1:230
	ds_write2_b32 v33, v73, v74 offset0:40 offset1:106
	ds_write2_b32 v33, v75, v52 offset0:172 offset1:238
	ds_write2_b32 v34, v38, v39 offset0:48 offset1:114
	ds_write2_b32 v34, v40, v41 offset0:180 offset1:246
	ds_write2_b32 v35, v42, v43 offset0:56 offset1:122
	ds_write2_b32 v35, v44, v36 offset0:188 offset1:254
	s_waitcnt lgkmcnt(0)
	ds_read2_b32 v[36:37], v25 offset1:33
	s_waitcnt lgkmcnt(0)
	v_cvt_pk_bf16_f32 v36, v36, v37
	ds_read2_b32 v[38:39], v25 offset0:66 offset1:99
	s_waitcnt lgkmcnt(0)
; #define LAS __attribute__((address_space(3)))
; __device__ __forceinline__ unsigned cvt_pk_bf16(float lo, float hi) { unsigned r; asm volatile("v_cvt_pk_bf16_f32 %0, %1, %2" : "=v"(r) : "v"(lo), "v"(hi)); return r; }
; __device__ __forceinline__ bf16_t* wt_ptr(const Frame& F, int layer, size_t off) { return (bf16_t*)(F.ws + WS_WT + (size_t)layer * LWT + off); }
; __device__ __forceinline__ void transpose_item(const float* W, int K, int N, bf16_t* WT, int dest_row0, int k0, int n0, LAS float* scr, int lane) {
;     ...
;     const int c = lane & 7;
; #pragma unroll
;     for (int j = 0; j < 4; ++j) { const int n = (lane >> 3) + 8 * j; const LAS float* s = scr + (8 * c) * 33 + n;
;         u32x4 o; o.x = cvt_pk_bf16(s[0 * 33], s[1 * 33]); o.y = cvt_pk_bf16(s[2 * 33], s[3 * 33]); o.z = cvt_pk_bf16(s[4 * 33], s[5 * 33]); o.w = cvt_pk_bf16(s[6 * 33], s[7 * 33]);
;         STG(u32x4, WT + (size_t)(dest_row0 + n) * K + k0 + 8 * c) = o; }
;     asm volatile("s_waitcnt lgkmcnt(0)" ::: "memory");
; }
; __device__ __forceinline__ void phase_weights(const Frame& F0, int lmask, int cu0, int ncu, int pm) {
;     ...
;             if (r < I_U) { const int nblk = 2 * DFF / 32, kb = r / nblk, nb = r % nblk; const int n0 = 32 * nb; const int half = n0 >= DFF ? 1 : 0, nn = n0 - half * DFF;
;                 const int drow = (nn >> 7) * 256 + half * 128 + (nn & 127);
;                 transpose_item(wup, DM, 2 * DFF, wt_ptr(F, layer, WT_UP), drow, 64 * kb, n0, scr, F.lane); continue; } r -= I_U;
	v_cvt_pk_bf16_f32 v37, v38, v39
	ds_read2_b32 v[38:39], v25 offset0:132 offset1:165
	v_lshl_add_u64 v[42:43], s[18:19], 1, v[8:9]
	v_add_u32_e32 v5, s20, v24
	s_waitcnt lgkmcnt(0)
	v_cvt_pk_bf16_f32 v38, v38, v39
	ds_read2_b32 v[40:41], v25 offset0:198 offset1:231
	s_waitcnt lgkmcnt(0)
	v_cvt_pk_bf16_f32 v39, v40, v41
	v_mad_i64_i32 v[44:45], s[18:19], v5, s63, v[42:43]
	ds_read2_b32 v[40:41], v25 offset0:8 offset1:41
	global_store_dwordx4 v[44:45], v[36:39], off
	v_add_u32_e32 v5, s20, v26
	v_mad_i64_i32 v[44:45], s[18:19], v5, s63, v[42:43]
	s_waitcnt lgkmcnt(0)
	v_cvt_pk_bf16_f32 v36, v40, v41
	ds_read2_b32 v[38:39], v25 offset0:74 offset1:107
	s_waitcnt lgkmcnt(0)
	v_cvt_pk_bf16_f32 v37, v38, v39
	ds_read2_b32 v[38:39], v25 offset0:140 offset1:173
	s_waitcnt lgkmcnt(0)
	v_cvt_pk_bf16_f32 v38, v38, v39
	ds_read2_b32 v[40:41], v25 offset0:206 offset1:239
	s_waitcnt lgkmcnt(0)
	v_cvt_pk_bf16_f32 v39, v40, v41
	ds_read2_b32 v[40:41], v25 offset0:16 offset1:49
	global_store_dwordx4 v[44:45], v[36:39], off
	v_add_u32_e32 v5, s20, v27
	v_mad_i64_i32 v[44:45], s[18:19], v5, s63, v[42:43]
	s_waitcnt lgkmcnt(0)
	v_cvt_pk_bf16_f32 v36, v40, v41
	ds_read2_b32 v[38:39], v25 offset0:82 offset1:115
	s_waitcnt lgkmcnt(0)
	v_cvt_pk_bf16_f32 v37, v38, v39
	ds_read2_b32 v[38:39], v25 offset0:148 offset1:181
	s_waitcnt lgkmcnt(0)
	v_cvt_pk_bf16_f32 v38, v38, v39
	ds_read2_b32 v[40:41], v25 offset0:214 offset1:247
	s_waitcnt lgkmcnt(0)
	v_cvt_pk_bf16_f32 v39, v40, v41
	ds_read2_b32 v[40:41], v25 offset0:24 offset1:57
	global_store_dwordx4 v[44:45], v[36:39], off
	v_add_u32_e32 v5, s20, v28
	s_waitcnt lgkmcnt(0)
	v_cvt_pk_bf16_f32 v36, v40, v41
	ds_read2_b32 v[38:39], v25 offset0:90 offset1:123
	s_waitcnt lgkmcnt(0)
	v_cvt_pk_bf16_f32 v37, v38, v39
	ds_read2_b32 v[38:39], v25 offset0:156 offset1:189
	s_waitcnt lgkmcnt(0)
	v_cvt_pk_bf16_f32 v38, v38, v39
	ds_read2_b32 v[40:41], v25 offset0:222 offset1:255
	s_waitcnt lgkmcnt(0)
	v_cvt_pk_bf16_f32 v39, v40, v41
	v_mad_i64_i32 v[40:41], s[18:19], v5, s63, v[42:43]
	global_store_dwordx4 v[40:41], v[36:39], off
	s_mov_b64 s[18:19], 0
.LBB0_236:
	s_andn2_b64 vcc, exec, s[18:19]
	s_cbranch_vccnz .LBB0_238
	s_add_i32 s4, s21, 0xf800
	s_and_b32 s18, s4, 0xffff
	s_mul_i32 s18, s18, 0xbe83
	s_lshr_b32 s20, s18, 24
	s_mul_i32 s18, s20, 0x158
	s_sub_i32 s4, s4, s18
	s_lshl_b32 s70, s4, 5
	s_and_b32 s71, s70, 0xffe0
	s_and_b32 s4, s4, 0xffff
	s_cmpk_gt_u32 s4, 0xab
	s_cselect_b32 s72, 0xffffea80, 0
	s_cselect_b32 s73, 0x80, 0
	v_lshl_add_u32 v5, s20, 6, v22
	s_lshl_b32 s4, s71, 2
	v_lshl_add_u64 v[36:37], v[10:11], 0, s[4:5]
	v_add_u32_e32 v40, 2, v5
	v_add_u32_e32 v42, 4, v5
	v_add_u32_e32 v44, 6, v5
	v_add_u32_e32 v46, 8, v5
	v_add_u32_e32 v48, 10, v5
	v_add_u32_e32 v50, 12, v5
	v_add_u32_e32 v52, 14, v5
	v_mad_i64_i32 v[38:39], s[18:19], v5, s64, v[36:37]
	v_mad_i64_i32 v[40:41], s[18:19], v40, s64, v[36:37]
	v_mad_i64_i32 v[42:43], s[18:19], v42, s64, v[36:37]
	v_mad_i64_i32 v[44:45], s[18:19], v44, s64, v[36:37]
	v_mad_i64_i32 v[46:47], s[18:19], v46, s64, v[36:37]
	v_mad_i64_i32 v[48:49], s[18:19], v48, s64, v[36:37]
	v_mad_i64_i32 v[50:51], s[18:19], v50, s64, v[36:37]
	v_mad_i64_i32 v[52:53], s[18:19], v52, s64, v[36:37]
	global_load_dword v54, v[38:39], off
	global_load_dword v55, v[40:41], off
	global_load_dword v56, v[42:43], off
	global_load_dword v57, v[44:45], off
	global_load_dword v58, v[46:47], off
	global_load_dword v59, v[48:49], off
	global_load_dword v60, v[50:51], off
	global_load_dword v61, v[52:53], off
	v_add_u32_e32 v38, 16, v5
	v_add_u32_e32 v40, 18, v5
	v_add_u32_e32 v42, 20, v5
	v_add_u32_e32 v44, 22, v5
	v_add_u32_e32 v46, 24, v5
	v_add_u32_e32 v48, 26, v5
	v_add_u32_e32 v50, 28, v5
	v_add_u32_e32 v52, 30, v5
	v_mad_i64_i32 v[38:39], s[18:19], v38, s64, v[36:37]
	v_mad_i64_i32 v[40:41], s[18:19], v40, s64, v[36:37]
	v_mad_i64_i32 v[42:43], s[18:19], v42, s64, v[36:37]
	v_mad_i64_i32 v[44:45], s[18:19], v44, s64, v[36:37]
	v_mad_i64_i32 v[46:47], s[18:19], v46, s64, v[36:37]
	v_mad_i64_i32 v[48:49], s[18:19], v48, s64, v[36:37]
	v_mad_i64_i32 v[50:51], s[18:19], v50, s64, v[36:37]
	v_mad_i64_i32 v[52:53], s[18:19], v52, s64, v[36:37]
	global_load_dword v62, v[38:39], off
	global_load_dword v63, v[40:41], off
	global_load_dword v64, v[42:43], off
	global_load_dword v65, v[44:45], off
	global_load_dword v66, v[46:47], off
	global_load_dword v67, v[48:49], off
	global_load_dword v68, v[50:51], off
	global_load_dword v69, v[52:53], off
	v_add_u32_e32 v38, 32, v5
	v_add_u32_e32 v40, 34, v5
	v_add_u32_e32 v42, 36, v5
	v_add_u32_e32 v44, 38, v5
	v_add_u32_e32 v46, 40, v5
	v_add_u32_e32 v48, 42, v5
	v_add_u32_e32 v50, 44, v5
	v_add_u32_e32 v52, 46, v5
	v_mad_i64_i32 v[38:39], s[18:19], v38, s64, v[36:37]
	v_mad_i64_i32 v[40:41], s[18:19], v40, s64, v[36:37]
	v_mad_i64_i32 v[42:43], s[18:19], v42, s64, v[36:37]
	v_mad_i64_i32 v[44:45], s[18:19], v44, s64, v[36:37]
	v_mad_i64_i32 v[46:47], s[18:19], v46, s64, v[36:37]
	v_mad_i64_i32 v[48:49], s[18:19], v48, s64, v[36:37]
	v_mad_i64_i32 v[50:51], s[18:19], v50, s64, v[36:37]
	v_mad_i64_i32 v[52:53], s[18:19], v52, s64, v[36:37]
	global_load_dword v70, v[38:39], off
	global_load_dword v71, v[40:41], off
	global_load_dword v72, v[42:43], off
	global_load_dword v73, v[44:45], off
	global_load_dword v74, v[46:47], off
	global_load_dword v75, v[48:49], off
	global_load_dword v76, v[50:51], off
	s_nop 0
	global_load_dword v52, v[52:53], off
	v_add_u32_e32 v38, 48, v5
	v_add_u32_e32 v40, 50, v5
	v_add_u32_e32 v42, 52, v5
	v_add_u32_e32 v44, 54, v5
	v_add_u32_e32 v46, 56, v5
	v_add_u32_e32 v48, 58, v5
	v_add_u32_e32 v50, 60, v5
	v_add_u32_e32 v5, 62, v5
	v_mad_i64_i32 v[38:39], s[18:19], v38, s64, v[36:37]
	v_mad_i64_i32 v[40:41], s[18:19], v40, s64, v[36:37]
	v_mad_i64_i32 v[42:43], s[18:19], v42, s64, v[36:37]
	v_mad_i64_i32 v[44:45], s[18:19], v44, s64, v[36:37]
	v_mad_i64_i32 v[46:47], s[18:19], v46, s64, v[36:37]
	v_mad_i64_i32 v[48:49], s[18:19], v48, s64, v[36:37]
	v_mad_i64_i32 v[50:51], s[18:19], v50, s64, v[36:37]
	v_mad_i64_i32 v[36:37], s[18:19], v5, s64, v[36:37]
	global_load_dword v5, v[38:39], off
	s_nop 0
	global_load_dword v38, v[40:41], off
	global_load_dword v39, v[42:43], off
	s_nop 0
	global_load_dword v40, v[44:45], off
	global_load_dword v41, v[46:47], off
	global_load_dword v42, v[48:49], off
	global_load_dword v43, v[50:51], off
	s_nop 0
	global_load_dword v36, v[36:37], off
	s_waitcnt vmcnt(0)
; #define LAS __attribute__((address_space(3)))
; __device__ __forceinline__ unsigned cvt_pk_bf16(float lo, float hi) { unsigned r; asm volatile("v_cvt_pk_bf16_f32 %0, %1, %2" : "=v"(r) : "v"(lo), "v"(hi)); return r; }
; __device__ __forceinline__ bf16_t* wt_ptr(const Frame& F, int layer, size_t off) { return (bf16_t*)(F.ws + WS_WT + (size_t)layer * LWT + off); }
; __device__ __forceinline__ void transpose_item(const float* W, int K, int N, bf16_t* WT, int dest_row0, int k0, int n0, LAS float* scr, int lane) {
;     ...
;     for (int i = 0; i < 32; ++i) { const int kk = 2 * i + (lane >> 5); scr[kk * 33 + (lane & 31)] = wv[i]; }
;     asm volatile("s_waitcnt lgkmcnt(0)" ::: "memory");
;     const int c = lane & 7;
; #pragma unroll
;     for (int j = 0; j < 4; ++j) { const int n = (lane >> 3) + 8 * j; const LAS float* s = scr + (8 * c) * 33 + n;
;         u32x4 o; o.x = cvt_pk_bf16(s[0 * 33], s[1 * 33]); o.y = cvt_pk_bf16(s[2 * 33], s[3 * 33]); o.z = cvt_pk_bf16(s[4 * 33], s[5 * 33]); o.w = cvt_pk_bf16(s[6 * 33], s[7 * 33]);
;         STG(u32x4, WT + (size_t)(dest_row0 + n) * K + k0 + 8 * c) = o; }
;     asm volatile("s_waitcnt lgkmcnt(0)" ::: "memory");
; }
; __device__ __forceinline__ void phase_weights(const Frame& F0, int lmask, int cu0, int ncu, int pm) {
;     ...
;             if (r < I_O) { const int nblk = DM / 32, kb = r / nblk, nb = r % nblk; transpose_item(wo, DM, DM, wt_ptr(F, layer, WT_WO), 32 * nb, 64 * kb, 32 * nb, scr, F.lane); continue; } r -= I_O;
	ds_write2_b32 v23, v54, v55 offset1:66
	ds_write2_b32 v23, v56, v57 offset0:132 offset1:198
	ds_write2_b32 v29, v58, v59 offset0:8 offset1:74
	ds_write2_b32 v29, v60, v61 offset0:140 offset1:206
	ds_write2_b32 v30, v62, v63 offset0:16 offset1:82
	ds_write2_b32 v30, v64, v65 offset0:148 offset1:214
	ds_write2_b32 v31, v66, v67 offset0:24 offset1:90
	ds_write2_b32 v31, v68, v69 offset0:156 offset1:222
	ds_write2_b32 v32, v70, v71 offset0:32 offset1:98
	ds_write2_b32 v32, v72, v73 offset0:164 offset1:230
	ds_write2_b32 v33, v74, v75 offset0:40 offset1:106
	ds_write2_b32 v33, v76, v52 offset0:172 offset1:238
	ds_write2_b32 v34, v5, v38 offset0:48 offset1:114
	ds_write2_b32 v34, v39, v40 offset0:180 offset1:246
	ds_write2_b32 v35, v41, v42 offset0:56 offset1:122
	ds_write2_b32 v35, v43, v36 offset0:188 offset1:254
	s_waitcnt lgkmcnt(0)
	ds_read2_b32 v[36:37], v25 offset1:33
	s_add_i32 s72, s72, s71
	s_waitcnt lgkmcnt(0)
	v_cvt_pk_bf16_f32 v36, v36, v37
	ds_read2_b32 v[38:39], v25 offset0:66 offset1:99
	s_lshl_b32 s4, s72, 1
	s_and_b32 s18, s70, 0x60
	s_waitcnt lgkmcnt(0)
	v_cvt_pk_bf16_f32 v37, v38, v39
	ds_read2_b32 v[38:39], v25 offset0:132 offset1:165
	s_and_b32 s4, s4, 0xffffff00
	s_or_b32 s18, s18, s73
	s_waitcnt lgkmcnt(0)
	v_cvt_pk_bf16_f32 v38, v38, v39
	ds_read2_b32 v[40:41], v25 offset0:198 offset1:231
	s_or_b32 s18, s18, s4
	s_waitcnt lgkmcnt(0)
	v_cvt_pk_bf16_f32 v39, v40, v41
	v_add_u32_e32 v40, s18, v24
	s_lshl_b32 s4, s20, 7
	v_ashrrev_i32_e32 v41, 31, v40
	v_lshl_add_u64 v[42:43], v[12:13], 0, s[4:5]
	v_lshlrev_b64 v[40:41], 12, v[40:41]
	v_lshl_add_u64 v[40:41], v[42:43], 0, v[40:41]
	ds_read2_b32 v[44:45], v25 offset0:8 offset1:41
	global_store_dwordx4 v[40:41], v[36:39], off
	s_waitcnt lgkmcnt(0)
	s_nop 0
	v_cvt_pk_bf16_f32 v36, v44, v45
	ds_read2_b32 v[38:39], v25 offset0:74 offset1:107
	s_waitcnt lgkmcnt(0)
	v_cvt_pk_bf16_f32 v37, v38, v39
	ds_read2_b32 v[38:39], v25 offset0:140 offset1:173
	s_waitcnt lgkmcnt(0)
	v_cvt_pk_bf16_f32 v38, v38, v39
	ds_read2_b32 v[40:41], v25 offset0:206 offset1:239
	s_waitcnt lgkmcnt(0)
	v_cvt_pk_bf16_f32 v39, v40, v41
	v_add_u32_e32 v40, s18, v26
	v_ashrrev_i32_e32 v41, 31, v40
	v_lshlrev_b64 v[40:41], 12, v[40:41]
	v_lshl_add_u64 v[40:41], v[42:43], 0, v[40:41]
	ds_read2_b32 v[44:45], v25 offset0:16 offset1:49
	global_store_dwordx4 v[40:41], v[36:39], off
	s_waitcnt lgkmcnt(0)
	s_nop 0
	v_cvt_pk_bf16_f32 v36, v44, v45
	ds_read2_b32 v[38:39], v25 offset0:82 offset1:115
	s_waitcnt lgkmcnt(0)
	v_cvt_pk_bf16_f32 v37, v38, v39
	ds_read2_b32 v[38:39], v25 offset0:148 offset1:181
	s_waitcnt lgkmcnt(0)
	v_cvt_pk_bf16_f32 v38, v38, v39
	ds_read2_b32 v[40:41], v25 offset0:214 offset1:247
	s_waitcnt lgkmcnt(0)
	v_cvt_pk_bf16_f32 v39, v40, v41
	v_add_u32_e32 v40, s18, v27
	v_ashrrev_i32_e32 v41, 31, v40
	v_lshlrev_b64 v[40:41], 12, v[40:41]
	v_lshl_add_u64 v[40:41], v[42:43], 0, v[40:41]
	ds_read2_b32 v[44:45], v25 offset0:24 offset1:57
	global_store_dwordx4 v[40:41], v[36:39], off
	s_waitcnt lgkmcnt(0)
	s_nop 0
	v_cvt_pk_bf16_f32 v36, v44, v45
	ds_read2_b32 v[38:39], v25 offset0:90 offset1:123
	s_waitcnt lgkmcnt(0)
	v_cvt_pk_bf16_f32 v37, v38, v39
	ds_read2_b32 v[38:39], v25 offset0:156 offset1:189
	s_waitcnt lgkmcnt(0)
	v_cvt_pk_bf16_f32 v38, v38, v39
	ds_read2_b32 v[40:41], v25 offset0:222 offset1:255
	s_waitcnt lgkmcnt(0)
	v_cvt_pk_bf16_f32 v39, v40, v41
	v_add_u32_e32 v40, s18, v28
	v_ashrrev_i32_e32 v41, 31, v40
	v_lshlrev_b64 v[40:41], 12, v[40:41]
	v_lshl_add_u64 v[40:41], v[42:43], 0, v[40:41]
	global_store_dwordx4 v[40:41], v[36:39], off
.LBB0_238:
	s_mov_b64 s[18:19], 0
.LBB0_239:
	s_andn2_b64 vcc, exec, s[18:19]
	s_cbranch_vccnz .LBB0_241
	s_ashr_i32 s4, s21, 31
	s_lshr_b32 s4, s4, 26
	s_add_i32 s4, s21, s4
	s_and_b32 s20, s4, 0xffffffc0
	s_sub_i32 s4, s21, s20
	s_lshl_b32 s18, s4, 5
	v_add_u32_e32 v36, s20, v22
	s_ashr_i32 s19, s18, 31
	v_ashrrev_i32_e32 v37, 31, v36
	v_lshl_add_u64 v[38:39], s[18:19], 2, v[14:15]
	v_lshlrev_b64 v[36:37], 13, v[36:37]
	v_lshl_add_u64 v[36:37], v[38:39], 0, v[36:37]
	v_add_co_u32_e32 v38, vcc, s31, v36
	s_ashr_i32 s21, s20, 31
	s_nop 0
	v_addc_co_u32_e32 v39, vcc, 0, v37, vcc
	v_add_co_u32_e32 v40, vcc, s33, v36
	s_nop 1
	v_addc_co_u32_e32 v41, vcc, 0, v37, vcc
	v_add_co_u32_e32 v42, vcc, s34, v36
	s_nop 1
	v_addc_co_u32_e32 v43, vcc, 0, v37, vcc
	v_add_co_u32_e32 v44, vcc, s35, v36
	s_nop 1
	v_addc_co_u32_e32 v45, vcc, 0, v37, vcc
	v_add_co_u32_e32 v46, vcc, s36, v36
	s_nop 1
	v_addc_co_u32_e32 v47, vcc, 0, v37, vcc
	v_add_co_u32_e32 v48, vcc, s37, v36
	s_nop 1
	v_addc_co_u32_e32 v49, vcc, 0, v37, vcc
	v_add_co_u32_e32 v50, vcc, s38, v36
	s_nop 1
	v_addc_co_u32_e32 v51, vcc, 0, v37, vcc
	global_load_dword v5, v[36:37], off
	global_load_dword v54, v[38:39], off
	global_load_dword v55, v[40:41], off
	global_load_dword v56, v[42:43], off
	global_load_dword v57, v[44:45], off
	global_load_dword v58, v[46:47], off
	global_load_dword v59, v[48:49], off
	global_load_dword v60, v[50:51], off
	v_add_co_u32_e32 v38, vcc, s39, v36
	s_nop 1
	v_addc_co_u32_e32 v39, vcc, 0, v37, vcc
	v_add_co_u32_e32 v40, vcc, s40, v36
	s_nop 1
	v_addc_co_u32_e32 v41, vcc, 0, v37, vcc
	v_add_co_u32_e32 v42, vcc, s41, v36
	s_nop 1
	v_addc_co_u32_e32 v43, vcc, 0, v37, vcc
	v_add_co_u32_e32 v44, vcc, s42, v36
	s_nop 1
	v_addc_co_u32_e32 v45, vcc, 0, v37, vcc
	v_add_co_u32_e32 v46, vcc, s43, v36
	s_nop 1
	v_addc_co_u32_e32 v47, vcc, 0, v37, vcc
	v_add_co_u32_e32 v48, vcc, s44, v36
	s_nop 1
	v_addc_co_u32_e32 v49, vcc, 0, v37, vcc
	v_add_co_u32_e32 v50, vcc, s45, v36
	s_nop 1
	v_addc_co_u32_e32 v51, vcc, 0, v37, vcc
	v_add_co_u32_e32 v52, vcc, s46, v36
	s_nop 1
	v_addc_co_u32_e32 v53, vcc, 0, v37, vcc
; #define LAS __attribute__((address_space(3)))
; __device__ __forceinline__ unsigned cvt_pk_bf16(float lo, float hi) { unsigned r; asm volatile("v_cvt_pk_bf16_f32 %0, %1, %2" : "=v"(r) : "v"(lo), "v"(hi)); return r; }
; __device__ __forceinline__ void transpose_item(const float* W, int K, int N, bf16_t* WT, int dest_row0, int k0, int n0, LAS float* scr, int lane) {
;     ...
;     for (int i = 0; i < 32; ++i) { const int kk = 2 * i + (lane >> 5); wv[i] = LDG(float, W + (size_t)(k0 + kk) * N + n0 + (lane & 31)); }
; #pragma unroll
;     for (int i = 0; i < 32; ++i) { const int kk = 2 * i + (lane >> 5); scr[kk * 33 + (lane & 31)] = wv[i]; }
;     asm volatile("s_waitcnt lgkmcnt(0)" ::: "memory");
;     const int c = lane & 7;
; #pragma unroll
;     for (int j = 0; j < 4; ++j) { const int n = (lane >> 3) + 8 * j; const LAS float* s = scr + (8 * c) * 33 + n;
;         u32x4 o; o.x = cvt_pk_bf16(s[0 * 33], s[1 * 33]); o.y = cvt_pk_bf16(s[2 * 33], s[3 * 33]); o.z = cvt_pk_bf16(s[4 * 33], s[5 * 33]); o.w = cvt_pk_bf16(s[6 * 33], s[7 * 33]);
;         STG(u32x4, WT + (size_t)(dest_row0 + n) * K + k0 + 8 * c) = o; }
	global_load_dword v61, v[38:39], off
	global_load_dword v62, v[40:41], off
	global_load_dword v63, v[42:43], off
	global_load_dword v64, v[44:45], off
	global_load_dword v65, v[46:47], off
	global_load_dword v66, v[48:49], off
	global_load_dword v67, v[50:51], off
	global_load_dword v68, v[52:53], off
	v_add_co_u32_e32 v38, vcc, s47, v36
	s_nop 1
	v_addc_co_u32_e32 v39, vcc, 0, v37, vcc
	v_add_co_u32_e32 v40, vcc, s48, v36
	s_nop 1
	v_addc_co_u32_e32 v41, vcc, 0, v37, vcc
	v_add_co_u32_e32 v42, vcc, s49, v36
	s_nop 1
	v_addc_co_u32_e32 v43, vcc, 0, v37, vcc
	v_add_co_u32_e32 v44, vcc, s50, v36
	s_nop 1
	v_addc_co_u32_e32 v45, vcc, 0, v37, vcc
	v_add_co_u32_e32 v46, vcc, s51, v36
	s_nop 1
	v_addc_co_u32_e32 v47, vcc, 0, v37, vcc
	v_add_co_u32_e32 v48, vcc, s52, v36
	s_nop 1
	v_addc_co_u32_e32 v49, vcc, 0, v37, vcc
	v_add_co_u32_e32 v50, vcc, s53, v36
	s_nop 1
	v_addc_co_u32_e32 v51, vcc, 0, v37, vcc
	v_add_co_u32_e32 v52, vcc, s54, v36
	s_nop 1
	v_addc_co_u32_e32 v53, vcc, 0, v37, vcc
	global_load_dword v69, v[38:39], off
	global_load_dword v70, v[40:41], off
	global_load_dword v71, v[42:43], off
	global_load_dword v72, v[44:45], off
	global_load_dword v73, v[46:47], off
	global_load_dword v74, v[48:49], off
	global_load_dword v75, v[50:51], off
	s_nop 0
	global_load_dword v52, v[52:53], off
	v_add_co_u32_e32 v38, vcc, s55, v36
	s_nop 1
	v_addc_co_u32_e32 v39, vcc, 0, v37, vcc
	v_add_co_u32_e32 v40, vcc, s56, v36
	s_nop 1
	v_addc_co_u32_e32 v41, vcc, 0, v37, vcc
	v_add_co_u32_e32 v42, vcc, s57, v36
	s_nop 1
	v_addc_co_u32_e32 v43, vcc, 0, v37, vcc
	v_add_co_u32_e32 v44, vcc, s58, v36
	s_nop 1
	v_addc_co_u32_e32 v45, vcc, 0, v37, vcc
	v_add_co_u32_e32 v46, vcc, s59, v36
	s_nop 1
	v_addc_co_u32_e32 v47, vcc, 0, v37, vcc
	v_add_co_u32_e32 v48, vcc, s60, v36
	s_nop 1
	v_addc_co_u32_e32 v49, vcc, 0, v37, vcc
	v_add_co_u32_e32 v50, vcc, s61, v36
	s_nop 1
	v_addc_co_u32_e32 v51, vcc, 0, v37, vcc
	v_add_co_u32_e32 v36, vcc, s62, v36
	s_nop 1
	v_addc_co_u32_e32 v37, vcc, 0, v37, vcc
	global_load_dword v38, v[38:39], off
	s_nop 0
	global_load_dword v39, v[40:41], off
	s_nop 0
	global_load_dword v40, v[42:43], off
	global_load_dword v41, v[44:45], off
	s_nop 0
	global_load_dword v42, v[46:47], off
	global_load_dword v43, v[48:49], off
	global_load_dword v44, v[50:51], off
	s_nop 0
	global_load_dword v36, v[36:37], off
	s_waitcnt vmcnt(0)
	ds_write2_b32 v23, v5, v54 offset1:66
	ds_write2_b32 v23, v55, v56 offset0:132 offset1:198
	ds_write2_b32 v29, v57, v58 offset0:8 offset1:74
	ds_write2_b32 v29, v59, v60 offset0:140 offset1:206
	ds_write2_b32 v30, v61, v62 offset0:16 offset1:82
	ds_write2_b32 v30, v63, v64 offset0:148 offset1:214
	ds_write2_b32 v31, v65, v66 offset0:24 offset1:90
	ds_write2_b32 v31, v67, v68 offset0:156 offset1:222
	ds_write2_b32 v32, v69, v70 offset0:32 offset1:98
	ds_write2_b32 v32, v71, v72 offset0:164 offset1:230
	ds_write2_b32 v33, v73, v74 offset0:40 offset1:106
	ds_write2_b32 v33, v75, v52 offset0:172 offset1:238
	ds_write2_b32 v34, v38, v39 offset0:48 offset1:114
	ds_write2_b32 v34, v40, v41 offset0:180 offset1:246
	ds_write2_b32 v35, v42, v43 offset0:56 offset1:122
	ds_write2_b32 v35, v44, v36 offset0:188 offset1:254
	s_waitcnt lgkmcnt(0)
	ds_read2_b32 v[36:37], v25 offset1:33
	s_waitcnt lgkmcnt(0)
	v_cvt_pk_bf16_f32 v36, v36, v37
	ds_read2_b32 v[38:39], v25 offset0:66 offset1:99
	s_waitcnt lgkmcnt(0)
	v_cvt_pk_bf16_f32 v37, v38, v39
	ds_read2_b32 v[38:39], v25 offset0:132 offset1:165
	s_waitcnt lgkmcnt(0)
	v_cvt_pk_bf16_f32 v38, v38, v39
	ds_read2_b32 v[40:41], v25 offset0:198 offset1:231
	s_waitcnt lgkmcnt(0)
	v_cvt_pk_bf16_f32 v39, v40, v41
	v_add_u32_e32 v40, s18, v24
	v_ashrrev_i32_e32 v41, 31, v40
	v_lshl_add_u64 v[42:43], s[20:21], 1, v[16:17]
	v_lshlrev_b64 v[40:41], 12, v[40:41]
	v_lshl_add_u64 v[40:41], v[42:43], 0, v[40:41]
	ds_read2_b32 v[44:45], v25 offset0:8 offset1:41
	global_store_dwordx4 v[40:41], v[36:39], off
	s_waitcnt lgkmcnt(0)
	s_nop 0
	v_cvt_pk_bf16_f32 v36, v44, v45
	ds_read2_b32 v[38:39], v25 offset0:74 offset1:107
	s_waitcnt lgkmcnt(0)
	v_cvt_pk_bf16_f32 v37, v38, v39
	ds_read2_b32 v[38:39], v25 offset0:140 offset1:173
	s_waitcnt lgkmcnt(0)
	v_cvt_pk_bf16_f32 v38, v38, v39
	ds_read2_b32 v[40:41], v25 offset0:206 offset1:239
	s_waitcnt lgkmcnt(0)
	v_cvt_pk_bf16_f32 v39, v40, v41
	v_add_u32_e32 v40, s18, v26
	v_ashrrev_i32_e32 v41, 31, v40
	v_lshlrev_b64 v[40:41], 12, v[40:41]
	v_lshl_add_u64 v[40:41], v[42:43], 0, v[40:41]
	ds_read2_b32 v[44:45], v25 offset0:16 offset1:49
	global_store_dwordx4 v[40:41], v[36:39], off
	s_waitcnt lgkmcnt(0)
	s_nop 0
	v_cvt_pk_bf16_f32 v36, v44, v45
	ds_read2_b32 v[38:39], v25 offset0:82 offset1:115
	s_waitcnt lgkmcnt(0)
	v_cvt_pk_bf16_f32 v37, v38, v39
	ds_read2_b32 v[38:39], v25 offset0:148 offset1:181
	s_waitcnt lgkmcnt(0)
	v_cvt_pk_bf16_f32 v38, v38, v39
	ds_read2_b32 v[40:41], v25 offset0:214 offset1:247
	s_waitcnt lgkmcnt(0)
	v_cvt_pk_bf16_f32 v39, v40, v41
	v_add_u32_e32 v40, s18, v27
	v_ashrrev_i32_e32 v41, 31, v40
	v_lshlrev_b64 v[40:41], 12, v[40:41]
	v_lshl_add_u64 v[40:41], v[42:43], 0, v[40:41]
	ds_read2_b32 v[44:45], v25 offset0:24 offset1:57
	global_store_dwordx4 v[40:41], v[36:39], off
	s_waitcnt lgkmcnt(0)
	s_nop 0
	v_cvt_pk_bf16_f32 v36, v44, v45
	ds_read2_b32 v[38:39], v25 offset0:90 offset1:123
	s_waitcnt lgkmcnt(0)
	v_cvt_pk_bf16_f32 v37, v38, v39
	ds_read2_b32 v[38:39], v25 offset0:156 offset1:189
	s_waitcnt lgkmcnt(0)
	v_cvt_pk_bf16_f32 v38, v38, v39
	ds_read2_b32 v[40:41], v25 offset0:222 offset1:255
	s_waitcnt lgkmcnt(0)
	v_cvt_pk_bf16_f32 v39, v40, v41
	v_add_u32_e32 v40, s18, v28
	v_ashrrev_i32_e32 v41, 31, v40
	v_lshlrev_b64 v[40:41], 12, v[40:41]
	v_lshl_add_u64 v[40:41], v[42:43], 0, v[40:41]
	global_store_dwordx4 v[40:41], v[36:39], off
; #define LAS __attribute__((address_space(3)))
; __device__ __forceinline__ bf16_t* wt_ptr(const Frame& F, int layer, size_t off) { return (bf16_t*)(F.ws + WS_WT + (size_t)layer * LWT + off); }
; __device__ __forceinline__ void transpose_item(const float* W, int K, int N, bf16_t* WT, int dest_row0, int k0, int n0, LAS float* scr, int lane) {
;     float wv[32];
; #pragma unroll
;     for (int i = 0; i < 32; ++i) { const int kk = 2 * i + (lane >> 5); wv[i] = LDG(float, W + (size_t)(k0 + kk) * N + n0 + (lane & 31)); }
; #pragma unroll
;     for (int i = 0; i < 32; ++i) { const int kk = 2 * i + (lane >> 5); scr[kk * 33 + (lane & 31)] = wv[i]; }
; __device__ __forceinline__ void phase_weights(const Frame& F0, int lmask, int cu0, int ncu, int pm) {
;     ...
;             if (r < I_Q) { const int nblk = NQ / 32, kb = r / nblk, nb = r % nblk; transpose_item(wqkv, DM, NQ, wt_ptr(F, layer, WT_QKV), 32 * nb, 64 * kb, 32 * nb, scr, F.lane); continue; } r -= I_Q;
.LBB0_241:
	s_cbranch_execnz .LBB0_230
.LBB0_242:
	s_abs_i32 s18, s69
	s_mul_hi_u32 s19, s18, s24
	s_mul_i32 s20, s19, s22
	s_ashr_i32 s4, s69, 31
	s_sub_i32 s18, s18, s20
	s_xor_b32 s4, s4, s23
	s_add_i32 s20, s19, 1
	s_sub_i32 s21, s18, s22
	s_cmp_ge_u32 s18, s22
	s_cselect_b32 s19, s20, s19
	s_cselect_b32 s18, s21, s18
	s_add_i32 s20, s19, 1
	s_cmp_ge_u32 s18, s22
	s_cselect_b32 s18, s20, s19
	s_xor_b32 s18, s18, s4
	s_sub_i32 s4, s18, s4
	s_mul_i32 s18, s25, s4
	s_lshl_b32 s20, s4, 6
	s_add_i32 s18, s26, s18
	v_add_u32_e32 v5, s20, v22
	s_ashr_i32 s19, s18, 31
	v_add_u32_e32 v40, 2, v5
	v_add_u32_e32 v42, 4, v5
	v_add_u32_e32 v44, 6, v5
	v_add_u32_e32 v46, 8, v5
	v_add_u32_e32 v48, 10, v5
	v_add_u32_e32 v50, 12, v5
	v_lshl_add_u64 v[36:37], s[18:19], 2, v[18:19]
	v_mad_i64_i32 v[38:39], s[70:71], v5, s66, 0
	v_mad_i64_i32 v[40:41], s[70:71], v40, s66, 0
	v_mad_i64_i32 v[42:43], s[70:71], v42, s66, 0
	v_mad_i64_i32 v[44:45], s[70:71], v44, s66, 0
	v_mad_i64_i32 v[46:47], s[70:71], v46, s66, 0
	v_mad_i64_i32 v[48:49], s[70:71], v48, s66, 0
	v_mad_i64_i32 v[50:51], s[70:71], v50, s66, 0
	v_add_u32_e32 v52, 14, v5
	v_lshl_add_u64 v[38:39], v[38:39], 2, v[36:37]
	v_lshl_add_u64 v[40:41], v[40:41], 2, v[36:37]
	v_lshl_add_u64 v[42:43], v[42:43], 2, v[36:37]
	v_lshl_add_u64 v[44:45], v[44:45], 2, v[36:37]
	v_lshl_add_u64 v[46:47], v[46:47], 2, v[36:37]
	v_lshl_add_u64 v[48:49], v[48:49], 2, v[36:37]
	v_lshl_add_u64 v[50:51], v[50:51], 2, v[36:37]
	v_mad_i64_i32 v[52:53], s[70:71], v52, s66, 0
	v_lshl_add_u64 v[52:53], v[52:53], 2, v[36:37]
	global_load_dword v54, v[38:39], off
	global_load_dword v55, v[40:41], off
	global_load_dword v56, v[42:43], off
	global_load_dword v57, v[44:45], off
	global_load_dword v58, v[46:47], off
	global_load_dword v59, v[48:49], off
	global_load_dword v60, v[50:51], off
	global_load_dword v61, v[52:53], off
	v_add_u32_e32 v38, 16, v5
	v_add_u32_e32 v40, 18, v5
	v_add_u32_e32 v42, 20, v5
	v_add_u32_e32 v44, 22, v5
	v_add_u32_e32 v46, 24, v5
	v_add_u32_e32 v48, 26, v5
	v_add_u32_e32 v50, 28, v5
	v_mad_i64_i32 v[38:39], s[70:71], v38, s66, 0
	v_mad_i64_i32 v[40:41], s[70:71], v40, s66, 0
	v_mad_i64_i32 v[42:43], s[70:71], v42, s66, 0
	v_mad_i64_i32 v[44:45], s[70:71], v44, s66, 0
	v_mad_i64_i32 v[46:47], s[70:71], v46, s66, 0
	v_mad_i64_i32 v[48:49], s[70:71], v48, s66, 0
	v_mad_i64_i32 v[50:51], s[70:71], v50, s66, 0
	v_add_u32_e32 v52, 30, v5
	v_lshl_add_u64 v[38:39], v[38:39], 2, v[36:37]
	v_lshl_add_u64 v[40:41], v[40:41], 2, v[36:37]
	v_lshl_add_u64 v[42:43], v[42:43], 2, v[36:37]
	v_lshl_add_u64 v[44:45], v[44:45], 2, v[36:37]
	v_lshl_add_u64 v[46:47], v[46:47], 2, v[36:37]
	v_lshl_add_u64 v[48:49], v[48:49], 2, v[36:37]
	v_lshl_add_u64 v[50:51], v[50:51], 2, v[36:37]
	v_mad_i64_i32 v[52:53], s[70:71], v52, s66, 0
	v_lshl_add_u64 v[52:53], v[52:53], 2, v[36:37]
	global_load_dword v62, v[38:39], off
	global_load_dword v63, v[40:41], off
	global_load_dword v64, v[42:43], off
	global_load_dword v65, v[44:45], off
	global_load_dword v66, v[46:47], off
	global_load_dword v67, v[48:49], off
	global_load_dword v68, v[50:51], off
	global_load_dword v69, v[52:53], off
	v_add_u32_e32 v38, 32, v5
	v_add_u32_e32 v40, 34, v5
	v_add_u32_e32 v42, 36, v5
	v_add_u32_e32 v44, 38, v5
	v_add_u32_e32 v46, 40, v5
	v_add_u32_e32 v48, 42, v5
	v_add_u32_e32 v50, 44, v5
	v_mad_i64_i32 v[38:39], s[70:71], v38, s66, 0
	v_mad_i64_i32 v[40:41], s[70:71], v40, s66, 0
	v_mad_i64_i32 v[42:43], s[70:71], v42, s66, 0
	v_mad_i64_i32 v[44:45], s[70:71], v44, s66, 0
	v_mad_i64_i32 v[46:47], s[70:71], v46, s66, 0
	v_mad_i64_i32 v[48:49], s[70:71], v48, s66, 0
	v_mad_i64_i32 v[50:51], s[70:71], v50, s66, 0
	v_add_u32_e32 v52, 46, v5
	v_lshl_add_u64 v[38:39], v[38:39], 2, v[36:37]
	v_lshl_add_u64 v[40:41], v[40:41], 2, v[36:37]
	v_lshl_add_u64 v[42:43], v[42:43], 2, v[36:37]
	v_lshl_add_u64 v[44:45], v[44:45], 2, v[36:37]
	v_lshl_add_u64 v[46:47], v[46:47], 2, v[36:37]
	v_lshl_add_u64 v[48:49], v[48:49], 2, v[36:37]
	v_lshl_add_u64 v[50:51], v[50:51], 2, v[36:37]
	v_mad_i64_i32 v[52:53], s[70:71], v52, s66, 0
	v_lshl_add_u64 v[52:53], v[52:53], 2, v[36:37]
	global_load_dword v70, v[38:39], off
	global_load_dword v71, v[40:41], off
	global_load_dword v72, v[42:43], off
	global_load_dword v73, v[44:45], off
	global_load_dword v74, v[46:47], off
	global_load_dword v75, v[48:49], off
	global_load_dword v76, v[50:51], off
	global_load_dword v77, v[52:53], off
	v_add_u32_e32 v38, 48, v5
	v_add_u32_e32 v40, 50, v5
	v_add_u32_e32 v42, 52, v5
	v_add_u32_e32 v44, 54, v5
	v_add_u32_e32 v46, 56, v5
	v_add_u32_e32 v48, 58, v5
	v_add_u32_e32 v50, 60, v5
	v_add_u32_e32 v5, 62, v5
	v_mad_i64_i32 v[38:39], s[70:71], v38, s66, 0
	v_mad_i64_i32 v[40:41], s[70:71], v40, s66, 0
	v_mad_i64_i32 v[42:43], s[70:71], v42, s66, 0
	v_mad_i64_i32 v[44:45], s[70:71], v44, s66, 0
	v_mad_i64_i32 v[46:47], s[70:71], v46, s66, 0
	v_mad_i64_i32 v[48:49], s[70:71], v48, s66, 0
	v_mad_i64_i32 v[50:51], s[70:71], v50, s66, 0
	v_mad_i64_i32 v[52:53], s[70:71], v5, s66, 0
	v_lshl_add_u64 v[38:39], v[38:39], 2, v[36:37]
	v_lshl_add_u64 v[40:41], v[40:41], 2, v[36:37]
	v_lshl_add_u64 v[42:43], v[42:43], 2, v[36:37]
	v_lshl_add_u64 v[44:45], v[44:45], 2, v[36:37]
	v_lshl_add_u64 v[46:47], v[46:47], 2, v[36:37]
	v_lshl_add_u64 v[48:49], v[48:49], 2, v[36:37]
	v_lshl_add_u64 v[50:51], v[50:51], 2, v[36:37]
	v_lshl_add_u64 v[36:37], v[52:53], 2, v[36:37]
	global_load_dword v5, v[38:39], off
	s_nop 0
	global_load_dword v38, v[40:41], off
	global_load_dword v39, v[42:43], off
	s_nop 0
	global_load_dword v40, v[44:45], off
	global_load_dword v41, v[46:47], off
	global_load_dword v42, v[48:49], off
	global_load_dword v43, v[50:51], off
	s_nop 0
	global_load_dword v36, v[36:37], off
	s_waitcnt vmcnt(0)
; #define LAS __attribute__((address_space(3)))
; __device__ __forceinline__ unsigned cvt_pk_bf16(float lo, float hi) { unsigned r; asm volatile("v_cvt_pk_bf16_f32 %0, %1, %2" : "=v"(r) : "v"(lo), "v"(hi)); return r; }
; __device__ __forceinline__ void transpose_item(const float* W, int K, int N, bf16_t* WT, int dest_row0, int k0, int n0, LAS float* scr, int lane) {
;     ...
;     for (int i = 0; i < 32; ++i) { const int kk = 2 * i + (lane >> 5); scr[kk * 33 + (lane & 31)] = wv[i]; }
;     asm volatile("s_waitcnt lgkmcnt(0)" ::: "memory");
;     const int c = lane & 7;
; #pragma unroll
;     for (int j = 0; j < 4; ++j) { const int n = (lane >> 3) + 8 * j; const LAS float* s = scr + (8 * c) * 33 + n;
;         u32x4 o; o.x = cvt_pk_bf16(s[0 * 33], s[1 * 33]); o.y = cvt_pk_bf16(s[2 * 33], s[3 * 33]); o.z = cvt_pk_bf16(s[4 * 33], s[5 * 33]); o.w = cvt_pk_bf16(s[6 * 33], s[7 * 33]);
;         STG(u32x4, WT + (size_t)(dest_row0 + n) * K + k0 + 8 * c) = o; }
;     asm volatile("s_waitcnt lgkmcnt(0)" ::: "memory");
; }
	ds_write2_b32 v23, v54, v55 offset1:66
	ds_write2_b32 v23, v56, v57 offset0:132 offset1:198
	ds_write2_b32 v29, v58, v59 offset0:8 offset1:74
	ds_write2_b32 v29, v60, v61 offset0:140 offset1:206
	ds_write2_b32 v30, v62, v63 offset0:16 offset1:82
	ds_write2_b32 v30, v64, v65 offset0:148 offset1:214
	ds_write2_b32 v31, v66, v67 offset0:24 offset1:90
	ds_write2_b32 v31, v68, v69 offset0:156 offset1:222
	ds_write2_b32 v32, v70, v71 offset0:32 offset1:98
	ds_write2_b32 v32, v72, v73 offset0:164 offset1:230
	ds_write2_b32 v33, v74, v75 offset0:40 offset1:106
	ds_write2_b32 v33, v76, v77 offset0:172 offset1:238
	ds_write2_b32 v34, v5, v38 offset0:48 offset1:114
	ds_write2_b32 v34, v39, v40 offset0:180 offset1:246
	ds_write2_b32 v35, v41, v42 offset0:56 offset1:122
	ds_write2_b32 v35, v43, v36 offset0:188 offset1:254
	s_waitcnt lgkmcnt(0)
	ds_read2_b32 v[36:37], v25 offset1:33
	s_waitcnt lgkmcnt(0)
	v_cvt_pk_bf16_f32 v36, v36, v37
	ds_read2_b32 v[38:39], v25 offset0:66 offset1:99
	s_waitcnt lgkmcnt(0)
	v_cvt_pk_bf16_f32 v37, v38, v39
	ds_read2_b32 v[38:39], v25 offset0:132 offset1:165
	s_waitcnt lgkmcnt(0)
	v_cvt_pk_bf16_f32 v38, v38, v39
	ds_read2_b32 v[40:41], v25 offset0:198 offset1:231
	s_waitcnt lgkmcnt(0)
	v_cvt_pk_bf16_f32 v39, v40, v41
	v_add_u32_e32 v40, s18, v24
	s_ashr_i32 s21, s20, 31
	v_ashrrev_i32_e32 v41, 31, v40
	v_lshl_add_u64 v[42:43], s[20:21], 1, v[20:21]
	v_lshlrev_b64 v[46:47], 12, v[40:41]
	v_lshl_add_u64 v[46:47], v[42:43], 0, v[46:47]
	ds_read2_b32 v[44:45], v25 offset0:8 offset1:41
	global_store_dwordx4 v[46:47], v[36:39], off
	s_waitcnt lgkmcnt(0)
	s_nop 0
	v_cvt_pk_bf16_f32 v36, v44, v45
	ds_read2_b32 v[38:39], v25 offset0:74 offset1:107
	s_waitcnt lgkmcnt(0)
	v_cvt_pk_bf16_f32 v37, v38, v39
	ds_read2_b32 v[38:39], v25 offset0:140 offset1:173
	s_waitcnt lgkmcnt(0)
	v_cvt_pk_bf16_f32 v38, v38, v39
	ds_read2_b32 v[44:45], v25 offset0:206 offset1:239
	s_waitcnt lgkmcnt(0)
	v_cvt_pk_bf16_f32 v39, v44, v45
	v_add_u32_e32 v44, 8, v40
	v_ashrrev_i32_e32 v45, 31, v44
	v_lshlrev_b64 v[44:45], 12, v[44:45]
	v_lshl_add_u64 v[44:45], v[42:43], 0, v[44:45]
	ds_read2_b32 v[46:47], v25 offset0:16 offset1:49
	global_store_dwordx4 v[44:45], v[36:39], off
	s_waitcnt lgkmcnt(0)
	s_nop 0
	v_cvt_pk_bf16_f32 v36, v46, v47
	ds_read2_b32 v[38:39], v25 offset0:82 offset1:115
	s_waitcnt lgkmcnt(0)
	v_cvt_pk_bf16_f32 v37, v38, v39
	ds_read2_b32 v[38:39], v25 offset0:148 offset1:181
	s_waitcnt lgkmcnt(0)
	v_cvt_pk_bf16_f32 v38, v38, v39
	ds_read2_b32 v[44:45], v25 offset0:214 offset1:247
	s_waitcnt lgkmcnt(0)
	v_cvt_pk_bf16_f32 v39, v44, v45
	v_add_u32_e32 v44, 16, v40
	v_ashrrev_i32_e32 v45, 31, v44
	v_lshlrev_b64 v[44:45], 12, v[44:45]
	v_add_u32_e32 v40, 24, v40
	v_lshl_add_u64 v[44:45], v[42:43], 0, v[44:45]
	v_ashrrev_i32_e32 v41, 31, v40
	ds_read2_b32 v[46:47], v25 offset0:24 offset1:57
	global_store_dwordx4 v[44:45], v[36:39], off
	v_lshlrev_b64 v[40:41], 12, v[40:41]
	v_lshl_add_u64 v[40:41], v[42:43], 0, v[40:41]
	s_waitcnt lgkmcnt(0)
	v_cvt_pk_bf16_f32 v36, v46, v47
	ds_read2_b32 v[38:39], v25 offset0:90 offset1:123
	s_waitcnt lgkmcnt(0)
	v_cvt_pk_bf16_f32 v37, v38, v39
	ds_read2_b32 v[38:39], v25 offset0:156 offset1:189
	s_waitcnt lgkmcnt(0)
	v_cvt_pk_bf16_f32 v38, v38, v39
	ds_read2_b32 v[44:45], v25 offset0:222 offset1:255
	s_waitcnt lgkmcnt(0)
	v_cvt_pk_bf16_f32 v39, v44, v45
	global_store_dwordx4 v[40:41], v[36:39], off
	s_branch .LBB0_230

; __device__ __forceinline__ unsigned xb_ld(unsigned* p)              { return __hip_atomic_load(p, __ATOMIC_RELAXED, __HIP_MEMORY_SCOPE_AGENT); }
; __device__ __forceinline__ unsigned xb_add(unsigned* p, unsigned v) { return __hip_atomic_fetch_add(p, v, __ATOMIC_RELAXED, __HIP_MEMORY_SCOPE_AGENT); }
; #define XB_SPIN(cond, bar) do { unsigned _sp = 0; while (cond) { __builtin_amdgcn_s_sleep(1); \
;     if ((++_sp & 255u) == 0u) { if (xb_ld(&(bar)[XB_TMO])) break; if (_sp > XB_SPIN_CAP) { atomicAdd(&(bar)[XB_TMO], 1u); break; } } } } while (0)
; __device__ __forceinline__ void xcd_barrier(const XcdBarrier& b) {
;     ...
;         if (old + 1u == (gen + 1u) * nloc) {
;             __builtin_amdgcn_fence(__ATOMIC_RELEASE, "agent");
;             asm volatile("s_waitcnt vmcnt(0)" ::: "memory");
;             const unsigned og = xb_add(&bar[XB_TOP], 1u);
;     ...
;         } else {
;             XB_SPIN(xb_ld(&bar[XB_XGEN(b.x)]) == gen, bar);
;             __builtin_amdgcn_fence(__ATOMIC_ACQUIRE, "agent");
;             asm volatile("s_waitcnt vmcnt(0)" ::: "memory");
.LBB0_275:
	s_or_b64 exec, exec, s[12:13]
	s_waitcnt vmcnt(0)
	buffer_inv sc1
.LBB0_276:
	s_andn2_saveexec_b64 s[8:9], s[8:9]
	s_cbranch_execz .LBB0_296
	s_mov_b64 s[8:9], exec
	buffer_wbl2 sc1
	s_waitcnt lgkmcnt(0)
	s_waitcnt vmcnt(0)
	v_mbcnt_lo_u32_b32 v1, s8, 0
	v_mbcnt_hi_u32_b32 v1, s9, v1
	v_cmp_eq_u32_e32 vcc, 0, v1
	s_and_saveexec_b64 s[12:13], vcc
	s_cbranch_execz .LBB0_279
	s_bcnt1_i32_b64 s8, s[8:9]
	v_readlane_b32 s16, v254, 2
	v_mov_b32_e32 v2, 0x7000
	v_mov_b32_e32 v3, s8
	v_readlane_b32 s17, v254, 3
	v_readlane_b32 s18, v254, 4
	v_readlane_b32 s19, v254, 5
	s_nop 2
	global_atomic_add v2, v2, v3, s[16:17] offset:1024 sc0

; __device__ __forceinline__ unsigned xb_ld(unsigned* p)              { return __hip_atomic_load(p, __ATOMIC_RELAXED, __HIP_MEMORY_SCOPE_AGENT); }
; __device__ __forceinline__ unsigned xb_add(unsigned* p, unsigned v) { return __hip_atomic_fetch_add(p, v, __ATOMIC_RELAXED, __HIP_MEMORY_SCOPE_AGENT); }
; #define XB_SPIN(cond, bar) do { unsigned _sp = 0; while (cond) { __builtin_amdgcn_s_sleep(1); \
;     if ((++_sp & 255u) == 0u) { if (xb_ld(&(bar)[XB_TMO])) break; if (_sp > XB_SPIN_CAP) { atomicAdd(&(bar)[XB_TMO], 1u); break; } } } } while (0)
; __device__ __forceinline__ void xcd_barrier(const XcdBarrier& b) {
;     ...
;         if (old + 1u == (gen + 1u) * nloc) {
;             __builtin_amdgcn_fence(__ATOMIC_RELEASE, "agent");
;             asm volatile("s_waitcnt vmcnt(0)" ::: "memory");
;             const unsigned og = xb_add(&bar[XB_TOP], 1u);
;     ...
;         } else {
;             XB_SPIN(xb_ld(&bar[XB_XGEN(b.x)]) == gen, bar);
;             __builtin_amdgcn_fence(__ATOMIC_ACQUIRE, "agent");
;             asm volatile("s_waitcnt vmcnt(0)" ::: "memory");
.LBB0_361:
	s_or_b64 exec, exec, s[6:7]
	s_waitcnt vmcnt(0)
	buffer_inv sc1
.LBB0_362:
	s_andn2_saveexec_b64 s[4:5], s[4:5]
	s_cbranch_execz .LBB0_382
	s_mov_b64 s[4:5], exec
	buffer_wbl2 sc1
	s_waitcnt lgkmcnt(0)
	s_waitcnt vmcnt(0)
	v_mbcnt_lo_u32_b32 v0, s4, 0
	v_mbcnt_hi_u32_b32 v0, s5, v0
	v_cmp_eq_u32_e32 vcc, 0, v0
	s_and_saveexec_b64 s[6:7], vcc
	s_cbranch_execz .LBB0_365
	s_bcnt1_i32_b64 s4, s[4:5]
	v_mov_b32_e32 v3, s4
	v_readlane_b32 s4, v255, 17
	v_readlane_b32 s5, v255, 18
	s_nop 4
	global_atomic_add v3, v1, v3, s[4:5] sc0

; __device__ __forceinline__ bf16_t* wt_ptr(const Frame& F, int layer, size_t off) { return (bf16_t*)(F.ws + WS_WT + (size_t)layer * LWT + off); }
; __device__ __forceinline__ void transpose_item(const float* W, int K, int N, bf16_t* WT, int dest_row0, int k0, int n0, LAS float* scr, int lane) {
;     ...
;     for (int i = 0; i < 32; ++i) { const int kk = 2 * i + (lane >> 5); wv[i] = LDG(float, W + (size_t)(k0 + kk) * N + n0 + (lane & 31)); }
; #pragma unroll
;     for (int i = 0; i < 32; ++i) { const int kk = 2 * i + (lane >> 5); scr[kk * 33 + (lane & 31)] = wv[i]; }
; __device__ __forceinline__ void phase_weights(const Frame& F0, int lmask, int cu0, int ncu, int pm) {
;     ...
;             { const int nblk = DM / 32, kb = r / nblk, nb = r % nblk; transpose_item(wdn, DFF, DM, wt_ptr(F, layer, WT_DOWN), 32 * nb, 64 * kb, 32 * nb, scr, F.lane); }
.LBB0_414:
	s_add_i32 s7, s46, s47
	s_cmpk_gt_i32 s7, 0x7ff
	s_cbranch_scc0 .LBB0_420
	s_cmpk_gt_u32 s7, 0x32ff
	s_cbranch_scc0 .LBB0_417
	s_and_b32 s4, s7, 0x7fffffc0
	s_addk_i32 s4, 0xcd00
	s_and_b32 s6, s43, 0x7e0
	v_add_u32_e32 v22, s4, v24
	s_lshl_b32 s72, s6, 2
	v_ashrrev_i32_e32 v23, 31, v22
	v_lshl_add_u64 v[32:33], v[6:7], 0, s[72:73]
	v_lshlrev_b64 v[22:23], 13, v[22:23]
	v_lshl_add_u64 v[22:23], v[32:33], 0, v[22:23]
	v_add_co_u32_e32 v32, vcc, 0x4000, v22
	global_load_dword v5, v[22:23], off
	s_nop 0
	v_addc_co_u32_e32 v33, vcc, 0, v23, vcc
	global_load_dword v31, v[32:33], off
	v_add_co_u32_e32 v32, vcc, 0x8000, v22
	s_mov_b32 s5, 0x34000
	s_nop 0
	v_addc_co_u32_e32 v33, vcc, 0, v23, vcc
	global_load_dword v34, v[32:33], off
	v_add_co_u32_e32 v32, vcc, s3, v22
	s_nop 1
	v_addc_co_u32_e32 v33, vcc, 0, v23, vcc
	global_load_dword v35, v[32:33], off
	v_add_co_u32_e32 v32, vcc, s55, v22
	s_nop 1
	v_addc_co_u32_e32 v33, vcc, 0, v23, vcc
	global_load_dword v36, v[32:33], off
	v_add_co_u32_e32 v32, vcc, s58, v22
	s_nop 1
	v_addc_co_u32_e32 v33, vcc, 0, v23, vcc
	global_load_dword v37, v[32:33], off
	v_add_co_u32_e32 v32, vcc, s59, v22
	s_nop 1
	v_addc_co_u32_e32 v33, vcc, 0, v23, vcc
	global_load_dword v38, v[32:33], off
	v_add_co_u32_e32 v32, vcc, s63, v22
	s_nop 1
	v_addc_co_u32_e32 v33, vcc, 0, v23, vcc
	global_load_dword v39, v[32:33], off
	v_add_co_u32_e32 v32, vcc, s66, v22
	s_nop 1
	v_addc_co_u32_e32 v33, vcc, 0, v23, vcc
	global_load_dword v40, v[32:33], off
	v_add_co_u32_e32 v32, vcc, s56, v22
	s_nop 1
	v_addc_co_u32_e32 v33, vcc, 0, v23, vcc
	global_load_dword v41, v[32:33], off
	v_add_co_u32_e32 v32, vcc, s57, v22
	s_nop 1
	v_addc_co_u32_e32 v33, vcc, 0, v23, vcc
	global_load_dword v42, v[32:33], off
	v_add_co_u32_e32 v32, vcc, s94, v22
	s_nop 1
	v_addc_co_u32_e32 v33, vcc, 0, v23, vcc
	global_load_dword v43, v[32:33], off
	v_add_co_u32_e32 v32, vcc, s54, v22
	s_nop 1
	v_addc_co_u32_e32 v33, vcc, 0, v23, vcc
	global_load_dword v44, v[32:33], off
	v_add_co_u32_e32 v32, vcc, s5, v22
	s_mov_b32 s5, 0x38000
	s_nop 0
	v_addc_co_u32_e32 v33, vcc, 0, v23, vcc
	global_load_dword v45, v[32:33], off
	v_add_co_u32_e32 v32, vcc, s5, v22
	s_mov_b32 s5, 0x3c000
	s_nop 0
	v_addc_co_u32_e32 v33, vcc, 0, v23, vcc
	global_load_dword v46, v[32:33], off
	v_add_co_u32_e32 v32, vcc, s5, v22
	s_mov_b32 s5, 0x40000
	s_nop 0
	v_addc_co_u32_e32 v33, vcc, 0, v23, vcc
	global_load_dword v47, v[32:33], off
	v_add_co_u32_e32 v32, vcc, s5, v22
	s_mov_b32 s5, 0x44000
	s_nop 0
	v_addc_co_u32_e32 v33, vcc, 0, v23, vcc
	global_load_dword v48, v[32:33], off
	v_add_co_u32_e32 v32, vcc, s5, v22
	s_mov_b32 s5, 0x48000
	s_nop 0
	v_addc_co_u32_e32 v33, vcc, 0, v23, vcc
	global_load_dword v49, v[32:33], off
	v_add_co_u32_e32 v32, vcc, s5, v22
	s_mov_b32 s5, 0x4c000
	s_nop 0
	v_addc_co_u32_e32 v33, vcc, 0, v23, vcc
	global_load_dword v50, v[32:33], off
	v_add_co_u32_e32 v32, vcc, s5, v22
	s_mov_b32 s5, 0x50000
	s_nop 0
	v_addc_co_u32_e32 v33, vcc, 0, v23, vcc
	global_load_dword v51, v[32:33], off
	v_add_co_u32_e32 v32, vcc, s5, v22
	s_mov_b32 s5, s73
	s_nop 0
	v_addc_co_u32_e32 v33, vcc, 0, v23, vcc
	global_load_dword v52, v[32:33], off
	v_add_co_u32_e32 v32, vcc, s70, v22
	s_nop 1
	v_addc_co_u32_e32 v33, vcc, 0, v23, vcc
	global_load_dword v53, v[32:33], off
	v_add_co_u32_e32 v32, vcc, s71, v22
	s_nop 1
	v_addc_co_u32_e32 v33, vcc, 0, v23, vcc
	global_load_dword v54, v[32:33], off
	v_add_co_u32_e32 v32, vcc, s18, v22
	s_nop 1
	v_addc_co_u32_e32 v33, vcc, 0, v23, vcc
	global_load_dword v55, v[32:33], off
	v_add_co_u32_e32 v32, vcc, s19, v22
	s_nop 1
	v_addc_co_u32_e32 v33, vcc, 0, v23, vcc
	global_load_dword v56, v[32:33], off
	v_add_co_u32_e32 v32, vcc, s10, v22
	s_nop 1
	v_addc_co_u32_e32 v33, vcc, 0, v23, vcc
	global_load_dword v57, v[32:33], off
	v_add_co_u32_e32 v32, vcc, s11, v22
	s_nop 1
	v_addc_co_u32_e32 v33, vcc, 0, v23, vcc
	global_load_dword v58, v[32:33], off
	v_add_co_u32_e32 v32, vcc, s20, v22
	s_nop 1
	v_addc_co_u32_e32 v33, vcc, 0, v23, vcc
	global_load_dword v59, v[32:33], off
	v_add_co_u32_e32 v32, vcc, s21, v22
	s_nop 1
	v_addc_co_u32_e32 v33, vcc, 0, v23, vcc
	global_load_dword v60, v[32:33], off
	v_add_co_u32_e32 v32, vcc, s22, v22
	s_nop 1
	v_addc_co_u32_e32 v33, vcc, 0, v23, vcc
	global_load_dword v61, v[32:33], off
	v_add_co_u32_e32 v32, vcc, s23, v22
	s_nop 1
	v_addc_co_u32_e32 v33, vcc, 0, v23, vcc
	v_add_co_u32_e32 v22, vcc, s14, v22
	global_load_dword v32, v[32:33], off
	s_nop 0
	v_addc_co_u32_e32 v23, vcc, 0, v23, vcc
	global_load_dword v22, v[22:23], off
	s_waitcnt vmcnt(0)
	ds_write2_b32 v25, v5, v31 offset1:66
	ds_write2_b32 v25, v34, v35 offset0:132 offset1:198
	v_add_u32_e32 v5, 0x400, v25
	ds_write2_b32 v5, v36, v37 offset0:8 offset1:74
	ds_write2_b32 v5, v38, v39 offset0:140 offset1:206
	v_add_u32_e32 v5, 0x800, v25
	ds_write2_b32 v5, v40, v41 offset0:16 offset1:82
	ds_write2_b32 v5, v42, v43 offset0:148 offset1:214
	v_add_u32_e32 v5, 0xc00, v25
	ds_write2_b32 v5, v44, v45 offset0:24 offset1:90
	ds_write2_b32 v5, v46, v47 offset0:156 offset1:222
	v_add_u32_e32 v5, 0x1000, v25
	ds_write2_b32 v5, v48, v49 offset0:32 offset1:98
	ds_write2_b32 v5, v50, v51 offset0:164 offset1:230
	v_add_u32_e32 v5, 0x1400, v25
	ds_write2_b32 v5, v52, v53 offset0:40 offset1:106
	ds_write2_b32 v5, v54, v55 offset0:172 offset1:238
	v_add_u32_e32 v5, 0x1800, v25
	ds_write2_b32 v5, v56, v57 offset0:48 offset1:114
	ds_write2_b32 v5, v58, v59 offset0:180 offset1:246
	v_add_u32_e32 v5, 0x1c00, v25
	ds_write2_b32 v5, v60, v61 offset0:56 offset1:122
	ds_write2_b32 v5, v32, v22 offset0:188 offset1:254
	s_waitcnt lgkmcnt(0)
	ds_read2_b32 v[32:33], v27 offset1:33
	s_waitcnt lgkmcnt(0)
; #define LAS __attribute__((address_space(3)))
; __device__ __forceinline__ unsigned cvt_pk_bf16(float lo, float hi) { unsigned r; asm volatile("v_cvt_pk_bf16_f32 %0, %1, %2" : "=v"(r) : "v"(lo), "v"(hi)); return r; }
; __device__ __forceinline__ bf16_t* wt_ptr(const Frame& F, int layer, size_t off) { return (bf16_t*)(F.ws + WS_WT + (size_t)layer * LWT + off); }
; __device__ __forceinline__ void transpose_item(const float* W, int K, int N, bf16_t* WT, int dest_row0, int k0, int n0, LAS float* scr, int lane) {
;     ...
;     for (int j = 0; j < 4; ++j) { const int n = (lane >> 3) + 8 * j; const LAS float* s = scr + (8 * c) * 33 + n;
;         u32x4 o; o.x = cvt_pk_bf16(s[0 * 33], s[1 * 33]); o.y = cvt_pk_bf16(s[2 * 33], s[3 * 33]); o.z = cvt_pk_bf16(s[4 * 33], s[5 * 33]); o.w = cvt_pk_bf16(s[6 * 33], s[7 * 33]);
;         STG(u32x4, WT + (size_t)(dest_row0 + n) * K + k0 + 8 * c) = o; }
; __device__ __forceinline__ void phase_weights(const Frame& F0, int lmask, int cu0, int ncu, int pm) {
;     ...
;             if (r < I_U) { const int nblk = 2 * DFF / 32, kb = r / nblk, nb = r % nblk; const int n0 = 32 * nb; const int half = n0 >= DFF ? 1 : 0, nn = n0 - half * DFF;
;                 const int drow = (nn >> 7) * 256 + half * 128 + (nn & 127);
;                 transpose_item(wup, DM, 2 * DFF, wt_ptr(F, layer, WT_UP), drow, 64 * kb, n0, scr, F.lane); continue; } r -= I_U;
	v_cvt_pk_bf16_f32 v32, v32, v33
	ds_read2_b32 v[34:35], v27 offset0:66 offset1:99
	s_waitcnt lgkmcnt(0)
	v_cvt_pk_bf16_f32 v33, v34, v35
	ds_read2_b32 v[34:35], v27 offset0:132 offset1:165
	v_lshl_add_u64 v[22:23], s[4:5], 1, v[8:9]
	s_waitcnt lgkmcnt(0)
	v_cvt_pk_bf16_f32 v34, v34, v35
	ds_read2_b32 v[36:37], v27 offset0:198 offset1:231
	v_add_u32_e32 v5, s6, v26
	s_waitcnt lgkmcnt(0)
	v_cvt_pk_bf16_f32 v35, v36, v37
	v_mad_i64_i32 v[36:37], s[4:5], v5, s33, v[22:23]
	global_store_dwordx4 v[36:37], v[32:35], off
	ds_read2_b32 v[32:33], v27 offset0:8 offset1:41
	v_add_u32_e32 v5, s6, v28
	s_waitcnt lgkmcnt(0)
	v_cvt_pk_bf16_f32 v32, v32, v33
	ds_read2_b32 v[34:35], v27 offset0:74 offset1:107
	s_waitcnt lgkmcnt(0)
	v_cvt_pk_bf16_f32 v33, v34, v35
	ds_read2_b32 v[34:35], v27 offset0:140 offset1:173
	s_waitcnt lgkmcnt(0)
	v_cvt_pk_bf16_f32 v34, v34, v35
	ds_read2_b32 v[36:37], v27 offset0:206 offset1:239
	s_waitcnt lgkmcnt(0)
	v_cvt_pk_bf16_f32 v35, v36, v37
	v_mad_i64_i32 v[36:37], s[4:5], v5, s33, v[22:23]
	global_store_dwordx4 v[36:37], v[32:35], off
	ds_read2_b32 v[32:33], v27 offset0:16 offset1:49
	v_add_u32_e32 v5, s6, v29
	s_waitcnt lgkmcnt(0)
	v_cvt_pk_bf16_f32 v32, v32, v33
	ds_read2_b32 v[34:35], v27 offset0:82 offset1:115
	s_waitcnt lgkmcnt(0)
	v_cvt_pk_bf16_f32 v33, v34, v35
	ds_read2_b32 v[34:35], v27 offset0:148 offset1:181
	s_waitcnt lgkmcnt(0)
	v_cvt_pk_bf16_f32 v34, v34, v35
	ds_read2_b32 v[36:37], v27 offset0:214 offset1:247
	s_waitcnt lgkmcnt(0)
	v_cvt_pk_bf16_f32 v35, v36, v37
	v_mad_i64_i32 v[36:37], s[4:5], v5, s33, v[22:23]
	global_store_dwordx4 v[36:37], v[32:35], off
	ds_read2_b32 v[32:33], v27 offset0:24 offset1:57
	v_add_u32_e32 v5, s6, v30
	s_waitcnt lgkmcnt(0)
	v_cvt_pk_bf16_f32 v32, v32, v33
	ds_read2_b32 v[34:35], v27 offset0:90 offset1:123
	s_waitcnt lgkmcnt(0)
	v_cvt_pk_bf16_f32 v33, v34, v35
	ds_read2_b32 v[34:35], v27 offset0:156 offset1:189
	v_mad_i64_i32 v[22:23], s[4:5], v5, s33, v[22:23]
	s_waitcnt lgkmcnt(0)
	v_cvt_pk_bf16_f32 v34, v34, v35
	ds_read2_b32 v[36:37], v27 offset0:222 offset1:255
	s_waitcnt lgkmcnt(0)
	v_cvt_pk_bf16_f32 v35, v36, v37
	global_store_dwordx4 v[22:23], v[32:35], off
	s_mov_b64 s[4:5], 0
.LBB0_417:
	s_andn2_b64 vcc, exec, s[4:5]
	s_cbranch_vccnz .LBB0_419
	s_add_i32 s4, s7, 0xf800
	s_and_b32 s5, s4, 0xffff
	s_mul_i32 s5, s5, 0xbe83
	s_lshr_b32 s5, s5, 24
	s_mul_i32 s6, s5, 0x158
	s_sub_i32 s4, s4, s6
	s_lshl_b32 s6, s4, 5
	s_and_b32 s27, s6, 0xffe0
	s_and_b32 s4, s4, 0xffff
	s_cmpk_gt_u32 s4, 0xab
	s_cselect_b32 s4, 0xffffea80, 0
	s_cselect_b32 s28, 0x80, 0
	s_lshl_b32 s72, s27, 2
	s_and_b32 s6, s6, 0x60
	v_lshl_add_u32 v5, s5, 6, v24
	v_lshl_add_u64 v[22:23], v[10:11], 0, s[72:73]
	s_or_b32 s6, s6, s28
	v_mad_i64_i32 v[32:33], s[28:29], v5, s15, v[22:23]
	global_load_dword v31, v[32:33], off
	v_add_u32_e32 v32, 2, v5
	v_mad_i64_i32 v[32:33], s[28:29], v32, s15, v[22:23]
	global_load_dword v34, v[32:33], off
	v_add_u32_e32 v32, 4, v5
	v_mad_i64_i32 v[32:33], s[28:29], v32, s15, v[22:23]
	global_load_dword v35, v[32:33], off
	v_add_u32_e32 v32, 6, v5
	v_mad_i64_i32 v[32:33], s[28:29], v32, s15, v[22:23]
	global_load_dword v36, v[32:33], off
	v_add_u32_e32 v32, 8, v5
	v_mad_i64_i32 v[32:33], s[28:29], v32, s15, v[22:23]
	global_load_dword v37, v[32:33], off
	v_add_u32_e32 v32, 10, v5
	v_mad_i64_i32 v[32:33], s[28:29], v32, s15, v[22:23]
	global_load_dword v38, v[32:33], off
	v_add_u32_e32 v32, 12, v5
	v_mad_i64_i32 v[32:33], s[28:29], v32, s15, v[22:23]
	global_load_dword v39, v[32:33], off
	v_add_u32_e32 v32, 14, v5
	v_mad_i64_i32 v[32:33], s[28:29], v32, s15, v[22:23]
	global_load_dword v40, v[32:33], off
	v_add_u32_e32 v32, 16, v5
	v_mad_i64_i32 v[32:33], s[28:29], v32, s15, v[22:23]
	global_load_dword v41, v[32:33], off
	v_add_u32_e32 v32, 18, v5
	v_mad_i64_i32 v[32:33], s[28:29], v32, s15, v[22:23]
	global_load_dword v42, v[32:33], off
	v_add_u32_e32 v32, 20, v5
	v_mad_i64_i32 v[32:33], s[28:29], v32, s15, v[22:23]
	global_load_dword v43, v[32:33], off
	v_add_u32_e32 v32, 22, v5
	v_mad_i64_i32 v[32:33], s[28:29], v32, s15, v[22:23]
	global_load_dword v44, v[32:33], off
	v_add_u32_e32 v32, 24, v5
	v_mad_i64_i32 v[32:33], s[28:29], v32, s15, v[22:23]
	global_load_dword v45, v[32:33], off
	v_add_u32_e32 v32, 26, v5
	v_mad_i64_i32 v[32:33], s[28:29], v32, s15, v[22:23]
	global_load_dword v46, v[32:33], off
	v_add_u32_e32 v32, 28, v5
	v_mad_i64_i32 v[32:33], s[28:29], v32, s15, v[22:23]
	global_load_dword v47, v[32:33], off
	v_add_u32_e32 v32, 30, v5
	v_mad_i64_i32 v[32:33], s[28:29], v32, s15, v[22:23]
	global_load_dword v48, v[32:33], off
	v_add_u32_e32 v32, 32, v5
	v_mad_i64_i32 v[32:33], s[28:29], v32, s15, v[22:23]
	global_load_dword v49, v[32:33], off
	v_add_u32_e32 v32, 34, v5
	v_mad_i64_i32 v[32:33], s[28:29], v32, s15, v[22:23]
	global_load_dword v50, v[32:33], off
	v_add_u32_e32 v32, 36, v5
	v_mad_i64_i32 v[32:33], s[28:29], v32, s15, v[22:23]
	global_load_dword v51, v[32:33], off
	v_add_u32_e32 v32, 38, v5
	v_mad_i64_i32 v[32:33], s[28:29], v32, s15, v[22:23]
	global_load_dword v52, v[32:33], off
	v_add_u32_e32 v32, 40, v5
	v_mad_i64_i32 v[32:33], s[28:29], v32, s15, v[22:23]
	global_load_dword v53, v[32:33], off
	v_add_u32_e32 v32, 42, v5
	v_mad_i64_i32 v[32:33], s[28:29], v32, s15, v[22:23]
	global_load_dword v54, v[32:33], off
	v_add_u32_e32 v32, 44, v5
	v_mad_i64_i32 v[32:33], s[28:29], v32, s15, v[22:23]
	global_load_dword v55, v[32:33], off
	v_add_u32_e32 v32, 46, v5
	v_mad_i64_i32 v[32:33], s[28:29], v32, s15, v[22:23]
	global_load_dword v56, v[32:33], off
	v_add_u32_e32 v32, 48, v5
	v_mad_i64_i32 v[32:33], s[28:29], v32, s15, v[22:23]
	global_load_dword v57, v[32:33], off
	v_add_u32_e32 v32, 50, v5
	v_mad_i64_i32 v[32:33], s[28:29], v32, s15, v[22:23]
	global_load_dword v58, v[32:33], off
	v_add_u32_e32 v32, 52, v5
	v_mad_i64_i32 v[32:33], s[28:29], v32, s15, v[22:23]
	global_load_dword v59, v[32:33], off
	v_add_u32_e32 v32, 54, v5
	v_mad_i64_i32 v[32:33], s[28:29], v32, s15, v[22:23]
	global_load_dword v60, v[32:33], off
	v_add_u32_e32 v32, 56, v5
	v_mad_i64_i32 v[32:33], s[28:29], v32, s15, v[22:23]
	global_load_dword v61, v[32:33], off
	v_add_u32_e32 v32, 58, v5
	v_mad_i64_i32 v[32:33], s[28:29], v32, s15, v[22:23]
	global_load_dword v62, v[32:33], off
	v_add_u32_e32 v32, 60, v5
	v_add_u32_e32 v5, 62, v5
	v_mad_i64_i32 v[32:33], s[28:29], v32, s15, v[22:23]
	v_mad_i64_i32 v[22:23], s[28:29], v5, s15, v[22:23]
	global_load_dword v32, v[32:33], off
	s_add_i32 s4, s4, s27
	global_load_dword v5, v[22:23], off
	v_add_u32_e32 v22, 0x400, v25
	s_waitcnt vmcnt(0)
; #define LAS __attribute__((address_space(3)))
; __device__ __forceinline__ unsigned cvt_pk_bf16(float lo, float hi) { unsigned r; asm volatile("v_cvt_pk_bf16_f32 %0, %1, %2" : "=v"(r) : "v"(lo), "v"(hi)); return r; }
; __device__ __forceinline__ bf16_t* wt_ptr(const Frame& F, int layer, size_t off) { return (bf16_t*)(F.ws + WS_WT + (size_t)layer * LWT + off); }
; __device__ __forceinline__ void transpose_item(const float* W, int K, int N, bf16_t* WT, int dest_row0, int k0, int n0, LAS float* scr, int lane) {
;     ...
;     for (int i = 0; i < 32; ++i) { const int kk = 2 * i + (lane >> 5); scr[kk * 33 + (lane & 31)] = wv[i]; }
;     asm volatile("s_waitcnt lgkmcnt(0)" ::: "memory");
;     const int c = lane & 7;
; #pragma unroll
;     for (int j = 0; j < 4; ++j) { const int n = (lane >> 3) + 8 * j; const LAS float* s = scr + (8 * c) * 33 + n;
;         u32x4 o; o.x = cvt_pk_bf16(s[0 * 33], s[1 * 33]); o.y = cvt_pk_bf16(s[2 * 33], s[3 * 33]); o.z = cvt_pk_bf16(s[4 * 33], s[5 * 33]); o.w = cvt_pk_bf16(s[6 * 33], s[7 * 33]);
;         STG(u32x4, WT + (size_t)(dest_row0 + n) * K + k0 + 8 * c) = o; }
; __device__ __forceinline__ void phase_weights(const Frame& F0, int lmask, int cu0, int ncu, int pm) {
;     ...
;             if (r < I_O) { const int nblk = DM / 32, kb = r / nblk, nb = r % nblk; transpose_item(wo, DM, DM, wt_ptr(F, layer, WT_WO), 32 * nb, 64 * kb, 32 * nb, scr, F.lane); continue; } r -= I_O;
	ds_write2_b32 v25, v31, v34 offset1:66
	ds_write2_b32 v25, v35, v36 offset0:132 offset1:198
	ds_write2_b32 v22, v37, v38 offset0:8 offset1:74
	ds_write2_b32 v22, v39, v40 offset0:140 offset1:206
	v_add_u32_e32 v22, 0x800, v25
	ds_write2_b32 v22, v41, v42 offset0:16 offset1:82
	ds_write2_b32 v22, v43, v44 offset0:148 offset1:214
	v_add_u32_e32 v22, 0xc00, v25
	ds_write2_b32 v22, v45, v46 offset0:24 offset1:90
	ds_write2_b32 v22, v47, v48 offset0:156 offset1:222
	v_add_u32_e32 v22, 0x1000, v25
	ds_write2_b32 v22, v49, v50 offset0:32 offset1:98
	ds_write2_b32 v22, v51, v52 offset0:164 offset1:230
	v_add_u32_e32 v22, 0x1400, v25
	ds_write2_b32 v22, v53, v54 offset0:40 offset1:106
	ds_write2_b32 v22, v55, v56 offset0:172 offset1:238
	v_add_u32_e32 v22, 0x1800, v25
	ds_write2_b32 v22, v57, v58 offset0:48 offset1:114
	ds_write2_b32 v22, v59, v60 offset0:180 offset1:246
	v_add_u32_e32 v22, 0x1c00, v25
	ds_write2_b32 v22, v61, v62 offset0:56 offset1:122
	ds_write2_b32 v22, v32, v5 offset0:188 offset1:254
	s_waitcnt lgkmcnt(0)
	ds_read2_b32 v[32:33], v27 offset1:33
	s_lshl_b32 s4, s4, 1
	s_waitcnt lgkmcnt(0)
	v_cvt_pk_bf16_f32 v32, v32, v33
	ds_read2_b32 v[34:35], v27 offset0:66 offset1:99
	s_and_b32 s4, s4, 0xffffff00
	s_waitcnt lgkmcnt(0)
	v_cvt_pk_bf16_f32 v33, v34, v35
	ds_read2_b32 v[34:35], v27 offset0:132 offset1:165
	s_or_b32 s4, s6, s4
	s_waitcnt lgkmcnt(0)
	v_cvt_pk_bf16_f32 v34, v34, v35
	ds_read2_b32 v[36:37], v27 offset0:198 offset1:231
	s_waitcnt lgkmcnt(0)
	v_cvt_pk_bf16_f32 v35, v36, v37
	v_add_u32_e32 v36, s4, v26
	s_lshl_b32 s72, s5, 7
	v_ashrrev_i32_e32 v37, 31, v36
	v_lshl_add_u64 v[22:23], v[12:13], 0, s[72:73]
	v_lshlrev_b64 v[36:37], 12, v[36:37]
	v_lshl_add_u64 v[36:37], v[22:23], 0, v[36:37]
	global_store_dwordx4 v[36:37], v[32:35], off
	ds_read2_b32 v[32:33], v27 offset0:8 offset1:41
	s_waitcnt lgkmcnt(0)
	v_cvt_pk_bf16_f32 v32, v32, v33
	ds_read2_b32 v[34:35], v27 offset0:74 offset1:107
	s_waitcnt lgkmcnt(0)
	v_cvt_pk_bf16_f32 v33, v34, v35
	ds_read2_b32 v[34:35], v27 offset0:140 offset1:173
	s_waitcnt lgkmcnt(0)
	v_cvt_pk_bf16_f32 v34, v34, v35
	ds_read2_b32 v[36:37], v27 offset0:206 offset1:239
	s_waitcnt lgkmcnt(0)
	v_cvt_pk_bf16_f32 v35, v36, v37
	v_add_u32_e32 v36, s4, v28
	v_ashrrev_i32_e32 v37, 31, v36
	v_lshlrev_b64 v[36:37], 12, v[36:37]
	v_lshl_add_u64 v[36:37], v[22:23], 0, v[36:37]
	global_store_dwordx4 v[36:37], v[32:35], off
	ds_read2_b32 v[32:33], v27 offset0:16 offset1:49
	s_waitcnt lgkmcnt(0)
	v_cvt_pk_bf16_f32 v32, v32, v33
	ds_read2_b32 v[34:35], v27 offset0:82 offset1:115
	s_waitcnt lgkmcnt(0)
	v_cvt_pk_bf16_f32 v33, v34, v35
	ds_read2_b32 v[34:35], v27 offset0:148 offset1:181
	s_waitcnt lgkmcnt(0)
	v_cvt_pk_bf16_f32 v34, v34, v35
	ds_read2_b32 v[36:37], v27 offset0:214 offset1:247
	s_waitcnt lgkmcnt(0)
	v_cvt_pk_bf16_f32 v35, v36, v37
	v_add_u32_e32 v36, s4, v29
	v_ashrrev_i32_e32 v37, 31, v36
	v_lshlrev_b64 v[36:37], 12, v[36:37]
	v_lshl_add_u64 v[36:37], v[22:23], 0, v[36:37]
	global_store_dwordx4 v[36:37], v[32:35], off
	ds_read2_b32 v[32:33], v27 offset0:24 offset1:57
	s_waitcnt lgkmcnt(0)
	v_cvt_pk_bf16_f32 v32, v32, v33
	ds_read2_b32 v[34:35], v27 offset0:90 offset1:123
	s_waitcnt lgkmcnt(0)
	v_cvt_pk_bf16_f32 v33, v34, v35
	ds_read2_b32 v[34:35], v27 offset0:156 offset1:189
	s_waitcnt lgkmcnt(0)
	v_cvt_pk_bf16_f32 v34, v34, v35
	ds_read2_b32 v[36:37], v27 offset0:222 offset1:255
	s_waitcnt lgkmcnt(0)
	v_cvt_pk_bf16_f32 v35, v36, v37
	v_add_u32_e32 v36, s4, v30
	v_ashrrev_i32_e32 v37, 31, v36
	v_lshlrev_b64 v[36:37], 12, v[36:37]
	v_lshl_add_u64 v[22:23], v[22:23], 0, v[36:37]
	global_store_dwordx4 v[22:23], v[32:35], off
.LBB0_419:
	s_mov_b64 s[4:5], 0
.LBB0_420:
	s_andn2_b64 vcc, exec, s[4:5]
	s_cbranch_vccnz .LBB0_422
	s_ashr_i32 s4, s7, 31
	s_lshr_b32 s4, s4, 26
	s_add_i32 s4, s7, s4
	s_and_b32 s6, s4, 0xffffffc0
	s_sub_i32 s4, s7, s6
	s_lshl_b32 s4, s4, 5
	v_add_u32_e32 v22, s6, v24
	s_ashr_i32 s5, s4, 31
	v_ashrrev_i32_e32 v23, 31, v22
	v_lshl_add_u64 v[32:33], s[4:5], 2, v[14:15]
	v_lshlrev_b64 v[22:23], 13, v[22:23]
	v_lshl_add_u64 v[22:23], v[32:33], 0, v[22:23]
	s_movk_i32 s5, 0x4000
	v_add_co_u32_e32 v32, vcc, s5, v22
	s_mov_b32 s5, 0x8000
	s_nop 0
	v_addc_co_u32_e32 v33, vcc, 0, v23, vcc
	global_load_dword v5, v[22:23], off
	global_load_dword v31, v[32:33], off
	v_add_co_u32_e32 v32, vcc, s5, v22
	s_mov_b32 s5, 0x34000
	s_nop 0
	v_addc_co_u32_e32 v33, vcc, 0, v23, vcc
	global_load_dword v34, v[32:33], off
	v_add_co_u32_e32 v32, vcc, s3, v22
	s_ashr_i32 s7, s6, 31
	s_nop 0
	v_addc_co_u32_e32 v33, vcc, 0, v23, vcc
	global_load_dword v35, v[32:33], off
	v_add_co_u32_e32 v32, vcc, s55, v22
	s_nop 1
	v_addc_co_u32_e32 v33, vcc, 0, v23, vcc
	global_load_dword v36, v[32:33], off
	v_add_co_u32_e32 v32, vcc, s58, v22
	s_nop 1
	v_addc_co_u32_e32 v33, vcc, 0, v23, vcc
	global_load_dword v37, v[32:33], off
	v_add_co_u32_e32 v32, vcc, s59, v22
	s_nop 1
	v_addc_co_u32_e32 v33, vcc, 0, v23, vcc
	global_load_dword v38, v[32:33], off
	v_add_co_u32_e32 v32, vcc, s63, v22
	s_nop 1
	v_addc_co_u32_e32 v33, vcc, 0, v23, vcc
	global_load_dword v39, v[32:33], off
	v_add_co_u32_e32 v32, vcc, s66, v22
	s_nop 1
	v_addc_co_u32_e32 v33, vcc, 0, v23, vcc
	global_load_dword v40, v[32:33], off
	v_add_co_u32_e32 v32, vcc, s56, v22
	s_nop 1
	v_addc_co_u32_e32 v33, vcc, 0, v23, vcc
	global_load_dword v41, v[32:33], off
	v_add_co_u32_e32 v32, vcc, s57, v22
	s_nop 1
	v_addc_co_u32_e32 v33, vcc, 0, v23, vcc
	global_load_dword v42, v[32:33], off
	v_add_co_u32_e32 v32, vcc, s94, v22
	s_nop 1
	v_addc_co_u32_e32 v33, vcc, 0, v23, vcc
	global_load_dword v43, v[32:33], off
	v_add_co_u32_e32 v32, vcc, s54, v22
	s_nop 1
; #define LAS __attribute__((address_space(3)))
; __device__ __forceinline__ unsigned cvt_pk_bf16(float lo, float hi) { unsigned r; asm volatile("v_cvt_pk_bf16_f32 %0, %1, %2" : "=v"(r) : "v"(lo), "v"(hi)); return r; }
; __device__ __forceinline__ void transpose_item(const float* W, int K, int N, bf16_t* WT, int dest_row0, int k0, int n0, LAS float* scr, int lane) {
;     ...
;     for (int i = 0; i < 32; ++i) { const int kk = 2 * i + (lane >> 5); wv[i] = LDG(float, W + (size_t)(k0 + kk) * N + n0 + (lane & 31)); }
; #pragma unroll
;     for (int i = 0; i < 32; ++i) { const int kk = 2 * i + (lane >> 5); scr[kk * 33 + (lane & 31)] = wv[i]; }
;     asm volatile("s_waitcnt lgkmcnt(0)" ::: "memory");
;     const int c = lane & 7;
; #pragma unroll
;     for (int j = 0; j < 4; ++j) { const int n = (lane >> 3) + 8 * j; const LAS float* s = scr + (8 * c) * 33 + n;
;         u32x4 o; o.x = cvt_pk_bf16(s[0 * 33], s[1 * 33]); o.y = cvt_pk_bf16(s[2 * 33], s[3 * 33]); o.z = cvt_pk_bf16(s[4 * 33], s[5 * 33]); o.w = cvt_pk_bf16(s[6 * 33], s[7 * 33]);
;         STG(u32x4, WT + (size_t)(dest_row0 + n) * K + k0 + 8 * c) = o; }
	v_addc_co_u32_e32 v33, vcc, 0, v23, vcc
	global_load_dword v44, v[32:33], off
	v_add_co_u32_e32 v32, vcc, s5, v22
	s_mov_b32 s5, 0x38000
	s_nop 0
	v_addc_co_u32_e32 v33, vcc, 0, v23, vcc
	global_load_dword v45, v[32:33], off
	v_add_co_u32_e32 v32, vcc, s5, v22
	s_mov_b32 s5, 0x3c000
	s_nop 0
	v_addc_co_u32_e32 v33, vcc, 0, v23, vcc
	global_load_dword v46, v[32:33], off
	v_add_co_u32_e32 v32, vcc, s5, v22
	s_mov_b32 s5, 0x40000
	s_nop 0
	v_addc_co_u32_e32 v33, vcc, 0, v23, vcc
	global_load_dword v47, v[32:33], off
	v_add_co_u32_e32 v32, vcc, s5, v22
	s_mov_b32 s5, 0x44000
	s_nop 0
	v_addc_co_u32_e32 v33, vcc, 0, v23, vcc
	global_load_dword v48, v[32:33], off
	v_add_co_u32_e32 v32, vcc, s5, v22
	s_mov_b32 s5, 0x48000
	s_nop 0
	v_addc_co_u32_e32 v33, vcc, 0, v23, vcc
	global_load_dword v49, v[32:33], off
	v_add_co_u32_e32 v32, vcc, s5, v22
	s_mov_b32 s5, 0x4c000
	s_nop 0
	v_addc_co_u32_e32 v33, vcc, 0, v23, vcc
	global_load_dword v50, v[32:33], off
	v_add_co_u32_e32 v32, vcc, s5, v22
	s_mov_b32 s5, 0x50000
	s_nop 0
	v_addc_co_u32_e32 v33, vcc, 0, v23, vcc
	global_load_dword v51, v[32:33], off
	v_add_co_u32_e32 v32, vcc, s5, v22
	s_nop 1
	v_addc_co_u32_e32 v33, vcc, 0, v23, vcc
	global_load_dword v52, v[32:33], off
	v_add_co_u32_e32 v32, vcc, s70, v22
	s_nop 1
	v_addc_co_u32_e32 v33, vcc, 0, v23, vcc
	global_load_dword v53, v[32:33], off
	v_add_co_u32_e32 v32, vcc, s71, v22
	s_nop 1
	v_addc_co_u32_e32 v33, vcc, 0, v23, vcc
	global_load_dword v54, v[32:33], off
	v_add_co_u32_e32 v32, vcc, s18, v22
	s_nop 1
	v_addc_co_u32_e32 v33, vcc, 0, v23, vcc
	global_load_dword v55, v[32:33], off
	v_add_co_u32_e32 v32, vcc, s19, v22
	s_nop 1
	v_addc_co_u32_e32 v33, vcc, 0, v23, vcc
	global_load_dword v56, v[32:33], off
	v_add_co_u32_e32 v32, vcc, s10, v22
	s_nop 1
	v_addc_co_u32_e32 v33, vcc, 0, v23, vcc
	global_load_dword v57, v[32:33], off
	v_add_co_u32_e32 v32, vcc, s11, v22
	s_nop 1
	v_addc_co_u32_e32 v33, vcc, 0, v23, vcc
	global_load_dword v58, v[32:33], off
	v_add_co_u32_e32 v32, vcc, s20, v22
	s_nop 1
	v_addc_co_u32_e32 v33, vcc, 0, v23, vcc
	global_load_dword v59, v[32:33], off
	v_add_co_u32_e32 v32, vcc, s21, v22
	s_nop 1
	v_addc_co_u32_e32 v33, vcc, 0, v23, vcc
	global_load_dword v60, v[32:33], off
	v_add_co_u32_e32 v32, vcc, s22, v22
	s_nop 1
	v_addc_co_u32_e32 v33, vcc, 0, v23, vcc
	global_load_dword v61, v[32:33], off
	v_add_co_u32_e32 v32, vcc, s23, v22
	s_nop 1
	v_addc_co_u32_e32 v33, vcc, 0, v23, vcc
	v_add_co_u32_e32 v22, vcc, s14, v22
	global_load_dword v32, v[32:33], off
	s_nop 0
	v_addc_co_u32_e32 v23, vcc, 0, v23, vcc
	global_load_dword v22, v[22:23], off
	s_waitcnt vmcnt(0)
	ds_write2_b32 v25, v5, v31 offset1:66
	ds_write2_b32 v25, v34, v35 offset0:132 offset1:198
	v_add_u32_e32 v5, 0x400, v25
	ds_write2_b32 v5, v36, v37 offset0:8 offset1:74
	ds_write2_b32 v5, v38, v39 offset0:140 offset1:206
	v_add_u32_e32 v5, 0x800, v25
	ds_write2_b32 v5, v40, v41 offset0:16 offset1:82
	ds_write2_b32 v5, v42, v43 offset0:148 offset1:214
	v_add_u32_e32 v5, 0xc00, v25
	ds_write2_b32 v5, v44, v45 offset0:24 offset1:90
	ds_write2_b32 v5, v46, v47 offset0:156 offset1:222
	v_add_u32_e32 v5, 0x1000, v25
	ds_write2_b32 v5, v48, v49 offset0:32 offset1:98
	ds_write2_b32 v5, v50, v51 offset0:164 offset1:230
	v_add_u32_e32 v5, 0x1400, v25
	ds_write2_b32 v5, v52, v53 offset0:40 offset1:106
	ds_write2_b32 v5, v54, v55 offset0:172 offset1:238
	v_add_u32_e32 v5, 0x1800, v25
	ds_write2_b32 v5, v56, v57 offset0:48 offset1:114
	ds_write2_b32 v5, v58, v59 offset0:180 offset1:246
	v_add_u32_e32 v5, 0x1c00, v25
	ds_write2_b32 v5, v60, v61 offset0:56 offset1:122
	ds_write2_b32 v5, v32, v22 offset0:188 offset1:254
	s_waitcnt lgkmcnt(0)
	ds_read2_b32 v[32:33], v27 offset1:33
	s_waitcnt lgkmcnt(0)
	v_cvt_pk_bf16_f32 v32, v32, v33
	ds_read2_b32 v[34:35], v27 offset0:66 offset1:99
	s_waitcnt lgkmcnt(0)
	v_cvt_pk_bf16_f32 v33, v34, v35
	ds_read2_b32 v[34:35], v27 offset0:132 offset1:165
	s_waitcnt lgkmcnt(0)
	v_cvt_pk_bf16_f32 v34, v34, v35
	ds_read2_b32 v[36:37], v27 offset0:198 offset1:231
	s_waitcnt lgkmcnt(0)
	v_cvt_pk_bf16_f32 v35, v36, v37
	v_add_u32_e32 v36, s4, v26
	v_ashrrev_i32_e32 v37, 31, v36
	v_lshl_add_u64 v[22:23], s[6:7], 1, v[16:17]
	v_lshlrev_b64 v[36:37], 12, v[36:37]
	v_lshl_add_u64 v[36:37], v[22:23], 0, v[36:37]
	global_store_dwordx4 v[36:37], v[32:35], off
	ds_read2_b32 v[32:33], v27 offset0:8 offset1:41
	s_waitcnt lgkmcnt(0)
	v_cvt_pk_bf16_f32 v32, v32, v33
	ds_read2_b32 v[34:35], v27 offset0:74 offset1:107
	s_waitcnt lgkmcnt(0)
	v_cvt_pk_bf16_f32 v33, v34, v35
	ds_read2_b32 v[34:35], v27 offset0:140 offset1:173
	s_waitcnt lgkmcnt(0)
	v_cvt_pk_bf16_f32 v34, v34, v35
	ds_read2_b32 v[36:37], v27 offset0:206 offset1:239
	s_waitcnt lgkmcnt(0)
	v_cvt_pk_bf16_f32 v35, v36, v37
	v_add_u32_e32 v36, s4, v28
	v_ashrrev_i32_e32 v37, 31, v36
	v_lshlrev_b64 v[36:37], 12, v[36:37]
	v_lshl_add_u64 v[36:37], v[22:23], 0, v[36:37]
	global_store_dwordx4 v[36:37], v[32:35], off
	ds_read2_b32 v[32:33], v27 offset0:16 offset1:49
	s_waitcnt lgkmcnt(0)
	v_cvt_pk_bf16_f32 v32, v32, v33
	ds_read2_b32 v[34:35], v27 offset0:82 offset1:115
	s_waitcnt lgkmcnt(0)
	v_cvt_pk_bf16_f32 v33, v34, v35
	ds_read2_b32 v[34:35], v27 offset0:148 offset1:181
	s_waitcnt lgkmcnt(0)
	v_cvt_pk_bf16_f32 v34, v34, v35
	ds_read2_b32 v[36:37], v27 offset0:214 offset1:247
	s_waitcnt lgkmcnt(0)
	v_cvt_pk_bf16_f32 v35, v36, v37
	v_add_u32_e32 v36, s4, v29
	v_ashrrev_i32_e32 v37, 31, v36
	v_lshlrev_b64 v[36:37], 12, v[36:37]
	v_lshl_add_u64 v[36:37], v[22:23], 0, v[36:37]
	global_store_dwordx4 v[36:37], v[32:35], off
	ds_read2_b32 v[32:33], v27 offset0:24 offset1:57
	s_waitcnt lgkmcnt(0)
	v_cvt_pk_bf16_f32 v32, v32, v33
	ds_read2_b32 v[34:35], v27 offset0:90 offset1:123
	s_waitcnt lgkmcnt(0)
	v_cvt_pk_bf16_f32 v33, v34, v35
	ds_read2_b32 v[34:35], v27 offset0:156 offset1:189
	s_waitcnt lgkmcnt(0)
	v_cvt_pk_bf16_f32 v34, v34, v35
	ds_read2_b32 v[36:37], v27 offset0:222 offset1:255
	s_waitcnt lgkmcnt(0)
	v_cvt_pk_bf16_f32 v35, v36, v37
	v_add_u32_e32 v36, s4, v30
	v_ashrrev_i32_e32 v37, 31, v36
	v_lshlrev_b64 v[36:37], 12, v[36:37]
	v_lshl_add_u64 v[22:23], v[22:23], 0, v[36:37]
	global_store_dwordx4 v[22:23], v[32:35], off
; #define LAS __attribute__((address_space(3)))
; __device__ __forceinline__ unsigned cvt_pk_bf16(float lo, float hi) { unsigned r; asm volatile("v_cvt_pk_bf16_f32 %0, %1, %2" : "=v"(r) : "v"(lo), "v"(hi)); return r; }
; __device__ __forceinline__ bf16_t* wt_ptr(const Frame& F, int layer, size_t off) { return (bf16_t*)(F.ws + WS_WT + (size_t)layer * LWT + off); }
; __device__ __forceinline__ void transpose_item(const float* W, int K, int N, bf16_t* WT, int dest_row0, int k0, int n0, LAS float* scr, int lane) {
;     ...
;     for (int i = 0; i < 32; ++i) { const int kk = 2 * i + (lane >> 5); wv[i] = LDG(float, W + (size_t)(k0 + kk) * N + n0 + (lane & 31)); }
; #pragma unroll
;     for (int i = 0; i < 32; ++i) { const int kk = 2 * i + (lane >> 5); scr[kk * 33 + (lane & 31)] = wv[i]; }
;     asm volatile("s_waitcnt lgkmcnt(0)" ::: "memory");
;     const int c = lane & 7;
; #pragma unroll
;     for (int j = 0; j < 4; ++j) { const int n = (lane >> 3) + 8 * j; const LAS float* s = scr + (8 * c) * 33 + n;
;         u32x4 o; o.x = cvt_pk_bf16(s[0 * 33], s[1 * 33]); o.y = cvt_pk_bf16(s[2 * 33], s[3 * 33]); o.z = cvt_pk_bf16(s[4 * 33], s[5 * 33]); o.w = cvt_pk_bf16(s[6 * 33], s[7 * 33]);
;         STG(u32x4, WT + (size_t)(dest_row0 + n) * K + k0 + 8 * c) = o; }
;     asm volatile("s_waitcnt lgkmcnt(0)" ::: "memory");
; __device__ __forceinline__ void phase_weights(const Frame& F0, int lmask, int cu0, int ncu, int pm) {
;     ...
;             if (r < I_Q) { const int nblk = NQ / 32, kb = r / nblk, nb = r % nblk; transpose_item(wqkv, DM, NQ, wt_ptr(F, layer, WT_QKV), 32 * nb, 64 * kb, 32 * nb, scr, F.lane); continue; } r -= I_Q;
.LBB0_422:
	s_cbranch_execnz .LBB0_411
.LBB0_423:
	s_abs_i32 s5, s47
	s_mul_hi_u32 s6, s5, s37
	s_mul_i32 s7, s6, s36
	s_ashr_i32 s4, s47, 31
	s_sub_i32 s5, s5, s7
	s_xor_b32 s4, s4, s26
	s_add_i32 s7, s6, 1
	s_sub_i32 s27, s5, s36
	s_cmp_ge_u32 s5, s36
	s_cselect_b32 s6, s7, s6
	s_cselect_b32 s5, s27, s5
	s_add_i32 s7, s6, 1
	s_cmp_ge_u32 s5, s36
	s_cselect_b32 s5, s7, s6
	s_xor_b32 s5, s5, s4
	s_sub_i32 s5, s5, s4
	s_mul_i32 s4, s42, s5
	s_add_i32 s4, s43, s4
	s_lshl_b32 s6, s5, 6
	v_add_u32_e32 v5, s6, v24
	s_ashr_i32 s5, s4, 31
	v_lshl_add_u64 v[22:23], s[4:5], 2, v[18:19]
	v_mad_i64_i32 v[32:33], s[28:29], v5, s24, 0
	v_lshl_add_u64 v[32:33], v[32:33], 2, v[22:23]
	global_load_dword v31, v[32:33], off
	v_add_u32_e32 v32, 2, v5
	v_mad_i64_i32 v[32:33], s[28:29], v32, s24, 0
	v_lshl_add_u64 v[32:33], v[32:33], 2, v[22:23]
	global_load_dword v34, v[32:33], off
	v_add_u32_e32 v32, 4, v5
	v_mad_i64_i32 v[32:33], s[28:29], v32, s24, 0
	v_lshl_add_u64 v[32:33], v[32:33], 2, v[22:23]
	global_load_dword v35, v[32:33], off
	v_add_u32_e32 v32, 6, v5
	v_mad_i64_i32 v[32:33], s[28:29], v32, s24, 0
	v_lshl_add_u64 v[32:33], v[32:33], 2, v[22:23]
	global_load_dword v36, v[32:33], off
	v_add_u32_e32 v32, 8, v5
	v_mad_i64_i32 v[32:33], s[28:29], v32, s24, 0
	v_lshl_add_u64 v[32:33], v[32:33], 2, v[22:23]
	global_load_dword v37, v[32:33], off
	v_add_u32_e32 v32, 10, v5
	v_mad_i64_i32 v[32:33], s[28:29], v32, s24, 0
	v_lshl_add_u64 v[32:33], v[32:33], 2, v[22:23]
	global_load_dword v38, v[32:33], off
	v_add_u32_e32 v32, 12, v5
	v_mad_i64_i32 v[32:33], s[28:29], v32, s24, 0
	v_lshl_add_u64 v[32:33], v[32:33], 2, v[22:23]
	global_load_dword v39, v[32:33], off
	v_add_u32_e32 v32, 14, v5
	v_mad_i64_i32 v[32:33], s[28:29], v32, s24, 0
	v_lshl_add_u64 v[32:33], v[32:33], 2, v[22:23]
	global_load_dword v40, v[32:33], off
	v_add_u32_e32 v32, 16, v5
	v_mad_i64_i32 v[32:33], s[28:29], v32, s24, 0
	v_lshl_add_u64 v[32:33], v[32:33], 2, v[22:23]
	global_load_dword v41, v[32:33], off
	v_add_u32_e32 v32, 18, v5
	v_mad_i64_i32 v[32:33], s[28:29], v32, s24, 0
	v_lshl_add_u64 v[32:33], v[32:33], 2, v[22:23]
	global_load_dword v42, v[32:33], off
	v_add_u32_e32 v32, 20, v5
	v_mad_i64_i32 v[32:33], s[28:29], v32, s24, 0
	v_lshl_add_u64 v[32:33], v[32:33], 2, v[22:23]
	global_load_dword v43, v[32:33], off
	v_add_u32_e32 v32, 22, v5
	v_mad_i64_i32 v[32:33], s[28:29], v32, s24, 0
	v_lshl_add_u64 v[32:33], v[32:33], 2, v[22:23]
	global_load_dword v44, v[32:33], off
	v_add_u32_e32 v32, 24, v5
	v_mad_i64_i32 v[32:33], s[28:29], v32, s24, 0
	v_lshl_add_u64 v[32:33], v[32:33], 2, v[22:23]
	global_load_dword v45, v[32:33], off
	v_add_u32_e32 v32, 26, v5
	v_mad_i64_i32 v[32:33], s[28:29], v32, s24, 0
	v_lshl_add_u64 v[32:33], v[32:33], 2, v[22:23]
	global_load_dword v46, v[32:33], off
	v_add_u32_e32 v32, 28, v5
	v_mad_i64_i32 v[32:33], s[28:29], v32, s24, 0
	v_lshl_add_u64 v[32:33], v[32:33], 2, v[22:23]
	global_load_dword v47, v[32:33], off
	v_add_u32_e32 v32, 30, v5
	v_mad_i64_i32 v[32:33], s[28:29], v32, s24, 0
	v_lshl_add_u64 v[32:33], v[32:33], 2, v[22:23]
	global_load_dword v48, v[32:33], off
	v_add_u32_e32 v32, 32, v5
	v_mad_i64_i32 v[32:33], s[28:29], v32, s24, 0
	v_lshl_add_u64 v[32:33], v[32:33], 2, v[22:23]
	global_load_dword v49, v[32:33], off
	v_add_u32_e32 v32, 34, v5
	v_mad_i64_i32 v[32:33], s[28:29], v32, s24, 0
	v_lshl_add_u64 v[32:33], v[32:33], 2, v[22:23]
	global_load_dword v50, v[32:33], off
	v_add_u32_e32 v32, 36, v5
	v_mad_i64_i32 v[32:33], s[28:29], v32, s24, 0
	v_lshl_add_u64 v[32:33], v[32:33], 2, v[22:23]
	global_load_dword v51, v[32:33], off
	v_add_u32_e32 v32, 38, v5
	v_mad_i64_i32 v[32:33], s[28:29], v32, s24, 0
	v_lshl_add_u64 v[32:33], v[32:33], 2, v[22:23]
	global_load_dword v52, v[32:33], off
	v_add_u32_e32 v32, 40, v5
	v_mad_i64_i32 v[32:33], s[28:29], v32, s24, 0
	v_lshl_add_u64 v[32:33], v[32:33], 2, v[22:23]
	global_load_dword v53, v[32:33], off
	v_add_u32_e32 v32, 42, v5
	v_mad_i64_i32 v[32:33], s[28:29], v32, s24, 0
	v_lshl_add_u64 v[32:33], v[32:33], 2, v[22:23]
	global_load_dword v54, v[32:33], off
	v_add_u32_e32 v32, 44, v5
	v_mad_i64_i32 v[32:33], s[28:29], v32, s24, 0
	v_lshl_add_u64 v[32:33], v[32:33], 2, v[22:23]
	global_load_dword v55, v[32:33], off
	v_add_u32_e32 v32, 46, v5
	v_mad_i64_i32 v[32:33], s[28:29], v32, s24, 0
	v_lshl_add_u64 v[32:33], v[32:33], 2, v[22:23]
	global_load_dword v56, v[32:33], off
	v_add_u32_e32 v32, 48, v5
	v_mad_i64_i32 v[32:33], s[28:29], v32, s24, 0
	v_lshl_add_u64 v[32:33], v[32:33], 2, v[22:23]
	global_load_dword v57, v[32:33], off
	v_add_u32_e32 v32, 50, v5
	v_mad_i64_i32 v[32:33], s[28:29], v32, s24, 0
	v_lshl_add_u64 v[32:33], v[32:33], 2, v[22:23]
	global_load_dword v58, v[32:33], off
	v_add_u32_e32 v32, 52, v5
	v_mad_i64_i32 v[32:33], s[28:29], v32, s24, 0
	v_lshl_add_u64 v[32:33], v[32:33], 2, v[22:23]
	global_load_dword v59, v[32:33], off
	v_add_u32_e32 v32, 54, v5
	v_mad_i64_i32 v[32:33], s[28:29], v32, s24, 0
	v_lshl_add_u64 v[32:33], v[32:33], 2, v[22:23]
	global_load_dword v60, v[32:33], off
	v_add_u32_e32 v32, 56, v5
	v_mad_i64_i32 v[32:33], s[28:29], v32, s24, 0
	v_lshl_add_u64 v[32:33], v[32:33], 2, v[22:23]
	global_load_dword v61, v[32:33], off
	v_add_u32_e32 v32, 58, v5
	v_mad_i64_i32 v[32:33], s[28:29], v32, s24, 0
	v_lshl_add_u64 v[32:33], v[32:33], 2, v[22:23]
	global_load_dword v62, v[32:33], off
	v_add_u32_e32 v32, 60, v5
	v_mad_i64_i32 v[32:33], s[28:29], v32, s24, 0
	v_lshl_add_u64 v[32:33], v[32:33], 2, v[22:23]
	v_add_u32_e32 v5, 62, v5
	global_load_dword v63, v[32:33], off
	v_mad_i64_i32 v[32:33], s[28:29], v5, s24, 0
	v_lshl_add_u64 v[22:23], v[32:33], 2, v[22:23]
	global_load_dword v5, v[22:23], off
	v_add_u32_e32 v22, 0x400, v25
	s_waitcnt vmcnt(0)
; #define LAS __attribute__((address_space(3)))
; __device__ __forceinline__ unsigned cvt_pk_bf16(float lo, float hi) { unsigned r; asm volatile("v_cvt_pk_bf16_f32 %0, %1, %2" : "=v"(r) : "v"(lo), "v"(hi)); return r; }
; __device__ __forceinline__ void transpose_item(const float* W, int K, int N, bf16_t* WT, int dest_row0, int k0, int n0, LAS float* scr, int lane) {
;     ...
;     for (int i = 0; i < 32; ++i) { const int kk = 2 * i + (lane >> 5); scr[kk * 33 + (lane & 31)] = wv[i]; }
;     asm volatile("s_waitcnt lgkmcnt(0)" ::: "memory");
;     const int c = lane & 7;
; #pragma unroll
;     for (int j = 0; j < 4; ++j) { const int n = (lane >> 3) + 8 * j; const LAS float* s = scr + (8 * c) * 33 + n;
;         u32x4 o; o.x = cvt_pk_bf16(s[0 * 33], s[1 * 33]); o.y = cvt_pk_bf16(s[2 * 33], s[3 * 33]); o.z = cvt_pk_bf16(s[4 * 33], s[5 * 33]); o.w = cvt_pk_bf16(s[6 * 33], s[7 * 33]);
;         STG(u32x4, WT + (size_t)(dest_row0 + n) * K + k0 + 8 * c) = o; }
;     asm volatile("s_waitcnt lgkmcnt(0)" ::: "memory");
	ds_write2_b32 v25, v31, v34 offset1:66
	ds_write2_b32 v25, v35, v36 offset0:132 offset1:198
	ds_write2_b32 v22, v37, v38 offset0:8 offset1:74
	ds_write2_b32 v22, v39, v40 offset0:140 offset1:206
	v_add_u32_e32 v22, 0x800, v25
	ds_write2_b32 v22, v41, v42 offset0:16 offset1:82
	ds_write2_b32 v22, v43, v44 offset0:148 offset1:214
	v_add_u32_e32 v22, 0xc00, v25
	ds_write2_b32 v22, v45, v46 offset0:24 offset1:90
	ds_write2_b32 v22, v47, v48 offset0:156 offset1:222
	v_add_u32_e32 v22, 0x1000, v25
	ds_write2_b32 v22, v49, v50 offset0:32 offset1:98
	ds_write2_b32 v22, v51, v52 offset0:164 offset1:230
	v_add_u32_e32 v22, 0x1400, v25
	ds_write2_b32 v22, v53, v54 offset0:40 offset1:106
	ds_write2_b32 v22, v55, v56 offset0:172 offset1:238
	v_add_u32_e32 v22, 0x1800, v25
	ds_write2_b32 v22, v57, v58 offset0:48 offset1:114
	ds_write2_b32 v22, v59, v60 offset0:180 offset1:246
	v_add_u32_e32 v22, 0x1c00, v25
	ds_write2_b32 v22, v61, v62 offset0:56 offset1:122
	ds_write2_b32 v22, v63, v5 offset0:188 offset1:254
	s_waitcnt lgkmcnt(0)
	ds_read2_b32 v[32:33], v27 offset1:33
	s_waitcnt lgkmcnt(0)
	v_cvt_pk_bf16_f32 v32, v32, v33
	ds_read2_b32 v[34:35], v27 offset0:66 offset1:99
	s_waitcnt lgkmcnt(0)
	v_cvt_pk_bf16_f32 v33, v34, v35
	ds_read2_b32 v[34:35], v27 offset0:132 offset1:165
	s_waitcnt lgkmcnt(0)
	v_cvt_pk_bf16_f32 v34, v34, v35
	ds_read2_b32 v[36:37], v27 offset0:198 offset1:231
	s_waitcnt lgkmcnt(0)
	v_cvt_pk_bf16_f32 v35, v36, v37
	v_add_u32_e32 v36, s4, v26
	s_ashr_i32 s7, s6, 31
	v_ashrrev_i32_e32 v37, 31, v36
	v_lshl_add_u64 v[22:23], s[6:7], 1, v[20:21]
	v_lshlrev_b64 v[38:39], 12, v[36:37]
	v_lshl_add_u64 v[38:39], v[22:23], 0, v[38:39]
	global_store_dwordx4 v[38:39], v[32:35], off
	ds_read2_b32 v[32:33], v27 offset0:8 offset1:41
	s_waitcnt lgkmcnt(0)
	v_cvt_pk_bf16_f32 v32, v32, v33
	ds_read2_b32 v[34:35], v27 offset0:74 offset1:107
	s_waitcnt lgkmcnt(0)
	v_cvt_pk_bf16_f32 v33, v34, v35
	ds_read2_b32 v[34:35], v27 offset0:140 offset1:173
	s_waitcnt lgkmcnt(0)
	v_cvt_pk_bf16_f32 v34, v34, v35
	ds_read2_b32 v[38:39], v27 offset0:206 offset1:239
	s_waitcnt lgkmcnt(0)
	v_cvt_pk_bf16_f32 v35, v38, v39
	v_add_u32_e32 v38, 8, v36
	v_ashrrev_i32_e32 v39, 31, v38
	v_lshlrev_b64 v[38:39], 12, v[38:39]
	v_lshl_add_u64 v[38:39], v[22:23], 0, v[38:39]
	global_store_dwordx4 v[38:39], v[32:35], off
	ds_read2_b32 v[32:33], v27 offset0:16 offset1:49
	s_waitcnt lgkmcnt(0)
	v_cvt_pk_bf16_f32 v32, v32, v33
	ds_read2_b32 v[34:35], v27 offset0:82 offset1:115
	s_waitcnt lgkmcnt(0)
	v_cvt_pk_bf16_f32 v33, v34, v35
	ds_read2_b32 v[34:35], v27 offset0:148 offset1:181
	s_waitcnt lgkmcnt(0)
	v_cvt_pk_bf16_f32 v34, v34, v35
	ds_read2_b32 v[38:39], v27 offset0:214 offset1:247
	s_waitcnt lgkmcnt(0)
	v_cvt_pk_bf16_f32 v35, v38, v39
	v_add_u32_e32 v38, 16, v36
	v_ashrrev_i32_e32 v39, 31, v38
	v_lshlrev_b64 v[38:39], 12, v[38:39]
	v_lshl_add_u64 v[38:39], v[22:23], 0, v[38:39]
	v_add_u32_e32 v36, 24, v36
	global_store_dwordx4 v[38:39], v[32:35], off
	ds_read2_b32 v[32:33], v27 offset0:24 offset1:57
	v_ashrrev_i32_e32 v37, 31, v36
	s_waitcnt lgkmcnt(0)
	v_cvt_pk_bf16_f32 v32, v32, v33
	ds_read2_b32 v[34:35], v27 offset0:90 offset1:123
	v_lshlrev_b64 v[36:37], 12, v[36:37]
	s_waitcnt lgkmcnt(0)
	v_cvt_pk_bf16_f32 v33, v34, v35
	ds_read2_b32 v[34:35], v27 offset0:156 offset1:189
	v_lshl_add_u64 v[22:23], v[22:23], 0, v[36:37]
	s_waitcnt lgkmcnt(0)
	v_cvt_pk_bf16_f32 v34, v34, v35
	ds_read2_b32 v[38:39], v27 offset0:222 offset1:255
	s_waitcnt lgkmcnt(0)
	v_cvt_pk_bf16_f32 v35, v38, v39
	global_store_dwordx4 v[22:23], v[32:35], off
	s_branch .LBB0_411

; __device__ __forceinline__ unsigned xb_ld(unsigned* p)              { return __hip_atomic_load(p, __ATOMIC_RELAXED, __HIP_MEMORY_SCOPE_AGENT); }
; __device__ __forceinline__ unsigned xb_add(unsigned* p, unsigned v) { return __hip_atomic_fetch_add(p, v, __ATOMIC_RELAXED, __HIP_MEMORY_SCOPE_AGENT); }
; #define XB_SPIN(cond, bar) do { unsigned _sp = 0; while (cond) { __builtin_amdgcn_s_sleep(1); \
;     if ((++_sp & 255u) == 0u) { if (xb_ld(&(bar)[XB_TMO])) break; if (_sp > XB_SPIN_CAP) { atomicAdd(&(bar)[XB_TMO], 1u); break; } } } } while (0)
; __device__ __forceinline__ void xcd_barrier(const XcdBarrier& b) {
;     ...
;             __builtin_amdgcn_fence(__ATOMIC_RELEASE, "agent");
;             asm volatile("s_waitcnt vmcnt(0)" ::: "memory");
;             const unsigned og = xb_add(&bar[XB_TOP], 1u);
;             const unsigned tg = og / nx;
;             if (og + 1u == (tg + 1u) * nx) xb_add(&bar[XB_TOPGEN], 1u);
;             else XB_SPIN(xb_ld(&bar[XB_TOPGEN]) == tg, bar);
;             __builtin_amdgcn_fence(__ATOMIC_ACQUIRE, "agent");
;             xb_add(&bar[XB_XGEN(b.x)], 1u);
;             asm volatile("s_waitcnt vmcnt(0)" ::: "memory");
;         } else {
;             XB_SPIN(xb_ld(&bar[XB_XGEN(b.x)]) == gen, bar);
;             __builtin_amdgcn_fence(__ATOMIC_ACQUIRE, "agent");
;             asm volatile("s_waitcnt vmcnt(0)" ::: "memory");
;         }
.LBB0_468:
	s_or_b64 exec, exec, s[6:7]
	s_waitcnt vmcnt(0)
	buffer_inv sc1
.LBB0_469:
	s_andn2_saveexec_b64 s[4:5], s[4:5]
	s_cbranch_execz .LBB0_489
	s_mov_b64 s[4:5], exec
	buffer_wbl2 sc1
	s_waitcnt lgkmcnt(0)
	s_waitcnt vmcnt(0)
	v_mbcnt_lo_u32_b32 v0, s4, 0
	v_mbcnt_hi_u32_b32 v0, s5, v0
	v_cmp_eq_u32_e32 vcc, 0, v0
	s_and_saveexec_b64 s[6:7], vcc
	s_cbranch_execz .LBB0_472
	s_bcnt1_i32_b64 s4, s[4:5]
	v_mov_b32_e32 v3, s4
	v_readlane_b32 s4, v255, 17
	v_readlane_b32 s5, v255, 18
	s_nop 4
	global_atomic_add v3, v1, v3, s[4:5] sc0

; #define LAS __attribute__((address_space(3)))
; __device__ __forceinline__ unsigned cvt_pk_bf16(float lo, float hi) { unsigned r; asm volatile("v_cvt_pk_bf16_f32 %0, %1, %2" : "=v"(r) : "v"(lo), "v"(hi)); return r; }
; __device__ __forceinline__ float bf_lo(unsigned w) { return __uint_as_float(w << 16); }
; __device__ __forceinline__ float bf_hi(unsigned w) { return __uint_as_float(w & 0xffff0000u); }
; __device__ __forceinline__ int crow(int r, int hi) { return (r & 3) + 8 * (r >> 2) + 4 * hi; }
; template <int WIN, bool ALIBI, int EPI, bool SINK>
; __device__ __forceinline__ void attn_item(const Item& I, char* lds, int tid_in) {
;     ...
;     __syncthreads();
;     constexpr int RB = (EPI == 2) ? 512 : 256;
;     LAS char* Sw = V_lds + wid * (32 * RB);
;     if constexpr (EPI == 5) {
; #pragma unroll
;       for (int r = 0; r < 16; r += 2) { const int or0 = crow(r, hi), or1 = crow(r + 1, hi); const float f0 = li_l[or0], f1 = li_l[or1];
; #pragma unroll
;         for (int d0 = 0; d0 < 4; ++d0) { const unsigned pk = park[(r >> 1) * 4 + d0]; const float v0 = bf_lo(pk) + o[d0][r] * f0, v1 = bf_hi(pk) + o[d0][r + 1] * f1;
;           const unsigned w = cvt_pk_bf16(v0, v1);
;           *(LAS bf16_t*)(Sw + or0 * RB + (d0 * 32 + r32) * 2) = (bf16_t)(w & 0xffffu); *(LAS bf16_t*)(Sw + or1 * RB + (d0 * 32 + r32) * 2) = (bf16_t)(w >> 16); } }
;     } else {
; #pragma unroll
;       for (int r = 0; r < 16; ++r) { const int orow = crow(r, hi); const float f = li_l[orow];
; #pragma unroll
;         for (int d0 = 0; d0 < 4; ++d0) { const float v = o[d0][r] * f;
;           if constexpr (EPI == 2) *(LAS float*)(Sw + orow * RB + (d0 * 32 + r32) * 4) = v;
;           else *(LAS bf16_t*)(Sw + orow * RB + (d0 * 32 + r32) * 2) = (bf16_t)(cvt_pk_bf16(v, v) & 0xffffu); } }
.LBB0_499:
	s_or_b64 exec, exec, s[4:5]
	s_add_i32 s4, s49, s9
	s_ashr_i32 s5, s4, 31
	s_lshl_b64 s[4:5], s[4:5], 12
	s_add_u32 s4, s44, s4
	s_waitcnt lgkmcnt(0)
	s_addc_u32 s5, s45, s5
	s_lshl_b32 s9, s12, 1
	s_barrier
	ds_read_b32 v0, v174
	s_add_u32 s4, s4, s9
	s_addc_u32 s5, s5, 0
	s_lshl_b32 s9, s24, 13
	s_add_i32 s9, s9, 0
	v_lshl_add_u32 v66, v169, 1, s9
	v_lshl_add_u32 v67, v170, 10, v66
	s_waitcnt lgkmcnt(0)
	v_mul_f32_e32 v50, v50, v0
	v_mul_f32_e32 v34, v34, v0
	v_mul_f32_e32 v18, v18, v0
	v_mul_f32_e32 v0, v2, v0
	v_cvt_pk_bf16_f32 v50, v50, v50
	ds_write_b16 v67, v50
	v_cvt_pk_bf16_f32 v34, v34, v34
	ds_write_b16 v67, v34 offset:64
	v_cvt_pk_bf16_f32 v18, v18, v18
	ds_write_b16 v67, v18 offset:128
	v_cvt_pk_bf16_f32 v0, v0, v0
	ds_read_b32 v2, v174 offset:4
	ds_write_b16 v67, v0 offset:192
	v_lshl_add_u32 v18, v171, 8, v66
	s_add_i32 s8, s8, 1
	s_waitcnt lgkmcnt(1)
	v_mul_f32_e32 v0, v51, v2
	v_cvt_pk_bf16_f32 v0, v0, v0
	ds_write_b16 v18, v0 offset:256
	v_mul_f32_e32 v0, v35, v2
	v_cvt_pk_bf16_f32 v0, v0, v0
	ds_write_b16 v18, v0 offset:320
	v_mul_f32_e32 v0, v19, v2
	v_cvt_pk_bf16_f32 v0, v0, v0
	ds_write_b16 v18, v0 offset:384
	v_mul_f32_e32 v0, v3, v2
	v_cvt_pk_bf16_f32 v0, v0, v0
	ds_read_b32 v2, v174 offset:8
	ds_write_b16 v18, v0 offset:448
	s_waitcnt lgkmcnt(1)
	v_mul_f32_e32 v0, v52, v2
	v_cvt_pk_bf16_f32 v0, v0, v0
	ds_write_b16 v18, v0 offset:512
	v_mul_f32_e32 v0, v36, v2
	v_cvt_pk_bf16_f32 v0, v0, v0
	ds_write_b16 v18, v0 offset:576
	v_mul_f32_e32 v0, v20, v2
	v_cvt_pk_bf16_f32 v0, v0, v0
	ds_write_b16 v18, v0 offset:640
	v_mul_f32_e32 v0, v4, v2
	v_cvt_pk_bf16_f32 v0, v0, v0
	ds_read_b32 v2, v174 offset:12
	ds_write_b16 v18, v0 offset:704
	s_waitcnt lgkmcnt(1)
	v_mul_f32_e32 v0, v53, v2
	v_cvt_pk_bf16_f32 v0, v0, v0
	ds_write_b16 v18, v0 offset:768
	v_mul_f32_e32 v0, v37, v2
	v_cvt_pk_bf16_f32 v0, v0, v0
	ds_write_b16 v18, v0 offset:832
	v_mul_f32_e32 v0, v21, v2
	v_cvt_pk_bf16_f32 v0, v0, v0
	ds_write_b16 v18, v0 offset:896
	v_mul_f32_e32 v0, v5, v2
	v_cvt_pk_bf16_f32 v0, v0, v0
	ds_read_b32 v2, v174 offset:32
	ds_write_b16 v18, v0 offset:960
	s_waitcnt lgkmcnt(1)
	v_mul_f32_e32 v0, v54, v2
	v_cvt_pk_bf16_f32 v0, v0, v0
	ds_write_b16 v18, v0 offset:2048
	v_mul_f32_e32 v0, v38, v2
	v_cvt_pk_bf16_f32 v0, v0, v0
	ds_write_b16 v18, v0 offset:2112
	v_mul_f32_e32 v0, v22, v2
	v_cvt_pk_bf16_f32 v0, v0, v0
	ds_write_b16 v18, v0 offset:2176
	v_mul_f32_e32 v0, v6, v2
	v_cvt_pk_bf16_f32 v0, v0, v0
	ds_read_b32 v2, v174 offset:36
	ds_write_b16 v18, v0 offset:2240
	s_waitcnt lgkmcnt(1)
	v_mul_f32_e32 v0, v55, v2
	v_cvt_pk_bf16_f32 v0, v0, v0
	ds_write_b16 v18, v0 offset:2304
	v_mul_f32_e32 v0, v39, v2
	v_cvt_pk_bf16_f32 v0, v0, v0
	ds_write_b16 v18, v0 offset:2368
	v_mul_f32_e32 v0, v23, v2
	v_cvt_pk_bf16_f32 v0, v0, v0
	ds_write_b16 v18, v0 offset:2432
	v_mul_f32_e32 v0, v7, v2
	v_cvt_pk_bf16_f32 v0, v0, v0
	ds_read_b32 v2, v174 offset:40
	ds_write_b16 v18, v0 offset:2496
	s_waitcnt lgkmcnt(1)
	v_mul_f32_e32 v0, v56, v2
	v_cvt_pk_bf16_f32 v0, v0, v0
	ds_write_b16 v18, v0 offset:2560
	v_mul_f32_e32 v0, v40, v2
	v_cvt_pk_bf16_f32 v0, v0, v0
	ds_write_b16 v18, v0 offset:2624
	v_mul_f32_e32 v0, v24, v2
	v_cvt_pk_bf16_f32 v0, v0, v0
	ds_write_b16 v18, v0 offset:2688
	v_mul_f32_e32 v0, v8, v2
	v_cvt_pk_bf16_f32 v0, v0, v0
	ds_read_b32 v2, v174 offset:44
	ds_write_b16 v18, v0 offset:2752
	s_waitcnt lgkmcnt(1)
	v_mul_f32_e32 v0, v57, v2
	v_cvt_pk_bf16_f32 v0, v0, v0
	ds_write_b16 v18, v0 offset:2816
	v_mul_f32_e32 v0, v41, v2
	v_cvt_pk_bf16_f32 v0, v0, v0
	ds_write_b16 v18, v0 offset:2880
	v_mul_f32_e32 v0, v25, v2
	v_cvt_pk_bf16_f32 v0, v0, v0
	ds_write_b16 v18, v0 offset:2944
	v_mul_f32_e32 v0, v9, v2
	v_cvt_pk_bf16_f32 v0, v0, v0
	ds_read_b32 v2, v174 offset:64
	ds_write_b16 v18, v0 offset:3008
	s_waitcnt lgkmcnt(1)
	v_mul_f32_e32 v0, v58, v2
	v_cvt_pk_bf16_f32 v0, v0, v0
	ds_write_b16 v18, v0 offset:4096
	v_mul_f32_e32 v0, v42, v2
	v_cvt_pk_bf16_f32 v0, v0, v0
	ds_write_b16 v18, v0 offset:4160
	v_mul_f32_e32 v0, v26, v2
	v_cvt_pk_bf16_f32 v0, v0, v0
	ds_write_b16 v18, v0 offset:4224
	v_mul_f32_e32 v0, v10, v2
	v_cvt_pk_bf16_f32 v0, v0, v0
	ds_read_b32 v2, v174 offset:68
	ds_write_b16 v18, v0 offset:4288
	s_waitcnt lgkmcnt(1)
	v_mul_f32_e32 v0, v59, v2
	v_cvt_pk_bf16_f32 v0, v0, v0
	ds_write_b16 v18, v0 offset:4352
	v_mul_f32_e32 v0, v43, v2
	v_cvt_pk_bf16_f32 v0, v0, v0
	ds_write_b16 v18, v0 offset:4416
	v_mul_f32_e32 v0, v27, v2
	v_cvt_pk_bf16_f32 v0, v0, v0
	ds_write_b16 v18, v0 offset:4480
	v_mul_f32_e32 v0, v11, v2
	v_cvt_pk_bf16_f32 v0, v0, v0
	ds_read_b32 v2, v174 offset:72
	ds_write_b16 v18, v0 offset:4544
	s_waitcnt lgkmcnt(1)
; #define LAS __attribute__((address_space(3)))
; __device__ __forceinline__ unsigned cvt_pk_bf16(float lo, float hi) { unsigned r; asm volatile("v_cvt_pk_bf16_f32 %0, %1, %2" : "=v"(r) : "v"(lo), "v"(hi)); return r; }
; __device__ __forceinline__ float bf_lo(unsigned w) { return __uint_as_float(w << 16); }
; __device__ __forceinline__ float bf_hi(unsigned w) { return __uint_as_float(w & 0xffff0000u); }
; __device__ __forceinline__ int crow(int r, int hi) { return (r & 3) + 8 * (r >> 2) + 4 * hi; }
; template <int WIN, bool ALIBI, int EPI, bool SINK>
; __device__ __forceinline__ void attn_item(const Item& I, char* lds, int tid_in) {
;     ...
;       for (int r = 0; r < 16; ++r) { const int orow = crow(r, hi); const float f = li_l[orow];
; #pragma unroll
;         for (int d0 = 0; d0 < 4; ++d0) { const float v = o[d0][r] * f;
;           if constexpr (EPI == 2) *(LAS float*)(Sw + orow * RB + (d0 * 32 + r32) * 4) = v;
;           else *(LAS bf16_t*)(Sw + orow * RB + (d0 * 32 + r32) * 2) = (bf16_t)(cvt_pk_bf16(v, v) & 0xffffu); } }
;     }
;     asm volatile("s_waitcnt lgkmcnt(0)" ::: "memory");
;     if constexpr (EPI == 2) {
; #pragma unroll
;       for (int j = 0; j < 8; ++j) { const int row = 4 * j + rsub; const float fo = al_l[row];
;         const f32x4 a0 = *(const LAS f32x4*)(Sw + row * RB + ch * 32), a1 = *(const LAS f32x4*)(Sw + row * RB + ch * 32 + 16); const u32x4 ov = oldv[j];
;         u32x4 w; w.x = cvt_pk_bf16(fo * bf_lo(ov.x) + a0[0], fo * bf_hi(ov.x) + a0[1]); w.y = cvt_pk_bf16(fo * bf_lo(ov.y) + a0[2], fo * bf_hi(ov.y) + a0[3]);
;         w.z = cvt_pk_bf16(fo * bf_lo(ov.z) + a1[0], fo * bf_hi(ov.z) + a1[1]); w.w = cvt_pk_bf16(fo * bf_lo(ov.w) + a1[2], fo * bf_hi(ov.w) + a1[3]);
;         STG(u32x4, Orow + (size_t)(I.dil * row) * DM) = w; }
;     } else {
; #pragma unroll
;       for (int j = 0; j < 8; ++j) { const int row = 4 * j + rsub; const u32x4 w = *(const LAS u32x4*)(Sw + row * RB + ch * 16);
;         STG(u32x4, Orow + (size_t)(I.dil * row) * DM) = w; }
;     }
;   }
;   __syncthreads();
	v_mul_f32_e32 v0, v60, v2
	v_cvt_pk_bf16_f32 v0, v0, v0
	ds_write_b16 v18, v0 offset:4608
	v_mul_f32_e32 v0, v44, v2
	v_cvt_pk_bf16_f32 v0, v0, v0
	ds_write_b16 v18, v0 offset:4672
	v_mul_f32_e32 v0, v28, v2
	v_cvt_pk_bf16_f32 v0, v0, v0
	ds_write_b16 v18, v0 offset:4736
	v_mul_f32_e32 v0, v12, v2
	v_cvt_pk_bf16_f32 v0, v0, v0
	ds_read_b32 v2, v174 offset:76
	ds_write_b16 v18, v0 offset:4800
	s_waitcnt lgkmcnt(1)
	v_mul_f32_e32 v0, v61, v2
	v_cvt_pk_bf16_f32 v0, v0, v0
	ds_write_b16 v18, v0 offset:4864
	v_mul_f32_e32 v0, v45, v2
	v_cvt_pk_bf16_f32 v0, v0, v0
	ds_write_b16 v18, v0 offset:4928
	v_mul_f32_e32 v0, v29, v2
	v_cvt_pk_bf16_f32 v0, v0, v0
	ds_write_b16 v18, v0 offset:4992
	v_mul_f32_e32 v0, v13, v2
	v_cvt_pk_bf16_f32 v0, v0, v0
	ds_read_b32 v2, v174 offset:96
	ds_write_b16 v18, v0 offset:5056
	s_waitcnt lgkmcnt(1)
	v_mul_f32_e32 v0, v62, v2
	v_cvt_pk_bf16_f32 v0, v0, v0
	ds_write_b16 v18, v0 offset:6144
	v_mul_f32_e32 v0, v46, v2
	v_cvt_pk_bf16_f32 v0, v0, v0
	ds_write_b16 v18, v0 offset:6208
	v_mul_f32_e32 v0, v30, v2
	v_cvt_pk_bf16_f32 v0, v0, v0
	ds_write_b16 v18, v0 offset:6272
	v_mul_f32_e32 v0, v14, v2
	v_cvt_pk_bf16_f32 v0, v0, v0
	ds_read_b32 v2, v174 offset:100
	ds_write_b16 v18, v0 offset:6336
	v_lshrrev_b32_e32 v14, 4, v167
	s_waitcnt lgkmcnt(1)
	v_mul_f32_e32 v0, v63, v2
	v_cvt_pk_bf16_f32 v0, v0, v0
	ds_write_b16 v18, v0 offset:6400
	v_mul_f32_e32 v0, v47, v2
	v_cvt_pk_bf16_f32 v0, v0, v0
	ds_write_b16 v18, v0 offset:6464
	v_mul_f32_e32 v0, v31, v2
	v_cvt_pk_bf16_f32 v0, v0, v0
	ds_write_b16 v18, v0 offset:6528
	v_mul_f32_e32 v0, v15, v2
	v_cvt_pk_bf16_f32 v0, v0, v0
	ds_read_b32 v2, v174 offset:104
	ds_write_b16 v18, v0 offset:6592
	s_waitcnt lgkmcnt(1)
	v_mul_f32_e32 v0, v64, v2
	v_cvt_pk_bf16_f32 v0, v0, v0
	ds_write_b16 v18, v0 offset:6656
	v_mul_f32_e32 v0, v48, v2
	v_cvt_pk_bf16_f32 v0, v0, v0
	ds_write_b16 v18, v0 offset:6720
	v_mul_f32_e32 v0, v32, v2
	v_cvt_pk_bf16_f32 v0, v0, v0
	ds_write_b16 v18, v0 offset:6784
	v_mul_f32_e32 v0, v16, v2
	v_cvt_pk_bf16_f32 v0, v0, v0
	ds_read_b32 v2, v174 offset:108
	ds_write_b16 v18, v0 offset:6848
	v_or_b32_e32 v16, 4, v14
	s_waitcnt lgkmcnt(1)
	v_mul_f32_e32 v0, v65, v2
	v_cvt_pk_bf16_f32 v0, v0, v0
	ds_write_b16 v18, v0 offset:6912
	v_mul_f32_e32 v0, v49, v2
	v_cvt_pk_bf16_f32 v0, v0, v0
	ds_write_b16 v18, v0 offset:6976
	v_mul_f32_e32 v0, v33, v2
	v_cvt_pk_bf16_f32 v0, v0, v0
	ds_write_b16 v18, v0 offset:7040
	v_mul_f32_e32 v0, v17, v2
	v_cvt_pk_bf16_f32 v0, v0, v0
	ds_write_b16 v18, v0 offset:7104
	v_and_b32_e32 v0, 0xf0, v168
	v_add_u32_e32 v15, s9, v0
	v_lshl_add_u64 v[10:11], s[4:5], 0, v[0:1]
	s_waitcnt lgkmcnt(0)
	v_lshl_add_u32 v0, v14, 8, v15
	ds_read_b128 v[2:5], v0
	v_lshl_add_u32 v6, v16, 8, v15
	ds_read_b128 v[6:9], v6
	v_lshlrev_b32_e32 v0, 12, v14
	v_lshl_add_u64 v[12:13], v[10:11], 0, v[0:1]
	v_lshlrev_b32_e32 v0, 12, v16
	s_waitcnt lgkmcnt(1)
	global_store_dwordx4 v[12:13], v[2:5], off
	v_or_b32_e32 v16, 12, v14
	s_mul_i32 s4, s8, s6
	v_lshl_add_u64 v[2:3], v[10:11], 0, v[0:1]
	v_or_b32_e32 v0, 8, v14
	s_waitcnt lgkmcnt(0)
	global_store_dwordx4 v[2:3], v[6:9], off
	v_lshl_add_u32 v2, v0, 8, v15
	ds_read_b128 v[2:5], v2
	v_lshl_add_u32 v6, v16, 8, v15
	ds_read_b128 v[6:9], v6
	v_lshlrev_b32_e32 v0, 12, v0
	v_lshl_add_u64 v[12:13], v[10:11], 0, v[0:1]
	v_lshlrev_b32_e32 v0, 12, v16
	s_waitcnt lgkmcnt(1)
	global_store_dwordx4 v[12:13], v[2:5], off
	v_or_b32_e32 v16, 20, v14
	s_add_i32 s12, s4, s7
	v_lshl_add_u64 v[2:3], v[10:11], 0, v[0:1]
	v_or_b32_e32 v0, 16, v14
	s_waitcnt lgkmcnt(0)
	global_store_dwordx4 v[2:3], v[6:9], off
	v_lshl_add_u32 v2, v0, 8, v15
	ds_read_b128 v[2:5], v2
	v_lshl_add_u32 v6, v16, 8, v15
	ds_read_b128 v[6:9], v6
	v_lshlrev_b32_e32 v0, 12, v0
	v_lshl_add_u64 v[12:13], v[10:11], 0, v[0:1]
	v_lshlrev_b32_e32 v0, 12, v16
	s_waitcnt lgkmcnt(1)
	global_store_dwordx4 v[12:13], v[2:5], off
	s_cmpk_lt_i32 s12, 0xa00
	s_nop 0
	v_lshl_add_u64 v[2:3], v[10:11], 0, v[0:1]
	v_or_b32_e32 v0, 24, v14
	s_waitcnt lgkmcnt(0)
	global_store_dwordx4 v[2:3], v[6:9], off
	v_lshl_add_u32 v2, v0, 8, v15
	v_or_b32_e32 v14, 28, v14
	ds_read_b128 v[2:5], v2
	v_lshl_add_u32 v6, v14, 8, v15
	ds_read_b128 v[6:9], v6
	v_lshlrev_b32_e32 v0, 12, v0
	v_lshl_add_u64 v[12:13], v[10:11], 0, v[0:1]
	v_lshlrev_b32_e32 v0, 12, v14
	s_waitcnt lgkmcnt(1)
	global_store_dwordx4 v[12:13], v[2:5], off
	s_nop 1
	v_lshl_add_u64 v[2:3], v[10:11], 0, v[0:1]
	s_waitcnt lgkmcnt(0)
	global_store_dwordx4 v[2:3], v[6:9], off
	s_barrier
	s_cbranch_scc0 .LBB0_521

; #define LAS __attribute__((address_space(3)))
; __device__ __forceinline__ const float* argp(const Frame& F, int idx) { unsigned long long p = F.kargs; asm volatile("" : "+s"(p)); return ((const float* const __attribute__((address_space(4)))*)p)[idx]; }
; __device__ __forceinline__ int v_rd_base(int lane) { return ((lane & 3) << 3) | (((lane >> 2) & 3) << 6) | (((lane >> 4) & 1) << 5) | (((lane >> 5) & 1) << 8); }
; #define WSLOAD(n) do { _Pragma("unroll") for (int i_ = 0; i_ < 4; ++i_) { int u_ = WUKB(n) + sr4 + 16 * i_; u_ = min(max(u_, 0), I.SU - 1); \
;       const bf16_t* rp_ = I.qkv + (size_t)(I.seq_base + clsw + I.dil * u_) * I.W + sc4; stv[i_] = LDG(bf16x8, rp_ + I.vcol); stk[i_] = LDG(bf16x8, rp_ + I.kcol); } } while (0)
; #define WSWRITE(b) do { _Pragma("unroll") for (int i_ = 0; i_ < 4; ++i_) { *(LAS bf16x8*)(Vh + (b) * SHM_V + v_st(sr4 + 16 * i_, sc4)) = stv[i_]; \
;       *(LAS bf16x8*)(Kh + (b) * SHM_K + KSWZ(sr4 + 16 * i_, sc4 * 2)) = stk[i_]; } } while (0)
; template <int WIN, bool ALIBI, int EPI, bool SINK>
; __device__ __forceinline__ void attn_item(const Item& I, char* lds, int tid_in) {
;     ...
;   const int hh = wid >> 2, tl = tid & 255, sr4 = tl >> 4, sc4 = (tl & 15) * 8;
;   LAS char* Vh = V_lds + hh * (2 * (SHM_V + SHM_K)); LAS char* Kh = Vh + 2 * SHM_V;
;   const int vbh = (int)(unsigned)(uintptr_t)Vh + v_rd_base(lane);
;   const int clsw = I.c0 + wcls, NTw = two ? 2 : (128 + 2 * WIN) / 64, ukbw = two ? 0 : I.u0 + 128 * hh - WIN;
;   bf16x8 stv[4], stk[4];
;     ...
;   WSLOAD(0); asm volatile("s_waitcnt vmcnt(0)" ::: "memory"); WSWRITE(0); if (1 < NTw) WSLOAD(1); __syncthreads();
; template <int MODE> __device__ __forceinline__ void phase_attn_fast(const Frame& F0) {
;     ...
;       const float slope2 = exp2f(-0.5f * (float)(d.h + 1)) * LOG2E;
;       if (MODE == 0) { I.ukb0 = 0; I.NT = d.S / 64; I.ropetab = (const float*)(F.ws + WS_ROPE); I.qgain = argp(F, 9); fa::attn_item<0, false, 0, false>(I, (char*)F.lds, F.tid); }
;       if (MODE == 1) { I.ukb0 = I.u0 - 128; I.NT = 8; I.nslope = -slope2; I.sink2 = argp(F, 13)[d.h] * LOG2E; fa::attn_item<128, true, 0, true>(I, (char*)F.lds, F.tid); }
;       if (MODE == 4) { I.ukb0 = I.u0 - 64; I.NT = 6; I.nslope = -slope2; fa::attn_item<64, true, 1, false>(I, (char*)F.lds, F.tid); }
.LBB0_505:
	s_lshr_b32 s24, s12, s13
	s_and_b32 s5, s5, s12
	s_lshl_b32 s31, s5, 8
	s_lshl_b32 s5, s24, 5
	s_and_b32 s13, s24, 15
	s_and_b32 s5, s5, 0x180
	s_or_b32 s27, s5, 0x800
	s_or_b32 s28, s5, 0xa00
	s_add_i32 s5, s13, 1
	v_cvt_f32_ubyte0_e32 v0, s5
	v_mul_f32_e32 v2, -0.5, v0
	s_mov_b32 s5, 0xc2fc0000
	v_cmp_gt_f32_e32 vcc, s5, v2
	s_lshl_b32 s12, s13, 7
	s_and_b64 s[36:37], vcc, exec
	v_cndmask_b32_e32 v2, 0, v230, vcc
	v_fmac_f32_e32 v2, -0.5, v0
	v_exp_f32_e32 v0, v2
	s_cselect_b32 s5, 0xffffffc0, 0
	v_mov_b32_e32 v36, v166
	v_ldexp_f32 v0, v0, s5
	v_readfirstlane_b32 s5, v36
	s_ashr_i32 s24, s5, 6
	v_and_b32_e32 v169, 31, v36
	s_lshl_b32 s49, s24, 5
	v_mul_f32_e32 v172, 0xbfb8aa3b, v0
	v_or_b32_e32 v0, s49, v169
	v_add_u32_e32 v4, s31, v0
	v_add_u32_e32 v162, s9, v4
	v_mov_b64_e32 v[2:3], s[40:41]
	v_bfe_u32 v170, v36, 5, 1
	v_mad_i64_i32 v[2:3], s[36:37], v162, s89, v[2:3]
	s_lshl_b32 s72, s13, 8
	v_lshl_add_u64 v[2:3], v[2:3], 0, s[72:73]
	v_lshlrev_b32_e32 v0, 4, v170
	s_and_b32 s26, s5, 0x3fffffc0
	v_lshl_add_u64 v[2:3], v[2:3], 0, v[0:1]
	s_lshl_b32 s26, s26, 2
	s_ashr_i32 s5, s5, 8
	global_load_dwordx4 v[98:101], v[2:3], off
	global_load_dwordx4 v[102:105], v[2:3], off offset:32
	global_load_dwordx4 v[106:109], v[2:3], off offset:64
	global_load_dwordx4 v[110:113], v[2:3], off offset:96
	global_load_dwordx4 v[114:117], v[2:3], off offset:128
	global_load_dwordx4 v[118:121], v[2:3], off offset:160
	global_load_dwordx4 v[122:125], v[2:3], off offset:192
	global_load_dwordx4 v[126:129], v[2:3], off offset:224
	v_sub_u32_e32 v2, 0, v4
	s_add_i32 s29, s26, 0
	v_max_i32_e32 v37, 0xffffffc0, v2
	v_xad_u32 v2, v4, -1, s4
	v_lshlrev_b32_e32 v40, 3, v36
	s_lshl_b32 s26, s5, 16
	s_lshl_b32 s5, s5, 7
	v_and_b32_e32 v167, 63, v36
	v_min_i32_e32 v38, 64, v2
	v_lshlrev_b32_e32 v171, 2, v170
	v_and_b32_e32 v2, 0x78, v40
	v_lshlrev_b32_e32 v168, 4, v36
	s_add_i32 s30, s26, 0
	s_add_i32 s26, s31, s5
	v_sub_u32_e32 v39, v171, v4
	v_lshlrev_b32_e32 v34, 1, v2
	v_lshlrev_b32_e32 v2, 3, v167
	v_and_b32_e32 v3, 0xc0, v168
	v_lshlrev_b32_e32 v4, 1, v36
	v_bfe_u32 v42, v36, 4, 4
	s_sub_i32 s5, s26, 64
	v_and_or_b32 v3, v2, 24, v3
	v_and_b32_e32 v4, 32, v4
	v_and_b32_e32 v2, 0x100, v2
	v_or_b32_e32 v44, s5, v42
	v_or3_b32 v43, v3, v4, v2
	s_add_i32 s48, s4, -1
	v_max_i32_e32 v2, 0, v44
	v_mov_b32_e32 v35, v1
	v_min_u32_e32 v2, s48, v2
	v_lshl_add_u64 v[164:165], s[40:41], 0, v[34:35]
	v_add_u32_e32 v2, s9, v2
	v_mad_i64_i32 v[6:7], s[4:5], v2, s89, v[164:165]
	s_lshl_b32 s72, s28, 1
	v_lshl_add_u64 v[2:3], v[6:7], 0, s[72:73]
	global_load_dwordx4 v[2:5], v[2:3], off
	v_max_i32_e32 v10, -16, v44
	v_add_u32_e32 v10, 16, v10
	v_min_u32_e32 v10, s48, v10
	v_max_i32_e32 v18, 0xffffffe0, v44
	s_lshl_b32 s4, s27, 1
	s_mov_b32 s5, s73
	v_add_u32_e32 v10, s9, v10
	v_add_u32_e32 v18, 32, v18
	v_lshl_add_u64 v[6:7], v[6:7], 0, s[4:5]
	v_mad_i64_i32 v[14:15], s[36:37], v10, s89, v[164:165]
	v_min_u32_e32 v18, s48, v18
	v_max_i32_e32 v26, 0xffffffd0, v44
	global_load_dwordx4 v[6:9], v[6:7], off
	v_lshl_add_u64 v[10:11], v[14:15], 0, s[72:73]
	v_add_u32_e32 v18, s9, v18
	v_add_u32_e32 v26, 48, v26
	global_load_dwordx4 v[10:13], v[10:11], off
	v_lshl_add_u64 v[14:15], v[14:15], 0, s[4:5]
	v_mad_i64_i32 v[22:23], s[36:37], v18, s89, v[164:165]
	v_min_u32_e32 v26, s48, v26
	global_load_dwordx4 v[14:17], v[14:15], off
	v_lshl_add_u64 v[18:19], v[22:23], 0, s[72:73]
	v_add_u32_e32 v26, s9, v26
	global_load_dwordx4 v[18:21], v[18:19], off
	v_lshl_add_u64 v[22:23], v[22:23], 0, s[4:5]
	v_mad_i64_i32 v[30:31], s[36:37], v26, s89, v[164:165]
	global_load_dwordx4 v[22:25], v[22:23], off
	v_lshl_add_u64 v[26:27], v[30:31], 0, s[72:73]
	global_load_dwordx4 v[26:29], v[26:27], off
	v_lshl_add_u64 v[30:31], v[30:31], 0, s[4:5]
	global_load_dwordx4 v[30:33], v[30:31], off
	v_lshrrev_b32_e32 v41, 4, v36
	v_bfe_u32 v35, v40, 5, 2
	v_lshrrev_b32_e32 v40, 5, v36
	v_bfe_u32 v45, v36, 4, 2
	v_and_or_b32 v40, v40, 4, v45
	v_and_or_b32 v35, v41, 4, v35
	v_cvt_f32_i32_e32 v173, v38
	v_and_b32_e32 v38, 48, v34
	v_lshl_add_u32 v40, v40, 6, s30
	v_lshlrev_b32_e32 v35, 9, v35
	s_add_i32 s49, s49, s31
	s_movk_i32 s31, 0x70
	v_add3_u32 v175, v40, v38, v35
	s_waitcnt vmcnt(0)
; #define WSLOAD(n) do { _Pragma("unroll") for (int i_ = 0; i_ < 4; ++i_) { int u_ = WUKB(n) + sr4 + 16 * i_; u_ = min(max(u_, 0), I.SU - 1); \
;       const bf16_t* rp_ = I.qkv + (size_t)(I.seq_base + clsw + I.dil * u_) * I.W + sc4; stv[i_] = LDG(bf16x8, rp_ + I.vcol); stk[i_] = LDG(bf16x8, rp_ + I.kcol); } } while (0)
; #define WSWRITE(b) do { _Pragma("unroll") for (int i_ = 0; i_ < 4; ++i_) { *(LAS bf16x8*)(Vh + (b) * SHM_V + v_st(sr4 + 16 * i_, sc4)) = stv[i_]; \
;       *(LAS bf16x8*)(Kh + (b) * SHM_K + KSWZ(sr4 + 16 * i_, sc4 * 2)) = stk[i_]; } } while (0)
; template <int WIN, bool ALIBI, int EPI, bool SINK>
; __device__ __forceinline__ void attn_item(const Item& I, char* lds, int tid_in) {
;     ...
;   bf16x8 stv[4], stk[4];
;     ...
;   WSLOAD(0); asm volatile("s_waitcnt vmcnt(0)" ::: "memory"); WSWRITE(0); if (1 < NTw) WSLOAD(1); __syncthreads();
	v_bitop3_b32 v34, v34, v36, s31 bitop3:0x78
	s_add_i32 s29, s29, 0x20000
	v_cvt_f32_i32_e32 v177, v39
	v_cvt_f32_i32_e32 v179, v37
	v_add_u32_e32 v180, s30, v43
	v_bitop3_b32 v182, v0, v168, s31 bitop3:0x78
	v_add_u32_e32 v174, s29, v0
	v_or3_b32 v191, v42, s26, 64
	s_mov_b32 s25, 0
	v_ashrrev_i32_e32 v163, 31, v162
	s_sub_i32 s50, s49, 64
	s_add_i32 s51, s49, 0x5f
	v_lshl_add_u32 v181, v169, 8, s30
	v_lshl_add_u32 v178, v169, 2, s29
	v_mov_b32_e32 v192, 0
	v_mov_b32_e32 v183, 0xf149f2ca
	s_lshl_b32 s46, s27, 1
	s_mov_b32 s52, 0
	ds_write_b128 v175, v[2:5]
	v_lshlrev_b32_e32 v2, 8, v42
	v_add3_u32 v176, s30, v34, v2
	v_max_i32_e32 v2, 0xffffffc0, v44
	v_add_u32_e32 v2, 64, v2
	v_min_u32_e32 v2, s48, v2
	v_add_u32_e32 v2, s9, v2
	v_mad_i64_i32 v[2:3], s[36:37], v2, s89, v[164:165]
	ds_write_b128 v176, v[6:9] offset:32768
	ds_write_b128 v175, v[10:13] offset:4096
	ds_write_b128 v176, v[14:17] offset:36864
	ds_write_b128 v175, v[18:21] offset:8192
	ds_write_b128 v176, v[22:25] offset:40960
	ds_write_b128 v175, v[26:29] offset:12288
	ds_write_b128 v176, v[30:33] offset:45056
	v_lshl_add_u64 v[4:5], v[2:3], 0, s[72:73]
	v_lshl_add_u64 v[2:3], v[2:3], 0, s[4:5]
	global_load_dwordx4 v[130:133], v[4:5], off
	global_load_dwordx4 v[134:137], v[2:3], off
	v_max_i32_e32 v2, 0xffffffb0, v44
	v_add_u32_e32 v2, 0x50, v2
	v_min_u32_e32 v2, s48, v2
	v_add_u32_e32 v2, s9, v2
	v_mad_i64_i32 v[2:3], s[36:37], v2, s89, v[164:165]
	v_lshl_add_u64 v[4:5], v[2:3], 0, s[72:73]
	v_lshl_add_u64 v[2:3], v[2:3], 0, s[4:5]
	global_load_dwordx4 v[138:141], v[4:5], off
	global_load_dwordx4 v[142:145], v[2:3], off
	v_max_i32_e32 v2, 0xffffffa0, v44
	v_add_u32_e32 v2, 0x60, v2
	v_min_u32_e32 v2, s48, v2
	v_add_u32_e32 v2, s9, v2
	v_mad_i64_i32 v[2:3], s[36:37], v2, s89, v[164:165]
	v_lshl_add_u64 v[4:5], v[2:3], 0, s[72:73]
	v_lshl_add_u64 v[2:3], v[2:3], 0, s[4:5]
	global_load_dwordx4 v[146:149], v[4:5], off
	global_load_dwordx4 v[150:153], v[2:3], off
	v_max_i32_e32 v2, 0xffffff90, v44
	v_add_u32_e32 v2, 0x70, v2
	v_min_u32_e32 v2, s48, v2
	v_add_u32_e32 v2, s9, v2
	v_mad_i64_i32 v[2:3], s[36:37], v2, s89, v[164:165]
	v_lshl_add_u64 v[4:5], v[2:3], 0, s[72:73]
	v_lshl_add_u64 v[2:3], v[2:3], 0, s[4:5]
	global_load_dwordx4 v[154:157], v[4:5], off
	global_load_dwordx4 v[158:161], v[2:3], off
	v_and_b32_e32 v2, 0x70, v168
	s_movk_i32 s4, 0xe0
	v_mov_b32_e32 v14, v1
	v_mov_b32_e32 v15, v1
	v_bitop3_b32 v184, v0, v2, 32 bitop3:0x36
	v_bitop3_b32 v185, v0, v2, 64 bitop3:0x36
	v_bitop3_b32 v186, v0, v2, s93 bitop3:0x36
	v_bitop3_b32 v187, v0, v2, s85 bitop3:0x36
	v_bitop3_b32 v188, v0, v2, s67 bitop3:0x36
	v_bitop3_b32 v189, v0, v2, s83 bitop3:0x36
	v_bitop3_b32 v190, v0, v2, s4 bitop3:0x36
	v_mov_b32_e32 v0, v1
	v_mov_b32_e32 v2, v1
	v_mov_b32_e32 v3, v1
	v_mov_b32_e32 v4, v1
	v_mov_b32_e32 v5, v1
	v_mov_b32_e32 v6, v1
	v_mov_b32_e32 v7, v1
	v_mov_b32_e32 v8, v1
	v_mov_b32_e32 v9, v1
	v_mov_b32_e32 v10, v1
	v_mov_b32_e32 v11, v1
	v_mov_b32_e32 v12, v1
	v_mov_b32_e32 v13, v1
	v_mov_b64_e32 v[64:65], v[14:15]
	v_mov_b64_e32 v[48:49], v[14:15]
	v_mov_b64_e32 v[32:33], v[14:15]
	v_mov_b64_e32 v[62:63], v[12:13]
	v_mov_b64_e32 v[60:61], v[10:11]
	v_mov_b64_e32 v[58:59], v[8:9]
	v_mov_b64_e32 v[56:57], v[6:7]
	v_mov_b64_e32 v[54:55], v[4:5]
	v_mov_b64_e32 v[52:53], v[2:3]
	v_mov_b64_e32 v[50:51], v[0:1]
	v_mov_b64_e32 v[46:47], v[12:13]
	v_mov_b64_e32 v[44:45], v[10:11]
	v_mov_b64_e32 v[42:43], v[8:9]
	v_mov_b64_e32 v[40:41], v[6:7]
	v_mov_b64_e32 v[38:39], v[4:5]
	v_mov_b64_e32 v[36:37], v[2:3]
	v_mov_b64_e32 v[34:35], v[0:1]
	v_mov_b64_e32 v[30:31], v[12:13]
	v_mov_b64_e32 v[28:29], v[10:11]
	v_mov_b64_e32 v[26:27], v[8:9]
	v_mov_b64_e32 v[24:25], v[6:7]
	v_mov_b64_e32 v[22:23], v[4:5]
	v_mov_b64_e32 v[20:21], v[2:3]
	v_mov_b64_e32 v[18:19], v[0:1]
	v_mov_b64_e32 v[16:17], v[14:15]
	v_cmp_gt_u32_e64 s[36:37], 32, v167
	s_lshl_b32 s72, s28, 1
	v_mov_b64_e32 v[14:15], v[12:13]
	v_mov_b64_e32 v[12:13], v[10:11]
	v_mov_b64_e32 v[10:11], v[8:9]
	v_mov_b64_e32 v[8:9], v[6:7]
	v_mov_b64_e32 v[6:7], v[4:5]
	v_mov_b64_e32 v[4:5], v[2:3]
	v_mov_b64_e32 v[2:3], v[0:1]
	s_waitcnt lgkmcnt(0)
	s_barrier
	s_branch .LBB0_507

; #define SBAR() __builtin_amdgcn_sched_barrier(0)
; #define RESC(a) do { if (__any((a) < 1.f)) { if (hi == 0) al_l[r32] = (a); asm volatile("s_waitcnt lgkmcnt(0)" ::: "memory"); \
;     _Pragma("unroll") for (int d = 0; d < 4; ++d) _Pragma("unroll") for (int r = 0; r < 16; ++r) o[d][r] *= al_l[crow(r, hi)]; } } while (0)
; #define WACT(n) (WUKB(n) + 63 >= uqw - WIN && WUKB(n) <= uqw + 31 + WIN)
; #define WSLOAD(n) do { _Pragma("unroll") for (int i_ = 0; i_ < 4; ++i_) { int u_ = WUKB(n) + sr4 + 16 * i_; u_ = min(max(u_, 0), I.SU - 1); \
;       const bf16_t* rp_ = I.qkv + (size_t)(I.seq_base + clsw + I.dil * u_) * I.W + sc4; stv[i_] = LDG(bf16x8, rp_ + I.vcol); stk[i_] = LDG(bf16x8, rp_ + I.kcol); } } while (0)
; #define WSWRITE(b) do { _Pragma("unroll") for (int i_ = 0; i_ < 4; ++i_) { *(LAS bf16x8*)(Vh + (b) * SHM_V + v_st(sr4 + 16 * i_, sc4)) = stv[i_]; \
;       *(LAS bf16x8*)(Kh + (b) * SHM_K + KSWZ(sr4 + 16 * i_, sc4 * 2)) = stk[i_]; } } while (0)
; template <int WIN, bool ALIBI, int EPI, bool SINK>
; __device__ __forceinline__ void attn_item(const Item& I, char* lds, int tid_in) {
;     ...
;   for (int n = 0; n < NTw; ++n) { const int bsel = n & 1;
;     if (WACT(n)) { qkt(pA0, pA1, Kh + bsel * SHM_K, qr, r32, hi);
;       partialSM<WIN, ALIBI>(pA0, pA1, m_reg, mnA, alA, dq + (float)WUKB(n), I.nslope, lo, hi_, true); RESC(alA);
;       finishSM(pA0, pA1, alA, l_reg, pa0, pa1, pa2, pa3); SBAR(); pv_d0(o, vbh + bsel * SHM_V, pa0, pa1, pa2, pa3); }
;     if (n + 1 < NTw) { asm volatile("s_waitcnt vmcnt(0)" ::: "memory"); WSWRITE(bsel ^ 1); if (n + 2 < NTw) WSLOAD(n + 2); }
;     __syncthreads();
.LBB0_513:
	s_cmp_gt_u32 s52, 2
	s_cbranch_scc1 .LBB0_506
	s_waitcnt vmcnt(0)
	s_lshl_b32 s4, s27, 14
	s_xor_b32 s4, s4, 0x4000
	v_add_u32_e32 v0, s4, v175
	v_add_u32_e32 v66, s4, v176
	s_cmpk_eq_i32 s25, 0x80
	ds_write_b128 v0, v[130:133]
	ds_write_b128 v66, v[134:137] offset:32768
	ds_write_b128 v0, v[138:141] offset:4096
	ds_write_b128 v66, v[142:145] offset:36864
	ds_write_b128 v0, v[146:149] offset:8192
	ds_write_b128 v66, v[150:153] offset:40960
	ds_write_b128 v0, v[154:157] offset:12288
	ds_write_b128 v66, v[158:161] offset:45056
	s_cbranch_scc1 .LBB0_506
	v_add_u32_e32 v0, s25, v191
	v_max_i32_e32 v66, 0, v0
	v_min_i32_e32 v66, s48, v66
	v_add_u32_e32 v66, s9, v66
	v_mad_i64_i32 v[66:67], s[4:5], v66, s89, v[164:165]
	s_mov_b32 s47, s73
	v_lshl_add_u64 v[68:69], v[66:67], 0, s[72:73]
	v_lshl_add_u64 v[66:67], v[66:67], 0, s[46:47]
	global_load_dwordx4 v[130:133], v[68:69], off
	global_load_dwordx4 v[134:137], v[66:67], off
	v_max_i32_e32 v66, -16, v0
	v_add_u32_e32 v66, 16, v66
	v_min_i32_e32 v66, s48, v66
	v_add_u32_e32 v66, s9, v66
	v_mad_i64_i32 v[66:67], s[4:5], v66, s89, v[164:165]
	v_lshl_add_u64 v[68:69], v[66:67], 0, s[72:73]
	v_lshl_add_u64 v[66:67], v[66:67], 0, s[46:47]
	global_load_dwordx4 v[138:141], v[68:69], off
	global_load_dwordx4 v[142:145], v[66:67], off
	v_max_i32_e32 v66, 0xffffffe0, v0
	v_add_u32_e32 v66, 32, v66
	v_min_i32_e32 v66, s48, v66
	v_max_i32_e32 v0, 0xffffffd0, v0
	v_add_u32_e32 v66, s9, v66
	v_add_u32_e32 v0, 48, v0
	v_mad_i64_i32 v[66:67], s[4:5], v66, s89, v[164:165]
	v_min_i32_e32 v0, s48, v0
	v_lshl_add_u64 v[68:69], v[66:67], 0, s[72:73]
	v_lshl_add_u64 v[66:67], v[66:67], 0, s[46:47]
	v_add_u32_e32 v0, s9, v0
	global_load_dwordx4 v[146:149], v[68:69], off
	global_load_dwordx4 v[150:153], v[66:67], off
	v_mad_i64_i32 v[66:67], s[4:5], v0, s89, v[164:165]
	v_lshl_add_u64 v[68:69], v[66:67], 0, s[72:73]
	v_lshl_add_u64 v[66:67], v[66:67], 0, s[46:47]
	global_load_dwordx4 v[154:157], v[68:69], off
	global_load_dwordx4 v[158:161], v[66:67], off
	s_branch .LBB0_506

; __device__ __forceinline__ unsigned xb_ld(unsigned* p)              { return __hip_atomic_load(p, __ATOMIC_RELAXED, __HIP_MEMORY_SCOPE_AGENT); }
; __device__ __forceinline__ unsigned xb_add(unsigned* p, unsigned v) { return __hip_atomic_fetch_add(p, v, __ATOMIC_RELAXED, __HIP_MEMORY_SCOPE_AGENT); }
; #define XB_SPIN(cond, bar) do { unsigned _sp = 0; while (cond) { __builtin_amdgcn_s_sleep(1); \
;     if ((++_sp & 255u) == 0u) { if (xb_ld(&(bar)[XB_TMO])) break; if (_sp > XB_SPIN_CAP) { atomicAdd(&(bar)[XB_TMO], 1u); break; } } } } while (0)
; __device__ __forceinline__ void xcd_barrier(const XcdBarrier& b) {
;     ...
;             __builtin_amdgcn_fence(__ATOMIC_RELEASE, "agent");
;             asm volatile("s_waitcnt vmcnt(0)" ::: "memory");
;             const unsigned og = xb_add(&bar[XB_TOP], 1u);
;             const unsigned tg = og / nx;
;             if (og + 1u == (tg + 1u) * nx) xb_add(&bar[XB_TOPGEN], 1u);
;             else XB_SPIN(xb_ld(&bar[XB_TOPGEN]) == tg, bar);
;             __builtin_amdgcn_fence(__ATOMIC_ACQUIRE, "agent");
;             xb_add(&bar[XB_XGEN(b.x)], 1u);
;             asm volatile("s_waitcnt vmcnt(0)" ::: "memory");
;         } else {
;             XB_SPIN(xb_ld(&bar[XB_XGEN(b.x)]) == gen, bar);
;             __builtin_amdgcn_fence(__ATOMIC_ACQUIRE, "agent");
;             asm volatile("s_waitcnt vmcnt(0)" ::: "memory");
;         }
.LBB0_553:
	s_or_b64 exec, exec, s[6:7]
	s_waitcnt vmcnt(0)
	buffer_inv sc1
.LBB0_554:
	s_andn2_saveexec_b64 s[4:5], s[4:5]
	s_cbranch_execz .LBB0_574
	s_mov_b64 s[4:5], exec
	buffer_wbl2 sc1
	s_waitcnt lgkmcnt(0)
	s_waitcnt vmcnt(0)
	v_mbcnt_lo_u32_b32 v0, s4, 0
	v_mbcnt_hi_u32_b32 v0, s5, v0
	v_cmp_eq_u32_e32 vcc, 0, v0
	s_and_saveexec_b64 s[6:7], vcc
	s_cbranch_execz .LBB0_557
	s_bcnt1_i32_b64 s4, s[4:5]
	v_mov_b32_e32 v3, s4
	v_readlane_b32 s4, v255, 17
	v_readlane_b32 s5, v255, 18
	s_nop 4
	global_atomic_add v3, v1, v3, s[4:5] sc0

; #define LAS __attribute__((address_space(3)))
; __device__ __forceinline__ unsigned cvt_pk_bf16(float lo, float hi) { unsigned r; asm volatile("v_cvt_pk_bf16_f32 %0, %1, %2" : "=v"(r) : "v"(lo), "v"(hi)); return r; }
; __device__ __forceinline__ float bf_lo(unsigned w) { return __uint_as_float(w << 16); }
; __device__ __forceinline__ float bf_hi(unsigned w) { return __uint_as_float(w & 0xffff0000u); }
; __device__ __forceinline__ int crow(int r, int hi) { return (r & 3) + 8 * (r >> 2) + 4 * hi; }
; template <int WIN, bool ALIBI, int EPI, bool SINK>
; __device__ __forceinline__ void attn_item(const Item& I, char* lds, int tid_in) {
;     ...
;     const int rsub = lane >> 4, ch = lane & 15;
;     bf16_t* Orow = I.O + (size_t)tokw * DM + I.ocol + ch * 8;
;     u32x4 oldv[(EPI == 2) ? 8 : 1];
;     if constexpr (EPI == 2) {
; #pragma unroll
;       for (int j = 0; j < 8; ++j) oldv[j] = LDG(u32x4, Orow + (size_t)(I.dil * (4 * j + rsub)) * DM); }
;     __syncthreads();
;     constexpr int RB = (EPI == 2) ? 512 : 256;
;     LAS char* Sw = V_lds + wid * (32 * RB);
;     if constexpr (EPI == 5) {
; #pragma unroll
;       for (int r = 0; r < 16; r += 2) { const int or0 = crow(r, hi), or1 = crow(r + 1, hi); const float f0 = li_l[or0], f1 = li_l[or1];
; #pragma unroll
;         for (int d0 = 0; d0 < 4; ++d0) { const unsigned pk = park[(r >> 1) * 4 + d0]; const float v0 = bf_lo(pk) + o[d0][r] * f0, v1 = bf_hi(pk) + o[d0][r + 1] * f1;
;           const unsigned w = cvt_pk_bf16(v0, v1);
;           *(LAS bf16_t*)(Sw + or0 * RB + (d0 * 32 + r32) * 2) = (bf16_t)(w & 0xffffu); *(LAS bf16_t*)(Sw + or1 * RB + (d0 * 32 + r32) * 2) = (bf16_t)(w >> 16); } }
;     } else {
; #pragma unroll
;       for (int r = 0; r < 16; ++r) { const int orow = crow(r, hi); const float f = li_l[orow];
; #pragma unroll
;         for (int d0 = 0; d0 < 4; ++d0) { const float v = o[d0][r] * f;
;           if constexpr (EPI == 2) *(LAS float*)(Sw + orow * RB + (d0 * 32 + r32) * 4) = v;
;           else *(LAS bf16_t*)(Sw + orow * RB + (d0 * 32 + r32) * 2) = (bf16_t)(cvt_pk_bf16(v, v) & 0xffffu); } }
.LBB0_581:
	s_or_b64 exec, exec, s[4:5]
	s_lshl_b32 s4, s25, 2
	s_add_i32 s4, s4, s13
	s_ashr_i32 s5, s4, 31
	s_lshl_b64 s[4:5], s[4:5], 12
	s_add_u32 s4, s44, s4
	s_addc_u32 s5, s45, s5
	s_lshl_b32 s13, s24, 1
	s_add_u32 s4, s4, s13
	v_and_b32_e32 v115, 15, v183
	s_addc_u32 s5, s5, 0
	v_lshrrev_b32_e32 v114, 4, v185
	v_lshlrev_b32_e32 v0, 4, v115
	v_lshl_add_u64 v[2:3], s[4:5], 0, v[0:1]
	v_lshlrev_b32_e32 v0, 14, v114
	v_or_b32_e32 v116, 4, v114
	v_lshl_add_u64 v[110:111], v[2:3], 0, v[0:1]
	v_lshlrev_b32_e32 v0, 14, v116
	v_or_b32_e32 v117, 8, v114
	v_lshl_add_u64 v[112:113], v[2:3], 0, v[0:1]
	v_lshlrev_b32_e32 v0, 14, v117
	v_or_b32_e32 v118, 12, v114
	v_lshl_add_u64 v[96:97], v[2:3], 0, v[0:1]
	v_lshlrev_b32_e32 v0, 14, v118
	v_or_b32_e32 v119, 16, v114
	v_lshl_add_u64 v[94:95], v[2:3], 0, v[0:1]
	v_lshlrev_b32_e32 v0, 14, v119
	v_or_b32_e32 v120, 20, v114
	v_lshl_add_u64 v[92:93], v[2:3], 0, v[0:1]
	v_lshlrev_b32_e32 v0, 14, v120
	v_or_b32_e32 v121, 24, v114
	v_lshl_add_u64 v[90:91], v[2:3], 0, v[0:1]
	v_lshlrev_b32_e32 v0, 14, v121
	v_or_b32_e32 v122, 28, v114
	s_waitcnt lgkmcnt(0)
	v_lshl_add_u64 v[88:89], v[2:3], 0, v[0:1]
	v_lshlrev_b32_e32 v0, 14, v122
	global_load_dwordx4 v[98:101], v[110:111], off
	global_load_dwordx4 v[102:105], v[112:113], off
	global_load_dwordx4 v[106:109], v[96:97], off
	global_load_dwordx4 v[84:87], v[94:95], off
	global_load_dwordx4 v[80:83], v[92:93], off
	global_load_dwordx4 v[10:13], v[90:91], off
	v_lshl_add_u64 v[14:15], v[2:3], 0, v[0:1]
	global_load_dwordx4 v[6:9], v[88:89], off
	global_load_dwordx4 v[2:5], v[14:15], off
	s_barrier
	ds_read_b32 v0, v191
	s_lshl_b32 s4, s12, 14
	s_add_i32 s4, s4, 0
	v_lshl_add_u32 v123, v181, 2, s4
	v_lshl_add_u32 v124, v182, 11, v123
	s_waitcnt lgkmcnt(0)
	v_mul_f32_e32 v48, v48, v0
	v_mul_f32_e32 v64, v64, v0
	v_mul_f32_e32 v16, v16, v0
	v_mul_f32_e32 v0, v32, v0
	ds_write2_b32 v124, v48, v64 offset1:32
	ds_write2_b32 v124, v16, v0 offset0:64 offset1:96
	ds_read_b32 v0, v191 offset:4
	v_lshl_add_u32 v32, v184, 9, v123
	s_add_i32 s8, s8, 1
	s_waitcnt lgkmcnt(0)
	v_mul_f32_e32 v16, v49, v0
	v_mul_f32_e32 v48, v65, v0
	ds_write2_b32 v32, v16, v48 offset0:128 offset1:160
	v_mul_f32_e32 v16, v17, v0
	v_mul_f32_e32 v0, v33, v0
	ds_write2_b32 v32, v16, v0 offset0:192 offset1:224
	ds_read_b32 v0, v191 offset:8
	v_add_u32_e32 v33, 0x400, v32
	s_waitcnt lgkmcnt(0)
	v_mul_f32_e32 v16, v50, v0
	v_mul_f32_e32 v17, v66, v0
	ds_write2_b32 v33, v16, v17 offset1:32
	v_mul_f32_e32 v16, v18, v0
	v_mul_f32_e32 v0, v34, v0
	ds_write2_b32 v33, v16, v0 offset0:64 offset1:96
	ds_read_b32 v0, v191 offset:12
	v_add_u32_e32 v18, 0x1000, v32
	s_waitcnt lgkmcnt(0)
	v_mul_f32_e32 v16, v51, v0
	v_mul_f32_e32 v17, v67, v0
	ds_write2_b32 v33, v16, v17 offset0:128 offset1:160
	v_mul_f32_e32 v16, v19, v0
	v_mul_f32_e32 v0, v35, v0
	ds_write2_b32 v33, v16, v0 offset0:192 offset1:224
	ds_read_b32 v0, v191 offset:32
	s_waitcnt lgkmcnt(0)
	v_mul_f32_e32 v16, v52, v0
	v_mul_f32_e32 v17, v68, v0
	ds_write2_b32 v18, v16, v17 offset1:32
	v_mul_f32_e32 v16, v20, v0
	v_mul_f32_e32 v0, v36, v0
	ds_write2_b32 v18, v16, v0 offset0:64 offset1:96
	ds_read_b32 v0, v191 offset:36
	s_waitcnt lgkmcnt(0)
	v_mul_f32_e32 v16, v53, v0
	v_mul_f32_e32 v17, v69, v0
	ds_write2_b32 v18, v16, v17 offset0:128 offset1:160
	v_mul_f32_e32 v16, v21, v0
	v_mul_f32_e32 v0, v37, v0
	ds_write2_b32 v18, v16, v0 offset0:192 offset1:224
	ds_read_b32 v0, v191 offset:40
	v_add_u32_e32 v18, 0x1400, v32
	s_waitcnt lgkmcnt(0)
	v_mul_f32_e32 v16, v54, v0
	v_mul_f32_e32 v17, v70, v0
	ds_write2_b32 v18, v16, v17 offset1:32
	v_mul_f32_e32 v16, v22, v0
	v_mul_f32_e32 v0, v38, v0
	ds_write2_b32 v18, v16, v0 offset0:64 offset1:96
	ds_read_b32 v0, v191 offset:44
	s_waitcnt lgkmcnt(0)
	v_mul_f32_e32 v16, v55, v0
	v_mul_f32_e32 v17, v71, v0
	ds_write2_b32 v18, v16, v17 offset0:128 offset1:160
	v_mul_f32_e32 v16, v23, v0
	v_mul_f32_e32 v0, v39, v0
	ds_write2_b32 v18, v16, v0 offset0:192 offset1:224
	ds_read_b32 v0, v191 offset:64
	v_add_u32_e32 v18, 0x2000, v32
	s_waitcnt lgkmcnt(0)
	v_mul_f32_e32 v16, v56, v0
	v_mul_f32_e32 v17, v72, v0
	ds_write2_b32 v18, v16, v17 offset1:32
	v_mul_f32_e32 v16, v24, v0
	v_mul_f32_e32 v0, v40, v0
	ds_write2_b32 v18, v16, v0 offset0:64 offset1:96
	ds_read_b32 v0, v191 offset:68
	v_lshl_add_u32 v24, v114, 2, s9
	s_waitcnt lgkmcnt(0)
	v_mul_f32_e32 v16, v57, v0
	v_mul_f32_e32 v17, v73, v0
	ds_write2_b32 v18, v16, v17 offset0:128 offset1:160
	v_mul_f32_e32 v16, v25, v0
	v_mul_f32_e32 v0, v41, v0
	ds_write2_b32 v18, v16, v0 offset0:192 offset1:224
	ds_read_b32 v0, v191 offset:72
	v_add_u32_e32 v18, 0x2400, v32
	s_waitcnt lgkmcnt(0)
	v_mul_f32_e32 v16, v58, v0
	v_mul_f32_e32 v17, v74, v0
	ds_write2_b32 v18, v16, v17 offset1:32
	v_mul_f32_e32 v16, v26, v0
	v_mul_f32_e32 v0, v42, v0
	ds_write2_b32 v18, v16, v0 offset0:64 offset1:96
	ds_read_b32 v0, v191 offset:76
	s_waitcnt vmcnt(7)
	v_lshlrev_b32_e32 v26, 16, v98
	s_waitcnt lgkmcnt(0)
	v_mul_f32_e32 v16, v59, v0
	v_mul_f32_e32 v17, v75, v0
	ds_write2_b32 v18, v16, v17 offset0:128 offset1:160
	v_mul_f32_e32 v16, v27, v0
	v_mul_f32_e32 v0, v43, v0
	ds_write2_b32 v18, v16, v0 offset0:192 offset1:224
	ds_read_b32 v0, v191 offset:96
	v_add_u32_e32 v18, 0x3000, v32
	s_waitcnt lgkmcnt(0)
	v_mul_f32_e32 v16, v60, v0
	v_mul_f32_e32 v17, v76, v0
	ds_write2_b32 v18, v16, v17 offset1:32
	v_mul_f32_e32 v16, v28, v0
	v_mul_f32_e32 v0, v44, v0
	ds_write2_b32 v18, v16, v0 offset0:64 offset1:96
	ds_read_b32 v0, v191 offset:100
	s_waitcnt lgkmcnt(0)
; #define LAS __attribute__((address_space(3)))
; __device__ __forceinline__ unsigned cvt_pk_bf16(float lo, float hi) { unsigned r; asm volatile("v_cvt_pk_bf16_f32 %0, %1, %2" : "=v"(r) : "v"(lo), "v"(hi)); return r; }
; __device__ __forceinline__ float bf_lo(unsigned w) { return __uint_as_float(w << 16); }
; __device__ __forceinline__ float bf_hi(unsigned w) { return __uint_as_float(w & 0xffff0000u); }
; __device__ __forceinline__ int crow(int r, int hi) { return (r & 3) + 8 * (r >> 2) + 4 * hi; }
; template <int WIN, bool ALIBI, int EPI, bool SINK>
; __device__ __forceinline__ void attn_item(const Item& I, char* lds, int tid_in) {
;     ...
; #pragma unroll
;       for (int r = 0; r < 16; ++r) { const int orow = crow(r, hi); const float f = li_l[orow];
; #pragma unroll
;         for (int d0 = 0; d0 < 4; ++d0) { const float v = o[d0][r] * f;
;           if constexpr (EPI == 2) *(LAS float*)(Sw + orow * RB + (d0 * 32 + r32) * 4) = v;
;           else *(LAS bf16_t*)(Sw + orow * RB + (d0 * 32 + r32) * 2) = (bf16_t)(cvt_pk_bf16(v, v) & 0xffffu); } }
;     }
;     asm volatile("s_waitcnt lgkmcnt(0)" ::: "memory");
;     if constexpr (EPI == 2) {
; #pragma unroll
;       for (int j = 0; j < 8; ++j) { const int row = 4 * j + rsub; const float fo = al_l[row];
;         const f32x4 a0 = *(const LAS f32x4*)(Sw + row * RB + ch * 32), a1 = *(const LAS f32x4*)(Sw + row * RB + ch * 32 + 16); const u32x4 ov = oldv[j];
;         u32x4 w; w.x = cvt_pk_bf16(fo * bf_lo(ov.x) + a0[0], fo * bf_hi(ov.x) + a0[1]); w.y = cvt_pk_bf16(fo * bf_lo(ov.y) + a0[2], fo * bf_hi(ov.y) + a0[3]);
;         w.z = cvt_pk_bf16(fo * bf_lo(ov.z) + a1[0], fo * bf_hi(ov.z) + a1[1]); w.w = cvt_pk_bf16(fo * bf_lo(ov.w) + a1[2], fo * bf_hi(ov.w) + a1[3]);
;         STG(u32x4, Orow + (size_t)(I.dil * row) * DM) = w; }
	v_mul_f32_e32 v16, v61, v0
	v_mul_f32_e32 v17, v77, v0
	ds_write2_b32 v18, v16, v17 offset0:128 offset1:160
	v_mul_f32_e32 v16, v29, v0
	v_mul_f32_e32 v0, v45, v0
	ds_write2_b32 v18, v16, v0 offset0:192 offset1:224
	ds_read_b32 v0, v191 offset:104
	v_add_u32_e32 v18, 0x3400, v32
	s_waitcnt lgkmcnt(0)
	v_mul_f32_e32 v16, v62, v0
	v_mul_f32_e32 v17, v78, v0
	ds_write2_b32 v18, v16, v17 offset1:32
	v_mul_f32_e32 v16, v30, v0
	v_mul_f32_e32 v0, v46, v0
	ds_write2_b32 v18, v16, v0 offset0:64 offset1:96
	ds_read_b32 v0, v191 offset:108
	s_waitcnt lgkmcnt(0)
	v_mul_f32_e32 v16, v63, v0
	v_mul_f32_e32 v17, v79, v0
	ds_write2_b32 v18, v16, v17 offset0:128 offset1:160
	v_mul_f32_e32 v16, v31, v0
	v_mul_f32_e32 v0, v47, v0
	ds_write2_b32 v18, v16, v0 offset0:192 offset1:224
	v_lshl_add_u32 v0, v115, 5, s4
	s_waitcnt lgkmcnt(0)
	v_lshl_add_u32 v20, v114, 9, v0
	ds_read_b32 v25, v24 offset:128
	ds_read_b128 v[16:19], v20
	ds_read_b128 v[20:23], v20 offset:16
	s_mul_i32 s4, s8, s6
	s_add_i32 s12, s4, s7
	s_cmpk_lt_i32 s12, 0xa00
	s_waitcnt lgkmcnt(1)
	v_fma_f32 v16, v25, v26, v16
	v_and_b32_e32 v26, 0xffff0000, v98
	v_fma_f32 v17, v25, v26, v17
	v_cvt_pk_bf16_f32 v16, v16, v17
	v_lshlrev_b32_e32 v17, 16, v99
	v_fma_f32 v17, v25, v17, v18
	v_and_b32_e32 v18, 0xffff0000, v99
	v_fmac_f32_e32 v19, v25, v18
	v_cvt_pk_bf16_f32 v17, v17, v19
	v_lshlrev_b32_e32 v18, 16, v100
	v_and_b32_e32 v19, 0xffff0000, v100
	s_waitcnt lgkmcnt(0)
	v_fma_f32 v18, v25, v18, v20
	v_fma_f32 v19, v25, v19, v21
	v_cvt_pk_bf16_f32 v18, v18, v19
	v_lshlrev_b32_e32 v19, 16, v101
	v_and_b32_e32 v20, 0xffff0000, v101
	v_fma_f32 v19, v25, v19, v22
	v_fmac_f32_e32 v23, v25, v20
	v_cvt_pk_bf16_f32 v19, v19, v23
	v_lshl_add_u32 v25, v116, 9, v0
	ds_read_b32 v26, v24 offset:144
	ds_read_b128 v[20:23], v25
	global_store_dwordx4 v[110:111], v[16:19], off
	ds_read_b128 v[16:19], v25 offset:16
	s_waitcnt vmcnt(7)
	v_lshlrev_b32_e32 v25, 16, v102
	s_waitcnt lgkmcnt(1)
	v_fma_f32 v20, v26, v25, v20
	v_and_b32_e32 v25, 0xffff0000, v102
	v_fma_f32 v21, v26, v25, v21
	v_cvt_pk_bf16_f32 v20, v20, v21
	v_lshlrev_b32_e32 v21, 16, v103
	v_fma_f32 v21, v26, v21, v22
	v_and_b32_e32 v22, 0xffff0000, v103
	v_fmac_f32_e32 v23, v26, v22
	v_lshlrev_b32_e32 v22, 16, v104
	s_waitcnt lgkmcnt(0)
	v_fma_f32 v16, v26, v22, v16
	v_and_b32_e32 v22, 0xffff0000, v104
	v_fma_f32 v17, v26, v22, v17
	v_cvt_pk_bf16_f32 v21, v21, v23
	v_cvt_pk_bf16_f32 v22, v16, v17
	v_lshlrev_b32_e32 v16, 16, v105
	v_and_b32_e32 v17, 0xffff0000, v105
	v_fma_f32 v16, v26, v16, v18
	v_fmac_f32_e32 v19, v26, v17
	v_cvt_pk_bf16_f32 v23, v16, v19
	v_lshl_add_u32 v25, v117, 9, v0
	ds_read_b32 v26, v24 offset:160
	ds_read_b128 v[16:19], v25
	global_store_dwordx4 v[112:113], v[20:23], off
	ds_read_b128 v[20:23], v25 offset:16
	s_waitcnt vmcnt(7)
	v_lshlrev_b32_e32 v25, 16, v106
	s_waitcnt lgkmcnt(1)
	v_fma_f32 v16, v26, v25, v16
	v_and_b32_e32 v25, 0xffff0000, v106
	v_fma_f32 v17, v26, v25, v17
	v_cvt_pk_bf16_f32 v16, v16, v17
	v_lshlrev_b32_e32 v17, 16, v107
	v_fma_f32 v17, v26, v17, v18
	v_and_b32_e32 v18, 0xffff0000, v107
	v_fmac_f32_e32 v19, v26, v18
	v_cvt_pk_bf16_f32 v17, v17, v19
	v_lshlrev_b32_e32 v18, 16, v108
	v_and_b32_e32 v19, 0xffff0000, v108
	s_waitcnt lgkmcnt(0)
	v_fma_f32 v18, v26, v18, v20
	v_fma_f32 v19, v26, v19, v21
	v_cvt_pk_bf16_f32 v18, v18, v19
	v_lshlrev_b32_e32 v19, 16, v109
	v_and_b32_e32 v20, 0xffff0000, v109
	v_fma_f32 v19, v26, v19, v22
	v_fmac_f32_e32 v23, v26, v20
	v_cvt_pk_bf16_f32 v19, v19, v23
	v_lshl_add_u32 v25, v118, 9, v0
	ds_read_b32 v26, v24 offset:176
	ds_read_b128 v[20:23], v25
	global_store_dwordx4 v[96:97], v[16:19], off
	ds_read_b128 v[16:19], v25 offset:16
	s_waitcnt vmcnt(7)
	v_lshlrev_b32_e32 v25, 16, v84
	s_waitcnt lgkmcnt(1)
	v_fma_f32 v20, v26, v25, v20
	v_and_b32_e32 v25, 0xffff0000, v84
	v_fma_f32 v21, v26, v25, v21
	v_cvt_pk_bf16_f32 v20, v20, v21
	v_lshlrev_b32_e32 v21, 16, v85
	v_fma_f32 v21, v26, v21, v22
	v_and_b32_e32 v22, 0xffff0000, v85
	v_fmac_f32_e32 v23, v26, v22
	v_lshlrev_b32_e32 v22, 16, v86
	s_waitcnt lgkmcnt(0)
; #define LAS __attribute__((address_space(3)))
; __device__ __forceinline__ unsigned cvt_pk_bf16(float lo, float hi) { unsigned r; asm volatile("v_cvt_pk_bf16_f32 %0, %1, %2" : "=v"(r) : "v"(lo), "v"(hi)); return r; }
; __device__ __forceinline__ float bf_lo(unsigned w) { return __uint_as_float(w << 16); }
; __device__ __forceinline__ float bf_hi(unsigned w) { return __uint_as_float(w & 0xffff0000u); }
; template <int WIN, bool ALIBI, int EPI, bool SINK>
; __device__ __forceinline__ void attn_item(const Item& I, char* lds, int tid_in) {
;     ...
;     if constexpr (EPI == 2) {
; #pragma unroll
;       for (int j = 0; j < 8; ++j) { const int row = 4 * j + rsub; const float fo = al_l[row];
;         const f32x4 a0 = *(const LAS f32x4*)(Sw + row * RB + ch * 32), a1 = *(const LAS f32x4*)(Sw + row * RB + ch * 32 + 16); const u32x4 ov = oldv[j];
;         u32x4 w; w.x = cvt_pk_bf16(fo * bf_lo(ov.x) + a0[0], fo * bf_hi(ov.x) + a0[1]); w.y = cvt_pk_bf16(fo * bf_lo(ov.y) + a0[2], fo * bf_hi(ov.y) + a0[3]);
;         w.z = cvt_pk_bf16(fo * bf_lo(ov.z) + a1[0], fo * bf_hi(ov.z) + a1[1]); w.w = cvt_pk_bf16(fo * bf_lo(ov.w) + a1[2], fo * bf_hi(ov.w) + a1[3]);
;         STG(u32x4, Orow + (size_t)(I.dil * row) * DM) = w; }
;     } else {
; #pragma unroll
;       for (int j = 0; j < 8; ++j) { const int row = 4 * j + rsub; const u32x4 w = *(const LAS u32x4*)(Sw + row * RB + ch * 16);
;         STG(u32x4, Orow + (size_t)(I.dil * row) * DM) = w; }
;     }
;   }
;   __syncthreads();
	v_fma_f32 v16, v26, v22, v16
	v_and_b32_e32 v22, 0xffff0000, v86
	v_fma_f32 v17, v26, v22, v17
	v_cvt_pk_bf16_f32 v21, v21, v23
	v_cvt_pk_bf16_f32 v22, v16, v17
	v_lshlrev_b32_e32 v16, 16, v87
	v_and_b32_e32 v17, 0xffff0000, v87
	v_fma_f32 v16, v26, v16, v18
	v_fmac_f32_e32 v19, v26, v17
	v_cvt_pk_bf16_f32 v23, v16, v19
	v_lshl_add_u32 v25, v119, 9, v0
	ds_read_b32 v26, v24 offset:192
	ds_read_b128 v[16:19], v25
	global_store_dwordx4 v[94:95], v[20:23], off
	ds_read_b128 v[20:23], v25 offset:16
	s_waitcnt vmcnt(7)
	v_lshlrev_b32_e32 v25, 16, v80
	s_waitcnt lgkmcnt(1)
	v_fma_f32 v16, v26, v25, v16
	v_and_b32_e32 v25, 0xffff0000, v80
	v_fma_f32 v17, v26, v25, v17
	v_cvt_pk_bf16_f32 v16, v16, v17
	v_lshlrev_b32_e32 v17, 16, v81
	v_fma_f32 v17, v26, v17, v18
	v_and_b32_e32 v18, 0xffff0000, v81
	v_fmac_f32_e32 v19, v26, v18
	v_cvt_pk_bf16_f32 v17, v17, v19
	v_lshlrev_b32_e32 v18, 16, v82
	v_and_b32_e32 v19, 0xffff0000, v82
	s_waitcnt lgkmcnt(0)
	v_fma_f32 v18, v26, v18, v20
	v_fma_f32 v19, v26, v19, v21
	v_cvt_pk_bf16_f32 v18, v18, v19
	v_lshlrev_b32_e32 v19, 16, v83
	v_and_b32_e32 v20, 0xffff0000, v83
	v_fma_f32 v19, v26, v19, v22
	v_fmac_f32_e32 v23, v26, v20
	v_cvt_pk_bf16_f32 v19, v19, v23
	v_lshl_add_u32 v25, v120, 9, v0
	ds_read_b32 v26, v24 offset:208
	ds_read_b128 v[20:23], v25
	global_store_dwordx4 v[92:93], v[16:19], off
	ds_read_b128 v[16:19], v25 offset:16
	s_waitcnt vmcnt(7)
	v_lshlrev_b32_e32 v25, 16, v10
	v_and_b32_e32 v10, 0xffff0000, v10
	s_waitcnt lgkmcnt(1)
	v_fma_f32 v20, v26, v25, v20
	v_fma_f32 v10, v26, v10, v21
	v_cvt_pk_bf16_f32 v10, v20, v10
	v_lshlrev_b32_e32 v20, 16, v11
	v_fma_f32 v20, v26, v20, v22
	v_and_b32_e32 v11, 0xffff0000, v11
	v_fmac_f32_e32 v23, v26, v11
	v_cvt_pk_bf16_f32 v11, v20, v23
	v_lshlrev_b32_e32 v20, 16, v12
	v_and_b32_e32 v12, 0xffff0000, v12
	s_waitcnt lgkmcnt(0)
	v_fma_f32 v16, v26, v20, v16
	v_fma_f32 v12, v26, v12, v17
	v_cvt_pk_bf16_f32 v12, v16, v12
	v_lshlrev_b32_e32 v16, 16, v13
	v_and_b32_e32 v13, 0xffff0000, v13
	v_fma_f32 v16, v26, v16, v18
	v_fmac_f32_e32 v19, v26, v13
	v_cvt_pk_bf16_f32 v13, v16, v19
	v_lshl_add_u32 v20, v121, 9, v0
	ds_read_b32 v21, v24 offset:224
	ds_read_b128 v[16:19], v20
	global_store_dwordx4 v[90:91], v[10:13], off
	ds_read_b128 v[10:13], v20 offset:16
	s_waitcnt vmcnt(7)
	v_lshlrev_b32_e32 v20, 16, v6
	v_and_b32_e32 v6, 0xffff0000, v6
	s_waitcnt lgkmcnt(1)
	v_fma_f32 v16, v21, v20, v16
	v_fma_f32 v6, v21, v6, v17
	v_cvt_pk_bf16_f32 v6, v16, v6
	v_lshlrev_b32_e32 v16, 16, v7
	v_fma_f32 v16, v21, v16, v18
	v_and_b32_e32 v7, 0xffff0000, v7
	v_fmac_f32_e32 v19, v21, v7
	v_cvt_pk_bf16_f32 v7, v16, v19
	v_lshlrev_b32_e32 v16, 16, v8
	v_and_b32_e32 v8, 0xffff0000, v8
	s_waitcnt lgkmcnt(0)
	v_fma_f32 v10, v21, v16, v10
	v_fma_f32 v8, v21, v8, v11
	v_cvt_pk_bf16_f32 v8, v10, v8
	v_lshlrev_b32_e32 v10, 16, v9
	v_and_b32_e32 v9, 0xffff0000, v9
	v_fma_f32 v10, v21, v10, v12
	v_fmac_f32_e32 v13, v21, v9
	v_cvt_pk_bf16_f32 v9, v10, v13
	v_lshl_add_u32 v0, v122, 9, v0
	ds_read_b32 v16, v24 offset:240
	ds_read_b128 v[10:13], v0
	global_store_dwordx4 v[88:89], v[6:9], off
	ds_read_b128 v[6:9], v0 offset:16
	s_waitcnt vmcnt(7)
	v_lshlrev_b32_e32 v0, 16, v2
	v_and_b32_e32 v2, 0xffff0000, v2
	s_waitcnt lgkmcnt(1)
	v_fma_f32 v0, v16, v0, v10
	v_fma_f32 v2, v16, v2, v11
	v_cvt_pk_bf16_f32 v2, v0, v2
	v_lshlrev_b32_e32 v0, 16, v3
	v_fma_f32 v0, v16, v0, v12
	v_and_b32_e32 v3, 0xffff0000, v3
	v_fmac_f32_e32 v13, v16, v3
	v_cvt_pk_bf16_f32 v3, v0, v13
	v_lshlrev_b32_e32 v0, 16, v4
	v_and_b32_e32 v4, 0xffff0000, v4
	s_waitcnt lgkmcnt(0)
	v_fma_f32 v0, v16, v0, v6
	v_fma_f32 v4, v16, v4, v7
	v_cvt_pk_bf16_f32 v4, v0, v4
	v_lshlrev_b32_e32 v0, 16, v5
	v_and_b32_e32 v5, 0xffff0000, v5
	v_fma_f32 v0, v16, v0, v8
	v_fmac_f32_e32 v9, v16, v5
	v_cvt_pk_bf16_f32 v5, v0, v9
	global_store_dwordx4 v[14:15], v[2:5], off
	s_barrier
	s_cbranch_scc0 .LBB0_602

; #define LAS __attribute__((address_space(3)))
; __device__ __forceinline__ int v_rd_base(int lane) { return ((lane & 3) << 3) | (((lane >> 2) & 3) << 6) | (((lane >> 4) & 1) << 5) | (((lane >> 5) & 1) << 8); }
; template <int WIN, bool ALIBI, int EPI, bool SINK>
; __device__ __forceinline__ void attn_item(const Item& I, char* lds, int tid_in) {
;     ...
;   const int hh = wid >> 2, tl = tid & 255, sr4 = tl >> 4, sc4 = (tl & 15) * 8;
;   LAS char* Vh = V_lds + hh * (2 * (SHM_V + SHM_K)); LAS char* Kh = Vh + 2 * SHM_V;
;   const int vbh = (int)(unsigned)(uintptr_t)Vh + v_rd_base(lane);
;   const int clsw = I.c0 + wcls, NTw = two ? 2 : (128 + 2 * WIN) / 64, ukbw = two ? 0 : I.u0 + 128 * hh - WIN;
;   bf16x8 stv[4], stk[4];
; template <int MODE> __device__ __forceinline__ void phase_attn_fast(const Frame& F0) {
;     ...
;       if (MODE == 5 || MODE == 6) { const int dil = (MODE == 5) ? 4 : 16; I.dil = dil; I.SU = d.S / dil; I.nslope = -slope2 * (float)dil;
;         const int nqc = I.SU / 256;
;         if (nqc == 0) { I.two = 1; I.c0 = 2 * d.qb; I.u0 = 0; I.ukb0 = 0; I.NT = 4; }
;         else { I.c0 = d.qb / nqc; I.u0 = 256 * (d.qb % nqc); I.ukb0 = I.u0 - 64; I.NT = 6; }
.LBB0_589:
	s_or_b64 exec, exec, s[4:5]
	s_lshl_b32 s4, s26, 5
	s_and_b32 s4, s4, 0x180
	s_or_b32 s27, s4, 0x800
	s_or_b32 s28, s4, 0xa00
	s_add_i32 s4, s26, 1
	v_cvt_f32_ubyte0_e32 v3, s4
	v_mul_f32_e32 v4, -0.5, v3
	s_mov_b32 s4, 0xc2fc0000
	v_cmp_gt_f32_e32 vcc, s4, v4
	s_and_b64 s[4:5], vcc, exec
	s_cselect_b32 s4, 0xffffffc0, 0
	v_cndmask_b32_e32 v4, 0, v230, vcc
	v_fmac_f32_e32 v4, -0.5, v3
	v_exp_f32_e32 v3, v4
	s_lshr_b32 s50, s9, 2
	v_lshlrev_b32_e32 v184, 2, v182
	v_lshlrev_b32_e32 v39, 3, v183
	v_ldexp_f32 v3, v3, s4
	s_and_b32 s4, s25, 0x3fffffc0
	v_mul_f32_e32 v3, 0xbfb8aa3b, v3
	s_lshl_b32 s4, s4, 2
	v_mul_f32_e32 v187, 4.0, v3
	s_add_i32 s9, s4, 0
	s_ashr_i32 s4, s25, 8
	v_sub_u32_e32 v3, 0, v2
	v_max_i32_e32 v36, 0xffffffc0, v3
	v_xad_u32 v3, v2, -1, s50
	s_lshl_b32 s5, s4, 16
	s_lshl_b32 s4, s4, 7
	s_add_i32 s25, s29, s49
	v_min_i32_e32 v37, 64, v3
	v_sub_u32_e32 v38, v184, v2
	v_and_b32_e32 v2, 0x78, v39
	v_lshlrev_b32_e32 v3, 4, v185
	s_add_i32 s49, s49, s4
	v_lshlrev_b32_e32 v34, 1, v2
	v_lshlrev_b32_e32 v2, 3, v185
	v_and_b32_e32 v3, 0xc0, v3
	v_lshlrev_b32_e32 v4, 1, v185
	v_bfe_u32 v41, v183, 4, 4
	s_sub_i32 s4, s49, 64
	v_and_or_b32 v3, v2, 24, v3
	v_and_b32_e32 v4, 32, v4
	v_and_b32_e32 v2, 0x100, v2
	v_or_b32_e32 v43, s4, v41
	v_or3_b32 v42, v3, v4, v2
	s_add_i32 s50, s50, -1
	v_max_i32_e32 v2, 0, v43
	v_mov_b32_e32 v35, v1
	v_min_u32_e32 v2, s50, v2
	v_lshl_add_u64 v[178:179], s[40:41], 0, v[34:35]
	v_lshl_add_u32 v2, v2, 2, s13
	s_add_i32 s29, s5, 0
	v_mad_i64_i32 v[6:7], s[4:5], v2, s89, v[178:179]
	s_lshl_b32 s72, s28, 1
	v_lshl_add_u64 v[2:3], v[6:7], 0, s[72:73]
	global_load_dwordx4 v[2:5], v[2:3], off
	v_max_i32_e32 v10, -16, v43
	v_add_u32_e32 v10, 16, v10
	v_min_u32_e32 v10, s50, v10
	v_max_i32_e32 v18, 0xffffffe0, v43
	s_lshl_b32 s4, s27, 1
	s_mov_b32 s5, s73
	v_lshl_add_u32 v10, v10, 2, s13
	v_add_u32_e32 v18, 32, v18
	v_lshl_add_u64 v[6:7], v[6:7], 0, s[4:5]
	v_mad_i64_i32 v[14:15], s[30:31], v10, s89, v[178:179]
	v_min_u32_e32 v18, s50, v18
	v_max_i32_e32 v26, 0xffffffd0, v43
	global_load_dwordx4 v[6:9], v[6:7], off
	v_lshl_add_u64 v[10:11], v[14:15], 0, s[72:73]
	v_lshl_add_u32 v18, v18, 2, s13
	v_add_u32_e32 v26, 48, v26
	global_load_dwordx4 v[10:13], v[10:11], off
	v_lshl_add_u64 v[14:15], v[14:15], 0, s[4:5]
	v_mad_i64_i32 v[22:23], s[30:31], v18, s89, v[178:179]
	v_min_u32_e32 v26, s50, v26
	global_load_dwordx4 v[14:17], v[14:15], off
	v_lshl_add_u64 v[18:19], v[22:23], 0, s[72:73]
	v_lshl_add_u32 v26, v26, 2, s13
	global_load_dwordx4 v[18:21], v[18:19], off
	v_lshl_add_u64 v[22:23], v[22:23], 0, s[4:5]
	v_mad_i64_i32 v[30:31], s[30:31], v26, s89, v[178:179]
	global_load_dwordx4 v[22:25], v[22:23], off
	v_lshl_add_u64 v[26:27], v[30:31], 0, s[72:73]
	global_load_dwordx4 v[26:29], v[26:27], off
	v_lshl_add_u64 v[30:31], v[30:31], 0, s[4:5]
	global_load_dwordx4 v[30:33], v[30:31], off
	v_lshrrev_b32_e32 v40, 4, v183
	v_bfe_u32 v35, v39, 5, 2
	v_add_u32_e32 v190, s29, v42
	v_lshrrev_b32_e32 v39, 5, v183
	v_bfe_u32 v42, v183, 4, 2
	v_and_or_b32 v39, v39, 4, v42
	v_and_or_b32 v35, v40, 4, v35
	v_cvt_f32_i32_e32 v189, v37
	v_and_b32_e32 v37, 48, v34
	v_lshl_add_u32 v39, v39, 6, s29
	v_lshlrev_b32_e32 v35, 9, v35
	s_movk_i32 s34, 0x70
	v_add3_u32 v192, v39, v37, v35
	s_waitcnt vmcnt(0)
; #define WSLOAD(n) do { _Pragma("unroll") for (int i_ = 0; i_ < 4; ++i_) { int u_ = WUKB(n) + sr4 + 16 * i_; u_ = min(max(u_, 0), I.SU - 1); \
;       const bf16_t* rp_ = I.qkv + (size_t)(I.seq_base + clsw + I.dil * u_) * I.W + sc4; stv[i_] = LDG(bf16x8, rp_ + I.vcol); stk[i_] = LDG(bf16x8, rp_ + I.kcol); } } while (0)
; #define WSWRITE(b) do { _Pragma("unroll") for (int i_ = 0; i_ < 4; ++i_) { *(LAS bf16x8*)(Vh + (b) * SHM_V + v_st(sr4 + 16 * i_, sc4)) = stv[i_]; \
;       *(LAS bf16x8*)(Kh + (b) * SHM_K + KSWZ(sr4 + 16 * i_, sc4 * 2)) = stk[i_]; } } while (0)
; template <int WIN, bool ALIBI, int EPI, bool SINK>
; __device__ __forceinline__ void attn_item(const Item& I, char* lds, int tid_in) {
;     ...
;   bf16x8 stv[4], stk[4];
;     ...
;   WSLOAD(0); asm volatile("s_waitcnt vmcnt(0)" ::: "memory"); WSWRITE(0); if (1 < NTw) WSLOAD(1); __syncthreads();
	v_bitop3_b32 v34, v34, v183, s34 bitop3:0x78
	v_cvt_f32_i32_e32 v194, v38
	v_cvt_f32_i32_e32 v196, v36
	s_add_i32 s9, s9, 0x20000
	v_add_u32_e32 v191, s9, v0
	v_add3_u32 v207, s49, 64, v41
	s_mov_b32 s48, 0
	s_sub_i32 s51, s25, 64
	s_add_i32 s52, s25, 0x5f
	v_lshl_add_u32 v197, v181, 8, s29
	v_lshl_add_u32 v195, v181, 2, s9
	v_mov_b32_e32 v205, 0xf149f2ca
	s_lshl_b32 s46, s27, 1
	s_mov_b32 s53, 0
	ds_write_b128 v192, v[2:5]
	v_lshlrev_b32_e32 v2, 8, v41
	v_add3_u32 v193, s29, v34, v2
	v_max_i32_e32 v2, 0xffffffc0, v43
	v_add_u32_e32 v2, 64, v2
	v_min_u32_e32 v2, s50, v2
	v_lshl_add_u32 v2, v2, 2, s13
	v_mad_i64_i32 v[2:3], s[30:31], v2, s89, v[178:179]
	ds_write_b128 v193, v[6:9] offset:32768
	ds_write_b128 v192, v[10:13] offset:4096
	ds_write_b128 v193, v[14:17] offset:36864
	ds_write_b128 v192, v[18:21] offset:8192
	ds_write_b128 v193, v[22:25] offset:40960
	ds_write_b128 v192, v[26:29] offset:12288
	ds_write_b128 v193, v[30:33] offset:45056
	v_lshl_add_u64 v[4:5], v[2:3], 0, s[72:73]
	v_lshl_add_u64 v[2:3], v[2:3], 0, s[4:5]
	global_load_dwordx4 v[144:147], v[4:5], off
	global_load_dwordx4 v[148:151], v[2:3], off
	v_max_i32_e32 v2, 0xffffffb0, v43
	v_add_u32_e32 v2, 0x50, v2
	v_min_u32_e32 v2, s50, v2
	v_lshl_add_u32 v2, v2, 2, s13
	v_mad_i64_i32 v[2:3], s[30:31], v2, s89, v[178:179]
	v_lshl_add_u64 v[4:5], v[2:3], 0, s[72:73]
	v_lshl_add_u64 v[2:3], v[2:3], 0, s[4:5]
	global_load_dwordx4 v[152:155], v[4:5], off
	global_load_dwordx4 v[156:159], v[2:3], off
	v_max_i32_e32 v2, 0xffffffa0, v43
	v_add_u32_e32 v2, 0x60, v2
	v_min_u32_e32 v2, s50, v2
	v_lshl_add_u32 v2, v2, 2, s13
	v_mad_i64_i32 v[2:3], s[30:31], v2, s89, v[178:179]
	v_lshl_add_u64 v[4:5], v[2:3], 0, s[72:73]
	v_lshl_add_u64 v[2:3], v[2:3], 0, s[4:5]
	global_load_dwordx4 v[160:163], v[4:5], off
	global_load_dwordx4 v[164:167], v[2:3], off
	v_max_i32_e32 v2, 0xffffff90, v43
	v_add_u32_e32 v2, 0x70, v2
	v_min_u32_e32 v2, s50, v2
	v_lshl_add_u32 v2, v2, 2, s13
	v_mad_i64_i32 v[2:3], s[30:31], v2, s89, v[178:179]
	v_lshl_add_u64 v[4:5], v[2:3], 0, s[72:73]
	v_lshl_add_u64 v[2:3], v[2:3], 0, s[4:5]
	global_load_dwordx4 v[168:171], v[4:5], off
	global_load_dwordx4 v[172:175], v[2:3], off
	v_lshlrev_b32_e32 v2, 4, v181
	v_and_b32_e32 v3, 0x70, v2
	s_movk_i32 s4, 0xe0
	v_mov_b32_e32 v14, v1
	v_mov_b32_e32 v15, v1
	v_bitop3_b32 v198, v0, v2, s34 bitop3:0x78
	v_bitop3_b32 v199, v0, v3, 32 bitop3:0x36
	v_bitop3_b32 v200, v0, v3, 64 bitop3:0x36
	v_bitop3_b32 v201, v0, v3, s93 bitop3:0x36
	v_bitop3_b32 v202, v0, v3, s85 bitop3:0x36
	v_bitop3_b32 v203, v0, v3, s67 bitop3:0x36
	v_bitop3_b32 v204, v0, v3, s83 bitop3:0x36
	v_bitop3_b32 v206, v0, v3, s4 bitop3:0x36
	v_mov_b32_e32 v0, v1
	v_mov_b32_e32 v2, v1
	v_mov_b32_e32 v3, v1
	v_mov_b32_e32 v4, v1
	v_mov_b32_e32 v5, v1
	v_mov_b32_e32 v6, v1
	v_mov_b32_e32 v7, v1
	v_mov_b32_e32 v8, v1
	v_mov_b32_e32 v9, v1
	v_mov_b32_e32 v10, v1
	v_mov_b32_e32 v11, v1
	v_mov_b32_e32 v12, v1
	v_mov_b32_e32 v13, v1
	v_mov_b64_e32 v[62:63], v[14:15]
	v_mov_b64_e32 v[78:79], v[14:15]
	v_mov_b64_e32 v[30:31], v[14:15]
	v_mov_b64_e32 v[46:47], v[14:15]
	s_lshl_b32 s72, s28, 1
	v_mov_b64_e32 v[60:61], v[12:13]
	v_mov_b64_e32 v[58:59], v[10:11]
	v_mov_b64_e32 v[56:57], v[8:9]
	v_mov_b64_e32 v[54:55], v[6:7]
	v_mov_b64_e32 v[52:53], v[4:5]
	v_mov_b64_e32 v[50:51], v[2:3]
	v_mov_b64_e32 v[48:49], v[0:1]
	v_mov_b64_e32 v[76:77], v[12:13]
	v_mov_b64_e32 v[74:75], v[10:11]
	v_mov_b64_e32 v[72:73], v[8:9]
	v_mov_b64_e32 v[70:71], v[6:7]
	v_mov_b64_e32 v[68:69], v[4:5]
	v_mov_b64_e32 v[66:67], v[2:3]
	v_mov_b64_e32 v[64:65], v[0:1]
	v_mov_b64_e32 v[28:29], v[12:13]
	v_mov_b64_e32 v[26:27], v[10:11]
	v_mov_b64_e32 v[24:25], v[8:9]
	v_mov_b64_e32 v[22:23], v[6:7]
	v_mov_b64_e32 v[20:21], v[4:5]
	v_mov_b64_e32 v[18:19], v[2:3]
	v_mov_b64_e32 v[16:17], v[0:1]
	v_mov_b64_e32 v[44:45], v[12:13]
	v_mov_b64_e32 v[42:43], v[10:11]
	v_mov_b64_e32 v[40:41], v[8:9]
	v_mov_b64_e32 v[38:39], v[6:7]
	v_mov_b64_e32 v[36:37], v[4:5]
	v_mov_b64_e32 v[34:35], v[2:3]
	v_mov_b64_e32 v[32:33], v[0:1]
	s_waitcnt lgkmcnt(0)
	s_barrier
	s_branch .LBB0_591

; #define SBAR() __builtin_amdgcn_sched_barrier(0)
; #define RESC(a) do { if (__any((a) < 1.f)) { if (hi == 0) al_l[r32] = (a); asm volatile("s_waitcnt lgkmcnt(0)" ::: "memory"); \
;     _Pragma("unroll") for (int d = 0; d < 4; ++d) _Pragma("unroll") for (int r = 0; r < 16; ++r) o[d][r] *= al_l[crow(r, hi)]; } } while (0)
; #define WACT(n) (WUKB(n) + 63 >= uqw - WIN && WUKB(n) <= uqw + 31 + WIN)
; #define WSLOAD(n) do { _Pragma("unroll") for (int i_ = 0; i_ < 4; ++i_) { int u_ = WUKB(n) + sr4 + 16 * i_; u_ = min(max(u_, 0), I.SU - 1); \
;       const bf16_t* rp_ = I.qkv + (size_t)(I.seq_base + clsw + I.dil * u_) * I.W + sc4; stv[i_] = LDG(bf16x8, rp_ + I.vcol); stk[i_] = LDG(bf16x8, rp_ + I.kcol); } } while (0)
; #define WSWRITE(b) do { _Pragma("unroll") for (int i_ = 0; i_ < 4; ++i_) { *(LAS bf16x8*)(Vh + (b) * SHM_V + v_st(sr4 + 16 * i_, sc4)) = stv[i_]; \
;       *(LAS bf16x8*)(Kh + (b) * SHM_K + KSWZ(sr4 + 16 * i_, sc4 * 2)) = stk[i_]; } } while (0)
; template <int WIN, bool ALIBI, int EPI, bool SINK>
; __device__ __forceinline__ void attn_item(const Item& I, char* lds, int tid_in) {
;     ...
;   for (int n = 0; n < NTw; ++n) { const int bsel = n & 1;
;     if (WACT(n)) { qkt(pA0, pA1, Kh + bsel * SHM_K, qr, r32, hi);
;       partialSM<WIN, ALIBI>(pA0, pA1, m_reg, mnA, alA, dq + (float)WUKB(n), I.nslope, lo, hi_, true); RESC(alA);
;       finishSM(pA0, pA1, alA, l_reg, pa0, pa1, pa2, pa3); SBAR(); pv_d0(o, vbh + bsel * SHM_V, pa0, pa1, pa2, pa3); }
;     if (n + 1 < NTw) { asm volatile("s_waitcnt vmcnt(0)" ::: "memory"); WSWRITE(bsel ^ 1); if (n + 2 < NTw) WSLOAD(n + 2); }
;     __syncthreads();
.LBB0_597:
	s_cmp_gt_u32 s53, 2
	s_cbranch_scc1 .LBB0_590
	s_waitcnt vmcnt(0)
	s_lshl_b32 s4, s27, 14
	s_xor_b32 s4, s4, 0x4000
	v_add_u32_e32 v0, s4, v192
	v_add_u32_e32 v2, s4, v193
	s_cmpk_eq_i32 s48, 0x80
	ds_write_b128 v0, v[144:147]
	ds_write_b128 v2, v[148:151] offset:32768
	ds_write_b128 v0, v[152:155] offset:4096
	ds_write_b128 v2, v[156:159] offset:36864
	ds_write_b128 v0, v[160:163] offset:8192
	ds_write_b128 v2, v[164:167] offset:40960
	ds_write_b128 v0, v[168:171] offset:12288
	ds_write_b128 v2, v[172:175] offset:45056
	s_cbranch_scc1 .LBB0_590
	v_add_u32_e32 v0, s48, v207
	v_max_i32_e32 v2, 0, v0
	v_min_i32_e32 v2, s50, v2
	v_lshl_add_u32 v2, v2, 2, s13
	v_mad_i64_i32 v[2:3], s[4:5], v2, s89, v[178:179]
	s_mov_b32 s47, s73
	v_lshl_add_u64 v[4:5], v[2:3], 0, s[72:73]
	v_lshl_add_u64 v[2:3], v[2:3], 0, s[46:47]
	global_load_dwordx4 v[144:147], v[4:5], off
	global_load_dwordx4 v[148:151], v[2:3], off
	v_max_i32_e32 v2, -16, v0
	v_add_u32_e32 v2, 16, v2
	v_min_i32_e32 v2, s50, v2
	v_lshl_add_u32 v2, v2, 2, s13
	v_mad_i64_i32 v[2:3], s[4:5], v2, s89, v[178:179]
	v_lshl_add_u64 v[4:5], v[2:3], 0, s[72:73]
	v_lshl_add_u64 v[2:3], v[2:3], 0, s[46:47]
	global_load_dwordx4 v[152:155], v[4:5], off
	global_load_dwordx4 v[156:159], v[2:3], off
	v_max_i32_e32 v2, 0xffffffe0, v0
	v_add_u32_e32 v2, 32, v2
	v_min_i32_e32 v2, s50, v2
	v_max_i32_e32 v0, 0xffffffd0, v0
	v_lshl_add_u32 v2, v2, 2, s13
	v_add_u32_e32 v0, 48, v0
	v_mad_i64_i32 v[2:3], s[4:5], v2, s89, v[178:179]
	v_min_i32_e32 v0, s50, v0
	v_lshl_add_u64 v[4:5], v[2:3], 0, s[72:73]
	v_lshl_add_u64 v[2:3], v[2:3], 0, s[46:47]
	v_lshl_add_u32 v0, v0, 2, s13
	global_load_dwordx4 v[160:163], v[4:5], off
	global_load_dwordx4 v[164:167], v[2:3], off
	v_mad_i64_i32 v[2:3], s[4:5], v0, s89, v[178:179]
	v_lshl_add_u64 v[4:5], v[2:3], 0, s[72:73]
	v_lshl_add_u64 v[2:3], v[2:3], 0, s[46:47]
	global_load_dwordx4 v[168:171], v[4:5], off
	global_load_dwordx4 v[172:175], v[2:3], off
	s_branch .LBB0_590

; __device__ __forceinline__ unsigned xb_ld(unsigned* p)              { return __hip_atomic_load(p, __ATOMIC_RELAXED, __HIP_MEMORY_SCOPE_AGENT); }
; __device__ __forceinline__ unsigned xb_add(unsigned* p, unsigned v) { return __hip_atomic_fetch_add(p, v, __ATOMIC_RELAXED, __HIP_MEMORY_SCOPE_AGENT); }
; #define XB_SPIN(cond, bar) do { unsigned _sp = 0; while (cond) { __builtin_amdgcn_s_sleep(1); \
;     if ((++_sp & 255u) == 0u) { if (xb_ld(&(bar)[XB_TMO])) break; if (_sp > XB_SPIN_CAP) { atomicAdd(&(bar)[XB_TMO], 1u); break; } } } } while (0)
; __device__ __forceinline__ void xcd_barrier(const XcdBarrier& b) {
;     ...
;             __builtin_amdgcn_fence(__ATOMIC_RELEASE, "agent");
;             asm volatile("s_waitcnt vmcnt(0)" ::: "memory");
;             const unsigned og = xb_add(&bar[XB_TOP], 1u);
;             const unsigned tg = og / nx;
;             if (og + 1u == (tg + 1u) * nx) xb_add(&bar[XB_TOPGEN], 1u);
;             else XB_SPIN(xb_ld(&bar[XB_TOPGEN]) == tg, bar);
;             __builtin_amdgcn_fence(__ATOMIC_ACQUIRE, "agent");
;             xb_add(&bar[XB_XGEN(b.x)], 1u);
;             asm volatile("s_waitcnt vmcnt(0)" ::: "memory");
;         } else {
;             XB_SPIN(xb_ld(&bar[XB_XGEN(b.x)]) == gen, bar);
;             __builtin_amdgcn_fence(__ATOMIC_ACQUIRE, "agent");
;             asm volatile("s_waitcnt vmcnt(0)" ::: "memory");
;         }
.LBB0_634:
	s_or_b64 exec, exec, s[6:7]
	s_waitcnt vmcnt(0)
	buffer_inv sc1
.LBB0_635:
	s_andn2_saveexec_b64 s[4:5], s[4:5]
	s_cbranch_execz .LBB0_655
	s_mov_b64 s[4:5], exec
	buffer_wbl2 sc1
	s_waitcnt lgkmcnt(0)
	s_waitcnt vmcnt(0)
	v_mbcnt_lo_u32_b32 v0, s4, 0
	v_mbcnt_hi_u32_b32 v0, s5, v0
	v_cmp_eq_u32_e32 vcc, 0, v0
	s_and_saveexec_b64 s[6:7], vcc
	s_cbranch_execz .LBB0_638
	s_bcnt1_i32_b64 s4, s[4:5]
	v_mov_b32_e32 v3, s4
	v_readlane_b32 s4, v255, 17
	v_readlane_b32 s5, v255, 18
	s_nop 4
	global_atomic_add v3, v1, v3, s[4:5] sc0

; #define LAS __attribute__((address_space(3)))
; __device__ __forceinline__ unsigned cvt_pk_bf16(float lo, float hi) { unsigned r; asm volatile("v_cvt_pk_bf16_f32 %0, %1, %2" : "=v"(r) : "v"(lo), "v"(hi)); return r; }
; __device__ __forceinline__ float bf_lo(unsigned w) { return __uint_as_float(w << 16); }
; __device__ __forceinline__ float bf_hi(unsigned w) { return __uint_as_float(w & 0xffff0000u); }
; __device__ __forceinline__ int crow(int r, int hi) { return (r & 3) + 8 * (r >> 2) + 4 * hi; }
; template <int WIN, bool ALIBI, int EPI, bool SINK>
; __device__ __forceinline__ void attn_item(const Item& I, char* lds, int tid_in) {
;     ...
;     const int rsub = lane >> 4, ch = lane & 15;
;     bf16_t* Orow = I.O + (size_t)tokw * DM + I.ocol + ch * 8;
;     u32x4 oldv[(EPI == 2) ? 8 : 1];
;     if constexpr (EPI == 2) {
; #pragma unroll
;       for (int j = 0; j < 8; ++j) oldv[j] = LDG(u32x4, Orow + (size_t)(I.dil * (4 * j + rsub)) * DM); }
;     __syncthreads();
;     constexpr int RB = (EPI == 2) ? 512 : 256;
;     LAS char* Sw = V_lds + wid * (32 * RB);
;     if constexpr (EPI == 5) {
; #pragma unroll
;       for (int r = 0; r < 16; r += 2) { const int or0 = crow(r, hi), or1 = crow(r + 1, hi); const float f0 = li_l[or0], f1 = li_l[or1];
; #pragma unroll
;         for (int d0 = 0; d0 < 4; ++d0) { const unsigned pk = park[(r >> 1) * 4 + d0]; const float v0 = bf_lo(pk) + o[d0][r] * f0, v1 = bf_hi(pk) + o[d0][r + 1] * f1;
;           const unsigned w = cvt_pk_bf16(v0, v1);
;           *(LAS bf16_t*)(Sw + or0 * RB + (d0 * 32 + r32) * 2) = (bf16_t)(w & 0xffffu); *(LAS bf16_t*)(Sw + or1 * RB + (d0 * 32 + r32) * 2) = (bf16_t)(w >> 16); } }
;     } else {
; #pragma unroll
;       for (int r = 0; r < 16; ++r) { const int orow = crow(r, hi); const float f = li_l[orow];
; #pragma unroll
;         for (int d0 = 0; d0 < 4; ++d0) { const float v = o[d0][r] * f;
;           if constexpr (EPI == 2) *(LAS float*)(Sw + orow * RB + (d0 * 32 + r32) * 4) = v;
;           else *(LAS bf16_t*)(Sw + orow * RB + (d0 * 32 + r32) * 2) = (bf16_t)(cvt_pk_bf16(v, v) & 0xffffu); } }
.LBB0_662:
	s_or_b64 exec, exec, s[4:5]
	s_lshl_b32 s4, s26, 4
	v_add_u32_e32 v2, s4, v184
	v_ashrrev_i32_e32 v3, 31, v2
	v_lshlrev_b64 v[2:3], 12, v[2:3]
	v_lshl_add_u64 v[2:3], s[46:47], 0, v[2:3]
	s_lshl_b32 s72, s25, 1
	v_and_b32_e32 v115, 15, v183
	v_lshl_add_u64 v[2:3], v[2:3], 0, s[72:73]
	v_lshlrev_b32_e32 v0, 4, v115
	v_lshrrev_b32_e32 v114, 4, v186
	v_lshl_add_u64 v[2:3], v[2:3], 0, v[0:1]
	v_lshlrev_b32_e32 v0, 12, v183
	v_and_b32_e32 v0, 0x30000, v0
	v_or_b32_e32 v116, 4, v114
	v_lshl_add_u64 v[110:111], v[2:3], 0, v[0:1]
	v_lshlrev_b32_e32 v0, 16, v116
	v_or_b32_e32 v117, 8, v114
	v_lshl_add_u64 v[112:113], v[2:3], 0, v[0:1]
	v_lshlrev_b32_e32 v0, 16, v117
	v_or_b32_e32 v118, 12, v114
	v_lshl_add_u64 v[96:97], v[2:3], 0, v[0:1]
	v_lshlrev_b32_e32 v0, 16, v118
	v_or_b32_e32 v119, 16, v114
	v_lshl_add_u64 v[94:95], v[2:3], 0, v[0:1]
	v_lshlrev_b32_e32 v0, 16, v119
	v_or_b32_e32 v120, 20, v114
	v_lshl_add_u64 v[92:93], v[2:3], 0, v[0:1]
	v_lshlrev_b32_e32 v0, 16, v120
	v_or_b32_e32 v121, 24, v114
	v_lshl_add_u64 v[90:91], v[2:3], 0, v[0:1]
	v_lshlrev_b32_e32 v0, 16, v121
	v_or_b32_e32 v122, 28, v114
	s_waitcnt lgkmcnt(0)
	v_lshl_add_u64 v[88:89], v[2:3], 0, v[0:1]
	v_lshlrev_b32_e32 v0, 16, v122
	global_load_dwordx4 v[98:101], v[110:111], off
	global_load_dwordx4 v[102:105], v[112:113], off
	global_load_dwordx4 v[106:109], v[96:97], off
	global_load_dwordx4 v[84:87], v[94:95], off
	global_load_dwordx4 v[80:83], v[92:93], off
	global_load_dwordx4 v[10:13], v[90:91], off
	v_lshl_add_u64 v[14:15], v[2:3], 0, v[0:1]
	global_load_dwordx4 v[6:9], v[88:89], off
	global_load_dwordx4 v[2:5], v[14:15], off
	s_barrier
	ds_read_b32 v0, v192
	s_lshl_b32 s4, s24, 14
	s_add_i32 s4, s4, 0
	v_lshl_add_u32 v123, v181, 2, s4
	v_lshl_add_u32 v124, v182, 11, v123
	s_waitcnt lgkmcnt(0)
	v_mul_f32_e32 v48, v48, v0
	v_mul_f32_e32 v64, v64, v0
	v_mul_f32_e32 v16, v16, v0
	v_mul_f32_e32 v0, v32, v0
	ds_write2_b32 v124, v48, v64 offset1:32
	ds_write2_b32 v124, v16, v0 offset0:64 offset1:96
	ds_read_b32 v0, v192 offset:4
	v_lshl_add_u32 v32, v185, 9, v123
	s_add_i32 s12, s12, 1
	s_waitcnt lgkmcnt(0)
	v_mul_f32_e32 v16, v49, v0
	v_mul_f32_e32 v48, v65, v0
	ds_write2_b32 v32, v16, v48 offset0:128 offset1:160
	v_mul_f32_e32 v16, v17, v0
	v_mul_f32_e32 v0, v33, v0
	ds_write2_b32 v32, v16, v0 offset0:192 offset1:224
	ds_read_b32 v0, v192 offset:8
	v_add_u32_e32 v33, 0x400, v32
	s_waitcnt lgkmcnt(0)
	v_mul_f32_e32 v16, v50, v0
	v_mul_f32_e32 v17, v66, v0
	ds_write2_b32 v33, v16, v17 offset1:32
	v_mul_f32_e32 v16, v18, v0
	v_mul_f32_e32 v0, v34, v0
	ds_write2_b32 v33, v16, v0 offset0:64 offset1:96
	ds_read_b32 v0, v192 offset:12
	v_add_u32_e32 v18, 0x1000, v32
	s_waitcnt lgkmcnt(0)
	v_mul_f32_e32 v16, v51, v0
	v_mul_f32_e32 v17, v67, v0
	ds_write2_b32 v33, v16, v17 offset0:128 offset1:160
	v_mul_f32_e32 v16, v19, v0
	v_mul_f32_e32 v0, v35, v0
	ds_write2_b32 v33, v16, v0 offset0:192 offset1:224
	ds_read_b32 v0, v192 offset:32
	s_waitcnt lgkmcnt(0)
	v_mul_f32_e32 v16, v52, v0
	v_mul_f32_e32 v17, v68, v0
	ds_write2_b32 v18, v16, v17 offset1:32
	v_mul_f32_e32 v16, v20, v0
	v_mul_f32_e32 v0, v36, v0
	ds_write2_b32 v18, v16, v0 offset0:64 offset1:96
	ds_read_b32 v0, v192 offset:36
	s_waitcnt lgkmcnt(0)
	v_mul_f32_e32 v16, v53, v0
	v_mul_f32_e32 v17, v69, v0
	ds_write2_b32 v18, v16, v17 offset0:128 offset1:160
	v_mul_f32_e32 v16, v21, v0
	v_mul_f32_e32 v0, v37, v0
	ds_write2_b32 v18, v16, v0 offset0:192 offset1:224
	ds_read_b32 v0, v192 offset:40
	v_add_u32_e32 v18, 0x1400, v32
	s_waitcnt lgkmcnt(0)
	v_mul_f32_e32 v16, v54, v0
	v_mul_f32_e32 v17, v70, v0
	ds_write2_b32 v18, v16, v17 offset1:32
	v_mul_f32_e32 v16, v22, v0
	v_mul_f32_e32 v0, v38, v0
	ds_write2_b32 v18, v16, v0 offset0:64 offset1:96
	ds_read_b32 v0, v192 offset:44
	s_waitcnt lgkmcnt(0)
	v_mul_f32_e32 v16, v55, v0
	v_mul_f32_e32 v17, v71, v0
	ds_write2_b32 v18, v16, v17 offset0:128 offset1:160
	v_mul_f32_e32 v16, v23, v0
	v_mul_f32_e32 v0, v39, v0
	ds_write2_b32 v18, v16, v0 offset0:192 offset1:224
	ds_read_b32 v0, v192 offset:64
	v_add_u32_e32 v18, 0x2000, v32
	s_waitcnt lgkmcnt(0)
	v_mul_f32_e32 v16, v56, v0
	v_mul_f32_e32 v17, v72, v0
	ds_write2_b32 v18, v16, v17 offset1:32
	v_mul_f32_e32 v16, v24, v0
	v_mul_f32_e32 v0, v40, v0
	ds_write2_b32 v18, v16, v0 offset0:64 offset1:96
	ds_read_b32 v0, v192 offset:68
	v_lshl_add_u32 v24, v114, 2, s13
	s_waitcnt lgkmcnt(0)
	v_mul_f32_e32 v16, v57, v0
	v_mul_f32_e32 v17, v73, v0
	ds_write2_b32 v18, v16, v17 offset0:128 offset1:160
	v_mul_f32_e32 v16, v25, v0
	v_mul_f32_e32 v0, v41, v0
	ds_write2_b32 v18, v16, v0 offset0:192 offset1:224
	ds_read_b32 v0, v192 offset:72
	v_add_u32_e32 v18, 0x2400, v32
	s_waitcnt lgkmcnt(0)
	v_mul_f32_e32 v16, v58, v0
	v_mul_f32_e32 v17, v74, v0
	ds_write2_b32 v18, v16, v17 offset1:32
	v_mul_f32_e32 v16, v26, v0
	v_mul_f32_e32 v0, v42, v0
	ds_write2_b32 v18, v16, v0 offset0:64 offset1:96
	ds_read_b32 v0, v192 offset:76
	s_waitcnt vmcnt(7)
	v_lshlrev_b32_e32 v26, 16, v98
	s_waitcnt lgkmcnt(0)
	v_mul_f32_e32 v16, v59, v0
	v_mul_f32_e32 v17, v75, v0
	ds_write2_b32 v18, v16, v17 offset0:128 offset1:160
	v_mul_f32_e32 v16, v27, v0
	v_mul_f32_e32 v0, v43, v0
	ds_write2_b32 v18, v16, v0 offset0:192 offset1:224
	ds_read_b32 v0, v192 offset:96
	v_add_u32_e32 v18, 0x3000, v32
	s_waitcnt lgkmcnt(0)
	v_mul_f32_e32 v16, v60, v0
	v_mul_f32_e32 v17, v76, v0
	ds_write2_b32 v18, v16, v17 offset1:32
	v_mul_f32_e32 v16, v28, v0
	v_mul_f32_e32 v0, v44, v0
	ds_write2_b32 v18, v16, v0 offset0:64 offset1:96
	ds_read_b32 v0, v192 offset:100
	s_waitcnt lgkmcnt(0)
; #define LAS __attribute__((address_space(3)))
; __device__ __forceinline__ unsigned cvt_pk_bf16(float lo, float hi) { unsigned r; asm volatile("v_cvt_pk_bf16_f32 %0, %1, %2" : "=v"(r) : "v"(lo), "v"(hi)); return r; }
; __device__ __forceinline__ float bf_lo(unsigned w) { return __uint_as_float(w << 16); }
; __device__ __forceinline__ float bf_hi(unsigned w) { return __uint_as_float(w & 0xffff0000u); }
; __device__ __forceinline__ int crow(int r, int hi) { return (r & 3) + 8 * (r >> 2) + 4 * hi; }
; template <int WIN, bool ALIBI, int EPI, bool SINK>
; __device__ __forceinline__ void attn_item(const Item& I, char* lds, int tid_in) {
;     ...
; #pragma unroll
;       for (int r = 0; r < 16; ++r) { const int orow = crow(r, hi); const float f = li_l[orow];
; #pragma unroll
;         for (int d0 = 0; d0 < 4; ++d0) { const float v = o[d0][r] * f;
;           if constexpr (EPI == 2) *(LAS float*)(Sw + orow * RB + (d0 * 32 + r32) * 4) = v;
;           else *(LAS bf16_t*)(Sw + orow * RB + (d0 * 32 + r32) * 2) = (bf16_t)(cvt_pk_bf16(v, v) & 0xffffu); } }
;     }
;     asm volatile("s_waitcnt lgkmcnt(0)" ::: "memory");
;     if constexpr (EPI == 2) {
; #pragma unroll
;       for (int j = 0; j < 8; ++j) { const int row = 4 * j + rsub; const float fo = al_l[row];
;         const f32x4 a0 = *(const LAS f32x4*)(Sw + row * RB + ch * 32), a1 = *(const LAS f32x4*)(Sw + row * RB + ch * 32 + 16); const u32x4 ov = oldv[j];
;         u32x4 w; w.x = cvt_pk_bf16(fo * bf_lo(ov.x) + a0[0], fo * bf_hi(ov.x) + a0[1]); w.y = cvt_pk_bf16(fo * bf_lo(ov.y) + a0[2], fo * bf_hi(ov.y) + a0[3]);
;         w.z = cvt_pk_bf16(fo * bf_lo(ov.z) + a1[0], fo * bf_hi(ov.z) + a1[1]); w.w = cvt_pk_bf16(fo * bf_lo(ov.w) + a1[2], fo * bf_hi(ov.w) + a1[3]);
;         STG(u32x4, Orow + (size_t)(I.dil * row) * DM) = w; }
	v_mul_f32_e32 v16, v61, v0
	v_mul_f32_e32 v17, v77, v0
	ds_write2_b32 v18, v16, v17 offset0:128 offset1:160
	v_mul_f32_e32 v16, v29, v0
	v_mul_f32_e32 v0, v45, v0
	ds_write2_b32 v18, v16, v0 offset0:192 offset1:224
	ds_read_b32 v0, v192 offset:104
	v_add_u32_e32 v18, 0x3400, v32
	s_waitcnt lgkmcnt(0)
	v_mul_f32_e32 v16, v62, v0
	v_mul_f32_e32 v17, v78, v0
	ds_write2_b32 v18, v16, v17 offset1:32
	v_mul_f32_e32 v16, v30, v0
	v_mul_f32_e32 v0, v46, v0
	ds_write2_b32 v18, v16, v0 offset0:64 offset1:96
	ds_read_b32 v0, v192 offset:108
	s_waitcnt lgkmcnt(0)
	v_mul_f32_e32 v16, v63, v0
	v_mul_f32_e32 v17, v79, v0
	ds_write2_b32 v18, v16, v17 offset0:128 offset1:160
	v_mul_f32_e32 v16, v31, v0
	v_mul_f32_e32 v0, v47, v0
	ds_write2_b32 v18, v16, v0 offset0:192 offset1:224
	v_lshl_add_u32 v0, v115, 5, s4
	s_waitcnt lgkmcnt(0)
	v_lshl_add_u32 v20, v114, 9, v0
	ds_read_b32 v25, v24 offset:128
	ds_read_b128 v[16:19], v20
	ds_read_b128 v[20:23], v20 offset:16
	s_mul_i32 s4, s12, s8
	s_add_i32 s13, s4, s9
	s_cmpk_lt_i32 s13, 0xa00
	s_waitcnt lgkmcnt(1)
	v_fma_f32 v16, v25, v26, v16
	v_and_b32_e32 v26, 0xffff0000, v98
	v_fma_f32 v17, v25, v26, v17
	v_cvt_pk_bf16_f32 v16, v16, v17
	v_lshlrev_b32_e32 v17, 16, v99
	v_fma_f32 v17, v25, v17, v18
	v_and_b32_e32 v18, 0xffff0000, v99
	v_fmac_f32_e32 v19, v25, v18
	v_cvt_pk_bf16_f32 v17, v17, v19
	v_lshlrev_b32_e32 v18, 16, v100
	v_and_b32_e32 v19, 0xffff0000, v100
	s_waitcnt lgkmcnt(0)
	v_fma_f32 v18, v25, v18, v20
	v_fma_f32 v19, v25, v19, v21
	v_cvt_pk_bf16_f32 v18, v18, v19
	v_lshlrev_b32_e32 v19, 16, v101
	v_and_b32_e32 v20, 0xffff0000, v101
	v_fma_f32 v19, v25, v19, v22
	v_fmac_f32_e32 v23, v25, v20
	v_cvt_pk_bf16_f32 v19, v19, v23
	v_lshl_add_u32 v25, v116, 9, v0
	ds_read_b32 v26, v24 offset:144
	ds_read_b128 v[20:23], v25
	global_store_dwordx4 v[110:111], v[16:19], off
	ds_read_b128 v[16:19], v25 offset:16
	s_waitcnt vmcnt(7)
	v_lshlrev_b32_e32 v25, 16, v102
	s_waitcnt lgkmcnt(1)
	v_fma_f32 v20, v26, v25, v20
	v_and_b32_e32 v25, 0xffff0000, v102
	v_fma_f32 v21, v26, v25, v21
	v_cvt_pk_bf16_f32 v20, v20, v21
	v_lshlrev_b32_e32 v21, 16, v103
	v_fma_f32 v21, v26, v21, v22
	v_and_b32_e32 v22, 0xffff0000, v103
	v_fmac_f32_e32 v23, v26, v22
	v_lshlrev_b32_e32 v22, 16, v104
	s_waitcnt lgkmcnt(0)
	v_fma_f32 v16, v26, v22, v16
	v_and_b32_e32 v22, 0xffff0000, v104
	v_fma_f32 v17, v26, v22, v17
	v_cvt_pk_bf16_f32 v21, v21, v23
	v_cvt_pk_bf16_f32 v22, v16, v17
	v_lshlrev_b32_e32 v16, 16, v105
	v_and_b32_e32 v17, 0xffff0000, v105
	v_fma_f32 v16, v26, v16, v18
	v_fmac_f32_e32 v19, v26, v17
	v_cvt_pk_bf16_f32 v23, v16, v19
	v_lshl_add_u32 v25, v117, 9, v0
	ds_read_b32 v26, v24 offset:160
	ds_read_b128 v[16:19], v25
	global_store_dwordx4 v[112:113], v[20:23], off
	ds_read_b128 v[20:23], v25 offset:16
	s_waitcnt vmcnt(7)
	v_lshlrev_b32_e32 v25, 16, v106
	s_waitcnt lgkmcnt(1)
	v_fma_f32 v16, v26, v25, v16
	v_and_b32_e32 v25, 0xffff0000, v106
	v_fma_f32 v17, v26, v25, v17
	v_cvt_pk_bf16_f32 v16, v16, v17
	v_lshlrev_b32_e32 v17, 16, v107
	v_fma_f32 v17, v26, v17, v18
	v_and_b32_e32 v18, 0xffff0000, v107
	v_fmac_f32_e32 v19, v26, v18
	v_cvt_pk_bf16_f32 v17, v17, v19
	v_lshlrev_b32_e32 v18, 16, v108
	v_and_b32_e32 v19, 0xffff0000, v108
	s_waitcnt lgkmcnt(0)
	v_fma_f32 v18, v26, v18, v20
	v_fma_f32 v19, v26, v19, v21
	v_cvt_pk_bf16_f32 v18, v18, v19
	v_lshlrev_b32_e32 v19, 16, v109
	v_and_b32_e32 v20, 0xffff0000, v109
	v_fma_f32 v19, v26, v19, v22
	v_fmac_f32_e32 v23, v26, v20
	v_cvt_pk_bf16_f32 v19, v19, v23
	v_lshl_add_u32 v25, v118, 9, v0
	ds_read_b32 v26, v24 offset:176
	ds_read_b128 v[20:23], v25
	global_store_dwordx4 v[96:97], v[16:19], off
	ds_read_b128 v[16:19], v25 offset:16
	s_waitcnt vmcnt(7)
	v_lshlrev_b32_e32 v25, 16, v84
	s_waitcnt lgkmcnt(1)
	v_fma_f32 v20, v26, v25, v20
	v_and_b32_e32 v25, 0xffff0000, v84
	v_fma_f32 v21, v26, v25, v21
	v_cvt_pk_bf16_f32 v20, v20, v21
	v_lshlrev_b32_e32 v21, 16, v85
	v_fma_f32 v21, v26, v21, v22
	v_and_b32_e32 v22, 0xffff0000, v85
	v_fmac_f32_e32 v23, v26, v22
	v_lshlrev_b32_e32 v22, 16, v86
	s_waitcnt lgkmcnt(0)
; #define LAS __attribute__((address_space(3)))
; __device__ __forceinline__ unsigned cvt_pk_bf16(float lo, float hi) { unsigned r; asm volatile("v_cvt_pk_bf16_f32 %0, %1, %2" : "=v"(r) : "v"(lo), "v"(hi)); return r; }
; __device__ __forceinline__ float bf_lo(unsigned w) { return __uint_as_float(w << 16); }
; __device__ __forceinline__ float bf_hi(unsigned w) { return __uint_as_float(w & 0xffff0000u); }
; template <int WIN, bool ALIBI, int EPI, bool SINK>
; __device__ __forceinline__ void attn_item(const Item& I, char* lds, int tid_in) {
;     ...
;     if constexpr (EPI == 2) {
; #pragma unroll
;       for (int j = 0; j < 8; ++j) { const int row = 4 * j + rsub; const float fo = al_l[row];
;         const f32x4 a0 = *(const LAS f32x4*)(Sw + row * RB + ch * 32), a1 = *(const LAS f32x4*)(Sw + row * RB + ch * 32 + 16); const u32x4 ov = oldv[j];
;         u32x4 w; w.x = cvt_pk_bf16(fo * bf_lo(ov.x) + a0[0], fo * bf_hi(ov.x) + a0[1]); w.y = cvt_pk_bf16(fo * bf_lo(ov.y) + a0[2], fo * bf_hi(ov.y) + a0[3]);
;         w.z = cvt_pk_bf16(fo * bf_lo(ov.z) + a1[0], fo * bf_hi(ov.z) + a1[1]); w.w = cvt_pk_bf16(fo * bf_lo(ov.w) + a1[2], fo * bf_hi(ov.w) + a1[3]);
;         STG(u32x4, Orow + (size_t)(I.dil * row) * DM) = w; }
;     } else {
; #pragma unroll
;       for (int j = 0; j < 8; ++j) { const int row = 4 * j + rsub; const u32x4 w = *(const LAS u32x4*)(Sw + row * RB + ch * 16);
;         STG(u32x4, Orow + (size_t)(I.dil * row) * DM) = w; }
;     }
;   }
;   __syncthreads();
	v_fma_f32 v16, v26, v22, v16
	v_and_b32_e32 v22, 0xffff0000, v86
	v_fma_f32 v17, v26, v22, v17
	v_cvt_pk_bf16_f32 v21, v21, v23
	v_cvt_pk_bf16_f32 v22, v16, v17
	v_lshlrev_b32_e32 v16, 16, v87
	v_and_b32_e32 v17, 0xffff0000, v87
	v_fma_f32 v16, v26, v16, v18
	v_fmac_f32_e32 v19, v26, v17
	v_cvt_pk_bf16_f32 v23, v16, v19
	v_lshl_add_u32 v25, v119, 9, v0
	ds_read_b32 v26, v24 offset:192
	ds_read_b128 v[16:19], v25
	global_store_dwordx4 v[94:95], v[20:23], off
	ds_read_b128 v[20:23], v25 offset:16
	s_waitcnt vmcnt(7)
	v_lshlrev_b32_e32 v25, 16, v80
	s_waitcnt lgkmcnt(1)
	v_fma_f32 v16, v26, v25, v16
	v_and_b32_e32 v25, 0xffff0000, v80
	v_fma_f32 v17, v26, v25, v17
	v_cvt_pk_bf16_f32 v16, v16, v17
	v_lshlrev_b32_e32 v17, 16, v81
	v_fma_f32 v17, v26, v17, v18
	v_and_b32_e32 v18, 0xffff0000, v81
	v_fmac_f32_e32 v19, v26, v18
	v_cvt_pk_bf16_f32 v17, v17, v19
	v_lshlrev_b32_e32 v18, 16, v82
	v_and_b32_e32 v19, 0xffff0000, v82
	s_waitcnt lgkmcnt(0)
	v_fma_f32 v18, v26, v18, v20
	v_fma_f32 v19, v26, v19, v21
	v_cvt_pk_bf16_f32 v18, v18, v19
	v_lshlrev_b32_e32 v19, 16, v83
	v_and_b32_e32 v20, 0xffff0000, v83
	v_fma_f32 v19, v26, v19, v22
	v_fmac_f32_e32 v23, v26, v20
	v_cvt_pk_bf16_f32 v19, v19, v23
	v_lshl_add_u32 v25, v120, 9, v0
	ds_read_b32 v26, v24 offset:208
	ds_read_b128 v[20:23], v25
	global_store_dwordx4 v[92:93], v[16:19], off
	ds_read_b128 v[16:19], v25 offset:16
	s_waitcnt vmcnt(7)
	v_lshlrev_b32_e32 v25, 16, v10
	v_and_b32_e32 v10, 0xffff0000, v10
	s_waitcnt lgkmcnt(1)
	v_fma_f32 v20, v26, v25, v20
	v_fma_f32 v10, v26, v10, v21
	v_cvt_pk_bf16_f32 v10, v20, v10
	v_lshlrev_b32_e32 v20, 16, v11
	v_fma_f32 v20, v26, v20, v22
	v_and_b32_e32 v11, 0xffff0000, v11
	v_fmac_f32_e32 v23, v26, v11
	v_cvt_pk_bf16_f32 v11, v20, v23
	v_lshlrev_b32_e32 v20, 16, v12
	v_and_b32_e32 v12, 0xffff0000, v12
	s_waitcnt lgkmcnt(0)
	v_fma_f32 v16, v26, v20, v16
	v_fma_f32 v12, v26, v12, v17
	v_cvt_pk_bf16_f32 v12, v16, v12
	v_lshlrev_b32_e32 v16, 16, v13
	v_and_b32_e32 v13, 0xffff0000, v13
	v_fma_f32 v16, v26, v16, v18
	v_fmac_f32_e32 v19, v26, v13
	v_cvt_pk_bf16_f32 v13, v16, v19
	v_lshl_add_u32 v20, v121, 9, v0
	ds_read_b32 v21, v24 offset:224
	ds_read_b128 v[16:19], v20
	global_store_dwordx4 v[90:91], v[10:13], off
	ds_read_b128 v[10:13], v20 offset:16
	s_waitcnt vmcnt(7)
	v_lshlrev_b32_e32 v20, 16, v6
	v_and_b32_e32 v6, 0xffff0000, v6
	s_waitcnt lgkmcnt(1)
	v_fma_f32 v16, v21, v20, v16
	v_fma_f32 v6, v21, v6, v17
	v_cvt_pk_bf16_f32 v6, v16, v6
	v_lshlrev_b32_e32 v16, 16, v7
	v_fma_f32 v16, v21, v16, v18
	v_and_b32_e32 v7, 0xffff0000, v7
	v_fmac_f32_e32 v19, v21, v7
	v_cvt_pk_bf16_f32 v7, v16, v19
	v_lshlrev_b32_e32 v16, 16, v8
	v_and_b32_e32 v8, 0xffff0000, v8
	s_waitcnt lgkmcnt(0)
	v_fma_f32 v10, v21, v16, v10
	v_fma_f32 v8, v21, v8, v11
	v_cvt_pk_bf16_f32 v8, v10, v8
	v_lshlrev_b32_e32 v10, 16, v9
	v_and_b32_e32 v9, 0xffff0000, v9
	v_fma_f32 v10, v21, v10, v12
	v_fmac_f32_e32 v13, v21, v9
	v_cvt_pk_bf16_f32 v9, v10, v13
	v_lshl_add_u32 v0, v122, 9, v0
	ds_read_b32 v16, v24 offset:240
	ds_read_b128 v[10:13], v0
	global_store_dwordx4 v[88:89], v[6:9], off
	ds_read_b128 v[6:9], v0 offset:16
	s_waitcnt vmcnt(7)
	v_lshlrev_b32_e32 v0, 16, v2
	v_and_b32_e32 v2, 0xffff0000, v2
	s_waitcnt lgkmcnt(1)
	v_fma_f32 v0, v16, v0, v10
	v_fma_f32 v2, v16, v2, v11
	v_cvt_pk_bf16_f32 v2, v0, v2
	v_lshlrev_b32_e32 v0, 16, v3
	v_fma_f32 v0, v16, v0, v12
	v_and_b32_e32 v3, 0xffff0000, v3
	v_fmac_f32_e32 v13, v16, v3
	v_cvt_pk_bf16_f32 v3, v0, v13
	v_lshlrev_b32_e32 v0, 16, v4
	v_and_b32_e32 v4, 0xffff0000, v4
	s_waitcnt lgkmcnt(0)
	v_fma_f32 v0, v16, v0, v6
	v_fma_f32 v4, v16, v4, v7
	v_cvt_pk_bf16_f32 v4, v0, v4
	v_lshlrev_b32_e32 v0, 16, v5
	v_and_b32_e32 v5, 0xffff0000, v5
	v_fma_f32 v0, v16, v0, v8
	v_fmac_f32_e32 v9, v16, v5
	v_cvt_pk_bf16_f32 v5, v0, v9
	global_store_dwordx4 v[14:15], v[2:5], off
	s_barrier
	s_cbranch_scc0 .LBB0_684

; #define LAS __attribute__((address_space(3)))
; __device__ __forceinline__ int v_rd_base(int lane) { return ((lane & 3) << 3) | (((lane >> 2) & 3) << 6) | (((lane >> 4) & 1) << 5) | (((lane >> 5) & 1) << 8); }
; template <int WIN, bool ALIBI, int EPI, bool SINK>
; __device__ __forceinline__ void attn_item(const Item& I, char* lds, int tid_in) {
;     ...
;   const int hh = wid >> 2, tl = tid & 255, sr4 = tl >> 4, sc4 = (tl & 15) * 8;
;   LAS char* Vh = V_lds + hh * (2 * (SHM_V + SHM_K)); LAS char* Kh = Vh + 2 * SHM_V;
;   const int vbh = (int)(unsigned)(uintptr_t)Vh + v_rd_base(lane);
;   const int clsw = I.c0 + wcls, NTw = two ? 2 : (128 + 2 * WIN) / 64, ukbw = two ? 0 : I.u0 + 128 * hh - WIN;
;   bf16x8 stv[4], stk[4];
; template <int MODE> __device__ __forceinline__ void phase_attn_fast(const Frame& F0) {
;     ...
;       if (MODE == 5 || MODE == 6) { const int dil = (MODE == 5) ? 4 : 16; I.dil = dil; I.SU = d.S / dil; I.nslope = -slope2 * (float)dil;
;         const int nqc = I.SU / 256;
;         if (nqc == 0) { I.two = 1; I.c0 = 2 * d.qb; I.u0 = 0; I.ukb0 = 0; I.NT = 4; }
;         else { I.c0 = d.qb / nqc; I.u0 = 256 * (d.qb % nqc); I.ukb0 = I.u0 - 64; I.NT = 6; }
.LBB0_670:
	s_or_b64 exec, exec, s[6:7]
	s_lshl_b32 s6, s50, 5
	s_and_b32 s6, s6, 0x180
	s_or_b32 s27, s6, 0x800
	s_or_b32 s28, s6, 0xa00
	s_add_i32 s6, s50, 1
	v_cvt_f32_ubyte0_e32 v3, s6
	v_mul_f32_e32 v4, -0.5, v3
	s_mov_b32 s6, 0xc2fc0000
	v_cmp_gt_f32_e32 vcc, s6, v4
	s_and_b64 s[6:7], vcc, exec
	s_cselect_b32 s6, 0xffffffc0, 0
	v_cndmask_b32_e32 v4, 0, v230, vcc
	v_fmac_f32_e32 v4, -0.5, v3
	v_exp_f32_e32 v3, v4
	v_lshlrev_b32_e32 v185, 2, v182
	v_lshlrev_b32_e32 v39, 3, v183
	v_sub_u32_e32 v38, v185, v2
	v_ldexp_f32 v3, v3, s6
	s_and_b32 s6, s13, 0x3fffffc0
	s_lshl_b32 s6, s6, 2
	v_mul_f32_e32 v3, 0xbfb8aa3b, v3
	s_add_i32 s13, s6, 0
	s_lshl_b32 s6, s31, 16
	v_mul_f32_e32 v188, 0x41800000, v3
	v_sub_u32_e32 v3, 0, v2
	s_add_i32 s29, s6, 0
	s_lshl_b32 s6, s31, 7
	s_add_i32 s13, s13, 0x20000
	v_max_i32_e32 v36, 0xffffffc0, v3
	v_xad_u32 v3, v2, -1, s30
	s_sub_i32 s31, s6, 64
	v_min_i32_e32 v37, 64, v3
	v_and_b32_e32 v2, 0x78, v39
	v_lshlrev_b32_e32 v3, 4, v186
	s_and_b64 s[6:7], exec, s[4:5]
	v_lshlrev_b32_e32 v34, 1, v2
	v_lshlrev_b32_e32 v2, 3, v186
	v_and_b32_e32 v3, 0xc0, v3
	v_lshlrev_b32_e32 v4, 1, v186
	v_bfe_u32 v41, v183, 4, 4
	s_cselect_b32 s51, 0, s31
	v_and_or_b32 v3, v2, 24, v3
	v_and_b32_e32 v4, 32, v4
	v_and_b32_e32 v2, 0x100, v2
	v_or_b32_e32 v43, s51, v41
	v_or3_b32 v42, v3, v4, v2
	s_add_i32 s52, s30, -1
	v_max_i32_e32 v2, 0, v43
	v_mov_b32_e32 v35, v1
	v_min_u32_e32 v2, s52, v2
	v_lshl_add_u64 v[178:179], s[42:43], 0, v[34:35]
	v_lshl_add_u32 v2, v2, 4, v184
	v_mad_i64_i32 v[6:7], s[6:7], v2, s89, v[178:179]
	s_lshl_b32 s72, s28, 1
	v_lshl_add_u64 v[2:3], v[6:7], 0, s[72:73]
	global_load_dwordx4 v[2:5], v[2:3], off
	v_max_i32_e32 v10, -16, v43
	v_add_u32_e32 v10, 16, v10
	v_min_u32_e32 v10, s52, v10
	v_max_i32_e32 v18, 0xffffffe0, v43
	s_lshl_b32 s6, s27, 1
	s_mov_b32 s7, s73
	v_lshl_add_u32 v10, v10, 4, v184
	v_add_u32_e32 v18, 32, v18
	v_lshl_add_u64 v[6:7], v[6:7], 0, s[6:7]
	v_mad_i64_i32 v[14:15], s[30:31], v10, s89, v[178:179]
	v_min_u32_e32 v18, s52, v18
	v_max_i32_e32 v26, 0xffffffd0, v43
	global_load_dwordx4 v[6:9], v[6:7], off
	v_lshl_add_u64 v[10:11], v[14:15], 0, s[72:73]
	v_lshl_add_u32 v18, v18, 4, v184
	v_add_u32_e32 v26, 48, v26
	global_load_dwordx4 v[10:13], v[10:11], off
	v_lshl_add_u64 v[14:15], v[14:15], 0, s[6:7]
	v_mad_i64_i32 v[22:23], s[30:31], v18, s89, v[178:179]
	v_min_u32_e32 v26, s52, v26
	global_load_dwordx4 v[14:17], v[14:15], off
	v_lshl_add_u64 v[18:19], v[22:23], 0, s[72:73]
	v_lshl_add_u32 v26, v26, 4, v184
	global_load_dwordx4 v[18:21], v[18:19], off
	v_lshl_add_u64 v[22:23], v[22:23], 0, s[6:7]
	v_mad_i64_i32 v[30:31], s[30:31], v26, s89, v[178:179]
	global_load_dwordx4 v[22:25], v[22:23], off
	v_lshl_add_u64 v[26:27], v[30:31], 0, s[72:73]
	global_load_dwordx4 v[26:29], v[26:27], off
	v_lshl_add_u64 v[30:31], v[30:31], 0, s[6:7]
	global_load_dwordx4 v[30:33], v[30:31], off
	v_lshrrev_b32_e32 v40, 4, v183
	v_bfe_u32 v35, v39, 5, 2
	v_add_u32_e32 v191, s29, v42
	v_lshrrev_b32_e32 v39, 5, v183
	v_bfe_u32 v42, v183, 4, 2
	v_and_or_b32 v39, v39, 4, v42
	v_and_or_b32 v35, v40, 4, v35
	v_cvt_f32_i32_e32 v190, v37
	v_and_b32_e32 v37, 48, v34
	v_lshl_add_u32 v39, v39, 6, s29
	v_lshlrev_b32_e32 v35, 9, v35
	s_movk_i32 s34, 0x70
	v_add3_u32 v193, v39, v37, v35
	s_waitcnt vmcnt(0)
; #define WSLOAD(n) do { _Pragma("unroll") for (int i_ = 0; i_ < 4; ++i_) { int u_ = WUKB(n) + sr4 + 16 * i_; u_ = min(max(u_, 0), I.SU - 1); \
;       const bf16_t* rp_ = I.qkv + (size_t)(I.seq_base + clsw + I.dil * u_) * I.W + sc4; stv[i_] = LDG(bf16x8, rp_ + I.vcol); stk[i_] = LDG(bf16x8, rp_ + I.kcol); } } while (0)
; #define WSWRITE(b) do { _Pragma("unroll") for (int i_ = 0; i_ < 4; ++i_) { *(LAS bf16x8*)(Vh + (b) * SHM_V + v_st(sr4 + 16 * i_, sc4)) = stv[i_]; \
;       *(LAS bf16x8*)(Kh + (b) * SHM_K + KSWZ(sr4 + 16 * i_, sc4 * 2)) = stk[i_]; } } while (0)
; template <int WIN, bool ALIBI, int EPI, bool SINK>
; __device__ __forceinline__ void attn_item(const Item& I, char* lds, int tid_in) {
;     ...
;   const int clsw = I.c0 + wcls, NTw = two ? 2 : (128 + 2 * WIN) / 64, ukbw = two ? 0 : I.u0 + 128 * hh - WIN;
;   bf16x8 stv[4], stk[4];
;     ...
;   WSLOAD(0); asm volatile("s_waitcnt vmcnt(0)" ::: "memory"); WSWRITE(0); if (1 < NTw) WSLOAD(1); __syncthreads();
	v_bitop3_b32 v34, v34, v183, s34 bitop3:0x78
	v_cvt_f32_i32_e32 v195, v38
	v_cvt_f32_i32_e32 v197, v36
	s_and_b64 s[4:5], exec, s[4:5]
	s_movk_i32 s4, 0xe0
	v_add_u32_e32 v192, s13, v0
	v_or_b32_e32 v208, 0x80, v41
	s_mov_b32 s49, 0
	v_lshl_add_u32 v198, v181, 8, s29
	v_lshl_add_u32 v196, v181, 2, s13
	v_mov_b32_e32 v206, 0xf149f2ca
	ds_write_b128 v193, v[2:5]
	v_lshlrev_b32_e32 v2, 8, v41
	v_add3_u32 v194, s29, v34, v2
	v_max_i32_e32 v2, 0xffffffc0, v43
	v_add_u32_e32 v2, 64, v2
	v_min_u32_e32 v2, s52, v2
	v_lshl_add_u32 v2, v2, 4, v184
	v_mad_i64_i32 v[2:3], s[30:31], v2, s89, v[178:179]
	ds_write_b128 v194, v[6:9] offset:32768
	ds_write_b128 v193, v[10:13] offset:4096
	ds_write_b128 v194, v[14:17] offset:36864
	ds_write_b128 v193, v[18:21] offset:8192
	ds_write_b128 v194, v[22:25] offset:40960
	ds_write_b128 v193, v[26:29] offset:12288
	ds_write_b128 v194, v[30:33] offset:45056
	v_lshl_add_u64 v[4:5], v[2:3], 0, s[72:73]
	v_lshl_add_u64 v[2:3], v[2:3], 0, s[6:7]
	global_load_dwordx4 v[144:147], v[4:5], off
	global_load_dwordx4 v[148:151], v[2:3], off
	v_max_i32_e32 v2, 0xffffffb0, v43
	v_add_u32_e32 v2, 0x50, v2
	v_min_u32_e32 v2, s52, v2
	v_lshl_add_u32 v2, v2, 4, v184
	v_mad_i64_i32 v[2:3], s[30:31], v2, s89, v[178:179]
	v_lshl_add_u64 v[4:5], v[2:3], 0, s[72:73]
	v_lshl_add_u64 v[2:3], v[2:3], 0, s[6:7]
	global_load_dwordx4 v[152:155], v[4:5], off
	global_load_dwordx4 v[156:159], v[2:3], off
	v_max_i32_e32 v2, 0xffffffa0, v43
	v_add_u32_e32 v2, 0x60, v2
	v_min_u32_e32 v2, s52, v2
	v_lshl_add_u32 v2, v2, 4, v184
	v_mad_i64_i32 v[2:3], s[30:31], v2, s89, v[178:179]
	v_lshl_add_u64 v[4:5], v[2:3], 0, s[72:73]
	v_lshl_add_u64 v[2:3], v[2:3], 0, s[6:7]
	global_load_dwordx4 v[160:163], v[4:5], off
	global_load_dwordx4 v[164:167], v[2:3], off
	v_max_i32_e32 v2, 0xffffff90, v43
	v_add_u32_e32 v2, 0x70, v2
	v_min_u32_e32 v2, s52, v2
	v_lshl_add_u32 v2, v2, 4, v184
	v_mad_i64_i32 v[2:3], s[30:31], v2, s89, v[178:179]
	v_lshl_add_u64 v[4:5], v[2:3], 0, s[72:73]
	v_lshl_add_u64 v[2:3], v[2:3], 0, s[6:7]
	global_load_dwordx4 v[168:171], v[4:5], off
	global_load_dwordx4 v[172:175], v[2:3], off
	v_lshlrev_b32_e32 v2, 4, v181
	v_and_b32_e32 v3, 0x70, v2
	v_mov_b32_e32 v14, v1
	v_mov_b32_e32 v15, v1
	v_bitop3_b32 v199, v0, v2, s34 bitop3:0x78
	v_bitop3_b32 v200, v0, v3, 32 bitop3:0x36
	v_bitop3_b32 v201, v0, v3, 64 bitop3:0x36
	v_bitop3_b32 v202, v0, v3, s93 bitop3:0x36
	v_bitop3_b32 v203, v0, v3, s85 bitop3:0x36
	v_bitop3_b32 v204, v0, v3, s67 bitop3:0x36
	v_bitop3_b32 v205, v0, v3, s83 bitop3:0x36
	v_bitop3_b32 v207, v0, v3, s4 bitop3:0x36
	v_mov_b32_e32 v0, v1
	v_mov_b32_e32 v2, v1
	v_mov_b32_e32 v3, v1
	v_mov_b32_e32 v4, v1
	v_mov_b32_e32 v5, v1
	v_mov_b32_e32 v6, v1
	v_mov_b32_e32 v7, v1
	v_mov_b32_e32 v8, v1
	v_mov_b32_e32 v9, v1
	v_mov_b32_e32 v10, v1
	v_mov_b32_e32 v11, v1
	v_mov_b32_e32 v12, v1
	v_mov_b32_e32 v13, v1
	v_mov_b64_e32 v[62:63], v[14:15]
	v_mov_b64_e32 v[78:79], v[14:15]
	v_mov_b64_e32 v[30:31], v[14:15]
	v_mov_b64_e32 v[46:47], v[14:15]
	s_cselect_b32 s6, 2, 4
	s_sub_i32 s7, s26, 64
	s_add_i32 s53, s26, 0x5f
	s_lshl_b32 s72, s28, 1
	s_lshl_b32 s48, s27, 1
	v_mov_b64_e32 v[60:61], v[12:13]
	v_mov_b64_e32 v[58:59], v[10:11]
	v_mov_b64_e32 v[56:57], v[8:9]
	v_mov_b64_e32 v[54:55], v[6:7]
	v_mov_b64_e32 v[52:53], v[4:5]
	v_mov_b64_e32 v[50:51], v[2:3]
	v_mov_b64_e32 v[48:49], v[0:1]
	v_mov_b64_e32 v[76:77], v[12:13]
	v_mov_b64_e32 v[74:75], v[10:11]
	v_mov_b64_e32 v[72:73], v[8:9]
	v_mov_b64_e32 v[70:71], v[6:7]
	v_mov_b64_e32 v[68:69], v[4:5]
	v_mov_b64_e32 v[66:67], v[2:3]
	v_mov_b64_e32 v[64:65], v[0:1]
	v_mov_b64_e32 v[28:29], v[12:13]
	v_mov_b64_e32 v[26:27], v[10:11]
	v_mov_b64_e32 v[24:25], v[8:9]
	v_mov_b64_e32 v[22:23], v[6:7]
	v_mov_b64_e32 v[20:21], v[4:5]
	v_mov_b64_e32 v[18:19], v[2:3]
	v_mov_b64_e32 v[16:17], v[0:1]
	v_mov_b64_e32 v[44:45], v[12:13]
	v_mov_b64_e32 v[42:43], v[10:11]
	v_mov_b64_e32 v[40:41], v[8:9]
	v_mov_b64_e32 v[38:39], v[6:7]
	v_mov_b64_e32 v[36:37], v[4:5]
	v_mov_b64_e32 v[34:35], v[2:3]
	v_mov_b64_e32 v[32:33], v[0:1]
	s_waitcnt lgkmcnt(0)
	s_barrier

; #define SBAR() __builtin_amdgcn_sched_barrier(0)
; #define RESC(a) do { if (__any((a) < 1.f)) { if (hi == 0) al_l[r32] = (a); asm volatile("s_waitcnt lgkmcnt(0)" ::: "memory"); \
;     _Pragma("unroll") for (int d = 0; d < 4; ++d) _Pragma("unroll") for (int r = 0; r < 16; ++r) o[d][r] *= al_l[crow(r, hi)]; } } while (0)
; #define WACT(n) (WUKB(n) + 63 >= uqw - WIN && WUKB(n) <= uqw + 31 + WIN)
; #define WSLOAD(n) do { _Pragma("unroll") for (int i_ = 0; i_ < 4; ++i_) { int u_ = WUKB(n) + sr4 + 16 * i_; u_ = min(max(u_, 0), I.SU - 1); \
;       const bf16_t* rp_ = I.qkv + (size_t)(I.seq_base + clsw + I.dil * u_) * I.W + sc4; stv[i_] = LDG(bf16x8, rp_ + I.vcol); stk[i_] = LDG(bf16x8, rp_ + I.kcol); } } while (0)
; #define WSWRITE(b) do { _Pragma("unroll") for (int i_ = 0; i_ < 4; ++i_) { *(LAS bf16x8*)(Vh + (b) * SHM_V + v_st(sr4 + 16 * i_, sc4)) = stv[i_]; \
;       *(LAS bf16x8*)(Kh + (b) * SHM_K + KSWZ(sr4 + 16 * i_, sc4 * 2)) = stk[i_]; } } while (0)
; template <int WIN, bool ALIBI, int EPI, bool SINK>
; __device__ __forceinline__ void attn_item(const Item& I, char* lds, int tid_in) {
;     ...
;   for (int n = 0; n < NTw; ++n) { const int bsel = n & 1;
;     if (WACT(n)) { qkt(pA0, pA1, Kh + bsel * SHM_K, qr, r32, hi);
;       partialSM<WIN, ALIBI>(pA0, pA1, m_reg, mnA, alA, dq + (float)WUKB(n), I.nslope, lo, hi_, true); RESC(alA);
;       finishSM(pA0, pA1, alA, l_reg, pa0, pa1, pa2, pa3); SBAR(); pv_d0(o, vbh + bsel * SHM_V, pa0, pa1, pa2, pa3); }
;     if (n + 1 < NTw) { asm volatile("s_waitcnt vmcnt(0)" ::: "memory"); WSWRITE(bsel ^ 1); if (n + 2 < NTw) WSLOAD(n + 2); }
;     __syncthreads();
.LBB0_677:
	s_add_i32 s4, s49, 1
	s_cmp_ge_u32 s4, s6
	s_cbranch_scc1 .LBB0_680
	s_lshl_b32 s5, s27, 14
	s_waitcnt vmcnt(0)
	s_xor_b32 s5, s5, 0x4000
	v_add_u32_e32 v0, s5, v193
	v_add_u32_e32 v2, s5, v194
	s_add_i32 s5, s49, 2
	s_cmp_ge_u32 s5, s6
	ds_write_b128 v0, v[144:147]
	ds_write_b128 v2, v[148:151] offset:32768
	ds_write_b128 v0, v[152:155] offset:4096
	ds_write_b128 v2, v[156:159] offset:36864
	ds_write_b128 v0, v[160:163] offset:8192
	ds_write_b128 v2, v[164:167] offset:40960
	ds_write_b128 v0, v[168:171] offset:12288
	ds_write_b128 v2, v[172:175] offset:45056
	s_cbranch_scc1 .LBB0_680
	v_add_u32_e32 v0, s51, v208
	v_max_i32_e32 v2, 0, v0
	v_min_i32_e32 v2, s52, v2
	v_lshl_add_u32 v2, v2, 4, v184
	v_mad_i64_i32 v[2:3], s[28:29], v2, s89, v[178:179]
	s_mov_b32 s49, s73
	v_lshl_add_u64 v[4:5], v[2:3], 0, s[72:73]
	v_lshl_add_u64 v[2:3], v[2:3], 0, s[48:49]
	global_load_dwordx4 v[144:147], v[4:5], off
	global_load_dwordx4 v[148:151], v[2:3], off
	v_max_i32_e32 v2, -16, v0
	v_add_u32_e32 v2, 16, v2
	v_min_i32_e32 v2, s52, v2
	v_lshl_add_u32 v2, v2, 4, v184
	v_mad_i64_i32 v[2:3], s[28:29], v2, s89, v[178:179]
	v_lshl_add_u64 v[4:5], v[2:3], 0, s[72:73]
	v_lshl_add_u64 v[2:3], v[2:3], 0, s[48:49]
	global_load_dwordx4 v[152:155], v[4:5], off
	global_load_dwordx4 v[156:159], v[2:3], off
	v_max_i32_e32 v2, 0xffffffe0, v0
	v_add_u32_e32 v2, 32, v2
	v_min_i32_e32 v2, s52, v2
	v_max_i32_e32 v0, 0xffffffd0, v0
	v_lshl_add_u32 v2, v2, 4, v184
	v_add_u32_e32 v0, 48, v0
	v_mad_i64_i32 v[2:3], s[28:29], v2, s89, v[178:179]
	v_min_i32_e32 v0, s52, v0
	v_lshl_add_u64 v[4:5], v[2:3], 0, s[72:73]
	v_lshl_add_u64 v[2:3], v[2:3], 0, s[48:49]
	v_lshl_add_u32 v0, v0, 4, v184
	global_load_dwordx4 v[160:163], v[4:5], off
	global_load_dwordx4 v[164:167], v[2:3], off
	v_mad_i64_i32 v[2:3], s[28:29], v0, s89, v[178:179]
	v_lshl_add_u64 v[4:5], v[2:3], 0, s[72:73]
	v_lshl_add_u64 v[2:3], v[2:3], 0, s[48:49]
	global_load_dwordx4 v[168:171], v[4:5], off
	global_load_dwordx4 v[172:175], v[2:3], off

; __device__ __forceinline__ unsigned xb_ld(unsigned* p)              { return __hip_atomic_load(p, __ATOMIC_RELAXED, __HIP_MEMORY_SCOPE_AGENT); }
; __device__ __forceinline__ unsigned xb_add(unsigned* p, unsigned v) { return __hip_atomic_fetch_add(p, v, __ATOMIC_RELAXED, __HIP_MEMORY_SCOPE_AGENT); }
; #define XB_SPIN(cond, bar) do { unsigned _sp = 0; while (cond) { __builtin_amdgcn_s_sleep(1); \
;     if ((++_sp & 255u) == 0u) { if (xb_ld(&(bar)[XB_TMO])) break; if (_sp > XB_SPIN_CAP) { atomicAdd(&(bar)[XB_TMO], 1u); break; } } } } while (0)
; __device__ __forceinline__ void xcd_barrier(const XcdBarrier& b) {
;     ...
;             __builtin_amdgcn_fence(__ATOMIC_RELEASE, "agent");
;             asm volatile("s_waitcnt vmcnt(0)" ::: "memory");
;             const unsigned og = xb_add(&bar[XB_TOP], 1u);
;             const unsigned tg = og / nx;
;             if (og + 1u == (tg + 1u) * nx) xb_add(&bar[XB_TOPGEN], 1u);
;             else XB_SPIN(xb_ld(&bar[XB_TOPGEN]) == tg, bar);
;             __builtin_amdgcn_fence(__ATOMIC_ACQUIRE, "agent");
;             xb_add(&bar[XB_XGEN(b.x)], 1u);
;             asm volatile("s_waitcnt vmcnt(0)" ::: "memory");
;         } else {
;             XB_SPIN(xb_ld(&bar[XB_XGEN(b.x)]) == gen, bar);
;             __builtin_amdgcn_fence(__ATOMIC_ACQUIRE, "agent");
;             asm volatile("s_waitcnt vmcnt(0)" ::: "memory");
;         }
.LBB0_716:
	s_or_b64 exec, exec, s[6:7]
	s_waitcnt vmcnt(0)
	buffer_inv sc1
.LBB0_717:
	s_andn2_saveexec_b64 s[4:5], s[4:5]
	s_cbranch_execz .LBB0_737
	s_mov_b64 s[4:5], exec
	buffer_wbl2 sc1
	s_waitcnt lgkmcnt(0)
	s_waitcnt vmcnt(0)
	v_mbcnt_lo_u32_b32 v0, s4, 0
	v_mbcnt_hi_u32_b32 v0, s5, v0
	v_cmp_eq_u32_e32 vcc, 0, v0
	s_and_saveexec_b64 s[6:7], vcc
	s_cbranch_execz .LBB0_720
	s_bcnt1_i32_b64 s4, s[4:5]
	v_mov_b32_e32 v3, s4
	v_readlane_b32 s4, v255, 17
	v_readlane_b32 s5, v255, 18
	s_nop 4
	global_atomic_add v3, v1, v3, s[4:5] sc0

; __device__ __forceinline__ unsigned xb_ld(unsigned* p)              { return __hip_atomic_load(p, __ATOMIC_RELAXED, __HIP_MEMORY_SCOPE_AGENT); }
; __device__ __forceinline__ unsigned xb_add(unsigned* p, unsigned v) { return __hip_atomic_fetch_add(p, v, __ATOMIC_RELAXED, __HIP_MEMORY_SCOPE_AGENT); }
; #define XB_SPIN(cond, bar) do { unsigned _sp = 0; while (cond) { __builtin_amdgcn_s_sleep(1); \
;     if ((++_sp & 255u) == 0u) { if (xb_ld(&(bar)[XB_TMO])) break; if (_sp > XB_SPIN_CAP) { atomicAdd(&(bar)[XB_TMO], 1u); break; } } } } while (0)
; __device__ __forceinline__ void xcd_barrier(const XcdBarrier& b) {
;     ...
;             __builtin_amdgcn_fence(__ATOMIC_RELEASE, "agent");
;             asm volatile("s_waitcnt vmcnt(0)" ::: "memory");
;             const unsigned og = xb_add(&bar[XB_TOP], 1u);
;             const unsigned tg = og / nx;
;             if (og + 1u == (tg + 1u) * nx) xb_add(&bar[XB_TOPGEN], 1u);
;             else XB_SPIN(xb_ld(&bar[XB_TOPGEN]) == tg, bar);
;             __builtin_amdgcn_fence(__ATOMIC_ACQUIRE, "agent");
;             xb_add(&bar[XB_XGEN(b.x)], 1u);
;             asm volatile("s_waitcnt vmcnt(0)" ::: "memory");
;         } else {
;             XB_SPIN(xb_ld(&bar[XB_XGEN(b.x)]) == gen, bar);
;             __builtin_amdgcn_fence(__ATOMIC_ACQUIRE, "agent");
;             asm volatile("s_waitcnt vmcnt(0)" ::: "memory");
;         }
.LBB0_780:
	s_or_b64 exec, exec, s[6:7]
	s_waitcnt vmcnt(0)
	buffer_inv sc1
.LBB0_781:
	s_andn2_saveexec_b64 s[4:5], s[4:5]
	s_cbranch_execz .LBB0_801
	s_mov_b64 s[4:5], exec
	buffer_wbl2 sc1
	s_waitcnt lgkmcnt(0)
	s_waitcnt vmcnt(0)
	v_mbcnt_lo_u32_b32 v0, s4, 0
	v_mbcnt_hi_u32_b32 v0, s5, v0
	v_cmp_eq_u32_e32 vcc, 0, v0
	s_and_saveexec_b64 s[6:7], vcc
	s_cbranch_execz .LBB0_784
	s_bcnt1_i32_b64 s4, s[4:5]
	v_mov_b32_e32 v3, s4
	v_readlane_b32 s4, v255, 17
	v_readlane_b32 s5, v255, 18
	s_nop 4
	global_atomic_add v3, v1, v3, s[4:5] sc0

; #define LAS __attribute__((address_space(3)))
; __device__ __forceinline__ unsigned cvt_pk_bf16(float lo, float hi) { unsigned r; asm volatile("v_cvt_pk_bf16_f32 %0, %1, %2" : "=v"(r) : "v"(lo), "v"(hi)); return r; }
; __device__ __forceinline__ int crow(int r, int hi) { return (r & 3) + 8 * (r >> 2) + 4 * hi; }
; template <int EPI>
; __device__ __forceinline__ void attn_item_c(const Item& I, char* lds, int tid_in) {
;     ...
;   if (hi == 0) li_l[r32] = ((EPI == 3) ? ((LAS float*)(base + 133120))[wid] : 1.f) / l_reg;
;   asm volatile("s_waitcnt lgkmcnt(0)" ::: "memory");
;   const int tokw = I.seq_base + I.u0 + wid * 32;
;   constexpr int RB = (EPI == 3) ? 512 : 256;
;   LAS char* Sw = base + wid * (32 * RB);
;   const int rsub = lane >> 4, ch = lane & 15;
;   f32x4 dv[2][8][2];
; #pragma unroll
;   for (int half = 0; half < 2; ++half) {
;     f32x16* o = half ? oB : oA;
;     asm volatile("s_waitcnt lgkmcnt(0)" ::: "memory");
; #pragma unroll
;     for (int r = 0; r < 16; ++r) { const int orow = crow(r, hi); const float fq_ = li_l[orow];
; #pragma unroll
;       for (int d0 = 0; d0 < 4; ++d0) { const float v = o[d0][r] * fq_;
;         if constexpr (EPI == 3) *(LAS float*)(Sw + orow * RB + (d0 * 32 + r32) * 4) = v;
;         else *(LAS bf16_t*)(Sw + orow * RB + (d0 * 32 + r32) * 2) = (bf16_t)(cvt_pk_bf16(v, v) & 0xffffu); } }
.LBB0_809:
	s_or_b64 exec, exec, s[4:5]
	s_waitcnt lgkmcnt(0)
	s_lshl_b32 s4, s91, 14
	v_lshrrev_b32_e32 v148, 4, v244
	s_add_i32 s6, s4, 0
	v_lshlrev_b32_e32 v130, 9, v148
	v_lshlrev_b32_e32 v149, 5, v241
	v_add3_u32 v150, s6, v130, v149
	ds_read_b32 v130, v240
	v_lshl_add_u32 v0, v243, 2, s6
	v_lshl_add_u32 v158, v242, 11, v0
	v_lshl_add_u32 v159, v245, 9, v0
	v_add_u32_e32 v156, 0x400, v159
	s_waitcnt lgkmcnt(0)
	v_mul_f32_e32 v98, v98, v130
	v_mul_f32_e32 v114, v114, v130
	v_mul_f32_e32 v66, v66, v130
	v_mul_f32_e32 v82, v82, v130
	ds_write2_b32 v158, v98, v114 offset1:32
	ds_write2_b32 v158, v66, v82 offset0:64 offset1:96
	ds_read_b32 v66, v240 offset:4
	v_add_u32_e32 v157, 0x1000, v159
	v_add_u32_e32 v155, 0x1400, v159
	v_add_u32_e32 v154, 0x2000, v159
	v_add_u32_e32 v153, 0x2400, v159
	s_waitcnt lgkmcnt(0)
	v_mul_f32_e32 v82, v99, v66
	v_mul_f32_e32 v0, v115, v66
	ds_write2_b32 v159, v82, v0 offset0:128 offset1:160
	v_mul_f32_e32 v0, v67, v66
	v_mul_f32_e32 v66, v83, v66
	ds_write2_b32 v159, v0, v66 offset0:192 offset1:224
	ds_read_b32 v0, v240 offset:8
	v_add_u32_e32 v152, 0x3000, v159
	v_add_u32_e32 v151, 0x3400, v159
	s_add_i32 s40, s92, s87
	s_ashr_i32 s41, s40, 31
	s_waitcnt lgkmcnt(0)
	v_mul_f32_e32 v66, v100, v0
	v_mul_f32_e32 v67, v116, v0
	ds_write2_b32 v156, v66, v67 offset1:32
	v_mul_f32_e32 v66, v68, v0
	v_mul_f32_e32 v0, v84, v0
	ds_write2_b32 v156, v66, v0 offset0:64 offset1:96
	ds_read_b32 v0, v240 offset:12
	s_lshl_b64 s[4:5], s[40:41], 12
	s_add_u32 s4, s48, s4
	s_addc_u32 s5, s49, s5
	s_add_u32 s4, s4, s52
	s_waitcnt lgkmcnt(0)
	v_mul_f32_e32 v66, v101, v0
	v_mul_f32_e32 v67, v117, v0
	ds_write2_b32 v156, v66, v67 offset0:128 offset1:160
	v_mul_f32_e32 v66, v69, v0
	v_mul_f32_e32 v0, v85, v0
	ds_write2_b32 v156, v66, v0 offset0:192 offset1:224
	ds_read_b32 v0, v240 offset:32
	s_addc_u32 s5, s5, s53
	v_mov_b32_e32 v143, v1
	v_mov_b32_e32 v141, v1
	v_mov_b32_e32 v139, v1
	s_waitcnt lgkmcnt(0)
	v_mul_f32_e32 v66, v102, v0
	v_mul_f32_e32 v67, v118, v0
	ds_write2_b32 v157, v66, v67 offset1:32
	v_mul_f32_e32 v66, v70, v0
	v_mul_f32_e32 v0, v86, v0
	ds_write2_b32 v157, v66, v0 offset0:64 offset1:96
	ds_read_b32 v0, v240 offset:36
	v_mov_b32_e32 v137, v1
	v_mov_b32_e32 v131, v1
	v_mov_b32_e32 v133, v1
	v_mov_b32_e32 v135, v1
	s_waitcnt lgkmcnt(0)
	v_mul_f32_e32 v66, v103, v0
	v_mul_f32_e32 v67, v119, v0
	ds_write2_b32 v157, v66, v67 offset0:128 offset1:160
	v_mul_f32_e32 v66, v71, v0
	v_mul_f32_e32 v0, v87, v0
	ds_write2_b32 v157, v66, v0 offset0:192 offset1:224
	ds_read_b32 v0, v240 offset:40
	s_mov_b32 s87, 0xf800000
	v_mov_b32_e32 v227, 0x260
	s_add_i32 s62, s62, 1
	v_readlane_b32 s79, v255, 56
	s_waitcnt lgkmcnt(0)
	v_mul_f32_e32 v66, v104, v0
	v_mul_f32_e32 v67, v120, v0
	ds_write2_b32 v155, v66, v67 offset1:32
	v_mul_f32_e32 v66, v72, v0
	v_mul_f32_e32 v0, v88, v0
	ds_write2_b32 v155, v66, v0 offset0:64 offset1:96
	ds_read_b32 v0, v240 offset:44
	v_readlane_b32 s69, v255, 57
	s_movk_i32 s67, 0xa0
	s_mov_b32 s54, 0x30000
	s_mov_b32 s55, 0x10000
	s_waitcnt lgkmcnt(0)
	v_mul_f32_e32 v66, v105, v0
	v_mul_f32_e32 v67, v121, v0
	ds_write2_b32 v155, v66, v67 offset0:128 offset1:160
	v_mul_f32_e32 v66, v73, v0
	v_mul_f32_e32 v0, v89, v0
	ds_write2_b32 v155, v66, v0 offset0:192 offset1:224
	ds_read_b32 v0, v240 offset:64
	s_mov_b32 s58, 0x14000
	s_mov_b32 s59, 0x18000
	s_mov_b32 s63, 0x1c000
	s_mov_b32 s66, 0x20000
	s_waitcnt lgkmcnt(0)
	v_mul_f32_e32 v66, v106, v0
	v_mul_f32_e32 v67, v122, v0
	ds_write2_b32 v154, v66, v67 offset1:32
	v_mul_f32_e32 v66, v74, v0
	v_mul_f32_e32 v0, v90, v0
	ds_write2_b32 v154, v66, v0 offset0:64 offset1:96
	ds_read_b32 v0, v240 offset:68
	s_mov_b32 s56, 0x24000
	s_mov_b32 s57, 0x28000
	v_mov_b32_e32 v230, 0x42800000
	s_waitcnt lgkmcnt(0)
	v_mul_f32_e32 v66, v107, v0
	v_mul_f32_e32 v67, v123, v0
	ds_write2_b32 v154, v66, v67 offset0:128 offset1:160
	v_mul_f32_e32 v66, v75, v0
	v_mul_f32_e32 v0, v91, v0
	ds_write2_b32 v154, v66, v0 offset0:192 offset1:224
	ds_read_b32 v0, v240 offset:72
	s_waitcnt lgkmcnt(0)
	v_mul_f32_e32 v66, v108, v0
	v_mul_f32_e32 v67, v124, v0
	ds_write2_b32 v153, v66, v67 offset1:32
	v_mul_f32_e32 v66, v76, v0
	v_mul_f32_e32 v0, v92, v0
	ds_write2_b32 v153, v66, v0 offset0:64 offset1:96
	ds_read_b32 v0, v240 offset:76
	s_waitcnt lgkmcnt(0)
	v_mul_f32_e32 v66, v109, v0
	v_mul_f32_e32 v67, v125, v0
	ds_write2_b32 v153, v66, v67 offset0:128 offset1:160
	v_mul_f32_e32 v66, v77, v0
	v_mul_f32_e32 v0, v93, v0
	ds_write2_b32 v153, v66, v0 offset0:192 offset1:224
	ds_read_b32 v0, v240 offset:96
	s_waitcnt lgkmcnt(0)
	v_mul_f32_e32 v66, v110, v0
	v_mul_f32_e32 v67, v126, v0
	ds_write2_b32 v152, v66, v67 offset1:32
	v_mul_f32_e32 v66, v78, v0
	v_mul_f32_e32 v0, v94, v0
	ds_write2_b32 v152, v66, v0 offset0:64 offset1:96
	ds_read_b32 v0, v240 offset:100
	s_waitcnt lgkmcnt(0)
	v_mul_f32_e32 v66, v111, v0
	v_mul_f32_e32 v67, v127, v0
	ds_write2_b32 v152, v66, v67 offset0:128 offset1:160
	v_mul_f32_e32 v66, v79, v0
	v_mul_f32_e32 v0, v95, v0
	ds_write2_b32 v152, v66, v0 offset0:192 offset1:224
	ds_read_b32 v0, v240 offset:104
	s_waitcnt lgkmcnt(0)
	v_mul_f32_e32 v66, v112, v0
	v_mul_f32_e32 v67, v128, v0
	ds_write2_b32 v151, v66, v67 offset1:32
	v_mul_f32_e32 v66, v80, v0
	v_mul_f32_e32 v0, v96, v0
	ds_write2_b32 v151, v66, v0 offset0:64 offset1:96
	ds_read_b32 v0, v240 offset:108
	s_waitcnt lgkmcnt(0)
	v_mul_f32_e32 v66, v113, v0
	v_mul_f32_e32 v67, v129, v0
	ds_write2_b32 v151, v66, v67 offset0:128 offset1:160
	v_mul_f32_e32 v66, v81, v0
	v_mul_f32_e32 v0, v97, v0
	ds_write2_b32 v151, v66, v0 offset0:192 offset1:224
	v_lshlrev_b32_e32 v0, 4, v241
	v_lshl_add_u64 v[146:147], s[4:5], 0, v[0:1]
	v_lshlrev_b32_e32 v66, 12, v148
	v_mov_b32_e32 v67, v1
	s_waitcnt lgkmcnt(0)
; #define LAS __attribute__((address_space(3)))
; __device__ __forceinline__ unsigned cvt_pk_bf16(float lo, float hi) { unsigned r; asm volatile("v_cvt_pk_bf16_f32 %0, %1, %2" : "=v"(r) : "v"(lo), "v"(hi)); return r; }
; __device__ __forceinline__ float bf_lo(unsigned w) { return __uint_as_float(w << 16); }
; __device__ __forceinline__ float bf_hi(unsigned w) { return __uint_as_float(w & 0xffff0000u); }
; __device__ __forceinline__ int crow(int r, int hi) { return (r & 3) + 8 * (r >> 2) + 4 * hi; }
; template <int EPI>
; __device__ __forceinline__ void attn_item_c(const Item& I, char* lds, int tid_in) {
;     ...
;   f32x4 dv[2][8][2];
; #pragma unroll
;   for (int half = 0; half < 2; ++half) {
;     f32x16* o = half ? oB : oA;
;     asm volatile("s_waitcnt lgkmcnt(0)" ::: "memory");
; #pragma unroll
;     for (int r = 0; r < 16; ++r) { const int orow = crow(r, hi); const float fq_ = li_l[orow];
; #pragma unroll
;       for (int d0 = 0; d0 < 4; ++d0) { const float v = o[d0][r] * fq_;
;         if constexpr (EPI == 3) *(LAS float*)(Sw + orow * RB + (d0 * 32 + r32) * 4) = v;
;         else *(LAS bf16_t*)(Sw + orow * RB + (d0 * 32 + r32) * 2) = (bf16_t)(cvt_pk_bf16(v, v) & 0xffffu); } }
;     asm volatile("s_waitcnt lgkmcnt(0)" ::: "memory");
;     bf16_t* Orow = I.O + (size_t)tokw * DM + I.ocol + half * 128 + ch * 8;
;     if constexpr (EPI == 3) {
;       u32x4 oldv[8];
; #pragma unroll
;       for (int j = 0; j < 8; ++j) oldv[j] = LDG(u32x4, Orow + (size_t)(4 * j + rsub) * DM);
;       asm volatile("" ::: "memory");
; #pragma unroll
;       for (int j = 0; j < 8; ++j) { const int row = 4 * j + rsub;
;         const f32x4 a0 = *(const LAS f32x4*)(Sw + row * RB + ch * 32), a1 = *(const LAS f32x4*)(Sw + row * RB + ch * 32 + 16); const u32x4 ov = oldv[j];
;         dv[half][j][0] = (f32x4){bf_lo(ov.x) + a0[0], bf_hi(ov.x) + a0[1], bf_lo(ov.y) + a0[2], bf_hi(ov.y) + a0[3]};
;         dv[half][j][1] = (f32x4){bf_lo(ov.z) + a1[0], bf_hi(ov.z) + a1[1], bf_lo(ov.w) + a1[2], bf_hi(ov.w) + a1[3]}; }
	v_lshl_add_u64 v[144:145], v[146:147], 0, v[66:67]
	global_load_dwordx4 v[86:89], v[144:145], off
	v_or_b32_e32 v142, 0x4000, v66
	v_lshl_add_u64 v[68:69], v[146:147], 0, v[142:143]
	global_load_dwordx4 v[90:93], v[68:69], off
	v_or_b32_e32 v140, 0x8000, v66
	v_lshl_add_u64 v[68:69], v[146:147], 0, v[140:141]
	global_load_dwordx4 v[94:97], v[68:69], off
	v_or_b32_e32 v138, 0xc000, v66
	v_lshl_add_u64 v[68:69], v[146:147], 0, v[138:139]
	global_load_dwordx4 v[82:85], v[68:69], off
	v_or_b32_e32 v136, 0x10000, v66
	v_lshl_add_u64 v[68:69], v[146:147], 0, v[136:137]
	global_load_dwordx4 v[78:81], v[68:69], off
	v_or_b32_e32 v130, 0x14000, v66
	v_lshl_add_u64 v[68:69], v[146:147], 0, v[130:131]
	global_load_dwordx4 v[74:77], v[68:69], off
	v_or_b32_e32 v132, 0x18000, v66
	v_lshl_add_u64 v[68:69], v[146:147], 0, v[132:133]
	global_load_dwordx4 v[70:73], v[68:69], off
	v_or_b32_e32 v134, 0x1c000, v66
	v_lshl_add_u64 v[66:67], v[146:147], 0, v[134:135]
	global_load_dwordx4 v[66:69], v[66:67], off
	ds_read_b128 v[98:101], v150
	ds_read_b128 v[102:105], v150 offset:16
	s_mov_b32 s4, 0x3f077f5a
	s_waitcnt vmcnt(7)
	v_lshlrev_b32_e32 v106, 16, v86
	v_and_b32_e32 v107, 0xffff0000, v86
	v_lshlrev_b32_e32 v86, 16, v87
	v_and_b32_e32 v87, 0xffff0000, v87
	s_waitcnt lgkmcnt(1)
	v_pk_add_f32 v[124:125], v[100:101], v[86:87]
	v_lshlrev_b32_e32 v86, 16, v88
	v_and_b32_e32 v87, 0xffff0000, v88
	s_waitcnt lgkmcnt(0)
	v_pk_add_f32 v[126:127], v[102:103], v[86:87]
	v_lshlrev_b32_e32 v86, 16, v89
	v_and_b32_e32 v87, 0xffff0000, v89
	v_pk_add_f32 v[122:123], v[98:99], v[106:107]
	v_pk_add_f32 v[128:129], v[104:105], v[86:87]
	ds_read_b128 v[86:89], v150 offset:2048
	ds_read_b128 v[98:101], v150 offset:2064
	s_waitcnt vmcnt(6)
	v_lshlrev_b32_e32 v102, 16, v90
	v_and_b32_e32 v103, 0xffff0000, v90
	s_waitcnt lgkmcnt(1)
	v_pk_add_f32 v[114:115], v[86:87], v[102:103]
	v_lshlrev_b32_e32 v86, 16, v91
	v_and_b32_e32 v87, 0xffff0000, v91
	v_pk_add_f32 v[116:117], v[88:89], v[86:87]
	v_lshlrev_b32_e32 v86, 16, v92
	v_and_b32_e32 v87, 0xffff0000, v92
	s_waitcnt lgkmcnt(0)
	v_pk_add_f32 v[118:119], v[98:99], v[86:87]
	v_lshlrev_b32_e32 v86, 16, v93
	v_and_b32_e32 v87, 0xffff0000, v93
	v_pk_add_f32 v[120:121], v[100:101], v[86:87]
	ds_read_b128 v[86:89], v150 offset:4096
	ds_read_b128 v[90:93], v150 offset:4112
	s_waitcnt vmcnt(5)
	v_lshlrev_b32_e32 v98, 16, v94
	v_and_b32_e32 v99, 0xffff0000, v94
	s_waitcnt vmcnt(4)
	v_lshlrev_b32_e32 v94, 16, v82
	s_waitcnt lgkmcnt(1)
	v_pk_add_f32 v[106:107], v[86:87], v[98:99]
	v_lshlrev_b32_e32 v86, 16, v95
	v_and_b32_e32 v87, 0xffff0000, v95
	v_pk_add_f32 v[108:109], v[88:89], v[86:87]
	v_lshlrev_b32_e32 v86, 16, v96
	v_and_b32_e32 v87, 0xffff0000, v96
	s_waitcnt lgkmcnt(0)
	v_pk_add_f32 v[110:111], v[90:91], v[86:87]
	v_lshlrev_b32_e32 v86, 16, v97
	v_and_b32_e32 v87, 0xffff0000, v97
	v_pk_add_f32 v[112:113], v[92:93], v[86:87]
	ds_read_b128 v[86:89], v150 offset:6144
	ds_read_b128 v[90:93], v150 offset:6160
	v_and_b32_e32 v95, 0xffff0000, v82
	v_lshlrev_b32_e32 v82, 16, v83
	v_and_b32_e32 v83, 0xffff0000, v83
	s_waitcnt lgkmcnt(1)
	v_pk_add_f32 v[100:101], v[88:89], v[82:83]
	v_lshlrev_b32_e32 v82, 16, v84
	v_and_b32_e32 v83, 0xffff0000, v84
	s_waitcnt lgkmcnt(0)
	v_pk_add_f32 v[102:103], v[90:91], v[82:83]
	v_lshlrev_b32_e32 v82, 16, v85
	v_and_b32_e32 v83, 0xffff0000, v85
	v_pk_add_f32 v[98:99], v[86:87], v[94:95]
	v_pk_add_f32 v[104:105], v[92:93], v[82:83]
	ds_read_b128 v[82:85], v150 offset:8192
	ds_read_b128 v[86:89], v150 offset:8208
	s_waitcnt vmcnt(3)
	v_lshlrev_b32_e32 v90, 16, v78
	v_and_b32_e32 v91, 0xffff0000, v78
	v_lshlrev_b32_e32 v78, 16, v79
	v_and_b32_e32 v79, 0xffff0000, v79
	s_waitcnt lgkmcnt(1)
	v_pk_add_f32 v[92:93], v[84:85], v[78:79]
	v_lshlrev_b32_e32 v78, 16, v80
	v_and_b32_e32 v79, 0xffff0000, v80
	s_waitcnt lgkmcnt(0)
	v_pk_add_f32 v[94:95], v[86:87], v[78:79]
	v_lshlrev_b32_e32 v78, 16, v81
	v_and_b32_e32 v79, 0xffff0000, v81
	v_pk_add_f32 v[96:97], v[88:89], v[78:79]
	ds_read_b128 v[78:81], v150 offset:10240
	ds_read_b128 v[86:89], v150 offset:10256
	v_pk_add_f32 v[90:91], v[82:83], v[90:91]
	s_waitcnt vmcnt(2)
	v_lshlrev_b32_e32 v82, 16, v74
	v_and_b32_e32 v83, 0xffff0000, v74
	v_lshlrev_b32_e32 v74, 16, v75
	v_and_b32_e32 v75, 0xffff0000, v75
	s_waitcnt lgkmcnt(1)
	v_pk_add_f32 v[84:85], v[80:81], v[74:75]
	v_lshlrev_b32_e32 v74, 16, v76
	v_and_b32_e32 v75, 0xffff0000, v76
	s_waitcnt lgkmcnt(0)
	v_pk_add_f32 v[86:87], v[86:87], v[74:75]
	v_lshlrev_b32_e32 v74, 16, v77
	v_and_b32_e32 v75, 0xffff0000, v77
	v_pk_add_f32 v[82:83], v[78:79], v[82:83]
	v_pk_add_f32 v[88:89], v[88:89], v[74:75]
	ds_read_b128 v[74:77], v150 offset:12288
	ds_read_b128 v[78:81], v150 offset:12304
	s_waitcnt vmcnt(1)
	v_lshlrev_b32_e32 v160, 16, v70
	v_and_b32_e32 v161, 0xffff0000, v70
	v_lshlrev_b32_e32 v70, 16, v71
	v_and_b32_e32 v71, 0xffff0000, v71
	s_waitcnt lgkmcnt(1)
	v_pk_add_f32 v[76:77], v[76:77], v[70:71]
	v_lshlrev_b32_e32 v70, 16, v72
	v_and_b32_e32 v71, 0xffff0000, v72
	s_waitcnt lgkmcnt(0)
	v_pk_add_f32 v[78:79], v[78:79], v[70:71]
	v_lshlrev_b32_e32 v70, 16, v73
	v_and_b32_e32 v71, 0xffff0000, v73
	v_pk_add_f32 v[74:75], v[74:75], v[160:161]
	v_pk_add_f32 v[80:81], v[80:81], v[70:71]
	ds_read_b128 v[70:73], v150 offset:14336
	ds_read_b128 v[160:163], v150 offset:14352
	s_waitcnt vmcnt(0)
	v_lshlrev_b32_e32 v164, 16, v66
	v_and_b32_e32 v165, 0xffff0000, v66
	v_lshlrev_b32_e32 v66, 16, v67
	v_and_b32_e32 v67, 0xffff0000, v67
	s_waitcnt lgkmcnt(1)
	v_pk_add_f32 v[66:67], v[72:73], v[66:67]
	v_lshlrev_b32_e32 v72, 16, v68
	v_and_b32_e32 v73, 0xffff0000, v68
	s_waitcnt lgkmcnt(0)
; #define LAS __attribute__((address_space(3)))
; __device__ __forceinline__ unsigned cvt_pk_bf16(float lo, float hi) { unsigned r; asm volatile("v_cvt_pk_bf16_f32 %0, %1, %2" : "=v"(r) : "v"(lo), "v"(hi)); return r; }
; __device__ __forceinline__ float bf_lo(unsigned w) { return __uint_as_float(w << 16); }
; __device__ __forceinline__ float bf_hi(unsigned w) { return __uint_as_float(w & 0xffff0000u); }
; __device__ __forceinline__ int crow(int r, int hi) { return (r & 3) + 8 * (r >> 2) + 4 * hi; }
; template <int EPI>
; __device__ __forceinline__ void attn_item_c(const Item& I, char* lds, int tid_in) {
;     ...
;   for (int half = 0; half < 2; ++half) {
;     f32x16* o = half ? oB : oA;
;     asm volatile("s_waitcnt lgkmcnt(0)" ::: "memory");
; #pragma unroll
;     for (int r = 0; r < 16; ++r) { const int orow = crow(r, hi); const float fq_ = li_l[orow];
; #pragma unroll
;       for (int d0 = 0; d0 < 4; ++d0) { const float v = o[d0][r] * fq_;
;         if constexpr (EPI == 3) *(LAS float*)(Sw + orow * RB + (d0 * 32 + r32) * 4) = v;
;         else *(LAS bf16_t*)(Sw + orow * RB + (d0 * 32 + r32) * 2) = (bf16_t)(cvt_pk_bf16(v, v) & 0xffffu); } }
;     asm volatile("s_waitcnt lgkmcnt(0)" ::: "memory");
;     bf16_t* Orow = I.O + (size_t)tokw * DM + I.ocol + half * 128 + ch * 8;
;     if constexpr (EPI == 3) {
;       u32x4 oldv[8];
; #pragma unroll
;       for (int j = 0; j < 8; ++j) oldv[j] = LDG(u32x4, Orow + (size_t)(4 * j + rsub) * DM);
;       asm volatile("" ::: "memory");
; #pragma unroll
;       for (int j = 0; j < 8; ++j) { const int row = 4 * j + rsub;
;         const f32x4 a0 = *(const LAS f32x4*)(Sw + row * RB + ch * 32), a1 = *(const LAS f32x4*)(Sw + row * RB + ch * 32 + 16); const u32x4 ov = oldv[j];
;         dv[half][j][0] = (f32x4){bf_lo(ov.x) + a0[0], bf_hi(ov.x) + a0[1], bf_lo(ov.y) + a0[2], bf_hi(ov.y) + a0[3]};
;         dv[half][j][1] = (f32x4){bf_lo(ov.z) + a1[0], bf_hi(ov.z) + a1[1], bf_lo(ov.w) + a1[2], bf_hi(ov.w) + a1[3]}; }
	v_pk_add_f32 v[72:73], v[160:161], v[72:73]
	ds_read_b32 v160, v240
	v_pk_add_f32 v[70:71], v[70:71], v[164:165]
	v_lshlrev_b32_e32 v68, 16, v69
	v_and_b32_e32 v69, 0xffff0000, v69
	v_pk_add_f32 v[68:69], v[162:163], v[68:69]
	s_waitcnt lgkmcnt(0)
	v_mul_f32_e32 v2, v2, v160
	v_mul_f32_e32 v50, v50, v160
	ds_write2_b32 v158, v2, v50 offset1:32
	v_mul_f32_e32 v2, v18, v160
	v_mul_f32_e32 v18, v34, v160
	ds_write2_b32 v158, v2, v18 offset0:64 offset1:96
	ds_read_b32 v2, v240 offset:4
	s_waitcnt lgkmcnt(0)
	v_mul_f32_e32 v3, v3, v2
	v_mul_f32_e32 v18, v51, v2
	ds_write2_b32 v159, v3, v18 offset0:128 offset1:160
	v_mul_f32_e32 v3, v19, v2
	v_mul_f32_e32 v2, v35, v2
	ds_write2_b32 v159, v3, v2 offset0:192 offset1:224
	ds_read_b32 v2, v240 offset:8
	s_waitcnt lgkmcnt(0)
	v_mul_f32_e32 v3, v4, v2
	v_mul_f32_e32 v4, v52, v2
	ds_write2_b32 v156, v3, v4 offset1:32
	v_mul_f32_e32 v3, v20, v2
	v_mul_f32_e32 v2, v36, v2
	ds_write2_b32 v156, v3, v2 offset0:64 offset1:96
	ds_read_b32 v2, v240 offset:12
	s_waitcnt lgkmcnt(0)
	v_mul_f32_e32 v3, v5, v2
	v_mul_f32_e32 v4, v53, v2
	ds_write2_b32 v156, v3, v4 offset0:128 offset1:160
	v_mul_f32_e32 v3, v21, v2
	v_mul_f32_e32 v2, v37, v2
	ds_write2_b32 v156, v3, v2 offset0:192 offset1:224
	ds_read_b32 v2, v240 offset:32
	s_waitcnt lgkmcnt(0)
	v_mul_f32_e32 v3, v6, v2
	v_mul_f32_e32 v4, v54, v2
	ds_write2_b32 v157, v3, v4 offset1:32
	v_mul_f32_e32 v3, v22, v2
	v_mul_f32_e32 v2, v38, v2
	ds_write2_b32 v157, v3, v2 offset0:64 offset1:96
	ds_read_b32 v2, v240 offset:36
	s_waitcnt lgkmcnt(0)
	v_mul_f32_e32 v3, v7, v2
	v_mul_f32_e32 v4, v55, v2
	ds_write2_b32 v157, v3, v4 offset0:128 offset1:160
	v_mul_f32_e32 v3, v23, v2
	v_mul_f32_e32 v2, v39, v2
	ds_write2_b32 v157, v3, v2 offset0:192 offset1:224
	ds_read_b32 v2, v240 offset:40
	s_waitcnt lgkmcnt(0)
	v_mul_f32_e32 v3, v8, v2
	v_mul_f32_e32 v4, v56, v2
	ds_write2_b32 v155, v3, v4 offset1:32
	v_mul_f32_e32 v3, v24, v2
	v_mul_f32_e32 v2, v40, v2
	ds_write2_b32 v155, v3, v2 offset0:64 offset1:96
	ds_read_b32 v2, v240 offset:44
	s_waitcnt lgkmcnt(0)
	v_mul_f32_e32 v3, v9, v2
	v_mul_f32_e32 v4, v57, v2
	ds_write2_b32 v155, v3, v4 offset0:128 offset1:160
	v_mul_f32_e32 v3, v25, v2
	v_mul_f32_e32 v2, v41, v2
	ds_write2_b32 v155, v3, v2 offset0:192 offset1:224
	ds_read_b32 v2, v240 offset:64
	s_waitcnt lgkmcnt(0)
	v_mul_f32_e32 v3, v10, v2
	v_mul_f32_e32 v4, v58, v2
	ds_write2_b32 v154, v3, v4 offset1:32
	v_mul_f32_e32 v3, v26, v2
	v_mul_f32_e32 v2, v42, v2
	ds_write2_b32 v154, v3, v2 offset0:64 offset1:96
	ds_read_b32 v2, v240 offset:68
	s_waitcnt lgkmcnt(0)
	v_mul_f32_e32 v3, v11, v2
	v_mul_f32_e32 v4, v59, v2
	ds_write2_b32 v154, v3, v4 offset0:128 offset1:160
	v_mul_f32_e32 v3, v27, v2
	v_mul_f32_e32 v2, v43, v2
	ds_write2_b32 v154, v3, v2 offset0:192 offset1:224
	ds_read_b32 v2, v240 offset:72
	s_waitcnt lgkmcnt(0)
	v_mul_f32_e32 v3, v12, v2
	v_mul_f32_e32 v4, v60, v2
	ds_write2_b32 v153, v3, v4 offset1:32
	v_mul_f32_e32 v3, v28, v2
	v_mul_f32_e32 v2, v44, v2
	ds_write2_b32 v153, v3, v2 offset0:64 offset1:96
	ds_read_b32 v2, v240 offset:76
	s_waitcnt lgkmcnt(0)
	v_mul_f32_e32 v3, v13, v2
	v_mul_f32_e32 v4, v61, v2
	ds_write2_b32 v153, v3, v4 offset0:128 offset1:160
	v_mul_f32_e32 v3, v29, v2
	v_mul_f32_e32 v2, v45, v2
	ds_write2_b32 v153, v3, v2 offset0:192 offset1:224
	ds_read_b32 v2, v240 offset:96
	s_waitcnt lgkmcnt(0)
	v_mul_f32_e32 v3, v14, v2
	v_mul_f32_e32 v4, v62, v2
	ds_write2_b32 v152, v3, v4 offset1:32
	v_mul_f32_e32 v3, v30, v2
	v_mul_f32_e32 v2, v46, v2
	ds_write2_b32 v152, v3, v2 offset0:64 offset1:96
	ds_read_b32 v2, v240 offset:100
	s_waitcnt lgkmcnt(0)
	v_mul_f32_e32 v3, v15, v2
	v_mul_f32_e32 v4, v63, v2
	ds_write2_b32 v152, v3, v4 offset0:128 offset1:160
	v_mul_f32_e32 v3, v31, v2
	v_mul_f32_e32 v2, v47, v2
	ds_write2_b32 v152, v3, v2 offset0:192 offset1:224
	ds_read_b32 v2, v240 offset:104
	v_lshl_add_u64 v[14:15], v[146:147], 0, s[76:77]
	v_lshl_add_u64 v[6:7], v[14:15], 0, v[142:143]
	v_lshl_add_u64 v[10:11], v[14:15], 0, v[140:141]
	v_lshl_add_u64 v[20:21], v[14:15], 0, v[136:137]
	s_waitcnt lgkmcnt(0)
	v_mul_f32_e32 v3, v16, v2
	v_mul_f32_e32 v4, v64, v2
	ds_write2_b32 v151, v3, v4 offset1:32
	v_mul_f32_e32 v3, v32, v2
	v_mul_f32_e32 v2, v48, v2
	ds_write2_b32 v151, v3, v2 offset0:64 offset1:96
	ds_read_b32 v2, v240 offset:108
	v_lshl_add_u64 v[24:25], v[14:15], 0, v[130:131]
	v_lshl_add_u64 v[28:29], v[14:15], 0, v[132:133]
	s_waitcnt lgkmcnt(0)
	v_mul_f32_e32 v3, v17, v2
	v_mul_f32_e32 v4, v65, v2
	ds_write2_b32 v151, v3, v4 offset0:128 offset1:160
	v_mul_f32_e32 v3, v33, v2
	v_mul_f32_e32 v2, v49, v2
	ds_write2_b32 v151, v3, v2 offset0:192 offset1:224
	s_waitcnt lgkmcnt(0)
	global_load_dwordx4 v[2:5], v[144:145], off offset:256
	global_load_dwordx4 v[32:35], v[28:29], off
	v_lshl_add_u64 v[16:17], v[14:15], 0, v[138:139]
	global_load_dwordx4 v[6:9], v[6:7], off
	v_lshl_add_u64 v[14:15], v[14:15], 0, v[134:135]
	global_load_dwordx4 v[10:13], v[10:11], off
	s_nop 0
	global_load_dwordx4 v[16:19], v[16:17], off
	s_nop 0
	global_load_dwordx4 v[152:155], v[14:15], off
	s_waitcnt vmcnt(5)
	v_lshlrev_b32_e32 v14, 16, v2
	global_load_dwordx4 v[20:23], v[20:21], off
	v_and_b32_e32 v15, 0xffff0000, v2
	global_load_dwordx4 v[24:27], v[24:25], off
	ds_read_b128 v[28:31], v150
	ds_read_b128 v[36:39], v150 offset:16
	v_lshlrev_b32_e32 v2, 16, v3
	v_and_b32_e32 v3, 0xffff0000, v3
	s_waitcnt lgkmcnt(1)
	v_pk_add_f32 v[142:143], v[30:31], v[2:3]
	v_lshlrev_b32_e32 v2, 16, v4
	v_and_b32_e32 v3, 0xffff0000, v4
	s_waitcnt lgkmcnt(0)
; #define LAS __attribute__((address_space(3)))
; __device__ __forceinline__ float bf_lo(unsigned w) { return __uint_as_float(w << 16); }
; __device__ __forceinline__ float bf_hi(unsigned w) { return __uint_as_float(w & 0xffff0000u); }
; template <int EPI>
; __device__ __forceinline__ void attn_item_c(const Item& I, char* lds, int tid_in) {
;     ...
;     if constexpr (EPI == 3) {
;       u32x4 oldv[8];
; #pragma unroll
;       for (int j = 0; j < 8; ++j) oldv[j] = LDG(u32x4, Orow + (size_t)(4 * j + rsub) * DM);
;       asm volatile("" ::: "memory");
; #pragma unroll
;       for (int j = 0; j < 8; ++j) { const int row = 4 * j + rsub;
;         const f32x4 a0 = *(const LAS f32x4*)(Sw + row * RB + ch * 32), a1 = *(const LAS f32x4*)(Sw + row * RB + ch * 32 + 16); const u32x4 ov = oldv[j];
;         dv[half][j][0] = (f32x4){bf_lo(ov.x) + a0[0], bf_hi(ov.x) + a0[1], bf_lo(ov.y) + a0[2], bf_hi(ov.y) + a0[3]};
;         dv[half][j][1] = (f32x4){bf_lo(ov.z) + a1[0], bf_hi(ov.z) + a1[1], bf_lo(ov.w) + a1[2], bf_hi(ov.w) + a1[3]}; }
;     } else {
; #pragma unroll
;       for (int j = 0; j < 8; ++j) { const int row = 4 * j + rsub; const u32x4 w = *(const LAS u32x4*)(Sw + row * RB + ch * 16);
;         STG(u32x4, Orow + (size_t)row * DM) = w; }
;     }
;   }
;   if constexpr (EPI == 3) {
;     f32x4 gsl[2][2];
; #pragma unroll
;     for (int half = 0; half < 2; ++half) { gsl[half][0] = LDG(f32x4, I.subg + half * 128 + ch * 8) * (1.f - LAM_INIT2); gsl[half][1] = LDG(f32x4, I.subg + half * 128 + ch * 8 + 4) * (1.f - LAM_INIT2); }
	v_pk_add_f32 v[144:145], v[36:37], v[2:3]
	v_lshlrev_b32_e32 v2, 16, v5
	v_and_b32_e32 v3, 0xffff0000, v5
	v_pk_add_f32 v[140:141], v[28:29], v[14:15]
	v_pk_add_f32 v[146:147], v[38:39], v[2:3]
	ds_read_b128 v[2:5], v150 offset:2048
	ds_read_b128 v[28:31], v150 offset:2064
	s_waitcnt vmcnt(5)
	v_lshlrev_b32_e32 v14, 16, v6
	v_and_b32_e32 v15, 0xffff0000, v6
	v_pk_mul_f32 v[156:157], v[144:145], v[144:145]
	s_waitcnt lgkmcnt(1)
	v_pk_add_f32 v[132:133], v[2:3], v[14:15]
	v_lshlrev_b32_e32 v2, 16, v7
	v_and_b32_e32 v3, 0xffff0000, v7
	v_pk_add_f32 v[134:135], v[4:5], v[2:3]
	v_lshlrev_b32_e32 v2, 16, v8
	v_and_b32_e32 v3, 0xffff0000, v8
	s_waitcnt lgkmcnt(0)
	v_pk_add_f32 v[136:137], v[28:29], v[2:3]
	v_lshlrev_b32_e32 v2, 16, v9
	v_and_b32_e32 v3, 0xffff0000, v9
	v_pk_add_f32 v[138:139], v[30:31], v[2:3]
	ds_read_b128 v[2:5], v150 offset:4096
	ds_read_b128 v[6:9], v150 offset:4112
	s_waitcnt vmcnt(4)
	v_lshlrev_b32_e32 v14, 16, v10
	v_and_b32_e32 v15, 0xffff0000, v10
	s_waitcnt vmcnt(3)
	v_lshlrev_b32_e32 v10, 16, v16
	s_waitcnt lgkmcnt(1)
	v_pk_add_f32 v[60:61], v[2:3], v[14:15]
	v_lshlrev_b32_e32 v2, 16, v11
	v_and_b32_e32 v3, 0xffff0000, v11
	v_pk_add_f32 v[62:63], v[4:5], v[2:3]
	v_lshlrev_b32_e32 v2, 16, v12
	v_and_b32_e32 v3, 0xffff0000, v12
	s_waitcnt lgkmcnt(0)
	v_pk_add_f32 v[64:65], v[6:7], v[2:3]
	v_lshlrev_b32_e32 v2, 16, v13
	v_and_b32_e32 v3, 0xffff0000, v13
	v_pk_add_f32 v[130:131], v[8:9], v[2:3]
	ds_read_b128 v[2:5], v150 offset:6144
	ds_read_b128 v[6:9], v150 offset:6160
	v_and_b32_e32 v11, 0xffff0000, v16
	v_pk_mul_f32 v[158:159], v[146:147], v[146:147]
	s_waitcnt lgkmcnt(1)
	v_pk_add_f32 v[52:53], v[2:3], v[10:11]
	v_lshlrev_b32_e32 v2, 16, v17
	v_and_b32_e32 v3, 0xffff0000, v17
	v_pk_add_f32 v[54:55], v[4:5], v[2:3]
	v_lshlrev_b32_e32 v2, 16, v18
	v_and_b32_e32 v3, 0xffff0000, v18
	s_waitcnt lgkmcnt(0)
	v_pk_add_f32 v[56:57], v[6:7], v[2:3]
	v_lshlrev_b32_e32 v2, 16, v19
	v_and_b32_e32 v3, 0xffff0000, v19
	v_pk_add_f32 v[58:59], v[8:9], v[2:3]
	ds_read_b128 v[2:5], v150 offset:8192
	ds_read_b128 v[6:9], v150 offset:8208
	s_waitcnt vmcnt(1)
	v_lshlrev_b32_e32 v10, 16, v20
	v_and_b32_e32 v11, 0xffff0000, v20
	s_waitcnt lgkmcnt(1)
	v_pk_add_f32 v[44:45], v[2:3], v[10:11]
	v_lshlrev_b32_e32 v2, 16, v21
	v_and_b32_e32 v3, 0xffff0000, v21
	v_pk_add_f32 v[46:47], v[4:5], v[2:3]
	v_lshlrev_b32_e32 v2, 16, v22
	v_and_b32_e32 v3, 0xffff0000, v22
	s_waitcnt lgkmcnt(0)
	v_pk_add_f32 v[48:49], v[6:7], v[2:3]
	v_lshlrev_b32_e32 v2, 16, v23
	v_and_b32_e32 v3, 0xffff0000, v23
	v_pk_add_f32 v[50:51], v[8:9], v[2:3]
	ds_read_b128 v[2:5], v150 offset:10240
	ds_read_b128 v[6:9], v150 offset:10256
	s_waitcnt vmcnt(0)
	v_lshlrev_b32_e32 v10, 16, v24
	v_and_b32_e32 v11, 0xffff0000, v24
	s_waitcnt lgkmcnt(1)
	v_pk_add_f32 v[36:37], v[2:3], v[10:11]
	v_lshlrev_b32_e32 v2, 16, v25
	v_and_b32_e32 v3, 0xffff0000, v25
	v_pk_add_f32 v[38:39], v[4:5], v[2:3]
	v_lshlrev_b32_e32 v2, 16, v26
	v_and_b32_e32 v3, 0xffff0000, v26
	s_waitcnt lgkmcnt(0)
	v_pk_add_f32 v[40:41], v[6:7], v[2:3]
	v_lshlrev_b32_e32 v2, 16, v27
	v_and_b32_e32 v3, 0xffff0000, v27
	v_pk_add_f32 v[42:43], v[8:9], v[2:3]
	ds_read_b128 v[2:5], v150 offset:12288
	ds_read_b128 v[6:9], v150 offset:12304
	v_lshlrev_b32_e32 v10, 16, v32
	v_and_b32_e32 v11, 0xffff0000, v32
	v_add_u32_e32 v26, s40, v148
	s_waitcnt lgkmcnt(1)
	v_pk_add_f32 v[28:29], v[2:3], v[10:11]
	v_lshlrev_b32_e32 v2, 16, v33
	v_and_b32_e32 v3, 0xffff0000, v33
	v_pk_add_f32 v[30:31], v[4:5], v[2:3]
	v_lshlrev_b32_e32 v2, 16, v34
	v_and_b32_e32 v3, 0xffff0000, v34
	s_waitcnt lgkmcnt(0)
	v_pk_add_f32 v[32:33], v[6:7], v[2:3]
	v_lshlrev_b32_e32 v2, 16, v35
	v_and_b32_e32 v3, 0xffff0000, v35
	v_pk_add_f32 v[34:35], v[8:9], v[2:3]
	ds_read_b128 v[2:5], v150 offset:14336
	ds_read_b128 v[6:9], v150 offset:14352
	global_load_dwordx4 v[18:21], v149, s[50:51] offset:16
	global_load_dwordx4 v[12:15], v149, s[50:51]
	v_lshlrev_b32_e32 v10, 16, v152
	v_and_b32_e32 v11, 0xffff0000, v152
	s_waitcnt lgkmcnt(1)
	v_pk_add_f32 v[2:3], v[2:3], v[10:11]
	v_lshlrev_b32_e32 v10, 16, v153
	v_and_b32_e32 v11, 0xffff0000, v153
	v_pk_add_f32 v[4:5], v[4:5], v[10:11]
	v_lshlrev_b32_e32 v10, 16, v154
	v_and_b32_e32 v11, 0xffff0000, v154
	s_waitcnt lgkmcnt(0)
	v_pk_add_f32 v[6:7], v[6:7], v[10:11]
	v_lshlrev_b32_e32 v10, 16, v155
	v_and_b32_e32 v11, 0xffff0000, v155
	v_pk_add_f32 v[8:9], v[8:9], v[10:11]
	v_mov_b32_e32 v148, v122
	v_mul_f32_e32 v154, v143, v143
	v_pk_fma_f32 v[154:155], v[142:143], v[142:143], v[154:155] op_sel_hi:[1,1,0]
	s_waitcnt vmcnt(1)
	v_pk_mul_f32 v[10:11], v[18:19], s[4:5] op_sel_hi:[1,0]
	s_waitcnt vmcnt(0)
	v_pk_mul_f32 v[16:17], v[14:15], s[4:5] op_sel_hi:[1,0]
	v_pk_mul_f32 v[14:15], v[20:21], s[4:5] op_sel_hi:[1,0]
	global_load_dwordx4 v[150:153], v149, s[50:51] offset:528
	global_load_dwordx4 v[20:23], v149, s[50:51] offset:512
	v_mov_b32_e32 v149, v124
	v_mov_b32_e32 v155, v159
	v_pk_mul_f32 v[12:13], v[12:13], s[4:5] op_sel_hi:[1,0]
	s_waitcnt vmcnt(1)
	v_pk_mul_f32 v[18:19], v[150:151], s[4:5] op_sel_hi:[1,0]
	v_mov_b32_e32 v150, v123
	v_mov_b32_e32 v151, v125
	s_waitcnt vmcnt(0)
; __device__ __forceinline__ unsigned cvt_pk_bf16(float lo, float hi) { unsigned r; asm volatile("v_cvt_pk_bf16_f32 %0, %1, %2" : "=v"(r) : "v"(lo), "v"(hi)); return r; }
; template <int O> __device__ __forceinline__ float swz_xor(float v) { return __int_as_float(__builtin_amdgcn_ds_swizzle(__float_as_int(v), (O << 10) | 0x1F)); }
; template <int EPI>
; __device__ __forceinline__ void attn_item_c(const Item& I, char* lds, int tid_in) {
;     ...
; #pragma unroll
;     for (int j = 0; j < 8; ++j) { float ss = 0.f;
; #pragma unroll
;       for (int half = 0; half < 2; ++half)
; #pragma unroll
;         for (int q = 0; q < 2; ++q) { const f32x4 d = dv[half][j][q]; ss += (d[0] * d[0] + d[1] * d[1]) + (d[2] * d[2] + d[3] * d[3]); }
;       ss += swz_xor<1>(ss); ss += swz_xor<2>(ss); ss += swz_xor<4>(ss); ss += swz_xor<8>(ss);
;       const float rstd = 1.0f / sqrtf(ss * (1.f / 256.f) + EPS);
; #pragma unroll
;       for (int half = 0; half < 2; ++half) { const f32x4 y0 = dv[half][j][0] * rstd * gsl[half][0], y1 = dv[half][j][1] * rstd * gsl[half][1];
;         u32x4 w; w.x = cvt_pk_bf16(y0[0], y0[1]); w.y = cvt_pk_bf16(y0[2], y0[3]); w.z = cvt_pk_bf16(y1[0], y1[1]); w.w = cvt_pk_bf16(y1[2], y1[3]);
;         STG(u32x4, I.O + (size_t)(tokw + 4 * j + rsub) * DM + I.ocol + half * 128 + ch * 8) = w; } }
	v_pk_mul_f32 v[24:25], v[22:23], s[4:5] op_sel_hi:[1,0]
	v_pk_mul_f32 v[22:23], v[152:153], s[4:5] op_sel_hi:[1,0]
	v_pk_mul_f32 v[150:151], v[150:151], v[150:151]
	v_mov_b32_e32 v152, v127
	v_mov_b32_e32 v153, v129
	v_pk_fma_f32 v[148:149], v[148:149], v[148:149], v[150:151]
	v_mov_b32_e32 v150, v126
	v_mov_b32_e32 v151, v128
	v_pk_mul_f32 v[152:153], v[152:153], v[152:153]
	v_pk_add_f32 v[148:149], v[148:149], v[148:149] op_sel:[0,1] op_sel_hi:[1,0]
	v_pk_fma_f32 v[150:151], v[150:151], v[150:151], v[152:153]
	v_mul_f32_e32 v152, v141, v141
	v_pk_add_f32 v[150:151], v[150:151], v[150:151] op_sel:[0,1] op_sel_hi:[1,0]
	v_pk_fma_f32 v[152:153], v[140:141], v[140:141], v[152:153] op_sel_hi:[1,1,0]
	v_mov_b32_e32 v149, v156
	v_mov_b32_e32 v151, v157
	v_mov_b32_e32 v153, v158
	v_pk_add_f32 v[148:149], v[148:149], v[150:151]
	v_pk_add_f32 v[150:151], v[152:153], v[154:155]
	v_pk_mul_f32 v[20:21], v[20:21], s[4:5] op_sel_hi:[1,0]
	v_pk_add_f32 v[148:149], v[148:149], v[150:151]
	s_nop 0
	v_add_f32_e32 v27, v148, v149
	ds_swizzle_b32 v148, v27 offset:swizzle(SWAP,1)
	s_waitcnt lgkmcnt(0)
	v_add_f32_e32 v27, v27, v148
	ds_swizzle_b32 v148, v27 offset:swizzle(SWAP,2)
	s_waitcnt lgkmcnt(0)
	v_add_f32_e32 v27, v27, v148
	ds_swizzle_b32 v148, v27 offset:swizzle(SWAP,4)
	s_waitcnt lgkmcnt(0)
	v_add_f32_e32 v27, v27, v148
	ds_swizzle_b32 v148, v27 offset:swizzle(SWAP,8)
	s_waitcnt lgkmcnt(0)
	v_add_f32_e32 v27, v27, v148
	v_fmamk_f32 v27, v27, 0x3b800000, v226
	v_cmp_gt_f32_e32 vcc, s87, v27
	v_mul_f32_e32 v148, 0x4f800000, v27
	s_nop 0
	v_cndmask_b32_e32 v27, v27, v148, vcc
	v_sqrt_f32_e32 v148, v27
	s_nop 0
	v_add_u32_e32 v149, -1, v148
	v_fma_f32 v150, -v149, v148, v27
	v_cmp_ge_f32_e64 s[40:41], 0, v150
	v_add_u32_e32 v150, 1, v148
	s_nop 0
	v_cndmask_b32_e64 v149, v148, v149, s[40:41]
	v_fma_f32 v148, -v150, v148, v27
	v_cmp_lt_f32_e64 s[40:41], 0, v148
	s_nop 1
	v_cndmask_b32_e64 v148, v149, v150, s[40:41]
	v_mul_f32_e32 v149, 0x37800000, v148
	v_cndmask_b32_e32 v148, v148, v149, vcc
	v_cmp_class_f32_e32 vcc, v27, v227
	s_nop 1
	v_cndmask_b32_e32 v27, v148, v27, vcc
	v_div_scale_f32 v148, s[4:5], v27, v27, 1.0
	v_rcp_f32_e32 v149, v148
	s_nop 0
	v_fma_f32 v150, -v148, v149, 1.0
	v_fmac_f32_e32 v149, v150, v149
	v_div_scale_f32 v150, vcc, 1.0, v27, 1.0
	v_mul_f32_e32 v151, v150, v149
	v_fma_f32 v152, -v148, v151, v150
	v_fmac_f32_e32 v151, v152, v149
	v_fma_f32 v148, -v148, v151, v150
	v_div_fmas_f32 v148, v148, v149, v151
	v_div_fixup_f32 v148, v148, v27, 1.0
	v_ashrrev_i32_e32 v27, 31, v26
	v_pk_mul_f32 v[122:123], v[122:123], v[148:149] op_sel_hi:[1,0]
	v_pk_mul_f32 v[124:125], v[124:125], v[148:149] op_sel_hi:[1,0]
	v_pk_mul_f32 v[126:127], v[126:127], v[148:149] op_sel_hi:[1,0]
	v_lshlrev_b64 v[150:151], 12, v[26:27]
	v_pk_mul_f32 v[124:125], v[16:17], v[124:125]
	v_pk_mul_f32 v[122:123], v[12:13], v[122:123]
	v_pk_mul_f32 v[126:127], v[10:11], v[126:127]
	v_cvt_pk_bf16_f32 v122, v122, v123
	v_cvt_pk_bf16_f32 v123, v124, v125
	v_pk_mul_f32 v[128:129], v[128:129], v[148:149] op_sel_hi:[1,0]
	v_cvt_pk_bf16_f32 v124, v126, v127
	v_lshl_add_u64 v[126:127], s[48:49], 0, v[150:151]
	v_lshl_add_u64 v[126:127], v[126:127], 0, s[52:53]
	v_pk_mul_f32 v[128:129], v[14:15], v[128:129]
	v_lshl_add_u64 v[126:127], v[126:127], 0, v[0:1]
	v_cvt_pk_bf16_f32 v125, v128, v129
	global_store_dwordx4 v[126:127], v[122:125], off
	v_pk_mul_f32 v[128:129], v[144:145], v[148:149] op_sel_hi:[1,0]
	s_nop 0
	v_pk_mul_f32 v[122:123], v[140:141], v[148:149] op_sel_hi:[1,0]
	v_pk_mul_f32 v[124:125], v[142:143], v[148:149] op_sel_hi:[1,0]
	v_pk_mul_f32 v[122:123], v[20:21], v[122:123]
	v_pk_mul_f32 v[124:125], v[24:25], v[124:125]
	v_pk_mul_f32 v[140:141], v[146:147], v[148:149] op_sel_hi:[1,0]
	v_pk_mul_f32 v[128:129], v[18:19], v[128:129]
	v_pk_mul_f32 v[140:141], v[22:23], v[140:141]
	v_cvt_pk_bf16_f32 v122, v122, v123
	v_cvt_pk_bf16_f32 v123, v124, v125
	v_cvt_pk_bf16_f32 v124, v128, v129
	v_mul_f32_e32 v128, v135, v135
	v_cvt_pk_bf16_f32 v125, v140, v141
	global_store_dwordx4 v[126:127], v[122:125], off offset:256
	v_mov_b32_e32 v126, v119
	v_mov_b32_e32 v127, v121
	v_mov_b32_e32 v124, v115
	v_mov_b32_e32 v125, v117
	v_mov_b32_e32 v122, v114
	v_mov_b32_e32 v123, v116
	v_pk_mul_f32 v[124:125], v[124:125], v[124:125]
	v_pk_mul_f32 v[126:127], v[126:127], v[126:127]
	v_pk_fma_f32 v[122:123], v[122:123], v[122:123], v[124:125]
	v_mov_b32_e32 v124, v118
	v_mov_b32_e32 v125, v120
	v_pk_fma_f32 v[124:125], v[124:125], v[124:125], v[126:127]
	v_mul_f32_e32 v126, v133, v133
	v_pk_add_f32 v[122:123], v[122:123], v[122:123] op_sel:[0,1] op_sel_hi:[1,0]
	v_pk_add_f32 v[124:125], v[124:125], v[124:125] op_sel:[0,1] op_sel_hi:[1,0]
	v_pk_fma_f32 v[126:127], v[132:133], v[132:133], v[126:127] op_sel_hi:[1,1,0]
	v_pk_fma_f32 v[128:129], v[134:135], v[134:135], v[128:129] op_sel_hi:[1,1,0]
	v_pk_mul_f32 v[140:141], v[136:137], v[136:137]
	v_pk_mul_f32 v[142:143], v[138:139], v[138:139]
	v_mov_b32_e32 v123, v140
	v_mov_b32_e32 v125, v141
	v_mov_b32_e32 v127, v142
	v_mov_b32_e32 v129, v143
	v_pk_add_f32 v[122:123], v[122:123], v[124:125]
	v_pk_add_f32 v[124:125], v[126:127], v[128:129]
	s_nop 0
	v_pk_add_f32 v[122:123], v[122:123], v[124:125]
	s_nop 0
	v_add_f32_e32 v27, v122, v123
	ds_swizzle_b32 v122, v27 offset:swizzle(SWAP,1)
	s_waitcnt lgkmcnt(0)
	v_add_f32_e32 v27, v27, v122
	ds_swizzle_b32 v122, v27 offset:swizzle(SWAP,2)
	s_waitcnt lgkmcnt(0)
	v_add_f32_e32 v27, v27, v122
	ds_swizzle_b32 v122, v27 offset:swizzle(SWAP,4)
	s_waitcnt lgkmcnt(0)
	v_add_f32_e32 v27, v27, v122
	ds_swizzle_b32 v122, v27 offset:swizzle(SWAP,8)
	s_waitcnt lgkmcnt(0)
; __device__ __forceinline__ unsigned cvt_pk_bf16(float lo, float hi) { unsigned r; asm volatile("v_cvt_pk_bf16_f32 %0, %1, %2" : "=v"(r) : "v"(lo), "v"(hi)); return r; }
; template <int O> __device__ __forceinline__ float swz_xor(float v) { return __int_as_float(__builtin_amdgcn_ds_swizzle(__float_as_int(v), (O << 10) | 0x1F)); }
; template <int EPI>
; __device__ __forceinline__ void attn_item_c(const Item& I, char* lds, int tid_in) {
;     ...
; #pragma unroll
;     for (int j = 0; j < 8; ++j) { float ss = 0.f;
; #pragma unroll
;       for (int half = 0; half < 2; ++half)
; #pragma unroll
;         for (int q = 0; q < 2; ++q) { const f32x4 d = dv[half][j][q]; ss += (d[0] * d[0] + d[1] * d[1]) + (d[2] * d[2] + d[3] * d[3]); }
;       ss += swz_xor<1>(ss); ss += swz_xor<2>(ss); ss += swz_xor<4>(ss); ss += swz_xor<8>(ss);
;       const float rstd = 1.0f / sqrtf(ss * (1.f / 256.f) + EPS);
; #pragma unroll
;       for (int half = 0; half < 2; ++half) { const f32x4 y0 = dv[half][j][0] * rstd * gsl[half][0], y1 = dv[half][j][1] * rstd * gsl[half][1];
;         u32x4 w; w.x = cvt_pk_bf16(y0[0], y0[1]); w.y = cvt_pk_bf16(y0[2], y0[3]); w.z = cvt_pk_bf16(y1[0], y1[1]); w.w = cvt_pk_bf16(y1[2], y1[3]);
;         STG(u32x4, I.O + (size_t)(tokw + 4 * j + rsub) * DM + I.ocol + half * 128 + ch * 8) = w; } }
	v_add_f32_e32 v27, v27, v122
	v_fmamk_f32 v27, v27, 0x3b800000, v226
	v_cmp_gt_f32_e32 vcc, s87, v27
	v_mul_f32_e32 v122, 0x4f800000, v27
	s_nop 0
	v_cndmask_b32_e32 v27, v27, v122, vcc
	v_sqrt_f32_e32 v122, v27
	s_nop 0
	v_add_u32_e32 v123, -1, v122
	v_fma_f32 v124, -v123, v122, v27
	v_cmp_ge_f32_e64 s[40:41], 0, v124
	v_add_u32_e32 v124, 1, v122
	s_nop 0
	v_cndmask_b32_e64 v123, v122, v123, s[40:41]
	v_fma_f32 v122, -v124, v122, v27
	v_cmp_lt_f32_e64 s[40:41], 0, v122
	s_nop 1
	v_cndmask_b32_e64 v122, v123, v124, s[40:41]
	v_mul_f32_e32 v123, 0x37800000, v122
	v_cndmask_b32_e32 v122, v122, v123, vcc
	v_cmp_class_f32_e32 vcc, v27, v227
	s_nop 1
	v_cndmask_b32_e32 v27, v122, v27, vcc
	v_div_scale_f32 v122, s[4:5], v27, v27, 1.0
	v_rcp_f32_e32 v123, v122
	s_nop 0
	v_fma_f32 v124, -v122, v123, 1.0
	v_fmac_f32_e32 v123, v124, v123
	v_div_scale_f32 v124, vcc, 1.0, v27, 1.0
	v_mul_f32_e32 v125, v124, v123
	v_fma_f32 v126, -v122, v125, v124
	v_fmac_f32_e32 v125, v126, v123
	v_fma_f32 v122, -v122, v125, v124
	v_div_fmas_f32 v122, v122, v123, v125
	v_div_fixup_f32 v122, v122, v27, 1.0
	v_add_u32_e32 v124, 4, v26
	v_ashrrev_i32_e32 v125, 31, v124
	v_pk_mul_f32 v[114:115], v[114:115], v[122:123] op_sel_hi:[1,0]
	v_pk_mul_f32 v[116:117], v[116:117], v[122:123] op_sel_hi:[1,0]
	v_pk_mul_f32 v[118:119], v[118:119], v[122:123] op_sel_hi:[1,0]
	v_lshlrev_b64 v[124:125], 12, v[124:125]
	v_pk_mul_f32 v[116:117], v[16:17], v[116:117]
	v_pk_mul_f32 v[114:115], v[12:13], v[114:115]
	v_pk_mul_f32 v[118:119], v[10:11], v[118:119]
	v_cvt_pk_bf16_f32 v114, v114, v115
	v_cvt_pk_bf16_f32 v115, v116, v117
	v_pk_mul_f32 v[120:121], v[120:121], v[122:123] op_sel_hi:[1,0]
	v_cvt_pk_bf16_f32 v116, v118, v119
	v_lshl_add_u64 v[118:119], s[48:49], 0, v[124:125]
	v_lshl_add_u64 v[118:119], v[118:119], 0, s[52:53]
	v_pk_mul_f32 v[120:121], v[14:15], v[120:121]
	v_lshl_add_u64 v[118:119], v[118:119], 0, v[0:1]
	v_cvt_pk_bf16_f32 v117, v120, v121
	global_store_dwordx4 v[118:119], v[114:117], off
	v_pk_mul_f32 v[120:121], v[136:137], v[122:123] op_sel_hi:[1,0]
	v_pk_mul_f32 v[124:125], v[130:131], v[130:131]
	v_pk_mul_f32 v[114:115], v[132:133], v[122:123] op_sel_hi:[1,0]
	v_pk_mul_f32 v[116:117], v[134:135], v[122:123] op_sel_hi:[1,0]
	v_pk_mul_f32 v[114:115], v[20:21], v[114:115]
	v_pk_mul_f32 v[116:117], v[24:25], v[116:117]
	v_pk_mul_f32 v[122:123], v[138:139], v[122:123] op_sel_hi:[1,0]
	v_pk_mul_f32 v[120:121], v[18:19], v[120:121]
	v_pk_mul_f32 v[122:123], v[22:23], v[122:123]
	v_cvt_pk_bf16_f32 v114, v114, v115
	v_cvt_pk_bf16_f32 v115, v116, v117
	v_cvt_pk_bf16_f32 v116, v120, v121
	v_mul_f32_e32 v120, v63, v63
	v_cvt_pk_bf16_f32 v117, v122, v123
	global_store_dwordx4 v[118:119], v[114:117], off offset:256
	v_mov_b32_e32 v118, v111
	v_mov_b32_e32 v119, v113
	v_mov_b32_e32 v116, v107
	v_mov_b32_e32 v117, v109
	v_mov_b32_e32 v114, v106
	v_mov_b32_e32 v115, v108
	v_pk_mul_f32 v[116:117], v[116:117], v[116:117]
	v_pk_mul_f32 v[118:119], v[118:119], v[118:119]
	v_pk_fma_f32 v[114:115], v[114:115], v[114:115], v[116:117]
	v_mov_b32_e32 v116, v110
	v_mov_b32_e32 v117, v112
	v_pk_fma_f32 v[116:117], v[116:117], v[116:117], v[118:119]
	v_mul_f32_e32 v118, v61, v61
	v_pk_add_f32 v[114:115], v[114:115], v[114:115] op_sel:[0,1] op_sel_hi:[1,0]
	v_pk_add_f32 v[116:117], v[116:117], v[116:117] op_sel:[0,1] op_sel_hi:[1,0]
	v_pk_fma_f32 v[118:119], v[60:61], v[60:61], v[118:119] op_sel_hi:[1,1,0]
	v_pk_fma_f32 v[120:121], v[62:63], v[62:63], v[120:121] op_sel_hi:[1,1,0]
	v_pk_mul_f32 v[122:123], v[64:65], v[64:65]
	v_mov_b32_e32 v119, v124
	v_mov_b32_e32 v115, v122
	v_mov_b32_e32 v117, v123
	v_mov_b32_e32 v121, v125
	v_pk_add_f32 v[114:115], v[114:115], v[116:117]
	v_pk_add_f32 v[116:117], v[118:119], v[120:121]
	s_nop 0
	v_pk_add_f32 v[114:115], v[114:115], v[116:117]
	s_nop 0
	v_add_f32_e32 v27, v114, v115
	ds_swizzle_b32 v114, v27 offset:swizzle(SWAP,1)
	s_waitcnt lgkmcnt(0)
	v_add_f32_e32 v27, v27, v114
	ds_swizzle_b32 v114, v27 offset:swizzle(SWAP,2)
	s_waitcnt lgkmcnt(0)
	v_add_f32_e32 v27, v27, v114
	ds_swizzle_b32 v114, v27 offset:swizzle(SWAP,4)
	s_waitcnt lgkmcnt(0)
	v_add_f32_e32 v27, v27, v114
	ds_swizzle_b32 v114, v27 offset:swizzle(SWAP,8)
	s_waitcnt lgkmcnt(0)
	v_add_f32_e32 v27, v27, v114
	v_fmamk_f32 v27, v27, 0x3b800000, v226
	v_cmp_gt_f32_e32 vcc, s87, v27
	v_mul_f32_e32 v114, 0x4f800000, v27
	s_nop 0
	v_cndmask_b32_e32 v27, v27, v114, vcc
	v_sqrt_f32_e32 v114, v27
	s_nop 0
	v_add_u32_e32 v115, -1, v114
	v_fma_f32 v116, -v115, v114, v27
	v_cmp_ge_f32_e64 s[40:41], 0, v116
	v_add_u32_e32 v116, 1, v114
	s_nop 0
	v_cndmask_b32_e64 v115, v114, v115, s[40:41]
	v_fma_f32 v114, -v116, v114, v27
	v_cmp_lt_f32_e64 s[40:41], 0, v114
	s_nop 1
	v_cndmask_b32_e64 v114, v115, v116, s[40:41]
	v_mul_f32_e32 v115, 0x37800000, v114
	v_cndmask_b32_e32 v114, v114, v115, vcc
	v_cmp_class_f32_e32 vcc, v27, v227
	s_nop 1
	v_cndmask_b32_e32 v27, v114, v27, vcc
	v_div_scale_f32 v114, s[4:5], v27, v27, 1.0
	v_rcp_f32_e32 v115, v114
	s_nop 0
	v_fma_f32 v116, -v114, v115, 1.0
	v_fmac_f32_e32 v115, v116, v115
	v_div_scale_f32 v116, vcc, 1.0, v27, 1.0
	v_mul_f32_e32 v117, v116, v115
	v_fma_f32 v118, -v114, v117, v116
	v_fmac_f32_e32 v117, v118, v115
	v_fma_f32 v114, -v114, v117, v116
	v_div_fmas_f32 v114, v114, v115, v117
	v_div_fixup_f32 v114, v114, v27, 1.0
	v_add_u32_e32 v116, 8, v26
	v_ashrrev_i32_e32 v117, 31, v116
	v_pk_mul_f32 v[106:107], v[106:107], v[114:115] op_sel_hi:[1,0]
	v_pk_mul_f32 v[108:109], v[108:109], v[114:115] op_sel_hi:[1,0]
	v_pk_mul_f32 v[110:111], v[110:111], v[114:115] op_sel_hi:[1,0]
	v_lshlrev_b64 v[116:117], 12, v[116:117]
	v_pk_mul_f32 v[108:109], v[16:17], v[108:109]
; __device__ __forceinline__ unsigned cvt_pk_bf16(float lo, float hi) { unsigned r; asm volatile("v_cvt_pk_bf16_f32 %0, %1, %2" : "=v"(r) : "v"(lo), "v"(hi)); return r; }
; template <int O> __device__ __forceinline__ float swz_xor(float v) { return __int_as_float(__builtin_amdgcn_ds_swizzle(__float_as_int(v), (O << 10) | 0x1F)); }
; template <int EPI>
; __device__ __forceinline__ void attn_item_c(const Item& I, char* lds, int tid_in) {
;     ...
; #pragma unroll
;     for (int j = 0; j < 8; ++j) { float ss = 0.f;
; #pragma unroll
;       for (int half = 0; half < 2; ++half)
; #pragma unroll
;         for (int q = 0; q < 2; ++q) { const f32x4 d = dv[half][j][q]; ss += (d[0] * d[0] + d[1] * d[1]) + (d[2] * d[2] + d[3] * d[3]); }
;       ss += swz_xor<1>(ss); ss += swz_xor<2>(ss); ss += swz_xor<4>(ss); ss += swz_xor<8>(ss);
;       const float rstd = 1.0f / sqrtf(ss * (1.f / 256.f) + EPS);
; #pragma unroll
;       for (int half = 0; half < 2; ++half) { const f32x4 y0 = dv[half][j][0] * rstd * gsl[half][0], y1 = dv[half][j][1] * rstd * gsl[half][1];
;         u32x4 w; w.x = cvt_pk_bf16(y0[0], y0[1]); w.y = cvt_pk_bf16(y0[2], y0[3]); w.z = cvt_pk_bf16(y1[0], y1[1]); w.w = cvt_pk_bf16(y1[2], y1[3]);
;         STG(u32x4, I.O + (size_t)(tokw + 4 * j + rsub) * DM + I.ocol + half * 128 + ch * 8) = w; } }
	v_pk_mul_f32 v[106:107], v[12:13], v[106:107]
	v_pk_mul_f32 v[110:111], v[10:11], v[110:111]
	v_cvt_pk_bf16_f32 v106, v106, v107
	v_cvt_pk_bf16_f32 v107, v108, v109
	v_pk_mul_f32 v[112:113], v[112:113], v[114:115] op_sel_hi:[1,0]
	v_cvt_pk_bf16_f32 v108, v110, v111
	v_lshl_add_u64 v[110:111], s[48:49], 0, v[116:117]
	v_lshl_add_u64 v[110:111], v[110:111], 0, s[52:53]
	v_lshl_add_u64 v[110:111], v[110:111], 0, v[0:1]
	v_pk_mul_f32 v[60:61], v[60:61], v[114:115] op_sel_hi:[1,0]
	v_pk_mul_f32 v[62:63], v[62:63], v[114:115] op_sel_hi:[1,0]
	v_pk_mul_f32 v[112:113], v[14:15], v[112:113]
	v_pk_mul_f32 v[62:63], v[24:25], v[62:63]
	v_cvt_pk_bf16_f32 v109, v112, v113
	global_store_dwordx4 v[110:111], v[106:109], off
	v_pk_mul_f32 v[60:61], v[20:21], v[60:61]
	v_pk_mul_f32 v[64:65], v[64:65], v[114:115] op_sel_hi:[1,0]
	v_pk_mul_f32 v[106:107], v[130:131], v[114:115] op_sel_hi:[1,0]
	v_pk_mul_f32 v[64:65], v[18:19], v[64:65]
	v_pk_mul_f32 v[106:107], v[22:23], v[106:107]
	v_cvt_pk_bf16_f32 v60, v60, v61
	v_cvt_pk_bf16_f32 v61, v62, v63
	v_cvt_pk_bf16_f32 v62, v64, v65
	v_mov_b32_e32 v64, v103
	v_cvt_pk_bf16_f32 v63, v106, v107
	global_store_dwordx4 v[110:111], v[60:63], off offset:256
	v_mov_b32_e32 v65, v105
	v_pk_mul_f32 v[64:65], v[64:65], v[64:65]
	v_mov_b32_e32 v62, v99
	v_mov_b32_e32 v63, v101
	v_mov_b32_e32 v60, v98
	v_mov_b32_e32 v61, v100
	v_pk_mul_f32 v[62:63], v[62:63], v[62:63]
	v_mul_f32_e32 v106, v55, v55
	v_pk_fma_f32 v[60:61], v[60:61], v[60:61], v[62:63]
	v_mov_b32_e32 v62, v102
	v_mov_b32_e32 v63, v104
	v_pk_fma_f32 v[62:63], v[62:63], v[62:63], v[64:65]
	v_mul_f32_e32 v64, v53, v53
	v_pk_add_f32 v[60:61], v[60:61], v[60:61] op_sel:[0,1] op_sel_hi:[1,0]
	v_pk_add_f32 v[62:63], v[62:63], v[62:63] op_sel:[0,1] op_sel_hi:[1,0]
	v_pk_fma_f32 v[64:65], v[52:53], v[52:53], v[64:65] op_sel_hi:[1,1,0]
	v_pk_fma_f32 v[106:107], v[54:55], v[54:55], v[106:107] op_sel_hi:[1,1,0]
	v_pk_mul_f32 v[108:109], v[56:57], v[56:57]
	v_pk_mul_f32 v[110:111], v[58:59], v[58:59]
	v_mov_b32_e32 v61, v108
	v_mov_b32_e32 v63, v109
	v_mov_b32_e32 v65, v110
	v_mov_b32_e32 v107, v111
	v_pk_add_f32 v[60:61], v[60:61], v[62:63]
	v_pk_add_f32 v[62:63], v[64:65], v[106:107]
	s_nop 0
	v_pk_add_f32 v[60:61], v[60:61], v[62:63]
	s_nop 0
	v_add_f32_e32 v27, v60, v61
	ds_swizzle_b32 v60, v27 offset:swizzle(SWAP,1)
	s_waitcnt lgkmcnt(0)
	v_add_f32_e32 v27, v27, v60
	ds_swizzle_b32 v60, v27 offset:swizzle(SWAP,2)
	s_waitcnt lgkmcnt(0)
	v_add_f32_e32 v27, v27, v60
	ds_swizzle_b32 v60, v27 offset:swizzle(SWAP,4)
	s_waitcnt lgkmcnt(0)
	v_add_f32_e32 v27, v27, v60
	ds_swizzle_b32 v60, v27 offset:swizzle(SWAP,8)
	s_waitcnt lgkmcnt(0)
	v_add_f32_e32 v27, v27, v60
	v_fmamk_f32 v27, v27, 0x3b800000, v226
	v_cmp_gt_f32_e32 vcc, s87, v27
	v_mul_f32_e32 v60, 0x4f800000, v27
	s_nop 0
	v_cndmask_b32_e32 v27, v27, v60, vcc
	v_sqrt_f32_e32 v60, v27
	s_nop 0
	v_add_u32_e32 v61, -1, v60
	v_fma_f32 v62, -v61, v60, v27
	v_cmp_ge_f32_e64 s[40:41], 0, v62
	v_add_u32_e32 v62, 1, v60
	s_nop 0
	v_cndmask_b32_e64 v61, v60, v61, s[40:41]
	v_fma_f32 v60, -v62, v60, v27
	v_cmp_lt_f32_e64 s[40:41], 0, v60
	s_nop 1
	v_cndmask_b32_e64 v60, v61, v62, s[40:41]
	v_mul_f32_e32 v61, 0x37800000, v60
	v_cndmask_b32_e32 v60, v60, v61, vcc
	v_cmp_class_f32_e32 vcc, v27, v227
	s_nop 1
	v_cndmask_b32_e32 v27, v60, v27, vcc
	v_div_scale_f32 v60, s[4:5], v27, v27, 1.0
	v_rcp_f32_e32 v61, v60
	s_nop 0
	v_fma_f32 v62, -v60, v61, 1.0
	v_fmac_f32_e32 v61, v62, v61
	v_div_scale_f32 v62, vcc, 1.0, v27, 1.0
	v_mul_f32_e32 v63, v62, v61
	v_fma_f32 v64, -v60, v63, v62
	v_fmac_f32_e32 v63, v64, v61
	v_fma_f32 v60, -v60, v63, v62
	v_div_fmas_f32 v60, v60, v61, v63
	v_div_fixup_f32 v64, v60, v27, 1.0
	v_add_u32_e32 v60, 12, v26
	v_ashrrev_i32_e32 v61, 31, v60
	v_lshlrev_b64 v[106:107], 12, v[60:61]
	v_pk_mul_f32 v[60:61], v[98:99], v[64:65] op_sel_hi:[1,0]
	v_pk_mul_f32 v[62:63], v[100:101], v[64:65] op_sel_hi:[1,0]
	v_pk_mul_f32 v[98:99], v[102:103], v[64:65] op_sel_hi:[1,0]
	v_pk_mul_f32 v[62:63], v[16:17], v[62:63]
	v_pk_mul_f32 v[60:61], v[12:13], v[60:61]
	v_pk_mul_f32 v[98:99], v[10:11], v[98:99]
	v_cvt_pk_bf16_f32 v60, v60, v61
	v_cvt_pk_bf16_f32 v61, v62, v63
	v_pk_mul_f32 v[52:53], v[52:53], v[64:65] op_sel_hi:[1,0]
	v_cvt_pk_bf16_f32 v62, v98, v99
	v_lshl_add_u64 v[98:99], s[48:49], 0, v[106:107]
	v_lshl_add_u64 v[98:99], v[98:99], 0, s[52:53]
	v_pk_mul_f32 v[54:55], v[54:55], v[64:65] op_sel_hi:[1,0]
	v_pk_mul_f32 v[100:101], v[104:105], v[64:65] op_sel_hi:[1,0]
	v_lshl_add_u64 v[98:99], v[98:99], 0, v[0:1]
	v_pk_mul_f32 v[54:55], v[24:25], v[54:55]
	v_pk_mul_f32 v[52:53], v[20:21], v[52:53]
	v_pk_mul_f32 v[56:57], v[56:57], v[64:65] op_sel_hi:[1,0]
	v_pk_mul_f32 v[58:59], v[58:59], v[64:65] op_sel_hi:[1,0]
	v_pk_mul_f32 v[100:101], v[14:15], v[100:101]
	v_pk_mul_f32 v[58:59], v[22:23], v[58:59]
	v_cvt_pk_bf16_f32 v63, v100, v101
	global_store_dwordx4 v[98:99], v[60:63], off
	v_pk_mul_f32 v[56:57], v[18:19], v[56:57]
	v_cvt_pk_bf16_f32 v52, v52, v53
	v_cvt_pk_bf16_f32 v53, v54, v55
	s_nop 0
	v_cvt_pk_bf16_f32 v54, v56, v57
	v_cvt_pk_bf16_f32 v55, v58, v59
	global_store_dwordx4 v[98:99], v[52:55], off offset:256
	v_mov_b32_e32 v56, v95
	v_mov_b32_e32 v57, v97
	v_mov_b32_e32 v54, v91
	v_mov_b32_e32 v55, v93
	v_mov_b32_e32 v52, v90
	v_mov_b32_e32 v53, v92
	v_pk_mul_f32 v[54:55], v[54:55], v[54:55]
	v_pk_mul_f32 v[56:57], v[56:57], v[56:57]
	v_pk_fma_f32 v[52:53], v[52:53], v[52:53], v[54:55]
	v_mov_b32_e32 v54, v94
	v_mov_b32_e32 v55, v96
	v_pk_fma_f32 v[54:55], v[54:55], v[54:55], v[56:57]
	v_mul_f32_e32 v56, v45, v45
	v_mul_f32_e32 v58, v47, v47
	v_pk_add_f32 v[52:53], v[52:53], v[52:53] op_sel:[0,1] op_sel_hi:[1,0]
	v_pk_add_f32 v[54:55], v[54:55], v[54:55] op_sel:[0,1] op_sel_hi:[1,0]
	v_pk_fma_f32 v[56:57], v[44:45], v[44:45], v[56:57] op_sel_hi:[1,1,0]
	v_pk_fma_f32 v[58:59], v[46:47], v[46:47], v[58:59] op_sel_hi:[1,1,0]
	v_pk_mul_f32 v[60:61], v[48:49], v[48:49]
	v_pk_mul_f32 v[62:63], v[50:51], v[50:51]
	v_mov_b32_e32 v53, v60
	v_mov_b32_e32 v55, v61
	v_mov_b32_e32 v57, v62
	v_mov_b32_e32 v59, v63
	v_pk_add_f32 v[52:53], v[52:53], v[54:55]
	v_pk_add_f32 v[54:55], v[56:57], v[58:59]
	s_nop 0
	v_pk_add_f32 v[52:53], v[52:53], v[54:55]
	s_nop 0
	v_add_f32_e32 v27, v52, v53
	ds_swizzle_b32 v52, v27 offset:swizzle(SWAP,1)
	s_waitcnt lgkmcnt(0)
; __device__ __forceinline__ unsigned cvt_pk_bf16(float lo, float hi) { unsigned r; asm volatile("v_cvt_pk_bf16_f32 %0, %1, %2" : "=v"(r) : "v"(lo), "v"(hi)); return r; }
; template <int O> __device__ __forceinline__ float swz_xor(float v) { return __int_as_float(__builtin_amdgcn_ds_swizzle(__float_as_int(v), (O << 10) | 0x1F)); }
; template <int EPI>
; __device__ __forceinline__ void attn_item_c(const Item& I, char* lds, int tid_in) {
;     ...
; #pragma unroll
;     for (int j = 0; j < 8; ++j) { float ss = 0.f;
; #pragma unroll
;       for (int half = 0; half < 2; ++half)
; #pragma unroll
;         for (int q = 0; q < 2; ++q) { const f32x4 d = dv[half][j][q]; ss += (d[0] * d[0] + d[1] * d[1]) + (d[2] * d[2] + d[3] * d[3]); }
;       ss += swz_xor<1>(ss); ss += swz_xor<2>(ss); ss += swz_xor<4>(ss); ss += swz_xor<8>(ss);
;       const float rstd = 1.0f / sqrtf(ss * (1.f / 256.f) + EPS);
; #pragma unroll
;       for (int half = 0; half < 2; ++half) { const f32x4 y0 = dv[half][j][0] * rstd * gsl[half][0], y1 = dv[half][j][1] * rstd * gsl[half][1];
;         u32x4 w; w.x = cvt_pk_bf16(y0[0], y0[1]); w.y = cvt_pk_bf16(y0[2], y0[3]); w.z = cvt_pk_bf16(y1[0], y1[1]); w.w = cvt_pk_bf16(y1[2], y1[3]);
;         STG(u32x4, I.O + (size_t)(tokw + 4 * j + rsub) * DM + I.ocol + half * 128 + ch * 8) = w; } }
	v_add_f32_e32 v27, v27, v52
	ds_swizzle_b32 v52, v27 offset:swizzle(SWAP,2)
	s_waitcnt lgkmcnt(0)
	v_add_f32_e32 v27, v27, v52
	ds_swizzle_b32 v52, v27 offset:swizzle(SWAP,4)
	s_waitcnt lgkmcnt(0)
	v_add_f32_e32 v27, v27, v52
	ds_swizzle_b32 v52, v27 offset:swizzle(SWAP,8)
	s_waitcnt lgkmcnt(0)
	v_add_f32_e32 v27, v27, v52
	v_fmamk_f32 v27, v27, 0x3b800000, v226
	v_cmp_gt_f32_e32 vcc, s87, v27
	v_mul_f32_e32 v52, 0x4f800000, v27
	s_nop 0
	v_cndmask_b32_e32 v27, v27, v52, vcc
	v_sqrt_f32_e32 v52, v27
	s_nop 0
	v_add_u32_e32 v53, -1, v52
	v_fma_f32 v54, -v53, v52, v27
	v_cmp_ge_f32_e64 s[40:41], 0, v54
	v_add_u32_e32 v54, 1, v52
	s_nop 0
	v_cndmask_b32_e64 v53, v52, v53, s[40:41]
	v_fma_f32 v52, -v54, v52, v27
	v_cmp_lt_f32_e64 s[40:41], 0, v52
	s_nop 1
	v_cndmask_b32_e64 v52, v53, v54, s[40:41]
	v_mul_f32_e32 v53, 0x37800000, v52
	v_cndmask_b32_e32 v52, v52, v53, vcc
	v_cmp_class_f32_e32 vcc, v27, v227
	s_nop 1
	v_cndmask_b32_e32 v27, v52, v27, vcc
	v_div_scale_f32 v52, s[4:5], v27, v27, 1.0
	v_rcp_f32_e32 v53, v52
	s_nop 0
	v_fma_f32 v54, -v52, v53, 1.0
	v_fmac_f32_e32 v53, v54, v53
	v_div_scale_f32 v54, vcc, 1.0, v27, 1.0
	v_mul_f32_e32 v55, v54, v53
	v_fma_f32 v56, -v52, v55, v54
	v_fmac_f32_e32 v55, v56, v53
	v_fma_f32 v52, -v52, v55, v54
	v_div_fmas_f32 v52, v52, v53, v55
	v_div_fixup_f32 v56, v52, v27, 1.0
	v_add_u32_e32 v52, 16, v26
	v_ashrrev_i32_e32 v53, 31, v52
	v_lshlrev_b64 v[58:59], 12, v[52:53]
	v_lshl_add_u64 v[58:59], s[48:49], 0, v[58:59]
	v_pk_mul_f32 v[52:53], v[90:91], v[56:57] op_sel_hi:[1,0]
	v_pk_mul_f32 v[54:55], v[92:93], v[56:57] op_sel_hi:[1,0]
	v_lshl_add_u64 v[58:59], v[58:59], 0, s[52:53]
	v_pk_mul_f32 v[44:45], v[44:45], v[56:57] op_sel_hi:[1,0]
	v_pk_mul_f32 v[46:47], v[46:47], v[56:57] op_sel_hi:[1,0]
	v_pk_mul_f32 v[54:55], v[16:17], v[54:55]
	v_pk_mul_f32 v[52:53], v[12:13], v[52:53]
	v_pk_mul_f32 v[60:61], v[94:95], v[56:57] op_sel_hi:[1,0]
	v_pk_mul_f32 v[62:63], v[96:97], v[56:57] op_sel_hi:[1,0]
	v_lshl_add_u64 v[58:59], v[58:59], 0, v[0:1]
	v_pk_mul_f32 v[46:47], v[24:25], v[46:47]
	v_pk_mul_f32 v[44:45], v[20:21], v[44:45]
	v_pk_mul_f32 v[48:49], v[48:49], v[56:57] op_sel_hi:[1,0]
	v_pk_mul_f32 v[50:51], v[50:51], v[56:57] op_sel_hi:[1,0]
	v_pk_mul_f32 v[62:63], v[14:15], v[62:63]
	v_pk_mul_f32 v[60:61], v[10:11], v[60:61]
	v_cvt_pk_bf16_f32 v52, v52, v53
	v_cvt_pk_bf16_f32 v53, v54, v55
	v_pk_mul_f32 v[50:51], v[22:23], v[50:51]
	v_cvt_pk_bf16_f32 v54, v60, v61
	v_cvt_pk_bf16_f32 v55, v62, v63
	global_store_dwordx4 v[58:59], v[52:55], off
	v_pk_mul_f32 v[48:49], v[18:19], v[48:49]
	v_cvt_pk_bf16_f32 v44, v44, v45
	v_cvt_pk_bf16_f32 v45, v46, v47
	s_nop 0
	v_cvt_pk_bf16_f32 v46, v48, v49
	v_cvt_pk_bf16_f32 v47, v50, v51
	global_store_dwordx4 v[58:59], v[44:47], off offset:256
	v_mov_b32_e32 v48, v87
	v_mov_b32_e32 v49, v89
	v_mov_b32_e32 v46, v83
	v_mov_b32_e32 v47, v85
	v_mov_b32_e32 v44, v82
	v_mov_b32_e32 v45, v84
	v_pk_mul_f32 v[46:47], v[46:47], v[46:47]
	v_pk_mul_f32 v[48:49], v[48:49], v[48:49]
	v_pk_fma_f32 v[44:45], v[44:45], v[44:45], v[46:47]
	v_mov_b32_e32 v46, v86
	v_mov_b32_e32 v47, v88
	v_pk_fma_f32 v[46:47], v[46:47], v[46:47], v[48:49]
	v_mul_f32_e32 v48, v37, v37
	v_mul_f32_e32 v50, v39, v39
	v_pk_add_f32 v[44:45], v[44:45], v[44:45] op_sel:[0,1] op_sel_hi:[1,0]
	v_pk_add_f32 v[46:47], v[46:47], v[46:47] op_sel:[0,1] op_sel_hi:[1,0]
	v_pk_fma_f32 v[48:49], v[36:37], v[36:37], v[48:49] op_sel_hi:[1,1,0]
	v_pk_fma_f32 v[50:51], v[38:39], v[38:39], v[50:51] op_sel_hi:[1,1,0]
	v_pk_mul_f32 v[52:53], v[40:41], v[40:41]
	v_pk_mul_f32 v[54:55], v[42:43], v[42:43]
	v_mov_b32_e32 v45, v52
	v_mov_b32_e32 v47, v53
	v_mov_b32_e32 v49, v54
	v_mov_b32_e32 v51, v55
	v_pk_add_f32 v[44:45], v[44:45], v[46:47]
	v_pk_add_f32 v[46:47], v[48:49], v[50:51]
	s_nop 0
	v_pk_add_f32 v[44:45], v[44:45], v[46:47]
	s_nop 0
	v_add_f32_e32 v27, v44, v45
	ds_swizzle_b32 v44, v27 offset:swizzle(SWAP,1)
	s_waitcnt lgkmcnt(0)
	v_add_f32_e32 v27, v27, v44
	ds_swizzle_b32 v44, v27 offset:swizzle(SWAP,2)
	s_waitcnt lgkmcnt(0)
	v_add_f32_e32 v27, v27, v44
	ds_swizzle_b32 v44, v27 offset:swizzle(SWAP,4)
	s_waitcnt lgkmcnt(0)
	v_add_f32_e32 v27, v27, v44
	ds_swizzle_b32 v44, v27 offset:swizzle(SWAP,8)
	s_waitcnt lgkmcnt(0)
	v_add_f32_e32 v27, v27, v44
	v_fmamk_f32 v27, v27, 0x3b800000, v226
	v_cmp_gt_f32_e32 vcc, s87, v27
	v_mul_f32_e32 v44, 0x4f800000, v27
	s_nop 0
	v_cndmask_b32_e32 v27, v27, v44, vcc
	v_sqrt_f32_e32 v44, v27
	s_nop 0
	v_add_u32_e32 v45, -1, v44
	v_fma_f32 v46, -v45, v44, v27
	v_cmp_ge_f32_e64 s[40:41], 0, v46
	v_add_u32_e32 v46, 1, v44
	s_nop 0
	v_cndmask_b32_e64 v45, v44, v45, s[40:41]
	v_fma_f32 v44, -v46, v44, v27
	v_cmp_lt_f32_e64 s[40:41], 0, v44
	s_nop 1
	v_cndmask_b32_e64 v44, v45, v46, s[40:41]
	v_mul_f32_e32 v45, 0x37800000, v44
	v_cndmask_b32_e32 v44, v44, v45, vcc
	v_cmp_class_f32_e32 vcc, v27, v227
	s_nop 1
	v_cndmask_b32_e32 v27, v44, v27, vcc
	v_div_scale_f32 v44, s[4:5], v27, v27, 1.0
	v_rcp_f32_e32 v45, v44
	s_nop 0
	v_fma_f32 v46, -v44, v45, 1.0
	v_fmac_f32_e32 v45, v46, v45
	v_div_scale_f32 v46, vcc, 1.0, v27, 1.0
	v_mul_f32_e32 v47, v46, v45
	v_fma_f32 v48, -v44, v47, v46
	v_fmac_f32_e32 v47, v48, v45
	v_fma_f32 v44, -v44, v47, v46
	v_div_fmas_f32 v44, v44, v45, v47
	v_div_fixup_f32 v48, v44, v27, 1.0
	v_add_u32_e32 v44, 20, v26
	v_ashrrev_i32_e32 v45, 31, v44
	v_lshlrev_b64 v[50:51], 12, v[44:45]
	v_lshl_add_u64 v[50:51], s[48:49], 0, v[50:51]
	v_pk_mul_f32 v[44:45], v[82:83], v[48:49] op_sel_hi:[1,0]
	v_pk_mul_f32 v[46:47], v[84:85], v[48:49] op_sel_hi:[1,0]
	v_lshl_add_u64 v[50:51], v[50:51], 0, s[52:53]
	v_pk_mul_f32 v[36:37], v[36:37], v[48:49] op_sel_hi:[1,0]
; __device__ __forceinline__ unsigned cvt_pk_bf16(float lo, float hi) { unsigned r; asm volatile("v_cvt_pk_bf16_f32 %0, %1, %2" : "=v"(r) : "v"(lo), "v"(hi)); return r; }
; template <int O> __device__ __forceinline__ float swz_xor(float v) { return __int_as_float(__builtin_amdgcn_ds_swizzle(__float_as_int(v), (O << 10) | 0x1F)); }
; template <int EPI>
; __device__ __forceinline__ void attn_item_c(const Item& I, char* lds, int tid_in) {
;     ...
; #pragma unroll
;     for (int j = 0; j < 8; ++j) { float ss = 0.f;
; #pragma unroll
;       for (int half = 0; half < 2; ++half)
; #pragma unroll
;         for (int q = 0; q < 2; ++q) { const f32x4 d = dv[half][j][q]; ss += (d[0] * d[0] + d[1] * d[1]) + (d[2] * d[2] + d[3] * d[3]); }
;       ss += swz_xor<1>(ss); ss += swz_xor<2>(ss); ss += swz_xor<4>(ss); ss += swz_xor<8>(ss);
;       const float rstd = 1.0f / sqrtf(ss * (1.f / 256.f) + EPS);
; #pragma unroll
;       for (int half = 0; half < 2; ++half) { const f32x4 y0 = dv[half][j][0] * rstd * gsl[half][0], y1 = dv[half][j][1] * rstd * gsl[half][1];
;         u32x4 w; w.x = cvt_pk_bf16(y0[0], y0[1]); w.y = cvt_pk_bf16(y0[2], y0[3]); w.z = cvt_pk_bf16(y1[0], y1[1]); w.w = cvt_pk_bf16(y1[2], y1[3]);
;         STG(u32x4, I.O + (size_t)(tokw + 4 * j + rsub) * DM + I.ocol + half * 128 + ch * 8) = w; } }
	v_pk_mul_f32 v[38:39], v[38:39], v[48:49] op_sel_hi:[1,0]
	v_pk_mul_f32 v[46:47], v[16:17], v[46:47]
	v_pk_mul_f32 v[44:45], v[12:13], v[44:45]
	v_pk_mul_f32 v[52:53], v[86:87], v[48:49] op_sel_hi:[1,0]
	v_pk_mul_f32 v[54:55], v[88:89], v[48:49] op_sel_hi:[1,0]
	v_lshl_add_u64 v[50:51], v[50:51], 0, v[0:1]
	v_pk_mul_f32 v[38:39], v[24:25], v[38:39]
	v_pk_mul_f32 v[36:37], v[20:21], v[36:37]
	v_pk_mul_f32 v[40:41], v[40:41], v[48:49] op_sel_hi:[1,0]
	v_pk_mul_f32 v[42:43], v[42:43], v[48:49] op_sel_hi:[1,0]
	v_pk_mul_f32 v[54:55], v[14:15], v[54:55]
	v_pk_mul_f32 v[52:53], v[10:11], v[52:53]
	v_cvt_pk_bf16_f32 v44, v44, v45
	v_cvt_pk_bf16_f32 v45, v46, v47
	v_pk_mul_f32 v[42:43], v[22:23], v[42:43]
	v_cvt_pk_bf16_f32 v46, v52, v53
	v_cvt_pk_bf16_f32 v47, v54, v55
	global_store_dwordx4 v[50:51], v[44:47], off
	v_pk_mul_f32 v[40:41], v[18:19], v[40:41]
	v_cvt_pk_bf16_f32 v36, v36, v37
	v_cvt_pk_bf16_f32 v37, v38, v39
	s_nop 0
	v_cvt_pk_bf16_f32 v38, v40, v41
	v_cvt_pk_bf16_f32 v39, v42, v43
	global_store_dwordx4 v[50:51], v[36:39], off offset:256
	v_mov_b32_e32 v40, v79
	v_mov_b32_e32 v41, v81
	v_mov_b32_e32 v38, v75
	v_mov_b32_e32 v39, v77
	v_mov_b32_e32 v36, v74
	v_mov_b32_e32 v37, v76
	v_pk_mul_f32 v[38:39], v[38:39], v[38:39]
	v_pk_mul_f32 v[40:41], v[40:41], v[40:41]
	v_pk_fma_f32 v[36:37], v[36:37], v[36:37], v[38:39]
	v_mov_b32_e32 v38, v78
	v_mov_b32_e32 v39, v80
	v_pk_fma_f32 v[38:39], v[38:39], v[38:39], v[40:41]
	v_mul_f32_e32 v40, v29, v29
	v_mul_f32_e32 v42, v31, v31
	v_pk_add_f32 v[36:37], v[36:37], v[36:37] op_sel:[0,1] op_sel_hi:[1,0]
	v_pk_add_f32 v[38:39], v[38:39], v[38:39] op_sel:[0,1] op_sel_hi:[1,0]
	v_pk_fma_f32 v[40:41], v[28:29], v[28:29], v[40:41] op_sel_hi:[1,1,0]
	v_pk_fma_f32 v[42:43], v[30:31], v[30:31], v[42:43] op_sel_hi:[1,1,0]
	v_pk_mul_f32 v[44:45], v[32:33], v[32:33]
	v_pk_mul_f32 v[46:47], v[34:35], v[34:35]
	v_mov_b32_e32 v37, v44
	v_mov_b32_e32 v39, v45
	v_mov_b32_e32 v41, v46
	v_mov_b32_e32 v43, v47
	v_pk_add_f32 v[36:37], v[36:37], v[38:39]
	v_pk_add_f32 v[38:39], v[40:41], v[42:43]
	s_nop 0
	v_pk_add_f32 v[36:37], v[36:37], v[38:39]
	s_nop 0
	v_add_f32_e32 v27, v36, v37
	ds_swizzle_b32 v36, v27 offset:swizzle(SWAP,1)
	s_waitcnt lgkmcnt(0)
	v_add_f32_e32 v27, v27, v36
	ds_swizzle_b32 v36, v27 offset:swizzle(SWAP,2)
	s_waitcnt lgkmcnt(0)
	v_add_f32_e32 v27, v27, v36
	ds_swizzle_b32 v36, v27 offset:swizzle(SWAP,4)
	s_waitcnt lgkmcnt(0)
	v_add_f32_e32 v27, v27, v36
	ds_swizzle_b32 v36, v27 offset:swizzle(SWAP,8)
	s_waitcnt lgkmcnt(0)
	v_add_f32_e32 v27, v27, v36
	v_fmamk_f32 v27, v27, 0x3b800000, v226
	v_cmp_gt_f32_e32 vcc, s87, v27
	v_mul_f32_e32 v36, 0x4f800000, v27
	s_nop 0
	v_cndmask_b32_e32 v27, v27, v36, vcc
	v_sqrt_f32_e32 v36, v27
	s_nop 0
	v_add_u32_e32 v37, -1, v36
	v_fma_f32 v38, -v37, v36, v27
	v_cmp_ge_f32_e64 s[40:41], 0, v38
	v_add_u32_e32 v38, 1, v36
	s_nop 0
	v_cndmask_b32_e64 v37, v36, v37, s[40:41]
	v_fma_f32 v36, -v38, v36, v27
	v_cmp_lt_f32_e64 s[40:41], 0, v36
	s_nop 1
	v_cndmask_b32_e64 v36, v37, v38, s[40:41]
	v_mul_f32_e32 v37, 0x37800000, v36
	v_cndmask_b32_e32 v36, v36, v37, vcc
	v_cmp_class_f32_e32 vcc, v27, v227
	s_nop 1
	v_cndmask_b32_e32 v27, v36, v27, vcc
	v_div_scale_f32 v36, s[4:5], v27, v27, 1.0
	v_rcp_f32_e32 v37, v36
	s_nop 0
	v_fma_f32 v38, -v36, v37, 1.0
	v_fmac_f32_e32 v37, v38, v37
	v_div_scale_f32 v38, vcc, 1.0, v27, 1.0
	v_mul_f32_e32 v39, v38, v37
	v_fma_f32 v40, -v36, v39, v38
	v_fmac_f32_e32 v39, v40, v37
	v_fma_f32 v36, -v36, v39, v38
	v_div_fmas_f32 v36, v36, v37, v39
	v_div_fixup_f32 v40, v36, v27, 1.0
	v_add_u32_e32 v36, 24, v26
	v_ashrrev_i32_e32 v37, 31, v36
	v_lshlrev_b64 v[42:43], 12, v[36:37]
	v_lshl_add_u64 v[42:43], s[48:49], 0, v[42:43]
	v_pk_mul_f32 v[36:37], v[74:75], v[40:41] op_sel_hi:[1,0]
	v_pk_mul_f32 v[38:39], v[76:77], v[40:41] op_sel_hi:[1,0]
	v_lshl_add_u64 v[42:43], v[42:43], 0, s[52:53]
	v_pk_mul_f32 v[28:29], v[28:29], v[40:41] op_sel_hi:[1,0]
	v_pk_mul_f32 v[30:31], v[30:31], v[40:41] op_sel_hi:[1,0]
	v_pk_mul_f32 v[38:39], v[16:17], v[38:39]
	v_pk_mul_f32 v[36:37], v[12:13], v[36:37]
	v_pk_mul_f32 v[44:45], v[78:79], v[40:41] op_sel_hi:[1,0]
	v_pk_mul_f32 v[46:47], v[80:81], v[40:41] op_sel_hi:[1,0]
	v_lshl_add_u64 v[42:43], v[42:43], 0, v[0:1]
	v_pk_mul_f32 v[30:31], v[24:25], v[30:31]
	v_pk_mul_f32 v[28:29], v[20:21], v[28:29]
	v_pk_mul_f32 v[32:33], v[32:33], v[40:41] op_sel_hi:[1,0]
	v_pk_mul_f32 v[34:35], v[34:35], v[40:41] op_sel_hi:[1,0]
	v_pk_mul_f32 v[46:47], v[14:15], v[46:47]
	v_pk_mul_f32 v[44:45], v[10:11], v[44:45]
	v_cvt_pk_bf16_f32 v36, v36, v37
	v_cvt_pk_bf16_f32 v37, v38, v39
	v_pk_mul_f32 v[34:35], v[22:23], v[34:35]
	v_cvt_pk_bf16_f32 v38, v44, v45
	v_cvt_pk_bf16_f32 v39, v46, v47
	global_store_dwordx4 v[42:43], v[36:39], off
	v_pk_mul_f32 v[32:33], v[18:19], v[32:33]
	v_cvt_pk_bf16_f32 v28, v28, v29
	v_cvt_pk_bf16_f32 v29, v30, v31
	v_add_u32_e32 v26, 28, v26
	v_cvt_pk_bf16_f32 v30, v32, v33
	v_cvt_pk_bf16_f32 v31, v34, v35
	global_store_dwordx4 v[42:43], v[28:31], off offset:256
	v_mov_b32_e32 v32, v73
	v_mov_b32_e32 v33, v69
	v_mov_b32_e32 v30, v71
	v_mov_b32_e32 v31, v67
	v_mov_b32_e32 v28, v70
	v_mov_b32_e32 v29, v66
	v_pk_mul_f32 v[30:31], v[30:31], v[30:31]
	v_pk_mul_f32 v[32:33], v[32:33], v[32:33]
	v_pk_fma_f32 v[28:29], v[28:29], v[28:29], v[30:31]
	v_mov_b32_e32 v30, v72
	v_mov_b32_e32 v31, v68
	v_pk_fma_f32 v[30:31], v[30:31], v[30:31], v[32:33]
	v_mul_f32_e32 v32, v3, v3
	v_mul_f32_e32 v34, v5, v5
	v_pk_add_f32 v[28:29], v[28:29], v[28:29] op_sel:[0,1] op_sel_hi:[1,0]
	v_pk_add_f32 v[30:31], v[30:31], v[30:31] op_sel:[0,1] op_sel_hi:[1,0]
	v_pk_fma_f32 v[32:33], v[2:3], v[2:3], v[32:33] op_sel_hi:[1,1,0]
	v_pk_fma_f32 v[34:35], v[4:5], v[4:5], v[34:35] op_sel_hi:[1,1,0]
	v_pk_mul_f32 v[36:37], v[6:7], v[6:7]
	v_pk_mul_f32 v[38:39], v[8:9], v[8:9]
	v_mov_b32_e32 v29, v36
	v_mov_b32_e32 v31, v37
	v_mov_b32_e32 v33, v38
	v_mov_b32_e32 v35, v39
	v_pk_add_f32 v[28:29], v[28:29], v[30:31]
	v_pk_add_f32 v[30:31], v[32:33], v[34:35]
	s_nop 0
	v_pk_add_f32 v[28:29], v[28:29], v[30:31]
	s_nop 0
	v_add_f32_e32 v27, v28, v29
	ds_swizzle_b32 v28, v27 offset:swizzle(SWAP,1)
	s_waitcnt lgkmcnt(0)
; __device__ __forceinline__ unsigned cvt_pk_bf16(float lo, float hi) { unsigned r; asm volatile("v_cvt_pk_bf16_f32 %0, %1, %2" : "=v"(r) : "v"(lo), "v"(hi)); return r; }
; template <int O> __device__ __forceinline__ float swz_xor(float v) { return __int_as_float(__builtin_amdgcn_ds_swizzle(__float_as_int(v), (O << 10) | 0x1F)); }
; template <int EPI>
; __device__ __forceinline__ void attn_item_c(const Item& I, char* lds, int tid_in) {
;     ...
;       ss += swz_xor<1>(ss); ss += swz_xor<2>(ss); ss += swz_xor<4>(ss); ss += swz_xor<8>(ss);
;       const float rstd = 1.0f / sqrtf(ss * (1.f / 256.f) + EPS);
; #pragma unroll
;       for (int half = 0; half < 2; ++half) { const f32x4 y0 = dv[half][j][0] * rstd * gsl[half][0], y1 = dv[half][j][1] * rstd * gsl[half][1];
;         u32x4 w; w.x = cvt_pk_bf16(y0[0], y0[1]); w.y = cvt_pk_bf16(y0[2], y0[3]); w.z = cvt_pk_bf16(y1[0], y1[1]); w.w = cvt_pk_bf16(y1[2], y1[3]);
;         STG(u32x4, I.O + (size_t)(tokw + 4 * j + rsub) * DM + I.ocol + half * 128 + ch * 8) = w; } }
;   }
;   asm volatile("s_waitcnt vmcnt(0)" ::: "memory");
;   __syncthreads();
	v_add_f32_e32 v27, v27, v28
	ds_swizzle_b32 v28, v27 offset:swizzle(SWAP,2)
	s_waitcnt lgkmcnt(0)
	v_add_f32_e32 v27, v27, v28
	ds_swizzle_b32 v28, v27 offset:swizzle(SWAP,4)
	s_waitcnt lgkmcnt(0)
	v_add_f32_e32 v27, v27, v28
	ds_swizzle_b32 v28, v27 offset:swizzle(SWAP,8)
	s_waitcnt lgkmcnt(0)
	v_add_f32_e32 v27, v27, v28
	v_fmamk_f32 v27, v27, 0x3b800000, v226
	v_cmp_gt_f32_e32 vcc, s87, v27
	v_mul_f32_e32 v28, 0x4f800000, v27
	s_nop 0
	v_cndmask_b32_e32 v27, v27, v28, vcc
	v_sqrt_f32_e32 v28, v27
	s_nop 0
	v_add_u32_e32 v29, -1, v28
	v_fma_f32 v30, -v29, v28, v27
	v_cmp_ge_f32_e64 s[40:41], 0, v30
	v_add_u32_e32 v30, 1, v28
	s_nop 0
	v_cndmask_b32_e64 v29, v28, v29, s[40:41]
	v_fma_f32 v28, -v30, v28, v27
	v_cmp_lt_f32_e64 s[40:41], 0, v28
	s_nop 1
	v_cndmask_b32_e64 v28, v29, v30, s[40:41]
	v_mul_f32_e32 v29, 0x37800000, v28
	v_cndmask_b32_e32 v28, v28, v29, vcc
	v_cmp_class_f32_e32 vcc, v27, v227
	s_nop 1
	v_cndmask_b32_e32 v27, v28, v27, vcc
	v_div_scale_f32 v28, s[4:5], v27, v27, 1.0
	v_rcp_f32_e32 v29, v28
	s_nop 0
	v_fma_f32 v30, -v28, v29, 1.0
	v_fmac_f32_e32 v29, v30, v29
	v_div_scale_f32 v30, vcc, 1.0, v27, 1.0
	v_mul_f32_e32 v31, v30, v29
	v_fma_f32 v32, -v28, v31, v30
	v_fmac_f32_e32 v31, v32, v29
	v_fma_f32 v28, -v28, v31, v30
	v_div_fmas_f32 v28, v28, v29, v31
	v_div_fixup_f32 v28, v28, v27, 1.0
	v_pk_mul_f32 v[32:33], v[66:67], v[28:29] op_sel_hi:[1,0]
	v_ashrrev_i32_e32 v27, 31, v26
	v_pk_mul_f32 v[30:31], v[70:71], v[28:29] op_sel_hi:[1,0]
	v_pk_mul_f32 v[16:17], v[16:17], v[32:33]
	v_pk_mul_f32 v[32:33], v[68:69], v[28:29] op_sel_hi:[1,0]
	v_lshlrev_b64 v[26:27], 12, v[26:27]
	v_pk_mul_f32 v[12:13], v[12:13], v[30:31]
	v_pk_mul_f32 v[30:31], v[72:73], v[28:29] op_sel_hi:[1,0]
	v_pk_mul_f32 v[14:15], v[14:15], v[32:33]
	v_pk_mul_f32 v[30:31], v[10:11], v[30:31]
	v_cvt_pk_bf16_f32 v10, v12, v13
	v_cvt_pk_bf16_f32 v11, v16, v17
	v_pk_mul_f32 v[2:3], v[2:3], v[28:29] op_sel_hi:[1,0]
	v_cvt_pk_bf16_f32 v12, v30, v31
	v_cvt_pk_bf16_f32 v13, v14, v15
	v_lshl_add_u64 v[14:15], s[48:49], 0, v[26:27]
	v_lshl_add_u64 v[14:15], v[14:15], 0, s[52:53]
	v_pk_mul_f32 v[4:5], v[4:5], v[28:29] op_sel_hi:[1,0]
	v_lshl_add_u64 v[14:15], v[14:15], 0, v[0:1]
	v_pk_mul_f32 v[4:5], v[24:25], v[4:5]
	v_pk_mul_f32 v[2:3], v[20:21], v[2:3]
	v_pk_mul_f32 v[6:7], v[6:7], v[28:29] op_sel_hi:[1,0]
	v_pk_mul_f32 v[8:9], v[8:9], v[28:29] op_sel_hi:[1,0]
	global_store_dwordx4 v[14:15], v[10:13], off
	v_pk_mul_f32 v[8:9], v[22:23], v[8:9]
	v_pk_mul_f32 v[6:7], v[18:19], v[6:7]
	v_cvt_pk_bf16_f32 v2, v2, v3
	v_cvt_pk_bf16_f32 v3, v4, v5
	s_nop 0
	v_cvt_pk_bf16_f32 v4, v6, v7
	v_cvt_pk_bf16_f32 v5, v8, v9
	global_store_dwordx4 v[14:15], v[2:5], off offset:256
	s_waitcnt vmcnt(0)
	s_barrier

; template <int EPI>
; __device__ __forceinline__ void attn_item_c(const Item& I, char* lds, int tid_in) {
;     ...
;   asm volatile("s_waitcnt vmcnt(0)" ::: "memory"); __syncthreads();
;   float qkb;
;   { float q2 = xw[0];
; #pragma unroll
;     for (int w = 1; w < 8; ++w) q2 = fmaxf(q2, xw[w]);
;     qkb = __uint_as_float(__builtin_amdgcn_readfirstlane(__float_as_uint(1.01f * sqrtf(q2 * LDG(float, I.kmax2))))); }
; __device__ __forceinline__ void phase_attn_c(const Frame& F0) {
;     ...
;     I.W = 4096; I.qcol = hq * 256; I.kcol = 2048 + kvh * 256; I.vcol = 3072 + kvh * 256; I.ocol = hq * 256;
;     I.nslope = -exp2f(-(float)(hq + 1)) * LOG2E; I.sink2 = 0.f; I.nlam = nlam; I.subg = subg;
;     I.kmax2 = (const float*)(F.ws + WS_KMAX) + batch_of(seq_base) * 8 + kvh * 2;
.LBB0_830:
	s_or_b64 exec, exec, s[4:5]
	s_add_i32 s4, s7, 1
	v_cvt_f32_i32_e32 v4, s4
	s_mov_b32 s4, 0x42fc0000
	s_waitcnt vmcnt(0)
	v_cmp_lt_f32_e32 vcc, s4, v4
	s_and_b64 s[4:5], vcc, exec
	s_cselect_b32 s4, 0xffffffc0, 0
	v_cndmask_b32_e32 v5, 0, v230, vcc
	v_sub_f32_e32 v4, v5, v4
	v_exp_f32_e32 v4, v4
	s_lshr_b32 s27, s56, 11
	s_barrier
	v_ldexp_f32 v4, v4, s4
	v_mul_f32_e32 v214, 0xbfb8aa3b, v4
	v_mov_b32_e32 v4, 0x2000
	v_sub_co_u32_e32 v4, vcc, s56, v4
	s_nop 0
	v_readfirstlane_b32 s4, v4
	s_lshr_b32 s4, s4, 12
	s_add_i32 s28, s4, 4
	s_and_b64 s[4:5], vcc, exec
	s_cselect_b32 s4, s27, s28
	s_lshl_b32 s4, s4, 5
	v_readlane_b32 s5, v255, 62
	s_add_u32 s27, s5, s4
	s_addc_u32 s28, s61, 0
	s_and_b32 s4, s7, -2
	s_ashr_i32 s5, s4, 31
	s_lshl_b64 s[4:5], s[4:5], 2
	s_add_u32 s54, s27, s4
	s_addc_u32 s55, s28, s5
	global_load_dword v43, v1, s[54:55]
	v_lshlrev_b32_e32 v246, 2, v244
	v_sub_u32_e32 v2, v246, v2
	v_cvt_f32_i32_e32 v247, v2
	v_cvt_f32_u32_e32 v240, s72
	s_mov_b32 s28, 2.0
	s_mov_b32 s29, 0x40400000
	v_lshlrev_b32_e32 v2, 1, v241
	v_add_f32_e32 v20, v240, v247
	v_pk_add_f32 v[22:23], v[20:21], s[28:29] op_sel_hi:[0,1]
	s_mov_b32 s28, 0x41000000
	s_mov_b32 s29, 0x41100000
	v_pk_add_f32 v[24:25], v[20:21], s[28:29] op_sel_hi:[0,1]
	s_mov_b32 s28, 0x41200000
	s_mov_b32 s29, 0x41300000
	v_pk_add_f32 v[26:27], v[20:21], s[28:29] op_sel_hi:[0,1]
	s_mov_b32 s28, 0x41800000
	s_mov_b32 s29, 0x41880000
	v_pk_add_f32 v[28:29], v[20:21], s[28:29] op_sel_hi:[0,1]
	s_mov_b32 s28, 0x41900000
	s_mov_b32 s29, 0x41980000
	v_pk_add_f32 v[30:31], v[20:21], s[28:29] op_sel_hi:[0,1]
	s_mov_b32 s28, 0x41c00000
	s_mov_b32 s29, 0x41c80000
	v_pk_add_f32 v[32:33], v[20:21], s[28:29] op_sel_hi:[0,1]
	s_mov_b32 s28, 0x41d00000
	s_mov_b32 s29, 0x41d80000
	v_pk_add_f32 v[34:35], v[20:21], s[28:29] op_sel_hi:[0,1]
	s_mov_b32 s28, 0x42680000
	s_mov_b32 s29, 0x426c0000
	v_and_b32_e32 v40, 32, v2
	v_and_b32_e32 v41, 0xc0, v3
	v_pk_add_f32 v[2:3], v[20:21], s[28:29] op_sel_hi:[0,1]
	s_mov_b32 s28, 0x42600000
	s_mov_b32 s29, 0x42640000
	v_pk_add_f32 v[4:5], v[20:21], s[28:29] op_sel_hi:[0,1]
	s_mov_b32 s28, 0x42480000
	s_mov_b32 s29, 0x424c0000
	v_pk_add_f32 v[6:7], v[20:21], s[28:29] op_sel_hi:[0,1]
	s_mov_b32 s28, 0x42400000
	s_mov_b32 s29, 0x42440000
	v_pk_add_f32 v[8:9], v[20:21], s[28:29] op_sel_hi:[0,1]
	s_mov_b32 s28, 0x42280000
	s_mov_b32 s29, 0x422c0000
	v_pk_add_f32 v[10:11], v[20:21], s[28:29] op_sel_hi:[0,1]
	s_mov_b32 s28, 0x42200000
	s_mov_b32 s29, 0x42240000
	v_pk_add_f32 v[12:13], v[20:21], s[28:29] op_sel_hi:[0,1]
	s_mov_b32 s28, 0x42080000
	s_mov_b32 s29, 0x420c0000
	v_pk_add_f32 v[14:15], v[20:21], s[28:29] op_sel_hi:[0,1]
	s_mov_b32 s28, 0x42000000
	s_mov_b32 s29, 0x42040000
	s_add_i32 s85, 0, 0x20840
	v_add_f32_e32 v42, 1.0, v20
	v_pk_add_f32 v[16:17], v[20:21], s[28:29] op_sel_hi:[0,1]
	v_and_b32_e32 v37, 0x7fffffff, v23
	v_and_b32_e32 v36, 0x7fffffff, v22
	v_and_b32_e32 v38, 0x7fffffff, v24
	v_and_b32_e32 v24, 0x7fffffff, v26
	v_and_b32_e32 v26, 0x7fffffff, v28
	v_and_b32_e32 v23, 0x7fffffff, v31
	v_and_b32_e32 v22, 0x7fffffff, v30
	v_and_b32_e32 v28, 0x7fffffff, v32
	v_and_b32_e32 v32, 0x7fffffff, v20
	v_mov_b32_e32 v20, s85
	v_and_b32_e32 v44, 0x100, v21
	v_pk_fma_f32 v[156:157], v[22:23], v[214:215], 0 op_sel_hi:[1,0,0]
	ds_read_b128 v[20:23], v20
	v_and_b32_e32 v39, 0x7fffffff, v25
	v_and_b32_e32 v25, 0x7fffffff, v27
	v_readlane_b32 s5, v255, 55
	v_and_b32_e32 v27, 0x7fffffff, v29
	v_pk_fma_f32 v[152:153], v[24:25], v[214:215], 0 op_sel_hi:[1,0,0]
	v_mov_b32_e32 v24, s5
	v_pk_fma_f32 v[154:155], v[26:27], v[214:215], 0 op_sel_hi:[1,0,0]
	ds_read_b128 v[24:27], v24
	s_waitcnt lgkmcnt(1)
	v_max_f32_e32 v21, v21, v21
	v_max_f32_e32 v20, v20, v20
	v_max_f32_e32 v20, v20, v21
	v_max3_f32 v20, v20, v22, v23
	s_waitcnt lgkmcnt(0)
	v_max3_f32 v20, v20, v24, v25
	v_max3_f32 v20, v20, v26, v27
	s_waitcnt vmcnt(0)
; #define BI2(R) do { constexpr float c_ = (float)(((R) & 3) + 8 * ((R) >> 2)); p0[R] = fmaf(fabsf(dubn + c_), nslope, negm); p1[R] = fmaf(fabsf(dubn + (c_ + 32.f)), nslope, negm); } while (0)
; template <int EPI>
; __device__ __forceinline__ void attn_item_c(const Item& I, char* lds, int tid_in) {
;     ...
;   { const float dubn = dq + (float)(64 * CT(0)), nslope = I.nslope, negm = 0.f;
;     BI2(0); BI2(1); BI2(2); BI2(3); BI2(4); BI2(5); BI2(6); BI2(7); BI2(8); BI2(9); BI2(10); BI2(11); BI2(12); BI2(13); BI2(14); BI2(15); }
;     ...
;   float qkb;
;   { float q2 = xw[0];
; #pragma unroll
;     for (int w = 1; w < 8; ++w) q2 = fmaxf(q2, xw[w]);
;     qkb = __uint_as_float(__builtin_amdgcn_readfirstlane(__float_as_uint(1.01f * sqrtf(q2 * LDG(float, I.kmax2))))); }
;   int R = NT, Lw = 0;
;   for (int n = 0, step = 0;; ++step) { const int bsel = step & 1;
	v_mul_f32_e32 v20, v20, v43
	v_mul_f32_e32 v21, 0x4f800000, v20
	v_cmp_gt_f32_e32 vcc, s60, v20
	s_and_b32 s4, s12, 0x3fffffc0
	s_lshl_b32 s4, s4, 2
	v_cndmask_b32_e32 v20, v20, v21, vcc
	v_sqrt_f32_e32 v21, v20
	s_movk_i32 s7, 0x70
	s_add_i32 s4, s4, 0
	s_add_i32 s4, s4, 0x20000
	v_add_u32_e32 v22, -1, v21
	v_fma_f32 v23, -v22, v21, v20
	v_cmp_ge_f32_e64 s[42:43], 0, v23
	v_add_u32_e32 v23, 1, v21
	v_and_b32_e32 v17, 0x7fffffff, v17
	v_cndmask_b32_e64 v22, v21, v22, s[42:43]
	v_fma_f32 v21, -v23, v21, v20
	v_cmp_lt_f32_e64 s[42:43], 0, v21
	v_and_b32_e32 v16, 0x7fffffff, v16
	v_and_b32_e32 v15, 0x7fffffff, v15
	v_cndmask_b32_e64 v21, v22, v23, s[42:43]
	v_mul_f32_e32 v22, 0x37800000, v21
	v_cndmask_b32_e32 v21, v21, v22, vcc
	v_cmp_class_f32_e32 vcc, v20, v227
	v_mov_b32_e32 v22, 0x3f8147ae
	v_and_b32_e32 v14, 0x7fffffff, v14
	v_cndmask_b32_e32 v20, v21, v20, vcc
	v_and_b32_e32 v13, 0x7fffffff, v13
	v_readfirstlane_b32 s5, v20
	v_lshlrev_b32_e32 v20, 4, v243
	v_and_b32_e32 v21, 0x70, v20
	v_bitop3_b32 v249, v18, v20, s7 bitop3:0x78
	v_mov_b32_e32 v20, 0x43180000
	v_fma_f32 v250, s5, v22, v20
	s_movk_i32 s5, 0xe0
	v_and_b32_e32 v12, 0x7fffffff, v12
	v_and_b32_e32 v11, 0x7fffffff, v11
	v_and_b32_e32 v10, 0x7fffffff, v10
	v_and_b32_e32 v9, 0x7fffffff, v9
	v_and_b32_e32 v8, 0x7fffffff, v8
	v_and_b32_e32 v7, 0x7fffffff, v7
	v_and_b32_e32 v6, 0x7fffffff, v6
	v_and_b32_e32 v5, 0x7fffffff, v5
	v_and_b32_e32 v4, 0x7fffffff, v4
	v_and_b32_e32 v3, 0x7fffffff, v3
	v_and_b32_e32 v2, 0x7fffffff, v2
	v_pk_fma_f32 v[130:131], v[16:17], v[214:215], 0 op_sel_hi:[1,0,0]
	v_mov_b32_e32 v16, v1
	v_mov_b32_e32 v17, v1
	v_and_b32_e32 v29, 0x7fffffff, v33
	v_and_b32_e32 v31, 0x7fffffff, v35
	v_and_b32_e32 v30, 0x7fffffff, v34
	v_and_b32_e32 v33, 0x7fffffff, v42
	v_bitop3_b32 v251, v18, v21, 32 bitop3:0x36
	v_bitop3_b32 v252, v18, v21, 64 bitop3:0x36
	v_bitop3_b32 v233, v18, v21, s30 bitop3:0x36
	v_bitop3_b32 v253, v18, v21, s35 bitop3:0x36
	v_bitop3_b32 v228, v18, v21, s31 bitop3:0x36
	v_bitop3_b32 v234, v18, v21, s34 bitop3:0x36
	v_bitop3_b32 v231, v18, v21, s5 bitop3:0x36
	v_add_u32_e32 v245, s4, v18
	v_or3_b32 v18, v41, v44, v19
	v_pk_fma_f32 v[144:145], v[2:3], v[214:215], 0 op_sel_hi:[1,0,0]
	v_pk_fma_f32 v[142:143], v[4:5], v[214:215], 0 op_sel_hi:[1,0,0]
	v_pk_fma_f32 v[140:141], v[6:7], v[214:215], 0 op_sel_hi:[1,0,0]
	v_pk_fma_f32 v[138:139], v[8:9], v[214:215], 0 op_sel_hi:[1,0,0]
	v_pk_fma_f32 v[136:137], v[10:11], v[214:215], 0 op_sel_hi:[1,0,0]
	v_pk_fma_f32 v[134:135], v[12:13], v[214:215], 0 op_sel_hi:[1,0,0]
	v_pk_fma_f32 v[132:133], v[14:15], v[214:215], 0 op_sel_hi:[1,0,0]
	v_mov_b32_e32 v2, v1
	v_mov_b32_e32 v3, v1
	v_mov_b32_e32 v4, v1
	v_mov_b32_e32 v5, v1
	v_mov_b32_e32 v6, v1
	v_mov_b32_e32 v7, v1
	v_mov_b32_e32 v8, v1
	v_mov_b32_e32 v9, v1
	v_mov_b32_e32 v10, v1
	v_mov_b32_e32 v11, v1
	v_mov_b32_e32 v12, v1
	v_mov_b32_e32 v13, v1
	v_mov_b32_e32 v14, v1
	v_mov_b32_e32 v15, v1
	v_pk_fma_f32 v[160:161], v[30:31], v[214:215], 0 op_sel_hi:[1,0,0]
	v_pk_fma_f32 v[158:159], v[28:29], v[214:215], 0 op_sel_hi:[1,0,0]
	v_pk_fma_f32 v[150:151], v[38:39], v[214:215], 0 op_sel_hi:[1,0,0]
	v_pk_fma_f32 v[148:149], v[36:37], v[214:215], 0 op_sel_hi:[1,0,0]
	v_pk_fma_f32 v[146:147], v[32:33], v[214:215], 0 op_sel_hi:[1,0,0]
	s_sub_i32 s67, s36, s25
	v_add3_u32 v210, v40, 0, v18
	v_mov_b64_e32 v[64:65], v[16:17]
	v_mov_b64_e32 v[48:49], v[16:17]
	v_mov_b64_e32 v[32:33], v[16:17]
	v_mov_b64_e32 v[128:129], v[16:17]
	v_mov_b64_e32 v[112:113], v[16:17]
	v_mov_b64_e32 v[96:97], v[16:17]
	v_mov_b64_e32 v[80:81], v[16:17]
	v_mov_b32_e32 v219, v1
	v_mov_b32_e32 v221, v1
	s_mov_b32 s95, 0
	v_mov_b32_e32 v216, v214
	v_mov_b32_e32 v217, v214
	v_mov_b32_e32 v230, 0x260
	s_add_i32 s67, s67, -4
	v_cmp_gt_u32_e64 s[42:43], 32, v241
	v_lshl_add_u32 v248, v243, 2, s4
	s_add_i32 s96, s85, s6
	v_mov_b32_e32 v211, 0
	v_mov_b64_e32 v[62:63], v[14:15]
	v_mov_b64_e32 v[60:61], v[12:13]
	v_mov_b64_e32 v[58:59], v[10:11]
	v_mov_b64_e32 v[56:57], v[8:9]
	v_mov_b64_e32 v[54:55], v[6:7]
	v_mov_b64_e32 v[52:53], v[4:5]
	v_mov_b64_e32 v[50:51], v[2:3]
	v_mov_b64_e32 v[46:47], v[14:15]
	v_mov_b64_e32 v[44:45], v[12:13]
	v_mov_b64_e32 v[42:43], v[10:11]
	v_mov_b64_e32 v[40:41], v[8:9]
	v_mov_b64_e32 v[38:39], v[6:7]
	v_mov_b64_e32 v[36:37], v[4:5]
	v_mov_b64_e32 v[34:35], v[2:3]
	v_mov_b64_e32 v[30:31], v[14:15]
	v_mov_b64_e32 v[28:29], v[12:13]
	v_mov_b64_e32 v[26:27], v[10:11]
	v_mov_b64_e32 v[24:25], v[8:9]
	v_mov_b64_e32 v[22:23], v[6:7]
	v_mov_b64_e32 v[20:21], v[4:5]
	v_mov_b64_e32 v[18:19], v[2:3]
	v_mov_b64_e32 v[126:127], v[14:15]
	v_mov_b64_e32 v[124:125], v[12:13]
	v_mov_b64_e32 v[122:123], v[10:11]
	v_mov_b64_e32 v[120:121], v[8:9]
	v_mov_b64_e32 v[118:119], v[6:7]
	v_mov_b64_e32 v[116:117], v[4:5]
	v_mov_b64_e32 v[114:115], v[2:3]
	v_mov_b64_e32 v[110:111], v[14:15]
	v_mov_b64_e32 v[108:109], v[12:13]
	v_mov_b64_e32 v[106:107], v[10:11]
	v_mov_b64_e32 v[104:105], v[8:9]
	v_mov_b64_e32 v[102:103], v[6:7]
	v_mov_b64_e32 v[100:101], v[4:5]
	v_mov_b64_e32 v[98:99], v[2:3]
	v_mov_b64_e32 v[94:95], v[14:15]
	v_mov_b64_e32 v[92:93], v[12:13]
	v_mov_b64_e32 v[90:91], v[10:11]
	v_mov_b64_e32 v[88:89], v[8:9]
	v_mov_b64_e32 v[86:87], v[6:7]
	v_mov_b64_e32 v[84:85], v[4:5]
	v_mov_b64_e32 v[82:83], v[2:3]
	v_mov_b64_e32 v[78:79], v[14:15]
	v_mov_b64_e32 v[76:77], v[12:13]
	v_mov_b64_e32 v[74:75], v[10:11]
	v_mov_b64_e32 v[72:73], v[8:9]
	v_mov_b64_e32 v[70:71], v[6:7]
	v_mov_b64_e32 v[68:69], v[4:5]
	v_mov_b64_e32 v[66:67], v[2:3]
	s_mov_b32 s4, 0
	s_mov_b32 s97, 0
	s_mov_b32 s12, s36
	v_mov_b32_e32 v224, 0
	s_cmp_lg_u32 s95, 4
	s_cbranch_scc1 .LBB0_832

; #define BI2(R) do { constexpr float c_ = (float)(((R) & 3) + 8 * ((R) >> 2)); p0[R] = fmaf(fabsf(dubn + c_), nslope, negm); p1[R] = fmaf(fabsf(dubn + (c_ + 32.f)), nslope, negm); } while (0)
; #define VRD4(S, D0, KS, vb) s16x4 S##l0 = tr_read<v_rd_off(D0, KS, 0)>(vb), S##h0 = tr_read<v_rd_off(D0, KS, 1)>(vb), S##l1 = tr_read<v_rd_off(D0, KS + 1, 0)>(vb), S##h1 = tr_read<v_rd_off(D0, KS + 1, 1)>(vb)
; #define VWT4(S, N) asm volatile("s_waitcnt lgkmcnt(" #N ")" : "+v"(S##l0), "+v"(S##h0), "+v"(S##l1), "+v"(S##h1) :: "memory")
; #define VMM2(S, od, PA, PB) do { od = __builtin_amdgcn_mfma_f32_32x32x16_bf16(PA, VPK(S##l0, S##h0), od, 0, 0, 0); od = __builtin_amdgcn_mfma_f32_32x32x16_bf16(PB, VPK(S##l1, S##h1), od, 0, 0, 0); } while (0)
; __device__ __forceinline__ void pv_pipe8b(f32x16* oA, f32x16* oB, int vbA, int vbB, bf16x8 pa0, bf16x8 pa1, bf16x8 pa2, bf16x8 pa3, f32x16& p0, f32x16& p1, float dubn, float nslope, float negm) {
;   VRD4(h0, 0, 0, vbA);
;   VRD4(h1, 0, 2, vbA); VWT4(h0, 4); VMM2(h0, oA[0], pa0, pa1); BI2(0);
;   VRD4(h2, 1, 0, vbA); VWT4(h1, 4); VMM2(h1, oA[0], pa2, pa3); BI2(1);
;   VRD4(h3, 1, 2, vbA); VWT4(h2, 4); VMM2(h2, oA[1], pa0, pa1); BI2(2);
;   VRD4(h4, 2, 0, vbA); VWT4(h3, 4); VMM2(h3, oA[1], pa2, pa3); BI2(3);
;   VRD4(h5, 2, 2, vbA); VWT4(h4, 4); VMM2(h4, oA[2], pa0, pa1); BI2(4);
;   VRD4(h6, 3, 0, vbA); VWT4(h5, 4); VMM2(h5, oA[2], pa2, pa3); BI2(5);
;   VRD4(h7, 3, 2, vbA); VWT4(h6, 4); VMM2(h6, oA[3], pa0, pa1); BI2(6);
;   VRD4(h8, 0, 0, vbB); VWT4(h7, 4); VMM2(h7, oA[3], pa2, pa3); BI2(7);
;   VRD4(h9, 0, 2, vbB); VWT4(h8, 4); VMM2(h8, oB[0], pa0, pa1); BI2(8);
; __device__ __forceinline__ void finishSM(f32x16& p0, f32x16& p1, float alpha, float& l_reg, bf16x8& pa0, bf16x8& pa1, bf16x8& pa2, bf16x8& pa3) {
; #pragma unroll
;   for (int r = 0; r < 16; ++r) p1[r] = __builtin_amdgcn_exp2f(p1[r]);
;   float ps = 0;
; #pragma unroll
;   for (int r = 0; r < 16; ++r) ps += p0[r];
; #pragma unroll
;   for (int r = 0; r < 16; ++r) ps += p1[r];
;   { auto rr = __builtin_amdgcn_permlane32_swap(__float_as_uint(ps), __float_as_uint(ps), false, false);
;     ps = __uint_as_float(rr[0]) + __uint_as_float(rr[1]); }
;   l_reg = l_reg * alpha + ps;
;     ...
;   PK4(p0, 0, pa0); PK4(p0, 8, pa1); PK4(p1, 0, pa2); PK4(p1, 8, pa3);
.LBB0_843:
	v_exp_f32_e32 v146, v146
	v_exp_f32_e32 v147, v147
	v_exp_f32_e32 v148, v148
	v_exp_f32_e32 v149, v149
	v_exp_f32_e32 v150, v150
	v_exp_f32_e32 v196, v130
	v_add_f32_e32 v130, 0, v146
	v_exp_f32_e32 v151, v151
	v_add_f32_e32 v130, v147, v130
	v_exp_f32_e32 v152, v152
	v_add_f32_e32 v130, v148, v130
	v_exp_f32_e32 v153, v153
	v_add_f32_e32 v130, v149, v130
	v_exp_f32_e32 v154, v154
	v_add_f32_e32 v130, v150, v130
	v_exp_f32_e32 v155, v155
	v_add_f32_e32 v130, v151, v130
	v_exp_f32_e32 v156, v156
	v_add_f32_e32 v130, v152, v130
	v_exp_f32_e32 v157, v157
	v_add_f32_e32 v130, v153, v130
	v_exp_f32_e32 v158, v158
	v_add_f32_e32 v130, v154, v130
	v_exp_f32_e32 v159, v159
	v_add_f32_e32 v130, v155, v130
	v_exp_f32_e32 v160, v160
	v_add_f32_e32 v130, v156, v130
	v_exp_f32_e32 v161, v161
	v_add_f32_e32 v130, v157, v130
	v_add_f32_e32 v130, v158, v130
	v_exp_f32_e32 v197, v131
	v_add_f32_e32 v130, v159, v130
	v_exp_f32_e32 v198, v132
	v_add_f32_e32 v130, v160, v130
	v_exp_f32_e32 v199, v133
	v_add_f32_e32 v130, v161, v130
	v_exp_f32_e32 v200, v134
	v_add_f32_e32 v130, v196, v130
	v_exp_f32_e32 v201, v135
	v_add_f32_e32 v130, v197, v130
	v_exp_f32_e32 v202, v136
	v_add_f32_e32 v130, v198, v130
	v_exp_f32_e32 v203, v137
	v_add_f32_e32 v130, v199, v130
	v_exp_f32_e32 v204, v138
	v_add_f32_e32 v130, v200, v130
	v_exp_f32_e32 v205, v139
	v_add_f32_e32 v130, v201, v130
	v_exp_f32_e32 v206, v140
	v_add_f32_e32 v130, v202, v130
	v_exp_f32_e32 v207, v141
	v_add_f32_e32 v130, v203, v130
	v_exp_f32_e32 v208, v142
	v_add_f32_e32 v130, v204, v130
	v_exp_f32_e32 v209, v143
	v_add_f32_e32 v130, v205, v130
	v_exp_f32_e32 v213, v144
	v_add_f32_e32 v130, v206, v130
	v_exp_f32_e32 v145, v145
	v_add_f32_e32 v130, v207, v130
	v_add_f32_e32 v130, v208, v130
	v_add_f32_e32 v130, v209, v130
	v_add_f32_e32 v130, v213, v130
	v_add_f32_e32 v194, v145, v130
	v_mov_b32_e32 v195, v194
	v_cvt_pk_bf16_f32 v130, v146, v147
	v_cvt_pk_bf16_f32 v131, v148, v149
	v_cvt_pk_bf16_f32 v132, v150, v151
	v_cvt_pk_bf16_f32 v133, v152, v153
	v_cvt_pk_bf16_f32 v134, v154, v155
	v_cvt_pk_bf16_f32 v135, v156, v157
	v_cvt_pk_bf16_f32 v136, v158, v159
	v_cvt_pk_bf16_f32 v137, v160, v161
	v_cvt_pk_bf16_f32 v138, v196, v197
	v_cvt_pk_bf16_f32 v139, v198, v199
	v_cvt_pk_bf16_f32 v140, v200, v201
	v_cvt_pk_bf16_f32 v141, v202, v203
	v_cvt_pk_bf16_f32 v142, v204, v205
	v_cvt_pk_bf16_f32 v143, v206, v207
	v_cvt_pk_bf16_f32 v144, v208, v209
	v_cvt_pk_bf16_f32 v145, v213, v145
	s_nop 1
	v_permlane32_swap_b32_e32 v194, v195
	v_permlane32_swap_b32_e32 v130, v132
	v_permlane32_swap_b32_e32 v131, v133
	v_permlane32_swap_b32_e32 v134, v136
	v_permlane32_swap_b32_e32 v135, v137
	v_permlane32_swap_b32_e32 v138, v140
	v_permlane32_swap_b32_e32 v139, v141
	v_permlane32_swap_b32_e32 v142, v144
	v_permlane32_swap_b32_e32 v143, v145
	v_add_u32_e32 v196, s27, v210
	ds_read_b64_tr_b16 v[146:147], v196 offset:0
	ds_read_b64_tr_b16 v[148:149], v196 offset:0x800
	ds_read_b64_tr_b16 v[150:151], v196 offset:0x1000
	ds_read_b64_tr_b16 v[152:153], v196 offset:0x1800
	ds_read_b64_tr_b16 v[154:155], v196 offset:0x2000
	ds_read_b64_tr_b16 v[156:157], v196 offset:0x2800
	ds_read_b64_tr_b16 v[158:159], v196 offset:0x3000
	ds_read_b64_tr_b16 v[160:161], v196 offset:0x3800
	v_add_u32_e32 v197, 0x4000, v196
	s_waitcnt lgkmcnt(4)
	s_mov_b64 s[4:5], -1
	v_mfma_f32_32x32x16_bf16 v[114:129], v[130:133], v[146:149], v[114:129]
	ds_read_b64_tr_b16 v[146:147], v196 offset:0x200
	ds_read_b64_tr_b16 v[148:149], v196 offset:0xa00
	s_andn2_b64 vcc, exec, s[52:53]
	v_mfma_f32_32x32x16_bf16 v[114:129], v[134:137], v[150:153], v[114:129]
	ds_read_b64_tr_b16 v[150:151], v196 offset:0x1200
	ds_read_b64_tr_b16 v[152:153], v196 offset:0x1a00
	s_waitcnt lgkmcnt(4)
	s_nop 0
	v_mfma_f32_32x32x16_bf16 v[114:129], v[138:141], v[154:157], v[114:129]
	ds_read_b64_tr_b16 v[154:155], v196 offset:0x2200
	ds_read_b64_tr_b16 v[156:157], v196 offset:0x2a00
	v_mfma_f32_32x32x16_bf16 v[114:129], v[142:145], v[158:161], v[114:129]
	ds_read_b64_tr_b16 v[158:159], v196 offset:0x3200
	ds_read_b64_tr_b16 v[160:161], v196 offset:0x3a00
	s_waitcnt lgkmcnt(4)
	s_nop 0
	v_mfma_f32_32x32x16_bf16 v[98:113], v[130:133], v[146:149], v[98:113]
	ds_read_b64_tr_b16 v[146:147], v196 offset:0x400
	ds_read_b64_tr_b16 v[148:149], v196 offset:0xc00
	v_mfma_f32_32x32x16_bf16 v[98:113], v[134:137], v[150:153], v[98:113]
	ds_read_b64_tr_b16 v[150:151], v196 offset:0x1400
	ds_read_b64_tr_b16 v[152:153], v196 offset:0x1c00
	s_waitcnt lgkmcnt(4)
	s_nop 0
	v_mfma_f32_32x32x16_bf16 v[98:113], v[138:141], v[154:157], v[98:113]
	ds_read_b64_tr_b16 v[154:155], v196 offset:0x2400
	ds_read_b64_tr_b16 v[156:157], v196 offset:0x2c00
	v_mfma_f32_32x32x16_bf16 v[98:113], v[142:145], v[158:161], v[98:113]
	ds_read_b64_tr_b16 v[158:159], v196 offset:0x3400
	ds_read_b64_tr_b16 v[160:161], v196 offset:0x3c00
	s_waitcnt lgkmcnt(4)
	s_nop 0
	v_mfma_f32_32x32x16_bf16 v[82:97], v[130:133], v[146:149], v[82:97]
	ds_read_b64_tr_b16 v[146:147], v196 offset:0x600
	ds_read_b64_tr_b16 v[148:149], v196 offset:0xe00
	v_mfma_f32_32x32x16_bf16 v[82:97], v[134:137], v[150:153], v[82:97]
	ds_read_b64_tr_b16 v[150:151], v196 offset:0x1600
	ds_read_b64_tr_b16 v[152:153], v196 offset:0x1e00
	s_waitcnt lgkmcnt(4)
	s_nop 0
	v_mfma_f32_32x32x16_bf16 v[82:97], v[138:141], v[154:157], v[82:97]
	ds_read_b64_tr_b16 v[154:155], v196 offset:0x2600
	ds_read_b64_tr_b16 v[156:157], v196 offset:0x2e00
	v_mfma_f32_32x32x16_bf16 v[82:97], v[142:145], v[158:161], v[82:97]
	ds_read_b64_tr_b16 v[158:159], v196 offset:0x3600
	ds_read_b64_tr_b16 v[160:161], v196 offset:0x3e00
	s_waitcnt lgkmcnt(4)
; #define BI2(R) do { constexpr float c_ = (float)(((R) & 3) + 8 * ((R) >> 2)); p0[R] = fmaf(fabsf(dubn + c_), nslope, negm); p1[R] = fmaf(fabsf(dubn + (c_ + 32.f)), nslope, negm); } while (0)
; #define VRD4(S, D0, KS, vb) s16x4 S##l0 = tr_read<v_rd_off(D0, KS, 0)>(vb), S##h0 = tr_read<v_rd_off(D0, KS, 1)>(vb), S##l1 = tr_read<v_rd_off(D0, KS + 1, 0)>(vb), S##h1 = tr_read<v_rd_off(D0, KS + 1, 1)>(vb)
; #define VWT4(S, N) asm volatile("s_waitcnt lgkmcnt(" #N ")" : "+v"(S##l0), "+v"(S##h0), "+v"(S##l1), "+v"(S##h1) :: "memory")
; #define VMM2(S, od, PA, PB) do { od = __builtin_amdgcn_mfma_f32_32x32x16_bf16(PA, VPK(S##l0, S##h0), od, 0, 0, 0); od = __builtin_amdgcn_mfma_f32_32x32x16_bf16(PB, VPK(S##l1, S##h1), od, 0, 0, 0); } while (0)
; __device__ __forceinline__ void pv_pipe8b(f32x16* oA, f32x16* oB, int vbA, int vbB, bf16x8 pa0, bf16x8 pa1, bf16x8 pa2, bf16x8 pa3, f32x16& p0, f32x16& p1, float dubn, float nslope, float negm) {
;     ...
;   VRD4(h9, 0, 2, vbB); VWT4(h8, 4); VMM2(h8, oB[0], pa0, pa1); BI2(8);
;   VRD4(h10, 1, 0, vbB); VWT4(h9, 4); VMM2(h9, oB[0], pa2, pa3); BI2(9);
;   VRD4(h11, 1, 2, vbB); VWT4(h10, 4); VMM2(h10, oB[1], pa0, pa1); BI2(10);
;   VRD4(h12, 2, 0, vbB); VWT4(h11, 4); VMM2(h11, oB[1], pa2, pa3); BI2(11);
;   VRD4(h13, 2, 2, vbB); VWT4(h12, 4); VMM2(h12, oB[2], pa0, pa1); BI2(12);
;   VRD4(h14, 3, 0, vbB); VWT4(h13, 4); VMM2(h13, oB[2], pa2, pa3); BI2(13);
;   VRD4(h15, 3, 2, vbB); VWT4(h14, 4); VMM2(h14, oB[3], pa0, pa1); BI2(14);
;   VWT4(h15, 0); VMM2(h15, oB[3], pa2, pa3); BI2(15);
; template <int EPI>
; __device__ __forceinline__ void attn_item_c(const Item& I, char* lds, int tid_in) {
;     ...
;     asm volatile("s_waitcnt vmcnt(0)" ::: "memory");
;     __syncthreads();
	s_nop 0
	v_mfma_f32_32x32x16_bf16 v[66:81], v[130:133], v[146:149], v[66:81]
	ds_read_b64_tr_b16 v[146:147], v197 offset:0
	ds_read_b64_tr_b16 v[148:149], v197 offset:0x800
	v_mfma_f32_32x32x16_bf16 v[66:81], v[134:137], v[150:153], v[66:81]
	ds_read_b64_tr_b16 v[150:151], v197 offset:0x1000
	ds_read_b64_tr_b16 v[152:153], v197 offset:0x1800
	s_waitcnt lgkmcnt(4)
	s_nop 0
	v_mfma_f32_32x32x16_bf16 v[66:81], v[138:141], v[154:157], v[66:81]
	ds_read_b64_tr_b16 v[154:155], v197 offset:0x2000
	ds_read_b64_tr_b16 v[156:157], v197 offset:0x2800
	v_mfma_f32_32x32x16_bf16 v[66:81], v[142:145], v[158:161], v[66:81]
	ds_read_b64_tr_b16 v[158:159], v197 offset:0x3000
	ds_read_b64_tr_b16 v[160:161], v197 offset:0x3800
	s_waitcnt lgkmcnt(4)
	s_nop 0
	v_mfma_f32_32x32x16_bf16 v[2:17], v[130:133], v[146:149], v[2:17]
	ds_read_b64_tr_b16 v[146:147], v197 offset:0x200
	ds_read_b64_tr_b16 v[148:149], v197 offset:0xa00
	v_mfma_f32_32x32x16_bf16 v[2:17], v[134:137], v[150:153], v[2:17]
	ds_read_b64_tr_b16 v[150:151], v197 offset:0x1200
	ds_read_b64_tr_b16 v[152:153], v197 offset:0x1a00
	s_waitcnt lgkmcnt(4)
	s_nop 0
	v_mfma_f32_32x32x16_bf16 v[2:17], v[138:141], v[154:157], v[2:17]
	ds_read_b64_tr_b16 v[154:155], v197 offset:0x2200
	ds_read_b64_tr_b16 v[156:157], v197 offset:0x2a00
	v_mfma_f32_32x32x16_bf16 v[2:17], v[142:145], v[158:161], v[2:17]
	ds_read_b64_tr_b16 v[158:159], v197 offset:0x3200
	ds_read_b64_tr_b16 v[160:161], v197 offset:0x3a00
	s_waitcnt lgkmcnt(4)
	s_nop 0
	v_mfma_f32_32x32x16_bf16 v[50:65], v[130:133], v[146:149], v[50:65]
	ds_read_b64_tr_b16 v[146:147], v197 offset:0x400
	ds_read_b64_tr_b16 v[148:149], v197 offset:0xc00
	v_mfma_f32_32x32x16_bf16 v[50:65], v[134:137], v[150:153], v[50:65]
	ds_read_b64_tr_b16 v[150:151], v197 offset:0x1400
	ds_read_b64_tr_b16 v[152:153], v197 offset:0x1c00
	s_waitcnt lgkmcnt(4)
	s_nop 0
	v_mfma_f32_32x32x16_bf16 v[50:65], v[138:141], v[154:157], v[50:65]
	ds_read_b64_tr_b16 v[154:155], v197 offset:0x2400
	ds_read_b64_tr_b16 v[156:157], v197 offset:0x2c00
	v_mfma_f32_32x32x16_bf16 v[50:65], v[142:145], v[158:161], v[50:65]
	ds_read_b64_tr_b16 v[158:159], v197 offset:0x3400
	ds_read_b64_tr_b16 v[160:161], v197 offset:0x3c00
	s_waitcnt lgkmcnt(4)
	s_nop 0
	v_mfma_f32_32x32x16_bf16 v[34:49], v[130:133], v[146:149], v[34:49]
	ds_read_b64_tr_b16 v[146:147], v197 offset:0x600
	ds_read_b64_tr_b16 v[148:149], v197 offset:0xe00
	v_mfma_f32_32x32x16_bf16 v[34:49], v[134:137], v[150:153], v[34:49]
	ds_read_b64_tr_b16 v[150:151], v197 offset:0x1600
	ds_read_b64_tr_b16 v[152:153], v197 offset:0x1e00
	s_waitcnt lgkmcnt(4)
	s_nop 0
	v_mfma_f32_32x32x16_bf16 v[34:49], v[138:141], v[154:157], v[34:49]
	ds_read_b64_tr_b16 v[154:155], v197 offset:0x2600
	ds_read_b64_tr_b16 v[156:157], v197 offset:0x2e00
	v_mfma_f32_32x32x16_bf16 v[34:49], v[142:145], v[158:161], v[34:49]
	ds_read_b64_tr_b16 v[158:159], v197 offset:0x3600
	ds_read_b64_tr_b16 v[160:161], v197 offset:0x3e00
	s_waitcnt lgkmcnt(4)
	s_nop 0
	s_waitcnt lgkmcnt(0)
	s_waitcnt vmcnt(0)
	v_mfma_f32_32x32x16_bf16 v[18:33], v[130:133], v[146:149], v[18:33]
	s_barrier
	v_mfma_f32_32x32x16_bf16 v[18:33], v[134:137], v[150:153], v[18:33]
	v_mfma_f32_32x32x16_bf16 v[18:33], v[138:141], v[154:157], v[18:33]
	v_mfma_f32_32x32x16_bf16 v[18:33], v[142:145], v[158:161], v[18:33]
	s_cbranch_vccnz .LBB0_845
; template <int EPI>
; __device__ __forceinline__ void attn_item_c(const Item& I, char* lds, int tid_in) {
;     ...
;     pv_pipe8b(oA, oB, vb0 + bsel * STG, vb0 + bsel * STG + SHM_V, pa0, pa1, pa2, pa3, p0, p1, dq + (float)(64 * CT(nf)), I.nslope, -m_reg);
	v_cvt_f32_u32_e32 v130, s72
	s_mov_b32 s4, 0x42680000
	s_mov_b32 s5, 0x426c0000
	v_mov_b32_e32 v215, v214
	v_add_f32_e32 v146, v247, v130
	v_pk_add_f32 v[130:131], v[146:147], s[4:5] op_sel_hi:[0,1]
	s_mov_b32 s4, 0x42600000
	s_mov_b32 s5, 0x42640000
	v_pk_add_f32 v[132:133], v[146:147], s[4:5] op_sel_hi:[0,1]
	s_mov_b32 s4, 0x42480000
	s_mov_b32 s5, 0x424c0000
	v_pk_add_f32 v[134:135], v[146:147], s[4:5] op_sel_hi:[0,1]
	s_mov_b32 s4, 0x42400000
	s_mov_b32 s5, 0x42440000
	v_pk_add_f32 v[136:137], v[146:147], s[4:5] op_sel_hi:[0,1]
	s_mov_b32 s4, 0x42280000
	s_mov_b32 s5, 0x422c0000
	v_pk_add_f32 v[138:139], v[146:147], s[4:5] op_sel_hi:[0,1]
	s_mov_b32 s4, 0x42200000
	s_mov_b32 s5, 0x42240000
	v_pk_add_f32 v[140:141], v[146:147], s[4:5] op_sel_hi:[0,1]
	s_mov_b32 s4, 0x42080000
	s_mov_b32 s5, 0x420c0000
	v_pk_add_f32 v[142:143], v[146:147], s[4:5] op_sel_hi:[0,1]
	s_mov_b32 s4, 0x42000000
	s_mov_b32 s5, 0x42040000
	v_pk_add_f32 v[144:145], v[146:147], s[4:5] op_sel_hi:[0,1]
	s_mov_b32 s4, 2.0
	v_and_b32_e32 v149, 0x7fffffff, v145
	v_and_b32_e32 v148, 0x7fffffff, v144
	v_and_b32_e32 v131, 0x7fffffff, v131
	v_and_b32_e32 v130, 0x7fffffff, v130
	v_add_f32_e32 v147, 1.0, v146
	s_mov_b32 s5, 0x40400000
	v_pk_fma_f32 v[144:145], v[130:131], v[214:215], v[224:225] op_sel_hi:[1,1,0] neg_lo:[0,0,1] neg_hi:[0,0,1]
	v_pk_fma_f32 v[130:131], v[148:149], v[216:217], v[224:225] op_sel_hi:[1,1,0] neg_lo:[0,0,1] neg_hi:[0,0,1]
	v_pk_add_f32 v[148:149], v[146:147], s[4:5] op_sel_hi:[0,1]
	s_mov_b32 s4, 0x41000000
	v_and_b32_e32 v151, 0x7fffffff, v143
	v_and_b32_e32 v150, 0x7fffffff, v142
	v_and_b32_e32 v133, 0x7fffffff, v133
	v_and_b32_e32 v132, 0x7fffffff, v132
	s_mov_b32 s5, 0x41100000
	v_pk_fma_f32 v[142:143], v[132:133], v[214:215], v[224:225] op_sel_hi:[1,1,0] neg_lo:[0,0,1] neg_hi:[0,0,1]
	v_pk_fma_f32 v[132:133], v[150:151], v[214:215], v[224:225] op_sel_hi:[1,1,0] neg_lo:[0,0,1] neg_hi:[0,0,1]
	v_pk_add_f32 v[150:151], v[146:147], s[4:5] op_sel_hi:[0,1]
	s_mov_b32 s4, 0x41200000
	v_and_b32_e32 v153, 0x7fffffff, v141
	v_and_b32_e32 v152, 0x7fffffff, v140
	v_and_b32_e32 v135, 0x7fffffff, v135
	v_and_b32_e32 v134, 0x7fffffff, v134
	s_mov_b32 s5, 0x41300000
	v_pk_fma_f32 v[140:141], v[134:135], v[214:215], v[224:225] op_sel_hi:[1,1,0] neg_lo:[0,0,1] neg_hi:[0,0,1]
	v_pk_fma_f32 v[134:135], v[152:153], v[214:215], v[224:225] op_sel_hi:[1,1,0] neg_lo:[0,0,1] neg_hi:[0,0,1]
	v_pk_add_f32 v[152:153], v[146:147], s[4:5] op_sel_hi:[0,1]
	s_mov_b32 s4, 0x41800000
	v_and_b32_e32 v155, 0x7fffffff, v139
	v_and_b32_e32 v154, 0x7fffffff, v138
	v_and_b32_e32 v137, 0x7fffffff, v137
	v_and_b32_e32 v136, 0x7fffffff, v136
	s_mov_b32 s5, 0x41880000
	v_pk_fma_f32 v[138:139], v[136:137], v[214:215], v[224:225] op_sel_hi:[1,1,0] neg_lo:[0,0,1] neg_hi:[0,0,1]
	v_pk_fma_f32 v[136:137], v[154:155], v[214:215], v[224:225] op_sel_hi:[1,1,0] neg_lo:[0,0,1] neg_hi:[0,0,1]
	v_pk_add_f32 v[154:155], v[146:147], s[4:5] op_sel_hi:[0,1]
	s_mov_b32 s4, 0x41900000
	s_mov_b32 s5, 0x41980000
	v_pk_add_f32 v[156:157], v[146:147], s[4:5] op_sel_hi:[0,1]
	s_mov_b32 s4, 0x41c00000
	s_mov_b32 s5, 0x41c80000
	v_pk_add_f32 v[158:159], v[146:147], s[4:5] op_sel_hi:[0,1]
	s_mov_b32 s4, 0x41d00000
	s_mov_b32 s5, 0x41d80000
	v_pk_add_f32 v[160:161], v[146:147], s[4:5] op_sel_hi:[0,1]
	v_and_b32_e32 v149, 0x7fffffff, v149
	v_and_b32_e32 v148, 0x7fffffff, v148
	v_and_b32_e32 v151, 0x7fffffff, v151
	v_and_b32_e32 v150, 0x7fffffff, v150
	v_and_b32_e32 v153, 0x7fffffff, v153
	v_and_b32_e32 v152, 0x7fffffff, v152
	v_and_b32_e32 v155, 0x7fffffff, v155
	v_and_b32_e32 v154, 0x7fffffff, v154
	v_and_b32_e32 v157, 0x7fffffff, v157
	v_and_b32_e32 v156, 0x7fffffff, v156
	v_and_b32_e32 v159, 0x7fffffff, v159
	v_and_b32_e32 v158, 0x7fffffff, v158
	v_and_b32_e32 v161, 0x7fffffff, v161
	v_and_b32_e32 v160, 0x7fffffff, v160
	v_and_b32_e32 v146, 0x7fffffff, v146
	v_and_b32_e32 v147, 0x7fffffff, v147
	v_pk_fma_f32 v[160:161], v[160:161], v[214:215], v[224:225] op_sel_hi:[1,1,0] neg_lo:[0,0,1] neg_hi:[0,0,1]
	v_pk_fma_f32 v[158:159], v[158:159], v[214:215], v[224:225] op_sel_hi:[1,1,0] neg_lo:[0,0,1] neg_hi:[0,0,1]
	v_pk_fma_f32 v[156:157], v[156:157], v[214:215], v[224:225] op_sel_hi:[1,1,0] neg_lo:[0,0,1] neg_hi:[0,0,1]
	v_pk_fma_f32 v[154:155], v[154:155], v[214:215], v[224:225] op_sel_hi:[1,1,0] neg_lo:[0,0,1] neg_hi:[0,0,1]
	v_pk_fma_f32 v[152:153], v[152:153], v[214:215], v[224:225] op_sel_hi:[1,1,0] neg_lo:[0,0,1] neg_hi:[0,0,1]
	v_pk_fma_f32 v[150:151], v[150:151], v[214:215], v[224:225] op_sel_hi:[1,1,0] neg_lo:[0,0,1] neg_hi:[0,0,1]
	v_pk_fma_f32 v[148:149], v[148:149], v[214:215], v[224:225] op_sel_hi:[1,1,0] neg_lo:[0,0,1] neg_hi:[0,0,1]
	v_pk_fma_f32 v[146:147], v[146:147], v[216:217], v[224:225] op_sel_hi:[1,1,0] neg_lo:[0,0,1] neg_hi:[0,0,1]
	s_add_i32 s95, s95, 1
	s_mov_b64 s[4:5], 0

; #define LAS __attribute__((address_space(3)))
; __device__ __forceinline__ unsigned cvt_pk_bf16(float lo, float hi) { unsigned r; asm volatile("v_cvt_pk_bf16_f32 %0, %1, %2" : "=v"(r) : "v"(lo), "v"(hi)); return r; }
; __device__ __forceinline__ int crow(int r, int hi) { return (r & 3) + 8 * (r >> 2) + 4 * hi; }
; template <int EPI>
; __device__ __forceinline__ void attn_item_c(const Item& I, char* lds, int tid_in) {
;     ...
;   if (hi == 0) li_l[r32] = ((EPI == 3) ? ((LAS float*)(base + 133120))[wid] : 1.f) / l_reg;
;   asm volatile("s_waitcnt lgkmcnt(0)" ::: "memory");
;   const int tokw = I.seq_base + I.u0 + wid * 32;
;   constexpr int RB = (EPI == 3) ? 512 : 256;
;   LAS char* Sw = base + wid * (32 * RB);
;   const int rsub = lane >> 4, ch = lane & 15;
;   f32x4 dv[2][8][2];
; #pragma unroll
;   for (int half = 0; half < 2; ++half) {
;     f32x16* o = half ? oB : oA;
;     asm volatile("s_waitcnt lgkmcnt(0)" ::: "memory");
; #pragma unroll
;     for (int r = 0; r < 16; ++r) { const int orow = crow(r, hi); const float fq_ = li_l[orow];
; #pragma unroll
;       for (int d0 = 0; d0 < 4; ++d0) { const float v = o[d0][r] * fq_;
;         if constexpr (EPI == 3) *(LAS float*)(Sw + orow * RB + (d0 * 32 + r32) * 4) = v;
;         else *(LAS bf16_t*)(Sw + orow * RB + (d0 * 32 + r32) * 2) = (bf16_t)(cvt_pk_bf16(v, v) & 0xffffu); } }
.LBB0_849:
	s_or_b64 exec, exec, s[4:5]
	s_waitcnt lgkmcnt(0)
	ds_read_b32 v0, v245
	s_lshl_b32 s4, s87, 13
	s_add_i32 s4, s4, 0
	v_lshl_add_u32 v130, v243, 1, s4
	v_lshl_add_u32 v131, v244, 10, v130
	s_waitcnt lgkmcnt(0)
	v_mul_f32_e32 v114, v114, v0
	v_mul_f32_e32 v98, v98, v0
	v_mul_f32_e32 v82, v82, v0
	v_mul_f32_e32 v0, v66, v0
	v_cvt_pk_bf16_f32 v114, v114, v114
	ds_write_b16 v131, v114
	v_cvt_pk_bf16_f32 v98, v98, v98
	ds_write_b16 v131, v98 offset:64
	v_cvt_pk_bf16_f32 v82, v82, v82
	ds_write_b16 v131, v82 offset:128
	v_cvt_pk_bf16_f32 v0, v0, v0
	ds_read_b32 v66, v245 offset:4
	ds_write_b16 v131, v0 offset:192
	v_lshl_add_u32 v82, v246, 8, v130
	s_add_i32 s87, s69, s56
	s_add_i32 s6, s91, s87
	s_waitcnt lgkmcnt(1)
	v_mul_f32_e32 v0, v115, v66
	v_cvt_pk_bf16_f32 v0, v0, v0
	ds_write_b16 v82, v0 offset:256
	v_mul_f32_e32 v0, v99, v66
	v_cvt_pk_bf16_f32 v0, v0, v0
	ds_write_b16 v82, v0 offset:320
	v_mul_f32_e32 v0, v83, v66
	v_cvt_pk_bf16_f32 v0, v0, v0
	ds_write_b16 v82, v0 offset:384
	v_mul_f32_e32 v0, v67, v66
	v_cvt_pk_bf16_f32 v0, v0, v0
	ds_read_b32 v66, v245 offset:8
	ds_write_b16 v82, v0 offset:448
	s_ashr_i32 s7, s6, 31
	v_lshrrev_b32_e32 v83, 4, v241
	s_lshl_b64 s[6:7], s[6:7], 12
	s_waitcnt lgkmcnt(1)
	v_mul_f32_e32 v0, v116, v66
	v_cvt_pk_bf16_f32 v0, v0, v0
	ds_write_b16 v82, v0 offset:512
	v_mul_f32_e32 v0, v100, v66
	v_cvt_pk_bf16_f32 v0, v0, v0
	ds_write_b16 v82, v0 offset:576
	v_mul_f32_e32 v0, v84, v66
	v_cvt_pk_bf16_f32 v0, v0, v0
	ds_write_b16 v82, v0 offset:640
	v_mul_f32_e32 v0, v68, v66
	v_cvt_pk_bf16_f32 v0, v0, v0
	ds_read_b32 v66, v245 offset:12
	ds_write_b16 v82, v0 offset:704
	v_mov_b32_e32 v223, v1
	s_waitcnt lgkmcnt(1)
	v_mul_f32_e32 v0, v117, v66
	v_cvt_pk_bf16_f32 v0, v0, v0
	ds_write_b16 v82, v0 offset:768
	v_mul_f32_e32 v0, v101, v66
	v_cvt_pk_bf16_f32 v0, v0, v0
	ds_write_b16 v82, v0 offset:832
	v_mul_f32_e32 v0, v85, v66
	v_cvt_pk_bf16_f32 v0, v0, v0
	ds_write_b16 v82, v0 offset:896
	v_mul_f32_e32 v0, v69, v66
	v_cvt_pk_bf16_f32 v0, v0, v0
	ds_read_b32 v66, v245 offset:32
	ds_write_b16 v82, v0 offset:960
	s_waitcnt lgkmcnt(1)
	v_mul_f32_e32 v0, v118, v66
	v_cvt_pk_bf16_f32 v0, v0, v0
	ds_write_b16 v82, v0 offset:2048
	v_mul_f32_e32 v0, v102, v66
	v_cvt_pk_bf16_f32 v0, v0, v0
	ds_write_b16 v82, v0 offset:2112
	v_mul_f32_e32 v0, v86, v66
	v_cvt_pk_bf16_f32 v0, v0, v0
	ds_write_b16 v82, v0 offset:2176
	v_mul_f32_e32 v0, v70, v66
	v_cvt_pk_bf16_f32 v0, v0, v0
	ds_read_b32 v66, v245 offset:36
	ds_write_b16 v82, v0 offset:2240
	s_waitcnt lgkmcnt(1)
	v_mul_f32_e32 v0, v119, v66
	v_cvt_pk_bf16_f32 v0, v0, v0
	ds_write_b16 v82, v0 offset:2304
	v_mul_f32_e32 v0, v103, v66
	v_cvt_pk_bf16_f32 v0, v0, v0
	ds_write_b16 v82, v0 offset:2368
	v_mul_f32_e32 v0, v87, v66
	v_cvt_pk_bf16_f32 v0, v0, v0
	ds_write_b16 v82, v0 offset:2432
	v_mul_f32_e32 v0, v71, v66
	v_cvt_pk_bf16_f32 v0, v0, v0
	ds_read_b32 v66, v245 offset:40
	ds_write_b16 v82, v0 offset:2496
	s_waitcnt lgkmcnt(1)
	v_mul_f32_e32 v0, v120, v66
	v_cvt_pk_bf16_f32 v0, v0, v0
	ds_write_b16 v82, v0 offset:2560
	v_mul_f32_e32 v0, v104, v66
	v_cvt_pk_bf16_f32 v0, v0, v0
	ds_write_b16 v82, v0 offset:2624
	v_mul_f32_e32 v0, v88, v66
	v_cvt_pk_bf16_f32 v0, v0, v0
	ds_write_b16 v82, v0 offset:2688
	v_mul_f32_e32 v0, v72, v66
	v_cvt_pk_bf16_f32 v0, v0, v0
	ds_read_b32 v66, v245 offset:44
	ds_write_b16 v82, v0 offset:2752
	s_waitcnt lgkmcnt(1)
	v_mul_f32_e32 v0, v121, v66
	v_cvt_pk_bf16_f32 v0, v0, v0
	ds_write_b16 v82, v0 offset:2816
	v_mul_f32_e32 v0, v105, v66
	v_cvt_pk_bf16_f32 v0, v0, v0
	ds_write_b16 v82, v0 offset:2880
	v_mul_f32_e32 v0, v89, v66
	v_cvt_pk_bf16_f32 v0, v0, v0
	ds_write_b16 v82, v0 offset:2944
	v_mul_f32_e32 v0, v73, v66
	v_cvt_pk_bf16_f32 v0, v0, v0
	ds_read_b32 v66, v245 offset:64
	ds_write_b16 v82, v0 offset:3008
	s_waitcnt lgkmcnt(1)
	v_mul_f32_e32 v0, v122, v66
	v_cvt_pk_bf16_f32 v0, v0, v0
	ds_write_b16 v82, v0 offset:4096
	v_mul_f32_e32 v0, v106, v66
	v_cvt_pk_bf16_f32 v0, v0, v0
	ds_write_b16 v82, v0 offset:4160
	v_mul_f32_e32 v0, v90, v66
	v_cvt_pk_bf16_f32 v0, v0, v0
	ds_write_b16 v82, v0 offset:4224
	v_mul_f32_e32 v0, v74, v66
	v_cvt_pk_bf16_f32 v0, v0, v0
	ds_read_b32 v66, v245 offset:68
	ds_write_b16 v82, v0 offset:4288
	s_waitcnt lgkmcnt(1)
	v_mul_f32_e32 v0, v123, v66
	v_cvt_pk_bf16_f32 v0, v0, v0
	ds_write_b16 v82, v0 offset:4352
	v_mul_f32_e32 v0, v107, v66
	v_cvt_pk_bf16_f32 v0, v0, v0
	ds_write_b16 v82, v0 offset:4416
	v_mul_f32_e32 v0, v91, v66
	v_cvt_pk_bf16_f32 v0, v0, v0
	ds_write_b16 v82, v0 offset:4480
	v_mul_f32_e32 v0, v75, v66
	v_cvt_pk_bf16_f32 v0, v0, v0
	ds_read_b32 v66, v245 offset:72
	ds_write_b16 v82, v0 offset:4544
	s_waitcnt lgkmcnt(1)
	v_mul_f32_e32 v0, v124, v66
	v_cvt_pk_bf16_f32 v0, v0, v0
	ds_write_b16 v82, v0 offset:4608
	v_mul_f32_e32 v0, v108, v66
	v_cvt_pk_bf16_f32 v0, v0, v0
	ds_write_b16 v82, v0 offset:4672
	v_mul_f32_e32 v0, v92, v66
	v_cvt_pk_bf16_f32 v0, v0, v0
	ds_write_b16 v82, v0 offset:4736
	v_mul_f32_e32 v0, v76, v66
	v_cvt_pk_bf16_f32 v0, v0, v0
	ds_read_b32 v66, v245 offset:76
	ds_write_b16 v82, v0 offset:4800
	v_or_b32_e32 v76, 4, v83
	s_waitcnt lgkmcnt(1)
	v_mul_f32_e32 v0, v125, v66
	v_cvt_pk_bf16_f32 v0, v0, v0
	ds_write_b16 v82, v0 offset:4864
	v_mul_f32_e32 v0, v109, v66
	v_cvt_pk_bf16_f32 v0, v0, v0
	ds_write_b16 v82, v0 offset:4928
	v_mul_f32_e32 v0, v93, v66
	v_cvt_pk_bf16_f32 v0, v0, v0
	ds_write_b16 v82, v0 offset:4992
	v_mul_f32_e32 v0, v77, v66
	v_cvt_pk_bf16_f32 v0, v0, v0
	ds_read_b32 v66, v245 offset:96
	ds_write_b16 v82, v0 offset:5056
	s_waitcnt lgkmcnt(1)
; #define LAS __attribute__((address_space(3)))
; __device__ __forceinline__ unsigned cvt_pk_bf16(float lo, float hi) { unsigned r; asm volatile("v_cvt_pk_bf16_f32 %0, %1, %2" : "=v"(r) : "v"(lo), "v"(hi)); return r; }
; __device__ __forceinline__ float bf_lo(unsigned w) { return __uint_as_float(w << 16); }
; __device__ __forceinline__ float bf_hi(unsigned w) { return __uint_as_float(w & 0xffff0000u); }
; __device__ __forceinline__ int crow(int r, int hi) { return (r & 3) + 8 * (r >> 2) + 4 * hi; }
; template <int EPI>
; __device__ __forceinline__ void attn_item_c(const Item& I, char* lds, int tid_in) {
;     ...
;     asm volatile("s_waitcnt lgkmcnt(0)" ::: "memory");
; #pragma unroll
;     for (int r = 0; r < 16; ++r) { const int orow = crow(r, hi); const float fq_ = li_l[orow];
; #pragma unroll
;       for (int d0 = 0; d0 < 4; ++d0) { const float v = o[d0][r] * fq_;
;         if constexpr (EPI == 3) *(LAS float*)(Sw + orow * RB + (d0 * 32 + r32) * 4) = v;
;         else *(LAS bf16_t*)(Sw + orow * RB + (d0 * 32 + r32) * 2) = (bf16_t)(cvt_pk_bf16(v, v) & 0xffffu); } }
;     asm volatile("s_waitcnt lgkmcnt(0)" ::: "memory");
;     bf16_t* Orow = I.O + (size_t)tokw * DM + I.ocol + half * 128 + ch * 8;
;     if constexpr (EPI == 3) {
;       u32x4 oldv[8];
; #pragma unroll
;       for (int j = 0; j < 8; ++j) oldv[j] = LDG(u32x4, Orow + (size_t)(4 * j + rsub) * DM);
;       asm volatile("" ::: "memory");
; #pragma unroll
;       for (int j = 0; j < 8; ++j) { const int row = 4 * j + rsub;
;         const f32x4 a0 = *(const LAS f32x4*)(Sw + row * RB + ch * 32), a1 = *(const LAS f32x4*)(Sw + row * RB + ch * 32 + 16); const u32x4 ov = oldv[j];
;         dv[half][j][0] = (f32x4){bf_lo(ov.x) + a0[0], bf_hi(ov.x) + a0[1], bf_lo(ov.y) + a0[2], bf_hi(ov.y) + a0[3]};
;         dv[half][j][1] = (f32x4){bf_lo(ov.z) + a1[0], bf_hi(ov.z) + a1[1], bf_lo(ov.w) + a1[2], bf_hi(ov.w) + a1[3]}; }
;     } else {
; #pragma unroll
;       for (int j = 0; j < 8; ++j) { const int row = 4 * j + rsub; const u32x4 w = *(const LAS u32x4*)(Sw + row * RB + ch * 16);
;         STG(u32x4, Orow + (size_t)row * DM) = w; }
	v_mul_f32_e32 v0, v126, v66
	v_cvt_pk_bf16_f32 v0, v0, v0
	ds_write_b16 v82, v0 offset:6144
	v_mul_f32_e32 v0, v110, v66
	v_cvt_pk_bf16_f32 v0, v0, v0
	ds_write_b16 v82, v0 offset:6208
	v_mul_f32_e32 v0, v94, v66
	v_cvt_pk_bf16_f32 v0, v0, v0
	ds_write_b16 v82, v0 offset:6272
	v_mul_f32_e32 v0, v78, v66
	v_cvt_pk_bf16_f32 v0, v0, v0
	ds_read_b32 v66, v245 offset:100
	ds_write_b16 v82, v0 offset:6336
	s_waitcnt lgkmcnt(1)
	v_mul_f32_e32 v0, v127, v66
	v_cvt_pk_bf16_f32 v0, v0, v0
	ds_write_b16 v82, v0 offset:6400
	v_mul_f32_e32 v0, v111, v66
	v_cvt_pk_bf16_f32 v0, v0, v0
	ds_write_b16 v82, v0 offset:6464
	v_mul_f32_e32 v0, v95, v66
	v_cvt_pk_bf16_f32 v0, v0, v0
	ds_write_b16 v82, v0 offset:6528
	v_mul_f32_e32 v0, v79, v66
	v_cvt_pk_bf16_f32 v0, v0, v0
	ds_read_b32 v66, v245 offset:104
	ds_write_b16 v82, v0 offset:6592
	s_waitcnt lgkmcnt(1)
	v_mul_f32_e32 v0, v128, v66
	v_cvt_pk_bf16_f32 v0, v0, v0
	ds_write_b16 v82, v0 offset:6656
	v_mul_f32_e32 v0, v112, v66
	v_cvt_pk_bf16_f32 v0, v0, v0
	ds_write_b16 v82, v0 offset:6720
	v_mul_f32_e32 v0, v96, v66
	v_cvt_pk_bf16_f32 v0, v0, v0
	ds_write_b16 v82, v0 offset:6784
	v_mul_f32_e32 v0, v80, v66
	v_cvt_pk_bf16_f32 v66, v0, v0
	ds_read_b32 v67, v245 offset:108
	ds_write_b16 v82, v66 offset:6848
	v_lshlrev_b32_e32 v0, 4, v242
	v_add_u32_e32 v88, s4, v0
	v_lshl_add_u32 v94, v83, 8, v88
	s_waitcnt lgkmcnt(1)
	v_mul_f32_e32 v66, v129, v67
	v_cvt_pk_bf16_f32 v66, v66, v66
	ds_write_b16 v82, v66 offset:6912
	v_mul_f32_e32 v66, v113, v67
	v_cvt_pk_bf16_f32 v66, v66, v66
	ds_write_b16 v82, v66 offset:6976
	v_mul_f32_e32 v66, v97, v67
	v_cvt_pk_bf16_f32 v66, v66, v66
	ds_write_b16 v82, v66 offset:7040
	v_mul_f32_e32 v66, v81, v67
	v_cvt_pk_bf16_f32 v66, v66, v66
	ds_write_b16 v82, v66 offset:7104
	s_waitcnt lgkmcnt(0)
	s_add_u32 s4, s48, s6
	s_addc_u32 s5, s49, s7
	s_lshl_b64 s[52:53], s[46:47], 1
	ds_read_b128 v[68:71], v94
	s_add_u32 s4, s4, s52
	v_lshl_add_u32 v95, v76, 8, v88
	s_addc_u32 s5, s5, s53
	ds_read_b128 v[72:75], v95
	v_lshl_add_u64 v[92:93], s[4:5], 0, v[0:1]
	v_lshlrev_b32_e32 v0, 12, v83
	v_lshl_add_u64 v[66:67], v[92:93], 0, v[0:1]
	v_lshlrev_b32_e32 v0, 12, v76
	s_waitcnt lgkmcnt(1)
	global_store_dwordx4 v[66:67], v[68:71], off
	s_addk_i32 s26, 0x1100
	s_nop 0
	v_lshl_add_u64 v[68:69], v[92:93], 0, v[0:1]
	v_or_b32_e32 v0, 8, v83
	v_or_b32_e32 v70, 12, v83
	v_lshl_add_u32 v96, v0, 8, v88
	v_lshl_add_u32 v97, v70, 8, v88
	s_waitcnt lgkmcnt(0)
	global_store_dwordx4 v[68:69], v[72:75], off
	ds_read_b128 v[74:77], v96
	ds_read_b128 v[78:81], v97
	v_lshlrev_b32_e32 v0, 12, v0
	v_lshl_add_u64 v[72:73], v[92:93], 0, v[0:1]
	v_lshlrev_b32_e32 v0, 12, v70
	v_lshl_add_u64 v[70:71], v[92:93], 0, v[0:1]
	v_or_b32_e32 v0, 16, v83
	v_lshl_add_u32 v98, v0, 8, v88
	s_waitcnt lgkmcnt(1)
	global_store_dwordx4 v[72:73], v[74:77], off
	s_waitcnt lgkmcnt(0)
	global_store_dwordx4 v[70:71], v[78:81], off
	ds_read_b128 v[76:79], v98
	v_lshlrev_b32_e32 v0, 12, v0
	v_or_b32_e32 v80, 20, v83
	v_lshl_add_u32 v99, v80, 8, v88
	ds_read_b128 v[84:87], v99
	v_lshl_add_u64 v[74:75], v[92:93], 0, v[0:1]
	v_lshlrev_b32_e32 v0, 12, v80
	s_waitcnt lgkmcnt(1)
	global_store_dwordx4 v[74:75], v[76:79], off
	v_or_b32_e32 v80, 28, v83
	s_nop 0
	v_lshl_add_u64 v[76:77], v[92:93], 0, v[0:1]
	v_or_b32_e32 v0, 24, v83
	v_lshl_add_u32 v100, v0, 8, v88
	v_lshl_add_u32 v83, v80, 8, v88
	ds_read_b128 v[88:91], v83
	s_waitcnt lgkmcnt(1)
	global_store_dwordx4 v[76:77], v[84:87], off
	ds_read_b128 v[84:87], v100
	v_lshlrev_b32_e32 v0, 12, v0
	v_lshl_add_u64 v[78:79], v[92:93], 0, v[0:1]
	v_lshlrev_b32_e32 v0, 12, v80
	v_lshl_add_u64 v[80:81], v[92:93], 0, v[0:1]
	s_waitcnt lgkmcnt(0)
	global_store_dwordx4 v[78:79], v[84:87], off
	global_store_dwordx4 v[80:81], v[88:91], off
	ds_read_b32 v0, v245
	s_waitcnt lgkmcnt(0)
	v_mul_f32_e32 v2, v2, v0
	v_cvt_pk_bf16_f32 v2, v2, v2
	ds_write_b16 v131, v2
	v_mul_f32_e32 v2, v50, v0
	v_cvt_pk_bf16_f32 v2, v2, v2
	ds_write_b16 v131, v2 offset:64
	v_mul_f32_e32 v2, v34, v0
	v_cvt_pk_bf16_f32 v2, v2, v2
	v_mul_f32_e32 v0, v18, v0
	ds_write_b16 v131, v2 offset:128
	v_cvt_pk_bf16_f32 v0, v0, v0
	ds_read_b32 v2, v245 offset:4
	ds_write_b16 v131, v0 offset:192
	s_waitcnt lgkmcnt(1)
	v_mul_f32_e32 v0, v3, v2
	v_cvt_pk_bf16_f32 v0, v0, v0
	ds_write_b16 v82, v0 offset:256
	v_mul_f32_e32 v0, v51, v2
	v_cvt_pk_bf16_f32 v0, v0, v0
	ds_write_b16 v82, v0 offset:320
	v_mul_f32_e32 v0, v35, v2
	v_cvt_pk_bf16_f32 v0, v0, v0
	ds_write_b16 v82, v0 offset:384
	v_mul_f32_e32 v0, v19, v2
	v_cvt_pk_bf16_f32 v0, v0, v0
	ds_read_b32 v2, v245 offset:8
	ds_write_b16 v82, v0 offset:448
	s_waitcnt lgkmcnt(1)
	v_mul_f32_e32 v0, v4, v2
	v_cvt_pk_bf16_f32 v0, v0, v0
	ds_write_b16 v82, v0 offset:512
	v_mul_f32_e32 v0, v52, v2
	v_cvt_pk_bf16_f32 v0, v0, v0
	ds_write_b16 v82, v0 offset:576
	v_mul_f32_e32 v0, v36, v2
	v_cvt_pk_bf16_f32 v0, v0, v0
	ds_write_b16 v82, v0 offset:640
	v_mul_f32_e32 v0, v20, v2
	v_cvt_pk_bf16_f32 v0, v0, v0
	ds_read_b32 v2, v245 offset:12
	ds_write_b16 v82, v0 offset:704
	s_waitcnt lgkmcnt(1)
	v_mul_f32_e32 v0, v5, v2
	v_cvt_pk_bf16_f32 v0, v0, v0
	ds_write_b16 v82, v0 offset:768
	v_mul_f32_e32 v0, v53, v2
	v_cvt_pk_bf16_f32 v0, v0, v0
	ds_write_b16 v82, v0 offset:832
	v_mul_f32_e32 v0, v37, v2
	v_cvt_pk_bf16_f32 v0, v0, v0
	ds_write_b16 v82, v0 offset:896
	v_mul_f32_e32 v0, v21, v2
	v_cvt_pk_bf16_f32 v0, v0, v0
	ds_read_b32 v2, v245 offset:32
	ds_write_b16 v82, v0 offset:960
	s_waitcnt lgkmcnt(1)
	v_mul_f32_e32 v0, v6, v2
	v_cvt_pk_bf16_f32 v0, v0, v0
	ds_write_b16 v82, v0 offset:2048
	v_mul_f32_e32 v0, v54, v2
	v_cvt_pk_bf16_f32 v0, v0, v0
	ds_write_b16 v82, v0 offset:2112
	v_mul_f32_e32 v0, v38, v2
	v_cvt_pk_bf16_f32 v0, v0, v0
	ds_write_b16 v82, v0 offset:2176
	v_mul_f32_e32 v0, v22, v2
	v_cvt_pk_bf16_f32 v0, v0, v0
	ds_read_b32 v2, v245 offset:36
	ds_write_b16 v82, v0 offset:2240
	s_waitcnt lgkmcnt(1)
; #define LAS __attribute__((address_space(3)))
; __device__ __forceinline__ unsigned cvt_pk_bf16(float lo, float hi) { unsigned r; asm volatile("v_cvt_pk_bf16_f32 %0, %1, %2" : "=v"(r) : "v"(lo), "v"(hi)); return r; }
; __device__ __forceinline__ float bf_lo(unsigned w) { return __uint_as_float(w << 16); }
; __device__ __forceinline__ float bf_hi(unsigned w) { return __uint_as_float(w & 0xffff0000u); }
; __device__ __forceinline__ int crow(int r, int hi) { return (r & 3) + 8 * (r >> 2) + 4 * hi; }
; template <int EPI>
; __device__ __forceinline__ void attn_item_c(const Item& I, char* lds, int tid_in) {
;     ...
;     for (int r = 0; r < 16; ++r) { const int orow = crow(r, hi); const float fq_ = li_l[orow];
; #pragma unroll
;       for (int d0 = 0; d0 < 4; ++d0) { const float v = o[d0][r] * fq_;
;         if constexpr (EPI == 3) *(LAS float*)(Sw + orow * RB + (d0 * 32 + r32) * 4) = v;
;         else *(LAS bf16_t*)(Sw + orow * RB + (d0 * 32 + r32) * 2) = (bf16_t)(cvt_pk_bf16(v, v) & 0xffffu); } }
;     asm volatile("s_waitcnt lgkmcnt(0)" ::: "memory");
;     bf16_t* Orow = I.O + (size_t)tokw * DM + I.ocol + half * 128 + ch * 8;
;     if constexpr (EPI == 3) {
;       u32x4 oldv[8];
; #pragma unroll
;       for (int j = 0; j < 8; ++j) oldv[j] = LDG(u32x4, Orow + (size_t)(4 * j + rsub) * DM);
;       asm volatile("" ::: "memory");
; #pragma unroll
;       for (int j = 0; j < 8; ++j) { const int row = 4 * j + rsub;
;         const f32x4 a0 = *(const LAS f32x4*)(Sw + row * RB + ch * 32), a1 = *(const LAS f32x4*)(Sw + row * RB + ch * 32 + 16); const u32x4 ov = oldv[j];
;         dv[half][j][0] = (f32x4){bf_lo(ov.x) + a0[0], bf_hi(ov.x) + a0[1], bf_lo(ov.y) + a0[2], bf_hi(ov.y) + a0[3]};
;         dv[half][j][1] = (f32x4){bf_lo(ov.z) + a1[0], bf_hi(ov.z) + a1[1], bf_lo(ov.w) + a1[2], bf_hi(ov.w) + a1[3]}; }
;     } else {
; #pragma unroll
;       for (int j = 0; j < 8; ++j) { const int row = 4 * j + rsub; const u32x4 w = *(const LAS u32x4*)(Sw + row * RB + ch * 16);
;         STG(u32x4, Orow + (size_t)row * DM) = w; }
;     ...
;   asm volatile("s_waitcnt vmcnt(0)" ::: "memory");
;   __syncthreads();
	v_mul_f32_e32 v0, v7, v2
	v_cvt_pk_bf16_f32 v0, v0, v0
	ds_write_b16 v82, v0 offset:2304
	v_mul_f32_e32 v0, v55, v2
	v_cvt_pk_bf16_f32 v0, v0, v0
	ds_write_b16 v82, v0 offset:2368
	v_mul_f32_e32 v0, v39, v2
	v_cvt_pk_bf16_f32 v0, v0, v0
	ds_write_b16 v82, v0 offset:2432
	v_mul_f32_e32 v0, v23, v2
	v_cvt_pk_bf16_f32 v0, v0, v0
	ds_read_b32 v2, v245 offset:40
	ds_write_b16 v82, v0 offset:2496
	s_waitcnt lgkmcnt(1)
	v_mul_f32_e32 v0, v8, v2
	v_cvt_pk_bf16_f32 v0, v0, v0
	ds_write_b16 v82, v0 offset:2560
	v_mul_f32_e32 v0, v56, v2
	v_cvt_pk_bf16_f32 v0, v0, v0
	ds_write_b16 v82, v0 offset:2624
	v_mul_f32_e32 v0, v40, v2
	v_cvt_pk_bf16_f32 v0, v0, v0
	ds_write_b16 v82, v0 offset:2688
	v_mul_f32_e32 v0, v24, v2
	v_cvt_pk_bf16_f32 v0, v0, v0
	ds_read_b32 v2, v245 offset:44
	ds_write_b16 v82, v0 offset:2752
	s_waitcnt lgkmcnt(1)
	v_mul_f32_e32 v0, v9, v2
	v_cvt_pk_bf16_f32 v0, v0, v0
	ds_write_b16 v82, v0 offset:2816
	v_mul_f32_e32 v0, v57, v2
	v_cvt_pk_bf16_f32 v0, v0, v0
	ds_write_b16 v82, v0 offset:2880
	v_mul_f32_e32 v0, v41, v2
	v_cvt_pk_bf16_f32 v0, v0, v0
	ds_write_b16 v82, v0 offset:2944
	v_mul_f32_e32 v0, v25, v2
	v_cvt_pk_bf16_f32 v0, v0, v0
	ds_read_b32 v2, v245 offset:64
	ds_write_b16 v82, v0 offset:3008
	s_waitcnt lgkmcnt(1)
	v_mul_f32_e32 v0, v10, v2
	v_cvt_pk_bf16_f32 v0, v0, v0
	ds_write_b16 v82, v0 offset:4096
	v_mul_f32_e32 v0, v58, v2
	v_cvt_pk_bf16_f32 v0, v0, v0
	ds_write_b16 v82, v0 offset:4160
	v_mul_f32_e32 v0, v42, v2
	v_cvt_pk_bf16_f32 v0, v0, v0
	ds_write_b16 v82, v0 offset:4224
	v_mul_f32_e32 v0, v26, v2
	v_cvt_pk_bf16_f32 v0, v0, v0
	ds_read_b32 v2, v245 offset:68
	ds_write_b16 v82, v0 offset:4288
	s_waitcnt lgkmcnt(1)
	v_mul_f32_e32 v0, v11, v2
	v_cvt_pk_bf16_f32 v0, v0, v0
	ds_write_b16 v82, v0 offset:4352
	v_mul_f32_e32 v0, v59, v2
	v_cvt_pk_bf16_f32 v0, v0, v0
	ds_write_b16 v82, v0 offset:4416
	v_mul_f32_e32 v0, v43, v2
	v_cvt_pk_bf16_f32 v0, v0, v0
	ds_write_b16 v82, v0 offset:4480
	v_mul_f32_e32 v0, v27, v2
	v_cvt_pk_bf16_f32 v0, v0, v0
	ds_read_b32 v2, v245 offset:72
	ds_write_b16 v82, v0 offset:4544
	s_waitcnt lgkmcnt(1)
	v_mul_f32_e32 v0, v12, v2
	v_cvt_pk_bf16_f32 v0, v0, v0
	ds_write_b16 v82, v0 offset:4608
	v_mul_f32_e32 v0, v60, v2
	v_cvt_pk_bf16_f32 v0, v0, v0
	ds_write_b16 v82, v0 offset:4672
	v_mul_f32_e32 v0, v44, v2
	v_cvt_pk_bf16_f32 v0, v0, v0
	ds_write_b16 v82, v0 offset:4736
	v_mul_f32_e32 v0, v28, v2
	v_cvt_pk_bf16_f32 v0, v0, v0
	ds_read_b32 v2, v245 offset:76
	ds_write_b16 v82, v0 offset:4800
	s_waitcnt lgkmcnt(1)
	v_mul_f32_e32 v0, v13, v2
	v_cvt_pk_bf16_f32 v0, v0, v0
	ds_write_b16 v82, v0 offset:4864
	v_mul_f32_e32 v0, v61, v2
	v_cvt_pk_bf16_f32 v0, v0, v0
	ds_write_b16 v82, v0 offset:4928
	v_mul_f32_e32 v0, v45, v2
	v_cvt_pk_bf16_f32 v0, v0, v0
	ds_write_b16 v82, v0 offset:4992
	v_mul_f32_e32 v0, v29, v2
	v_cvt_pk_bf16_f32 v0, v0, v0
	ds_read_b32 v2, v245 offset:96
	ds_write_b16 v82, v0 offset:5056
	s_waitcnt lgkmcnt(1)
	v_mul_f32_e32 v0, v14, v2
	v_cvt_pk_bf16_f32 v0, v0, v0
	ds_write_b16 v82, v0 offset:6144
	v_mul_f32_e32 v0, v62, v2
	v_cvt_pk_bf16_f32 v0, v0, v0
	ds_write_b16 v82, v0 offset:6208
	v_mul_f32_e32 v0, v46, v2
	v_cvt_pk_bf16_f32 v0, v0, v0
	ds_write_b16 v82, v0 offset:6272
	v_mul_f32_e32 v0, v30, v2
	v_cvt_pk_bf16_f32 v0, v0, v0
	ds_read_b32 v2, v245 offset:100
	ds_write_b16 v82, v0 offset:6336
	s_waitcnt lgkmcnt(1)
	v_mul_f32_e32 v0, v15, v2
	v_cvt_pk_bf16_f32 v0, v0, v0
	ds_write_b16 v82, v0 offset:6400
	v_mul_f32_e32 v0, v63, v2
	v_cvt_pk_bf16_f32 v0, v0, v0
	ds_write_b16 v82, v0 offset:6464
	v_mul_f32_e32 v0, v47, v2
	v_cvt_pk_bf16_f32 v0, v0, v0
	ds_write_b16 v82, v0 offset:6528
	v_mul_f32_e32 v0, v31, v2
	v_cvt_pk_bf16_f32 v0, v0, v0
	ds_read_b32 v2, v245 offset:104
	ds_write_b16 v82, v0 offset:6592
	s_waitcnt lgkmcnt(1)
	v_mul_f32_e32 v0, v16, v2
	v_cvt_pk_bf16_f32 v0, v0, v0
	ds_write_b16 v82, v0 offset:6656
	v_mul_f32_e32 v0, v64, v2
	v_cvt_pk_bf16_f32 v0, v0, v0
	ds_write_b16 v82, v0 offset:6720
	v_mul_f32_e32 v0, v48, v2
	v_cvt_pk_bf16_f32 v0, v0, v0
	ds_write_b16 v82, v0 offset:6784
	v_mul_f32_e32 v0, v32, v2
	v_cvt_pk_bf16_f32 v0, v0, v0
	ds_read_b32 v2, v245 offset:108
	ds_write_b16 v82, v0 offset:6848
	s_waitcnt lgkmcnt(1)
	v_mul_f32_e32 v0, v17, v2
	v_cvt_pk_bf16_f32 v0, v0, v0
	ds_write_b16 v82, v0 offset:6912
	v_mul_f32_e32 v0, v65, v2
	v_cvt_pk_bf16_f32 v0, v0, v0
	ds_write_b16 v82, v0 offset:6976
	v_mul_f32_e32 v0, v49, v2
	v_cvt_pk_bf16_f32 v0, v0, v0
	ds_write_b16 v82, v0 offset:7040
	v_mul_f32_e32 v0, v33, v2
	v_cvt_pk_bf16_f32 v0, v0, v0
	ds_write_b16 v82, v0 offset:7104
	s_waitcnt lgkmcnt(0)
	ds_read_b128 v[2:5], v94
	ds_read_b128 v[6:9], v95
	ds_read_b128 v[10:13], v96
	s_waitcnt lgkmcnt(2)
	global_store_dwordx4 v[66:67], v[2:5], off offset:256
	s_waitcnt lgkmcnt(1)
	global_store_dwordx4 v[68:69], v[6:9], off offset:256
	s_waitcnt lgkmcnt(0)
	global_store_dwordx4 v[72:73], v[10:13], off offset:256
	ds_read_b128 v[2:5], v97
	ds_read_b128 v[6:9], v98
	ds_read_b128 v[10:13], v99
	ds_read_b128 v[14:17], v100
	ds_read_b128 v[18:21], v83
	s_waitcnt lgkmcnt(4)
	global_store_dwordx4 v[70:71], v[2:5], off offset:256
	s_waitcnt lgkmcnt(3)
	global_store_dwordx4 v[74:75], v[6:9], off offset:256
	s_waitcnt lgkmcnt(2)
	global_store_dwordx4 v[76:77], v[10:13], off offset:256
	s_waitcnt lgkmcnt(1)
	global_store_dwordx4 v[78:79], v[14:17], off offset:256
	s_waitcnt lgkmcnt(0)
	global_store_dwordx4 v[80:81], v[18:21], off offset:256
	v_mov_b32_e32 v0, v239
	s_waitcnt vmcnt(0)
	s_barrier
; #define LAS __attribute__((address_space(3)))
; __device__ __forceinline__ int v_rd_base(int lane) { return ((lane & 3) << 3) | (((lane >> 2) & 3) << 6) | (((lane >> 4) & 1) << 5) | (((lane >> 5) & 1) << 8); }
; template <int EPI>
; __device__ __forceinline__ void attn_item_c(const Item& I, char* lds, int tid_in) {
;   int tid = tid_in; asm volatile("" : "+v"(tid));
;   const int wid = __builtin_amdgcn_readfirstlane(tid >> 6), lane = tid & 63, r32 = lane & 31, hi = lane >> 5;
;   constexpr int STG = 3 * SHM_V;
;   LAS char* base = (LAS char*)lds;
;   LAS float* wsf = (LAS float*)(base + 131072) + wid * 64; LAS float* li_l = wsf; LAS float* al_l = wsf + 32;
;   float m_reg = -1e30f, l_reg = 0.f; f32x16 oA[4] = {}, oB[4] = {}; bf16x8 qr[8];
;   const int uq = I.u0 + wid * 32 + r32;
;   { const bf16_t* Qw = I.qkv + (size_t)(I.seq_base + uq) * I.W + I.qcol + hi * 8;
; #pragma unroll
;     for (int d0 = 0; d0 < 8; ++d0) qr[d0] = LDG(bf16x8, Qw + d0 * 16); }
;   const float dq = (float)(4 * hi - uq);
;   const int vb0 = (int)(unsigned)(uintptr_t)base + v_rd_base(lane);
;   unsigned gk[2], gv[2];
; #pragma unroll
;   for (int i = 0; i < 2; ++i) { const int p = i * 8192 + wid * 1024 + lane * 16;
;     { const int row = p >> 8, chunk = ((p & 255) >> 4) ^ (row & 7); gk[i] = (unsigned)(row * I.W + chunk * 8) * 2u; }
;     { const int sub = p >> 9, within = p & 511, kk = (sub >> 2) * 8 + (within >> 6), k = (kk & ~0xC) | ((kk & 4) << 1) | ((kk & 8) >> 1), c = (sub & 3) * 32 + ((within & 63) >> 1);
;       gv[i] = (unsigned)(k * I.W + c) * 2u; } }
;   const char* kvb = (const char*)(I.qkv + (size_t)I.seq_base * I.W);
;     ...
;   f32x16 p0, p1; float mn, al; bf16x8 pa0, pa1, pa2, pa3; const int NT = I.NT;
;   const int n0 = I.u0 >> 6, ntm = NT - 1;
;     ...
;   CDMA(CT(0), 0);
	v_mov_b32_e32 v19, v1
	v_readfirstlane_b32 s6, v0
	s_ashr_i32 s91, s6, 6
	v_and_b32_e32 v243, 31, v0
	s_lshl_b32 s92, s91, 5
	v_or_b32_e32 v2, s92, v243
	v_add_u32_e32 v2, s69, v2
	v_add_u32_e32 v4, s56, v2
	v_ashrrev_i32_e32 v5, 31, v4
	v_lshlrev_b64 v[4:5], 13, v[4:5]
	v_bfe_u32 v242, v0, 5, 1
	v_lshl_add_u64 v[4:5], s[44:45], 0, v[4:5]
	v_lshl_add_u64 v[4:5], v[4:5], 0, s[52:53]
	v_lshlrev_b32_e32 v18, 4, v242
	v_lshl_add_u64 v[4:5], v[4:5], 0, v[18:19]
	global_load_dwordx4 v[162:165], v[4:5], off offset:256
	global_load_dwordx4 v[166:169], v[4:5], off offset:288
	global_load_dwordx4 v[170:173], v[4:5], off offset:320
	global_load_dwordx4 v[174:177], v[4:5], off offset:352
	global_load_dwordx4 v[178:181], v[4:5], off offset:384
	global_load_dwordx4 v[182:185], v[4:5], off offset:416
	global_load_dwordx4 v[186:189], v[4:5], off offset:448
	global_load_dwordx4 v[190:193], v[4:5], off offset:480
	v_and_b32_e32 v244, 63, v0
	v_lshlrev_b32_e32 v3, 4, v244
	s_lshl_b32 s7, s91, 10
	v_and_b32_e32 v241, 15, v0
	v_bfe_u32 v4, v0, 2, 2
	v_lshrrev_b32_e32 v0, 1, v0
	v_and_or_b32 v4, v0, 8, v4
	v_or_b32_e32 v0, s7, v3
	s_lshl_b32 s56, s91, 2
	s_lshl_b32 s5, s91, 1
	v_ashrrev_i32_e32 v5, 8, v0
	s_and_b32 s4, s56, 0xffff0
	s_and_b32 s5, s5, 4
	v_bitop3_b32 v6, v5, v241, 7 bitop3:0x6c
	v_lshlrev_b32_e32 v5, 13, v5
	s_or_b32 s4, s4, s5
	v_lshlrev_b32_e32 v21, 3, v244
	v_lshl_or_b32 v218, v6, 4, v5
	v_or_b32_e32 v5, s4, v4
	v_lshrrev_b32_e32 v0, 4, v0
	v_and_b32_e32 v19, 24, v21
	v_and_b32_e32 v0, 0x60, v0
	v_lshlrev_b32_e32 v5, 12, v5
	s_add_i32 s4, s7, 0x2000
	v_or3_b32 v0, v5, v0, v19
	v_or_b32_e32 v5, s4, v3
	s_ashr_i32 s4, s4, 8
	s_and_b32 s5, s4, 0xffff0
	s_lshr_b32 s4, s4, 1
	s_and_b32 s4, s4, 4
	s_or_b32 s4, s5, s4
	v_ashrrev_i32_e32 v6, 8, v5
	v_or_b32_e32 v4, s4, v4
	v_lshrrev_b32_e32 v5, 4, v5
	s_ashr_i32 s69, s26, 31
	v_and_b32_e32 v5, 0x60, v5
	v_lshlrev_b32_e32 v4, 12, v4
	s_add_u32 s4, s79, s26
	v_lshlrev_b32_e32 v0, 1, v0
	v_or3_b32 v4, v4, v5, v19
	s_addc_u32 s5, s83, s69
	s_add_i32 s79, s7, 0
	v_lshlrev_b32_e32 v222, 1, v4
	s_add_i32 s7, s79, 0x4000
	v_lshl_add_u64 v[4:5], s[58:59], 0, v[0:1]
	s_mov_b32 m0, s79
	s_add_i32 s12, s79, 0x8000
	global_load_lds_dwordx4 v0, s[58:59]
	v_lshl_add_u64 v[4:5], v[4:5], 0, s[76:77]
	s_mov_b32 m0, s7
	v_bitop3_b32 v7, v6, v241, 7 bitop3:0x6c
	global_load_lds_dwordx4 v[4:5], off
	s_mov_b32 m0, s12
	v_lshl_add_u64 v[4:5], s[58:59], 0, v[222:223]
	global_load_lds_dwordx4 v218, s[4:5]
	s_add_i32 m0, s79, 0x2000
	v_lshl_add_u64 v[4:5], v[4:5], 0, s[76:77]
	global_load_lds_dwordx4 v222, s[58:59]
	s_add_i32 m0, s79, 0x6000
	v_lshlrev_b32_e32 v6, 13, v6
	global_load_lds_dwordx4 v[4:5], off
	v_lshl_or_b32 v220, v7, 4, v6
	s_add_i32 m0, s79, 0xa000
	v_cmp_eq_u32_e64 s[40:41], 0, v244
	global_load_lds_dwordx4 v220, s[4:5]
	s_waitcnt vmcnt(0)
; template <int EPI>
; __device__ __forceinline__ void attn_item_c(const Item& I, char* lds, int tid_in) {
;     ...
;   { float qs = 0.f;
; #pragma unroll
;     for (int d0 = 0; d0 < 8; ++d0)
; #pragma unroll
;       for (int j = 0; j < 8; ++j) { const float x = __uint_as_float((unsigned)(unsigned short)qr[d0][j] << 16); qs = fmaf(x, x, qs); }
;     { auto rr = __builtin_amdgcn_permlane32_swap(__float_as_uint(qs), __float_as_uint(qs), false, false); qs = __uint_as_float(rr[0]) + __uint_as_float(rr[1]); }
;     qs = wave_max(qs); if (lane == 0) xw[wid] = qs; }
	v_lshlrev_b32_e32 v4, 16, v162
	v_fma_f32 v4, v4, v4, 0
	v_and_b32_e32 v5, 0xffff0000, v162
	v_fmac_f32_e32 v4, v5, v5
	v_lshlrev_b32_e32 v5, 16, v163
	v_fmac_f32_e32 v4, v5, v5
	v_and_b32_e32 v5, 0xffff0000, v163
	v_fmac_f32_e32 v4, v5, v5
	v_lshlrev_b32_e32 v5, 16, v164
	v_fmac_f32_e32 v4, v5, v5
	v_and_b32_e32 v5, 0xffff0000, v164
	v_fmac_f32_e32 v4, v5, v5
	v_lshlrev_b32_e32 v5, 16, v165
	v_fmac_f32_e32 v4, v5, v5
	v_and_b32_e32 v5, 0xffff0000, v165
	v_fmac_f32_e32 v4, v5, v5
	v_lshlrev_b32_e32 v5, 16, v166
	v_fmac_f32_e32 v4, v5, v5
	v_and_b32_e32 v5, 0xffff0000, v166
	v_fmac_f32_e32 v4, v5, v5
	v_lshlrev_b32_e32 v5, 16, v167
	v_fmac_f32_e32 v4, v5, v5
	v_and_b32_e32 v5, 0xffff0000, v167
	v_fmac_f32_e32 v4, v5, v5
	v_lshlrev_b32_e32 v5, 16, v168
	v_fmac_f32_e32 v4, v5, v5
	v_and_b32_e32 v5, 0xffff0000, v168
	v_fmac_f32_e32 v4, v5, v5
	v_lshlrev_b32_e32 v5, 16, v169
	v_fmac_f32_e32 v4, v5, v5
	v_and_b32_e32 v5, 0xffff0000, v169
	v_fmac_f32_e32 v4, v5, v5
	v_lshlrev_b32_e32 v5, 16, v170
	v_fmac_f32_e32 v4, v5, v5
	v_and_b32_e32 v5, 0xffff0000, v170
	v_fmac_f32_e32 v4, v5, v5
	v_lshlrev_b32_e32 v5, 16, v171
	v_fmac_f32_e32 v4, v5, v5
	v_and_b32_e32 v5, 0xffff0000, v171
	v_fmac_f32_e32 v4, v5, v5
	v_lshlrev_b32_e32 v5, 16, v172
	v_fmac_f32_e32 v4, v5, v5
	v_and_b32_e32 v5, 0xffff0000, v172
	v_fmac_f32_e32 v4, v5, v5
	v_lshlrev_b32_e32 v5, 16, v173
	v_fmac_f32_e32 v4, v5, v5
	v_and_b32_e32 v5, 0xffff0000, v173
	v_fmac_f32_e32 v4, v5, v5
	v_lshlrev_b32_e32 v5, 16, v174
	v_fmac_f32_e32 v4, v5, v5
	v_and_b32_e32 v5, 0xffff0000, v174
	v_fmac_f32_e32 v4, v5, v5
	v_lshlrev_b32_e32 v5, 16, v175
	v_fmac_f32_e32 v4, v5, v5
	v_and_b32_e32 v5, 0xffff0000, v175
	v_fmac_f32_e32 v4, v5, v5
	v_lshlrev_b32_e32 v5, 16, v176
	v_fmac_f32_e32 v4, v5, v5
	v_and_b32_e32 v5, 0xffff0000, v176
	v_fmac_f32_e32 v4, v5, v5
	v_lshlrev_b32_e32 v5, 16, v177
	v_fmac_f32_e32 v4, v5, v5
	v_and_b32_e32 v5, 0xffff0000, v177
	v_fmac_f32_e32 v4, v5, v5
	v_lshlrev_b32_e32 v5, 16, v178
	v_fmac_f32_e32 v4, v5, v5
	v_and_b32_e32 v5, 0xffff0000, v178
	v_fmac_f32_e32 v4, v5, v5
	v_lshlrev_b32_e32 v5, 16, v179
	v_fmac_f32_e32 v4, v5, v5
	v_and_b32_e32 v5, 0xffff0000, v179
	v_fmac_f32_e32 v4, v5, v5
	v_lshlrev_b32_e32 v5, 16, v180
	v_fmac_f32_e32 v4, v5, v5
	v_and_b32_e32 v5, 0xffff0000, v180
	v_fmac_f32_e32 v4, v5, v5
	v_lshlrev_b32_e32 v5, 16, v181
	v_fmac_f32_e32 v4, v5, v5
	v_and_b32_e32 v5, 0xffff0000, v181
	v_fmac_f32_e32 v4, v5, v5
	v_lshlrev_b32_e32 v5, 16, v182
	v_fmac_f32_e32 v4, v5, v5
	v_and_b32_e32 v5, 0xffff0000, v182
	v_fmac_f32_e32 v4, v5, v5
	v_lshlrev_b32_e32 v5, 16, v183
	v_fmac_f32_e32 v4, v5, v5
	v_and_b32_e32 v5, 0xffff0000, v183
	v_fmac_f32_e32 v4, v5, v5
	v_lshlrev_b32_e32 v5, 16, v184
	v_fmac_f32_e32 v4, v5, v5
	v_and_b32_e32 v5, 0xffff0000, v184
	v_fmac_f32_e32 v4, v5, v5
	v_lshlrev_b32_e32 v5, 16, v185
	v_fmac_f32_e32 v4, v5, v5
	v_and_b32_e32 v5, 0xffff0000, v185
	v_fmac_f32_e32 v4, v5, v5
	v_lshlrev_b32_e32 v5, 16, v186
	v_fmac_f32_e32 v4, v5, v5
	v_and_b32_e32 v5, 0xffff0000, v186
	v_fmac_f32_e32 v4, v5, v5
	v_lshlrev_b32_e32 v5, 16, v187
	v_fmac_f32_e32 v4, v5, v5
	v_and_b32_e32 v5, 0xffff0000, v187
	v_fmac_f32_e32 v4, v5, v5
	v_lshlrev_b32_e32 v5, 16, v188
	v_fmac_f32_e32 v4, v5, v5
	v_and_b32_e32 v5, 0xffff0000, v188
	v_fmac_f32_e32 v4, v5, v5
	v_lshlrev_b32_e32 v5, 16, v189
	v_fmac_f32_e32 v4, v5, v5
	v_and_b32_e32 v5, 0xffff0000, v189
	v_fmac_f32_e32 v4, v5, v5
	v_lshlrev_b32_e32 v5, 16, v190
	v_fmac_f32_e32 v4, v5, v5
	v_and_b32_e32 v5, 0xffff0000, v190
	v_fmac_f32_e32 v4, v5, v5
	v_lshlrev_b32_e32 v5, 16, v191
	v_fmac_f32_e32 v4, v5, v5
	v_and_b32_e32 v5, 0xffff0000, v191
	v_fmac_f32_e32 v4, v5, v5
	v_lshlrev_b32_e32 v5, 16, v192
	v_fmac_f32_e32 v4, v5, v5
	v_and_b32_e32 v5, 0xffff0000, v192
	v_fmac_f32_e32 v4, v5, v5
	v_lshlrev_b32_e32 v5, 16, v193
	v_fmac_f32_e32 v4, v5, v5
	v_and_b32_e32 v5, 0xffff0000, v193
	v_fmac_f32_e32 v4, v5, v5
	v_mov_b32_e32 v5, v4
	s_nop 1
	v_permlane32_swap_b32_e32 v4, v5
	v_add_f32_e32 v4, v4, v5
	ds_swizzle_b32 v5, v4 offset:swizzle(SWAP,1)
	s_waitcnt lgkmcnt(0)
	v_max_f32_e32 v5, v5, v5
	v_max_f32_e32 v4, v4, v5
	ds_swizzle_b32 v5, v4 offset:swizzle(SWAP,2)
	s_waitcnt lgkmcnt(0)
	v_max_f32_e32 v5, v5, v5
	v_max_f32_e32 v4, v4, v5
	ds_swizzle_b32 v5, v4 offset:swizzle(SWAP,4)
	s_waitcnt lgkmcnt(0)
	v_max_f32_e32 v5, v5, v5
	v_max_f32_e32 v4, v4, v5
	ds_swizzle_b32 v5, v4 offset:swizzle(SWAP,8)
	s_waitcnt lgkmcnt(0)
	v_max_f32_e32 v5, v5, v5
	v_max_f32_e32 v4, v4, v5
	ds_swizzle_b32 v5, v4 offset:swizzle(SWAP,16)
	s_waitcnt lgkmcnt(0)
	v_max_f32_e32 v5, v5, v5
	v_max_f32_e32 v4, v4, v5
	v_mov_b32_e32 v5, v4
	s_nop 1
	v_permlane32_swap_b32_e32 v4, v5
	s_and_saveexec_b64 s[4:5], s[40:41]
	s_movk_i32 s93, 0x60
	s_mov_b32 s94, 0x2c000
	s_cbranch_execz .LBB0_851
	s_add_i32 s7, s56, 0
	s_add_i32 s7, s7, 0x20840
	v_max_f32_e32 v4, v4, v4
	v_max_f32_e32 v5, v5, v5
	v_max_f32_e32 v4, v4, v5
	v_mov_b32_e32 v5, s7
	ds_write_b32 v5, v4

; #define BI2(R) do { constexpr float c_ = (float)(((R) & 3) + 8 * ((R) >> 2)); p0[R] = fmaf(fabsf(dubn + c_), nslope, negm); p1[R] = fmaf(fabsf(dubn + (c_ + 32.f)), nslope, negm); } while (0)
; #define VRD4(S, D0, KS, vb) s16x4 S##l0 = tr_read<v_rd_off(D0, KS, 0)>(vb), S##h0 = tr_read<v_rd_off(D0, KS, 1)>(vb), S##l1 = tr_read<v_rd_off(D0, KS + 1, 0)>(vb), S##h1 = tr_read<v_rd_off(D0, KS + 1, 1)>(vb)
; #define VWT4(S, N) asm volatile("s_waitcnt lgkmcnt(" #N ")" : "+v"(S##l0), "+v"(S##h0), "+v"(S##l1), "+v"(S##h1) :: "memory")
; #define VMM2(S, od, PA, PB) do { od = __builtin_amdgcn_mfma_f32_32x32x16_bf16(PA, VPK(S##l0, S##h0), od, 0, 0, 0); od = __builtin_amdgcn_mfma_f32_32x32x16_bf16(PB, VPK(S##l1, S##h1), od, 0, 0, 0); } while (0)
; __device__ __forceinline__ void pv_pipe8b(f32x16* oA, f32x16* oB, int vbA, int vbB, bf16x8 pa0, bf16x8 pa1, bf16x8 pa2, bf16x8 pa3, f32x16& p0, f32x16& p1, float dubn, float nslope, float negm) {
;   VRD4(h0, 0, 0, vbA);
;   VRD4(h1, 0, 2, vbA); VWT4(h0, 4); VMM2(h0, oA[0], pa0, pa1); BI2(0);
;   VRD4(h2, 1, 0, vbA); VWT4(h1, 4); VMM2(h1, oA[0], pa2, pa3); BI2(1);
;   VRD4(h3, 1, 2, vbA); VWT4(h2, 4); VMM2(h2, oA[1], pa0, pa1); BI2(2);
;   VRD4(h4, 2, 0, vbA); VWT4(h3, 4); VMM2(h3, oA[1], pa2, pa3); BI2(3);
;   VRD4(h5, 2, 2, vbA); VWT4(h4, 4); VMM2(h4, oA[2], pa0, pa1); BI2(4);
;   VRD4(h6, 3, 0, vbA); VWT4(h5, 4); VMM2(h5, oA[2], pa2, pa3); BI2(5);
;   VRD4(h7, 3, 2, vbA); VWT4(h6, 4); VMM2(h6, oA[3], pa0, pa1); BI2(6);
;   VRD4(h8, 0, 0, vbB); VWT4(h7, 4); VMM2(h7, oA[3], pa2, pa3); BI2(7);
;   VRD4(h9, 0, 2, vbB); VWT4(h8, 4); VMM2(h8, oB[0], pa0, pa1); BI2(8);
; __device__ __forceinline__ void finishSM(f32x16& p0, f32x16& p1, float alpha, float& l_reg, bf16x8& pa0, bf16x8& pa1, bf16x8& pa2, bf16x8& pa3) {
; #pragma unroll
;   for (int r = 0; r < 16; ++r) p1[r] = __builtin_amdgcn_exp2f(p1[r]);
;   float ps = 0;
; #pragma unroll
;   for (int r = 0; r < 16; ++r) ps += p0[r];
; #pragma unroll
;   for (int r = 0; r < 16; ++r) ps += p1[r];
;   { auto rr = __builtin_amdgcn_permlane32_swap(__float_as_uint(ps), __float_as_uint(ps), false, false);
;     ps = __uint_as_float(rr[0]) + __uint_as_float(rr[1]); }
;   l_reg = l_reg * alpha + ps;
;     ...
;   PK4(p0, 0, pa0); PK4(p0, 8, pa1); PK4(p1, 0, pa2); PK4(p1, 8, pa3);
.LBB0_864:
	v_exp_f32_e32 v146, v146
	v_exp_f32_e32 v147, v147
	v_exp_f32_e32 v148, v148
	v_exp_f32_e32 v149, v149
	v_exp_f32_e32 v150, v150
	v_exp_f32_e32 v196, v130
	v_add_f32_e32 v130, 0, v146
	v_exp_f32_e32 v151, v151
	v_add_f32_e32 v130, v147, v130
	v_exp_f32_e32 v152, v152
	v_add_f32_e32 v130, v148, v130
	v_exp_f32_e32 v153, v153
	v_add_f32_e32 v130, v149, v130
	v_exp_f32_e32 v154, v154
	v_add_f32_e32 v130, v150, v130
	v_exp_f32_e32 v155, v155
	v_add_f32_e32 v130, v151, v130
	v_exp_f32_e32 v156, v156
	v_add_f32_e32 v130, v152, v130
	v_exp_f32_e32 v157, v157
	v_add_f32_e32 v130, v153, v130
	v_exp_f32_e32 v158, v158
	v_add_f32_e32 v130, v154, v130
	v_exp_f32_e32 v159, v159
	v_add_f32_e32 v130, v155, v130
	v_exp_f32_e32 v160, v160
	v_add_f32_e32 v130, v156, v130
	v_exp_f32_e32 v161, v161
	v_add_f32_e32 v130, v157, v130
	v_add_f32_e32 v130, v158, v130
	v_exp_f32_e32 v197, v131
	v_add_f32_e32 v130, v159, v130
	v_exp_f32_e32 v198, v132
	v_add_f32_e32 v130, v160, v130
	v_exp_f32_e32 v199, v133
	v_add_f32_e32 v130, v161, v130
	v_exp_f32_e32 v200, v134
	v_add_f32_e32 v130, v196, v130
	v_exp_f32_e32 v201, v135
	v_add_f32_e32 v130, v197, v130
	v_exp_f32_e32 v202, v136
	v_add_f32_e32 v130, v198, v130
	v_exp_f32_e32 v203, v137
	v_add_f32_e32 v130, v199, v130
	v_exp_f32_e32 v204, v138
	v_add_f32_e32 v130, v200, v130
	v_exp_f32_e32 v205, v139
	v_add_f32_e32 v130, v201, v130
	v_exp_f32_e32 v206, v140
	v_add_f32_e32 v130, v202, v130
	v_exp_f32_e32 v207, v141
	v_add_f32_e32 v130, v203, v130
	v_exp_f32_e32 v208, v142
	v_add_f32_e32 v130, v204, v130
	v_exp_f32_e32 v209, v143
	v_add_f32_e32 v130, v205, v130
	v_exp_f32_e32 v213, v144
	v_add_f32_e32 v130, v206, v130
	v_exp_f32_e32 v145, v145
	v_add_f32_e32 v130, v207, v130
	v_add_f32_e32 v130, v208, v130
	v_add_f32_e32 v130, v209, v130
	v_add_f32_e32 v130, v213, v130
	v_add_f32_e32 v194, v145, v130
	v_mov_b32_e32 v195, v194
	v_cvt_pk_bf16_f32 v130, v146, v147
	v_cvt_pk_bf16_f32 v131, v148, v149
	v_cvt_pk_bf16_f32 v132, v150, v151
	v_cvt_pk_bf16_f32 v133, v152, v153
	v_cvt_pk_bf16_f32 v134, v154, v155
	v_cvt_pk_bf16_f32 v135, v156, v157
	v_cvt_pk_bf16_f32 v136, v158, v159
	v_cvt_pk_bf16_f32 v137, v160, v161
	v_cvt_pk_bf16_f32 v138, v196, v197
	v_cvt_pk_bf16_f32 v139, v198, v199
	v_cvt_pk_bf16_f32 v140, v200, v201
	v_cvt_pk_bf16_f32 v141, v202, v203
	v_cvt_pk_bf16_f32 v142, v204, v205
	v_cvt_pk_bf16_f32 v143, v206, v207
	v_cvt_pk_bf16_f32 v144, v208, v209
	v_cvt_pk_bf16_f32 v145, v213, v145
	s_nop 1
	v_permlane32_swap_b32_e32 v194, v195
	v_permlane32_swap_b32_e32 v130, v132
	v_permlane32_swap_b32_e32 v131, v133
	v_permlane32_swap_b32_e32 v134, v136
	v_permlane32_swap_b32_e32 v135, v137
	v_permlane32_swap_b32_e32 v138, v140
	v_permlane32_swap_b32_e32 v139, v141
	v_permlane32_swap_b32_e32 v142, v144
	v_permlane32_swap_b32_e32 v143, v145
	v_add_u32_e32 v196, s27, v210
	ds_read_b64_tr_b16 v[146:147], v196 offset:0
	ds_read_b64_tr_b16 v[148:149], v196 offset:0x800
	ds_read_b64_tr_b16 v[150:151], v196 offset:0x1000
	ds_read_b64_tr_b16 v[152:153], v196 offset:0x1800
	ds_read_b64_tr_b16 v[154:155], v196 offset:0x2000
	ds_read_b64_tr_b16 v[156:157], v196 offset:0x2800
	ds_read_b64_tr_b16 v[158:159], v196 offset:0x3000
	ds_read_b64_tr_b16 v[160:161], v196 offset:0x3800
	v_add_u32_e32 v197, 0x4000, v196
	s_waitcnt lgkmcnt(4)
	s_mov_b64 s[4:5], -1
	v_mfma_f32_32x32x16_bf16 v[98:113], v[130:133], v[146:149], v[98:113]
	ds_read_b64_tr_b16 v[146:147], v196 offset:0x200
	ds_read_b64_tr_b16 v[148:149], v196 offset:0xa00
	s_andn2_b64 vcc, exec, s[46:47]
	v_mfma_f32_32x32x16_bf16 v[98:113], v[134:137], v[150:153], v[98:113]
	ds_read_b64_tr_b16 v[150:151], v196 offset:0x1200
	ds_read_b64_tr_b16 v[152:153], v196 offset:0x1a00
	s_waitcnt lgkmcnt(4)
	s_nop 0
	v_mfma_f32_32x32x16_bf16 v[98:113], v[138:141], v[154:157], v[98:113]
	ds_read_b64_tr_b16 v[154:155], v196 offset:0x2200
	ds_read_b64_tr_b16 v[156:157], v196 offset:0x2a00
	v_mfma_f32_32x32x16_bf16 v[98:113], v[142:145], v[158:161], v[98:113]
	ds_read_b64_tr_b16 v[158:159], v196 offset:0x3200
	ds_read_b64_tr_b16 v[160:161], v196 offset:0x3a00
	s_waitcnt lgkmcnt(4)
	s_nop 0
	v_mfma_f32_32x32x16_bf16 v[114:129], v[130:133], v[146:149], v[114:129]
	ds_read_b64_tr_b16 v[146:147], v196 offset:0x400
	ds_read_b64_tr_b16 v[148:149], v196 offset:0xc00
	v_mfma_f32_32x32x16_bf16 v[114:129], v[134:137], v[150:153], v[114:129]
	ds_read_b64_tr_b16 v[150:151], v196 offset:0x1400
	ds_read_b64_tr_b16 v[152:153], v196 offset:0x1c00
	s_waitcnt lgkmcnt(4)
	s_nop 0
	v_mfma_f32_32x32x16_bf16 v[114:129], v[138:141], v[154:157], v[114:129]
	ds_read_b64_tr_b16 v[154:155], v196 offset:0x2400
	ds_read_b64_tr_b16 v[156:157], v196 offset:0x2c00
	v_mfma_f32_32x32x16_bf16 v[114:129], v[142:145], v[158:161], v[114:129]
	ds_read_b64_tr_b16 v[158:159], v196 offset:0x3400
	ds_read_b64_tr_b16 v[160:161], v196 offset:0x3c00
	s_waitcnt lgkmcnt(4)
	s_nop 0
	v_mfma_f32_32x32x16_bf16 v[66:81], v[130:133], v[146:149], v[66:81]
	ds_read_b64_tr_b16 v[146:147], v196 offset:0x600
	ds_read_b64_tr_b16 v[148:149], v196 offset:0xe00
	v_mfma_f32_32x32x16_bf16 v[66:81], v[134:137], v[150:153], v[66:81]
	ds_read_b64_tr_b16 v[150:151], v196 offset:0x1600
	ds_read_b64_tr_b16 v[152:153], v196 offset:0x1e00
	s_waitcnt lgkmcnt(4)
	s_nop 0
	v_mfma_f32_32x32x16_bf16 v[66:81], v[138:141], v[154:157], v[66:81]
	ds_read_b64_tr_b16 v[154:155], v196 offset:0x2600
	ds_read_b64_tr_b16 v[156:157], v196 offset:0x2e00
	v_mfma_f32_32x32x16_bf16 v[66:81], v[142:145], v[158:161], v[66:81]
	ds_read_b64_tr_b16 v[158:159], v196 offset:0x3600
	ds_read_b64_tr_b16 v[160:161], v196 offset:0x3e00
	s_waitcnt lgkmcnt(4)
; #define BI2(R) do { constexpr float c_ = (float)(((R) & 3) + 8 * ((R) >> 2)); p0[R] = fmaf(fabsf(dubn + c_), nslope, negm); p1[R] = fmaf(fabsf(dubn + (c_ + 32.f)), nslope, negm); } while (0)
; #define VRD4(S, D0, KS, vb) s16x4 S##l0 = tr_read<v_rd_off(D0, KS, 0)>(vb), S##h0 = tr_read<v_rd_off(D0, KS, 1)>(vb), S##l1 = tr_read<v_rd_off(D0, KS + 1, 0)>(vb), S##h1 = tr_read<v_rd_off(D0, KS + 1, 1)>(vb)
; #define VWT4(S, N) asm volatile("s_waitcnt lgkmcnt(" #N ")" : "+v"(S##l0), "+v"(S##h0), "+v"(S##l1), "+v"(S##h1) :: "memory")
; #define VMM2(S, od, PA, PB) do { od = __builtin_amdgcn_mfma_f32_32x32x16_bf16(PA, VPK(S##l0, S##h0), od, 0, 0, 0); od = __builtin_amdgcn_mfma_f32_32x32x16_bf16(PB, VPK(S##l1, S##h1), od, 0, 0, 0); } while (0)
; __device__ __forceinline__ void pv_pipe8b(f32x16* oA, f32x16* oB, int vbA, int vbB, bf16x8 pa0, bf16x8 pa1, bf16x8 pa2, bf16x8 pa3, f32x16& p0, f32x16& p1, float dubn, float nslope, float negm) {
;     ...
;   VRD4(h9, 0, 2, vbB); VWT4(h8, 4); VMM2(h8, oB[0], pa0, pa1); BI2(8);
;   VRD4(h10, 1, 0, vbB); VWT4(h9, 4); VMM2(h9, oB[0], pa2, pa3); BI2(9);
;   VRD4(h11, 1, 2, vbB); VWT4(h10, 4); VMM2(h10, oB[1], pa0, pa1); BI2(10);
;   VRD4(h12, 2, 0, vbB); VWT4(h11, 4); VMM2(h11, oB[1], pa2, pa3); BI2(11);
;   VRD4(h13, 2, 2, vbB); VWT4(h12, 4); VMM2(h12, oB[2], pa0, pa1); BI2(12);
;   VRD4(h14, 3, 0, vbB); VWT4(h13, 4); VMM2(h13, oB[2], pa2, pa3); BI2(13);
;   VRD4(h15, 3, 2, vbB); VWT4(h14, 4); VMM2(h14, oB[3], pa0, pa1); BI2(14);
;   VWT4(h15, 0); VMM2(h15, oB[3], pa2, pa3); BI2(15);
; template <int EPI>
; __device__ __forceinline__ void attn_item_c(const Item& I, char* lds, int tid_in) {
;     ...
;     asm volatile("s_waitcnt vmcnt(0)" ::: "memory");
;     __syncthreads();
	s_nop 0
	v_mfma_f32_32x32x16_bf16 v[82:97], v[130:133], v[146:149], v[82:97]
	ds_read_b64_tr_b16 v[146:147], v197 offset:0
	ds_read_b64_tr_b16 v[148:149], v197 offset:0x800
	v_mfma_f32_32x32x16_bf16 v[82:97], v[134:137], v[150:153], v[82:97]
	ds_read_b64_tr_b16 v[150:151], v197 offset:0x1000
	ds_read_b64_tr_b16 v[152:153], v197 offset:0x1800
	s_waitcnt lgkmcnt(4)
	s_nop 0
	v_mfma_f32_32x32x16_bf16 v[82:97], v[138:141], v[154:157], v[82:97]
	ds_read_b64_tr_b16 v[154:155], v197 offset:0x2000
	ds_read_b64_tr_b16 v[156:157], v197 offset:0x2800
	v_mfma_f32_32x32x16_bf16 v[82:97], v[142:145], v[158:161], v[82:97]
	ds_read_b64_tr_b16 v[158:159], v197 offset:0x3000
	ds_read_b64_tr_b16 v[160:161], v197 offset:0x3800
	s_waitcnt lgkmcnt(4)
	s_nop 0
	v_mfma_f32_32x32x16_bf16 v[2:17], v[130:133], v[146:149], v[2:17]
	ds_read_b64_tr_b16 v[146:147], v197 offset:0x200
	ds_read_b64_tr_b16 v[148:149], v197 offset:0xa00
	v_mfma_f32_32x32x16_bf16 v[2:17], v[134:137], v[150:153], v[2:17]
	ds_read_b64_tr_b16 v[150:151], v197 offset:0x1200
	ds_read_b64_tr_b16 v[152:153], v197 offset:0x1a00
	s_waitcnt lgkmcnt(4)
	s_nop 0
	v_mfma_f32_32x32x16_bf16 v[2:17], v[138:141], v[154:157], v[2:17]
	ds_read_b64_tr_b16 v[154:155], v197 offset:0x2200
	ds_read_b64_tr_b16 v[156:157], v197 offset:0x2a00
	v_mfma_f32_32x32x16_bf16 v[2:17], v[142:145], v[158:161], v[2:17]
	ds_read_b64_tr_b16 v[158:159], v197 offset:0x3200
	ds_read_b64_tr_b16 v[160:161], v197 offset:0x3a00
	s_waitcnt lgkmcnt(4)
	s_nop 0
	v_mfma_f32_32x32x16_bf16 v[50:65], v[130:133], v[146:149], v[50:65]
	ds_read_b64_tr_b16 v[146:147], v197 offset:0x400
	ds_read_b64_tr_b16 v[148:149], v197 offset:0xc00
	v_mfma_f32_32x32x16_bf16 v[50:65], v[134:137], v[150:153], v[50:65]
	ds_read_b64_tr_b16 v[150:151], v197 offset:0x1400
	ds_read_b64_tr_b16 v[152:153], v197 offset:0x1c00
	s_waitcnt lgkmcnt(4)
	s_nop 0
	v_mfma_f32_32x32x16_bf16 v[50:65], v[138:141], v[154:157], v[50:65]
	ds_read_b64_tr_b16 v[154:155], v197 offset:0x2400
	ds_read_b64_tr_b16 v[156:157], v197 offset:0x2c00
	v_mfma_f32_32x32x16_bf16 v[50:65], v[142:145], v[158:161], v[50:65]
	ds_read_b64_tr_b16 v[158:159], v197 offset:0x3400
	ds_read_b64_tr_b16 v[160:161], v197 offset:0x3c00
	s_waitcnt lgkmcnt(4)
	s_nop 0
	v_mfma_f32_32x32x16_bf16 v[18:33], v[130:133], v[146:149], v[18:33]
	ds_read_b64_tr_b16 v[146:147], v197 offset:0x600
	ds_read_b64_tr_b16 v[148:149], v197 offset:0xe00
	v_mfma_f32_32x32x16_bf16 v[18:33], v[134:137], v[150:153], v[18:33]
	ds_read_b64_tr_b16 v[150:151], v197 offset:0x1600
	ds_read_b64_tr_b16 v[152:153], v197 offset:0x1e00
	s_waitcnt lgkmcnt(4)
	s_nop 0
	v_mfma_f32_32x32x16_bf16 v[18:33], v[138:141], v[154:157], v[18:33]
	ds_read_b64_tr_b16 v[154:155], v197 offset:0x2600
	ds_read_b64_tr_b16 v[156:157], v197 offset:0x2e00
	v_mfma_f32_32x32x16_bf16 v[18:33], v[142:145], v[158:161], v[18:33]
	ds_read_b64_tr_b16 v[158:159], v197 offset:0x3600
	ds_read_b64_tr_b16 v[160:161], v197 offset:0x3e00
	s_waitcnt lgkmcnt(4)
	s_nop 0
	s_waitcnt lgkmcnt(0)
	s_waitcnt vmcnt(0)
	v_mfma_f32_32x32x16_bf16 v[34:49], v[130:133], v[146:149], v[34:49]
	s_barrier
	v_mfma_f32_32x32x16_bf16 v[34:49], v[134:137], v[150:153], v[34:49]
	v_mfma_f32_32x32x16_bf16 v[34:49], v[138:141], v[154:157], v[34:49]
	v_mfma_f32_32x32x16_bf16 v[34:49], v[142:145], v[158:161], v[34:49]
	s_cbranch_vccnz .LBB0_866
; template <int EPI>
; __device__ __forceinline__ void attn_item_c(const Item& I, char* lds, int tid_in) {
;     ...
;     pv_pipe8b(oA, oB, vb0 + bsel * STG, vb0 + bsel * STG + SHM_V, pa0, pa1, pa2, pa3, p0, p1, dq + (float)(64 * CT(nf)), I.nslope, -m_reg);
	v_cvt_f32_u32_e32 v130, s72
	s_mov_b32 s4, 0x42680000
	s_mov_b32 s5, 0x426c0000
	v_mov_b32_e32 v215, v214
	v_add_f32_e32 v146, v246, v130
	v_pk_add_f32 v[130:131], v[146:147], s[4:5] op_sel_hi:[0,1]
	s_mov_b32 s4, 0x42600000
	s_mov_b32 s5, 0x42640000
	v_pk_add_f32 v[132:133], v[146:147], s[4:5] op_sel_hi:[0,1]
	s_mov_b32 s4, 0x42480000
	s_mov_b32 s5, 0x424c0000
	v_pk_add_f32 v[134:135], v[146:147], s[4:5] op_sel_hi:[0,1]
	s_mov_b32 s4, 0x42400000
	s_mov_b32 s5, 0x42440000
	v_pk_add_f32 v[136:137], v[146:147], s[4:5] op_sel_hi:[0,1]
	s_mov_b32 s4, 0x42280000
	s_mov_b32 s5, 0x422c0000
	v_pk_add_f32 v[138:139], v[146:147], s[4:5] op_sel_hi:[0,1]
	s_mov_b32 s4, 0x42200000
	s_mov_b32 s5, 0x42240000
	v_pk_add_f32 v[140:141], v[146:147], s[4:5] op_sel_hi:[0,1]
	s_mov_b32 s4, 0x42080000
	s_mov_b32 s5, 0x420c0000
	v_pk_add_f32 v[142:143], v[146:147], s[4:5] op_sel_hi:[0,1]
	s_mov_b32 s4, 0x42000000
	s_mov_b32 s5, 0x42040000
	v_pk_add_f32 v[144:145], v[146:147], s[4:5] op_sel_hi:[0,1]
	s_mov_b32 s4, 2.0
	v_and_b32_e32 v149, 0x7fffffff, v145
	v_and_b32_e32 v148, 0x7fffffff, v144
	v_and_b32_e32 v131, 0x7fffffff, v131
	v_and_b32_e32 v130, 0x7fffffff, v130
	v_add_f32_e32 v147, 1.0, v146
	s_mov_b32 s5, 0x40400000
	v_pk_fma_f32 v[144:145], v[130:131], v[214:215], v[224:225] op_sel_hi:[1,1,0] neg_lo:[0,0,1] neg_hi:[0,0,1]
	v_pk_fma_f32 v[130:131], v[148:149], v[216:217], v[224:225] op_sel_hi:[1,1,0] neg_lo:[0,0,1] neg_hi:[0,0,1]
	v_pk_add_f32 v[148:149], v[146:147], s[4:5] op_sel_hi:[0,1]
	s_mov_b32 s4, 0x41000000
	v_and_b32_e32 v151, 0x7fffffff, v143
	v_and_b32_e32 v150, 0x7fffffff, v142
	v_and_b32_e32 v133, 0x7fffffff, v133
	v_and_b32_e32 v132, 0x7fffffff, v132
	s_mov_b32 s5, 0x41100000
	v_pk_fma_f32 v[142:143], v[132:133], v[214:215], v[224:225] op_sel_hi:[1,1,0] neg_lo:[0,0,1] neg_hi:[0,0,1]
	v_pk_fma_f32 v[132:133], v[150:151], v[214:215], v[224:225] op_sel_hi:[1,1,0] neg_lo:[0,0,1] neg_hi:[0,0,1]
	v_pk_add_f32 v[150:151], v[146:147], s[4:5] op_sel_hi:[0,1]
	s_mov_b32 s4, 0x41200000
	v_and_b32_e32 v153, 0x7fffffff, v141
	v_and_b32_e32 v152, 0x7fffffff, v140
	v_and_b32_e32 v135, 0x7fffffff, v135
	v_and_b32_e32 v134, 0x7fffffff, v134
	s_mov_b32 s5, 0x41300000
	v_pk_fma_f32 v[140:141], v[134:135], v[214:215], v[224:225] op_sel_hi:[1,1,0] neg_lo:[0,0,1] neg_hi:[0,0,1]
	v_pk_fma_f32 v[134:135], v[152:153], v[214:215], v[224:225] op_sel_hi:[1,1,0] neg_lo:[0,0,1] neg_hi:[0,0,1]
	v_pk_add_f32 v[152:153], v[146:147], s[4:5] op_sel_hi:[0,1]
	s_mov_b32 s4, 0x41800000
	v_and_b32_e32 v155, 0x7fffffff, v139
	v_and_b32_e32 v154, 0x7fffffff, v138
	v_and_b32_e32 v137, 0x7fffffff, v137
	v_and_b32_e32 v136, 0x7fffffff, v136
	s_mov_b32 s5, 0x41880000
	v_pk_fma_f32 v[138:139], v[136:137], v[214:215], v[224:225] op_sel_hi:[1,1,0] neg_lo:[0,0,1] neg_hi:[0,0,1]
	v_pk_fma_f32 v[136:137], v[154:155], v[214:215], v[224:225] op_sel_hi:[1,1,0] neg_lo:[0,0,1] neg_hi:[0,0,1]
	v_pk_add_f32 v[154:155], v[146:147], s[4:5] op_sel_hi:[0,1]
	s_mov_b32 s4, 0x41900000
	s_mov_b32 s5, 0x41980000
	v_pk_add_f32 v[156:157], v[146:147], s[4:5] op_sel_hi:[0,1]
	s_mov_b32 s4, 0x41c00000
	s_mov_b32 s5, 0x41c80000
	v_pk_add_f32 v[158:159], v[146:147], s[4:5] op_sel_hi:[0,1]
	s_mov_b32 s4, 0x41d00000
	s_mov_b32 s5, 0x41d80000
	v_pk_add_f32 v[160:161], v[146:147], s[4:5] op_sel_hi:[0,1]
	v_and_b32_e32 v149, 0x7fffffff, v149
	v_and_b32_e32 v148, 0x7fffffff, v148
	v_and_b32_e32 v151, 0x7fffffff, v151
	v_and_b32_e32 v150, 0x7fffffff, v150
	v_and_b32_e32 v153, 0x7fffffff, v153
	v_and_b32_e32 v152, 0x7fffffff, v152
	v_and_b32_e32 v155, 0x7fffffff, v155
	v_and_b32_e32 v154, 0x7fffffff, v154
	v_and_b32_e32 v157, 0x7fffffff, v157
	v_and_b32_e32 v156, 0x7fffffff, v156
	v_and_b32_e32 v159, 0x7fffffff, v159
	v_and_b32_e32 v158, 0x7fffffff, v158
	v_and_b32_e32 v161, 0x7fffffff, v161
	v_and_b32_e32 v160, 0x7fffffff, v160
	v_and_b32_e32 v146, 0x7fffffff, v146
	v_and_b32_e32 v147, 0x7fffffff, v147
	v_pk_fma_f32 v[160:161], v[160:161], v[214:215], v[224:225] op_sel_hi:[1,1,0] neg_lo:[0,0,1] neg_hi:[0,0,1]
	v_pk_fma_f32 v[158:159], v[158:159], v[214:215], v[224:225] op_sel_hi:[1,1,0] neg_lo:[0,0,1] neg_hi:[0,0,1]
	v_pk_fma_f32 v[156:157], v[156:157], v[214:215], v[224:225] op_sel_hi:[1,1,0] neg_lo:[0,0,1] neg_hi:[0,0,1]
	v_pk_fma_f32 v[154:155], v[154:155], v[214:215], v[224:225] op_sel_hi:[1,1,0] neg_lo:[0,0,1] neg_hi:[0,0,1]
	v_pk_fma_f32 v[152:153], v[152:153], v[214:215], v[224:225] op_sel_hi:[1,1,0] neg_lo:[0,0,1] neg_hi:[0,0,1]
	v_pk_fma_f32 v[150:151], v[150:151], v[214:215], v[224:225] op_sel_hi:[1,1,0] neg_lo:[0,0,1] neg_hi:[0,0,1]
	v_pk_fma_f32 v[148:149], v[148:149], v[214:215], v[224:225] op_sel_hi:[1,1,0] neg_lo:[0,0,1] neg_hi:[0,0,1]
	v_pk_fma_f32 v[146:147], v[146:147], v[216:217], v[224:225] op_sel_hi:[1,1,0] neg_lo:[0,0,1] neg_hi:[0,0,1]
	s_add_i32 s54, s54, 1
	s_mov_b64 s[4:5], 0

; __device__ __forceinline__ unsigned xb_ld(unsigned* p)              { return __hip_atomic_load(p, __ATOMIC_RELAXED, __HIP_MEMORY_SCOPE_AGENT); }
; __device__ __forceinline__ unsigned xb_add(unsigned* p, unsigned v) { return __hip_atomic_fetch_add(p, v, __ATOMIC_RELAXED, __HIP_MEMORY_SCOPE_AGENT); }
; #define XB_SPIN(cond, bar) do { unsigned _sp = 0; while (cond) { __builtin_amdgcn_s_sleep(1); \
;     if ((++_sp & 255u) == 0u) { if (xb_ld(&(bar)[XB_TMO])) break; if (_sp > XB_SPIN_CAP) { atomicAdd(&(bar)[XB_TMO], 1u); break; } } } } while (0)
; __device__ __forceinline__ void xcd_barrier(const XcdBarrier& b) {
;     ...
;         const unsigned old = xb_add(&bar[XB_XSUB(b.x)], 1u);
;         const unsigned gen = old / nloc;
;         if (old + 1u == (gen + 1u) * nloc) {
;             __builtin_amdgcn_fence(__ATOMIC_RELEASE, "agent");
;             asm volatile("s_waitcnt vmcnt(0)" ::: "memory");
;             const unsigned og = xb_add(&bar[XB_TOP], 1u);
;             const unsigned tg = og / nx;
;             if (og + 1u == (tg + 1u) * nx) xb_add(&bar[XB_TOPGEN], 1u);
;             else XB_SPIN(xb_ld(&bar[XB_TOPGEN]) == tg, bar);
;             __builtin_amdgcn_fence(__ATOMIC_ACQUIRE, "agent");
;             xb_add(&bar[XB_XGEN(b.x)], 1u);
;             asm volatile("s_waitcnt vmcnt(0)" ::: "memory");
;         } else {
;             XB_SPIN(xb_ld(&bar[XB_XGEN(b.x)]) == gen, bar);
;             __builtin_amdgcn_fence(__ATOMIC_ACQUIRE, "agent");
;             asm volatile("s_waitcnt vmcnt(0)" ::: "memory");
;         }
.LBB0_902:
	s_or_b64 exec, exec, s[6:7]
	s_waitcnt vmcnt(0)
	buffer_inv sc1
.LBB0_903:
	s_andn2_saveexec_b64 s[4:5], s[4:5]
	s_cbranch_execz .LBB0_923
	s_mov_b64 s[4:5], exec
	buffer_wbl2 sc1
	s_waitcnt lgkmcnt(0)
	s_waitcnt vmcnt(0)
	v_mbcnt_lo_u32_b32 v0, s4, 0
	v_mbcnt_hi_u32_b32 v0, s5, v0
	v_cmp_eq_u32_e32 vcc, 0, v0
	s_and_saveexec_b64 s[6:7], vcc
	s_cbranch_execz .LBB0_906
	s_bcnt1_i32_b64 s4, s[4:5]
	v_mov_b32_e32 v3, s4
	v_readlane_b32 s4, v255, 17
	v_readlane_b32 s5, v255, 18
	s_nop 4
	global_atomic_add v3, v1, v3, s[4:5] sc0

; #define LAS __attribute__((address_space(3)))
; template <int WIN, bool ALIBI, int EPI, bool SINK>
; __device__ __forceinline__ void attn_item(const Item& I, char* lds, int tid_in) {
;     ...
;   const int tokq = I.seq_base + I.c0 + wcls + I.dil * uq;
;     ...
;       const float wa = __builtin_amdgcn_exp2f(lold - mx), wb = __builtin_amdgcn_exp2f(lcur - mx), den = wa + wb; STG(float, lp) = mx + __log2f(den);
;       al_l[r32] = wa / den; li_l[r32] = wb / (den * l_reg); } }
;   asm volatile("s_waitcnt lgkmcnt(0)" ::: "memory");
;   const int tokw = I.seq_base + I.c0 + wcls + I.dil * (I.u0 + (two ? (wid & 3) * 32 : wid * 32));
;   bf16_t* Ow = I.O + (size_t)tokw * DM + I.ocol + r32;
;   LAS unsigned* park = (LAS unsigned*)(V_lds + 2 * SHM_V + 2 * SHM_K + 2048) + tid * 32;
;   if constexpr (EPI == 4) {
; #pragma unroll
;     for (int r = 0; r < 16; r += 2) { const float f0 = li_l[crow(r, hi)], f1 = li_l[crow(r + 1, hi)];
; #pragma unroll
;       for (int d0 = 0; d0 < 4; ++d0) park[(r >> 1) * 4 + d0] = cvt_pk_bf16(o[d0][r] * f0, o[d0][r + 1] * f1); }
;   } else if constexpr (EPI == 3) {
;     unsigned oldv[16][4];
; #pragma unroll
;     for (int r = 0; r < 16; ++r) { const bf16_t* Or = Ow + (size_t)(I.dil * crow(r, hi)) * DM;
; #pragma unroll
;       for (int d0 = 0; d0 < 4; ++d0) oldv[r][d0] = (unsigned)LDG(bf16_t, Or + d0 * 32); }
;     asm volatile("" ::: "memory");
; #pragma unroll
;     for (int r = 0; r < 16; ++r) { const int orow = crow(r, hi); const float f = li_l[orow];
;       bf16_t* Or = Ow + (size_t)(I.dil * orow) * DM;
; #pragma unroll
;       for (int d0 = 0; d0 < 4; ++d0) { const float v = __uint_as_float(oldv[r][d0] << 16) + o[d0][r] * f;
;         STG(bf16_t, Or + d0 * 32) = (bf16_t)(cvt_pk_bf16(v, v) & 0xffffu); } }
;   } else {
;     const int rsub = lane >> 4, ch = lane & 15;
;     bf16_t* Orow = I.O + (size_t)tokw * DM + I.ocol + ch * 8;
;     u32x4 oldv[(EPI == 2) ? 8 : 1];
;     if constexpr (EPI == 2) {
; #pragma unroll
;       for (int j = 0; j < 8; ++j) oldv[j] = LDG(u32x4, Orow + (size_t)(I.dil * (4 * j + rsub)) * DM); }
;     __syncthreads();
;     constexpr int RB = (EPI == 2) ? 512 : 256;
;     LAS char* Sw = V_lds + wid * (32 * RB);
;     if constexpr (EPI == 5) {
; #pragma unroll
;       for (int r = 0; r < 16; r += 2) { const int or0 = crow(r, hi), or1 = crow(r + 1, hi); const float f0 = li_l[or0], f1 = li_l[or1];
; #pragma unroll
.LBB0_931:
	s_or_b64 exec, exec, s[4:5]
	s_add_i32 s4, s48, s9
	s_ashr_i32 s5, s4, 31
	s_lshl_b64 s[4:5], s[4:5], 12
	s_add_u32 s4, s44, s4
	s_waitcnt lgkmcnt(0)
	s_addc_u32 s5, s45, s5
	s_lshl_b32 s9, s12, 1
	s_barrier
	ds_read_b32 v0, v173
	s_add_u32 s4, s4, s9
	s_addc_u32 s5, s5, 0
	s_lshl_b32 s9, s24, 13
	s_add_i32 s9, s9, 0
	v_lshl_add_u32 v66, v168, 1, s9
	v_lshl_add_u32 v67, v169, 10, v66
	s_waitcnt lgkmcnt(0)
	v_mul_f32_e32 v50, v50, v0
	v_mul_f32_e32 v34, v34, v0
	v_mul_f32_e32 v18, v18, v0
	v_mul_f32_e32 v0, v2, v0
	v_cvt_pk_bf16_f32 v50, v50, v50
	ds_write_b16 v67, v50
	v_cvt_pk_bf16_f32 v34, v34, v34
	ds_write_b16 v67, v34 offset:64
	v_cvt_pk_bf16_f32 v18, v18, v18
	ds_write_b16 v67, v18 offset:128
	v_cvt_pk_bf16_f32 v0, v0, v0
	ds_read_b32 v2, v173 offset:4
	ds_write_b16 v67, v0 offset:192
	v_lshl_add_u32 v18, v171, 8, v66
	s_add_i32 s8, s8, 1
	s_waitcnt lgkmcnt(1)
	v_mul_f32_e32 v0, v51, v2
	v_cvt_pk_bf16_f32 v0, v0, v0
	ds_write_b16 v18, v0 offset:256
	v_mul_f32_e32 v0, v35, v2
	v_cvt_pk_bf16_f32 v0, v0, v0
	ds_write_b16 v18, v0 offset:320
	v_mul_f32_e32 v0, v19, v2
	v_cvt_pk_bf16_f32 v0, v0, v0
	ds_write_b16 v18, v0 offset:384
	v_mul_f32_e32 v0, v3, v2
	v_cvt_pk_bf16_f32 v0, v0, v0
	ds_read_b32 v2, v173 offset:8
	ds_write_b16 v18, v0 offset:448
	s_waitcnt lgkmcnt(1)
	v_mul_f32_e32 v0, v52, v2
	v_cvt_pk_bf16_f32 v0, v0, v0
	ds_write_b16 v18, v0 offset:512
	v_mul_f32_e32 v0, v36, v2
	v_cvt_pk_bf16_f32 v0, v0, v0
	ds_write_b16 v18, v0 offset:576
	v_mul_f32_e32 v0, v20, v2
	v_cvt_pk_bf16_f32 v0, v0, v0
	ds_write_b16 v18, v0 offset:640
	v_mul_f32_e32 v0, v4, v2
	v_cvt_pk_bf16_f32 v0, v0, v0
	ds_read_b32 v2, v173 offset:12
	ds_write_b16 v18, v0 offset:704
	s_waitcnt lgkmcnt(1)
	v_mul_f32_e32 v0, v53, v2
	v_cvt_pk_bf16_f32 v0, v0, v0
	ds_write_b16 v18, v0 offset:768
	v_mul_f32_e32 v0, v37, v2
	v_cvt_pk_bf16_f32 v0, v0, v0
	ds_write_b16 v18, v0 offset:832
	v_mul_f32_e32 v0, v21, v2
	v_cvt_pk_bf16_f32 v0, v0, v0
	ds_write_b16 v18, v0 offset:896
	v_mul_f32_e32 v0, v5, v2
	v_cvt_pk_bf16_f32 v0, v0, v0
	ds_read_b32 v2, v173 offset:32
	ds_write_b16 v18, v0 offset:960
	s_waitcnt lgkmcnt(1)
	v_mul_f32_e32 v0, v54, v2
	v_cvt_pk_bf16_f32 v0, v0, v0
	ds_write_b16 v18, v0 offset:2048
	v_mul_f32_e32 v0, v38, v2
	v_cvt_pk_bf16_f32 v0, v0, v0
	ds_write_b16 v18, v0 offset:2112
	v_mul_f32_e32 v0, v22, v2
	v_cvt_pk_bf16_f32 v0, v0, v0
	ds_write_b16 v18, v0 offset:2176
	v_mul_f32_e32 v0, v6, v2
	v_cvt_pk_bf16_f32 v0, v0, v0
	ds_read_b32 v2, v173 offset:36
	ds_write_b16 v18, v0 offset:2240
	s_waitcnt lgkmcnt(1)
	v_mul_f32_e32 v0, v55, v2
	v_cvt_pk_bf16_f32 v0, v0, v0
	ds_write_b16 v18, v0 offset:2304
	v_mul_f32_e32 v0, v39, v2
	v_cvt_pk_bf16_f32 v0, v0, v0
	ds_write_b16 v18, v0 offset:2368
	v_mul_f32_e32 v0, v23, v2
	v_cvt_pk_bf16_f32 v0, v0, v0
	ds_write_b16 v18, v0 offset:2432
	v_mul_f32_e32 v0, v7, v2
	v_cvt_pk_bf16_f32 v0, v0, v0
	ds_read_b32 v2, v173 offset:40
	ds_write_b16 v18, v0 offset:2496
	s_waitcnt lgkmcnt(1)
	v_mul_f32_e32 v0, v56, v2
	v_cvt_pk_bf16_f32 v0, v0, v0
	ds_write_b16 v18, v0 offset:2560
	v_mul_f32_e32 v0, v40, v2
	v_cvt_pk_bf16_f32 v0, v0, v0
	ds_write_b16 v18, v0 offset:2624
	v_mul_f32_e32 v0, v24, v2
	v_cvt_pk_bf16_f32 v0, v0, v0
	ds_write_b16 v18, v0 offset:2688
	v_mul_f32_e32 v0, v8, v2
	v_cvt_pk_bf16_f32 v0, v0, v0
	ds_read_b32 v2, v173 offset:44
	ds_write_b16 v18, v0 offset:2752
	s_waitcnt lgkmcnt(1)
	v_mul_f32_e32 v0, v57, v2
	v_cvt_pk_bf16_f32 v0, v0, v0
	ds_write_b16 v18, v0 offset:2816
	v_mul_f32_e32 v0, v41, v2
	v_cvt_pk_bf16_f32 v0, v0, v0
	ds_write_b16 v18, v0 offset:2880
	v_mul_f32_e32 v0, v25, v2
	v_cvt_pk_bf16_f32 v0, v0, v0
	ds_write_b16 v18, v0 offset:2944
	v_mul_f32_e32 v0, v9, v2
	v_cvt_pk_bf16_f32 v0, v0, v0
	ds_read_b32 v2, v173 offset:64
	ds_write_b16 v18, v0 offset:3008
	s_waitcnt lgkmcnt(1)
	v_mul_f32_e32 v0, v58, v2
	v_cvt_pk_bf16_f32 v0, v0, v0
	ds_write_b16 v18, v0 offset:4096
	v_mul_f32_e32 v0, v42, v2
	v_cvt_pk_bf16_f32 v0, v0, v0
	ds_write_b16 v18, v0 offset:4160
	v_mul_f32_e32 v0, v26, v2
	v_cvt_pk_bf16_f32 v0, v0, v0
	ds_write_b16 v18, v0 offset:4224
	v_mul_f32_e32 v0, v10, v2
	v_cvt_pk_bf16_f32 v0, v0, v0
	ds_read_b32 v2, v173 offset:68
	ds_write_b16 v18, v0 offset:4288
	s_waitcnt lgkmcnt(1)
	v_mul_f32_e32 v0, v59, v2
	v_cvt_pk_bf16_f32 v0, v0, v0
	ds_write_b16 v18, v0 offset:4352
	v_mul_f32_e32 v0, v43, v2
	v_cvt_pk_bf16_f32 v0, v0, v0
	ds_write_b16 v18, v0 offset:4416
	v_mul_f32_e32 v0, v27, v2
	v_cvt_pk_bf16_f32 v0, v0, v0
	ds_write_b16 v18, v0 offset:4480
	v_mul_f32_e32 v0, v11, v2
	v_cvt_pk_bf16_f32 v0, v0, v0
	ds_read_b32 v2, v173 offset:72
	ds_write_b16 v18, v0 offset:4544
	s_waitcnt lgkmcnt(1)
; #define LAS __attribute__((address_space(3)))
; __device__ __forceinline__ unsigned cvt_pk_bf16(float lo, float hi) { unsigned r; asm volatile("v_cvt_pk_bf16_f32 %0, %1, %2" : "=v"(r) : "v"(lo), "v"(hi)); return r; }
; __device__ __forceinline__ float bf_lo(unsigned w) { return __uint_as_float(w << 16); }
; __device__ __forceinline__ float bf_hi(unsigned w) { return __uint_as_float(w & 0xffff0000u); }
; __device__ __forceinline__ int crow(int r, int hi) { return (r & 3) + 8 * (r >> 2) + 4 * hi; }
; template <int WIN, bool ALIBI, int EPI, bool SINK>
; __device__ __forceinline__ void attn_item(const Item& I, char* lds, int tid_in) {
;     ...
; #pragma unroll
;       for (int r = 0; r < 16; ++r) { const int orow = crow(r, hi); const float f = li_l[orow];
; #pragma unroll
;         for (int d0 = 0; d0 < 4; ++d0) { const float v = o[d0][r] * f;
;           if constexpr (EPI == 2) *(LAS float*)(Sw + orow * RB + (d0 * 32 + r32) * 4) = v;
;           else *(LAS bf16_t*)(Sw + orow * RB + (d0 * 32 + r32) * 2) = (bf16_t)(cvt_pk_bf16(v, v) & 0xffffu); } }
;     }
;     asm volatile("s_waitcnt lgkmcnt(0)" ::: "memory");
;     if constexpr (EPI == 2) {
; #pragma unroll
;       for (int j = 0; j < 8; ++j) { const int row = 4 * j + rsub; const float fo = al_l[row];
;         const f32x4 a0 = *(const LAS f32x4*)(Sw + row * RB + ch * 32), a1 = *(const LAS f32x4*)(Sw + row * RB + ch * 32 + 16); const u32x4 ov = oldv[j];
;         u32x4 w; w.x = cvt_pk_bf16(fo * bf_lo(ov.x) + a0[0], fo * bf_hi(ov.x) + a0[1]); w.y = cvt_pk_bf16(fo * bf_lo(ov.y) + a0[2], fo * bf_hi(ov.y) + a0[3]);
;         w.z = cvt_pk_bf16(fo * bf_lo(ov.z) + a1[0], fo * bf_hi(ov.z) + a1[1]); w.w = cvt_pk_bf16(fo * bf_lo(ov.w) + a1[2], fo * bf_hi(ov.w) + a1[3]);
;         STG(u32x4, Orow + (size_t)(I.dil * row) * DM) = w; }
;     } else {
; #pragma unroll
;       for (int j = 0; j < 8; ++j) { const int row = 4 * j + rsub; const u32x4 w = *(const LAS u32x4*)(Sw + row * RB + ch * 16);
;         STG(u32x4, Orow + (size_t)(I.dil * row) * DM) = w; }
;     }
;   }
;   __syncthreads();
; template <int MODE> __device__ __forceinline__ void phase_attn_fast(const Frame& F0) {
;     ...
;   for (int i = 0;; ++i) {
;     const int it = i * F.G + F.vcu; if (it >= 2560) break;
	v_mul_f32_e32 v0, v60, v2
	v_cvt_pk_bf16_f32 v0, v0, v0
	ds_write_b16 v18, v0 offset:4608
	v_mul_f32_e32 v0, v44, v2
	v_cvt_pk_bf16_f32 v0, v0, v0
	ds_write_b16 v18, v0 offset:4672
	v_mul_f32_e32 v0, v28, v2
	v_cvt_pk_bf16_f32 v0, v0, v0
	ds_write_b16 v18, v0 offset:4736
	v_mul_f32_e32 v0, v12, v2
	v_cvt_pk_bf16_f32 v0, v0, v0
	ds_read_b32 v2, v173 offset:76
	ds_write_b16 v18, v0 offset:4800
	s_waitcnt lgkmcnt(1)
	v_mul_f32_e32 v0, v61, v2
	v_cvt_pk_bf16_f32 v0, v0, v0
	ds_write_b16 v18, v0 offset:4864
	v_mul_f32_e32 v0, v45, v2
	v_cvt_pk_bf16_f32 v0, v0, v0
	ds_write_b16 v18, v0 offset:4928
	v_mul_f32_e32 v0, v29, v2
	v_cvt_pk_bf16_f32 v0, v0, v0
	ds_write_b16 v18, v0 offset:4992
	v_mul_f32_e32 v0, v13, v2
	v_cvt_pk_bf16_f32 v0, v0, v0
	ds_read_b32 v2, v173 offset:96
	ds_write_b16 v18, v0 offset:5056
	s_waitcnt lgkmcnt(1)
	v_mul_f32_e32 v0, v62, v2
	v_cvt_pk_bf16_f32 v0, v0, v0
	ds_write_b16 v18, v0 offset:6144
	v_mul_f32_e32 v0, v46, v2
	v_cvt_pk_bf16_f32 v0, v0, v0
	ds_write_b16 v18, v0 offset:6208
	v_mul_f32_e32 v0, v30, v2
	v_cvt_pk_bf16_f32 v0, v0, v0
	ds_write_b16 v18, v0 offset:6272
	v_mul_f32_e32 v0, v14, v2
	v_cvt_pk_bf16_f32 v0, v0, v0
	ds_read_b32 v2, v173 offset:100
	ds_write_b16 v18, v0 offset:6336
	v_lshrrev_b32_e32 v14, 4, v165
	s_waitcnt lgkmcnt(1)
	v_mul_f32_e32 v0, v63, v2
	v_cvt_pk_bf16_f32 v0, v0, v0
	ds_write_b16 v18, v0 offset:6400
	v_mul_f32_e32 v0, v47, v2
	v_cvt_pk_bf16_f32 v0, v0, v0
	ds_write_b16 v18, v0 offset:6464
	v_mul_f32_e32 v0, v31, v2
	v_cvt_pk_bf16_f32 v0, v0, v0
	ds_write_b16 v18, v0 offset:6528
	v_mul_f32_e32 v0, v15, v2
	v_cvt_pk_bf16_f32 v0, v0, v0
	ds_read_b32 v2, v173 offset:104
	ds_write_b16 v18, v0 offset:6592
	s_waitcnt lgkmcnt(1)
	v_mul_f32_e32 v0, v64, v2
	v_cvt_pk_bf16_f32 v0, v0, v0
	ds_write_b16 v18, v0 offset:6656
	v_mul_f32_e32 v0, v48, v2
	v_cvt_pk_bf16_f32 v0, v0, v0
	ds_write_b16 v18, v0 offset:6720
	v_mul_f32_e32 v0, v32, v2
	v_cvt_pk_bf16_f32 v0, v0, v0
	ds_write_b16 v18, v0 offset:6784
	v_mul_f32_e32 v0, v16, v2
	v_cvt_pk_bf16_f32 v0, v0, v0
	ds_read_b32 v2, v173 offset:108
	ds_write_b16 v18, v0 offset:6848
	v_or_b32_e32 v16, 4, v14
	s_waitcnt lgkmcnt(1)
	v_mul_f32_e32 v0, v65, v2
	v_cvt_pk_bf16_f32 v0, v0, v0
	ds_write_b16 v18, v0 offset:6912
	v_mul_f32_e32 v0, v49, v2
	v_cvt_pk_bf16_f32 v0, v0, v0
	ds_write_b16 v18, v0 offset:6976
	v_mul_f32_e32 v0, v33, v2
	v_cvt_pk_bf16_f32 v0, v0, v0
	ds_write_b16 v18, v0 offset:7040
	v_mul_f32_e32 v0, v17, v2
	v_cvt_pk_bf16_f32 v0, v0, v0
	ds_write_b16 v18, v0 offset:7104
	v_and_b32_e32 v0, 0xf0, v166
	v_add_u32_e32 v15, s9, v0
	v_lshl_add_u64 v[10:11], s[4:5], 0, v[0:1]
	s_waitcnt lgkmcnt(0)
	v_lshl_add_u32 v0, v14, 8, v15
	ds_read_b128 v[2:5], v0
	v_lshl_add_u32 v6, v16, 8, v15
	ds_read_b128 v[6:9], v6
	v_lshlrev_b32_e32 v0, 12, v14
	v_lshl_add_u64 v[12:13], v[10:11], 0, v[0:1]
	v_lshlrev_b32_e32 v0, 12, v16
	s_waitcnt lgkmcnt(1)
	global_store_dwordx4 v[12:13], v[2:5], off
	v_or_b32_e32 v16, 12, v14
	s_mul_i32 s4, s8, s6
	v_lshl_add_u64 v[2:3], v[10:11], 0, v[0:1]
	v_or_b32_e32 v0, 8, v14
	s_waitcnt lgkmcnt(0)
	global_store_dwordx4 v[2:3], v[6:9], off
	v_lshl_add_u32 v2, v0, 8, v15
	ds_read_b128 v[2:5], v2
	v_lshl_add_u32 v6, v16, 8, v15
	ds_read_b128 v[6:9], v6
	v_lshlrev_b32_e32 v0, 12, v0
	v_lshl_add_u64 v[12:13], v[10:11], 0, v[0:1]
	v_lshlrev_b32_e32 v0, 12, v16
	s_waitcnt lgkmcnt(1)
	global_store_dwordx4 v[12:13], v[2:5], off
	v_or_b32_e32 v16, 20, v14
	s_add_i32 s12, s4, s7
	v_lshl_add_u64 v[2:3], v[10:11], 0, v[0:1]
	v_or_b32_e32 v0, 16, v14
	s_waitcnt lgkmcnt(0)
	global_store_dwordx4 v[2:3], v[6:9], off
	v_lshl_add_u32 v2, v0, 8, v15
	ds_read_b128 v[2:5], v2
	v_lshl_add_u32 v6, v16, 8, v15
	ds_read_b128 v[6:9], v6
	v_lshlrev_b32_e32 v0, 12, v0
	v_lshl_add_u64 v[12:13], v[10:11], 0, v[0:1]
	v_lshlrev_b32_e32 v0, 12, v16
	s_waitcnt lgkmcnt(1)
	global_store_dwordx4 v[12:13], v[2:5], off
	s_cmpk_lt_i32 s12, 0xa00
	s_nop 0
	v_lshl_add_u64 v[2:3], v[10:11], 0, v[0:1]
	v_or_b32_e32 v0, 24, v14
	s_waitcnt lgkmcnt(0)
	global_store_dwordx4 v[2:3], v[6:9], off
	v_lshl_add_u32 v2, v0, 8, v15
	v_or_b32_e32 v14, 28, v14
	ds_read_b128 v[2:5], v2
	v_lshl_add_u32 v6, v14, 8, v15
	ds_read_b128 v[6:9], v6
	v_lshlrev_b32_e32 v0, 12, v0
	v_lshl_add_u64 v[12:13], v[10:11], 0, v[0:1]
	v_lshlrev_b32_e32 v0, 12, v14
	s_waitcnt lgkmcnt(1)
	global_store_dwordx4 v[12:13], v[2:5], off
	s_nop 1
	v_lshl_add_u64 v[2:3], v[10:11], 0, v[0:1]
	s_waitcnt lgkmcnt(0)
	global_store_dwordx4 v[2:3], v[6:9], off
	s_barrier
	s_cbranch_scc0 .LBB0_950

; template <int WIN, bool ALIBI, int EPI, bool SINK>
; __device__ __forceinline__ void attn_item(const Item& I, char* lds, int tid_in) {
;     ...
;   const float lo = WIN ? (float)max(-WIN, -uq) : 0.f, hi_ = WIN ? (float)min(WIN, I.SU - 1 - uq) : 0.f;
;   const float dq = (float)(4 * hi - uq);
;   const int sr = tid >> 4, sc = (tid & 15) * 8, vst0 = v_st(sr, sc), vst1 = v_st(32 + sr, sc);
;   const int vb0 = (int)(unsigned)(uintptr_t)V_lds + v_rd_base(lane);
;   struct { bf16x8 vs0, vs1, ks0, ks1; } sr_[2];
;     ...
;   f32x16 pA0, pA1, pB0, pB1; float mnA, mnB, alA, alB; bf16x8 pa0, pa1, pa2, pa3; const int NT = I.NT;
;   constexpr int SE = 0, SO = 1;
;   if constexpr (WIN == 0) {
;   SLOAD(SE, 0); asm volatile("s_waitcnt vmcnt(0)" ::: "memory"); SWRITE(0, SE); __syncthreads();
;   qkt(pA0, pA1, K_lds, qr, r32, hi); PSM(pA0, pA1, mnA, alA, 0);
;   SLOAD(SO, 1); if (2 < NT) SLOAD(SE, 2);
;   SWAIT(); SWRITE(1, SO); __syncthreads();
;   for (int j = 1; j + 1 < NT; j += 2) {
;     SBAR(); qkt(pB0, pB1, K_lds + SHM_K, qr, r32, hi);
;     finishSM(pA0, pA1, alA, l_reg, pa0, pa1, pa2, pa3); SBAR();
;     SLOAD(SO, j + 2); SBAR();
;     pv_psm<ALIBI>(o, vb0, pa0, pa1, pa2, pa3, pB0, pB1, m_reg, mnB, alB, dq + (float)TILE_UKB(j), I.nslope);
;     __syncthreads(); SWAIT(); SWRITE(0, SE);
;     RESC(alB); __syncthreads();
;     SBAR(); qkt(pA0, pA1, K_lds, qr, r32, hi);
;     finishSM(pB0, pB1, alB, l_reg, pa0, pa1, pa2, pa3); SBAR();
;     if (j + 3 < NT) SLOAD(SE, j + 3); SBAR();
;     pv_psm<ALIBI>(o, vb0 + SHM_V, pa0, pa1, pa2, pa3, pA0, pA1, m_reg, mnA, alA, dq + (float)TILE_UKB(j + 1), I.nslope);
;     __syncthreads(); SWAIT(); SWRITE(1, SO);
;     RESC(alA); __syncthreads();
;   }
; template <int MODE> __device__ __forceinline__ void phase_attn_fast(const Frame& F0) {
;     ...
;     } else { const int kvh = d.h >> 2; I.W = 3072; I.qcol = d.h * 128; I.kcol = 2048 + kvh * 128; I.vcol = 2560 + kvh * 128; I.ocol = d.h * 128;
;       const float slope2 = exp2f(-0.5f * (float)(d.h + 1)) * LOG2E;
;       if (MODE == 0) { I.ukb0 = 0; I.NT = d.S / 64; I.ropetab = (const float*)(F.ws + WS_ROPE); I.qgain = argp(F, 9); fa::attn_item<0, false, 0, false>(I, (char*)F.lds, F.tid); }
;       if (MODE == 1) { I.ukb0 = I.u0 - 128; I.NT = 8; I.nslope = -slope2; I.sink2 = argp(F, 13)[d.h] * LOG2E; fa::attn_item<128, true, 0, true>(I, (char*)F.lds, F.tid); }
.LBB0_937:
	s_lshr_b32 s13, s12, s13
	s_and_b32 s5, s5, s12
	s_lshl_b32 s31, s5, 8
	s_lshl_b32 s5, s13, 5
	s_and_b32 s26, s13, 15
	s_and_b32 s5, s5, 0x180
	s_or_b32 s27, s5, 0x800
	s_or_b32 s28, s5, 0xa00
	s_add_i32 s5, s26, 1
	v_cvt_f32_ubyte0_e32 v0, s5
	v_mul_f32_e32 v2, -0.5, v0
	s_mov_b32 s5, 0xc2fc0000
	s_lshl_b32 s12, s26, 7
	v_cmp_gt_f32_e32 vcc, s5, v2
	s_and_b64 s[24:25], vcc, exec
	s_mov_b64 s[24:25], s[40:41]
	v_cndmask_b32_e32 v2, 0, v230, vcc
	v_fmac_f32_e32 v2, -0.5, v0
	v_exp_f32_e32 v0, v2
	s_load_dwordx2 s[24:25], s[24:25], 0x68
	s_cselect_b32 s5, 0xffffffc0, 0
	v_ldexp_f32 v0, v0, s5
	s_lshl_b32 s5, s26, 2
	v_mul_f32_e32 v167, 0xbfb8aa3b, v0
	v_mov_b32_e32 v0, s5
	s_waitcnt lgkmcnt(0)
	global_load_dword v0, v0, s[24:25]
	v_mov_b32_e32 v15, v164
	v_mov_b64_e32 v[2:3], s[42:43]
	v_readfirstlane_b32 s5, v15
	s_ashr_i32 s24, s5, 6
	v_and_b32_e32 v168, 31, v15
	s_lshl_b32 s48, s24, 5
	v_bfe_u32 v169, v15, 5, 1
	s_lshl_b32 s72, s26, 8
	s_and_b32 s25, s5, 0x3fffffc0
	s_lshl_b32 s25, s25, 2
	s_ashr_i32 s5, s5, 8
	s_add_i32 s29, s25, 0
	v_lshlrev_b32_e32 v44, 3, v15
	s_lshl_b32 s25, s5, 16
	s_lshl_b32 s5, s5, 7
	v_and_b32_e32 v165, 63, v15
	v_lshlrev_b32_e32 v171, 2, v169
	v_lshlrev_b32_e32 v166, 4, v15
	s_add_i32 s30, s25, 0
	s_add_i32 s25, s31, s5
	v_bfe_u32 v17, v15, 4, 4
	s_add_i32 s5, s25, 0xffffff80
	v_or_b32_e32 v13, s5, v17
	s_add_i32 s26, s4, -1
	v_mov_b32_e32 v11, v1
	v_lshrrev_b32_e32 v18, 4, v15
	v_bfe_u32 v45, v15, 4, 2
	s_add_i32 s29, s29, 0x20000
	v_add_u32_e32 v189, 0x80, v13
	s_mov_b32 s13, 0
	v_lshl_add_u32 v180, v168, 8, s30
	v_lshl_add_u32 v177, v168, 2, s29
	v_mov_b32_e32 v190, 1.0
	s_lshl_b32 s46, s27, 1
	s_mov_b32 s51, 0
	s_waitcnt vmcnt(0)
	v_mul_f32_e32 v170, 0x3fb8aa3b, v0
	v_or_b32_e32 v0, s48, v168
	v_add_u32_e32 v4, s31, v0
	v_add_u32_e32 v0, s9, v4
	v_mad_i64_i32 v[2:3], s[36:37], v0, s89, v[2:3]
	v_lshl_add_u64 v[2:3], v[2:3], 0, s[72:73]
	v_lshlrev_b32_e32 v0, 4, v169
	v_lshl_add_u64 v[2:3], v[2:3], 0, v[0:1]
	global_load_dwordx4 v[98:101], v[2:3], off
	global_load_dwordx4 v[102:105], v[2:3], off offset:32
	global_load_dwordx4 v[106:109], v[2:3], off offset:64
	global_load_dwordx4 v[110:113], v[2:3], off offset:96
	global_load_dwordx4 v[114:117], v[2:3], off offset:128
	global_load_dwordx4 v[118:121], v[2:3], off offset:160
	global_load_dwordx4 v[122:125], v[2:3], off offset:192
	global_load_dwordx4 v[126:129], v[2:3], off offset:224
	v_sub_u32_e32 v2, 0, v4
	v_max_i32_e32 v12, 0xffffff80, v2
	v_xad_u32 v2, v4, -1, s4
	v_min_i32_e32 v19, 0x80, v2
	v_and_b32_e32 v2, 0x78, v44
	v_sub_u32_e32 v16, v171, v4
	v_lshlrev_b32_e32 v10, 1, v2
	v_lshlrev_b32_e32 v2, 3, v165
	v_and_b32_e32 v3, 0xc0, v166
	v_lshlrev_b32_e32 v4, 1, v15
	v_and_or_b32 v3, v2, 24, v3
	v_and_b32_e32 v4, 32, v4
	v_and_b32_e32 v2, 0x100, v2
	v_or3_b32 v14, v3, v4, v2
	v_max_i32_e32 v2, 0, v13
	v_min_u32_e32 v2, s26, v2
	v_lshl_add_u64 v[162:163], s[42:43], 0, v[10:11]
	v_add_u32_e32 v2, s9, v2
	v_max_i32_e32 v11, -16, v13
	v_mad_i64_i32 v[6:7], s[4:5], v2, s89, v[162:163]
	s_lshl_b32 s72, s28, 1
	v_add_u32_e32 v11, 16, v11
	v_lshl_add_u64 v[2:3], v[6:7], 0, s[72:73]
	v_min_u32_e32 v11, s26, v11
	global_load_dwordx4 v[2:5], v[2:3], off
	v_add_u32_e32 v11, s9, v11
	v_mad_i64_i32 v[24:25], s[36:37], v11, s89, v[162:163]
	v_max_i32_e32 v11, 0xffffffe0, v13
	v_add_u32_e32 v11, 32, v11
	v_min_u32_e32 v11, s26, v11
	s_lshl_b32 s4, s27, 1
	s_mov_b32 s5, s73
	v_add_u32_e32 v11, s9, v11
	v_lshl_add_u64 v[6:7], v[6:7], 0, s[4:5]
	v_mad_i64_i32 v[32:33], s[36:37], v11, s89, v[162:163]
	v_max_i32_e32 v11, 0xffffffd0, v13
	global_load_dwordx4 v[6:9], v[6:7], off
	v_lshl_add_u64 v[20:21], v[24:25], 0, s[72:73]
	v_add_u32_e32 v11, 48, v11
	global_load_dwordx4 v[20:23], v[20:21], off
	v_lshl_add_u64 v[24:25], v[24:25], 0, s[4:5]
	v_min_u32_e32 v11, s26, v11
	global_load_dwordx4 v[24:27], v[24:25], off
	v_lshl_add_u64 v[28:29], v[32:33], 0, s[72:73]
	v_add_u32_e32 v11, s9, v11
	global_load_dwordx4 v[28:31], v[28:29], off
	v_lshl_add_u64 v[32:33], v[32:33], 0, s[4:5]
	v_mad_i64_i32 v[40:41], s[36:37], v11, s89, v[162:163]
	global_load_dwordx4 v[32:35], v[32:33], off
	v_lshl_add_u64 v[36:37], v[40:41], 0, s[72:73]
	global_load_dwordx4 v[36:39], v[36:37], off
	v_lshl_add_u64 v[40:41], v[40:41], 0, s[4:5]
	global_load_dwordx4 v[40:43], v[40:41], off
	v_bfe_u32 v11, v44, 5, 2
	v_lshrrev_b32_e32 v44, 5, v15
	v_and_or_b32 v44, v44, 4, v45
	v_and_or_b32 v11, v18, 4, v11
	v_cvt_f32_i32_e32 v172, v19
	v_and_b32_e32 v19, 48, v10
	v_lshl_add_u32 v44, v44, 6, s30
	v_lshlrev_b32_e32 v11, 9, v11
	s_add_i32 s48, s48, s31
	s_movk_i32 s31, 0x70
	v_add3_u32 v174, v44, v19, v11
	s_waitcnt vmcnt(0)
; #define SBAR() __builtin_amdgcn_sched_barrier(0)
; #define RESC(a) do { if (__any((a) < 1.f)) { if (hi == 0) al_l[r32] = (a); asm volatile("s_waitcnt lgkmcnt(0)" ::: "memory"); \
;     _Pragma("unroll") for (int d = 0; d < 4; ++d) _Pragma("unroll") for (int r = 0; r < 16; ++r) o[d][r] *= al_l[crow(r, hi)]; } } while (0)
; #define WACT(n) (WUKB(n) + 63 >= uqw - WIN && WUKB(n) <= uqw + 31 + WIN)
; #define WSLOAD(n) do { _Pragma("unroll") for (int i_ = 0; i_ < 4; ++i_) { int u_ = WUKB(n) + sr4 + 16 * i_; u_ = min(max(u_, 0), I.SU - 1); \
;       const bf16_t* rp_ = I.qkv + (size_t)(I.seq_base + clsw + I.dil * u_) * I.W + sc4; stv[i_] = LDG(bf16x8, rp_ + I.vcol); stk[i_] = LDG(bf16x8, rp_ + I.kcol); } } while (0)
; #define WSWRITE(b) do { _Pragma("unroll") for (int i_ = 0; i_ < 4; ++i_) { *(LAS bf16x8*)(Vh + (b) * SHM_V + v_st(sr4 + 16 * i_, sc4)) = stv[i_]; \
;       *(LAS bf16x8*)(Kh + (b) * SHM_K + KSWZ(sr4 + 16 * i_, sc4 * 2)) = stk[i_]; } } while (0)
; template <int WIN, bool ALIBI, int EPI, bool SINK>
; __device__ __forceinline__ void attn_item(const Item& I, char* lds, int tid_in) {
;     ...
;   WSLOAD(0); asm volatile("s_waitcnt vmcnt(0)" ::: "memory"); WSWRITE(0); if (1 < NTw) WSLOAD(1); __syncthreads();
;   for (int n = 0; n < NTw; ++n) { const int bsel = n & 1;
;     if (WACT(n)) { qkt(pA0, pA1, Kh + bsel * SHM_K, qr, r32, hi);
;       partialSM<WIN, ALIBI>(pA0, pA1, m_reg, mnA, alA, dq + (float)WUKB(n), I.nslope, lo, hi_, true); RESC(alA);
;       finishSM(pA0, pA1, alA, l_reg, pa0, pa1, pa2, pa3); SBAR(); pv_d0(o, vbh + bsel * SHM_V, pa0, pa1, pa2, pa3); }
;     if (n + 1 < NTw) { asm volatile("s_waitcnt vmcnt(0)" ::: "memory"); WSWRITE(bsel ^ 1); if (n + 2 < NTw) WSLOAD(n + 2); }
;     __syncthreads();
	v_bitop3_b32 v10, v10, v15, s31 bitop3:0x78
	v_cvt_f32_i32_e32 v176, v16
	v_cvt_f32_i32_e32 v178, v12
	v_add_u32_e32 v179, s30, v14
	v_mov_b32_e32 v14, v1
	v_mov_b32_e32 v15, v1
	v_bitop3_b32 v181, v0, v166, s31 bitop3:0x78
	v_add_u32_e32 v173, s29, v0
	v_mov_b32_e32 v11, v1
	v_mov_b32_e32 v12, v1
	s_add_i32 s49, s48, 0xffffff80
	s_add_i32 s50, s48, 0x9f
	ds_write_b128 v174, v[2:5]
	v_lshlrev_b32_e32 v2, 8, v17
	v_add3_u32 v175, s30, v10, v2
	v_or_b32_e32 v2, 64, v13
	v_max_i32_e32 v2, 0, v2
	v_min_u32_e32 v2, s26, v2
	v_add_u32_e32 v2, s9, v2
	v_mad_i64_i32 v[2:3], s[36:37], v2, s89, v[162:163]
	ds_write_b128 v175, v[6:9] offset:32768
	ds_write_b128 v174, v[20:23] offset:4096
	ds_write_b128 v175, v[24:27] offset:36864
	ds_write_b128 v174, v[28:31] offset:8192
	ds_write_b128 v175, v[32:35] offset:40960
	ds_write_b128 v174, v[36:39] offset:12288
	ds_write_b128 v175, v[40:43] offset:45056
	v_lshl_add_u64 v[4:5], v[2:3], 0, s[72:73]
	v_lshl_add_u64 v[2:3], v[2:3], 0, s[4:5]
	global_load_dwordx4 v[130:133], v[4:5], off
	global_load_dwordx4 v[134:137], v[2:3], off
	v_or_b32_e32 v2, 0x50, v13
	v_max_i32_e32 v2, 0, v2
	v_min_u32_e32 v2, s26, v2
	v_add_u32_e32 v2, s9, v2
	v_mad_i64_i32 v[2:3], s[36:37], v2, s89, v[162:163]
	v_lshl_add_u64 v[4:5], v[2:3], 0, s[72:73]
	v_lshl_add_u64 v[2:3], v[2:3], 0, s[4:5]
	global_load_dwordx4 v[138:141], v[4:5], off
	global_load_dwordx4 v[142:145], v[2:3], off
	v_or_b32_e32 v2, 0x60, v13
	v_max_i32_e32 v2, 0, v2
	v_min_u32_e32 v2, s26, v2
	v_add_u32_e32 v2, s9, v2
	v_mad_i64_i32 v[2:3], s[36:37], v2, s89, v[162:163]
	v_lshl_add_u64 v[4:5], v[2:3], 0, s[72:73]
	v_lshl_add_u64 v[2:3], v[2:3], 0, s[4:5]
	global_load_dwordx4 v[146:149], v[4:5], off
	global_load_dwordx4 v[150:153], v[2:3], off
	v_or_b32_e32 v2, 0x70, v13
	v_max_i32_e32 v2, 0, v2
	v_min_u32_e32 v2, s26, v2
	v_add_u32_e32 v2, s9, v2
	v_mad_i64_i32 v[2:3], s[36:37], v2, s89, v[162:163]
	v_lshl_add_u64 v[4:5], v[2:3], 0, s[72:73]
	v_lshl_add_u64 v[2:3], v[2:3], 0, s[4:5]
	global_load_dwordx4 v[154:157], v[4:5], off
	global_load_dwordx4 v[158:161], v[2:3], off
	v_and_b32_e32 v2, 0x70, v166
	s_movk_i32 s4, 0xe0
	v_bitop3_b32 v182, v0, v2, 32 bitop3:0x36
	v_bitop3_b32 v183, v0, v2, 64 bitop3:0x36
	v_bitop3_b32 v184, v0, v2, s93 bitop3:0x36
	v_bitop3_b32 v185, v0, v2, s85 bitop3:0x36
	v_bitop3_b32 v186, v0, v2, s67 bitop3:0x36
	v_bitop3_b32 v187, v0, v2, s83 bitop3:0x36
	v_bitop3_b32 v188, v0, v2, s4 bitop3:0x36
	v_mov_b32_e32 v0, v1
	v_mov_b32_e32 v2, v1
	v_mov_b32_e32 v3, v1
	v_mov_b32_e32 v4, v1
	v_mov_b32_e32 v5, v1
	v_mov_b32_e32 v6, v1
	v_mov_b32_e32 v7, v1
	v_mov_b32_e32 v8, v1
	v_mov_b32_e32 v9, v1
	v_mov_b32_e32 v10, v1
	v_mov_b32_e32 v13, v1
	v_mov_b64_e32 v[64:65], v[14:15]
	v_mov_b64_e32 v[48:49], v[14:15]
	v_mov_b64_e32 v[32:33], v[14:15]
	v_mov_b64_e32 v[62:63], v[12:13]
	v_mov_b64_e32 v[60:61], v[10:11]
	v_mov_b64_e32 v[58:59], v[8:9]
	v_mov_b64_e32 v[56:57], v[6:7]
	v_mov_b64_e32 v[54:55], v[4:5]
	v_mov_b64_e32 v[52:53], v[2:3]
	v_mov_b64_e32 v[50:51], v[0:1]
	v_mov_b64_e32 v[46:47], v[12:13]
	v_mov_b64_e32 v[44:45], v[10:11]
	v_mov_b64_e32 v[42:43], v[8:9]
	v_mov_b64_e32 v[40:41], v[6:7]
	v_mov_b64_e32 v[38:39], v[4:5]
	v_mov_b64_e32 v[36:37], v[2:3]
	v_mov_b64_e32 v[34:35], v[0:1]
	v_mov_b64_e32 v[30:31], v[12:13]
	v_mov_b64_e32 v[28:29], v[10:11]
	v_mov_b64_e32 v[26:27], v[8:9]
	v_mov_b64_e32 v[24:25], v[6:7]
	v_mov_b64_e32 v[22:23], v[4:5]
	v_mov_b64_e32 v[20:21], v[2:3]
	v_mov_b64_e32 v[18:19], v[0:1]
	v_mov_b64_e32 v[16:17], v[14:15]
	v_cmp_gt_u32_e64 s[36:37], 32, v165
	s_lshl_b32 s72, s28, 1
	v_mov_b64_e32 v[14:15], v[12:13]
	v_mov_b64_e32 v[12:13], v[10:11]
	v_mov_b64_e32 v[10:11], v[8:9]
	v_mov_b64_e32 v[8:9], v[6:7]
	v_mov_b64_e32 v[6:7], v[4:5]
	v_mov_b64_e32 v[4:5], v[2:3]
	v_mov_b64_e32 v[2:3], v[0:1]
	s_waitcnt lgkmcnt(0)
	s_barrier
	s_branch .LBB0_939

; #define WSLOAD(n) do { _Pragma("unroll") for (int i_ = 0; i_ < 4; ++i_) { int u_ = WUKB(n) + sr4 + 16 * i_; u_ = min(max(u_, 0), I.SU - 1); \
;       const bf16_t* rp_ = I.qkv + (size_t)(I.seq_base + clsw + I.dil * u_) * I.W + sc4; stv[i_] = LDG(bf16x8, rp_ + I.vcol); stk[i_] = LDG(bf16x8, rp_ + I.kcol); } } while (0)
; #define WSWRITE(b) do { _Pragma("unroll") for (int i_ = 0; i_ < 4; ++i_) { *(LAS bf16x8*)(Vh + (b) * SHM_V + v_st(sr4 + 16 * i_, sc4)) = stv[i_]; \
;       *(LAS bf16x8*)(Kh + (b) * SHM_K + KSWZ(sr4 + 16 * i_, sc4 * 2)) = stk[i_]; } } while (0)
; template <int WIN, bool ALIBI, int EPI, bool SINK>
; __device__ __forceinline__ void attn_item(const Item& I, char* lds, int tid_in) {
;     ...
;     if (n + 1 < NTw) { asm volatile("s_waitcnt vmcnt(0)" ::: "memory"); WSWRITE(bsel ^ 1); if (n + 2 < NTw) WSLOAD(n + 2); }
.LBB0_945:
	s_cmp_gt_u32 s51, 4
	s_cbranch_scc1 .LBB0_938
	s_waitcnt vmcnt(0)
	s_lshl_b32 s4, s27, 14
	s_xor_b32 s4, s4, 0x4000
	v_add_u32_e32 v0, s4, v174
	v_add_u32_e32 v66, s4, v175
	s_cmpk_eq_i32 s13, 0x100
	ds_write_b128 v0, v[130:133]
	ds_write_b128 v66, v[134:137] offset:32768
	ds_write_b128 v0, v[138:141] offset:4096
	ds_write_b128 v66, v[142:145] offset:36864
	ds_write_b128 v0, v[146:149] offset:8192
	ds_write_b128 v66, v[150:153] offset:40960
	ds_write_b128 v0, v[154:157] offset:12288
	ds_write_b128 v66, v[158:161] offset:45056
	s_cbranch_scc1 .LBB0_938
	v_add_u32_e32 v0, s13, v189
	v_max_i32_e32 v66, 0, v0
	v_min_i32_e32 v66, s26, v66
	v_add_u32_e32 v66, s9, v66
	v_mad_i64_i32 v[66:67], s[4:5], v66, s89, v[162:163]
	s_mov_b32 s47, s73
	v_lshl_add_u64 v[68:69], v[66:67], 0, s[72:73]
	v_lshl_add_u64 v[66:67], v[66:67], 0, s[46:47]
	global_load_dwordx4 v[130:133], v[68:69], off
	global_load_dwordx4 v[134:137], v[66:67], off
	v_max_i32_e32 v66, -16, v0
	v_add_u32_e32 v66, 16, v66
	v_min_i32_e32 v66, s26, v66
	v_add_u32_e32 v66, s9, v66
	v_mad_i64_i32 v[66:67], s[4:5], v66, s89, v[162:163]
	v_lshl_add_u64 v[68:69], v[66:67], 0, s[72:73]
	v_lshl_add_u64 v[66:67], v[66:67], 0, s[46:47]
	global_load_dwordx4 v[138:141], v[68:69], off
	global_load_dwordx4 v[142:145], v[66:67], off
	v_max_i32_e32 v66, 0xffffffe0, v0
	v_add_u32_e32 v66, 32, v66
	v_min_i32_e32 v66, s26, v66
	v_max_i32_e32 v0, 0xffffffd0, v0
	v_add_u32_e32 v66, s9, v66
	v_add_u32_e32 v0, 48, v0
	v_mad_i64_i32 v[66:67], s[4:5], v66, s89, v[162:163]
	v_min_i32_e32 v0, s26, v0
	v_lshl_add_u64 v[68:69], v[66:67], 0, s[72:73]
	v_lshl_add_u64 v[66:67], v[66:67], 0, s[46:47]
	v_add_u32_e32 v0, s9, v0
	global_load_dwordx4 v[146:149], v[68:69], off
	global_load_dwordx4 v[150:153], v[66:67], off
	v_mad_i64_i32 v[66:67], s[4:5], v0, s89, v[162:163]
	v_lshl_add_u64 v[68:69], v[66:67], 0, s[72:73]
	v_lshl_add_u64 v[66:67], v[66:67], 0, s[46:47]
	global_load_dwordx4 v[154:157], v[68:69], off
	global_load_dwordx4 v[158:161], v[66:67], off
	s_branch .LBB0_938

; __device__ __forceinline__ unsigned xb_ld(unsigned* p)              { return __hip_atomic_load(p, __ATOMIC_RELAXED, __HIP_MEMORY_SCOPE_AGENT); }
; __device__ __forceinline__ unsigned xb_add(unsigned* p, unsigned v) { return __hip_atomic_fetch_add(p, v, __ATOMIC_RELAXED, __HIP_MEMORY_SCOPE_AGENT); }
; #define XB_SPIN(cond, bar) do { unsigned _sp = 0; while (cond) { __builtin_amdgcn_s_sleep(1); \
;     if ((++_sp & 255u) == 0u) { if (xb_ld(&(bar)[XB_TMO])) break; if (_sp > XB_SPIN_CAP) { atomicAdd(&(bar)[XB_TMO], 1u); break; } } } } while (0)
; __device__ __forceinline__ void xcd_barrier(const XcdBarrier& b) {
;     ...
;         const unsigned old = xb_add(&bar[XB_XSUB(b.x)], 1u);
;         const unsigned gen = old / nloc;
;         if (old + 1u == (gen + 1u) * nloc) {
;             __builtin_amdgcn_fence(__ATOMIC_RELEASE, "agent");
;             asm volatile("s_waitcnt vmcnt(0)" ::: "memory");
;             const unsigned og = xb_add(&bar[XB_TOP], 1u);
;             const unsigned tg = og / nx;
;             if (og + 1u == (tg + 1u) * nx) xb_add(&bar[XB_TOPGEN], 1u);
;             else XB_SPIN(xb_ld(&bar[XB_TOPGEN]) == tg, bar);
;             __builtin_amdgcn_fence(__ATOMIC_ACQUIRE, "agent");
;             xb_add(&bar[XB_XGEN(b.x)], 1u);
;             asm volatile("s_waitcnt vmcnt(0)" ::: "memory");
;         } else {
;             XB_SPIN(xb_ld(&bar[XB_XGEN(b.x)]) == gen, bar);
;             __builtin_amdgcn_fence(__ATOMIC_ACQUIRE, "agent");
;             asm volatile("s_waitcnt vmcnt(0)" ::: "memory");
;         }
.LBB0_982:
	s_or_b64 exec, exec, s[6:7]
	s_waitcnt vmcnt(0)
	buffer_inv sc1
.LBB0_983:
	s_andn2_saveexec_b64 s[4:5], s[4:5]
	s_cbranch_execz .LBB0_1003
	s_mov_b64 s[4:5], exec
	buffer_wbl2 sc1
	s_waitcnt lgkmcnt(0)
	s_waitcnt vmcnt(0)
	v_mbcnt_lo_u32_b32 v0, s4, 0
	v_mbcnt_hi_u32_b32 v0, s5, v0
	v_cmp_eq_u32_e32 vcc, 0, v0
	s_and_saveexec_b64 s[6:7], vcc
	s_cbranch_execz .LBB0_986
	s_bcnt1_i32_b64 s4, s[4:5]
	v_mov_b32_e32 v3, s4
	v_readlane_b32 s4, v255, 17
	v_readlane_b32 s5, v255, 18
	s_nop 4
	global_atomic_add v3, v1, v3, s[4:5] sc0

; __device__ __forceinline__ unsigned xb_ld(unsigned* p)              { return __hip_atomic_load(p, __ATOMIC_RELAXED, __HIP_MEMORY_SCOPE_AGENT); }
; __device__ __forceinline__ unsigned xb_add(unsigned* p, unsigned v) { return __hip_atomic_fetch_add(p, v, __ATOMIC_RELAXED, __HIP_MEMORY_SCOPE_AGENT); }
; #define XB_SPIN(cond, bar) do { unsigned _sp = 0; while (cond) { __builtin_amdgcn_s_sleep(1); \
;     if ((++_sp & 255u) == 0u) { if (xb_ld(&(bar)[XB_TMO])) break; if (_sp > XB_SPIN_CAP) { atomicAdd(&(bar)[XB_TMO], 1u); break; } } } } while (0)
; __device__ __forceinline__ void xcd_barrier(const XcdBarrier& b) {
;     ...
;         const unsigned old = xb_add(&bar[XB_XSUB(b.x)], 1u);
;         const unsigned gen = old / nloc;
;         if (old + 1u == (gen + 1u) * nloc) {
;             __builtin_amdgcn_fence(__ATOMIC_RELEASE, "agent");
;             asm volatile("s_waitcnt vmcnt(0)" ::: "memory");
;             const unsigned og = xb_add(&bar[XB_TOP], 1u);
;             const unsigned tg = og / nx;
;             if (og + 1u == (tg + 1u) * nx) xb_add(&bar[XB_TOPGEN], 1u);
;             else XB_SPIN(xb_ld(&bar[XB_TOPGEN]) == tg, bar);
;             __builtin_amdgcn_fence(__ATOMIC_ACQUIRE, "agent");
;             xb_add(&bar[XB_XGEN(b.x)], 1u);
;             asm volatile("s_waitcnt vmcnt(0)" ::: "memory");
;         } else {
;             XB_SPIN(xb_ld(&bar[XB_XGEN(b.x)]) == gen, bar);
;             __builtin_amdgcn_fence(__ATOMIC_ACQUIRE, "agent");
;             asm volatile("s_waitcnt vmcnt(0)" ::: "memory");
;         }
.LBB0_1076:
	s_or_b64 exec, exec, s[6:7]
	s_waitcnt vmcnt(0)
	buffer_inv sc1
.LBB0_1077:
	s_andn2_saveexec_b64 s[4:5], s[4:5]
	s_cbranch_execz .LBB0_1097
	s_mov_b64 s[4:5], exec
	buffer_wbl2 sc1
	s_waitcnt lgkmcnt(0)
	s_waitcnt vmcnt(0)
	v_mbcnt_lo_u32_b32 v0, s4, 0
	v_mbcnt_hi_u32_b32 v0, s5, v0
	v_cmp_eq_u32_e32 vcc, 0, v0
	s_and_saveexec_b64 s[6:7], vcc
	s_cbranch_execz .LBB0_1080
	s_bcnt1_i32_b64 s4, s[4:5]
	v_mov_b32_e32 v3, s4
	v_readlane_b32 s4, v255, 17
	v_readlane_b32 s5, v255, 18
	s_nop 4
	global_atomic_add v3, v1, v3, s[4:5] sc0

; #define LAS __attribute__((address_space(3)))
; template <int WIN, bool ALIBI, int EPI, bool SINK>
; __device__ __forceinline__ void attn_item(const Item& I, char* lds, int tid_in) {
;     ...
;       const float wa = __builtin_amdgcn_exp2f(lold - mx), wb = __builtin_amdgcn_exp2f(lcur - mx), den = wa + wb; STG(float, lp) = mx + __log2f(den);
;       al_l[r32] = wa / den; li_l[r32] = wb / (den * l_reg); } }
;   asm volatile("s_waitcnt lgkmcnt(0)" ::: "memory");
;   const int tokw = I.seq_base + I.c0 + wcls + I.dil * (I.u0 + (two ? (wid & 3) * 32 : wid * 32));
;   bf16_t* Ow = I.O + (size_t)tokw * DM + I.ocol + r32;
;   LAS unsigned* park = (LAS unsigned*)(V_lds + 2 * SHM_V + 2 * SHM_K + 2048) + tid * 32;
;   if constexpr (EPI == 4) {
; #pragma unroll
;     for (int r = 0; r < 16; r += 2) { const float f0 = li_l[crow(r, hi)], f1 = li_l[crow(r + 1, hi)];
; #pragma unroll
;       for (int d0 = 0; d0 < 4; ++d0) park[(r >> 1) * 4 + d0] = cvt_pk_bf16(o[d0][r] * f0, o[d0][r + 1] * f1); }
;   } else if constexpr (EPI == 3) {
;     unsigned oldv[16][4];
; #pragma unroll
;     for (int r = 0; r < 16; ++r) { const bf16_t* Or = Ow + (size_t)(I.dil * crow(r, hi)) * DM;
; #pragma unroll
;       for (int d0 = 0; d0 < 4; ++d0) oldv[r][d0] = (unsigned)LDG(bf16_t, Or + d0 * 32); }
;     asm volatile("" ::: "memory");
; #pragma unroll
;     for (int r = 0; r < 16; ++r) { const int orow = crow(r, hi); const float f = li_l[orow];
;       bf16_t* Or = Ow + (size_t)(I.dil * orow) * DM;
; #pragma unroll
;       for (int d0 = 0; d0 < 4; ++d0) { const float v = __uint_as_float(oldv[r][d0] << 16) + o[d0][r] * f;
;         STG(bf16_t, Or + d0 * 32) = (bf16_t)(cvt_pk_bf16(v, v) & 0xffffu); } }
;   } else {
;     const int rsub = lane >> 4, ch = lane & 15;
;     bf16_t* Orow = I.O + (size_t)tokw * DM + I.ocol + ch * 8;
;     u32x4 oldv[(EPI == 2) ? 8 : 1];
;     if constexpr (EPI == 2) {
; #pragma unroll
;       for (int j = 0; j < 8; ++j) oldv[j] = LDG(u32x4, Orow + (size_t)(I.dil * (4 * j + rsub)) * DM); }
;     __syncthreads();
;     constexpr int RB = (EPI == 2) ? 512 : 256;
;     LAS char* Sw = V_lds + wid * (32 * RB);
;     if constexpr (EPI == 5) {
; #pragma unroll
;       for (int r = 0; r < 16; r += 2) { const int or0 = crow(r, hi), or1 = crow(r + 1, hi); const float f0 = li_l[or0], f1 = li_l[or1];
; #pragma unroll
.LBB0_1104:
	s_or_b64 exec, exec, s[4:5]
	s_add_i32 s4, s13, s12
	s_ashr_i32 s5, s4, 31
	s_lshl_b64 s[4:5], s[4:5], 12
	s_add_u32 s4, s44, s4
	s_waitcnt lgkmcnt(0)
	s_addc_u32 s5, s45, s5
	s_lshl_b32 s12, s24, 1
	s_barrier
	ds_read_b32 v66, v0
	s_add_u32 s4, s4, s12
	s_addc_u32 s5, s5, 0
	s_lshl_b32 s9, s9, 13
	s_add_i32 s9, s9, 0
	v_lshl_add_u32 v67, v182, 1, s9
	v_lshl_add_u32 v68, v183, 10, v67
	s_waitcnt lgkmcnt(0)
	v_mul_f32_e32 v50, v50, v66
	v_mul_f32_e32 v34, v34, v66
	v_mul_f32_e32 v18, v18, v66
	v_cvt_pk_bf16_f32 v50, v50, v50
	ds_write_b16 v68, v50
	v_cvt_pk_bf16_f32 v34, v34, v34
	ds_write_b16 v68, v34 offset:64
	v_cvt_pk_bf16_f32 v18, v18, v18
	v_mul_f32_e32 v2, v2, v66
	ds_write_b16 v68, v18 offset:128
	v_cvt_pk_bf16_f32 v2, v2, v2
	ds_read_b32 v18, v0 offset:4
	ds_write_b16 v68, v2 offset:192
	v_lshl_add_u32 v34, v186, 8, v67
	s_add_i32 s8, s8, 1
	s_waitcnt lgkmcnt(1)
	v_mul_f32_e32 v2, v51, v18
	v_cvt_pk_bf16_f32 v2, v2, v2
	ds_write_b16 v34, v2 offset:256
	v_mul_f32_e32 v2, v35, v18
	v_cvt_pk_bf16_f32 v2, v2, v2
	ds_write_b16 v34, v2 offset:320
	v_mul_f32_e32 v2, v19, v18
	v_cvt_pk_bf16_f32 v2, v2, v2
	ds_write_b16 v34, v2 offset:384
	v_mul_f32_e32 v2, v3, v18
	v_cvt_pk_bf16_f32 v2, v2, v2
	ds_read_b32 v3, v0 offset:8
	ds_write_b16 v34, v2 offset:448
	s_waitcnt lgkmcnt(1)
	v_mul_f32_e32 v2, v52, v3
	v_cvt_pk_bf16_f32 v2, v2, v2
	ds_write_b16 v34, v2 offset:512
	v_mul_f32_e32 v2, v36, v3
	v_cvt_pk_bf16_f32 v2, v2, v2
	ds_write_b16 v34, v2 offset:576
	v_mul_f32_e32 v2, v20, v3
	v_cvt_pk_bf16_f32 v2, v2, v2
	ds_write_b16 v34, v2 offset:640
	v_mul_f32_e32 v2, v4, v3
	v_cvt_pk_bf16_f32 v2, v2, v2
	ds_read_b32 v3, v0 offset:12
	ds_write_b16 v34, v2 offset:704
	s_waitcnt lgkmcnt(1)
	v_mul_f32_e32 v2, v53, v3
	v_cvt_pk_bf16_f32 v2, v2, v2
	ds_write_b16 v34, v2 offset:768
	v_mul_f32_e32 v2, v37, v3
	v_cvt_pk_bf16_f32 v2, v2, v2
	ds_write_b16 v34, v2 offset:832
	v_mul_f32_e32 v2, v21, v3
	v_cvt_pk_bf16_f32 v2, v2, v2
	ds_write_b16 v34, v2 offset:896
	v_mul_f32_e32 v2, v5, v3
	v_cvt_pk_bf16_f32 v2, v2, v2
	ds_read_b32 v3, v0 offset:32
	ds_write_b16 v34, v2 offset:960
	s_waitcnt lgkmcnt(1)
	v_mul_f32_e32 v2, v54, v3
	v_cvt_pk_bf16_f32 v2, v2, v2
	ds_write_b16 v34, v2 offset:2048
	v_mul_f32_e32 v2, v38, v3
	v_cvt_pk_bf16_f32 v2, v2, v2
	ds_write_b16 v34, v2 offset:2112
	v_mul_f32_e32 v2, v22, v3
	v_cvt_pk_bf16_f32 v2, v2, v2
	ds_write_b16 v34, v2 offset:2176
	v_mul_f32_e32 v2, v6, v3
	v_cvt_pk_bf16_f32 v2, v2, v2
	ds_read_b32 v3, v0 offset:36
	ds_write_b16 v34, v2 offset:2240
	s_waitcnt lgkmcnt(1)
	v_mul_f32_e32 v2, v55, v3
	v_cvt_pk_bf16_f32 v2, v2, v2
	ds_write_b16 v34, v2 offset:2304
	v_mul_f32_e32 v2, v39, v3
	v_cvt_pk_bf16_f32 v2, v2, v2
	ds_write_b16 v34, v2 offset:2368
	v_mul_f32_e32 v2, v23, v3
	v_cvt_pk_bf16_f32 v2, v2, v2
	ds_write_b16 v34, v2 offset:2432
	v_mul_f32_e32 v2, v7, v3
	v_cvt_pk_bf16_f32 v2, v2, v2
	ds_read_b32 v3, v0 offset:40
	ds_write_b16 v34, v2 offset:2496
	s_waitcnt lgkmcnt(1)
	v_mul_f32_e32 v2, v56, v3
	v_cvt_pk_bf16_f32 v2, v2, v2
	ds_write_b16 v34, v2 offset:2560
	v_mul_f32_e32 v2, v40, v3
	v_cvt_pk_bf16_f32 v2, v2, v2
	ds_write_b16 v34, v2 offset:2624
	v_mul_f32_e32 v2, v24, v3
	v_cvt_pk_bf16_f32 v2, v2, v2
	ds_write_b16 v34, v2 offset:2688
	v_mul_f32_e32 v2, v8, v3
	v_cvt_pk_bf16_f32 v2, v2, v2
	ds_read_b32 v3, v0 offset:44
	ds_write_b16 v34, v2 offset:2752
	s_waitcnt lgkmcnt(1)
	v_mul_f32_e32 v2, v57, v3
	v_cvt_pk_bf16_f32 v2, v2, v2
	ds_write_b16 v34, v2 offset:2816
	v_mul_f32_e32 v2, v41, v3
	v_cvt_pk_bf16_f32 v2, v2, v2
	ds_write_b16 v34, v2 offset:2880
	v_mul_f32_e32 v2, v25, v3
	v_cvt_pk_bf16_f32 v2, v2, v2
	ds_write_b16 v34, v2 offset:2944
	v_mul_f32_e32 v2, v9, v3
	v_cvt_pk_bf16_f32 v2, v2, v2
	ds_read_b32 v3, v0 offset:64
	ds_write_b16 v34, v2 offset:3008
	s_waitcnt lgkmcnt(1)
	v_mul_f32_e32 v2, v58, v3
	v_cvt_pk_bf16_f32 v2, v2, v2
	ds_write_b16 v34, v2 offset:4096
	v_mul_f32_e32 v2, v42, v3
	v_cvt_pk_bf16_f32 v2, v2, v2
	ds_write_b16 v34, v2 offset:4160
	v_mul_f32_e32 v2, v26, v3
	v_cvt_pk_bf16_f32 v2, v2, v2
	ds_write_b16 v34, v2 offset:4224
	v_mul_f32_e32 v2, v10, v3
	v_cvt_pk_bf16_f32 v2, v2, v2
	ds_read_b32 v3, v0 offset:68
	ds_write_b16 v34, v2 offset:4288
	s_waitcnt lgkmcnt(1)
	v_mul_f32_e32 v2, v59, v3
	v_cvt_pk_bf16_f32 v2, v2, v2
	ds_write_b16 v34, v2 offset:4352
	v_mul_f32_e32 v2, v43, v3
	v_cvt_pk_bf16_f32 v2, v2, v2
	ds_write_b16 v34, v2 offset:4416
	v_mul_f32_e32 v2, v27, v3
	v_cvt_pk_bf16_f32 v2, v2, v2
	ds_write_b16 v34, v2 offset:4480
	v_mul_f32_e32 v2, v11, v3
	v_cvt_pk_bf16_f32 v2, v2, v2
	ds_read_b32 v3, v0 offset:72
	ds_write_b16 v34, v2 offset:4544
	s_waitcnt lgkmcnt(1)
; #define LAS __attribute__((address_space(3)))
; __device__ __forceinline__ unsigned cvt_pk_bf16(float lo, float hi) { unsigned r; asm volatile("v_cvt_pk_bf16_f32 %0, %1, %2" : "=v"(r) : "v"(lo), "v"(hi)); return r; }
; __device__ __forceinline__ float bf_lo(unsigned w) { return __uint_as_float(w << 16); }
; __device__ __forceinline__ float bf_hi(unsigned w) { return __uint_as_float(w & 0xffff0000u); }
; __device__ __forceinline__ int crow(int r, int hi) { return (r & 3) + 8 * (r >> 2) + 4 * hi; }
; template <int WIN, bool ALIBI, int EPI, bool SINK>
; __device__ __forceinline__ void attn_item(const Item& I, char* lds, int tid_in) {
;     ...
; #pragma unroll
;       for (int r = 0; r < 16; ++r) { const int orow = crow(r, hi); const float f = li_l[orow];
; #pragma unroll
;         for (int d0 = 0; d0 < 4; ++d0) { const float v = o[d0][r] * f;
;           if constexpr (EPI == 2) *(LAS float*)(Sw + orow * RB + (d0 * 32 + r32) * 4) = v;
;           else *(LAS bf16_t*)(Sw + orow * RB + (d0 * 32 + r32) * 2) = (bf16_t)(cvt_pk_bf16(v, v) & 0xffffu); } }
;     }
;     asm volatile("s_waitcnt lgkmcnt(0)" ::: "memory");
;     if constexpr (EPI == 2) {
; #pragma unroll
;       for (int j = 0; j < 8; ++j) { const int row = 4 * j + rsub; const float fo = al_l[row];
;         const f32x4 a0 = *(const LAS f32x4*)(Sw + row * RB + ch * 32), a1 = *(const LAS f32x4*)(Sw + row * RB + ch * 32 + 16); const u32x4 ov = oldv[j];
;         u32x4 w; w.x = cvt_pk_bf16(fo * bf_lo(ov.x) + a0[0], fo * bf_hi(ov.x) + a0[1]); w.y = cvt_pk_bf16(fo * bf_lo(ov.y) + a0[2], fo * bf_hi(ov.y) + a0[3]);
;         w.z = cvt_pk_bf16(fo * bf_lo(ov.z) + a1[0], fo * bf_hi(ov.z) + a1[1]); w.w = cvt_pk_bf16(fo * bf_lo(ov.w) + a1[2], fo * bf_hi(ov.w) + a1[3]);
;         STG(u32x4, Orow + (size_t)(I.dil * row) * DM) = w; }
;     } else {
; #pragma unroll
;       for (int j = 0; j < 8; ++j) { const int row = 4 * j + rsub; const u32x4 w = *(const LAS u32x4*)(Sw + row * RB + ch * 16);
;         STG(u32x4, Orow + (size_t)(I.dil * row) * DM) = w; }
;     }
;   }
;   __syncthreads();
; template <int MODE> __device__ __forceinline__ void phase_attn_fast(const Frame& F0) {
;     ...
;   for (int i = 0;; ++i) {
;     const int it = i * F.G + F.vcu; if (it >= 2560) break;
;     const ItemId d = item_decode(it);
	v_mul_f32_e32 v2, v60, v3
	v_cvt_pk_bf16_f32 v2, v2, v2
	ds_write_b16 v34, v2 offset:4608
	v_mul_f32_e32 v2, v44, v3
	v_cvt_pk_bf16_f32 v2, v2, v2
	ds_write_b16 v34, v2 offset:4672
	v_mul_f32_e32 v2, v28, v3
	v_cvt_pk_bf16_f32 v2, v2, v2
	ds_write_b16 v34, v2 offset:4736
	v_mul_f32_e32 v2, v12, v3
	v_cvt_pk_bf16_f32 v2, v2, v2
	ds_read_b32 v3, v0 offset:76
	ds_write_b16 v34, v2 offset:4800
	s_waitcnt lgkmcnt(1)
	v_mul_f32_e32 v2, v61, v3
	v_cvt_pk_bf16_f32 v2, v2, v2
	ds_write_b16 v34, v2 offset:4864
	v_mul_f32_e32 v2, v45, v3
	v_cvt_pk_bf16_f32 v2, v2, v2
	ds_write_b16 v34, v2 offset:4928
	v_mul_f32_e32 v2, v29, v3
	v_cvt_pk_bf16_f32 v2, v2, v2
	ds_write_b16 v34, v2 offset:4992
	v_mul_f32_e32 v2, v13, v3
	v_cvt_pk_bf16_f32 v2, v2, v2
	ds_read_b32 v3, v0 offset:96
	ds_write_b16 v34, v2 offset:5056
	s_waitcnt lgkmcnt(1)
	v_mul_f32_e32 v2, v62, v3
	v_cvt_pk_bf16_f32 v2, v2, v2
	ds_write_b16 v34, v2 offset:6144
	v_mul_f32_e32 v2, v46, v3
	v_cvt_pk_bf16_f32 v2, v2, v2
	ds_write_b16 v34, v2 offset:6208
	v_mul_f32_e32 v2, v30, v3
	v_cvt_pk_bf16_f32 v2, v2, v2
	ds_write_b16 v34, v2 offset:6272
	v_mul_f32_e32 v2, v14, v3
	v_cvt_pk_bf16_f32 v2, v2, v2
	ds_read_b32 v3, v0 offset:100
	ds_write_b16 v34, v2 offset:6336
	v_lshrrev_b32_e32 v14, 4, v185
	s_waitcnt lgkmcnt(1)
	v_mul_f32_e32 v2, v63, v3
	v_cvt_pk_bf16_f32 v2, v2, v2
	ds_write_b16 v34, v2 offset:6400
	v_mul_f32_e32 v2, v47, v3
	v_cvt_pk_bf16_f32 v2, v2, v2
	ds_write_b16 v34, v2 offset:6464
	v_mul_f32_e32 v2, v31, v3
	v_cvt_pk_bf16_f32 v2, v2, v2
	ds_write_b16 v34, v2 offset:6528
	v_mul_f32_e32 v2, v15, v3
	v_cvt_pk_bf16_f32 v2, v2, v2
	ds_read_b32 v3, v0 offset:104
	ds_write_b16 v34, v2 offset:6592
	s_waitcnt lgkmcnt(1)
	v_mul_f32_e32 v2, v64, v3
	v_cvt_pk_bf16_f32 v2, v2, v2
	ds_write_b16 v34, v2 offset:6656
	v_mul_f32_e32 v2, v48, v3
	v_cvt_pk_bf16_f32 v2, v2, v2
	ds_write_b16 v34, v2 offset:6720
	v_mul_f32_e32 v2, v32, v3
	v_cvt_pk_bf16_f32 v2, v2, v2
	ds_write_b16 v34, v2 offset:6784
	v_mul_f32_e32 v2, v16, v3
	v_cvt_pk_bf16_f32 v2, v2, v2
	ds_read_b32 v0, v0 offset:108
	ds_write_b16 v34, v2 offset:6848
	v_or_b32_e32 v16, 4, v14
	s_waitcnt lgkmcnt(1)
	v_mul_f32_e32 v2, v65, v0
	v_cvt_pk_bf16_f32 v2, v2, v2
	ds_write_b16 v34, v2 offset:6912
	v_mul_f32_e32 v2, v49, v0
	v_cvt_pk_bf16_f32 v2, v2, v2
	ds_write_b16 v34, v2 offset:6976
	v_mul_f32_e32 v2, v33, v0
	v_mul_f32_e32 v0, v17, v0
	v_cvt_pk_bf16_f32 v2, v2, v2
	ds_write_b16 v34, v2 offset:7040
	v_cvt_pk_bf16_f32 v0, v0, v0
	ds_write_b16 v34, v0 offset:7104
	v_and_b32_e32 v0, 0xf0, v184
	v_add_u32_e32 v15, s9, v0
	v_lshl_add_u64 v[10:11], s[4:5], 0, v[0:1]
	s_waitcnt lgkmcnt(0)
	v_lshl_add_u32 v0, v14, 8, v15
	ds_read_b128 v[2:5], v0
	v_lshl_add_u32 v6, v16, 8, v15
	ds_read_b128 v[6:9], v6
	v_lshlrev_b32_e32 v0, 12, v14
	v_lshl_add_u64 v[12:13], v[10:11], 0, v[0:1]
	v_lshlrev_b32_e32 v0, 12, v16
	s_waitcnt lgkmcnt(1)
	global_store_dwordx4 v[12:13], v[2:5], off
	v_or_b32_e32 v16, 12, v14
	s_mul_i32 s4, s8, s6
	v_lshl_add_u64 v[2:3], v[10:11], 0, v[0:1]
	v_or_b32_e32 v0, 8, v14
	s_waitcnt lgkmcnt(0)
	global_store_dwordx4 v[2:3], v[6:9], off
	v_lshl_add_u32 v2, v0, 8, v15
	ds_read_b128 v[2:5], v2
	v_lshl_add_u32 v6, v16, 8, v15
	ds_read_b128 v[6:9], v6
	v_lshlrev_b32_e32 v0, 12, v0
	v_lshl_add_u64 v[12:13], v[10:11], 0, v[0:1]
	v_lshlrev_b32_e32 v0, 12, v16
	s_waitcnt lgkmcnt(1)
	global_store_dwordx4 v[12:13], v[2:5], off
	v_or_b32_e32 v16, 20, v14
	s_add_i32 s9, s4, s7
	v_lshl_add_u64 v[2:3], v[10:11], 0, v[0:1]
	v_or_b32_e32 v0, 16, v14
	s_waitcnt lgkmcnt(0)
	global_store_dwordx4 v[2:3], v[6:9], off
	v_lshl_add_u32 v2, v0, 8, v15
	ds_read_b128 v[2:5], v2
	v_lshl_add_u32 v6, v16, 8, v15
	ds_read_b128 v[6:9], v6
	v_lshlrev_b32_e32 v0, 12, v0
	v_lshl_add_u64 v[12:13], v[10:11], 0, v[0:1]
	v_lshlrev_b32_e32 v0, 12, v16
	s_waitcnt lgkmcnt(1)
	global_store_dwordx4 v[12:13], v[2:5], off
	s_cmpk_lt_i32 s9, 0xa00
	s_nop 0
	v_lshl_add_u64 v[2:3], v[10:11], 0, v[0:1]
	v_or_b32_e32 v0, 24, v14
	s_waitcnt lgkmcnt(0)
	global_store_dwordx4 v[2:3], v[6:9], off
	v_lshl_add_u32 v2, v0, 8, v15
	v_or_b32_e32 v14, 28, v14
	ds_read_b128 v[2:5], v2
	v_lshl_add_u32 v6, v14, 8, v15
	ds_read_b128 v[6:9], v6
	v_lshlrev_b32_e32 v0, 12, v0
	v_lshl_add_u64 v[12:13], v[10:11], 0, v[0:1]
	v_lshlrev_b32_e32 v0, 12, v14
	s_waitcnt lgkmcnt(1)
	global_store_dwordx4 v[12:13], v[2:5], off
	s_nop 1
	v_lshl_add_u64 v[2:3], v[10:11], 0, v[0:1]
	s_waitcnt lgkmcnt(0)
	global_store_dwordx4 v[2:3], v[6:9], off
	s_barrier
	s_cbranch_scc0 .LBB0_1130

; #define LAS __attribute__((address_space(3)))
; #define BF2F(v) __uint_as_float((unsigned)(unsigned short)(v) << 16)
; template <int WIN, bool ALIBI, int EPI, bool SINK>
; __device__ __forceinline__ void attn_item(const Item& I, char* lds, int tid_in) {
;   int tid = tid_in; asm volatile("" : "+v"(tid));
;   const int wid = __builtin_amdgcn_readfirstlane(tid >> 6), lane = tid & 63, r32 = lane & 31, hi = lane >> 5;
;   LAS char* V_lds = (LAS char*)lds; LAS char* K_lds = V_lds + 2 * SHM_V;
;   LAS float* wsf = (LAS float*)(V_lds + (WIN ? 4 : 2) * (SHM_V + SHM_K)) + wid * 64; LAS float* li_l = wsf; LAS float* al_l = wsf + 32;
;   float m_reg = SINK ? I.sink2 : -1e30f, l_reg = SINK ? 1.f : 0.f; f32x16 o[4] = {}; bf16x8 qr[8];
;   const int two = I.two;
;   const int wcls = two ? (wid >> 2) : 0;
;   const int uq = I.u0 + (two ? ((wid & 3) * 32 + r32) : (wid * 32 + r32));
;   { const bf16_t* Qw = I.qkv + (size_t)(I.seq_base + I.c0 + wcls + I.dil * uq) * I.W + I.qcol + hi * 8;
; #pragma unroll
;     for (int d0 = 0; d0 < 8; ++d0) qr[d0] = LDG(bf16x8, Qw + d0 * 16); }
;   if constexpr (WIN == 0 && !ALIBI) { if (I.ropetab) {
;     ...
;     float ss = 0.f;
; #pragma unroll
;     for (int d0 = 0; d0 < 8; ++d0)
; #pragma unroll
;       for (int e = 0; e < 8; ++e) { const float x = BF2F(qr[d0][e]); ss = fmaf(x, x, ss); }
;     { auto rr = __builtin_amdgcn_permlane32_swap(__float_as_uint(ss), __float_as_uint(ss), false, false); ss = __uint_as_float(rr[0]) + __uint_as_float(rr[1]); }
.LBB0_1110:
	s_and_b32 s4, s4, s9
	s_lshr_b32 s26, s9, s5
	s_lshl_b32 s30, s4, 8
	s_mov_b64 s[4:5], s[40:41]
	v_mov_b32_e32 v92, v181
	s_load_dwordx2 s[4:5], s[4:5], 0x48
	s_add_i32 s13, s46, s30
	v_readfirstlane_b32 s27, v92
	s_ashr_i32 s9, s27, 6
	v_and_b32_e32 v182, 31, v92
	s_lshl_b32 s12, s9, 5
	v_or_b32_e32 v112, s12, v182
	s_and_b32 s24, s26, 15
	v_add_u32_e32 v0, s13, v112
	v_mov_b64_e32 v[50:51], s[42:43]
	v_bfe_u32 v183, v92, 5, 1
	v_mad_i64_i32 v[2:3], s[28:29], v0, s89, v[50:51]
	s_lshl_b32 s72, s24, 8
	v_lshl_add_u64 v[2:3], v[2:3], 0, s[72:73]
	v_lshlrev_b32_e32 v0, 4, v183
	v_lshl_add_u64 v[2:3], v[2:3], 0, v[0:1]
	global_load_dwordx4 v[46:49], v[2:3], off offset:160
	global_load_dwordx4 v[52:55], v[2:3], off offset:224
	global_load_dwordx4 v[64:67], v[2:3], off offset:128
	global_load_dwordx4 v[72:75], v[2:3], off offset:192
	global_load_dwordx4 v[82:85], v[2:3], off offset:32
	global_load_dwordx4 v[86:89], v[2:3], off offset:96
	v_and_b32_e32 v93, 32, v92
	global_load_dwordx4 v[94:97], v[2:3], off
	global_load_dwordx4 v[98:101], v[2:3], off offset:64
	s_waitcnt lgkmcnt(0)
	global_load_dwordx4 v[6:9], v93, s[4:5] offset:144
	global_load_dwordx4 v[2:5], v93, s[4:5] offset:16
	global_load_dwordx4 v[14:17], v93, s[4:5]
	global_load_dwordx4 v[22:25], v93, s[4:5] offset:128
	v_add_u32_e32 v10, s30, v112
	v_lshlrev_b32_e32 v113, 3, v183
	v_ashrrev_i32_e32 v10, 1, v10
	s_movk_i32 s28, 0xffe0
	v_and_or_b32 v10, v10, s28, v113
	v_ashrrev_i32_e32 v11, 31, v10
	v_lshl_add_u64 v[30:31], v[10:11], 3, s[38:39]
	v_or_b32_e32 v70, 16, v10
	global_load_dwordx4 v[10:13], v[30:31], off offset:48
	global_load_dwordx4 v[18:21], v[30:31], off offset:32
	global_load_dwordx4 v[26:29], v[30:31], off offset:16
	s_nop 0
	global_load_dwordx4 v[30:33], v[30:31], off
	s_mov_b32 s30, 0x3e0293ee
	v_ashrrev_i32_e32 v71, 31, v70
	v_lshlrev_b32_e32 v184, 4, v92
	v_and_b32_e32 v185, 63, v92
	s_and_b32 s27, s27, 0x3fffffc0
	s_lshl_b32 s27, s27, 2
	s_add_i32 s27, s27, 0
	s_lshl_b32 s24, s24, 7
	s_add_i32 s27, s27, 0x10000
	s_mov_b32 s48, s73
	s_mov_b32 s49, s73
	s_mov_b32 s50, s73
	s_mov_b32 s51, s73
	s_mov_b32 s52, s73
	s_mov_b32 s53, s73
	s_mov_b32 s54, s73
	s_mov_b32 s55, s73
	s_mov_b32 s56, s73
	s_mov_b32 s57, s73
	s_mov_b32 s58, s73
	s_mov_b32 s59, s73
	s_mov_b32 s60, s73
	s_mov_b32 s61, s73
	s_mov_b32 s62, s73
	s_mov_b32 s63, s73
	s_mov_b32 s66, 4
	v_lshlrev_b32_e32 v186, 2, v183
	v_lshl_add_u32 v187, v182, 2, s27
	v_mov_b32_e32 v188, 0
	s_waitcnt vmcnt(0)
	v_lshlrev_b32_e32 v37, 16, v49
	v_and_b32_e32 v35, 0xffff0000, v49
	v_lshlrev_b32_e32 v41, 16, v48
	v_lshlrev_b32_e32 v40, 16, v54
	v_lshlrev_b32_e32 v103, 16, v94
	v_and_b32_e32 v39, 0xffff0000, v48
	v_and_b32_e32 v38, 0xffff0000, v54
	v_lshlrev_b32_e32 v45, 16, v47
	v_and_b32_e32 v43, 0xffff0000, v47
	v_lshlrev_b32_e32 v49, 16, v46
	v_lshlrev_b32_e32 v48, 16, v52
	v_and_b32_e32 v47, 0xffff0000, v46
	v_and_b32_e32 v46, 0xffff0000, v52
	v_lshlrev_b32_e32 v54, 16, v75
	v_and_b32_e32 v52, 0xffff0000, v75
	v_lshlrev_b32_e32 v58, 16, v74
	v_and_b32_e32 v56, 0xffff0000, v74
	v_lshlrev_b32_e32 v62, 16, v73
	v_and_b32_e32 v60, 0xffff0000, v73
	v_lshlrev_b32_e32 v73, 16, v85
	v_and_b32_e32 v69, 0xffff0000, v85
	v_lshlrev_b32_e32 v77, 16, v84
	v_lshlrev_b32_e32 v76, 16, v88
	v_and_b32_e32 v75, 0xffff0000, v84
	v_and_b32_e32 v74, 0xffff0000, v88
	v_lshlrev_b32_e32 v81, 16, v83
	v_and_b32_e32 v79, 0xffff0000, v83
	v_lshlrev_b32_e32 v85, 16, v82
	v_lshlrev_b32_e32 v84, 16, v86
	v_and_b32_e32 v83, 0xffff0000, v82
	v_and_b32_e32 v82, 0xffff0000, v86
	v_lshlrev_b32_e32 v86, 16, v101
	v_mov_b32_e32 v91, v4
	v_and_b32_e32 v88, 0xffff0000, v101
	v_lshlrev_b32_e32 v101, 16, v95
	v_and_b32_e32 v107, 0xffff0000, v95
	v_fma_f32 v4, v103, v103, 0
	v_and_b32_e32 v95, 0xffff0000, v94
	v_fmac_f32_e32 v4, v95, v95
	v_fmac_f32_e32 v4, v101, v101
	v_lshlrev_b32_e32 v105, 16, v96
	v_fmac_f32_e32 v4, v107, v107
	v_lshlrev_b32_e32 v36, 16, v55
	v_and_b32_e32 v34, 0xffff0000, v55
	v_lshlrev_b32_e32 v44, 16, v53
	v_and_b32_e32 v42, 0xffff0000, v53
	v_lshlrev_b32_e32 v55, 16, v67
	v_and_b32_e32 v53, 0xffff0000, v67
	v_lshlrev_b32_e32 v59, 16, v66
	v_and_b32_e32 v57, 0xffff0000, v66
	v_lshlrev_b32_e32 v63, 16, v65
	v_and_b32_e32 v61, 0xffff0000, v65
	v_lshlrev_b32_e32 v67, 16, v64
	v_lshlrev_b32_e32 v66, 16, v72
	v_and_b32_e32 v65, 0xffff0000, v64
	v_and_b32_e32 v64, 0xffff0000, v72
	v_lshlrev_b32_e32 v72, 16, v89
	v_and_b32_e32 v68, 0xffff0000, v89
	v_lshlrev_b32_e32 v80, 16, v87
	v_and_b32_e32 v78, 0xffff0000, v87
	v_lshlrev_b32_e32 v87, 16, v97
	v_and_b32_e32 v89, 0xffff0000, v97
	v_and_b32_e32 v97, 0xffff0000, v96
	v_fmac_f32_e32 v4, v105, v105
	v_fmac_f32_e32 v4, v97, v97
	v_fmac_f32_e32 v4, v87, v87
	v_fmac_f32_e32 v4, v89, v89
	v_fmac_f32_e32 v4, v85, v85
	v_fmac_f32_e32 v4, v83, v83
	v_fmac_f32_e32 v4, v81, v81
	v_fmac_f32_e32 v4, v79, v79
	v_fmac_f32_e32 v4, v77, v77
	v_fmac_f32_e32 v4, v75, v75
	v_fmac_f32_e32 v4, v73, v73
	v_lshlrev_b32_e32 v102, 16, v98
	v_fmac_f32_e32 v4, v69, v69
	v_and_b32_e32 v94, 0xffff0000, v98
	v_fmac_f32_e32 v4, v102, v102
	v_lshlrev_b32_e32 v104, 16, v100
	v_and_b32_e32 v96, 0xffff0000, v100
	v_lshlrev_b32_e32 v100, 16, v99
	v_fmac_f32_e32 v4, v94, v94
	v_and_b32_e32 v106, 0xffff0000, v99
	v_fmac_f32_e32 v4, v100, v100
	v_fmac_f32_e32 v4, v106, v106
	v_fmac_f32_e32 v4, v104, v104
	v_fmac_f32_e32 v4, v96, v96
	v_fmac_f32_e32 v4, v86, v86
	v_fmac_f32_e32 v4, v88, v88
	v_fmac_f32_e32 v4, v84, v84
	v_fmac_f32_e32 v4, v82, v82
	v_fmac_f32_e32 v4, v80, v80
	v_fmac_f32_e32 v4, v78, v78
	v_fmac_f32_e32 v4, v76, v76
	v_fmac_f32_e32 v4, v74, v74
	v_fmac_f32_e32 v4, v72, v72
	v_fmac_f32_e32 v4, v68, v68
; __device__ __forceinline__ unsigned cvt_pk_bf16(float lo, float hi) { unsigned r; asm volatile("v_cvt_pk_bf16_f32 %0, %1, %2" : "=v"(r) : "v"(lo), "v"(hi)); return r; }
; #define BF2F(v) __uint_as_float((unsigned)(unsigned short)(v) << 16)
; template <int WIN, bool ALIBI, int EPI, bool SINK>
; __device__ __forceinline__ void attn_item(const Item& I, char* lds, int tid_in) {
;     ...
;     const float rs = QSCALE / sqrtf(ss * (1.f / 128.f) + EPS);
; #pragma unroll
;     for (int ax = 0; ax < 2; ++ax) { const int pos = ax ? (uq & 63) : (uq >> 6);
; #pragma unroll
;       for (int pi = 0; pi < 2; ++pi) { const int dl = 4 * ax + pi, dh = dl + 2;
;         const float* tp = I.ropetab + (size_t)(pos * 32 + pi * 16 + hi * 8) * 2; const float* gl = I.qgain + dl * 16 + hi * 8; const float* gh = I.qgain + dh * 16 + hi * 8;
;         const f32x4 t0 = LDG(f32x4, tp), t1 = LDG(f32x4, tp + 4), t2 = LDG(f32x4, tp + 8), t3 = LDG(f32x4, tp + 12);
;         const f32x4 ga = LDG(f32x4, gl), gb = LDG(f32x4, gl + 4), gc = LDG(f32x4, gh), gd = LDG(f32x4, gh + 4);
;         const float cs[8] = {t0[0], t0[2], t1[0], t1[2], t2[0], t2[2], t3[0], t3[2]}, sn[8] = {t0[1], t0[3], t1[1], t1[3], t2[1], t2[3], t3[1], t3[3]};
;         const float gL[8] = {ga[0], ga[1], ga[2], ga[3], gb[0], gb[1], gb[2], gb[3]}, gH[8] = {gc[0], gc[1], gc[2], gc[3], gd[0], gd[1], gd[2], gd[3]};
;         unsigned wl[4], wh[4];
; #pragma unroll
;         for (int e2 = 0; e2 < 4; ++e2) { float ol[2], oh[2];
; #pragma unroll
;           for (int q = 0; q < 2; ++q) { const int e = 2 * e2 + q; const float yl = BF2F(qr[dl][e]) * rs * gL[e], yh = BF2F(qr[dh][e]) * rs * gH[e];
;             ol[q] = yl * cs[e] - yh * sn[e]; oh[q] = yh * cs[e] + yl * sn[e]; }
;           wl[e2] = cvt_pk_bf16(ol[0], ol[1]); wh[e2] = cvt_pk_bf16(oh[0], oh[1]); }
;         { u32x4 w = {wl[0], wl[1], wl[2], wl[3]}; qr[dl] = *reinterpret_cast<bf16x8*>(&w); }
;         { u32x4 w = {wh[0], wh[1], wh[2], wh[3]}; qr[dh] = *reinterpret_cast<bf16x8*>(&w); } } }
	v_fmac_f32_e32 v4, v67, v67
	v_fmac_f32_e32 v4, v65, v65
	v_fmac_f32_e32 v4, v63, v63
	v_fmac_f32_e32 v4, v61, v61
	v_fmac_f32_e32 v4, v59, v59
	v_fmac_f32_e32 v4, v57, v57
	v_fmac_f32_e32 v4, v55, v55
	v_fmac_f32_e32 v4, v53, v53
	v_fmac_f32_e32 v4, v49, v49
	v_fmac_f32_e32 v4, v47, v47
	v_fmac_f32_e32 v4, v45, v45
	v_fmac_f32_e32 v4, v43, v43
	v_fmac_f32_e32 v4, v41, v41
	v_fmac_f32_e32 v4, v39, v39
	v_fmac_f32_e32 v4, v37, v37
	v_fmac_f32_e32 v4, v35, v35
	v_fmac_f32_e32 v4, v66, v66
	v_fmac_f32_e32 v4, v64, v64
	v_fmac_f32_e32 v4, v62, v62
	v_fmac_f32_e32 v4, v60, v60
	v_fmac_f32_e32 v4, v58, v58
	v_fmac_f32_e32 v4, v56, v56
	v_fmac_f32_e32 v4, v54, v54
	v_fmac_f32_e32 v4, v52, v52
	v_fmac_f32_e32 v4, v48, v48
	v_fmac_f32_e32 v4, v46, v46
	v_fmac_f32_e32 v4, v44, v44
	v_fmac_f32_e32 v4, v42, v42
	v_fmac_f32_e32 v4, v40, v40
	v_fmac_f32_e32 v4, v38, v38
	v_fmac_f32_e32 v4, v36, v36
	v_fmac_f32_e32 v4, v34, v34
	v_mov_b32_e32 v90, v8
	v_mov_b32_e32 v8, v4
	s_nop 1
	v_permlane32_swap_b32_e32 v4, v8
	v_add_f32_e32 v4, v4, v8
	v_fmamk_f32 v4, v4, 0x3c000000, v226
	v_mul_f32_e32 v8, 0x4f800000, v4
	v_cmp_gt_f32_e32 vcc, s87, v4
	v_mov_b32_e32 v109, v2
	v_mov_b32_e32 v108, v6
	v_cndmask_b32_e32 v4, v4, v8, vcc
	v_sqrt_f32_e32 v8, v4
	v_mov_b32_e32 v99, v14
	v_mov_b32_e32 v111, v16
	v_mov_b32_e32 v98, v22
	v_add_u32_e32 v2, -1, v8
	v_fma_f32 v6, -v2, v8, v4
	v_cmp_ge_f32_e64 s[36:37], 0, v6
	v_add_u32_e32 v6, 1, v8
	v_mov_b32_e32 v110, v24
	v_cndmask_b32_e64 v2, v8, v2, s[36:37]
	v_fma_f32 v8, -v6, v8, v4
	v_cmp_lt_f32_e64 s[36:37], 0, v8
	s_nop 1
	v_cndmask_b32_e64 v2, v2, v6, s[36:37]
	v_mul_f32_e32 v6, 0x37800000, v2
	v_cndmask_b32_e32 v2, v2, v6, vcc
	v_cmp_class_f32_e32 vcc, v4, v227
	v_cmp_gt_u32_e64 s[36:37], 32, v185
	s_nop 0
	v_cndmask_b32_e32 v2, v2, v4, vcc
	v_div_scale_f32 v4, s[28:29], v2, v2, s30
	v_rcp_f32_e32 v6, v4
	s_movk_i32 s28, 0x7e0
	s_movk_i32 s29, 0x70
	v_fma_f32 v8, -v4, v6, 1.0
	v_fmac_f32_e32 v6, v8, v6
	v_div_scale_f32 v8, vcc, s30, v2, s30
	v_mul_f32_e32 v14, v8, v6
	v_fma_f32 v16, -v4, v14, v8
	v_fmac_f32_e32 v14, v16, v6
	v_fma_f32 v4, -v4, v14, v8
	v_div_fmas_f32 v4, v4, v6, v14
	v_div_fixup_f32 v6, v4, v2, s30
	v_pk_mul_f32 v[102:103], v[6:7], v[102:103] op_sel_hi:[0,1]
	v_pk_mul_f32 v[98:99], v[98:99], v[102:103]
	v_mov_b32_e32 v14, v23
	v_pk_mul_f32 v[102:103], v[30:31], v[98:99] op_sel:[0,1] op_sel_hi:[1,0]
	v_pk_mul_f32 v[30:31], v[30:31], v[98:99]
	v_sub_f32_e32 v2, v102, v103
	v_add_f32_e32 v4, v31, v30
	v_pk_mul_f32 v[30:31], v[6:7], v[94:95] op_sel_hi:[0,1]
	v_pk_mul_f32 v[14:15], v[14:15], v[30:31]
	v_mov_b32_e32 v16, v25
	v_pk_mul_f32 v[22:23], v[32:33], v[14:15] op_sel:[0,1] op_sel_hi:[1,0]
	v_pk_mul_f32 v[14:15], v[32:33], v[14:15]
	v_sub_f32_e32 v8, v22, v23
	v_add_f32_e32 v14, v15, v14
	v_cvt_pk_bf16_f32 v102, v2, v8
	v_cvt_pk_bf16_f32 v98, v4, v14
	v_pk_mul_f32 v[14:15], v[6:7], v[100:101] op_sel_hi:[0,1]
	v_pk_mul_f32 v[14:15], v[110:111], v[14:15]
	v_lshl_add_u64 v[32:33], v[70:71], 3, s[38:39]
	v_pk_mul_f32 v[22:23], v[26:27], v[14:15] op_sel:[0,1] op_sel_hi:[1,0]
	v_pk_mul_f32 v[14:15], v[26:27], v[14:15]
	v_sub_f32_e32 v2, v22, v23
	v_add_f32_e32 v4, v15, v14
	v_pk_mul_f32 v[14:15], v[6:7], v[106:107] op_sel_hi:[0,1]
	v_pk_mul_f32 v[14:15], v[16:17], v[14:15]
	s_nop 0
	v_pk_mul_f32 v[16:17], v[28:29], v[14:15] op_sel:[0,1] op_sel_hi:[1,0]
	v_pk_mul_f32 v[14:15], v[28:29], v[14:15]
	v_sub_f32_e32 v8, v16, v17
	v_add_f32_e32 v14, v15, v14
	v_cvt_pk_bf16_f32 v103, v2, v8
	v_cvt_pk_bf16_f32 v99, v4, v14
	v_pk_mul_f32 v[14:15], v[6:7], v[104:105] op_sel_hi:[0,1]
	v_pk_mul_f32 v[14:15], v[108:109], v[14:15]
	v_mov_b32_e32 v2, v7
	v_pk_mul_f32 v[16:17], v[18:19], v[14:15] op_sel:[0,1] op_sel_hi:[1,0]
	v_pk_mul_f32 v[14:15], v[18:19], v[14:15]
	v_sub_f32_e32 v4, v16, v17
	v_add_f32_e32 v8, v15, v14
	v_pk_mul_f32 v[14:15], v[6:7], v[96:97] op_sel_hi:[0,1]
	v_pk_mul_f32 v[2:3], v[2:3], v[14:15]
	s_nop 0
	v_pk_mul_f32 v[14:15], v[20:21], v[2:3] op_sel:[0,1] op_sel_hi:[1,0]
	v_pk_mul_f32 v[2:3], v[20:21], v[2:3]
	v_sub_f32_e32 v7, v14, v15
	v_add_f32_e32 v2, v3, v2
	v_cvt_pk_bf16_f32 v104, v4, v7
	v_cvt_pk_bf16_f32 v100, v8, v2
	v_pk_mul_f32 v[2:3], v[6:7], v[86:87] op_sel_hi:[0,1]
	v_pk_mul_f32 v[2:3], v[90:91], v[2:3]
	v_mov_b32_e32 v4, v9
	v_pk_mul_f32 v[14:15], v[10:11], v[2:3] op_sel:[0,1] op_sel_hi:[1,0]
	v_pk_mul_f32 v[2:3], v[10:11], v[2:3]
	v_sub_f32_e32 v7, v14, v15
	v_add_f32_e32 v8, v3, v2
	v_pk_mul_f32 v[2:3], v[6:7], v[88:89] op_sel_hi:[0,1]
	v_pk_mul_f32 v[2:3], v[4:5], v[2:3]
	s_nop 0
	v_pk_mul_f32 v[4:5], v[12:13], v[2:3] op_sel:[0,1] op_sel_hi:[1,0]
	v_pk_mul_f32 v[2:3], v[12:13], v[2:3]
	v_sub_f32_e32 v4, v4, v5
	v_add_f32_e32 v2, v3, v2
	v_cvt_pk_bf16_f32 v105, v7, v4
	v_cvt_pk_bf16_f32 v101, v8, v2
	global_load_dwordx4 v[2:5], v93, s[4:5] offset:192
	global_load_dwordx4 v[8:11], v93, s[4:5] offset:64
	global_load_dwordx4 v[12:15], v[32:33], off
	global_load_dwordx4 v[16:19], v[32:33], off offset:16
	global_load_dwordx4 v[20:23], v93, s[4:5] offset:208
	global_load_dwordx4 v[24:27], v93, s[4:5] offset:80
	global_load_dwordx4 v[28:31], v[32:33], off offset:32
	global_load_dwordx4 v[86:89], v[32:33], off offset:48
	v_lshlrev_b32_e32 v7, 5, v112
	v_and_or_b32 v7, v7, s28, v113
	v_pk_mul_f32 v[32:33], v[6:7], v[84:85] op_sel_hi:[0,1]
	s_waitcnt vmcnt(7)
	v_mov_b32_e32 v70, v2
	s_waitcnt vmcnt(6)
	v_mov_b32_e32 v71, v8
	v_pk_mul_f32 v[32:33], v[32:33], v[70:71]
	v_mov_b32_e32 v8, v3
	s_waitcnt vmcnt(5)
; __device__ __forceinline__ unsigned cvt_pk_bf16(float lo, float hi) { unsigned r; asm volatile("v_cvt_pk_bf16_f32 %0, %1, %2" : "=v"(r) : "v"(lo), "v"(hi)); return r; }
; #define BF2F(v) __uint_as_float((unsigned)(unsigned short)(v) << 16)
; template <int WIN, bool ALIBI, int EPI, bool SINK>
; __device__ __forceinline__ void attn_item(const Item& I, char* lds, int tid_in) {
;     ...
;     for (int ax = 0; ax < 2; ++ax) { const int pos = ax ? (uq & 63) : (uq >> 6);
; #pragma unroll
;       for (int pi = 0; pi < 2; ++pi) { const int dl = 4 * ax + pi, dh = dl + 2;
;         const float* tp = I.ropetab + (size_t)(pos * 32 + pi * 16 + hi * 8) * 2; const float* gl = I.qgain + dl * 16 + hi * 8; const float* gh = I.qgain + dh * 16 + hi * 8;
;         const f32x4 t0 = LDG(f32x4, tp), t1 = LDG(f32x4, tp + 4), t2 = LDG(f32x4, tp + 8), t3 = LDG(f32x4, tp + 12);
;         const f32x4 ga = LDG(f32x4, gl), gb = LDG(f32x4, gl + 4), gc = LDG(f32x4, gh), gd = LDG(f32x4, gh + 4);
;         const float cs[8] = {t0[0], t0[2], t1[0], t1[2], t2[0], t2[2], t3[0], t3[2]}, sn[8] = {t0[1], t0[3], t1[1], t1[3], t2[1], t2[3], t3[1], t3[3]};
;         const float gL[8] = {ga[0], ga[1], ga[2], ga[3], gb[0], gb[1], gb[2], gb[3]}, gH[8] = {gc[0], gc[1], gc[2], gc[3], gd[0], gd[1], gd[2], gd[3]};
;         unsigned wl[4], wh[4];
; #pragma unroll
;         for (int e2 = 0; e2 < 4; ++e2) { float ol[2], oh[2];
; #pragma unroll
;           for (int q = 0; q < 2; ++q) { const int e = 2 * e2 + q; const float yl = BF2F(qr[dl][e]) * rs * gL[e], yh = BF2F(qr[dh][e]) * rs * gH[e];
;             ol[q] = yl * cs[e] - yh * sn[e]; oh[q] = yh * cs[e] + yl * sn[e]; }
;           wl[e2] = cvt_pk_bf16(ol[0], ol[1]); wh[e2] = cvt_pk_bf16(oh[0], oh[1]); }
;         { u32x4 w = {wl[0], wl[1], wl[2], wl[3]}; qr[dl] = *reinterpret_cast<bf16x8*>(&w); }
;         { u32x4 w = {wh[0], wh[1], wh[2], wh[3]}; qr[dh] = *reinterpret_cast<bf16x8*>(&w); } } }
	v_pk_mul_f32 v[70:71], v[12:13], v[32:33] op_sel:[0,1] op_sel_hi:[1,0]
	v_pk_mul_f32 v[12:13], v[12:13], v[32:33]
	v_sub_f32_e32 v70, v70, v71
	v_add_f32_e32 v32, v13, v12
	v_pk_mul_f32 v[12:13], v[6:7], v[82:83] op_sel_hi:[0,1]
	v_pk_mul_f32 v[2:3], v[12:13], v[8:9]
	s_nop 0
	v_pk_mul_f32 v[8:9], v[14:15], v[2:3] op_sel:[0,1] op_sel_hi:[1,0]
	v_pk_mul_f32 v[2:3], v[14:15], v[2:3]
	v_sub_f32_e32 v8, v8, v9
	v_add_f32_e32 v2, v3, v2
	v_cvt_pk_bf16_f32 v110, v70, v8
	v_cvt_pk_bf16_f32 v106, v32, v2
	v_pk_mul_f32 v[2:3], v[6:7], v[80:81] op_sel_hi:[0,1]
	v_mov_b32_e32 v8, v4
	v_mov_b32_e32 v9, v10
	v_pk_mul_f32 v[2:3], v[2:3], v[8:9]
	v_mov_b32_e32 v10, v5
	s_waitcnt vmcnt(4)
	v_pk_mul_f32 v[8:9], v[16:17], v[2:3] op_sel:[0,1] op_sel_hi:[1,0]
	v_pk_mul_f32 v[2:3], v[16:17], v[2:3]
	v_sub_f32_e32 v8, v8, v9
	v_add_f32_e32 v9, v3, v2
	v_pk_mul_f32 v[2:3], v[6:7], v[78:79] op_sel_hi:[0,1]
	v_pk_mul_f32 v[2:3], v[2:3], v[10:11]
	s_nop 0
	v_pk_mul_f32 v[4:5], v[18:19], v[2:3] op_sel:[0,1] op_sel_hi:[1,0]
	v_pk_mul_f32 v[2:3], v[18:19], v[2:3]
	v_sub_f32_e32 v4, v4, v5
	v_add_f32_e32 v2, v3, v2
	v_cvt_pk_bf16_f32 v111, v8, v4
	v_cvt_pk_bf16_f32 v107, v9, v2
	v_pk_mul_f32 v[2:3], v[6:7], v[76:77] op_sel_hi:[0,1]
	s_waitcnt vmcnt(3)
	v_mov_b32_e32 v4, v20
	s_waitcnt vmcnt(2)
	v_mov_b32_e32 v5, v24
	v_pk_mul_f32 v[2:3], v[2:3], v[4:5]
	v_mov_b32_e32 v24, v21
	s_waitcnt vmcnt(1)
	v_pk_mul_f32 v[4:5], v[28:29], v[2:3] op_sel:[0,1] op_sel_hi:[1,0]
	v_pk_mul_f32 v[2:3], v[28:29], v[2:3]
	v_sub_f32_e32 v8, v4, v5
	v_add_f32_e32 v9, v3, v2
	v_pk_mul_f32 v[2:3], v[6:7], v[74:75] op_sel_hi:[0,1]
	v_pk_mul_f32 v[2:3], v[2:3], v[24:25]
	v_ashrrev_i32_e32 v76, 4, v92
	v_pk_mul_f32 v[4:5], v[30:31], v[2:3] op_sel:[0,1] op_sel_hi:[1,0]
	v_pk_mul_f32 v[2:3], v[30:31], v[2:3]
	v_sub_f32_e32 v4, v4, v5
	v_add_f32_e32 v2, v3, v2
	v_cvt_pk_bf16_f32 v112, v8, v4
	v_cvt_pk_bf16_f32 v108, v9, v2
	v_pk_mul_f32 v[2:3], v[6:7], v[72:73] op_sel_hi:[0,1]
	v_mov_b32_e32 v4, v22
	v_mov_b32_e32 v5, v26
	v_pk_mul_f32 v[2:3], v[2:3], v[4:5]
	v_mov_b32_e32 v26, v23
	s_waitcnt vmcnt(0)
	v_pk_mul_f32 v[4:5], v[86:87], v[2:3] op_sel:[0,1] op_sel_hi:[1,0]
	v_pk_mul_f32 v[2:3], v[86:87], v[2:3]
	v_sub_f32_e32 v8, v4, v5
	v_add_f32_e32 v9, v3, v2
	v_pk_mul_f32 v[2:3], v[6:7], v[68:69] op_sel_hi:[0,1]
	v_pk_mul_f32 v[2:3], v[2:3], v[26:27]
	v_lshlrev_b32_e32 v7, 3, v7
	v_pk_mul_f32 v[4:5], v[88:89], v[2:3] op_sel:[0,1] op_sel_hi:[1,0]
	v_pk_mul_f32 v[2:3], v[88:89], v[2:3]
	v_sub_f32_e32 v4, v4, v5
	v_add_f32_e32 v2, v3, v2
	v_cvt_pk_bf16_f32 v113, v8, v4
	v_cvt_pk_bf16_f32 v109, v9, v2
	global_load_dwordx4 v[2:5], v93, s[4:5] offset:384
	global_load_dwordx4 v[8:11], v93, s[4:5] offset:256
	global_load_dwordx4 v[12:15], v7, s[38:39]
	global_load_dwordx4 v[16:19], v7, s[38:39] offset:16
	global_load_dwordx4 v[20:23], v93, s[4:5] offset:400
	global_load_dwordx4 v[24:27], v93, s[4:5] offset:272
	global_load_dwordx4 v[28:31], v7, s[38:39] offset:32
	global_load_dwordx4 v[68:71], v7, s[38:39] offset:48
	v_pk_mul_f32 v[32:33], v[6:7], v[66:67] op_sel_hi:[0,1]
	v_add_u32_e32 v72, s46, v76
	s_waitcnt vmcnt(7)
	v_mov_b32_e32 v66, v2
	s_waitcnt vmcnt(6)
	v_mov_b32_e32 v67, v8
	v_pk_mul_f32 v[32:33], v[32:33], v[66:67]
	v_mov_b32_e32 v8, v3
	s_waitcnt vmcnt(5)
	v_pk_mul_f32 v[66:67], v[12:13], v[32:33] op_sel:[0,1] op_sel_hi:[1,0]
	v_pk_mul_f32 v[12:13], v[12:13], v[32:33]
	v_sub_f32_e32 v66, v66, v67
	v_add_f32_e32 v32, v13, v12
	v_pk_mul_f32 v[12:13], v[6:7], v[64:65] op_sel_hi:[0,1]
	v_pk_mul_f32 v[2:3], v[12:13], v[8:9]
	s_nop 0
	v_pk_mul_f32 v[8:9], v[14:15], v[2:3] op_sel:[0,1] op_sel_hi:[1,0]
	v_pk_mul_f32 v[2:3], v[14:15], v[2:3]
	v_sub_f32_e32 v8, v8, v9
	v_add_f32_e32 v2, v3, v2
	v_cvt_pk_bf16_f32 v118, v66, v8
	v_cvt_pk_bf16_f32 v114, v32, v2
	v_pk_mul_f32 v[2:3], v[6:7], v[62:63] op_sel_hi:[0,1]
	v_mov_b32_e32 v8, v4
	v_mov_b32_e32 v9, v10
	v_pk_mul_f32 v[2:3], v[2:3], v[8:9]
	v_mov_b32_e32 v10, v5
	s_waitcnt vmcnt(4)
	v_pk_mul_f32 v[8:9], v[16:17], v[2:3] op_sel:[0,1] op_sel_hi:[1,0]
	v_pk_mul_f32 v[2:3], v[16:17], v[2:3]
	v_sub_f32_e32 v8, v8, v9
	v_add_f32_e32 v9, v3, v2
	v_pk_mul_f32 v[2:3], v[6:7], v[60:61] op_sel_hi:[0,1]
	v_pk_mul_f32 v[2:3], v[2:3], v[10:11]
	v_pk_mul_f32 v[32:33], v[6:7], v[48:49] op_sel_hi:[0,1]
	v_pk_mul_f32 v[4:5], v[18:19], v[2:3] op_sel:[0,1] op_sel_hi:[1,0]
	v_pk_mul_f32 v[2:3], v[18:19], v[2:3]
	v_sub_f32_e32 v4, v4, v5
	v_add_f32_e32 v2, v3, v2
	v_cvt_pk_bf16_f32 v119, v8, v4
	v_cvt_pk_bf16_f32 v115, v9, v2
	v_pk_mul_f32 v[2:3], v[6:7], v[58:59] op_sel_hi:[0,1]
	s_waitcnt vmcnt(3)
	v_mov_b32_e32 v4, v20
	s_waitcnt vmcnt(2)
	v_mov_b32_e32 v5, v24
	v_pk_mul_f32 v[2:3], v[2:3], v[4:5]
	v_mov_b32_e32 v24, v21
	s_waitcnt vmcnt(1)
	v_pk_mul_f32 v[4:5], v[28:29], v[2:3] op_sel:[0,1] op_sel_hi:[1,0]
	v_pk_mul_f32 v[2:3], v[28:29], v[2:3]
	v_sub_f32_e32 v8, v4, v5
	v_add_f32_e32 v9, v3, v2
	v_pk_mul_f32 v[2:3], v[6:7], v[56:57] op_sel_hi:[0,1]
	v_pk_mul_f32 v[2:3], v[2:3], v[24:25]
	s_nop 0
	v_pk_mul_f32 v[4:5], v[30:31], v[2:3] op_sel:[0,1] op_sel_hi:[1,0]
	v_pk_mul_f32 v[2:3], v[30:31], v[2:3]
	v_sub_f32_e32 v4, v4, v5
	v_add_f32_e32 v2, v3, v2
	v_cvt_pk_bf16_f32 v120, v8, v4
	v_cvt_pk_bf16_f32 v116, v9, v2
	v_pk_mul_f32 v[2:3], v[6:7], v[54:55] op_sel_hi:[0,1]
	v_mov_b32_e32 v4, v22
	v_mov_b32_e32 v5, v26
	v_pk_mul_f32 v[2:3], v[2:3], v[4:5]
	v_mov_b32_e32 v26, v23
	s_waitcnt vmcnt(0)
; __device__ __forceinline__ unsigned cvt_pk_bf16(float lo, float hi) { unsigned r; asm volatile("v_cvt_pk_bf16_f32 %0, %1, %2" : "=v"(r) : "v"(lo), "v"(hi)); return r; }
; __device__ __forceinline__ int v_st(int k, int c) { const int kk = (k & ~0xC) | ((k & 4) << 1) | ((k & 8) >> 1); return ((kk >> 3) * 4 + (c >> 5)) * 512 + ((kk & 7) * 32 + (c & 31)) * 2; }
; __device__ __forceinline__ int v_rd_base(int lane) { return ((lane & 3) << 3) | (((lane >> 2) & 3) << 6) | (((lane >> 4) & 1) << 5) | (((lane >> 5) & 1) << 8); }
; #define BF2F(v) __uint_as_float((unsigned)(unsigned short)(v) << 16)
; #define SWRITE(b, i) do { *(LAS bf16x8*)(V_lds + (b) * SHM_V + vst0) = sr_[i].vs0; *(LAS bf16x8*)(V_lds + (b) * SHM_V + vst1) = sr_[i].vs1; const int kc = sc * 2; \
;     *(LAS bf16x8*)(K_lds + (b) * SHM_K + KSWZ(sr, kc)) = sr_[i].ks0; *(LAS bf16x8*)(K_lds + (b) * SHM_K + KSWZ(32 + sr, kc)) = sr_[i].ks1; } while (0)
; template <int WIN, bool ALIBI, int EPI, bool SINK>
; __device__ __forceinline__ void attn_item(const Item& I, char* lds, int tid_in) {
;     ...
;           for (int q = 0; q < 2; ++q) { const int e = 2 * e2 + q; const float yl = BF2F(qr[dl][e]) * rs * gL[e], yh = BF2F(qr[dh][e]) * rs * gH[e];
;             ol[q] = yl * cs[e] - yh * sn[e]; oh[q] = yh * cs[e] + yl * sn[e]; }
;           wl[e2] = cvt_pk_bf16(ol[0], ol[1]); wh[e2] = cvt_pk_bf16(oh[0], oh[1]); }
;         { u32x4 w = {wl[0], wl[1], wl[2], wl[3]}; qr[dl] = *reinterpret_cast<bf16x8*>(&w); }
;         { u32x4 w = {wh[0], wh[1], wh[2], wh[3]}; qr[dh] = *reinterpret_cast<bf16x8*>(&w); } } }
;     ...
;   } }
;   const int uqw = I.u0 + (two ? (wid & 3) * 32 : wid * 32);
;   float lse_old = 0.f;
;     ...
;   const float lo = WIN ? (float)max(-WIN, -uq) : 0.f, hi_ = WIN ? (float)min(WIN, I.SU - 1 - uq) : 0.f;
;   const float dq = (float)(4 * hi - uq);
;   const int sr = tid >> 4, sc = (tid & 15) * 8, vst0 = v_st(sr, sc), vst1 = v_st(32 + sr, sc);
;   const int vb0 = (int)(unsigned)(uintptr_t)V_lds + v_rd_base(lane);
;   struct { bf16x8 vs0, vs1, ks0, ks1; } sr_[2];
;     ...
;   f32x16 pA0, pA1, pB0, pB1; float mnA, mnB, alA, alB; bf16x8 pa0, pa1, pa2, pa3; const int NT = I.NT;
;   constexpr int SE = 0, SO = 1;
;   if constexpr (WIN == 0) {
;   SLOAD(SE, 0); asm volatile("s_waitcnt vmcnt(0)" ::: "memory"); SWRITE(0, SE); __syncthreads();
	v_pk_mul_f32 v[4:5], v[68:69], v[2:3] op_sel:[0,1] op_sel_hi:[1,0]
	v_pk_mul_f32 v[2:3], v[68:69], v[2:3]
	v_sub_f32_e32 v8, v4, v5
	v_add_f32_e32 v9, v3, v2
	v_pk_mul_f32 v[2:3], v[6:7], v[52:53] op_sel_hi:[0,1]
	v_pk_mul_f32 v[2:3], v[2:3], v[26:27]
	s_nop 0
	v_pk_mul_f32 v[4:5], v[70:71], v[2:3] op_sel:[0,1] op_sel_hi:[1,0]
	v_pk_mul_f32 v[2:3], v[70:71], v[2:3]
	v_sub_f32_e32 v4, v4, v5
	v_add_f32_e32 v2, v3, v2
	v_cvt_pk_bf16_f32 v121, v8, v4
	v_cvt_pk_bf16_f32 v117, v9, v2
	global_load_dwordx4 v[2:5], v93, s[4:5] offset:448
	global_load_dwordx4 v[8:11], v93, s[4:5] offset:320
	global_load_dwordx4 v[12:15], v7, s[38:39] offset:128
	global_load_dwordx4 v[16:19], v7, s[38:39] offset:144
	global_load_dwordx4 v[20:23], v93, s[4:5] offset:464
	global_load_dwordx4 v[24:27], v93, s[4:5] offset:336
	global_load_dwordx4 v[28:31], v7, s[38:39] offset:160
	global_load_dwordx4 v[52:55], v7, s[38:39] offset:176
	s_lshl_b32 s4, s26, 5
	s_and_b32 s28, s4, 0x180
	s_or_b32 s26, s28, 0xa00
	s_lshl_b32 s72, s26, 1
	s_bitset1_b32 s28, 11
	s_waitcnt vmcnt(7)
	v_mov_b32_e32 v48, v2
	s_waitcnt vmcnt(6)
	v_mov_b32_e32 v49, v8
	v_pk_mul_f32 v[32:33], v[32:33], v[48:49]
	v_mov_b32_e32 v8, v3
	s_waitcnt vmcnt(5)
	v_pk_mul_f32 v[48:49], v[12:13], v[32:33] op_sel:[0,1] op_sel_hi:[1,0]
	v_pk_mul_f32 v[12:13], v[12:13], v[32:33]
	v_sub_f32_e32 v7, v48, v49
	v_add_f32_e32 v32, v13, v12
	v_pk_mul_f32 v[12:13], v[6:7], v[46:47] op_sel_hi:[0,1]
	v_pk_mul_f32 v[2:3], v[12:13], v[8:9]
	s_nop 0
	v_pk_mul_f32 v[8:9], v[14:15], v[2:3] op_sel:[0,1] op_sel_hi:[1,0]
	v_pk_mul_f32 v[2:3], v[14:15], v[2:3]
	v_sub_f32_e32 v8, v8, v9
	v_add_f32_e32 v2, v3, v2
	v_cvt_pk_bf16_f32 v126, v7, v8
	v_cvt_pk_bf16_f32 v122, v32, v2
	v_pk_mul_f32 v[2:3], v[6:7], v[44:45] op_sel_hi:[0,1]
	v_mov_b32_e32 v8, v4
	v_mov_b32_e32 v9, v10
	v_pk_mul_f32 v[2:3], v[2:3], v[8:9]
	v_mov_b32_e32 v10, v5
	s_waitcnt vmcnt(4)
	v_pk_mul_f32 v[8:9], v[16:17], v[2:3] op_sel:[0,1] op_sel_hi:[1,0]
	v_pk_mul_f32 v[2:3], v[16:17], v[2:3]
	v_sub_f32_e32 v7, v8, v9
	v_add_f32_e32 v8, v3, v2
	v_pk_mul_f32 v[2:3], v[6:7], v[42:43] op_sel_hi:[0,1]
	v_pk_mul_f32 v[2:3], v[2:3], v[10:11]
	s_nop 0
	v_pk_mul_f32 v[4:5], v[18:19], v[2:3] op_sel:[0,1] op_sel_hi:[1,0]
	v_pk_mul_f32 v[2:3], v[18:19], v[2:3]
	v_sub_f32_e32 v4, v4, v5
	v_add_f32_e32 v2, v3, v2
	v_cvt_pk_bf16_f32 v127, v7, v4
	v_cvt_pk_bf16_f32 v123, v8, v2
	v_pk_mul_f32 v[2:3], v[6:7], v[40:41] op_sel_hi:[0,1]
	s_waitcnt vmcnt(3)
	v_mov_b32_e32 v4, v20
	s_waitcnt vmcnt(2)
	v_mov_b32_e32 v5, v24
	v_pk_mul_f32 v[2:3], v[2:3], v[4:5]
	v_mov_b32_e32 v24, v21
	s_waitcnt vmcnt(1)
	v_pk_mul_f32 v[4:5], v[28:29], v[2:3] op_sel:[0,1] op_sel_hi:[1,0]
	v_pk_mul_f32 v[2:3], v[28:29], v[2:3]
	v_sub_f32_e32 v7, v4, v5
	v_add_f32_e32 v8, v3, v2
	v_pk_mul_f32 v[2:3], v[6:7], v[38:39] op_sel_hi:[0,1]
	v_pk_mul_f32 v[2:3], v[2:3], v[24:25]
	v_lshlrev_b32_e32 v18, 3, v92
	v_pk_mul_f32 v[4:5], v[30:31], v[2:3] op_sel:[0,1] op_sel_hi:[1,0]
	v_pk_mul_f32 v[2:3], v[30:31], v[2:3]
	v_sub_f32_e32 v4, v4, v5
	v_add_f32_e32 v2, v3, v2
	v_cvt_pk_bf16_f32 v128, v7, v4
	v_cvt_pk_bf16_f32 v124, v8, v2
	v_pk_mul_f32 v[2:3], v[6:7], v[36:37] op_sel_hi:[0,1]
	v_mov_b32_e32 v4, v22
	v_mov_b32_e32 v5, v26
	v_pk_mul_f32 v[2:3], v[2:3], v[4:5]
	v_mov_b32_e32 v26, v23
	s_waitcnt vmcnt(0)
	v_pk_mul_f32 v[4:5], v[52:53], v[2:3] op_sel:[0,1] op_sel_hi:[1,0]
	v_pk_mul_f32 v[2:3], v[52:53], v[2:3]
	v_sub_f32_e32 v7, v4, v5
	v_add_f32_e32 v8, v3, v2
	v_pk_mul_f32 v[2:3], v[6:7], v[34:35] op_sel_hi:[0,1]
	v_pk_mul_f32 v[2:3], v[2:3], v[26:27]
	v_add_u32_e32 v19, 32, v76
	v_pk_mul_f32 v[4:5], v[54:55], v[2:3] op_sel:[0,1] op_sel_hi:[1,0]
	v_pk_mul_f32 v[2:3], v[54:55], v[2:3]
	v_sub_f32_e32 v4, v4, v5
	v_add_f32_e32 v2, v3, v2
	v_cvt_pk_bf16_f32 v129, v7, v4
	v_cvt_pk_bf16_f32 v125, v8, v2
	v_and_b32_e32 v2, 0x78, v18
	v_lshlrev_b32_e32 v52, 1, v2
	v_mad_i64_i32 v[2:3], s[4:5], v72, s89, v[50:51]
	v_mov_b32_e32 v53, v1
	v_lshl_add_u64 v[10:11], v[2:3], 0, v[52:53]
	v_add_u32_e32 v2, s46, v19
	v_mad_i64_i32 v[2:3], s[4:5], v2, s89, v[50:51]
	v_lshl_add_u64 v[14:15], v[2:3], 0, v[52:53]
	v_lshl_add_u64 v[2:3], v[10:11], 0, s[72:73]
	global_load_dwordx4 v[2:5], v[2:3], off
	s_lshl_b32 s4, s28, 1
	s_mov_b32 s5, s73
	v_lshl_add_u64 v[6:7], v[14:15], 0, s[72:73]
	v_lshl_add_u64 v[10:11], v[10:11], 0, s[4:5]
	global_load_dwordx4 v[6:9], v[6:7], off
	v_lshl_add_u64 v[14:15], v[14:15], 0, s[4:5]
	global_load_dwordx4 v[10:13], v[10:11], off
	v_and_b32_e32 v20, 0xfffff0, v76
	global_load_dwordx4 v[14:17], v[14:15], off
	v_lshlrev_b32_e32 v21, 1, v76
	v_and_or_b32 v20, v21, 8, v20
	v_lshrrev_b32_e32 v21, 1, v76
	v_lshrrev_b32_e32 v20, 1, v20
	v_bfe_u32 v18, v18, 5, 2
	v_and_b32_e32 v22, 3, v76
	v_or_b32_e32 v20, v20, v18
	v_and_or_b32 v21, v21, 4, v22
	v_lshlrev_b32_e32 v20, 9, v20
	v_lshlrev_b32_e32 v21, 6, v21
	v_and_b32_e32 v22, 48, v52
	v_and_b32_e32 v23, 0xfffff0, v19
	v_lshlrev_b32_e32 v24, 1, v19
	v_or3_b32 v20, v20, v21, v22
	v_and_or_b32 v23, v24, 8, v23
	v_lshrrev_b32_e32 v23, 1, v23
	v_add_u32_e32 v191, 0, v20
	v_or_b32_e32 v18, v23, v18
	s_waitcnt vmcnt(0)
	v_lshlrev_b32_e32 v18, 9, v18
	v_or3_b32 v18, v18, v21, v22
	v_add_u32_e32 v192, 0, v18
	v_lshl_add_u64 v[178:179], s[42:43], 0, v[52:53]
	ds_write_b128 v191, v[2:5]
	v_lshlrev_b32_e32 v2, 8, v76
	v_and_b32_e32 v3, 0x70, v92
	v_bitop3_b32 v2, v52, v2, v3 bitop3:0xde
	v_add_u32_e32 v193, 0, v2
	v_lshlrev_b32_e32 v2, 8, v19
	v_bitop3_b32 v2, v52, v2, v3 bitop3:0xde
	ds_write_b128 v192, v[6:9]
	ds_write_b128 v193, v[10:13] offset:32768
	v_add_u32_e32 v194, 0, v2
	v_lshl_add_u32 v10, v182, 8, 0
	v_bitop3_b32 v2, v0, v184, s29 bitop3:0x78
	v_add_u32_e32 v195, v10, v2
	ds_write_b128 v194, v[14:17] offset:32768
	s_waitcnt lgkmcnt(0)
	s_barrier
; #define PSM(P0, P1, MN, AL, n) partialSM<WIN, ALIBI>(P0, P1, m_reg, MN, AL, dq + (float)TILE_UKB(n), I.nslope, lo, hi_, TILE_OK(n))
; template <int WIN, bool ALIBI>
; __device__ __forceinline__ void partialSM(f32x16& p0, f32x16& p1, float& m_reg, float& mn, float& alpha, float dub, float nslope, float lo, float hi_, bool tile_ok) {
;     ...
;   float pmax = p0[0];
; #pragma unroll
;   for (int r = 1; r < 16; ++r) pmax = fmaxf(pmax, p0[r]);
; #pragma unroll
;   for (int r = 0; r < 16; ++r) pmax = fmaxf(pmax, p1[r]);
;   { auto rr = __builtin_amdgcn_permlane32_swap(__float_as_uint(pmax), __float_as_uint(pmax), false, false);
;     pmax = fmaxf(__uint_as_float(rr[0]), __uint_as_float(rr[1])); }
;   if (__builtin_expect(__all(pmax - m_reg <= THR2), 1)) { mn = m_reg; alpha = 1.f; }
;   else { mn = fmaxf(m_reg, pmax); alpha = __builtin_amdgcn_exp2f(m_reg - mn); m_reg = mn; }
; #pragma unroll
;   for (int r = 0; r < 16; ++r) { p0[r] = p0[r] - mn; p1[r] = p1[r] - mn; }
; #pragma unroll
;   for (int r = 0; r < 16; ++r) p0[r] = __builtin_amdgcn_exp2f(p0[r]);
; template <int WIN, bool ALIBI, int EPI, bool SINK>
; __device__ __forceinline__ void attn_item(const Item& I, char* lds, int tid_in) {
;     ...
;   qkt(pA0, pA1, K_lds, qr, r32, hi); PSM(pA0, pA1, mnA, alA, 0);
;   SLOAD(SO, 1); if (2 < NT) SLOAD(SE, 2);
	ds_read_b128 v[2:5], v195 offset:32768
	ds_read_b128 v[6:9], v195 offset:40960
	s_waitcnt lgkmcnt(1)
	v_mfma_f32_32x32x16_bf16 v[34:49], v[2:5], v[102:105], 0
	v_and_b32_e32 v11, 0x70, v184
	v_bitop3_b32 v2, v0, v11, 32 bitop3:0x36
	v_add_u32_e32 v202, v10, v2
	v_lshlrev_b32_e32 v12, 3, v185
	v_and_b32_e32 v13, 0xc0, v184
	s_movk_i32 s29, 0xe0
	s_waitcnt lgkmcnt(0)
	v_mfma_f32_32x32x16_bf16 v[18:33], v[6:9], v[102:105], 0
	ds_read_b128 v[2:5], v202 offset:32768
	ds_read_b128 v[6:9], v202 offset:40960
	s_waitcnt lgkmcnt(1)
	v_mfma_f32_32x32x16_bf16 v[34:49], v[2:5], v[110:113], v[34:49]
	v_bitop3_b32 v2, v0, v11, 64 bitop3:0x36
	v_add_u32_e32 v201, v10, v2
	s_waitcnt lgkmcnt(0)
	v_mfma_f32_32x32x16_bf16 v[18:33], v[6:9], v[110:113], v[18:33]
	ds_read_b128 v[2:5], v201 offset:32768
	ds_read_b128 v[6:9], v201 offset:40960
	s_waitcnt lgkmcnt(1)
	v_mfma_f32_32x32x16_bf16 v[34:49], v[2:5], v[98:101], v[34:49]
	v_bitop3_b32 v2, v0, v11, s93 bitop3:0x36
	v_add_u32_e32 v200, v10, v2
	s_waitcnt lgkmcnt(0)
	v_mfma_f32_32x32x16_bf16 v[18:33], v[6:9], v[98:101], v[18:33]
	ds_read_b128 v[2:5], v200 offset:32768
	ds_read_b128 v[6:9], v200 offset:40960
	s_waitcnt lgkmcnt(1)
	v_mfma_f32_32x32x16_bf16 v[34:49], v[2:5], v[106:109], v[34:49]
	v_bitop3_b32 v2, v0, v11, s85 bitop3:0x36
	v_add_u32_e32 v197, v10, v2
	s_waitcnt lgkmcnt(0)
	v_mfma_f32_32x32x16_bf16 v[18:33], v[6:9], v[106:109], v[18:33]
	ds_read_b128 v[2:5], v197 offset:32768
	ds_read_b128 v[6:9], v197 offset:40960
	s_waitcnt lgkmcnt(1)
	v_mfma_f32_32x32x16_bf16 v[34:49], v[2:5], v[118:121], v[34:49]
	v_bitop3_b32 v2, v0, v11, s67 bitop3:0x36
	v_add_u32_e32 v196, v10, v2
	ds_read_b128 v[2:5], v196 offset:32768
	s_waitcnt lgkmcnt(1)
	v_mfma_f32_32x32x16_bf16 v[18:33], v[6:9], v[118:121], v[18:33]
	ds_read_b128 v[6:9], v196 offset:40960
	s_waitcnt lgkmcnt(1)
	v_mfma_f32_32x32x16_bf16 v[34:49], v[2:5], v[126:129], v[34:49]
	v_bitop3_b32 v2, v0, v11, s83 bitop3:0x36
	v_add_u32_e32 v198, v10, v2
	ds_read_b128 v[2:5], v198 offset:32768
	s_waitcnt lgkmcnt(1)
	v_mfma_f32_32x32x16_bf16 v[18:33], v[6:9], v[126:129], v[18:33]
	v_lshlrev_b32_e32 v7, 1, v92
	v_and_or_b32 v6, v12, 24, v13
	v_and_b32_e32 v7, 32, v7
	v_and_b32_e32 v8, 0x100, v12
	v_or3_b32 v77, v6, v7, v8
	ds_read_b128 v[6:9], v198 offset:40960
	v_add_u32_e32 v190, 0, v77
	s_waitcnt lgkmcnt(1)
	v_mfma_f32_32x32x16_bf16 v[34:49], v[2:5], v[114:117], v[34:49]
	v_bitop3_b32 v2, v0, v11, s29 bitop3:0x36
	v_add_u32_e32 v199, v10, v2
	ds_read_b128 v[2:5], v199 offset:32768
	ds_read_b128 v[54:57], v199 offset:40960
	v_add_u32_e32 v0, s27, v0
	s_waitcnt lgkmcnt(2)
	v_mfma_f32_32x32x16_bf16 v[18:33], v[6:9], v[114:117], v[18:33]
	s_waitcnt lgkmcnt(1)
	v_mfma_f32_32x32x16_bf16 v[34:49], v[2:5], v[122:125], v[34:49]
	v_mov_b64_e32 v[2:3], s[48:49]
	v_mov_b64_e32 v[16:17], s[62:63]
	v_mov_b64_e32 v[4:5], s[50:51]
	v_mov_b64_e32 v[6:7], s[52:53]
	v_mov_b64_e32 v[8:9], s[54:55]
	v_mov_b64_e32 v[10:11], s[56:57]
	v_mov_b64_e32 v[12:13], s[58:59]
	s_waitcnt lgkmcnt(0)
	v_mfma_f32_32x32x16_bf16 v[18:33], v[54:57], v[122:125], v[18:33]
	s_nop 2
	v_max_f32_e32 v54, v35, v35
	v_max_f32_e32 v55, v34, v34
	v_max_f32_e32 v54, v55, v54
	v_max3_f32 v54, v54, v36, v37
	v_max3_f32 v54, v54, v38, v39
	v_max3_f32 v54, v54, v40, v41
	v_max3_f32 v54, v54, v42, v43
	v_max3_f32 v54, v54, v44, v45
	v_max3_f32 v54, v54, v46, v47
	v_max3_f32 v54, v54, v48, v49
	v_max3_f32 v54, v54, v18, v19
	v_max3_f32 v54, v54, v20, v21
	v_max3_f32 v54, v54, v22, v23
	v_max3_f32 v54, v54, v24, v25
	v_max3_f32 v54, v54, v26, v27
	v_max3_f32 v54, v54, v28, v29
	v_max3_f32 v54, v54, v30, v31
	v_max3_f32 v70, v54, v32, v33
	v_mov_b32_e32 v54, v70
	s_nop 1
	v_permlane32_swap_b32_e32 v70, v54
	v_max_f32_e32 v78, v54, v54
	v_add_u32_e32 v54, 64, v72
	v_mad_i64_i32 v[54:55], s[30:31], v54, s89, v[50:51]
	v_lshl_add_u64 v[62:63], v[54:55], 0, v[52:53]
	v_add_u32_e32 v54, 0x60, v72
	v_mad_i64_i32 v[54:55], s[30:31], v54, s89, v[50:51]
	v_lshl_add_u64 v[64:65], v[54:55], 0, v[52:53]
	v_max_f32_e32 v79, v70, v70
	v_add_u32_e32 v70, 0x80, v72
	v_lshl_add_u64 v[54:55], v[62:63], 0, s[72:73]
	v_lshl_add_u64 v[58:59], v[64:65], 0, s[72:73]
	v_lshl_add_u64 v[62:63], v[62:63], 0, s[4:5]
	v_lshl_add_u64 v[66:67], v[64:65], 0, s[4:5]
	v_mad_i64_i32 v[70:71], s[30:31], v70, s89, v[50:51]
	v_add_u32_e32 v72, 0xa0, v72
	global_load_dwordx4 v[54:57], v[54:55], off
	s_nop 0
	global_load_dwordx4 v[58:61], v[58:59], off
	s_nop 0
	global_load_dwordx4 v[62:65], v[62:63], off
	s_nop 0
	global_load_dwordx4 v[66:69], v[66:67], off
	v_lshl_add_u64 v[70:71], v[70:71], 0, v[52:53]
	v_mad_i64_i32 v[50:51], s[30:31], v72, s89, v[50:51]
	v_lshl_add_u64 v[50:51], v[50:51], 0, v[52:53]
	v_lshl_add_u64 v[72:73], v[70:71], 0, s[72:73]
	v_lshl_add_u64 v[70:71], v[70:71], 0, s[4:5]
	v_lshl_add_u64 v[74:75], v[50:51], 0, s[72:73]
	global_load_dwordx4 v[130:133], v[72:73], off
	global_load_dwordx4 v[134:137], v[74:75], off
	v_lshl_add_u64 v[50:51], v[50:51], 0, s[4:5]
	global_load_dwordx4 v[138:141], v[70:71], off
	global_load_dwordx4 v[142:145], v[50:51], off
	v_max_f32_e32 v50, v79, v78
	v_add_f32_e32 v51, 0x7149f2ca, v50
	v_cmp_ge_f32_e32 vcc, s16, v51
	v_max_f32_e32 v50, 0xf149f2ca, v50
	s_cmp_eq_u64 vcc, exec
	v_sub_f32_e32 v51, 0xf149f2ca, v50
	s_cselect_b64 vcc, -1, 0
	v_mov_b32_e32 v70, 0xf149f2ca
	v_exp_f32_e32 v51, v51
	v_cndmask_b32_e32 v180, v50, v70, vcc
	v_sub_f32_e32 v34, v34, v180
	v_sub_f32_e32 v35, v35, v180
	v_sub_f32_e32 v36, v36, v180
	v_sub_f32_e32 v37, v37, v180
	v_sub_f32_e32 v38, v38, v180
	v_sub_f32_e32 v39, v39, v180
	v_sub_f32_e32 v40, v40, v180
	v_sub_f32_e32 v41, v41, v180
	v_sub_f32_e32 v42, v42, v180
	v_sub_f32_e32 v43, v43, v180
	v_sub_f32_e32 v44, v44, v180
	v_sub_f32_e32 v45, v45, v180
	v_sub_f32_e32 v46, v46, v180
	v_sub_f32_e32 v47, v47, v180
	v_sub_f32_e32 v48, v48, v180
	v_sub_f32_e32 v49, v49, v180
	v_exp_f32_e32 v166, v34
	v_exp_f32_e32 v177, v35
	v_exp_f32_e32 v167, v36
	v_exp_f32_e32 v176, v37
	v_exp_f32_e32 v168, v38
	v_exp_f32_e32 v175, v39
	v_exp_f32_e32 v169, v40
	v_exp_f32_e32 v174, v41
	v_exp_f32_e32 v162, v42
	v_exp_f32_e32 v173, v43
	v_exp_f32_e32 v163, v44
	v_exp_f32_e32 v172, v45
	v_exp_f32_e32 v164, v46
	v_exp_f32_e32 v171, v47
	v_exp_f32_e32 v165, v48
	v_exp_f32_e32 v170, v49
	s_waitcnt vmcnt(4)
; #define SBAR() __builtin_amdgcn_sched_barrier(0)
; #define SWRITE(b, i) do { *(LAS bf16x8*)(V_lds + (b) * SHM_V + vst0) = sr_[i].vs0; *(LAS bf16x8*)(V_lds + (b) * SHM_V + vst1) = sr_[i].vs1; const int kc = sc * 2; \
;     *(LAS bf16x8*)(K_lds + (b) * SHM_K + KSWZ(sr, kc)) = sr_[i].ks0; *(LAS bf16x8*)(K_lds + (b) * SHM_K + KSWZ(32 + sr, kc)) = sr_[i].ks1; } while (0)
; #define SWAIT() asm volatile("s_waitcnt vmcnt(4)" ::: "memory")
; __device__ __forceinline__ void finishSM(f32x16& p0, f32x16& p1, float alpha, float& l_reg, bf16x8& pa0, bf16x8& pa1, bf16x8& pa2, bf16x8& pa3) {
; #pragma unroll
;   for (int r = 0; r < 16; ++r) p1[r] = __builtin_amdgcn_exp2f(p1[r]);
;   float ps = 0;
; #pragma unroll
;   for (int r = 0; r < 16; ++r) ps += p0[r];
; #pragma unroll
;   for (int r = 0; r < 16; ++r) ps += p1[r];
;   { auto rr = __builtin_amdgcn_permlane32_swap(__float_as_uint(ps), __float_as_uint(ps), false, false);
;     ps = __uint_as_float(rr[0]) + __uint_as_float(rr[1]); }
;   l_reg = l_reg * alpha + ps;
;     ...
;   PK4(p0, 0, pa0); PK4(p0, 8, pa1); PK4(p1, 0, pa2); PK4(p1, 8, pa3);
; template <int WIN, bool ALIBI, int EPI, bool SINK>
; __device__ __forceinline__ void attn_item(const Item& I, char* lds, int tid_in) {
;     ...
;   SWAIT(); SWRITE(1, SO); __syncthreads();
;   for (int j = 1; j + 1 < NT; j += 2) {
;     SBAR(); qkt(pB0, pB1, K_lds + SHM_K, qr, r32, hi);
;     finishSM(pA0, pA1, alA, l_reg, pa0, pa1, pa2, pa3); SBAR();
	s_add_i32 s4, 0, 0x4000
	v_mov_b64_e32 v[14:15], s[60:61]
	v_cndmask_b32_e64 v203, v51, 1.0, vcc
	v_sub_f32_e32 v158, v18, v180
	v_sub_f32_e32 v159, v19, v180
	v_sub_f32_e32 v160, v20, v180
	v_sub_f32_e32 v161, v21, v180
	v_sub_f32_e32 v150, v22, v180
	v_sub_f32_e32 v151, v23, v180
	v_sub_f32_e32 v152, v24, v180
	v_sub_f32_e32 v153, v25, v180
	v_sub_f32_e32 v154, v26, v180
	v_sub_f32_e32 v155, v27, v180
	v_sub_f32_e32 v156, v28, v180
	v_sub_f32_e32 v157, v29, v180
	v_sub_f32_e32 v146, v30, v180
	v_sub_f32_e32 v147, v31, v180
	v_sub_f32_e32 v148, v32, v180
	v_sub_f32_e32 v149, v33, v180
	ds_write_b128 v191, v[54:57] offset:16384
	ds_write_b128 v192, v[58:61] offset:16384
	ds_write_b128 v193, v[62:65] offset:49152
	ds_write_b128 v194, v[66:69] offset:49152
	v_add_u32_e32 v189, s4, v77
	s_add_i32 s4, s46, 0x120
	v_mov_b64_e32 v[32:33], v[16:17]
	v_mov_b64_e32 v[48:49], v[16:17]
	v_mov_b64_e32 v[64:65], v[16:17]
	v_add_u32_e32 v204, s4, v76
	s_lshl_b32 s46, s28, 1
	v_mov_b64_e32 v[30:31], v[14:15]
	v_mov_b64_e32 v[28:29], v[12:13]
	v_mov_b64_e32 v[26:27], v[10:11]
	v_mov_b64_e32 v[24:25], v[8:9]
	v_mov_b64_e32 v[22:23], v[6:7]
	v_mov_b64_e32 v[20:21], v[4:5]
	v_mov_b64_e32 v[18:19], v[2:3]
	v_mov_b64_e32 v[46:47], v[14:15]
	v_mov_b64_e32 v[44:45], v[12:13]
	v_mov_b64_e32 v[42:43], v[10:11]
	v_mov_b64_e32 v[40:41], v[8:9]
	v_mov_b64_e32 v[38:39], v[6:7]
	v_mov_b64_e32 v[36:37], v[4:5]
	v_mov_b64_e32 v[34:35], v[2:3]
	v_mov_b64_e32 v[62:63], v[14:15]
	v_mov_b64_e32 v[60:61], v[12:13]
	v_mov_b64_e32 v[58:59], v[10:11]
	v_mov_b64_e32 v[56:57], v[8:9]
	v_mov_b64_e32 v[54:55], v[6:7]
	v_mov_b64_e32 v[52:53], v[4:5]
	v_mov_b64_e32 v[50:51], v[2:3]
	s_mov_b32 s54, 0x30000
	s_mov_b32 s55, 0x10000
	s_mov_b32 s58, 0x14000
	s_mov_b32 s59, 0x18000
	s_mov_b32 s63, 0x1c000
	s_mov_b32 s56, 0x24000
	s_mov_b32 s57, 0x28000
	s_waitcnt lgkmcnt(0)
	s_barrier
.LBB0_1111:
	ds_read_b128 v[66:69], v195 offset:49152
	ds_read_b128 v[70:73], v195 offset:57344
	ds_read_b128 v[206:209], v202 offset:49152
	ds_read_b128 v[210:213], v202 offset:57344
	v_add_f32_e32 v205, 0, v166
	v_add_f32_e32 v205, v177, v205
	s_waitcnt lgkmcnt(3)
	v_mfma_f32_32x32x16_bf16 v[82:97], v[66:69], v[102:105], 0
	v_add_f32_e32 v205, v167, v205
	v_add_f32_e32 v205, v176, v205
	v_add_f32_e32 v205, v168, v205
	v_add_f32_e32 v205, v175, v205
	v_add_f32_e32 v205, v169, v205
	v_add_f32_e32 v205, v174, v205
	v_add_f32_e32 v205, v162, v205
	s_waitcnt lgkmcnt(2)
	v_mfma_f32_32x32x16_bf16 v[66:81], v[70:73], v[102:105], 0
	v_add_f32_e32 v205, v173, v205
	v_add_f32_e32 v205, v163, v205
	v_add_f32_e32 v205, v172, v205
	v_exp_f32_e32 v158, v158
	v_add_f32_e32 v205, v164, v205
	v_exp_f32_e32 v159, v159
	v_add_f32_e32 v205, v171, v205
	s_waitcnt lgkmcnt(1)
	v_mfma_f32_32x32x16_bf16 v[82:97], v[206:209], v[110:113], v[82:97]
	v_exp_f32_e32 v160, v160
	v_add_f32_e32 v205, v165, v205
	v_exp_f32_e32 v161, v161
	v_add_f32_e32 v205, v170, v205
	v_exp_f32_e32 v150, v150
	v_add_f32_e32 v205, v158, v205
	v_exp_f32_e32 v151, v151
	s_waitcnt lgkmcnt(0)
	v_mfma_f32_32x32x16_bf16 v[66:81], v[210:213], v[110:113], v[66:81]
	ds_read_b128 v[206:209], v201 offset:49152
	ds_read_b128 v[210:213], v201 offset:57344
	v_add_f32_e32 v205, v159, v205
	v_exp_f32_e32 v152, v152
	v_add_f32_e32 v205, v160, v205
	v_exp_f32_e32 v153, v153
	v_add_f32_e32 v205, v161, v205
	v_exp_f32_e32 v154, v154
	s_waitcnt lgkmcnt(1)
	v_mfma_f32_32x32x16_bf16 v[82:97], v[206:209], v[98:101], v[82:97]
	v_add_f32_e32 v205, v150, v205
	v_exp_f32_e32 v155, v155
	v_add_f32_e32 v205, v151, v205
	v_exp_f32_e32 v156, v156
	v_add_f32_e32 v205, v152, v205
	v_exp_f32_e32 v157, v157
	v_add_f32_e32 v205, v153, v205
	s_waitcnt lgkmcnt(0)
	v_mfma_f32_32x32x16_bf16 v[66:81], v[210:213], v[98:101], v[66:81]
	ds_read_b128 v[206:209], v200 offset:49152
	ds_read_b128 v[210:213], v200 offset:57344
	v_exp_f32_e32 v146, v146
	v_add_f32_e32 v205, v154, v205
	v_exp_f32_e32 v147, v147
	v_add_f32_e32 v205, v155, v205
	v_exp_f32_e32 v148, v148
	v_add_f32_e32 v205, v156, v205
	s_waitcnt lgkmcnt(1)
	v_mfma_f32_32x32x16_bf16 v[82:97], v[206:209], v[106:109], v[82:97]
	v_exp_f32_e32 v149, v149
	v_add_f32_e32 v205, v157, v205
	v_add_f32_e32 v205, v146, v205
	v_add_f32_e32 v205, v147, v205
	v_add_f32_e32 v205, v148, v205
	s_waitcnt lgkmcnt(0)
	v_mfma_f32_32x32x16_bf16 v[66:81], v[210:213], v[106:109], v[66:81]
	ds_read_b128 v[206:209], v197 offset:49152
	ds_read_b128 v[210:213], v197 offset:57344
	s_waitcnt lgkmcnt(1)
	v_mfma_f32_32x32x16_bf16 v[82:97], v[206:209], v[118:121], v[82:97]
	s_waitcnt lgkmcnt(0)
	v_mfma_f32_32x32x16_bf16 v[66:81], v[210:213], v[118:121], v[66:81]
	ds_read_b128 v[206:209], v196 offset:49152
	ds_read_b128 v[210:213], v196 offset:57344
	s_waitcnt lgkmcnt(1)
	v_mfma_f32_32x32x16_bf16 v[82:97], v[206:209], v[126:129], v[82:97]
	s_waitcnt lgkmcnt(0)
	v_mfma_f32_32x32x16_bf16 v[66:81], v[210:213], v[126:129], v[66:81]
	ds_read_b128 v[206:209], v198 offset:49152
	ds_read_b128 v[210:213], v198 offset:57344
	s_waitcnt lgkmcnt(1)
	v_mfma_f32_32x32x16_bf16 v[82:97], v[206:209], v[114:117], v[82:97]
	s_waitcnt lgkmcnt(0)
	v_mfma_f32_32x32x16_bf16 v[66:81], v[210:213], v[114:117], v[66:81]
	ds_read_b128 v[206:209], v199 offset:49152
	ds_read_b128 v[210:213], v199 offset:57344
	v_cvt_pk_bf16_f32 v166, v166, v177
	v_cvt_pk_bf16_f32 v167, v167, v176
	v_cvt_pk_bf16_f32 v168, v168, v175
	v_cvt_pk_bf16_f32 v169, v169, v174
	v_cvt_pk_bf16_f32 v162, v162, v173
	v_cvt_pk_bf16_f32 v163, v163, v172
	s_waitcnt lgkmcnt(1)
	v_mfma_f32_32x32x16_bf16 v[82:97], v[206:209], v[122:125], v[82:97]
	v_add_f32_e32 v206, v149, v205
	v_mov_b32_e32 v207, v206
	s_nop 1
	v_permlane32_swap_b32_e32 v206, v207
	v_cvt_pk_bf16_f32 v164, v164, v171
	v_cvt_pk_bf16_f32 v165, v165, v170
	v_cvt_pk_bf16_f32 v170, v158, v159
	s_waitcnt lgkmcnt(0)
; #define SBAR() __builtin_amdgcn_sched_barrier(0)
; #define SWRITE(b, i) do { *(LAS bf16x8*)(V_lds + (b) * SHM_V + vst0) = sr_[i].vs0; *(LAS bf16x8*)(V_lds + (b) * SHM_V + vst1) = sr_[i].vs1; const int kc = sc * 2; \
;     *(LAS bf16x8*)(K_lds + (b) * SHM_K + KSWZ(sr, kc)) = sr_[i].ks0; *(LAS bf16x8*)(K_lds + (b) * SHM_K + KSWZ(32 + sr, kc)) = sr_[i].ks1; } while (0)
; #define SWAIT() asm volatile("s_waitcnt vmcnt(4)" ::: "memory")
; template <bool ALIBI>
; __device__ __forceinline__ void pv_psm(f32x16* o, int vb, bf16x8 pa0, bf16x8 pa1, bf16x8 pa2, bf16x8 pa3, f32x16& p0, f32x16& p1, float& m_reg, float& mn, float& alpha, float dub, float nslope) {
;   pv_one<0>(o[0], vb, pa0, pa1, pa2, pa3);
;   if (ALIBI) {
; #pragma unroll
;     for (int r = 0; r < 16; ++r) { const float c = (float)((r & 3) + 8 * (r >> 2)); p0[r] = fmaf(fabsf(dub + c), nslope, p0[r]); p1[r] = fmaf(fabsf(dub + (c + 32.f)), nslope, p1[r]); } }
;   float pmax = p0[0];
; #pragma unroll
;   for (int r = 1; r < 16; ++r) pmax = fmaxf(pmax, p0[r]);
;   pv_one<1>(o[1], vb, pa0, pa1, pa2, pa3);
; #pragma unroll
;   for (int r = 0; r < 16; ++r) pmax = fmaxf(pmax, p1[r]);
;   { auto rr = __builtin_amdgcn_permlane32_swap(__float_as_uint(pmax), __float_as_uint(pmax), false, false);
;     pmax = fmaxf(__uint_as_float(rr[0]), __uint_as_float(rr[1])); }
;   { const bool keep = __all(pmax - m_reg <= THR2); const float mnew = fmaxf(m_reg, pmax); mn = keep ? m_reg : mnew; alpha = __builtin_amdgcn_exp2f(m_reg - mn); m_reg = mn; }
; #pragma unroll
;   for (int r = 0; r < 16; ++r) p0[r] = p0[r] - mn;
;   pv_one<2>(o[2], vb, pa0, pa1, pa2, pa3);
; #pragma unroll
;   for (int r = 0; r < 16; ++r) p1[r] = p1[r] - mn;
; #pragma unroll
;   for (int r = 0; r < 8; ++r) p0[r] = __builtin_amdgcn_exp2f(p0[r]);
;   pv_one<3>(o[3], vb, pa0, pa1, pa2, pa3);
; #pragma unroll
;   for (int r = 8; r < 16; ++r) p0[r] = __builtin_amdgcn_exp2f(p0[r]);
; }
; template <int WIN, bool ALIBI, int EPI, bool SINK>
; __device__ __forceinline__ void attn_item(const Item& I, char* lds, int tid_in) {
;     ...
;     SLOAD(SO, j + 2); SBAR();
;     pv_psm<ALIBI>(o, vb0, pa0, pa1, pa2, pa3, pB0, pB1, m_reg, mnB, alB, dq + (float)TILE_UKB(j), I.nslope);
;     __syncthreads(); SWAIT(); SWRITE(0, SE);
	v_mfma_f32_32x32x16_bf16 v[66:81], v[210:213], v[122:125], v[66:81]
	v_cvt_pk_bf16_f32 v171, v160, v161
	v_cvt_pk_bf16_f32 v172, v150, v151
	v_cvt_pk_bf16_f32 v173, v152, v153
	v_cvt_pk_bf16_f32 v174, v154, v155
	v_cvt_pk_bf16_f32 v175, v156, v157
	v_cvt_pk_bf16_f32 v176, v146, v147
	v_cvt_pk_bf16_f32 v177, v148, v149
	v_permlane32_swap_b32_e32 v166, v168
	v_permlane32_swap_b32_e32 v167, v169
	v_permlane32_swap_b32_e32 v162, v164
	v_permlane32_swap_b32_e32 v163, v165
	v_permlane32_swap_b32_e32 v170, v172
	v_permlane32_swap_b32_e32 v171, v173
	v_permlane32_swap_b32_e32 v174, v176
	v_permlane32_swap_b32_e32 v175, v177
	v_add_u32_e32 v146, 0xffffffa0, v204
	v_mad_i64_i32 v[154:155], s[4:5], v146, s89, v[178:179]
	v_subrev_u32_e32 v146, 64, v204
	v_mad_i64_i32 v[156:157], s[4:5], v146, s89, v[178:179]
	s_lshl_b32 s72, s26, 1
	s_mov_b32 s47, s73
	v_lshl_add_u64 v[146:147], v[154:155], 0, s[72:73]
	v_lshl_add_u64 v[150:151], v[156:157], 0, s[72:73]
	v_lshl_add_u64 v[154:155], v[154:155], 0, s[46:47]
	v_lshl_add_u64 v[158:159], v[156:157], 0, s[46:47]
	global_load_dwordx4 v[146:149], v[146:147], off
	s_nop 0
	global_load_dwordx4 v[150:153], v[150:151], off
	s_nop 0
	global_load_dwordx4 v[154:157], v[154:155], off
	s_nop 0
	global_load_dwordx4 v[158:161], v[158:159], off
	ds_read_b64_tr_b16 v[208:209], v190 offset:0
	ds_read_b64_tr_b16 v[210:211], v190 offset:0x800
	ds_read_b64_tr_b16 v[212:213], v190 offset:0x1000
	ds_read_b64_tr_b16 v[214:215], v190 offset:0x1800
	ds_read_b64_tr_b16 v[216:217], v190 offset:0x2000
	ds_read_b64_tr_b16 v[218:219], v190 offset:0x2800
	ds_read_b64_tr_b16 v[220:221], v190 offset:0x3000
	ds_read_b64_tr_b16 v[222:223], v190 offset:0x3800
	v_max_f32_e32 v205, v83, v83
	s_waitcnt lgkmcnt(0)
	s_nop 0
	v_mfma_f32_32x32x16_bf16 v[50:65], v[166:169], v[208:211], v[50:65]
	v_max_f32_e32 v208, v82, v82
	v_max_f32_e32 v205, v208, v205
	ds_read_b64_tr_b16 v[208:209], v190 offset:0x200
	ds_read_b64_tr_b16 v[210:211], v190 offset:0xa00
	v_max3_f32 v205, v205, v84, v85
	v_max3_f32 v205, v205, v86, v87
	v_max3_f32 v205, v205, v88, v89
	v_mfma_f32_32x32x16_bf16 v[50:65], v[162:165], v[212:215], v[50:65]
	ds_read_b64_tr_b16 v[212:213], v190 offset:0x1200
	ds_read_b64_tr_b16 v[214:215], v190 offset:0x1a00
	v_max3_f32 v205, v205, v90, v91
	v_max3_f32 v205, v205, v92, v93
	v_max3_f32 v205, v205, v94, v95
	v_max3_f32 v205, v205, v96, v97
	v_max3_f32 v205, v205, v66, v67
	v_mfma_f32_32x32x16_bf16 v[50:65], v[170:173], v[216:219], v[50:65]
	ds_read_b64_tr_b16 v[216:217], v190 offset:0x2200
	ds_read_b64_tr_b16 v[218:219], v190 offset:0x2a00
	v_max3_f32 v205, v205, v68, v69
	v_max3_f32 v205, v205, v70, v71
	v_max3_f32 v205, v205, v72, v73
	v_max3_f32 v205, v205, v74, v75
	v_max3_f32 v205, v205, v76, v77
	v_mfma_f32_32x32x16_bf16 v[50:65], v[174:177], v[220:223], v[50:65]
	ds_read_b64_tr_b16 v[220:221], v190 offset:0x3200
	ds_read_b64_tr_b16 v[222:223], v190 offset:0x3a00
	v_max3_f32 v205, v205, v78, v79
	s_waitcnt lgkmcnt(0)
	v_max3_f32 v205, v205, v80, v81
	v_mfma_f32_32x32x16_bf16 v[34:49], v[166:169], v[208:211], v[34:49]
	ds_read_b64_tr_b16 v[210:211], v190 offset:0x400
	v_mov_b32_e32 v208, v205
	s_nop 1
	v_permlane32_swap_b32_e32 v205, v208
	v_max_f32_e32 v208, v208, v208
	v_max_f32_e32 v205, v205, v205
	v_max_f32_e32 v205, v205, v208
	v_mfma_f32_32x32x16_bf16 v[34:49], v[162:165], v[212:215], v[34:49]
	ds_read_b64_tr_b16 v[212:213], v190 offset:0xc00
	ds_read_b64_tr_b16 v[214:215], v190 offset:0x1400
	v_sub_f32_e32 v208, v205, v180
	v_cmp_ge_f32_e32 vcc, s16, v208
	s_cmp_eq_u64 vcc, exec
	v_max_f32_e32 v208, v180, v180
	s_cselect_b64 vcc, -1, 0
	v_mfma_f32_32x32x16_bf16 v[34:49], v[170:173], v[216:219], v[34:49]
	ds_read_b64_tr_b16 v[216:217], v190 offset:0x1c00
	ds_read_b64_tr_b16 v[218:219], v190 offset:0x2400
	v_max_f32_e32 v205, v208, v205
	v_cndmask_b32_e32 v205, v205, v180, vcc
	v_sub_f32_e32 v180, v180, v205
	v_exp_f32_e32 v208, v180
	v_mfma_f32_32x32x16_bf16 v[34:49], v[174:177], v[220:223], v[34:49]
	ds_read_b64_tr_b16 v[220:221], v190 offset:0x2c00
	ds_read_b64_tr_b16 v[240:241], v190 offset:0x3400
	ds_read_b64_tr_b16 v[242:243], v190 offset:0x3c00
	v_cmp_gt_f32_e32 vcc, 1.0, v208
	s_waitcnt lgkmcnt(0)
	s_nop 0
	v_mfma_f32_32x32x16_bf16 v[18:33], v[166:169], v[210:213], v[18:33]
	ds_read_b64_tr_b16 v[210:211], v190 offset:0x600
	ds_read_b64_tr_b16 v[212:213], v190 offset:0xe00
	v_mfma_f32_32x32x16_bf16 v[18:33], v[162:165], v[214:217], v[18:33]
	ds_read_b64_tr_b16 v[214:215], v190 offset:0x1600
	ds_read_b64_tr_b16 v[216:217], v190 offset:0x1e00
	v_mfma_f32_32x32x16_bf16 v[18:33], v[170:173], v[218:221], v[18:33]
	ds_read_b64_tr_b16 v[218:219], v190 offset:0x2600
	ds_read_b64_tr_b16 v[220:221], v190 offset:0x2e00
	v_mfma_f32_32x32x16_bf16 v[18:33], v[174:177], v[240:243], v[18:33]
	ds_read_b64_tr_b16 v[240:241], v190 offset:0x3600
	ds_read_b64_tr_b16 v[242:243], v190 offset:0x3e00
	s_nop 0
	s_waitcnt lgkmcnt(0)
	s_barrier
; #define SWRITE(b, i) do { *(LAS bf16x8*)(V_lds + (b) * SHM_V + vst0) = sr_[i].vs0; *(LAS bf16x8*)(V_lds + (b) * SHM_V + vst1) = sr_[i].vs1; const int kc = sc * 2; \
;     *(LAS bf16x8*)(K_lds + (b) * SHM_K + KSWZ(sr, kc)) = sr_[i].ks0; *(LAS bf16x8*)(K_lds + (b) * SHM_K + KSWZ(32 + sr, kc)) = sr_[i].ks1; } while (0)
; #define SWAIT() asm volatile("s_waitcnt vmcnt(4)" ::: "memory")
; #define RESC(a) do { if (__any((a) < 1.f)) { if (hi == 0) al_l[r32] = (a); asm volatile("s_waitcnt lgkmcnt(0)" ::: "memory"); \
;     _Pragma("unroll") for (int d = 0; d < 4; ++d) _Pragma("unroll") for (int r = 0; r < 16; ++r) o[d][r] *= al_l[crow(r, hi)]; } } while (0)
; template <int WIN, bool ALIBI, int EPI, bool SINK>
; __device__ __forceinline__ void attn_item(const Item& I, char* lds, int tid_in) {
;     ...
;     __syncthreads(); SWAIT(); SWRITE(0, SE);
;     RESC(alB); __syncthreads();
	v_mfma_f32_32x32x16_bf16 v[2:17], v[166:169], v[210:213], v[2:17]
	s_waitcnt vmcnt(4)
	ds_write_b128 v191, v[130:133]
	ds_write_b128 v192, v[134:137]
	ds_write_b128 v193, v[138:141] offset:32768
	ds_write_b128 v194, v[142:145] offset:32768
	v_mfma_f32_32x32x16_bf16 v[2:17], v[162:165], v[214:217], v[2:17]
	v_mfma_f32_32x32x16_bf16 v[2:17], v[170:173], v[218:221], v[2:17]
	v_mfma_f32_32x32x16_bf16 v[2:17], v[174:177], v[240:243], v[2:17]
	s_cbranch_vccz .LBB0_1115
	s_and_saveexec_b64 s[4:5], s[36:37]
	ds_write_b32 v187, v208 offset:128
	s_or_b64 exec, exec, s[4:5]
	s_waitcnt lgkmcnt(0)
	ds_read_b128 v[162:165], v0 offset:224
	ds_read_b128 v[166:169], v0 offset:192
	ds_read_b128 v[170:173], v0 offset:160
	ds_read_b128 v[174:177], v0 offset:128
	s_waitcnt lgkmcnt(3)
	v_pk_mul_f32 v[64:65], v[64:65], v[164:165]
	s_waitcnt lgkmcnt(2)
	v_pk_mul_f32 v[60:61], v[60:61], v[168:169]
	s_waitcnt lgkmcnt(1)
	v_pk_mul_f32 v[56:57], v[56:57], v[172:173]
	s_waitcnt lgkmcnt(0)
	v_pk_mul_f32 v[52:53], v[52:53], v[176:177]
	v_pk_mul_f32 v[62:63], v[62:63], v[162:163]
	v_pk_mul_f32 v[58:59], v[58:59], v[166:167]
	v_pk_mul_f32 v[54:55], v[54:55], v[170:171]
	v_pk_mul_f32 v[50:51], v[50:51], v[174:175]
	v_pk_mul_f32 v[48:49], v[48:49], v[164:165]
	v_pk_mul_f32 v[44:45], v[44:45], v[168:169]
	v_pk_mul_f32 v[40:41], v[40:41], v[172:173]
	v_pk_mul_f32 v[36:37], v[36:37], v[176:177]
	v_pk_mul_f32 v[46:47], v[46:47], v[162:163]
	v_pk_mul_f32 v[42:43], v[42:43], v[166:167]
	v_pk_mul_f32 v[38:39], v[38:39], v[170:171]
	v_pk_mul_f32 v[34:35], v[34:35], v[174:175]
	v_pk_mul_f32 v[32:33], v[32:33], v[164:165]
	v_pk_mul_f32 v[28:29], v[28:29], v[168:169]
	v_pk_mul_f32 v[24:25], v[24:25], v[172:173]
	v_pk_mul_f32 v[20:21], v[20:21], v[176:177]
	v_pk_mul_f32 v[30:31], v[30:31], v[162:163]
	v_pk_mul_f32 v[26:27], v[26:27], v[166:167]
	v_pk_mul_f32 v[22:23], v[22:23], v[170:171]
	v_pk_mul_f32 v[18:19], v[18:19], v[174:175]
	v_pk_mul_f32 v[16:17], v[16:17], v[164:165]
	v_pk_mul_f32 v[12:13], v[12:13], v[168:169]
	v_pk_mul_f32 v[8:9], v[8:9], v[172:173]
	v_pk_mul_f32 v[4:5], v[4:5], v[176:177]
	v_pk_mul_f32 v[14:15], v[14:15], v[162:163]
	v_pk_mul_f32 v[10:11], v[10:11], v[166:167]
	v_pk_mul_f32 v[6:7], v[6:7], v[170:171]
	v_pk_mul_f32 v[2:3], v[2:3], v[174:175]

; __device__ __forceinline__ unsigned xb_ld(unsigned* p)              { return __hip_atomic_load(p, __ATOMIC_RELAXED, __HIP_MEMORY_SCOPE_AGENT); }
; __device__ __forceinline__ unsigned xb_add(unsigned* p, unsigned v) { return __hip_atomic_fetch_add(p, v, __ATOMIC_RELAXED, __HIP_MEMORY_SCOPE_AGENT); }
; #define XB_SPIN(cond, bar) do { unsigned _sp = 0; while (cond) { __builtin_amdgcn_s_sleep(1); \
;     if ((++_sp & 255u) == 0u) { if (xb_ld(&(bar)[XB_TMO])) break; if (_sp > XB_SPIN_CAP) { atomicAdd(&(bar)[XB_TMO], 1u); break; } } } } while (0)
; __device__ __forceinline__ void xcd_barrier(const XcdBarrier& b) {
;     ...
;         const unsigned old = xb_add(&bar[XB_XSUB(b.x)], 1u);
;         const unsigned gen = old / nloc;
;         if (old + 1u == (gen + 1u) * nloc) {
;             __builtin_amdgcn_fence(__ATOMIC_RELEASE, "agent");
;             asm volatile("s_waitcnt vmcnt(0)" ::: "memory");
;             const unsigned og = xb_add(&bar[XB_TOP], 1u);
;             const unsigned tg = og / nx;
;             if (og + 1u == (tg + 1u) * nx) xb_add(&bar[XB_TOPGEN], 1u);
;             else XB_SPIN(xb_ld(&bar[XB_TOPGEN]) == tg, bar);
;             __builtin_amdgcn_fence(__ATOMIC_ACQUIRE, "agent");
;             xb_add(&bar[XB_XGEN(b.x)], 1u);
;             asm volatile("s_waitcnt vmcnt(0)" ::: "memory");
;         } else {
;             XB_SPIN(xb_ld(&bar[XB_XGEN(b.x)]) == gen, bar);
;             __builtin_amdgcn_fence(__ATOMIC_ACQUIRE, "agent");
;             asm volatile("s_waitcnt vmcnt(0)" ::: "memory");
;         }
.LBB0_1162:
	s_or_b64 exec, exec, s[6:7]
	s_waitcnt vmcnt(0)
	buffer_inv sc1
.LBB0_1163:
	s_andn2_saveexec_b64 s[4:5], s[4:5]
	s_cbranch_execz .LBB0_1183
	s_mov_b64 s[4:5], exec
	buffer_wbl2 sc1
	s_waitcnt lgkmcnt(0)
	s_waitcnt vmcnt(0)
	v_mbcnt_lo_u32_b32 v0, s4, 0
	v_mbcnt_hi_u32_b32 v0, s5, v0
	v_cmp_eq_u32_e32 vcc, 0, v0
	s_and_saveexec_b64 s[6:7], vcc
	s_cbranch_execz .LBB0_1166
	s_bcnt1_i32_b64 s4, s[4:5]
	v_mov_b32_e32 v3, s4
	v_readlane_b32 s4, v255, 17
	v_readlane_b32 s5, v255, 18
	s_nop 4
	global_atomic_add v3, v1, v3, s[4:5] sc0

; __device__ __forceinline__ unsigned xb_ld(unsigned* p)              { return __hip_atomic_load(p, __ATOMIC_RELAXED, __HIP_MEMORY_SCOPE_AGENT); }
; __device__ __forceinline__ unsigned xb_add(unsigned* p, unsigned v) { return __hip_atomic_fetch_add(p, v, __ATOMIC_RELAXED, __HIP_MEMORY_SCOPE_AGENT); }
; #define XB_SPIN(cond, bar) do { unsigned _sp = 0; while (cond) { __builtin_amdgcn_s_sleep(1); \
;     if ((++_sp & 255u) == 0u) { if (xb_ld(&(bar)[XB_TMO])) break; if (_sp > XB_SPIN_CAP) { atomicAdd(&(bar)[XB_TMO], 1u); break; } } } } while (0)
; __device__ __forceinline__ void xcd_barrier(const XcdBarrier& b) {
;     ...
;         const unsigned old = xb_add(&bar[XB_XSUB(b.x)], 1u);
;         const unsigned gen = old / nloc;
;         if (old + 1u == (gen + 1u) * nloc) {
;             __builtin_amdgcn_fence(__ATOMIC_RELEASE, "agent");
;             asm volatile("s_waitcnt vmcnt(0)" ::: "memory");
;             const unsigned og = xb_add(&bar[XB_TOP], 1u);
;             const unsigned tg = og / nx;
;             if (og + 1u == (tg + 1u) * nx) xb_add(&bar[XB_TOPGEN], 1u);
;             else XB_SPIN(xb_ld(&bar[XB_TOPGEN]) == tg, bar);
;             __builtin_amdgcn_fence(__ATOMIC_ACQUIRE, "agent");
;             xb_add(&bar[XB_XGEN(b.x)], 1u);
;             asm volatile("s_waitcnt vmcnt(0)" ::: "memory");
;         } else {
;             XB_SPIN(xb_ld(&bar[XB_XGEN(b.x)]) == gen, bar);
;             __builtin_amdgcn_fence(__ATOMIC_ACQUIRE, "agent");
;             asm volatile("s_waitcnt vmcnt(0)" ::: "memory");
;         }
.LBB0_1256:
	s_or_b64 exec, exec, s[6:7]
	s_waitcnt vmcnt(0)
	buffer_inv sc1
.LBB0_1257:
	s_andn2_saveexec_b64 s[4:5], s[4:5]
	s_cbranch_execz .LBB0_1277
	s_mov_b64 s[4:5], exec
	buffer_wbl2 sc1
	s_waitcnt lgkmcnt(0)
	s_waitcnt vmcnt(0)
	v_mbcnt_lo_u32_b32 v0, s4, 0
	v_mbcnt_hi_u32_b32 v0, s5, v0
	v_cmp_eq_u32_e32 vcc, 0, v0
	s_and_saveexec_b64 s[6:7], vcc
	s_cbranch_execz .LBB0_1260
	s_bcnt1_i32_b64 s4, s[4:5]
	v_mov_b32_e32 v3, s4
	v_readlane_b32 s4, v255, 17
	v_readlane_b32 s5, v255, 18
	s_nop 4
	global_atomic_add v3, v1, v3, s[4:5] sc0

; #define LAS __attribute__((address_space(3)))
; __device__ __forceinline__ bf16_t* wt_ptr(const Frame& F, int layer, size_t off) { return (bf16_t*)(F.ws + WS_WT + (size_t)layer * LWT + off); }
; __device__ __forceinline__ void transpose_item(const float* W, int K, int N, bf16_t* WT, int dest_row0, int k0, int n0, LAS float* scr, int lane) {
;     float wv[32];
; #pragma unroll
;     for (int i = 0; i < 32; ++i) { const int kk = 2 * i + (lane >> 5); wv[i] = LDG(float, W + (size_t)(k0 + kk) * N + n0 + (lane & 31)); }
; #pragma unroll
;     for (int i = 0; i < 32; ++i) { const int kk = 2 * i + (lane >> 5); scr[kk * 33 + (lane & 31)] = wv[i]; }
;     asm volatile("s_waitcnt lgkmcnt(0)" ::: "memory");
; __device__ __forceinline__ void phase_weights(const Frame& F0, int lmask, int cu0, int ncu, int pm) {
;     ...
;             { const int nblk = DM / 32, kb = r / nblk, nb = r % nblk; transpose_item(wdn, DFF, DM, wt_ptr(F, layer, WT_DOWN), 32 * nb, 64 * kb, 32 * nb, scr, F.lane); }
.LBB0_1394:
	s_add_i32 s6, s9, 0xfffff400
	s_cmpk_gt_u32 s9, 0x13ff
	s_cbranch_scc0 .LBB0_1400
	s_cmpk_gt_u32 s6, 0x32ff
	s_cbranch_scc0 .LBB0_1397
	s_and_b32 s4, s6, 0x7fffffc0
	s_addk_i32 s4, 0xcd00
	s_and_b32 s7, s8, 0x7e0
	v_add_u32_e32 v18, s4, v20
	s_lshl_b32 s72, s7, 2
	v_ashrrev_i32_e32 v19, 31, v18
	v_lshl_add_u64 v[28:29], v[10:11], 0, s[72:73]
	v_lshlrev_b64 v[18:19], 13, v[18:19]
	v_lshl_add_u64 v[18:19], v[28:29], 0, v[18:19]
	v_add_co_u32_e32 v28, vcc, 0x4000, v18
	global_load_dword v27, v[18:19], off
	s_nop 0
	v_addc_co_u32_e32 v29, vcc, 0, v19, vcc
	global_load_dword v30, v[28:29], off
	v_add_co_u32_e32 v28, vcc, 0x8000, v18
	s_mov_b32 s5, 0x34000
	s_nop 0
	v_addc_co_u32_e32 v29, vcc, 0, v19, vcc
	global_load_dword v31, v[28:29], off
	v_add_co_u32_e32 v28, vcc, s3, v18
	s_nop 1
	v_addc_co_u32_e32 v29, vcc, 0, v19, vcc
	global_load_dword v32, v[28:29], off
	v_add_co_u32_e32 v28, vcc, s55, v18
	s_nop 1
	v_addc_co_u32_e32 v29, vcc, 0, v19, vcc
	global_load_dword v33, v[28:29], off
	v_add_co_u32_e32 v28, vcc, s58, v18
	s_nop 1
	v_addc_co_u32_e32 v29, vcc, 0, v19, vcc
	global_load_dword v34, v[28:29], off
	v_add_co_u32_e32 v28, vcc, s59, v18
	s_nop 1
	v_addc_co_u32_e32 v29, vcc, 0, v19, vcc
	global_load_dword v35, v[28:29], off
	v_add_co_u32_e32 v28, vcc, s63, v18
	s_nop 1
	v_addc_co_u32_e32 v29, vcc, 0, v19, vcc
	global_load_dword v36, v[28:29], off
	v_add_co_u32_e32 v28, vcc, s66, v18
	s_nop 1
	v_addc_co_u32_e32 v29, vcc, 0, v19, vcc
	global_load_dword v37, v[28:29], off
	v_add_co_u32_e32 v28, vcc, s56, v18
	s_nop 1
	v_addc_co_u32_e32 v29, vcc, 0, v19, vcc
	global_load_dword v38, v[28:29], off
	v_add_co_u32_e32 v28, vcc, s57, v18
	s_nop 1
	v_addc_co_u32_e32 v29, vcc, 0, v19, vcc
	global_load_dword v39, v[28:29], off
	v_add_co_u32_e32 v28, vcc, s94, v18
	s_nop 1
	v_addc_co_u32_e32 v29, vcc, 0, v19, vcc
	global_load_dword v40, v[28:29], off
	v_add_co_u32_e32 v28, vcc, s54, v18
	s_nop 1
	v_addc_co_u32_e32 v29, vcc, 0, v19, vcc
	global_load_dword v41, v[28:29], off
	v_add_co_u32_e32 v28, vcc, s5, v18
	s_mov_b32 s5, 0x38000
	s_nop 0
	v_addc_co_u32_e32 v29, vcc, 0, v19, vcc
	global_load_dword v42, v[28:29], off
	v_add_co_u32_e32 v28, vcc, s5, v18
	s_mov_b32 s5, 0x3c000
	s_nop 0
	v_addc_co_u32_e32 v29, vcc, 0, v19, vcc
	global_load_dword v43, v[28:29], off
	v_add_co_u32_e32 v28, vcc, s5, v18
	s_mov_b32 s5, 0x40000
	s_nop 0
	v_addc_co_u32_e32 v29, vcc, 0, v19, vcc
	global_load_dword v44, v[28:29], off
	v_add_co_u32_e32 v28, vcc, s5, v18
	s_mov_b32 s5, 0x44000
	s_nop 0
	v_addc_co_u32_e32 v29, vcc, 0, v19, vcc
	global_load_dword v45, v[28:29], off
	v_add_co_u32_e32 v28, vcc, s5, v18
	s_mov_b32 s5, 0x48000
	s_nop 0
	v_addc_co_u32_e32 v29, vcc, 0, v19, vcc
	global_load_dword v46, v[28:29], off
	v_add_co_u32_e32 v28, vcc, s5, v18
	s_mov_b32 s5, 0x4c000
	s_nop 0
	v_addc_co_u32_e32 v29, vcc, 0, v19, vcc
	global_load_dword v47, v[28:29], off
	v_add_co_u32_e32 v28, vcc, s5, v18
	s_mov_b32 s5, 0x50000
	s_nop 0
	v_addc_co_u32_e32 v29, vcc, 0, v19, vcc
	global_load_dword v48, v[28:29], off
	v_add_co_u32_e32 v28, vcc, s5, v18
	s_mov_b32 s5, s73
	s_nop 0
	v_addc_co_u32_e32 v29, vcc, 0, v19, vcc
	global_load_dword v49, v[28:29], off
	v_add_co_u32_e32 v28, vcc, s70, v18
	s_nop 1
	v_addc_co_u32_e32 v29, vcc, 0, v19, vcc
	global_load_dword v50, v[28:29], off
	v_add_co_u32_e32 v28, vcc, s71, v18
	s_nop 1
	v_addc_co_u32_e32 v29, vcc, 0, v19, vcc
	global_load_dword v51, v[28:29], off
	v_add_co_u32_e32 v28, vcc, s18, v18
	s_nop 1
	v_addc_co_u32_e32 v29, vcc, 0, v19, vcc
	global_load_dword v52, v[28:29], off
	v_add_co_u32_e32 v28, vcc, s19, v18
	s_nop 1
	v_addc_co_u32_e32 v29, vcc, 0, v19, vcc
	global_load_dword v53, v[28:29], off
	v_add_co_u32_e32 v28, vcc, s10, v18
	s_nop 1
	v_addc_co_u32_e32 v29, vcc, 0, v19, vcc
	global_load_dword v54, v[28:29], off
	v_add_co_u32_e32 v28, vcc, s11, v18
	s_nop 1
	v_addc_co_u32_e32 v29, vcc, 0, v19, vcc
	global_load_dword v55, v[28:29], off
	v_add_co_u32_e32 v28, vcc, s20, v18
	s_nop 1
	v_addc_co_u32_e32 v29, vcc, 0, v19, vcc
	global_load_dword v56, v[28:29], off
	v_add_co_u32_e32 v28, vcc, s21, v18
	s_nop 1
	v_addc_co_u32_e32 v29, vcc, 0, v19, vcc
	global_load_dword v57, v[28:29], off
	v_add_co_u32_e32 v28, vcc, s22, v18
	s_nop 1
	v_addc_co_u32_e32 v29, vcc, 0, v19, vcc
	global_load_dword v58, v[28:29], off
	v_add_co_u32_e32 v28, vcc, s23, v18
	s_nop 1
	v_addc_co_u32_e32 v29, vcc, 0, v19, vcc
	v_add_co_u32_e32 v18, vcc, s14, v18
	global_load_dword v28, v[28:29], off
	s_nop 0
	v_addc_co_u32_e32 v19, vcc, 0, v19, vcc
	global_load_dword v18, v[18:19], off
	v_add_u32_e32 v19, 0x400, v21
	s_waitcnt vmcnt(0)
	ds_write2_b32 v21, v27, v30 offset1:66
	ds_write2_b32 v21, v31, v32 offset0:132 offset1:198
	ds_write2_b32 v19, v33, v34 offset0:8 offset1:74
	ds_write2_b32 v19, v35, v36 offset0:140 offset1:206
	v_add_u32_e32 v19, 0x800, v21
	ds_write2_b32 v19, v37, v38 offset0:16 offset1:82
	ds_write2_b32 v19, v39, v40 offset0:148 offset1:214
	v_add_u32_e32 v19, 0xc00, v21
	ds_write2_b32 v19, v41, v42 offset0:24 offset1:90
	ds_write2_b32 v19, v43, v44 offset0:156 offset1:222
	v_add_u32_e32 v19, 0x1000, v21
	ds_write2_b32 v19, v45, v46 offset0:32 offset1:98
	ds_write2_b32 v19, v47, v48 offset0:164 offset1:230
	v_add_u32_e32 v19, 0x1400, v21
	ds_write2_b32 v19, v49, v50 offset0:40 offset1:106
	ds_write2_b32 v19, v51, v52 offset0:172 offset1:238
	v_add_u32_e32 v19, 0x1800, v21
	ds_write2_b32 v19, v53, v54 offset0:48 offset1:114
	ds_write2_b32 v19, v55, v56 offset0:180 offset1:246
	v_add_u32_e32 v19, 0x1c00, v21
	ds_write2_b32 v19, v57, v58 offset0:56 offset1:122
	ds_write2_b32 v19, v28, v18 offset0:188 offset1:254
	s_waitcnt lgkmcnt(0)
; #define LAS __attribute__((address_space(3)))
; __device__ __forceinline__ unsigned cvt_pk_bf16(float lo, float hi) { unsigned r; asm volatile("v_cvt_pk_bf16_f32 %0, %1, %2" : "=v"(r) : "v"(lo), "v"(hi)); return r; }
; __device__ __forceinline__ bf16_t* wt_ptr(const Frame& F, int layer, size_t off) { return (bf16_t*)(F.ws + WS_WT + (size_t)layer * LWT + off); }
; __device__ __forceinline__ void transpose_item(const float* W, int K, int N, bf16_t* WT, int dest_row0, int k0, int n0, LAS float* scr, int lane) {
;     ...
;     const int c = lane & 7;
; #pragma unroll
;     for (int j = 0; j < 4; ++j) { const int n = (lane >> 3) + 8 * j; const LAS float* s = scr + (8 * c) * 33 + n;
;         u32x4 o; o.x = cvt_pk_bf16(s[0 * 33], s[1 * 33]); o.y = cvt_pk_bf16(s[2 * 33], s[3 * 33]); o.z = cvt_pk_bf16(s[4 * 33], s[5 * 33]); o.w = cvt_pk_bf16(s[6 * 33], s[7 * 33]);
;         STG(u32x4, WT + (size_t)(dest_row0 + n) * K + k0 + 8 * c) = o; }
;     asm volatile("s_waitcnt lgkmcnt(0)" ::: "memory");
; }
; __device__ __forceinline__ void phase_weights(const Frame& F0, int lmask, int cu0, int ncu, int pm) {
;     ...
;             if (r < I_U) { const int nblk = 2 * DFF / 32, kb = r / nblk, nb = r % nblk; const int n0 = 32 * nb; const int half = n0 >= DFF ? 1 : 0, nn = n0 - half * DFF;
;                 const int drow = (nn >> 7) * 256 + half * 128 + (nn & 127);
;                 transpose_item(wup, DM, 2 * DFF, wt_ptr(F, layer, WT_UP), drow, 64 * kb, n0, scr, F.lane); continue; } r -= I_U;
	ds_read2_b32 v[28:29], v23 offset1:33
	s_waitcnt lgkmcnt(0)
	v_cvt_pk_bf16_f32 v28, v28, v29
	ds_read2_b32 v[30:31], v23 offset0:66 offset1:99
	s_waitcnt lgkmcnt(0)
	v_cvt_pk_bf16_f32 v29, v30, v31
	ds_read2_b32 v[30:31], v23 offset0:132 offset1:165
	v_lshl_add_u64 v[18:19], s[4:5], 1, v[2:3]
	s_waitcnt lgkmcnt(0)
	v_cvt_pk_bf16_f32 v30, v30, v31
	ds_read2_b32 v[32:33], v23 offset0:198 offset1:231
	v_add_u32_e32 v27, s7, v22
	s_waitcnt lgkmcnt(0)
	v_cvt_pk_bf16_f32 v31, v32, v33
	v_mad_i64_i32 v[32:33], s[4:5], v27, s33, v[18:19]
	global_store_dwordx4 v[32:33], v[28:31], off
	ds_read2_b32 v[28:29], v23 offset0:8 offset1:41
	v_add_u32_e32 v27, s7, v24
	s_waitcnt lgkmcnt(0)
	v_cvt_pk_bf16_f32 v28, v28, v29
	ds_read2_b32 v[30:31], v23 offset0:74 offset1:107
	s_waitcnt lgkmcnt(0)
	v_cvt_pk_bf16_f32 v29, v30, v31
	ds_read2_b32 v[30:31], v23 offset0:140 offset1:173
	s_waitcnt lgkmcnt(0)
	v_cvt_pk_bf16_f32 v30, v30, v31
	ds_read2_b32 v[32:33], v23 offset0:206 offset1:239
	s_waitcnt lgkmcnt(0)
	v_cvt_pk_bf16_f32 v31, v32, v33
	v_mad_i64_i32 v[32:33], s[4:5], v27, s33, v[18:19]
	global_store_dwordx4 v[32:33], v[28:31], off
	ds_read2_b32 v[28:29], v23 offset0:16 offset1:49
	v_add_u32_e32 v27, s7, v25
	s_waitcnt lgkmcnt(0)
	v_cvt_pk_bf16_f32 v28, v28, v29
	ds_read2_b32 v[30:31], v23 offset0:82 offset1:115
	s_waitcnt lgkmcnt(0)
	v_cvt_pk_bf16_f32 v29, v30, v31
	ds_read2_b32 v[30:31], v23 offset0:148 offset1:181
	s_waitcnt lgkmcnt(0)
	v_cvt_pk_bf16_f32 v30, v30, v31
	ds_read2_b32 v[32:33], v23 offset0:214 offset1:247
	s_waitcnt lgkmcnt(0)
	v_cvt_pk_bf16_f32 v31, v32, v33
	v_mad_i64_i32 v[32:33], s[4:5], v27, s33, v[18:19]
	global_store_dwordx4 v[32:33], v[28:31], off
	ds_read2_b32 v[28:29], v23 offset0:24 offset1:57
	v_add_u32_e32 v27, s7, v26
	s_waitcnt lgkmcnt(0)
	v_cvt_pk_bf16_f32 v28, v28, v29
	ds_read2_b32 v[30:31], v23 offset0:90 offset1:123
	s_waitcnt lgkmcnt(0)
	v_cvt_pk_bf16_f32 v29, v30, v31
	ds_read2_b32 v[30:31], v23 offset0:156 offset1:189
	v_mad_i64_i32 v[18:19], s[4:5], v27, s33, v[18:19]
	s_waitcnt lgkmcnt(0)
	v_cvt_pk_bf16_f32 v30, v30, v31
	ds_read2_b32 v[32:33], v23 offset0:222 offset1:255
	s_waitcnt lgkmcnt(0)
	v_cvt_pk_bf16_f32 v31, v32, v33
	global_store_dwordx4 v[18:19], v[28:31], off
	s_mov_b64 s[4:5], 0
.LBB0_1397:
	s_andn2_b64 vcc, exec, s[4:5]
	s_cbranch_vccnz .LBB0_1399
	s_add_i32 s4, s6, 0xf800
	s_and_b32 s5, s4, 0xffff
	s_mul_i32 s5, s5, 0xbe83
	s_lshr_b32 s5, s5, 24
	s_mul_i32 s7, s5, 0x158
	s_sub_i32 s4, s4, s7
	s_lshl_b32 s7, s4, 5
	s_and_b32 s25, s7, 0xffe0
	s_and_b32 s4, s4, 0xffff
	s_cmpk_gt_u32 s4, 0xab
	s_cselect_b32 s4, 0xffffea80, 0
	s_cselect_b32 s26, 0x80, 0
	s_lshl_b32 s72, s25, 2
	s_and_b32 s7, s7, 0x60
	v_lshl_add_u32 v27, s5, 6, v20
	v_lshl_add_u64 v[18:19], v[12:13], 0, s[72:73]
	s_or_b32 s7, s7, s26
	v_mad_i64_i32 v[28:29], s[26:27], v27, s15, v[18:19]
	global_load_dword v30, v[28:29], off
	v_add_u32_e32 v28, 2, v27
	v_mad_i64_i32 v[28:29], s[26:27], v28, s15, v[18:19]
	global_load_dword v31, v[28:29], off
	v_add_u32_e32 v28, 4, v27
	v_mad_i64_i32 v[28:29], s[26:27], v28, s15, v[18:19]
	global_load_dword v32, v[28:29], off
	v_add_u32_e32 v28, 6, v27
	v_mad_i64_i32 v[28:29], s[26:27], v28, s15, v[18:19]
	global_load_dword v33, v[28:29], off
	v_add_u32_e32 v28, 8, v27
	v_mad_i64_i32 v[28:29], s[26:27], v28, s15, v[18:19]
	global_load_dword v34, v[28:29], off
	v_add_u32_e32 v28, 10, v27
	v_mad_i64_i32 v[28:29], s[26:27], v28, s15, v[18:19]
	global_load_dword v35, v[28:29], off
	v_add_u32_e32 v28, 12, v27
	v_mad_i64_i32 v[28:29], s[26:27], v28, s15, v[18:19]
	global_load_dword v36, v[28:29], off
	v_add_u32_e32 v28, 14, v27
	v_mad_i64_i32 v[28:29], s[26:27], v28, s15, v[18:19]
	global_load_dword v37, v[28:29], off
	v_add_u32_e32 v28, 16, v27
	v_mad_i64_i32 v[28:29], s[26:27], v28, s15, v[18:19]
	global_load_dword v38, v[28:29], off
	v_add_u32_e32 v28, 18, v27
	v_mad_i64_i32 v[28:29], s[26:27], v28, s15, v[18:19]
	global_load_dword v39, v[28:29], off
	v_add_u32_e32 v28, 20, v27
	v_mad_i64_i32 v[28:29], s[26:27], v28, s15, v[18:19]
	global_load_dword v40, v[28:29], off
	v_add_u32_e32 v28, 22, v27
	v_mad_i64_i32 v[28:29], s[26:27], v28, s15, v[18:19]
	global_load_dword v41, v[28:29], off
	v_add_u32_e32 v28, 24, v27
	v_mad_i64_i32 v[28:29], s[26:27], v28, s15, v[18:19]
	global_load_dword v42, v[28:29], off
	v_add_u32_e32 v28, 26, v27
	v_mad_i64_i32 v[28:29], s[26:27], v28, s15, v[18:19]
	global_load_dword v43, v[28:29], off
	v_add_u32_e32 v28, 28, v27
	v_mad_i64_i32 v[28:29], s[26:27], v28, s15, v[18:19]
	global_load_dword v44, v[28:29], off
	v_add_u32_e32 v28, 30, v27
	v_mad_i64_i32 v[28:29], s[26:27], v28, s15, v[18:19]
	global_load_dword v45, v[28:29], off
	v_add_u32_e32 v28, 32, v27
	v_mad_i64_i32 v[28:29], s[26:27], v28, s15, v[18:19]
	global_load_dword v46, v[28:29], off
	v_add_u32_e32 v28, 34, v27
	v_mad_i64_i32 v[28:29], s[26:27], v28, s15, v[18:19]
	global_load_dword v47, v[28:29], off
	v_add_u32_e32 v28, 36, v27
	v_mad_i64_i32 v[28:29], s[26:27], v28, s15, v[18:19]
	global_load_dword v48, v[28:29], off
	v_add_u32_e32 v28, 38, v27
	v_mad_i64_i32 v[28:29], s[26:27], v28, s15, v[18:19]
	global_load_dword v49, v[28:29], off
	v_add_u32_e32 v28, 40, v27
	v_mad_i64_i32 v[28:29], s[26:27], v28, s15, v[18:19]
	global_load_dword v50, v[28:29], off
	v_add_u32_e32 v28, 42, v27
	v_mad_i64_i32 v[28:29], s[26:27], v28, s15, v[18:19]
	global_load_dword v51, v[28:29], off
	v_add_u32_e32 v28, 44, v27
	v_mad_i64_i32 v[28:29], s[26:27], v28, s15, v[18:19]
	global_load_dword v52, v[28:29], off
	v_add_u32_e32 v28, 46, v27
	v_mad_i64_i32 v[28:29], s[26:27], v28, s15, v[18:19]
	global_load_dword v53, v[28:29], off
	v_add_u32_e32 v28, 48, v27
	v_mad_i64_i32 v[28:29], s[26:27], v28, s15, v[18:19]
	global_load_dword v54, v[28:29], off
	v_add_u32_e32 v28, 50, v27
	v_mad_i64_i32 v[28:29], s[26:27], v28, s15, v[18:19]
	global_load_dword v55, v[28:29], off
	v_add_u32_e32 v28, 52, v27
	v_mad_i64_i32 v[28:29], s[26:27], v28, s15, v[18:19]
	global_load_dword v56, v[28:29], off
	v_add_u32_e32 v28, 54, v27
	v_mad_i64_i32 v[28:29], s[26:27], v28, s15, v[18:19]
	global_load_dword v57, v[28:29], off
	v_add_u32_e32 v28, 56, v27
	v_mad_i64_i32 v[28:29], s[26:27], v28, s15, v[18:19]
	global_load_dword v58, v[28:29], off
	v_add_u32_e32 v28, 58, v27
	v_mad_i64_i32 v[28:29], s[26:27], v28, s15, v[18:19]
	global_load_dword v59, v[28:29], off
	v_add_u32_e32 v28, 60, v27
	v_add_u32_e32 v27, 62, v27
	v_mad_i64_i32 v[28:29], s[26:27], v28, s15, v[18:19]
	v_mad_i64_i32 v[18:19], s[26:27], v27, s15, v[18:19]
	global_load_dword v28, v[28:29], off
	s_add_i32 s4, s4, s25
	global_load_dword v18, v[18:19], off
	v_add_u32_e32 v19, 0x400, v21
	s_waitcnt vmcnt(0)
; #define LAS __attribute__((address_space(3)))
; __device__ __forceinline__ unsigned cvt_pk_bf16(float lo, float hi) { unsigned r; asm volatile("v_cvt_pk_bf16_f32 %0, %1, %2" : "=v"(r) : "v"(lo), "v"(hi)); return r; }
; __device__ __forceinline__ bf16_t* wt_ptr(const Frame& F, int layer, size_t off) { return (bf16_t*)(F.ws + WS_WT + (size_t)layer * LWT + off); }
; __device__ __forceinline__ void transpose_item(const float* W, int K, int N, bf16_t* WT, int dest_row0, int k0, int n0, LAS float* scr, int lane) {
;     ...
;     for (int i = 0; i < 32; ++i) { const int kk = 2 * i + (lane >> 5); scr[kk * 33 + (lane & 31)] = wv[i]; }
;     asm volatile("s_waitcnt lgkmcnt(0)" ::: "memory");
;     const int c = lane & 7;
; #pragma unroll
;     for (int j = 0; j < 4; ++j) { const int n = (lane >> 3) + 8 * j; const LAS float* s = scr + (8 * c) * 33 + n;
;         u32x4 o; o.x = cvt_pk_bf16(s[0 * 33], s[1 * 33]); o.y = cvt_pk_bf16(s[2 * 33], s[3 * 33]); o.z = cvt_pk_bf16(s[4 * 33], s[5 * 33]); o.w = cvt_pk_bf16(s[6 * 33], s[7 * 33]);
;         STG(u32x4, WT + (size_t)(dest_row0 + n) * K + k0 + 8 * c) = o; }
;     asm volatile("s_waitcnt lgkmcnt(0)" ::: "memory");
; }
; __device__ __forceinline__ void phase_weights(const Frame& F0, int lmask, int cu0, int ncu, int pm) {
;     ...
;             if (r < I_O) { const int nblk = DM / 32, kb = r / nblk, nb = r % nblk; transpose_item(wo, DM, DM, wt_ptr(F, layer, WT_WO), 32 * nb, 64 * kb, 32 * nb, scr, F.lane); continue; } r -= I_O;
	ds_write2_b32 v21, v30, v31 offset1:66
	ds_write2_b32 v21, v32, v33 offset0:132 offset1:198
	ds_write2_b32 v19, v34, v35 offset0:8 offset1:74
	ds_write2_b32 v19, v36, v37 offset0:140 offset1:206
	v_add_u32_e32 v19, 0x800, v21
	ds_write2_b32 v19, v38, v39 offset0:16 offset1:82
	ds_write2_b32 v19, v40, v41 offset0:148 offset1:214
	v_add_u32_e32 v19, 0xc00, v21
	ds_write2_b32 v19, v42, v43 offset0:24 offset1:90
	ds_write2_b32 v19, v44, v45 offset0:156 offset1:222
	v_add_u32_e32 v19, 0x1000, v21
	ds_write2_b32 v19, v46, v47 offset0:32 offset1:98
	ds_write2_b32 v19, v48, v49 offset0:164 offset1:230
	v_add_u32_e32 v19, 0x1400, v21
	ds_write2_b32 v19, v50, v51 offset0:40 offset1:106
	ds_write2_b32 v19, v52, v53 offset0:172 offset1:238
	v_add_u32_e32 v19, 0x1800, v21
	ds_write2_b32 v19, v54, v55 offset0:48 offset1:114
	ds_write2_b32 v19, v56, v57 offset0:180 offset1:246
	v_add_u32_e32 v19, 0x1c00, v21
	ds_write2_b32 v19, v58, v59 offset0:56 offset1:122
	ds_write2_b32 v19, v28, v18 offset0:188 offset1:254
	s_waitcnt lgkmcnt(0)
	ds_read2_b32 v[28:29], v23 offset1:33
	s_lshl_b32 s4, s4, 1
	s_waitcnt lgkmcnt(0)
	v_cvt_pk_bf16_f32 v28, v28, v29
	ds_read2_b32 v[30:31], v23 offset0:66 offset1:99
	s_and_b32 s4, s4, 0xffffff00
	s_waitcnt lgkmcnt(0)
	v_cvt_pk_bf16_f32 v29, v30, v31
	ds_read2_b32 v[30:31], v23 offset0:132 offset1:165
	s_or_b32 s4, s7, s4
	s_waitcnt lgkmcnt(0)
	v_cvt_pk_bf16_f32 v30, v30, v31
	ds_read2_b32 v[32:33], v23 offset0:198 offset1:231
	s_waitcnt lgkmcnt(0)
	v_cvt_pk_bf16_f32 v31, v32, v33
	v_add_u32_e32 v32, s4, v22
	s_lshl_b32 s72, s5, 7
	v_ashrrev_i32_e32 v33, 31, v32
	v_lshl_add_u64 v[18:19], v[4:5], 0, s[72:73]
	v_lshlrev_b64 v[32:33], 12, v[32:33]
	v_lshl_add_u64 v[32:33], v[18:19], 0, v[32:33]
	global_store_dwordx4 v[32:33], v[28:31], off
	ds_read2_b32 v[28:29], v23 offset0:8 offset1:41
	s_waitcnt lgkmcnt(0)
	v_cvt_pk_bf16_f32 v28, v28, v29
	ds_read2_b32 v[30:31], v23 offset0:74 offset1:107
	s_waitcnt lgkmcnt(0)
	v_cvt_pk_bf16_f32 v29, v30, v31
	ds_read2_b32 v[30:31], v23 offset0:140 offset1:173
	s_waitcnt lgkmcnt(0)
	v_cvt_pk_bf16_f32 v30, v30, v31
	ds_read2_b32 v[32:33], v23 offset0:206 offset1:239
	s_waitcnt lgkmcnt(0)
	v_cvt_pk_bf16_f32 v31, v32, v33
	v_add_u32_e32 v32, s4, v24
	v_ashrrev_i32_e32 v33, 31, v32
	v_lshlrev_b64 v[32:33], 12, v[32:33]
	v_lshl_add_u64 v[32:33], v[18:19], 0, v[32:33]
	global_store_dwordx4 v[32:33], v[28:31], off
	ds_read2_b32 v[28:29], v23 offset0:16 offset1:49
	s_waitcnt lgkmcnt(0)
	v_cvt_pk_bf16_f32 v28, v28, v29
	ds_read2_b32 v[30:31], v23 offset0:82 offset1:115
	s_waitcnt lgkmcnt(0)
	v_cvt_pk_bf16_f32 v29, v30, v31
	ds_read2_b32 v[30:31], v23 offset0:148 offset1:181
	s_waitcnt lgkmcnt(0)
	v_cvt_pk_bf16_f32 v30, v30, v31
	ds_read2_b32 v[32:33], v23 offset0:214 offset1:247
	s_waitcnt lgkmcnt(0)
	v_cvt_pk_bf16_f32 v31, v32, v33
	v_add_u32_e32 v32, s4, v25
	v_ashrrev_i32_e32 v33, 31, v32
	v_lshlrev_b64 v[32:33], 12, v[32:33]
	v_lshl_add_u64 v[32:33], v[18:19], 0, v[32:33]
	global_store_dwordx4 v[32:33], v[28:31], off
	ds_read2_b32 v[28:29], v23 offset0:24 offset1:57
	s_waitcnt lgkmcnt(0)
	v_cvt_pk_bf16_f32 v28, v28, v29
	ds_read2_b32 v[30:31], v23 offset0:90 offset1:123
	s_waitcnt lgkmcnt(0)
	v_cvt_pk_bf16_f32 v29, v30, v31
	ds_read2_b32 v[30:31], v23 offset0:156 offset1:189
	s_waitcnt lgkmcnt(0)
	v_cvt_pk_bf16_f32 v30, v30, v31
	ds_read2_b32 v[32:33], v23 offset0:222 offset1:255
	s_waitcnt lgkmcnt(0)
	v_cvt_pk_bf16_f32 v31, v32, v33
	v_add_u32_e32 v32, s4, v26
	v_ashrrev_i32_e32 v33, 31, v32
	v_lshlrev_b64 v[32:33], 12, v[32:33]
	v_lshl_add_u64 v[18:19], v[18:19], 0, v[32:33]
	global_store_dwordx4 v[18:19], v[28:31], off
.LBB0_1399:
	s_mov_b64 s[4:5], 0
.LBB0_1400:
	s_andn2_b64 vcc, exec, s[4:5]
	s_cbranch_vccnz .LBB0_1402
	s_and_b32 s4, s6, 0xffffffc0
	s_and_b32 s6, s8, 0x7e0
	v_add_u32_e32 v18, s4, v20
	s_lshl_b32 s72, s6, 2
	v_ashrrev_i32_e32 v19, 31, v18
	v_lshl_add_u64 v[28:29], v[14:15], 0, s[72:73]
	v_lshlrev_b64 v[18:19], 13, v[18:19]
	v_lshl_add_u64 v[18:19], v[28:29], 0, v[18:19]
	v_add_co_u32_e32 v28, vcc, 0x4000, v18
	global_load_dword v27, v[18:19], off
	s_nop 0
	v_addc_co_u32_e32 v29, vcc, 0, v19, vcc
	global_load_dword v30, v[28:29], off
	v_add_co_u32_e32 v28, vcc, 0x8000, v18
	s_mov_b32 s5, 0x34000
	s_nop 0
	v_addc_co_u32_e32 v29, vcc, 0, v19, vcc
	global_load_dword v31, v[28:29], off
	v_add_co_u32_e32 v28, vcc, s3, v18
	s_nop 1
	v_addc_co_u32_e32 v29, vcc, 0, v19, vcc
	global_load_dword v32, v[28:29], off
	v_add_co_u32_e32 v28, vcc, s55, v18
	s_nop 1
	v_addc_co_u32_e32 v29, vcc, 0, v19, vcc
	global_load_dword v33, v[28:29], off
	v_add_co_u32_e32 v28, vcc, s58, v18
	s_nop 1
	v_addc_co_u32_e32 v29, vcc, 0, v19, vcc
	global_load_dword v34, v[28:29], off
	v_add_co_u32_e32 v28, vcc, s59, v18
	s_nop 1
	v_addc_co_u32_e32 v29, vcc, 0, v19, vcc
	global_load_dword v35, v[28:29], off
	v_add_co_u32_e32 v28, vcc, s63, v18
	s_nop 1
	v_addc_co_u32_e32 v29, vcc, 0, v19, vcc
	global_load_dword v36, v[28:29], off
	v_add_co_u32_e32 v28, vcc, s66, v18
	s_nop 1
	v_addc_co_u32_e32 v29, vcc, 0, v19, vcc
	global_load_dword v37, v[28:29], off
	v_add_co_u32_e32 v28, vcc, s56, v18
	s_nop 1
	v_addc_co_u32_e32 v29, vcc, 0, v19, vcc
	global_load_dword v38, v[28:29], off
	v_add_co_u32_e32 v28, vcc, s57, v18
	s_nop 1
	v_addc_co_u32_e32 v29, vcc, 0, v19, vcc
	global_load_dword v39, v[28:29], off
	v_add_co_u32_e32 v28, vcc, s94, v18
	s_nop 1
	v_addc_co_u32_e32 v29, vcc, 0, v19, vcc
	global_load_dword v40, v[28:29], off
	v_add_co_u32_e32 v28, vcc, s54, v18
	s_nop 1
	v_addc_co_u32_e32 v29, vcc, 0, v19, vcc
	global_load_dword v41, v[28:29], off
	v_add_co_u32_e32 v28, vcc, s5, v18
	s_mov_b32 s5, 0x38000
	s_nop 0
; #define LAS __attribute__((address_space(3)))
; __device__ __forceinline__ unsigned cvt_pk_bf16(float lo, float hi) { unsigned r; asm volatile("v_cvt_pk_bf16_f32 %0, %1, %2" : "=v"(r) : "v"(lo), "v"(hi)); return r; }
; __device__ __forceinline__ void transpose_item(const float* W, int K, int N, bf16_t* WT, int dest_row0, int k0, int n0, LAS float* scr, int lane) {
;     ...
;     for (int i = 0; i < 32; ++i) { const int kk = 2 * i + (lane >> 5); wv[i] = LDG(float, W + (size_t)(k0 + kk) * N + n0 + (lane & 31)); }
; #pragma unroll
;     for (int i = 0; i < 32; ++i) { const int kk = 2 * i + (lane >> 5); scr[kk * 33 + (lane & 31)] = wv[i]; }
;     asm volatile("s_waitcnt lgkmcnt(0)" ::: "memory");
;     const int c = lane & 7;
; #pragma unroll
;     for (int j = 0; j < 4; ++j) { const int n = (lane >> 3) + 8 * j; const LAS float* s = scr + (8 * c) * 33 + n;
;         u32x4 o; o.x = cvt_pk_bf16(s[0 * 33], s[1 * 33]); o.y = cvt_pk_bf16(s[2 * 33], s[3 * 33]); o.z = cvt_pk_bf16(s[4 * 33], s[5 * 33]); o.w = cvt_pk_bf16(s[6 * 33], s[7 * 33]);
;         STG(u32x4, WT + (size_t)(dest_row0 + n) * K + k0 + 8 * c) = o; }
;     asm volatile("s_waitcnt lgkmcnt(0)" ::: "memory");
	v_addc_co_u32_e32 v29, vcc, 0, v19, vcc
	global_load_dword v42, v[28:29], off
	v_add_co_u32_e32 v28, vcc, s5, v18
	s_mov_b32 s5, 0x3c000
	s_nop 0
	v_addc_co_u32_e32 v29, vcc, 0, v19, vcc
	global_load_dword v43, v[28:29], off
	v_add_co_u32_e32 v28, vcc, s5, v18
	s_mov_b32 s5, 0x40000
	s_nop 0
	v_addc_co_u32_e32 v29, vcc, 0, v19, vcc
	global_load_dword v44, v[28:29], off
	v_add_co_u32_e32 v28, vcc, s5, v18
	s_mov_b32 s5, 0x44000
	s_nop 0
	v_addc_co_u32_e32 v29, vcc, 0, v19, vcc
	global_load_dword v45, v[28:29], off
	v_add_co_u32_e32 v28, vcc, s5, v18
	s_mov_b32 s5, 0x48000
	s_nop 0
	v_addc_co_u32_e32 v29, vcc, 0, v19, vcc
	global_load_dword v46, v[28:29], off
	v_add_co_u32_e32 v28, vcc, s5, v18
	s_mov_b32 s5, 0x4c000
	s_nop 0
	v_addc_co_u32_e32 v29, vcc, 0, v19, vcc
	global_load_dword v47, v[28:29], off
	v_add_co_u32_e32 v28, vcc, s5, v18
	s_mov_b32 s5, 0x50000
	s_nop 0
	v_addc_co_u32_e32 v29, vcc, 0, v19, vcc
	global_load_dword v48, v[28:29], off
	v_add_co_u32_e32 v28, vcc, s5, v18
	s_mov_b32 s5, s73
	s_nop 0
	v_addc_co_u32_e32 v29, vcc, 0, v19, vcc
	global_load_dword v49, v[28:29], off
	v_add_co_u32_e32 v28, vcc, s70, v18
	s_nop 1
	v_addc_co_u32_e32 v29, vcc, 0, v19, vcc
	global_load_dword v50, v[28:29], off
	v_add_co_u32_e32 v28, vcc, s71, v18
	s_nop 1
	v_addc_co_u32_e32 v29, vcc, 0, v19, vcc
	global_load_dword v51, v[28:29], off
	v_add_co_u32_e32 v28, vcc, s18, v18
	s_nop 1
	v_addc_co_u32_e32 v29, vcc, 0, v19, vcc
	global_load_dword v52, v[28:29], off
	v_add_co_u32_e32 v28, vcc, s19, v18
	s_nop 1
	v_addc_co_u32_e32 v29, vcc, 0, v19, vcc
	global_load_dword v53, v[28:29], off
	v_add_co_u32_e32 v28, vcc, s10, v18
	s_nop 1
	v_addc_co_u32_e32 v29, vcc, 0, v19, vcc
	global_load_dword v54, v[28:29], off
	v_add_co_u32_e32 v28, vcc, s11, v18
	s_nop 1
	v_addc_co_u32_e32 v29, vcc, 0, v19, vcc
	global_load_dword v55, v[28:29], off
	v_add_co_u32_e32 v28, vcc, s20, v18
	s_nop 1
	v_addc_co_u32_e32 v29, vcc, 0, v19, vcc
	global_load_dword v56, v[28:29], off
	v_add_co_u32_e32 v28, vcc, s21, v18
	s_nop 1
	v_addc_co_u32_e32 v29, vcc, 0, v19, vcc
	global_load_dword v57, v[28:29], off
	v_add_co_u32_e32 v28, vcc, s22, v18
	s_nop 1
	v_addc_co_u32_e32 v29, vcc, 0, v19, vcc
	global_load_dword v58, v[28:29], off
	v_add_co_u32_e32 v28, vcc, s23, v18
	s_nop 1
	v_addc_co_u32_e32 v29, vcc, 0, v19, vcc
	v_add_co_u32_e32 v18, vcc, s14, v18
	global_load_dword v28, v[28:29], off
	s_nop 0
	v_addc_co_u32_e32 v19, vcc, 0, v19, vcc
	global_load_dword v18, v[18:19], off
	v_add_u32_e32 v19, 0x400, v21
	s_waitcnt vmcnt(0)
	ds_write2_b32 v21, v27, v30 offset1:66
	ds_write2_b32 v21, v31, v32 offset0:132 offset1:198
	ds_write2_b32 v19, v33, v34 offset0:8 offset1:74
	ds_write2_b32 v19, v35, v36 offset0:140 offset1:206
	v_add_u32_e32 v19, 0x800, v21
	ds_write2_b32 v19, v37, v38 offset0:16 offset1:82
	ds_write2_b32 v19, v39, v40 offset0:148 offset1:214
	v_add_u32_e32 v19, 0xc00, v21
	ds_write2_b32 v19, v41, v42 offset0:24 offset1:90
	ds_write2_b32 v19, v43, v44 offset0:156 offset1:222
	v_add_u32_e32 v19, 0x1000, v21
	ds_write2_b32 v19, v45, v46 offset0:32 offset1:98
	ds_write2_b32 v19, v47, v48 offset0:164 offset1:230
	v_add_u32_e32 v19, 0x1400, v21
	ds_write2_b32 v19, v49, v50 offset0:40 offset1:106
	ds_write2_b32 v19, v51, v52 offset0:172 offset1:238
	v_add_u32_e32 v19, 0x1800, v21
	ds_write2_b32 v19, v53, v54 offset0:48 offset1:114
	ds_write2_b32 v19, v55, v56 offset0:180 offset1:246
	v_add_u32_e32 v19, 0x1c00, v21
	ds_write2_b32 v19, v57, v58 offset0:56 offset1:122
	ds_write2_b32 v19, v28, v18 offset0:188 offset1:254
	s_waitcnt lgkmcnt(0)
	ds_read2_b32 v[28:29], v23 offset1:33
	s_waitcnt lgkmcnt(0)
	v_cvt_pk_bf16_f32 v28, v28, v29
	ds_read2_b32 v[30:31], v23 offset0:66 offset1:99
	s_waitcnt lgkmcnt(0)
	v_cvt_pk_bf16_f32 v29, v30, v31
	ds_read2_b32 v[30:31], v23 offset0:132 offset1:165
	s_waitcnt lgkmcnt(0)
	v_cvt_pk_bf16_f32 v30, v30, v31
	ds_read2_b32 v[32:33], v23 offset0:198 offset1:231
	s_waitcnt lgkmcnt(0)
	v_cvt_pk_bf16_f32 v31, v32, v33
	v_add_u32_e32 v32, s6, v22
	v_ashrrev_i32_e32 v33, 31, v32
	v_lshl_add_u64 v[18:19], s[4:5], 1, v[6:7]
	v_lshlrev_b64 v[32:33], 12, v[32:33]
	v_lshl_add_u64 v[32:33], v[18:19], 0, v[32:33]
	global_store_dwordx4 v[32:33], v[28:31], off
	ds_read2_b32 v[28:29], v23 offset0:8 offset1:41
	s_waitcnt lgkmcnt(0)
	v_cvt_pk_bf16_f32 v28, v28, v29
	ds_read2_b32 v[30:31], v23 offset0:74 offset1:107
	s_waitcnt lgkmcnt(0)
	v_cvt_pk_bf16_f32 v29, v30, v31
	ds_read2_b32 v[30:31], v23 offset0:140 offset1:173
	s_waitcnt lgkmcnt(0)
	v_cvt_pk_bf16_f32 v30, v30, v31
	ds_read2_b32 v[32:33], v23 offset0:206 offset1:239
	s_waitcnt lgkmcnt(0)
	v_cvt_pk_bf16_f32 v31, v32, v33
	v_add_u32_e32 v32, s6, v24
	v_ashrrev_i32_e32 v33, 31, v32
	v_lshlrev_b64 v[32:33], 12, v[32:33]
	v_lshl_add_u64 v[32:33], v[18:19], 0, v[32:33]
	global_store_dwordx4 v[32:33], v[28:31], off
	ds_read2_b32 v[28:29], v23 offset0:16 offset1:49
	s_waitcnt lgkmcnt(0)
	v_cvt_pk_bf16_f32 v28, v28, v29
	ds_read2_b32 v[30:31], v23 offset0:82 offset1:115
	s_waitcnt lgkmcnt(0)
	v_cvt_pk_bf16_f32 v29, v30, v31
	ds_read2_b32 v[30:31], v23 offset0:148 offset1:181
	s_waitcnt lgkmcnt(0)
	v_cvt_pk_bf16_f32 v30, v30, v31
	ds_read2_b32 v[32:33], v23 offset0:214 offset1:247
	s_waitcnt lgkmcnt(0)
	v_cvt_pk_bf16_f32 v31, v32, v33
	v_add_u32_e32 v32, s6, v25
	v_ashrrev_i32_e32 v33, 31, v32
	v_lshlrev_b64 v[32:33], 12, v[32:33]
	v_lshl_add_u64 v[32:33], v[18:19], 0, v[32:33]
	global_store_dwordx4 v[32:33], v[28:31], off
	ds_read2_b32 v[28:29], v23 offset0:24 offset1:57
	s_waitcnt lgkmcnt(0)
	v_cvt_pk_bf16_f32 v28, v28, v29
	ds_read2_b32 v[30:31], v23 offset0:90 offset1:123
	s_waitcnt lgkmcnt(0)
	v_cvt_pk_bf16_f32 v29, v30, v31
	ds_read2_b32 v[30:31], v23 offset0:156 offset1:189
	s_waitcnt lgkmcnt(0)
	v_cvt_pk_bf16_f32 v30, v30, v31
	ds_read2_b32 v[32:33], v23 offset0:222 offset1:255
	s_waitcnt lgkmcnt(0)
	v_cvt_pk_bf16_f32 v31, v32, v33
	v_add_u32_e32 v32, s6, v26
	v_ashrrev_i32_e32 v33, 31, v32
	v_lshlrev_b64 v[32:33], 12, v[32:33]
	v_lshl_add_u64 v[18:19], v[18:19], 0, v[32:33]
	global_store_dwordx4 v[18:19], v[28:31], off
; #define LAS __attribute__((address_space(3)))
; __device__ __forceinline__ bf16_t* wt_ptr(const Frame& F, int layer, size_t off) { return (bf16_t*)(F.ws + WS_WT + (size_t)layer * LWT + off); }
; __device__ __forceinline__ void transpose_item(const float* W, int K, int N, bf16_t* WT, int dest_row0, int k0, int n0, LAS float* scr, int lane) {
;     float wv[32];
; #pragma unroll
;     for (int i = 0; i < 32; ++i) { const int kk = 2 * i + (lane >> 5); wv[i] = LDG(float, W + (size_t)(k0 + kk) * N + n0 + (lane & 31)); }
; __device__ __forceinline__ void phase_weights(const Frame& F0, int lmask, int cu0, int ncu, int pm) {
;     ...
;         for (int it = it_lo + gw_; it < it_hi; it += ngw_) {
;             int r = it;
;             if (r < I_Q) { const int nblk = NQ / 32, kb = r / nblk, nb = r % nblk; transpose_item(wqkv, DM, NQ, wt_ptr(F, layer, WT_QKV), 32 * nb, 64 * kb, 32 * nb, scr, F.lane); continue; } r -= I_Q;
.LBB0_1402:
	s_cbranch_execnz .LBB0_1391
.LBB0_1403:
	s_mul_hi_i32 s4, s9, 0x2aaaaaab
	s_lshr_b32 s5, s4, 31
	s_ashr_i32 s4, s4, 4
	s_add_i32 s5, s4, s5
	s_mul_i32 s4, s5, 0xfffff400
	s_add_i32 s4, s8, s4
	s_lshl_b32 s6, s5, 6
	s_ashr_i32 s5, s4, 31
	v_add_u32_e32 v27, s6, v20
	v_lshl_add_u64 v[18:19], s[4:5], 2, v[16:17]
	v_mad_i64_i32 v[28:29], s[26:27], v27, s68, v[18:19]
	global_load_dword v30, v[28:29], off
	v_add_u32_e32 v28, 2, v27
	v_mad_i64_i32 v[28:29], s[26:27], v28, s68, v[18:19]
	global_load_dword v31, v[28:29], off
	v_add_u32_e32 v28, 4, v27
	v_mad_i64_i32 v[28:29], s[26:27], v28, s68, v[18:19]
	global_load_dword v32, v[28:29], off
	v_add_u32_e32 v28, 6, v27
	v_mad_i64_i32 v[28:29], s[26:27], v28, s68, v[18:19]
	global_load_dword v33, v[28:29], off
	v_add_u32_e32 v28, 8, v27
	v_mad_i64_i32 v[28:29], s[26:27], v28, s68, v[18:19]
	global_load_dword v34, v[28:29], off
	v_add_u32_e32 v28, 10, v27
	v_mad_i64_i32 v[28:29], s[26:27], v28, s68, v[18:19]
	global_load_dword v35, v[28:29], off
	v_add_u32_e32 v28, 12, v27
	v_mad_i64_i32 v[28:29], s[26:27], v28, s68, v[18:19]
	global_load_dword v36, v[28:29], off
	v_add_u32_e32 v28, 14, v27
	v_mad_i64_i32 v[28:29], s[26:27], v28, s68, v[18:19]
	global_load_dword v37, v[28:29], off
	v_add_u32_e32 v28, 16, v27
	v_mad_i64_i32 v[28:29], s[26:27], v28, s68, v[18:19]
	global_load_dword v38, v[28:29], off
	v_add_u32_e32 v28, 18, v27
	v_mad_i64_i32 v[28:29], s[26:27], v28, s68, v[18:19]
	global_load_dword v39, v[28:29], off
	v_add_u32_e32 v28, 20, v27
	v_mad_i64_i32 v[28:29], s[26:27], v28, s68, v[18:19]
	global_load_dword v40, v[28:29], off
	v_add_u32_e32 v28, 22, v27
	v_mad_i64_i32 v[28:29], s[26:27], v28, s68, v[18:19]
	global_load_dword v41, v[28:29], off
	v_add_u32_e32 v28, 24, v27
	v_mad_i64_i32 v[28:29], s[26:27], v28, s68, v[18:19]
	global_load_dword v42, v[28:29], off
	v_add_u32_e32 v28, 26, v27
	v_mad_i64_i32 v[28:29], s[26:27], v28, s68, v[18:19]
	global_load_dword v43, v[28:29], off
	v_add_u32_e32 v28, 28, v27
	v_mad_i64_i32 v[28:29], s[26:27], v28, s68, v[18:19]
	global_load_dword v44, v[28:29], off
	v_add_u32_e32 v28, 30, v27
	v_mad_i64_i32 v[28:29], s[26:27], v28, s68, v[18:19]
	global_load_dword v45, v[28:29], off
	v_add_u32_e32 v28, 32, v27
	v_mad_i64_i32 v[28:29], s[26:27], v28, s68, v[18:19]
	global_load_dword v46, v[28:29], off
	v_add_u32_e32 v28, 34, v27
	v_mad_i64_i32 v[28:29], s[26:27], v28, s68, v[18:19]
	global_load_dword v47, v[28:29], off
	v_add_u32_e32 v28, 36, v27
	v_mad_i64_i32 v[28:29], s[26:27], v28, s68, v[18:19]
	global_load_dword v48, v[28:29], off
	v_add_u32_e32 v28, 38, v27
	v_mad_i64_i32 v[28:29], s[26:27], v28, s68, v[18:19]
	global_load_dword v49, v[28:29], off
	v_add_u32_e32 v28, 40, v27
	v_mad_i64_i32 v[28:29], s[26:27], v28, s68, v[18:19]
	global_load_dword v50, v[28:29], off
	v_add_u32_e32 v28, 42, v27
	v_mad_i64_i32 v[28:29], s[26:27], v28, s68, v[18:19]
	global_load_dword v51, v[28:29], off
	v_add_u32_e32 v28, 44, v27
	v_mad_i64_i32 v[28:29], s[26:27], v28, s68, v[18:19]
	global_load_dword v52, v[28:29], off
	v_add_u32_e32 v28, 46, v27
	v_mad_i64_i32 v[28:29], s[26:27], v28, s68, v[18:19]
	global_load_dword v53, v[28:29], off
	v_add_u32_e32 v28, 48, v27
	v_mad_i64_i32 v[28:29], s[26:27], v28, s68, v[18:19]
	global_load_dword v54, v[28:29], off
	v_add_u32_e32 v28, 50, v27
	v_mad_i64_i32 v[28:29], s[26:27], v28, s68, v[18:19]
	global_load_dword v55, v[28:29], off
	v_add_u32_e32 v28, 52, v27
	v_mad_i64_i32 v[28:29], s[26:27], v28, s68, v[18:19]
	global_load_dword v56, v[28:29], off
	v_add_u32_e32 v28, 54, v27
	v_mad_i64_i32 v[28:29], s[26:27], v28, s68, v[18:19]
	global_load_dword v57, v[28:29], off
	v_add_u32_e32 v28, 56, v27
	v_mad_i64_i32 v[28:29], s[26:27], v28, s68, v[18:19]
	global_load_dword v58, v[28:29], off
	v_add_u32_e32 v28, 58, v27
	v_mad_i64_i32 v[28:29], s[26:27], v28, s68, v[18:19]
	global_load_dword v59, v[28:29], off
	v_add_u32_e32 v28, 60, v27
	v_add_u32_e32 v27, 62, v27
	v_mad_i64_i32 v[28:29], s[26:27], v28, s68, v[18:19]
	v_mad_i64_i32 v[18:19], s[26:27], v27, s68, v[18:19]
	global_load_dword v28, v[28:29], off
	s_ashr_i32 s7, s6, 31
	global_load_dword v18, v[18:19], off
	v_add_u32_e32 v19, 0x400, v21
	s_waitcnt vmcnt(0)
; #define LAS __attribute__((address_space(3)))
; __device__ __forceinline__ unsigned cvt_pk_bf16(float lo, float hi) { unsigned r; asm volatile("v_cvt_pk_bf16_f32 %0, %1, %2" : "=v"(r) : "v"(lo), "v"(hi)); return r; }
; __device__ __forceinline__ void transpose_item(const float* W, int K, int N, bf16_t* WT, int dest_row0, int k0, int n0, LAS float* scr, int lane) {
;     ...
; #pragma unroll
;     for (int i = 0; i < 32; ++i) { const int kk = 2 * i + (lane >> 5); scr[kk * 33 + (lane & 31)] = wv[i]; }
;     asm volatile("s_waitcnt lgkmcnt(0)" ::: "memory");
;     const int c = lane & 7;
; #pragma unroll
;     for (int j = 0; j < 4; ++j) { const int n = (lane >> 3) + 8 * j; const LAS float* s = scr + (8 * c) * 33 + n;
;         u32x4 o; o.x = cvt_pk_bf16(s[0 * 33], s[1 * 33]); o.y = cvt_pk_bf16(s[2 * 33], s[3 * 33]); o.z = cvt_pk_bf16(s[4 * 33], s[5 * 33]); o.w = cvt_pk_bf16(s[6 * 33], s[7 * 33]);
;         STG(u32x4, WT + (size_t)(dest_row0 + n) * K + k0 + 8 * c) = o; }
;     asm volatile("s_waitcnt lgkmcnt(0)" ::: "memory");
; }
	ds_write2_b32 v21, v30, v31 offset1:66
	ds_write2_b32 v21, v32, v33 offset0:132 offset1:198
	ds_write2_b32 v19, v34, v35 offset0:8 offset1:74
	ds_write2_b32 v19, v36, v37 offset0:140 offset1:206
	v_add_u32_e32 v19, 0x800, v21
	ds_write2_b32 v19, v38, v39 offset0:16 offset1:82
	ds_write2_b32 v19, v40, v41 offset0:148 offset1:214
	v_add_u32_e32 v19, 0xc00, v21
	ds_write2_b32 v19, v42, v43 offset0:24 offset1:90
	ds_write2_b32 v19, v44, v45 offset0:156 offset1:222
	v_add_u32_e32 v19, 0x1000, v21
	ds_write2_b32 v19, v46, v47 offset0:32 offset1:98
	ds_write2_b32 v19, v48, v49 offset0:164 offset1:230
	v_add_u32_e32 v19, 0x1400, v21
	ds_write2_b32 v19, v50, v51 offset0:40 offset1:106
	ds_write2_b32 v19, v52, v53 offset0:172 offset1:238
	v_add_u32_e32 v19, 0x1800, v21
	ds_write2_b32 v19, v54, v55 offset0:48 offset1:114
	ds_write2_b32 v19, v56, v57 offset0:180 offset1:246
	v_add_u32_e32 v19, 0x1c00, v21
	ds_write2_b32 v19, v58, v59 offset0:56 offset1:122
	ds_write2_b32 v19, v28, v18 offset0:188 offset1:254
	s_waitcnt lgkmcnt(0)
	ds_read2_b32 v[28:29], v23 offset1:33
	s_waitcnt lgkmcnt(0)
	v_cvt_pk_bf16_f32 v28, v28, v29
	ds_read2_b32 v[30:31], v23 offset0:66 offset1:99
	s_waitcnt lgkmcnt(0)
	v_cvt_pk_bf16_f32 v29, v30, v31
	ds_read2_b32 v[30:31], v23 offset0:132 offset1:165
	s_waitcnt lgkmcnt(0)
	v_cvt_pk_bf16_f32 v30, v30, v31
	ds_read2_b32 v[32:33], v23 offset0:198 offset1:231
	s_waitcnt lgkmcnt(0)
	v_cvt_pk_bf16_f32 v31, v32, v33
	v_add_u32_e32 v32, s4, v22
	v_ashrrev_i32_e32 v33, 31, v32
	v_lshl_add_u64 v[18:19], s[6:7], 1, v[8:9]
	v_lshlrev_b64 v[34:35], 12, v[32:33]
	v_lshl_add_u64 v[34:35], v[18:19], 0, v[34:35]
	global_store_dwordx4 v[34:35], v[28:31], off
	ds_read2_b32 v[28:29], v23 offset0:8 offset1:41
	s_waitcnt lgkmcnt(0)
	v_cvt_pk_bf16_f32 v28, v28, v29
	ds_read2_b32 v[30:31], v23 offset0:74 offset1:107
	s_waitcnt lgkmcnt(0)
	v_cvt_pk_bf16_f32 v29, v30, v31
	ds_read2_b32 v[30:31], v23 offset0:140 offset1:173
	s_waitcnt lgkmcnt(0)
	v_cvt_pk_bf16_f32 v30, v30, v31
	ds_read2_b32 v[34:35], v23 offset0:206 offset1:239
	s_waitcnt lgkmcnt(0)
	v_cvt_pk_bf16_f32 v31, v34, v35
	v_add_u32_e32 v34, 8, v32
	v_ashrrev_i32_e32 v35, 31, v34
	v_lshlrev_b64 v[34:35], 12, v[34:35]
	v_lshl_add_u64 v[34:35], v[18:19], 0, v[34:35]
	global_store_dwordx4 v[34:35], v[28:31], off
	ds_read2_b32 v[28:29], v23 offset0:16 offset1:49
	s_waitcnt lgkmcnt(0)
	v_cvt_pk_bf16_f32 v28, v28, v29
	ds_read2_b32 v[30:31], v23 offset0:82 offset1:115
	s_waitcnt lgkmcnt(0)
	v_cvt_pk_bf16_f32 v29, v30, v31
	ds_read2_b32 v[30:31], v23 offset0:148 offset1:181
	s_waitcnt lgkmcnt(0)
	v_cvt_pk_bf16_f32 v30, v30, v31
	ds_read2_b32 v[34:35], v23 offset0:214 offset1:247
	s_waitcnt lgkmcnt(0)
	v_cvt_pk_bf16_f32 v31, v34, v35
	v_add_u32_e32 v34, 16, v32
	v_ashrrev_i32_e32 v35, 31, v34
	v_lshlrev_b64 v[34:35], 12, v[34:35]
	v_lshl_add_u64 v[34:35], v[18:19], 0, v[34:35]
	v_add_u32_e32 v32, 24, v32
	global_store_dwordx4 v[34:35], v[28:31], off
	ds_read2_b32 v[28:29], v23 offset0:24 offset1:57
	v_ashrrev_i32_e32 v33, 31, v32
	s_waitcnt lgkmcnt(0)
	v_cvt_pk_bf16_f32 v28, v28, v29
	ds_read2_b32 v[30:31], v23 offset0:90 offset1:123
	v_lshlrev_b64 v[32:33], 12, v[32:33]
	s_waitcnt lgkmcnt(0)
	v_cvt_pk_bf16_f32 v29, v30, v31
	ds_read2_b32 v[30:31], v23 offset0:156 offset1:189
	v_lshl_add_u64 v[18:19], v[18:19], 0, v[32:33]
	s_waitcnt lgkmcnt(0)
	v_cvt_pk_bf16_f32 v30, v30, v31
	ds_read2_b32 v[34:35], v23 offset0:222 offset1:255
	s_waitcnt lgkmcnt(0)
	v_cvt_pk_bf16_f32 v31, v34, v35
	global_store_dwordx4 v[18:19], v[28:31], off
	s_branch .LBB0_1391

; __device__ __forceinline__ unsigned xb_ld(unsigned* p)              { return __hip_atomic_load(p, __ATOMIC_RELAXED, __HIP_MEMORY_SCOPE_AGENT); }
; __device__ __forceinline__ unsigned xb_add(unsigned* p, unsigned v) { return __hip_atomic_fetch_add(p, v, __ATOMIC_RELAXED, __HIP_MEMORY_SCOPE_AGENT); }
; #define XB_SPIN(cond, bar) do { unsigned _sp = 0; while (cond) { __builtin_amdgcn_s_sleep(1); \
;     if ((++_sp & 255u) == 0u) { if (xb_ld(&(bar)[XB_TMO])) break; if (_sp > XB_SPIN_CAP) { atomicAdd(&(bar)[XB_TMO], 1u); break; } } } } while (0)
; __device__ __forceinline__ void xcd_barrier(const XcdBarrier& b) {
;     ...
;         const unsigned old = xb_add(&bar[XB_XSUB(b.x)], 1u);
;         const unsigned gen = old / nloc;
;         if (old + 1u == (gen + 1u) * nloc) {
;             __builtin_amdgcn_fence(__ATOMIC_RELEASE, "agent");
;             asm volatile("s_waitcnt vmcnt(0)" ::: "memory");
;             const unsigned og = xb_add(&bar[XB_TOP], 1u);
;             const unsigned tg = og / nx;
;             if (og + 1u == (tg + 1u) * nx) xb_add(&bar[XB_TOPGEN], 1u);
;             else XB_SPIN(xb_ld(&bar[XB_TOPGEN]) == tg, bar);
;             __builtin_amdgcn_fence(__ATOMIC_ACQUIRE, "agent");
;             xb_add(&bar[XB_XGEN(b.x)], 1u);
;             asm volatile("s_waitcnt vmcnt(0)" ::: "memory");
;         } else {
;             XB_SPIN(xb_ld(&bar[XB_XGEN(b.x)]) == gen, bar);
;             __builtin_amdgcn_fence(__ATOMIC_ACQUIRE, "agent");
;             asm volatile("s_waitcnt vmcnt(0)" ::: "memory");
;         }
.LBB0_1436:
	s_or_b64 exec, exec, s[6:7]
	s_waitcnt vmcnt(0)
	buffer_inv sc1
.LBB0_1437:
	s_andn2_saveexec_b64 s[4:5], s[4:5]
	s_cbranch_execz .LBB0_1457
	s_mov_b64 s[4:5], exec
	buffer_wbl2 sc1
	s_waitcnt lgkmcnt(0)
	s_waitcnt vmcnt(0)
	v_mbcnt_lo_u32_b32 v0, s4, 0
	v_mbcnt_hi_u32_b32 v0, s5, v0
	v_cmp_eq_u32_e32 vcc, 0, v0
	s_and_saveexec_b64 s[6:7], vcc
	s_cbranch_execz .LBB0_1440
	s_bcnt1_i32_b64 s4, s[4:5]
	v_mov_b32_e32 v3, s4
	v_readlane_b32 s4, v255, 17
	v_readlane_b32 s5, v255, 18
	s_nop 4
	global_atomic_add v3, v1, v3, s[4:5] sc0

; __device__ __forceinline__ unsigned xb_ld(unsigned* p)              { return __hip_atomic_load(p, __ATOMIC_RELAXED, __HIP_MEMORY_SCOPE_AGENT); }
; #define XB_SPIN(cond, bar) do { unsigned _sp = 0; while (cond) { __builtin_amdgcn_s_sleep(1); \
;     if ((++_sp & 255u) == 0u) { if (xb_ld(&(bar)[XB_TMO])) break; if (_sp > XB_SPIN_CAP) { atomicAdd(&(bar)[XB_TMO], 1u); break; } } } } while (0)
; __device__ __forceinline__ void xcd_barrier(const XcdBarrier& b) {
;     ...
;             XB_SPIN(xb_ld(&bar[XB_XGEN(b.x)]) == gen, bar);
;             __builtin_amdgcn_fence(__ATOMIC_ACQUIRE, "agent");
;             asm volatile("s_waitcnt vmcnt(0)" ::: "memory");
;         }
.LBB0_1553:
	s_or_b64 exec, exec, s[6:7]
	s_waitcnt vmcnt(0)
	buffer_inv sc1
.LBB0_1554:
	s_andn2_saveexec_b64 s[4:5], s[4:5]
	s_cbranch_execnz .LBB0_1555
	s_getpc_b64 s[98:99]
